# M3 scans and sample loops: ds_read hoisted to region tops with renamed destination quads and exact recomputed lgkmcnt (2k reads); on top of M4 weight hoist and P0 fast path
# speedup vs baseline: 1.0061x; 1.0044x over previous
.LBB0_1542:
	s_or_b64 exec, exec, s[8:9]
	s_waitcnt vmcnt(0)
	v_mov_b32_e32 v3, s97
	v_or_b32_e32 v2, s96, v152
	v_lshl_add_u64 v[2:3], s[4:5], 0, v[2:3]
	v_readlane_b32 s0, v253, 60
	v_lshlrev_b64 v[2:3], 11, v[2:3]
	v_readlane_b32 s1, v253, 61
	s_lshl_b32 s60, s35, 1
	s_mov_b32 s49, s61
	v_lshl_add_u64 v[2:3], s[0:1], 0, v[2:3]
	v_lshl_add_u64 v[2:3], v[2:3], 0, s[60:61]
	s_mov_b32 s51, s61
	v_lshl_add_u64 v[2:3], v[2:3], 0, s[48:49]
	v_lshl_add_u64 v[2:3], v[2:3], 0, s[50:51]
	v_cvt_pk_bf16_f32 v4, v26, v26
	v_lshl_add_u64 v[34:35], v[2:3], 0, v[196:197]
	s_mov_b64 s[0:1], 0x3c0000
	v_and_b32_e32 v4, 0xffff, v4
	v_lshl_add_u64 v[2:3], v[34:35], 0, s[0:1]
	global_store_short v[2:3], v4, off
	v_cvt_pk_bf16_f32 v4, v27, v27
	s_mov_b64 s[0:1], 0x3c0800
	v_and_b32_e32 v4, 0xffff, v4
	v_lshl_add_u64 v[2:3], v[34:35], 0, s[0:1]
	global_store_short v[2:3], v4, off
	v_cvt_pk_bf16_f32 v4, v28, v28
	s_mov_b64 s[0:1], 0x3c1000
	v_and_b32_e32 v4, 0xffff, v4
	v_lshl_add_u64 v[2:3], v[34:35], 0, s[0:1]
	global_store_short v[2:3], v4, off
	s_mov_b64 s[0:1], 0x3c1800
	v_cvt_pk_bf16_f32 v4, v29, v29
	v_lshl_add_u64 v[2:3], v[34:35], 0, s[0:1]
	v_and_b32_e32 v4, 0xffff, v4
	global_store_short v[2:3], v4, off
	s_waitcnt lgkmcnt(0)
	s_barrier
	ds_read_b128 v[2:5], v149 offset:54784
	ds_read_b128 v[10:13], v149 offset:54848
	ds_read_b128 v[14:17], v162
	ds_read_b128 v[18:21], v162 offset:64
	ds_read_b128 v[26:29], v147 offset:65024
	s_waitcnt lgkmcnt(2)
	v_mfma_f32_16x16x32_bf16 v[2:5], v[2:5], v[14:17], 0
	s_add_i32 s0, 0, 0x1d000
	v_add3_u32 v31, s0, v145, v146
	ds_read_b128 v[14:17], v31
	ds_read_b128 v[206:209], v147 offset:65088
	ds_read_b128 v[210:213], v31 offset:64
	ds_read_b128 v[214:217], v147 offset:65152
	ds_read_b128 v[218:221], v31 offset:128
	ds_read_b128 v[222:225], v147 offset:65216
	s_waitcnt lgkmcnt(7)
	v_mfma_f32_16x16x32_bf16 v[2:5], v[10:13], v[18:21], v[2:5]
	s_nop 0
	s_nop 0
	v_add_u32_e32 v30, s52, v30
	s_mov_b64 s[0:1], 0x3e0000
	s_waitcnt lgkmcnt(5)
	v_mfma_f32_16x16x32_bf16 v[2:5], v[26:29], v[14:17], v[2:5]
	s_nop 0
	s_nop 0
	v_lshlrev_b32_e32 v196, 2, v140
	s_waitcnt lgkmcnt(3)
	v_mfma_f32_16x16x32_bf16 v[2:5], v[206:209], v[210:213], v[2:5]
	ds_read_b128 v[18:21], v31 offset:192
	ds_read_b128 v[206:209], v161
	ds_read_b128 v[210:213], v30
	s_nop 0
	s_nop 0
	s_waitcnt lgkmcnt(4)
	v_mfma_f32_16x16x32_bf16 v[2:5], v[214:217], v[218:221], v[2:5]
	ds_read_b128 v[214:217], v163
	ds_read_b128 v[218:221], v163 offset:2560
	s_nop 0
	s_nop 0
	s_nop 0
	s_waitcnt lgkmcnt(2)
	v_pk_mul_f32 v[8:9], v[8:9], v[212:213]
	v_mfma_f32_16x16x32_bf16 v[2:5], v[222:225], v[18:21], v[2:5]
	ds_read_b128 v[18:21], v161 offset:64
	ds_read_b128 v[222:225], v164
	s_nop 0
	s_nop 0
	v_pk_mul_f32 v[6:7], v[6:7], v[210:211]
	v_pk_mul_f32 v[24:25], v[24:25], v[212:213]
	v_pk_mul_f32 v[22:23], v[22:23], v[210:211]
	ds_read_b128 v[210:213], v164 offset:2560
	s_waitcnt lgkmcnt(4)
	v_mfma_f32_16x16x32_bf16 v[6:9], v[206:209], v[214:217], v[6:9]
	s_nop 0
	v_cvt_pk_bf16_f32 v2, v2, v2
	v_and_b32_e32 v2, 0xffff, v2
	v_cvt_pk_bf16_f32 v4, v4, v4
	s_waitcnt lgkmcnt(3)
	v_mfma_f32_16x16x32_bf16 v[10:13], v[206:209], v[218:221], v[22:25]
	s_nop 0
	s_nop 1
	s_nop 0
	v_and_b32_e32 v4, 0xffff, v4
	s_waitcnt lgkmcnt(1)
	v_mfma_f32_16x16x32_bf16 v[6:9], v[18:21], v[222:225], v[6:9]
	s_waitcnt lgkmcnt(0)
	v_mfma_f32_16x16x32_bf16 v[10:13], v[18:21], v[210:213], v[10:13]
	s_nop 5
	v_cvt_pk_bf16_f32 v14, v6, v7
	v_cvt_pk_bf16_f32 v15, v8, v9
	v_cvt_pk_bf16_f32 v16, v10, v11
	v_cvt_pk_bf16_f32 v17, v12, v13
	ds_write2st64_b64 v151, v[14:15], v[16:17] offset1:9
	v_lshl_add_u64 v[14:15], v[34:35], 0, s[0:1]
	global_store_short v[14:15], v2, off
	s_mov_b64 s[0:1], 0x3e0800
	v_cvt_pk_bf16_f32 v2, v3, v3
	v_lshl_add_u64 v[14:15], v[34:35], 0, s[0:1]
	v_and_b32_e32 v2, 0xffff, v2
	s_mov_b64 s[0:1], 0x3e1000
	global_store_short v[14:15], v2, off
	v_lshl_add_u64 v[2:3], v[34:35], 0, s[0:1]
	s_mov_b64 s[0:1], 0x3e1800
	global_store_short v[2:3], v4, off
	v_lshl_add_u64 v[2:3], v[34:35], 0, s[0:1]
	v_readlane_b32 s0, v255, 25
	s_add_u32 s0, s0, s6
	v_readlane_b32 s1, v255, 26
	s_addc_u32 s1, s1, s7
	s_lshl_b32 s4, s31, 17
	s_add_u32 s0, s0, s4
	v_cvt_pk_bf16_f32 v4, v5, v5
	s_addc_u32 s1, s1, 0
	s_lshl_b32 s4, s34, 2
	v_and_b32_e32 v4, 0xffff, v4
	global_store_short v[2:3], v4, off
	v_or_b32_e32 v2, s47, v152
	s_add_u32 s0, s0, s4
	s_addc_u32 s1, s1, 0
	v_ashrrev_i32_e32 v3, 31, v2
	v_or_b32_e32 v16, 1, v2
	v_lshl_add_u64 v[4:5], s[0:1], 0, v[196:197]
	v_lshlrev_b64 v[14:15], 10, v[2:3]
	v_ashrrev_i32_e32 v17, 31, v16
	v_lshl_add_u64 v[14:15], v[4:5], 0, v[14:15]
	v_lshlrev_b64 v[16:17], 10, v[16:17]
	global_store_dword v[14:15], v6, off
	v_lshl_add_u64 v[16:17], v[4:5], 0, v[16:17]
	v_or_b32_e32 v6, 2, v2
	v_or_b32_e32 v2, 3, v2
	global_store_dword v[16:17], v7, off
	v_ashrrev_i32_e32 v7, 31, v6
	v_ashrrev_i32_e32 v3, 31, v2
	v_lshlrev_b64 v[6:7], 10, v[6:7]
	v_lshlrev_b64 v[2:3], 10, v[2:3]
	v_lshl_add_u64 v[6:7], v[4:5], 0, v[6:7]
	v_lshl_add_u64 v[2:3], v[4:5], 0, v[2:3]
	global_store_dword v[6:7], v8, off
	global_store_dword v[2:3], v9, off
	global_store_dword v[14:15], v10, off offset:64
	global_store_dword v[16:17], v11, off offset:64
	global_store_dword v[6:7], v12, off offset:64
	global_store_dword v[2:3], v13, off offset:64
	s_waitcnt lgkmcnt(0)
	s_barrier

.LBB0_1547:
	s_or_b64 exec, exec, s[4:5]
	s_or_b32 s4, s34, 1
	s_lshl_b32 s0, s4, 5
	s_or_b32 s45, s0, s78
	s_lshl_b32 s5, s45, 13
	s_add_u32 s0, s40, s5
	s_addc_u32 s1, s41, 0
	v_lshl_add_u64 v[2:3], s[0:1], 0, v[156:157]
	s_add_u32 s0, s62, s5
	s_addc_u32 s1, s63, 0
	global_load_dwordx4 v[42:45], v[2:3], off
	v_lshl_add_u64 v[2:3], s[0:1], 0, v[156:157]
	s_add_u32 s0, s42, s5
	s_addc_u32 s1, s43, 0
	global_load_dwordx4 v[46:49], v[2:3], off
	v_lshl_add_u64 v[2:3], s[0:1], 0, v[156:157]
	s_lshl_b32 s0, s4, 16
	s_lshl_b32 s5, s44, 1
	s_or_b32 s0, s0, s5
	s_add_u32 s0, s77, s0
	s_addc_u32 s1, s28, 0
	global_load_dwordx4 v[50:53], v[2:3], off
	v_lshl_add_u64 v[2:3], s[0:1], 0, v[156:157]
	global_load_dwordx4 v[58:61], v[2:3], off
	v_lshl_add_u64 v[2:3], s[0:1], 0, v[158:159]
	s_lshl_b32 s0, s45, 8
	s_add_u32 s0, s58, s0
	s_addc_u32 s1, s59, 0
	v_or_b32_e32 v196, s6, v170
	global_load_dwordx4 v[62:65], v[2:3], off
	global_load_dwordx4 v[54:57], v134, s[0:1]
	v_lshl_add_u64 v[2:3], s[46:47], 0, v[196:197]
	v_lshl_add_u64 v[4:5], v[2:3], 0, 64
	v_mov_b64_e32 v[6:7], s[80:81]
	v_mad_u64_u32 v[8:9], s[0:1], v4, s19, v[6:7]
	v_mad_i32_i24 v9, v5, s19, v9
	s_lshl_b32 s60, s50, 1
	v_lshl_add_u64 v[4:5], v[8:9], 0, s[60:61]
	v_lshlrev_b32_e32 v196, 1, v187
	v_lshl_add_u64 v[4:5], v[4:5], 0, v[196:197]
	s_mov_b64 s[50:51], 0x1400
	s_movk_i32 s52, 0x1000
	v_lshl_add_u64 v[8:9], v[4:5], 0, s[50:51]
	v_add_co_u32_e64 v4, s[44:45], s52, v4
	s_or_b32 s4, s34, 2
	s_nop 0
	v_addc_co_u32_e64 v5, s[44:45], 0, v5, s[44:45]
	s_lshl_b32 s0, s4, 5
	s_or_b32 s44, s0, s78
	s_lshl_b32 s45, s44, 13
	s_add_u32 s0, s40, s45
	s_addc_u32 s1, s41, 0
	global_load_dwordx4 v[86:89], v[4:5], off offset:1024
	global_load_dwordx4 v[94:97], v[8:9], off offset:64
	global_load_dwordx4 v[90:93], v[8:9], off offset:128
	global_load_dwordx4 v[82:85], v[8:9], off offset:192
	v_lshl_add_u64 v[4:5], s[0:1], 0, v[156:157]
	s_add_u32 s0, s62, s45
	s_addc_u32 s1, s63, 0
	global_load_dwordx4 v[18:21], v[4:5], off
	v_lshl_add_u64 v[4:5], s[0:1], 0, v[156:157]
	s_add_u32 s0, s42, s45
	s_addc_u32 s1, s43, 0
	global_load_dwordx4 v[22:25], v[4:5], off
	v_lshl_add_u64 v[4:5], s[0:1], 0, v[156:157]
	s_lshl_b32 s0, s4, 16
	s_or_b32 s0, s0, s5
	s_add_u32 s0, s77, s0
	s_addc_u32 s1, s28, 0
	global_load_dwordx4 v[26:29], v[4:5], off
	v_lshl_add_u64 v[4:5], s[0:1], 0, v[156:157]
	global_load_dwordx4 v[30:33], v[4:5], off
	v_lshl_add_u64 v[4:5], s[0:1], 0, v[158:159]
	s_lshl_b32 s0, s44, 8
	s_add_u32 s0, s58, s0
	s_addc_u32 s1, s59, 0
	v_lshl_add_u64 v[2:3], v[2:3], 0, s[16:17]
	global_load_dwordx4 v[34:37], v[4:5], off
	global_load_dwordx4 v[38:41], v134, s[0:1]
	v_mad_u64_u32 v[4:5], s[0:1], v2, s19, v[6:7]
	v_mad_i32_i24 v5, v3, s19, v5
	v_lshl_add_u64 v[2:3], v[4:5], 0, s[60:61]
	v_lshl_add_u64 v[2:3], v[2:3], 0, v[196:197]
	v_and_b32_e32 v139, 48, v98
	v_lshrrev_b32_e32 v98, 1, v98
	v_lshl_add_u64 v[14:15], v[2:3], 0, s[50:51]
	v_add_co_u32_e64 v2, s[44:45], s52, v2
	v_and_b32_e32 v98, 24, v98
	s_nop 0
	v_addc_co_u32_e64 v3, s[44:45], 0, v3, s[44:45]
	v_lshlrev_b32_e32 v140, 1, v98
	s_lshl_b32 s0, s49, 6
	s_and_b32 s45, s48, 32
	v_or_b32_e32 v160, s46, v170
	v_add_u32_e32 v136, 0, v140
	s_movk_i32 s48, 0xa0
	s_add_i32 s44, s0, 0
	v_mad_u64_u32 v[150:151], s[0:1], v160, s48, v[136:137]
	s_add_i32 s0, 0, 0x19200
	s_lshl_b32 s4, s8, 4
	global_load_dwordx4 v[2:5], v[2:3], off offset:1024
	s_nop 0
	global_load_dwordx4 v[10:13], v[14:15], off offset:64
	global_load_dwordx4 v[6:9], v[14:15], off offset:128
	s_nop 0
	global_load_dwordx4 v[14:17], v[14:15], off offset:192
	v_add_u32_e32 v189, s0, v140
	v_or_b32_e32 v135, s45, v170
	s_movk_i32 s0, 0x120
	v_or_b32_e32 v98, s4, v170
	s_add_i32 s9, s9, 0x1da00
	v_add_u32_e32 v176, s44, v139
	v_mad_u32_u24 v130, v135, s0, v189
	v_mul_lo_u32 v141, v98, s48
	v_add_u32_e32 v98, s9, v137
	v_readlane_b32 s0, v253, 16
	s_waitcnt lgkmcnt(0)
	s_barrier
	v_mad_u32_u24 v126, v135, s48, v136
	v_add_u32_e32 v174, v98, v187
	v_add_u32_e32 v173, s0, v99
	v_add_u32_e32 v175, s0, v100
	ds_read_b128 v[98:101], v176 offset:51200
	ds_read_b128 v[110:113], v150
	ds_read_b128 v[106:109], v126 offset:10240
	ds_read_b128 v[114:117], v150 offset:64
	ds_read_b128 v[118:121], v126 offset:10304
	ds_read_b128 v[102:105], v130
	ds_read_b128 v[122:125], v130 offset:64
	ds_read_b128 v[206:209], v130 offset:128
	ds_read_b128 v[210:213], v130 offset:192
	ds_read_b128 v[214:217], v126 offset:12800
	ds_read_b128 v[218:221], v126 offset:12864
	ds_read_b128 v[222:225], v130 offset:4608
	s_waitcnt lgkmcnt(6)
	v_mfma_f32_16x16x32_bf16 v[102:105], v[74:77], v[102:105], 0
	v_add_u32_e32 v180, v136, v141
	v_mad_u32_u24 v179, v170, s48, v136
	s_mov_b64 s[20:21], 0x1400
	s_waitcnt lgkmcnt(5)
	v_mfma_f32_16x16x32_bf16 v[102:105], v[78:81], v[122:125], v[102:105]
	s_nop 0
	s_movk_i32 s14, 0x1000
	s_movk_i32 s26, 0xa0
	s_waitcnt lgkmcnt(4)
	v_mfma_f32_16x16x32_bf16 v[102:105], v[70:73], v[206:209], v[102:105]
	ds_read_b128 v[206:209], v130 offset:4672
	s_nop 0
	v_add_u32_e32 v172, 0x11900, v171
	v_add_u32_e32 v185, 0x19100, v177
	v_mfma_f32_16x16x32_bf16 v[106:109], v[110:113], v[106:109], 0
	s_waitcnt lgkmcnt(4)
	v_mfma_f32_16x16x32_bf16 v[102:105], v[66:69], v[210:213], v[102:105]
	ds_read_b128 v[210:213], v130 offset:4736
	v_mfma_f32_16x16x32_bf16 v[106:109], v[114:117], v[118:121], v[106:109]
	s_nop 0
	s_nop 0
	s_nop 0
	s_waitcnt lgkmcnt(2)
	v_mfma_f32_16x16x32_bf16 v[74:77], v[74:77], v[222:225], 0
	ds_read_b128 v[222:225], v130 offset:4800
	s_nop 0
	s_waitcnt lgkmcnt(2)
	v_mfma_f32_16x16x32_bf16 v[74:77], v[78:81], v[206:209], v[74:77]
	ds_read_b32 v206, v197 offset:51452
	s_nop 0
	s_waitcnt lgkmcnt(2)
	v_mfma_f32_16x16x32_bf16 v[70:73], v[70:73], v[210:213], v[74:77]
	ds_read_b128 v[210:213], v180 offset:30720
	s_nop 4
	s_nop 0
	s_waitcnt lgkmcnt(2)
	v_mfma_f32_16x16x32_bf16 v[126:129], v[66:69], v[222:225], v[70:73]
	ds_read_b128 v[74:77], v179 offset:20480
	ds_read_b128 v[78:81], v179 offset:23040
	ds_read_b128 v[222:225], v179 offset:25600
	v_mfma_f32_16x16x32_bf16 v[66:69], v[110:113], v[214:217], 0
	ds_read_b128 v[214:217], v179 offset:28160
	v_mfma_f32_16x16x32_bf16 v[130:133], v[114:117], v[218:221], v[66:69]
	ds_read_b128 v[218:221], v180 offset:30784
	s_nop 6
	s_nop 0
	s_nop 0
	s_nop 0
	s_nop 0
	s_nop 0
	s_waitcnt lgkmcnt(6)
	v_mul_f32_e32 v66, 0, v206
	ds_read_b128 v[206:209], v179 offset:20544
	v_mov_b32_e32 v67, v66
	v_mov_b32_e32 v68, v66
	v_mov_b32_e32 v69, v66
	s_waitcnt lgkmcnt(3)
	s_nop 0
	v_mfma_f32_16x16x32_bf16 v[118:121], v[210:213], v[222:225], v[66:69]
	ds_read_b128 v[222:225], v179 offset:23104
	s_nop 0
	v_mfma_f32_16x16x32_bf16 v[74:77], v[210:213], v[74:77], v[66:69]
	v_mfma_f32_16x16x32_bf16 v[78:81], v[210:213], v[78:81], v[66:69]
	s_waitcnt lgkmcnt(3)
	v_mfma_f32_16x16x32_bf16 v[66:69], v[210:213], v[214:217], v[66:69]
	ds_read_b128 v[210:213], v179 offset:25664
	ds_read_b128 v[214:217], v179 offset:28224
	s_nop 0
	s_nop 0
	s_waitcnt lgkmcnt(3)
	v_mfma_f32_16x16x32_bf16 v[110:113], v[218:221], v[206:209], v[74:77]
	s_nop 2
	s_nop 0
	s_waitcnt lgkmcnt(2)
	v_mfma_f32_16x16x32_bf16 v[114:117], v[218:221], v[222:225], v[78:81]
	s_nop 0
	s_waitcnt lgkmcnt(1)
	v_mfma_f32_16x16x32_bf16 v[118:121], v[218:221], v[210:213], v[118:121]
	s_nop 0
	s_waitcnt lgkmcnt(0)
	v_mfma_f32_16x16x32_bf16 v[122:125], v[218:221], v[214:217], v[66:69]
	s_nop 2
	v_cvt_pk_bf16_f32 v66, v110, v111
	v_cvt_pk_bf16_f32 v67, v112, v113
	v_cvt_pk_bf16_f32 v68, v114, v115
	v_cvt_pk_bf16_f32 v69, v116, v117
	ds_write2st64_b64 v174, v[66:67], v[68:69] offset1:9
	v_cvt_pk_bf16_f32 v66, v118, v119
	v_cvt_pk_bf16_f32 v67, v120, v121
	v_cvt_pk_bf16_f32 v68, v122, v123
	v_cvt_pk_bf16_f32 v69, v124, v125
	ds_write2st64_b64 v174, v[66:67], v[68:69] offset0:18 offset1:27
	s_waitcnt vmcnt(19)
	ds_write_b128 v171, v[42:45] offset:51456
	s_waitcnt vmcnt(18)
	ds_write_b128 v171, v[46:49] offset:61696
	s_waitcnt vmcnt(17)
	ds_write_b128 v172, v[50:53]
	s_waitcnt vmcnt(16)
	ds_write_b128 v173, v[58:61]
	s_waitcnt vmcnt(15)
	ds_write_b128 v175, v[62:65]
	s_and_saveexec_b64 s[8:9], vcc
	s_cbranch_execz .LBB0_1549
	s_waitcnt vmcnt(14)
	ds_write_b128 v185, v[54:57]
.LBB0_1549:
	s_or_b64 exec, exec, s[8:9]
	s_lshl_b32 s0, s78, 7
	v_readlane_b32 s1, v255, 19
	s_add_u32 s0, s1, s0
	v_readlane_b32 s1, v255, 20
	s_addc_u32 s1, s1, 0
	s_lshl_b32 s8, s45, 1
	s_add_u32 s0, s0, s8
	s_addc_u32 s1, s1, 0
	v_lshlrev_b32_e32 v42, 1, v170
	v_mov_b32_e32 v43, v197
	v_lshl_add_u64 v[154:155], s[0:1], 0, v[42:43]
	s_add_i32 s0, 0, 0x1da00
	v_lshlrev_b32_e32 v151, 2, v138
	v_add_u32_e32 v138, s0, v140
	v_readlane_b32 s0, v253, 16
	v_mul_u32_u24_e32 v44, 0xa0, v170
	s_or_b32 s9, s34, 3
	v_add3_u32 v183, s0, v141, v140
	s_add_i32 s0, 0, 0x11900
	v_add3_u32 v184, s0, v44, v140
	v_readlane_b32 s0, v253, 17
	v_add_u32_e32 v191, s35, v137
	v_lshl_add_u64 v[168:169], s[40:41], 0, v[156:157]
	v_add3_u32 v182, s0, v44, v140
	s_lshl_b32 s0, s9, 5
	s_or_b32 s35, s0, s78
	s_lshl_b32 s0, s35, 13
	s_mov_b32 s1, s61
	v_lshl_add_u64 v[166:167], s[62:63], 0, v[156:157]
	v_lshl_add_u64 v[42:43], v[168:169], 0, s[0:1]
	v_lshl_add_u64 v[164:165], s[42:43], 0, v[156:157]
	global_load_dwordx4 v[58:61], v[42:43], off
	v_lshl_add_u64 v[42:43], v[166:167], 0, s[0:1]
	global_load_dwordx4 v[62:65], v[42:43], off
	v_lshl_add_u64 v[42:43], v[164:165], 0, s[0:1]
	s_lshl_b32 s0, s9, 16
	s_add_i32 s8, s44, 0x19100
	s_or_b32 s0, s0, s5
	s_add_u32 s0, s77, s0
	s_addc_u32 s1, s28, 0
	v_mul_u32_u24_e32 v142, 0xa0, v135
	v_mul_u32_u24_e32 v190, 0x120, v135
	v_mov_b32_e32 v135, v197
	global_load_dwordx4 v[66:69], v[42:43], off
	v_lshl_add_u64 v[42:43], s[0:1], 0, v[156:157]
	v_lshl_add_u64 v[162:163], s[58:59], 0, v[134:135]
	global_load_dwordx4 v[70:73], v[42:43], off
	v_lshl_add_u64 v[42:43], s[0:1], 0, v[158:159]
	s_lshl_b32 s0, s35, 8
	s_mov_b32 s1, s61
	v_mov_b32_e32 v161, s47
	v_or_b32_e32 v152, s46, v151
	v_mov_b32_e32 v153, s47
	global_load_dwordx4 v[74:77], v[42:43], off
	v_lshl_add_u64 v[42:43], v[162:163], 0, s[0:1]
	s_or_b32 s46, s6, 0xc0
	s_mov_b32 s47, s61
	global_load_dwordx4 v[78:81], v[42:43], off
	v_lshl_add_u64 v[42:43], v[160:161], 0, s[46:47]
	v_mov_b64_e32 v[44:45], s[80:81]
	v_mad_u64_u32 v[44:45], s[0:1], v42, s19, v[44:45]
	v_mad_i32_i24 v45, v43, s19, v45
	v_lshl_add_u64 v[42:43], v[44:45], 0, s[60:61]
	v_lshl_add_u64 v[42:43], v[42:43], 0, v[196:197]
	v_pk_fma_f32 v[126:127], v[98:99], v[126:127], v[130:131]
	v_pk_fma_f32 v[98:99], v[98:99], v[102:103], v[106:107]
	s_waitcnt vmcnt(20)
	v_lshl_add_u64 v[54:55], v[42:43], 0, s[20:21]
	v_add_co_u32_e64 v42, s[44:45], s14, v42
	v_lshl_add_u64 v[102:103], v[152:153], 0, s[6:7]
	v_cvt_pk_bf16_f32 v98, v98, v98
	v_addc_co_u32_e64 v43, s[44:45], 0, v43, s[44:45]
	v_pk_fma_f32 v[128:129], v[100:101], v[128:129], v[132:133]
	v_pk_fma_f32 v[100:101], v[100:101], v[104:105], v[108:109]
	v_lshlrev_b64 v[102:103], 12, v[102:103]
	v_and_b32_e32 v98, 0xffff, v98
	global_load_dwordx4 v[42:45], v[42:43], off offset:1024
	s_nop 0
	global_load_dwordx4 v[50:53], v[54:55], off offset:64
	global_load_dwordx4 v[46:49], v[54:55], off offset:128
	s_nop 0
	global_load_dwordx4 v[54:57], v[54:55], off offset:192
	v_lshl_add_u64 v[102:103], v[154:155], 0, v[102:103]
	global_store_short v[102:103], v98, off
	v_cvt_pk_bf16_f32 v98, v99, v99
	v_cvt_pk_bf16_f32 v100, v100, v100
	v_lshl_add_u64 v[104:105], v[102:103], 0, s[86:87]
	v_and_b32_e32 v98, 0xffff, v98
	global_store_short v[104:105], v98, off
	v_and_b32_e32 v100, 0xffff, v100
	v_lshl_add_u64 v[98:99], v[102:103], 0, s[74:75]
	global_store_short v[98:99], v100, off
	v_cvt_pk_bf16_f32 v100, v101, v101
	v_and_b32_e32 v100, 0xffff, v100
	v_lshl_add_u64 v[98:99], v[102:103], 0, s[66:67]
	global_store_short v[98:99], v100, off
	v_cvt_pk_bf16_f32 v100, v126, v126
	v_and_b32_e32 v100, 0xffff, v100
	v_lshl_add_u64 v[98:99], v[102:103], 0, 32
	global_store_short v[98:99], v100, off
	v_cvt_pk_bf16_f32 v100, v127, v127
	v_and_b32_e32 v100, 0xffff, v100
	v_lshl_add_u64 v[98:99], v[102:103], 0, s[22:23]
	global_store_short v[98:99], v100, off
	v_cvt_pk_bf16_f32 v100, v128, v128
	v_and_b32_e32 v100, 0xffff, v100
	v_lshl_add_u64 v[98:99], v[102:103], 0, s[12:13]
	global_store_short v[98:99], v100, off
	v_cvt_pk_bf16_f32 v100, v129, v129
	v_lshl_add_u64 v[98:99], v[102:103], 0, s[56:57]
	v_and_b32_e32 v100, 0xffff, v100
	global_store_short v[98:99], v100, off
	s_waitcnt lgkmcnt(0)
	s_barrier
	v_add_u32_e32 v181, s8, v139
	ds_read_b128 v[98:101], v181
	ds_read_b128 v[130:133], v150 offset:51456
	v_add_u32_e32 v186, v136, v142
	ds_read_b128 v[106:109], v186 offset:61696
	ds_read_b128 v[134:137], v150 offset:51520
	ds_read_b128 v[126:129], v186 offset:61760
	v_add_u32_e32 v188, v138, v190
	ds_read_b128 v[102:105], v188
	ds_read_b128 v[138:141], v188 offset:64
	ds_read_b128 v[206:209], v188 offset:128
	ds_read_b128 v[210:213], v188 offset:192
	ds_read_b128 v[214:217], v186 offset:64256
	ds_read_b128 v[142:145], v186 offset:64320
	ds_read_b128 v[218:221], v188 offset:4608
	ds_read_b128 v[222:225], v188 offset:4672
	s_nop 0
	s_nop 0
	s_nop 0
	s_nop 0
	s_nop 0
	s_nop 0
	s_nop 0
	s_waitcnt vmcnt(23) lgkmcnt(7)
	v_mfma_f32_16x16x32_bf16 v[102:105], v[86:89], v[102:105], 0
	v_readlane_b32 s0, v253, 18
	v_add_u32_e32 v187, v191, v187
	s_waitcnt vmcnt(22) lgkmcnt(6)
	v_mfma_f32_16x16x32_bf16 v[102:105], v[94:97], v[138:141], v[102:105]
	s_nop 0
	s_waitcnt vmcnt(21) lgkmcnt(5)
	v_mfma_f32_16x16x32_bf16 v[102:105], v[90:93], v[206:209], v[102:105]
	s_nop 0
	v_mfma_f32_16x16x32_bf16 v[106:109], v[130:133], v[106:109], 0
	s_waitcnt vmcnt(20) lgkmcnt(4)
	v_mfma_f32_16x16x32_bf16 v[102:105], v[82:85], v[210:213], v[102:105]
	v_mfma_f32_16x16x32_bf16 v[106:109], v[134:137], v[126:129], v[106:109]
	s_nop 0
	s_nop 0
	s_nop 0
	s_waitcnt lgkmcnt(1)
	v_mfma_f32_16x16x32_bf16 v[86:89], v[86:89], v[218:221], 0
	s_nop 0
	s_waitcnt lgkmcnt(0)
	v_mfma_f32_16x16x32_bf16 v[86:89], v[94:97], v[222:225], v[86:89]
	ds_read_b128 v[94:97], v188 offset:4736
	ds_read_b128 v[206:209], v188 offset:4800
	s_waitcnt lgkmcnt(1)
	v_mfma_f32_16x16x32_bf16 v[86:89], v[90:93], v[94:97], v[86:89]
	s_nop 0
	s_waitcnt lgkmcnt(0)
	v_mfma_f32_16x16x32_bf16 v[126:129], v[82:85], v[206:209], v[86:89]
	v_mfma_f32_16x16x32_bf16 v[82:85], v[130:133], v[214:217], 0
	v_mfma_f32_16x16x32_bf16 v[130:133], v[134:137], v[142:145], v[82:85]
	s_nop 6
	v_mov_b32_e32 v82, s0
	ds_read_b32 v94, v82
	ds_read_b128 v[210:213], v183
	ds_read_b128 v[214:217], v184
	ds_read_b128 v[218:221], v184 offset:2560
	ds_read_b128 v[222:225], v184 offset:5120
	s_waitcnt lgkmcnt(4)
	v_pk_mul_f32 v[84:85], v[112:113], v[94:95] op_sel_hi:[1,0]
	v_pk_mul_f32 v[82:83], v[110:111], v[94:95] op_sel_hi:[1,0]
	v_pk_mul_f32 v[88:89], v[116:117], v[94:95] op_sel_hi:[1,0]
	v_pk_mul_f32 v[86:87], v[114:115], v[94:95] op_sel_hi:[1,0]
	s_nop 0
	s_nop 0
	s_waitcnt lgkmcnt(2)
	v_mfma_f32_16x16x32_bf16 v[82:85], v[210:213], v[214:217], v[82:85]
	ds_read_b128 v[214:217], v184 offset:7680
	s_nop 0
	v_pk_mul_f32 v[92:93], v[120:121], v[94:95] op_sel_hi:[1,0]
	v_pk_mul_f32 v[90:91], v[118:119], v[94:95] op_sel_hi:[1,0]
	ds_read_b128 v[206:209], v183 offset:64
	s_waitcnt lgkmcnt(3)
	v_mfma_f32_16x16x32_bf16 v[86:89], v[210:213], v[218:221], v[86:89]
	ds_read_b128 v[218:221], v182
	s_nop 0
	v_pk_mul_f32 v[96:97], v[124:125], v[94:95] op_sel_hi:[1,0]
	v_pk_mul_f32 v[94:95], v[122:123], v[94:95] op_sel_hi:[1,0]
	s_waitcnt lgkmcnt(3)
	v_mfma_f32_16x16x32_bf16 v[90:93], v[210:213], v[222:225], v[90:93]
	ds_read_b128 v[222:225], v182 offset:2560
	s_nop 0
	s_waitcnt lgkmcnt(3)
	v_mfma_f32_16x16x32_bf16 v[94:97], v[210:213], v[214:217], v[94:97]
	ds_read_b128 v[210:213], v182 offset:5120
	ds_read_b128 v[214:217], v182 offset:7680
	s_nop 0
	s_nop 0
	s_waitcnt lgkmcnt(3)
	v_mfma_f32_16x16x32_bf16 v[134:137], v[206:209], v[218:221], v[82:85]
	s_nop 2
	s_nop 0
	s_waitcnt lgkmcnt(2)
	v_mfma_f32_16x16x32_bf16 v[142:145], v[206:209], v[222:225], v[86:89]
	s_nop 0
	s_waitcnt lgkmcnt(1)
	v_mfma_f32_16x16x32_bf16 v[138:141], v[206:209], v[210:213], v[90:93]
	s_nop 0
	s_waitcnt lgkmcnt(0)
	v_mfma_f32_16x16x32_bf16 v[146:149], v[206:209], v[214:217], v[94:97]
	v_cvt_pk_bf16_f32 v82, v134, v135
	v_cvt_pk_bf16_f32 v83, v136, v137
	v_cvt_pk_bf16_f32 v84, v142, v143
	v_cvt_pk_bf16_f32 v85, v144, v145
	ds_write2st64_b64 v187, v[82:83], v[84:85] offset1:9
	v_cvt_pk_bf16_f32 v82, v138, v139
	v_cvt_pk_bf16_f32 v83, v140, v141
	s_nop 0
	v_cvt_pk_bf16_f32 v84, v146, v147
	v_cvt_pk_bf16_f32 v85, v148, v149
	ds_write2st64_b64 v187, v[82:83], v[84:85] offset0:18 offset1:27
	s_waitcnt vmcnt(19)
	ds_write_b128 v171, v[18:21]
	s_waitcnt vmcnt(18)
	ds_write_b128 v171, v[22:25] offset:10240
	s_waitcnt vmcnt(17)
	ds_write_b128 v171, v[26:29] offset:20480
	s_waitcnt vmcnt(16)
	ds_write_b128 v171, v[30:33] offset:30720
	s_waitcnt vmcnt(15)
	ds_write_b128 v178, v[34:37] offset:30720
	s_and_saveexec_b64 s[8:9], vcc
	s_cbranch_execz .LBB0_1551
	s_waitcnt vmcnt(14)
	ds_write_b128 v177, v[38:41] offset:51200
.LBB0_1551:
	s_or_b64 exec, exec, s[8:9]
	s_or_b32 s7, s34, 4
	s_lshl_b32 s0, s7, 5
	s_or_b32 s8, s0, s78
	s_lshl_b32 s0, s8, 13
	s_mov_b32 s1, s61
	v_lshl_add_u64 v[18:19], v[168:169], 0, s[0:1]
	v_lshl_add_u64 v[20:21], v[166:167], 0, s[0:1]
	global_load_dwordx4 v[34:37], v[18:19], off
	global_load_dwordx4 v[38:41], v[20:21], off
	v_lshl_add_u64 v[18:19], v[164:165], 0, s[0:1]
	s_lshl_b32 s0, s7, 16
	s_or_b32 s0, s0, s5
	s_add_u32 s0, s77, s0
	s_addc_u32 s1, s28, 0
	v_lshl_add_u64 v[20:21], s[0:1], 0, v[156:157]
	global_load_dwordx4 v[82:85], v[18:19], off
	global_load_dwordx4 v[86:89], v[20:21], off
	v_lshl_add_u64 v[18:19], s[0:1], 0, v[158:159]
	s_lshl_b32 s0, s8, 8
	s_mov_b32 s1, s61
	v_lshl_add_u64 v[20:21], v[162:163], 0, s[0:1]
	s_or_b32 s48, s6, 0x100
	s_mov_b32 s49, s61
	global_load_dwordx4 v[94:97], v[18:19], off
	global_load_dwordx4 v[90:93], v[20:21], off
	v_lshl_add_u64 v[18:19], v[160:161], 0, s[48:49]
	v_mov_b64_e32 v[20:21], s[80:81]
	v_mad_u64_u32 v[20:21], s[0:1], v18, s19, v[20:21]
	v_mad_i32_i24 v21, v19, s19, v21
	v_lshl_add_u64 v[18:19], v[20:21], 0, s[60:61]
	v_lshl_add_u64 v[18:19], v[18:19], 0, v[196:197]
	v_pk_fma_f32 v[112:113], v[98:99], v[126:127], v[130:131]
	v_pk_fma_f32 v[98:99], v[98:99], v[102:103], v[106:107]
	s_or_b32 s0, s6, 64
	s_mov_b32 s1, s61
	v_add_co_u32_e64 v24, s[44:45], s14, v18
	v_lshl_add_u64 v[102:103], v[152:153], 0, s[0:1]
	v_cvt_pk_bf16_f32 v98, v98, v98
	v_lshl_add_u64 v[22:23], v[18:19], 0, s[20:21]
	v_addc_co_u32_e64 v25, s[44:45], 0, v19, s[44:45]
	v_pk_fma_f32 v[110:111], v[100:101], v[128:129], v[132:133]
	v_pk_fma_f32 v[100:101], v[100:101], v[104:105], v[108:109]
	v_lshlrev_b64 v[102:103], 12, v[102:103]
	v_and_b32_e32 v98, 0xffff, v98
	global_load_dwordx4 v[26:29], v[22:23], off offset:64
	global_load_dwordx4 v[18:21], v[22:23], off offset:128
	global_load_dwordx4 v[30:33], v[24:25], off offset:1024
	s_nop 0
	global_load_dwordx4 v[22:25], v[22:23], off offset:192
	v_lshl_add_u64 v[102:103], v[154:155], 0, v[102:103]
	global_store_short v[102:103], v98, off
	v_cvt_pk_bf16_f32 v98, v99, v99
	v_cvt_pk_bf16_f32 v100, v100, v100
	v_lshl_add_u64 v[104:105], v[102:103], 0, s[86:87]
	v_and_b32_e32 v98, 0xffff, v98
	global_store_short v[104:105], v98, off
	v_and_b32_e32 v100, 0xffff, v100
	v_lshl_add_u64 v[98:99], v[102:103], 0, s[74:75]
	global_store_short v[98:99], v100, off
	v_cvt_pk_bf16_f32 v100, v101, v101
	v_and_b32_e32 v100, 0xffff, v100
	v_lshl_add_u64 v[98:99], v[102:103], 0, s[66:67]
	global_store_short v[98:99], v100, off
	v_cvt_pk_bf16_f32 v100, v112, v112
	v_and_b32_e32 v100, 0xffff, v100
	v_lshl_add_u64 v[98:99], v[102:103], 0, 32
	global_store_short v[98:99], v100, off
	v_cvt_pk_bf16_f32 v100, v113, v113
	v_and_b32_e32 v100, 0xffff, v100
	v_lshl_add_u64 v[98:99], v[102:103], 0, s[22:23]
	global_store_short v[98:99], v100, off
	v_cvt_pk_bf16_f32 v100, v110, v110
	v_and_b32_e32 v100, 0xffff, v100
	v_lshl_add_u64 v[98:99], v[102:103], 0, s[12:13]
	global_store_short v[98:99], v100, off
	v_cvt_pk_bf16_f32 v100, v111, v111
	v_lshl_add_u64 v[98:99], v[102:103], 0, s[56:57]
	v_and_b32_e32 v100, 0xffff, v100
	global_store_short v[98:99], v100, off
	s_waitcnt lgkmcnt(0)
	s_barrier
	v_add_u32_e32 v189, v189, v190
	ds_read_b128 v[98:101], v189
	ds_read_b128 v[102:105], v189 offset:64
	ds_read_b128 v[206:209], v189 offset:128
	ds_read_b128 v[106:109], v150
	ds_read_b128 v[210:213], v189 offset:192
	ds_read_b128 v[114:117], v186 offset:10240
	ds_read_b128 v[214:217], v150 offset:64
	ds_read_b128 v[218:221], v186 offset:10304
	ds_read_b128 v[222:225], v189 offset:4608
	s_waitcnt vmcnt(23) lgkmcnt(8)
	v_mfma_f32_16x16x32_bf16 v[98:101], v[2:5], v[98:101], 0
	s_waitcnt vmcnt(22) lgkmcnt(7)
	v_mfma_f32_16x16x32_bf16 v[98:101], v[10:13], v[102:105], v[98:101]
	s_nop 0
	s_nop 0
	s_waitcnt vmcnt(21) lgkmcnt(6)
	v_mfma_f32_16x16x32_bf16 v[98:101], v[6:9], v[206:209], v[98:101]
	ds_read_b128 v[206:209], v189 offset:4672
	s_nop 0
	s_nop 0
	s_waitcnt vmcnt(20) lgkmcnt(5)
	v_mfma_f32_16x16x32_bf16 v[110:113], v[14:17], v[210:213], v[98:101]
	ds_read_b128 v[210:213], v189 offset:4736
	s_nop 3
	s_nop 0
	s_waitcnt lgkmcnt(5)
	v_mfma_f32_16x16x32_bf16 v[102:105], v[106:109], v[114:117], 0
	s_nop 0
	s_waitcnt lgkmcnt(3)
	v_mfma_f32_16x16x32_bf16 v[114:117], v[214:217], v[218:221], v[102:105]
	ds_read_b128 v[218:221], v189 offset:4800
	s_nop 4
	s_nop 0
	s_waitcnt lgkmcnt(3)
	v_mfma_f32_16x16x32_bf16 v[2:5], v[2:5], v[222:225], 0
	ds_read_b128 v[222:225], v186 offset:12800
	s_nop 0
	s_waitcnt lgkmcnt(3)
	v_mfma_f32_16x16x32_bf16 v[2:5], v[10:13], v[206:209], v[2:5]
	ds_read_b128 v[206:209], v186 offset:12864
	s_nop 0
	s_waitcnt lgkmcnt(3)
	v_mfma_f32_16x16x32_bf16 v[2:5], v[6:9], v[210:213], v[2:5]
	ds_read_b128 v[10:13], v180 offset:30720
	s_nop 0
	s_waitcnt lgkmcnt(3)
	v_mfma_f32_16x16x32_bf16 v[118:121], v[14:17], v[218:221], v[2:5]
	s_nop 4
	s_nop 0
	s_nop 0
	s_waitcnt lgkmcnt(2)
	v_mfma_f32_16x16x32_bf16 v[2:5], v[106:109], v[222:225], 0
	ds_read_b32 v106, v197 offset:51452
	ds_read_b128 v[14:17], v179 offset:20480
	ds_read_b128 v[102:105], v179 offset:28160
	ds_read_b128 v[210:213], v179 offset:23040
	ds_read_b128 v[218:221], v179 offset:25600
	ds_read_b128 v[222:225], v180 offset:30784
	s_nop 0
	s_nop 0
	s_nop 0
	s_nop 0
	s_waitcnt lgkmcnt(5)
	v_pk_mul_f32 v[108:109], v[148:149], v[106:107] op_sel_hi:[1,0]
	v_mfma_f32_16x16x32_bf16 v[122:125], v[214:217], v[206:209], v[2:5]
	ds_read_b128 v[206:209], v179 offset:20544
	ds_read_b128 v[214:217], v179 offset:23104
	s_nop 0
	s_nop 0
	s_nop 0
	v_pk_mul_f32 v[4:5], v[136:137], v[106:107] op_sel_hi:[1,0]
	v_pk_mul_f32 v[2:3], v[134:135], v[106:107] op_sel_hi:[1,0]
	s_waitcnt lgkmcnt(6)
	s_nop 0
	v_mfma_f32_16x16x32_bf16 v[2:5], v[10:13], v[14:17], v[2:5]
	v_mul_f32_e64 v16, v144, v106
	v_mul_f32_e64 v17, v145, v106
	v_pk_mul_f32 v[14:15], v[142:143], v[106:107] op_sel_hi:[1,0]
	s_waitcnt lgkmcnt(4)
	s_nop 0
	v_mfma_f32_16x16x32_bf16 v[6:9], v[10:13], v[210:213], v[14:17]
	ds_read_b128 v[210:213], v179 offset:25664
	s_nop 2
	v_mul_f32_e64 v16, v140, v106
	v_mul_f32_e64 v17, v141, v106
	v_pk_mul_f32 v[14:15], v[138:139], v[106:107] op_sel_hi:[1,0]
	v_pk_mul_f32 v[106:107], v[146:147], v[106:107] op_sel_hi:[1,0]
	s_waitcnt lgkmcnt(4)
	v_mfma_f32_16x16x32_bf16 v[14:17], v[10:13], v[218:221], v[14:17]
	ds_read_b128 v[218:221], v179 offset:28224
	ds_read_b128 v[130:133], v176 offset:51200
	s_nop 0
	v_mfma_f32_16x16x32_bf16 v[10:13], v[10:13], v[102:105], v[106:109]
	s_nop 0
	s_waitcnt lgkmcnt(4)
	v_mfma_f32_16x16x32_bf16 v[106:109], v[222:225], v[206:209], v[2:5]
	s_nop 2
	s_nop 0
	s_waitcnt lgkmcnt(3)
	v_mfma_f32_16x16x32_bf16 v[102:105], v[222:225], v[214:217], v[6:9]
	s_nop 0
	s_waitcnt lgkmcnt(2)
	v_mfma_f32_16x16x32_bf16 v[14:17], v[222:225], v[210:213], v[14:17]
	s_nop 0
	s_nop 0
	s_waitcnt lgkmcnt(1)
	v_mfma_f32_16x16x32_bf16 v[126:129], v[222:225], v[218:221], v[10:13]
	v_cvt_pk_bf16_f32 v2, v106, v107
	v_cvt_pk_bf16_f32 v3, v108, v109
	v_cvt_pk_bf16_f32 v4, v102, v103
	v_cvt_pk_bf16_f32 v5, v104, v105
	ds_write2st64_b64 v174, v[2:3], v[4:5] offset1:9
	v_cvt_pk_bf16_f32 v2, v14, v15
	v_cvt_pk_bf16_f32 v3, v16, v17
	s_nop 0
	v_cvt_pk_bf16_f32 v4, v126, v127
	v_cvt_pk_bf16_f32 v5, v128, v129
	ds_write2st64_b64 v174, v[2:3], v[4:5] offset0:18 offset1:27
	s_waitcnt vmcnt(19)
	ds_write_b128 v171, v[58:61] offset:51456
	s_waitcnt vmcnt(18)
	ds_write_b128 v171, v[62:65] offset:61696
	s_waitcnt vmcnt(17)
	ds_write_b128 v172, v[66:69]
	s_waitcnt vmcnt(16)
	ds_write_b128 v173, v[70:73]
	s_waitcnt vmcnt(15)
	ds_write_b128 v175, v[74:77]
	s_and_saveexec_b64 s[8:9], vcc
	s_cbranch_execz .LBB0_1553
	s_waitcnt vmcnt(14)
	ds_write_b128 v185, v[78:81]
.LBB0_1553:
	s_or_b64 exec, exec, s[8:9]
	s_or_b32 s7, s34, 5
	s_lshl_b32 s0, s7, 5
	s_or_b32 s8, s0, s78
	s_lshl_b32 s0, s8, 13
	s_mov_b32 s1, s61
	v_lshl_add_u64 v[2:3], v[168:169], 0, s[0:1]
	v_lshl_add_u64 v[4:5], v[166:167], 0, s[0:1]
	global_load_dwordx4 v[62:65], v[2:3], off
	global_load_dwordx4 v[66:69], v[4:5], off
	v_lshl_add_u64 v[2:3], v[164:165], 0, s[0:1]
	s_lshl_b32 s0, s7, 16
	s_or_b32 s0, s0, s5
	s_add_u32 s0, s77, s0
	s_addc_u32 s1, s28, 0
	v_lshl_add_u64 v[4:5], s[0:1], 0, v[156:157]
	global_load_dwordx4 v[70:73], v[2:3], off
	global_load_dwordx4 v[74:77], v[4:5], off
	v_lshl_add_u64 v[2:3], s[0:1], 0, v[158:159]
	s_lshl_b32 s0, s8, 8
	s_mov_b32 s1, s61
	v_lshl_add_u64 v[4:5], v[162:163], 0, s[0:1]
	s_or_b32 s50, s6, 0x140
	s_mov_b32 s51, s61
	global_load_dwordx4 v[98:101], v[2:3], off
	global_load_dwordx4 v[78:81], v[4:5], off
	v_lshl_add_u64 v[2:3], v[160:161], 0, s[50:51]
	v_mov_b64_e32 v[4:5], s[80:81]
	v_mad_u64_u32 v[4:5], s[0:1], v2, s19, v[4:5]
	v_mad_i32_i24 v5, v3, s19, v5
	v_lshl_add_u64 v[2:3], v[4:5], 0, s[60:61]
	v_lshl_add_u64 v[2:3], v[2:3], 0, v[196:197]
	s_waitcnt lgkmcnt(7)
	v_pk_fma_f32 v[110:111], v[130:131], v[110:111], v[114:115]
	s_or_b32 s0, s6, 0x80
	s_mov_b32 s1, s61
	v_add_co_u32_e64 v8, s[44:45], s14, v2
	v_lshl_add_u64 v[114:115], v[152:153], 0, s[0:1]
	v_cvt_pk_bf16_f32 v110, v110, v110
	v_lshl_add_u64 v[6:7], v[2:3], 0, s[20:21]
	v_addc_co_u32_e64 v9, s[44:45], 0, v3, s[44:45]
	v_pk_fma_f32 v[112:113], v[132:133], v[112:113], v[116:117]
	v_lshlrev_b64 v[114:115], 12, v[114:115]
	v_and_b32_e32 v110, 0xffff, v110
	global_load_dwordx4 v[10:13], v[6:7], off offset:64
	global_load_dwordx4 v[2:5], v[6:7], off offset:128
	global_load_dwordx4 v[58:61], v[8:9], off offset:1024
	s_nop 0
	global_load_dwordx4 v[6:9], v[6:7], off offset:192
	v_lshl_add_u64 v[114:115], v[154:155], 0, v[114:115]
	global_store_short v[114:115], v110, off
	v_cvt_pk_bf16_f32 v110, v111, v111
	v_cvt_pk_bf16_f32 v112, v112, v112
	v_lshl_add_u64 v[116:117], v[114:115], 0, s[86:87]
	v_and_b32_e32 v110, 0xffff, v110
	global_store_short v[116:117], v110, off
	v_and_b32_e32 v112, 0xffff, v112
	v_lshl_add_u64 v[110:111], v[114:115], 0, s[74:75]
	global_store_short v[110:111], v112, off
	v_cvt_pk_bf16_f32 v112, v113, v113
	v_pk_fma_f32 v[118:119], v[130:131], v[118:119], v[122:123]
	v_and_b32_e32 v112, 0xffff, v112
	v_lshl_add_u64 v[110:111], v[114:115], 0, s[66:67]
	global_store_short v[110:111], v112, off
	v_cvt_pk_bf16_f32 v112, v118, v118
	v_and_b32_e32 v112, 0xffff, v112
	v_lshl_add_u64 v[110:111], v[114:115], 0, 32
	global_store_short v[110:111], v112, off
	v_cvt_pk_bf16_f32 v112, v119, v119
	v_pk_fma_f32 v[120:121], v[132:133], v[120:121], v[124:125]
	v_and_b32_e32 v112, 0xffff, v112
	v_lshl_add_u64 v[110:111], v[114:115], 0, s[22:23]
	global_store_short v[110:111], v112, off
	v_cvt_pk_bf16_f32 v112, v120, v120
	v_and_b32_e32 v112, 0xffff, v112
	v_lshl_add_u64 v[110:111], v[114:115], 0, s[12:13]
	global_store_short v[110:111], v112, off
	v_cvt_pk_bf16_f32 v112, v121, v121
	v_lshl_add_u64 v[110:111], v[114:115], 0, s[56:57]
	v_and_b32_e32 v112, 0xffff, v112
	global_store_short v[110:111], v112, off
	s_waitcnt lgkmcnt(0)
	s_barrier
	ds_read_b128 v[110:113], v188
	ds_read_b128 v[114:117], v188 offset:64
	ds_read_b128 v[206:209], v188 offset:128
	ds_read_b128 v[122:125], v150 offset:51456
	ds_read_b128 v[210:213], v188 offset:192
	ds_read_b128 v[118:121], v186 offset:61696
	ds_read_b128 v[130:133], v150 offset:51520
	ds_read_b128 v[214:217], v186 offset:61760
	ds_read_b128 v[218:221], v188 offset:4608
	ds_read_b128 v[222:225], v188 offset:4672
	s_waitcnt vmcnt(23) lgkmcnt(9)
	v_mfma_f32_16x16x32_bf16 v[110:113], v[42:45], v[110:113], 0
	v_readlane_b32 s0, v253, 18
	s_waitcnt vmcnt(22) lgkmcnt(8)
	v_mfma_f32_16x16x32_bf16 v[110:113], v[50:53], v[114:117], v[110:113]
	s_nop 0
	s_nop 0
	s_waitcnt vmcnt(21) lgkmcnt(7)
	v_mfma_f32_16x16x32_bf16 v[110:113], v[46:49], v[206:209], v[110:113]
	ds_read_b128 v[206:209], v188 offset:4736
	s_nop 0
	s_nop 0
	s_nop 0
	s_waitcnt vmcnt(20) lgkmcnt(6)
	v_mfma_f32_16x16x32_bf16 v[110:113], v[54:57], v[210:213], v[110:113]
	ds_read_b128 v[210:213], v188 offset:4800
	s_waitcnt lgkmcnt(6)
	v_mfma_f32_16x16x32_bf16 v[114:117], v[122:125], v[118:121], 0
	s_nop 0
	s_waitcnt lgkmcnt(4)
	v_mfma_f32_16x16x32_bf16 v[114:117], v[130:133], v[214:217], v[114:117]
	ds_read_b128 v[214:217], v186 offset:64256
	s_nop 0
	s_waitcnt lgkmcnt(4)
	v_mfma_f32_16x16x32_bf16 v[42:45], v[42:45], v[218:221], 0
	ds_read_b128 v[218:221], v186 offset:64320
	s_nop 0
	s_waitcnt lgkmcnt(4)
	v_mfma_f32_16x16x32_bf16 v[42:45], v[50:53], v[222:225], v[42:45]
	ds_read_b128 v[222:225], v183
	s_nop 0
	s_waitcnt lgkmcnt(4)
	v_mfma_f32_16x16x32_bf16 v[42:45], v[46:49], v[206:209], v[42:45]
	s_nop 0
	s_waitcnt lgkmcnt(3)
	v_mfma_f32_16x16x32_bf16 v[118:121], v[54:57], v[210:213], v[42:45]
	s_nop 4
	s_nop 0
	s_nop 0
	v_mov_b32_e32 v54, s0
	ds_read_b32 v138, v54
	ds_read_b128 v[206:209], v184
	ds_read_b128 v[134:137], v183 offset:64
	ds_read_b128 v[210:213], v184 offset:2560
	s_nop 0
	s_nop 0
	s_nop 0
	s_waitcnt lgkmcnt(6)
	v_mfma_f32_16x16x32_bf16 v[42:45], v[122:125], v[214:217], 0
	ds_read_b128 v[214:217], v184 offset:5120
	s_nop 0
	s_waitcnt lgkmcnt(4)
	v_pk_mul_f32 v[16:17], v[16:17], v[138:139] op_sel_hi:[1,0]
	v_pk_mul_f32 v[14:15], v[14:15], v[138:139] op_sel_hi:[1,0]
	v_mfma_f32_16x16x32_bf16 v[122:125], v[130:133], v[218:221], v[42:45]
	ds_read_b128 v[218:221], v184 offset:7680
	s_nop 0
	s_nop 1
	v_pk_mul_f32 v[44:45], v[108:109], v[138:139] op_sel_hi:[1,0]
	v_pk_mul_f32 v[42:43], v[106:107], v[138:139] op_sel_hi:[1,0]
	s_waitcnt lgkmcnt(4)
	s_nop 0
	v_mfma_f32_16x16x32_bf16 v[42:45], v[222:225], v[206:209], v[42:45]
	v_mul_f32_e64 v56, v104, v138
	v_mul_f32_e64 v57, v105, v138
	v_pk_mul_f32 v[54:55], v[102:103], v[138:139] op_sel_hi:[1,0]
	ds_read_b128 v[206:209], v182
	s_nop 0
	s_waitcnt lgkmcnt(2)
	v_mfma_f32_16x16x32_bf16 v[14:17], v[222:225], v[214:217], v[14:17]
	v_mul_f32_e64 v104, v128, v138
	v_mul_f32_e64 v105, v129, v138
	v_pk_mul_f32 v[102:103], v[126:127], v[138:139] op_sel_hi:[1,0]
	ds_read_b128 v[214:217], v182 offset:2560
	v_mfma_f32_16x16x32_bf16 v[46:49], v[222:225], v[210:213], v[54:57]
	ds_read_b128 v[210:213], v182 offset:5120
	s_nop 2
	s_nop 0
	s_waitcnt lgkmcnt(3)
	v_mfma_f32_16x16x32_bf16 v[50:53], v[222:225], v[218:221], v[102:105]
	ds_read_b128 v[218:221], v182 offset:7680
	ds_read_b128 v[130:133], v181
	s_nop 0
	s_waitcnt lgkmcnt(4)
	v_mfma_f32_16x16x32_bf16 v[106:109], v[134:137], v[206:209], v[42:45]
	s_nop 2
	s_nop 0
	s_waitcnt lgkmcnt(3)
	v_mfma_f32_16x16x32_bf16 v[102:105], v[134:137], v[214:217], v[46:49]
	s_nop 0
	s_waitcnt lgkmcnt(2)
	v_mfma_f32_16x16x32_bf16 v[46:49], v[134:137], v[210:213], v[14:17]
	s_nop 2
	s_nop 0
	s_nop 0
	s_waitcnt lgkmcnt(1)
	v_mfma_f32_16x16x32_bf16 v[126:129], v[134:137], v[218:221], v[50:53]
	v_cvt_pk_bf16_f32 v14, v106, v107
	v_cvt_pk_bf16_f32 v15, v108, v109
	v_cvt_pk_bf16_f32 v16, v102, v103
	v_cvt_pk_bf16_f32 v17, v104, v105
	ds_write2st64_b64 v187, v[14:15], v[16:17] offset1:9
	v_cvt_pk_bf16_f32 v14, v46, v47
	v_cvt_pk_bf16_f32 v15, v48, v49
	s_nop 0
	v_cvt_pk_bf16_f32 v16, v126, v127
	v_cvt_pk_bf16_f32 v17, v128, v129
	ds_write2st64_b64 v187, v[14:15], v[16:17] offset0:18 offset1:27
	s_waitcnt vmcnt(19)
	ds_write_b128 v171, v[34:37]
	s_waitcnt vmcnt(18)
	ds_write_b128 v171, v[38:41] offset:10240
	s_waitcnt vmcnt(17)
	ds_write_b128 v171, v[82:85] offset:20480
	s_waitcnt vmcnt(16)
	ds_write_b128 v171, v[86:89] offset:30720
	s_waitcnt vmcnt(15)
	ds_write_b128 v178, v[94:97] offset:30720
	s_and_saveexec_b64 s[8:9], vcc
	s_cbranch_execz .LBB0_1555
	s_waitcnt vmcnt(14)
	ds_write_b128 v177, v[90:93] offset:51200
.LBB0_1555:
	s_or_b64 exec, exec, s[8:9]
	s_or_b32 s7, s34, 6
	s_lshl_b32 s0, s7, 5
	s_or_b32 s8, s0, s78
	s_lshl_b32 s0, s8, 13
	s_mov_b32 s1, s61
	v_lshl_add_u64 v[14:15], v[168:169], 0, s[0:1]
	v_lshl_add_u64 v[16:17], v[166:167], 0, s[0:1]
	global_load_dwordx4 v[50:53], v[14:15], off
	global_load_dwordx4 v[54:57], v[16:17], off
	v_lshl_add_u64 v[14:15], v[164:165], 0, s[0:1]
	s_lshl_b32 s0, s7, 16
	s_or_b32 s0, s0, s5
	s_add_u32 s0, s77, s0
	s_addc_u32 s1, s28, 0
	v_lshl_add_u64 v[16:17], s[0:1], 0, v[156:157]
	global_load_dwordx4 v[82:85], v[14:15], off
	global_load_dwordx4 v[86:89], v[16:17], off
	v_lshl_add_u64 v[14:15], s[0:1], 0, v[158:159]
	s_lshl_b32 s0, s8, 8
	s_mov_b32 s1, s61
	v_lshl_add_u64 v[16:17], v[162:163], 0, s[0:1]
	s_or_b32 s52, s6, 0x180
	s_mov_b32 s53, s61
	global_load_dwordx4 v[94:97], v[14:15], off
	global_load_dwordx4 v[90:93], v[16:17], off
	v_lshl_add_u64 v[14:15], v[160:161], 0, s[52:53]
	v_mov_b64_e32 v[16:17], s[80:81]
	v_mad_u64_u32 v[16:17], s[0:1], v14, s19, v[16:17]
	v_mad_i32_i24 v17, v15, s19, v17
	v_lshl_add_u64 v[14:15], v[16:17], 0, s[60:61]
	v_lshl_add_u64 v[14:15], v[14:15], 0, v[196:197]
	s_waitcnt lgkmcnt(7)
	v_pk_fma_f32 v[110:111], v[130:131], v[110:111], v[114:115]
	v_add_co_u32_e64 v36, s[44:45], s14, v14
	v_lshl_add_u64 v[114:115], v[152:153], 0, s[46:47]
	v_cvt_pk_bf16_f32 v110, v110, v110
	v_lshl_add_u64 v[34:35], v[14:15], 0, s[20:21]
	v_addc_co_u32_e64 v37, s[44:45], 0, v15, s[44:45]
	v_pk_fma_f32 v[112:113], v[132:133], v[112:113], v[116:117]
	v_lshlrev_b64 v[114:115], 12, v[114:115]
	v_and_b32_e32 v110, 0xffff, v110
	global_load_dwordx4 v[38:41], v[34:35], off offset:64
	global_load_dwordx4 v[14:17], v[34:35], off offset:128
	global_load_dwordx4 v[42:45], v[36:37], off offset:1024
	s_nop 0
	global_load_dwordx4 v[34:37], v[34:35], off offset:192
	v_lshl_add_u64 v[114:115], v[154:155], 0, v[114:115]
	global_store_short v[114:115], v110, off
	v_cvt_pk_bf16_f32 v110, v111, v111
	v_cvt_pk_bf16_f32 v112, v112, v112
	v_lshl_add_u64 v[116:117], v[114:115], 0, s[86:87]
	v_and_b32_e32 v110, 0xffff, v110
	global_store_short v[116:117], v110, off
	v_and_b32_e32 v112, 0xffff, v112
	v_lshl_add_u64 v[110:111], v[114:115], 0, s[74:75]
	global_store_short v[110:111], v112, off
	v_cvt_pk_bf16_f32 v112, v113, v113
	v_pk_fma_f32 v[118:119], v[130:131], v[118:119], v[122:123]
	v_and_b32_e32 v112, 0xffff, v112
	v_lshl_add_u64 v[110:111], v[114:115], 0, s[66:67]
	global_store_short v[110:111], v112, off
	v_cvt_pk_bf16_f32 v112, v118, v118
	v_and_b32_e32 v112, 0xffff, v112
	v_lshl_add_u64 v[110:111], v[114:115], 0, 32
	global_store_short v[110:111], v112, off
	v_cvt_pk_bf16_f32 v112, v119, v119
	v_pk_fma_f32 v[120:121], v[132:133], v[120:121], v[124:125]
	v_and_b32_e32 v112, 0xffff, v112
	v_lshl_add_u64 v[110:111], v[114:115], 0, s[22:23]
	global_store_short v[110:111], v112, off
	v_cvt_pk_bf16_f32 v112, v120, v120
	v_and_b32_e32 v112, 0xffff, v112
	v_lshl_add_u64 v[110:111], v[114:115], 0, s[12:13]
	global_store_short v[110:111], v112, off
	v_cvt_pk_bf16_f32 v112, v121, v121
	v_lshl_add_u64 v[110:111], v[114:115], 0, s[56:57]
	v_and_b32_e32 v112, 0xffff, v112
	global_store_short v[110:111], v112, off
	s_waitcnt lgkmcnt(0)
	s_barrier
	ds_read_b128 v[110:113], v189
	ds_read_b128 v[114:117], v189 offset:64
	ds_read_b128 v[206:209], v189 offset:128
	ds_read_b128 v[122:125], v150
	ds_read_b128 v[210:213], v189 offset:192
	ds_read_b128 v[118:121], v186 offset:10240
	ds_read_b128 v[130:133], v150 offset:64
	ds_read_b128 v[214:217], v186 offset:10304
	ds_read_b128 v[218:221], v189 offset:4608
	ds_read_b128 v[222:225], v189 offset:4672
	s_waitcnt vmcnt(21) lgkmcnt(9)
	v_mfma_f32_16x16x32_bf16 v[110:113], v[30:33], v[110:113], 0
	s_waitcnt lgkmcnt(8)
	v_mfma_f32_16x16x32_bf16 v[110:113], v[26:29], v[114:117], v[110:113]
	s_nop 0
	s_nop 0
	s_waitcnt lgkmcnt(7)
	v_mfma_f32_16x16x32_bf16 v[110:113], v[18:21], v[206:209], v[110:113]
	ds_read_b128 v[206:209], v189 offset:4736
	s_nop 0
	s_nop 0
	s_nop 0
	s_waitcnt vmcnt(20) lgkmcnt(6)
	v_mfma_f32_16x16x32_bf16 v[110:113], v[22:25], v[210:213], v[110:113]
	ds_read_b128 v[210:213], v189 offset:4800
	s_waitcnt lgkmcnt(6)
	v_mfma_f32_16x16x32_bf16 v[114:117], v[122:125], v[118:121], 0
	s_nop 0
	s_waitcnt lgkmcnt(4)
	v_mfma_f32_16x16x32_bf16 v[114:117], v[130:133], v[214:217], v[114:117]
	ds_read_b128 v[214:217], v186 offset:12800
	s_nop 0
	s_waitcnt lgkmcnt(4)
	v_mfma_f32_16x16x32_bf16 v[30:33], v[30:33], v[218:221], 0
	ds_read_b128 v[218:221], v186 offset:12864
	s_nop 0
	s_waitcnt lgkmcnt(4)
	v_mfma_f32_16x16x32_bf16 v[26:29], v[26:29], v[222:225], v[30:33]
	ds_read_b128 v[222:225], v180 offset:30720
	ds_read_b32 v138, v197 offset:51452
	s_nop 4
	s_nop 0
	s_waitcnt lgkmcnt(5)
	v_mfma_f32_16x16x32_bf16 v[18:21], v[18:21], v[206:209], v[26:29]
	ds_read_b128 v[30:33], v179 offset:20480
	ds_read_b128 v[134:137], v180 offset:30784
	ds_read_b128 v[206:209], v179 offset:23040
	s_nop 2
	s_nop 0
	s_waitcnt lgkmcnt(7)
	v_mfma_f32_16x16x32_bf16 v[118:121], v[22:25], v[210:213], v[18:21]
	ds_read_b128 v[210:213], v179 offset:25600
	s_nop 2
	s_nop 0
	s_nop 0
	s_nop 0
	s_nop 0
	s_nop 0
	s_nop 0
	s_waitcnt lgkmcnt(7)
	v_mfma_f32_16x16x32_bf16 v[18:21], v[122:125], v[214:217], 0
	ds_read_b128 v[214:217], v179 offset:28160
	s_waitcnt lgkmcnt(7)
	v_mfma_f32_16x16x32_bf16 v[122:125], v[130:133], v[218:221], v[18:21]
	ds_read_b128 v[218:221], v179 offset:20544
	s_nop 0
	s_waitcnt lgkmcnt(6)
	s_nop 3
	v_pk_mul_f32 v[20:21], v[108:109], v[138:139] op_sel_hi:[1,0]
	v_pk_mul_f32 v[18:19], v[106:107], v[138:139] op_sel_hi:[1,0]
	s_waitcnt lgkmcnt(5)
	s_nop 0
	v_mfma_f32_16x16x32_bf16 v[18:21], v[222:225], v[30:33], v[18:21]
	v_mul_f32_e64 v32, v104, v138
	v_mul_f32_e64 v33, v105, v138
	v_pk_mul_f32 v[30:31], v[102:103], v[138:139] op_sel_hi:[1,0]
	s_nop 0
	s_waitcnt lgkmcnt(3)
	v_mfma_f32_16x16x32_bf16 v[22:25], v[222:225], v[206:209], v[30:33]
	ds_read_b128 v[206:209], v179 offset:23104
	s_nop 2
	v_mul_f32_e64 v32, v48, v138
	v_mul_f32_e64 v33, v49, v138
	v_pk_mul_f32 v[30:31], v[46:47], v[138:139] op_sel_hi:[1,0]
	s_nop 0
	s_waitcnt lgkmcnt(3)
	v_mfma_f32_16x16x32_bf16 v[30:33], v[222:225], v[210:213], v[30:33]
	v_mul_f32_e64 v104, v128, v138
	v_mul_f32_e64 v105, v129, v138
	v_pk_mul_f32 v[102:103], v[126:127], v[138:139] op_sel_hi:[1,0]
	ds_read_b128 v[210:213], v179 offset:25664
	s_waitcnt lgkmcnt(3)
	s_nop 0
	v_mfma_f32_16x16x32_bf16 v[26:29], v[222:225], v[214:217], v[102:105]
	ds_read_b128 v[214:217], v179 offset:28224
	ds_read_b128 v[130:133], v176 offset:51200
	s_nop 0
	s_waitcnt lgkmcnt(4)
	v_mfma_f32_16x16x32_bf16 v[106:109], v[134:137], v[218:221], v[18:21]
	s_nop 2
	s_nop 0
	s_waitcnt lgkmcnt(3)
	v_mfma_f32_16x16x32_bf16 v[102:105], v[134:137], v[206:209], v[22:25]
	s_nop 0
	s_waitcnt lgkmcnt(2)
	v_mfma_f32_16x16x32_bf16 v[30:33], v[134:137], v[210:213], v[30:33]
	s_nop 0
	s_nop 0
	s_waitcnt lgkmcnt(1)
	v_mfma_f32_16x16x32_bf16 v[126:129], v[134:137], v[214:217], v[26:29]
	v_cvt_pk_bf16_f32 v18, v106, v107
	v_cvt_pk_bf16_f32 v19, v108, v109
	v_cvt_pk_bf16_f32 v20, v102, v103
	v_cvt_pk_bf16_f32 v21, v104, v105
	ds_write2st64_b64 v174, v[18:19], v[20:21] offset1:9
	v_cvt_pk_bf16_f32 v18, v30, v31
	v_cvt_pk_bf16_f32 v19, v32, v33
	s_nop 0
	v_cvt_pk_bf16_f32 v20, v126, v127
	v_cvt_pk_bf16_f32 v21, v128, v129
	ds_write2st64_b64 v174, v[18:19], v[20:21] offset0:18 offset1:27
	s_waitcnt vmcnt(19)
	ds_write_b128 v171, v[62:65] offset:51456
	s_waitcnt vmcnt(18)
	ds_write_b128 v171, v[66:69] offset:61696
	s_waitcnt vmcnt(17)
	ds_write_b128 v172, v[70:73]
	s_waitcnt vmcnt(16)
	ds_write_b128 v173, v[74:77]
	s_waitcnt vmcnt(15)
	ds_write_b128 v175, v[98:101]
	s_and_saveexec_b64 s[8:9], vcc
	s_cbranch_execz .LBB0_1557
	s_waitcnt vmcnt(14)
	ds_write_b128 v185, v[78:81]
.LBB0_1557:
	s_or_b64 exec, exec, s[8:9]
	s_or_b32 s7, s34, 7
	s_lshl_b32 s0, s7, 5
	s_or_b32 s8, s0, s78
	s_lshl_b32 s0, s8, 13
	s_mov_b32 s1, s61
	v_lshl_add_u64 v[18:19], v[168:169], 0, s[0:1]
	v_lshl_add_u64 v[20:21], v[166:167], 0, s[0:1]
	global_load_dwordx4 v[62:65], v[18:19], off
	global_load_dwordx4 v[66:69], v[20:21], off
	v_lshl_add_u64 v[18:19], v[164:165], 0, s[0:1]
	s_lshl_b32 s0, s7, 16
	s_or_b32 s0, s0, s5
	s_add_u32 s0, s77, s0
	s_addc_u32 s1, s28, 0
	v_lshl_add_u64 v[20:21], s[0:1], 0, v[156:157]
	global_load_dwordx4 v[70:73], v[18:19], off
	global_load_dwordx4 v[74:77], v[20:21], off
	v_lshl_add_u64 v[18:19], s[0:1], 0, v[158:159]
	s_lshl_b32 s0, s8, 8
	s_mov_b32 s1, s61
	v_lshl_add_u64 v[20:21], v[162:163], 0, s[0:1]
	s_or_b32 s96, s6, 0x1c0
	s_mov_b32 s97, s61
	global_load_dwordx4 v[98:101], v[18:19], off
	global_load_dwordx4 v[78:81], v[20:21], off
	v_lshl_add_u64 v[18:19], v[160:161], 0, s[96:97]
	v_mov_b64_e32 v[20:21], s[80:81]
	v_mad_u64_u32 v[20:21], s[0:1], v18, s19, v[20:21]
	v_mad_i32_i24 v21, v19, s19, v21
	v_lshl_add_u64 v[18:19], v[20:21], 0, s[60:61]
	v_lshl_add_u64 v[18:19], v[18:19], 0, v[196:197]
	s_waitcnt lgkmcnt(7)
	v_pk_fma_f32 v[110:111], v[130:131], v[110:111], v[114:115]
	v_add_co_u32_e64 v24, s[44:45], s14, v18
	v_lshl_add_u64 v[114:115], v[152:153], 0, s[48:49]
	v_cvt_pk_bf16_f32 v110, v110, v110
	v_lshl_add_u64 v[22:23], v[18:19], 0, s[20:21]
	v_addc_co_u32_e64 v25, s[44:45], 0, v19, s[44:45]
	v_pk_fma_f32 v[112:113], v[132:133], v[112:113], v[116:117]
	v_lshlrev_b64 v[114:115], 12, v[114:115]
	v_and_b32_e32 v110, 0xffff, v110
	global_load_dwordx4 v[26:29], v[22:23], off offset:64
	global_load_dwordx4 v[18:21], v[22:23], off offset:128
	global_load_dwordx4 v[46:49], v[24:25], off offset:1024
	s_nop 0
	global_load_dwordx4 v[22:25], v[22:23], off offset:192
	v_lshl_add_u64 v[114:115], v[154:155], 0, v[114:115]
	global_store_short v[114:115], v110, off
	v_cvt_pk_bf16_f32 v110, v111, v111
	v_cvt_pk_bf16_f32 v112, v112, v112
	v_lshl_add_u64 v[116:117], v[114:115], 0, s[86:87]
	v_and_b32_e32 v110, 0xffff, v110
	global_store_short v[116:117], v110, off
	v_and_b32_e32 v112, 0xffff, v112
	v_lshl_add_u64 v[110:111], v[114:115], 0, s[74:75]
	global_store_short v[110:111], v112, off
	v_cvt_pk_bf16_f32 v112, v113, v113
	v_pk_fma_f32 v[118:119], v[130:131], v[118:119], v[122:123]
	v_and_b32_e32 v112, 0xffff, v112
	v_lshl_add_u64 v[110:111], v[114:115], 0, s[66:67]
	global_store_short v[110:111], v112, off
	v_cvt_pk_bf16_f32 v112, v118, v118
	v_and_b32_e32 v112, 0xffff, v112
	v_lshl_add_u64 v[110:111], v[114:115], 0, 32
	global_store_short v[110:111], v112, off
	v_cvt_pk_bf16_f32 v112, v119, v119
	v_pk_fma_f32 v[120:121], v[132:133], v[120:121], v[124:125]
	v_and_b32_e32 v112, 0xffff, v112
	v_lshl_add_u64 v[110:111], v[114:115], 0, s[22:23]
	global_store_short v[110:111], v112, off
	v_cvt_pk_bf16_f32 v112, v120, v120
	v_and_b32_e32 v112, 0xffff, v112
	v_lshl_add_u64 v[110:111], v[114:115], 0, s[12:13]
	global_store_short v[110:111], v112, off
	v_cvt_pk_bf16_f32 v112, v121, v121
	v_lshl_add_u64 v[110:111], v[114:115], 0, s[56:57]
	v_and_b32_e32 v112, 0xffff, v112
	global_store_short v[110:111], v112, off
	s_waitcnt lgkmcnt(0)
	s_barrier
	ds_read_b128 v[110:113], v188
	ds_read_b128 v[114:117], v188 offset:64
	ds_read_b128 v[206:209], v188 offset:128
	ds_read_b128 v[122:125], v150 offset:51456
	ds_read_b128 v[210:213], v188 offset:192
	ds_read_b128 v[118:121], v186 offset:61696
	ds_read_b128 v[130:133], v150 offset:51520
	ds_read_b128 v[214:217], v186 offset:61760
	ds_read_b128 v[218:221], v188 offset:4608
	ds_read_b128 v[222:225], v188 offset:4672
	s_waitcnt vmcnt(21) lgkmcnt(9)
	v_mfma_f32_16x16x32_bf16 v[110:113], v[58:61], v[110:113], 0
	v_readlane_b32 s0, v253, 18
	s_waitcnt lgkmcnt(8)
	v_mfma_f32_16x16x32_bf16 v[110:113], v[10:13], v[114:117], v[110:113]
	s_nop 0
	s_nop 0
	s_waitcnt lgkmcnt(7)
	v_mfma_f32_16x16x32_bf16 v[110:113], v[2:5], v[206:209], v[110:113]
	ds_read_b128 v[206:209], v188 offset:4736
	s_nop 0
	s_nop 0
	s_nop 0
	s_waitcnt vmcnt(20) lgkmcnt(6)
	v_mfma_f32_16x16x32_bf16 v[110:113], v[6:9], v[210:213], v[110:113]
	ds_read_b128 v[210:213], v188 offset:4800
	s_waitcnt lgkmcnt(6)
	v_mfma_f32_16x16x32_bf16 v[114:117], v[122:125], v[118:121], 0
	s_nop 0
	s_waitcnt lgkmcnt(4)
	v_mfma_f32_16x16x32_bf16 v[114:117], v[130:133], v[214:217], v[114:117]
	ds_read_b128 v[214:217], v186 offset:64256
	s_nop 0
	s_waitcnt lgkmcnt(4)
	v_mfma_f32_16x16x32_bf16 v[58:61], v[58:61], v[218:221], 0
	ds_read_b128 v[218:221], v186 offset:64320
	s_nop 0
	s_waitcnt lgkmcnt(4)
	v_mfma_f32_16x16x32_bf16 v[10:13], v[10:13], v[222:225], v[58:61]
	ds_read_b128 v[222:225], v183
	s_nop 4
	s_nop 0
	s_waitcnt lgkmcnt(4)
	v_mfma_f32_16x16x32_bf16 v[2:5], v[2:5], v[206:209], v[10:13]
	s_nop 2
	s_nop 0
	v_mov_b32_e32 v58, s0
	ds_read_b32 v138, v58
	ds_read_b128 v[206:209], v184
	ds_read_b128 v[134:137], v183 offset:64
	s_waitcnt lgkmcnt(6)
	v_mfma_f32_16x16x32_bf16 v[118:121], v[6:9], v[210:213], v[2:5]
	ds_read_b128 v[210:213], v184 offset:2560
	s_nop 2
	s_nop 0
	s_nop 0
	s_nop 0
	s_nop 0
	s_nop 0
	s_nop 0
	s_waitcnt lgkmcnt(6)
	v_mfma_f32_16x16x32_bf16 v[2:5], v[122:125], v[214:217], 0
	ds_read_b128 v[214:217], v184 offset:5120
	s_waitcnt lgkmcnt(4)
	v_pk_mul_f32 v[32:33], v[32:33], v[138:139] op_sel_hi:[1,0]
	v_pk_mul_f32 v[30:31], v[30:31], v[138:139] op_sel_hi:[1,0]
	v_mfma_f32_16x16x32_bf16 v[122:125], v[130:133], v[218:221], v[2:5]
	ds_read_b128 v[218:221], v184 offset:7680
	s_nop 0
	s_nop 2
	v_pk_mul_f32 v[4:5], v[108:109], v[138:139] op_sel_hi:[1,0]
	v_pk_mul_f32 v[2:3], v[106:107], v[138:139] op_sel_hi:[1,0]
	s_waitcnt lgkmcnt(4)
	s_nop 0
	v_mfma_f32_16x16x32_bf16 v[2:5], v[222:225], v[206:209], v[2:5]
	v_mul_f32_e64 v60, v104, v138
	v_mul_f32_e64 v61, v105, v138
	v_pk_mul_f32 v[58:59], v[102:103], v[138:139] op_sel_hi:[1,0]
	ds_read_b128 v[206:209], v182
	s_nop 0
	s_waitcnt lgkmcnt(2)
	v_mfma_f32_16x16x32_bf16 v[30:33], v[222:225], v[214:217], v[30:33]
	v_mul_f32_e64 v104, v128, v138
	v_mul_f32_e64 v105, v129, v138
	v_pk_mul_f32 v[102:103], v[126:127], v[138:139] op_sel_hi:[1,0]
	ds_read_b128 v[214:217], v182 offset:2560
	v_mfma_f32_16x16x32_bf16 v[6:9], v[222:225], v[210:213], v[58:61]
	ds_read_b128 v[210:213], v182 offset:5120
	s_nop 2
	s_nop 0
	s_waitcnt lgkmcnt(3)
	v_mfma_f32_16x16x32_bf16 v[58:61], v[222:225], v[218:221], v[102:105]
	ds_read_b128 v[218:221], v182 offset:7680
	ds_read_b128 v[130:133], v181
	s_nop 0
	s_waitcnt lgkmcnt(4)
	v_mfma_f32_16x16x32_bf16 v[106:109], v[134:137], v[206:209], v[2:5]
	s_nop 2
	s_nop 0
	s_waitcnt lgkmcnt(3)
	v_mfma_f32_16x16x32_bf16 v[102:105], v[134:137], v[214:217], v[6:9]
	s_nop 0
	s_waitcnt lgkmcnt(2)
	v_mfma_f32_16x16x32_bf16 v[10:13], v[134:137], v[210:213], v[30:33]
	s_nop 0
	s_nop 0
	s_waitcnt lgkmcnt(1)
	v_mfma_f32_16x16x32_bf16 v[126:129], v[134:137], v[218:221], v[58:61]
	v_cvt_pk_bf16_f32 v2, v106, v107
	v_cvt_pk_bf16_f32 v3, v108, v109
	v_cvt_pk_bf16_f32 v4, v102, v103
	v_cvt_pk_bf16_f32 v5, v104, v105
	ds_write2st64_b64 v187, v[2:3], v[4:5] offset1:9
	v_cvt_pk_bf16_f32 v2, v10, v11
	v_cvt_pk_bf16_f32 v3, v12, v13
	s_nop 0
	v_cvt_pk_bf16_f32 v4, v126, v127
	v_cvt_pk_bf16_f32 v5, v128, v129
	ds_write2st64_b64 v187, v[2:3], v[4:5] offset0:18 offset1:27
	s_waitcnt vmcnt(19)
	ds_write_b128 v171, v[50:53]
	s_waitcnt vmcnt(18)
	ds_write_b128 v171, v[54:57] offset:10240
	s_waitcnt vmcnt(17)
	ds_write_b128 v171, v[82:85] offset:20480
	s_waitcnt vmcnt(16)
	ds_write_b128 v171, v[86:89] offset:30720
	s_waitcnt vmcnt(15)
	ds_write_b128 v178, v[94:97] offset:30720
	s_and_saveexec_b64 s[8:9], vcc
	s_cbranch_execz .LBB0_1559
	s_waitcnt vmcnt(14)
	ds_write_b128 v177, v[90:93] offset:51200
.LBB0_1559:
	s_or_b64 exec, exec, s[8:9]
	s_or_b32 s7, s34, 8
	s_lshl_b32 s0, s7, 5
	s_or_b32 s8, s0, s78
	s_lshl_b32 s0, s8, 13
	s_mov_b32 s1, s61
	v_lshl_add_u64 v[2:3], v[168:169], 0, s[0:1]
	v_lshl_add_u64 v[4:5], v[166:167], 0, s[0:1]
	global_load_dwordx4 v[54:57], v[2:3], off
	global_load_dwordx4 v[58:61], v[4:5], off
	v_lshl_add_u64 v[2:3], v[164:165], 0, s[0:1]
	s_lshl_b32 s0, s7, 16
	s_or_b32 s0, s0, s5
	s_add_u32 s0, s77, s0
	s_addc_u32 s1, s28, 0
	v_lshl_add_u64 v[4:5], s[0:1], 0, v[156:157]
	global_load_dwordx4 v[82:85], v[2:3], off
	global_load_dwordx4 v[86:89], v[4:5], off
	v_lshl_add_u64 v[2:3], s[0:1], 0, v[158:159]
	s_lshl_b32 s0, s8, 8
	s_mov_b32 s1, s61
	v_lshl_add_u64 v[4:5], v[162:163], 0, s[0:1]
	s_or_b32 s46, s6, 0x200
	s_mov_b32 s47, s61
	global_load_dwordx4 v[94:97], v[2:3], off
	global_load_dwordx4 v[90:93], v[4:5], off
	v_lshl_add_u64 v[2:3], v[160:161], 0, s[46:47]
	v_mov_b64_e32 v[4:5], s[80:81]
	v_mad_u64_u32 v[4:5], s[0:1], v2, s19, v[4:5]
	v_mad_i32_i24 v5, v3, s19, v5
	v_lshl_add_u64 v[2:3], v[4:5], 0, s[60:61]
	v_lshl_add_u64 v[2:3], v[2:3], 0, v[196:197]
	s_waitcnt lgkmcnt(7)
	v_pk_fma_f32 v[110:111], v[130:131], v[110:111], v[114:115]
	v_add_co_u32_e64 v8, s[44:45], s14, v2
	v_lshl_add_u64 v[114:115], v[152:153], 0, s[50:51]
	v_cvt_pk_bf16_f32 v110, v110, v110
	v_lshl_add_u64 v[6:7], v[2:3], 0, s[20:21]
	v_addc_co_u32_e64 v9, s[44:45], 0, v3, s[44:45]
	v_pk_fma_f32 v[112:113], v[132:133], v[112:113], v[116:117]
	v_lshlrev_b64 v[114:115], 12, v[114:115]
	v_and_b32_e32 v110, 0xffff, v110
	global_load_dwordx4 v[30:33], v[6:7], off offset:64
	global_load_dwordx4 v[2:5], v[6:7], off offset:128
	global_load_dwordx4 v[50:53], v[8:9], off offset:1024
	s_nop 0
	global_load_dwordx4 v[6:9], v[6:7], off offset:192
	v_lshl_add_u64 v[114:115], v[154:155], 0, v[114:115]
	global_store_short v[114:115], v110, off
	v_cvt_pk_bf16_f32 v110, v111, v111
	v_cvt_pk_bf16_f32 v112, v112, v112
	v_lshl_add_u64 v[116:117], v[114:115], 0, s[86:87]
	v_and_b32_e32 v110, 0xffff, v110
	global_store_short v[116:117], v110, off
	v_and_b32_e32 v112, 0xffff, v112
	v_lshl_add_u64 v[110:111], v[114:115], 0, s[74:75]
	global_store_short v[110:111], v112, off
	v_cvt_pk_bf16_f32 v112, v113, v113
	v_pk_fma_f32 v[118:119], v[130:131], v[118:119], v[122:123]
	v_and_b32_e32 v112, 0xffff, v112
	v_lshl_add_u64 v[110:111], v[114:115], 0, s[66:67]
	global_store_short v[110:111], v112, off
	v_cvt_pk_bf16_f32 v112, v118, v118
	v_and_b32_e32 v112, 0xffff, v112
	v_lshl_add_u64 v[110:111], v[114:115], 0, 32
	global_store_short v[110:111], v112, off
	v_cvt_pk_bf16_f32 v112, v119, v119
	v_pk_fma_f32 v[120:121], v[132:133], v[120:121], v[124:125]
	v_and_b32_e32 v112, 0xffff, v112
	v_lshl_add_u64 v[110:111], v[114:115], 0, s[22:23]
	global_store_short v[110:111], v112, off
	v_cvt_pk_bf16_f32 v112, v120, v120
	v_and_b32_e32 v112, 0xffff, v112
	v_lshl_add_u64 v[110:111], v[114:115], 0, s[12:13]
	global_store_short v[110:111], v112, off
	v_cvt_pk_bf16_f32 v112, v121, v121
	v_lshl_add_u64 v[110:111], v[114:115], 0, s[56:57]
	v_and_b32_e32 v112, 0xffff, v112
	global_store_short v[110:111], v112, off
	s_waitcnt lgkmcnt(0)
	s_barrier
	ds_read_b128 v[110:113], v189
	ds_read_b128 v[114:117], v189 offset:64
	ds_read_b128 v[206:209], v189 offset:128
	ds_read_b128 v[122:125], v150
	ds_read_b128 v[210:213], v189 offset:192
	ds_read_b128 v[118:121], v186 offset:10240
	ds_read_b128 v[130:133], v150 offset:64
	ds_read_b128 v[214:217], v186 offset:10304
	ds_read_b128 v[218:221], v189 offset:4608
	ds_read_b128 v[222:225], v189 offset:4672
	s_waitcnt vmcnt(21) lgkmcnt(9)
	v_mfma_f32_16x16x32_bf16 v[110:113], v[42:45], v[110:113], 0
	s_waitcnt lgkmcnt(8)
	v_mfma_f32_16x16x32_bf16 v[110:113], v[38:41], v[114:117], v[110:113]
	s_nop 0
	s_nop 0
	s_waitcnt lgkmcnt(7)
	v_mfma_f32_16x16x32_bf16 v[110:113], v[14:17], v[206:209], v[110:113]
	ds_read_b128 v[206:209], v189 offset:4736
	s_nop 0
	s_nop 0
	s_nop 0
	s_waitcnt vmcnt(20) lgkmcnt(6)
	v_mfma_f32_16x16x32_bf16 v[110:113], v[34:37], v[210:213], v[110:113]
	ds_read_b128 v[210:213], v189 offset:4800
	s_waitcnt lgkmcnt(6)
	v_mfma_f32_16x16x32_bf16 v[114:117], v[122:125], v[118:121], 0
	s_nop 0
	s_waitcnt lgkmcnt(4)
	v_mfma_f32_16x16x32_bf16 v[114:117], v[130:133], v[214:217], v[114:117]
	ds_read_b128 v[214:217], v186 offset:12800
	s_nop 0
	s_waitcnt lgkmcnt(4)
	v_mfma_f32_16x16x32_bf16 v[42:45], v[42:45], v[218:221], 0
	ds_read_b128 v[218:221], v186 offset:12864
	s_nop 0
	s_waitcnt lgkmcnt(4)
	v_mfma_f32_16x16x32_bf16 v[38:41], v[38:41], v[222:225], v[42:45]
	ds_read_b128 v[222:225], v180 offset:30720
	ds_read_b32 v138, v197 offset:51452
	s_nop 4
	s_nop 0
	s_waitcnt lgkmcnt(5)
	v_mfma_f32_16x16x32_bf16 v[14:17], v[14:17], v[206:209], v[38:41]
	ds_read_b128 v[42:45], v179 offset:20480
	ds_read_b128 v[134:137], v180 offset:30784
	ds_read_b128 v[206:209], v179 offset:23040
	s_nop 2
	s_nop 0
	s_waitcnt lgkmcnt(7)
	v_mfma_f32_16x16x32_bf16 v[118:121], v[34:37], v[210:213], v[14:17]
	ds_read_b128 v[210:213], v179 offset:25600
	s_nop 2
	s_nop 0
	s_nop 0
	s_nop 0
	s_nop 0
	s_nop 0
	s_nop 0
	s_waitcnt lgkmcnt(7)
	v_mfma_f32_16x16x32_bf16 v[14:17], v[122:125], v[214:217], 0
	ds_read_b128 v[214:217], v179 offset:28160
	s_waitcnt lgkmcnt(5)
	v_pk_mul_f32 v[12:13], v[12:13], v[138:139] op_sel_hi:[1,0]
	v_pk_mul_f32 v[10:11], v[10:11], v[138:139] op_sel_hi:[1,0]
	v_mfma_f32_16x16x32_bf16 v[122:125], v[130:133], v[218:221], v[14:17]
	ds_read_b128 v[218:221], v179 offset:20544
	s_nop 0
	s_nop 2
	v_pk_mul_f32 v[16:17], v[108:109], v[138:139] op_sel_hi:[1,0]
	v_pk_mul_f32 v[14:15], v[106:107], v[138:139] op_sel_hi:[1,0]
	s_waitcnt lgkmcnt(5)
	s_nop 0
	v_mfma_f32_16x16x32_bf16 v[14:17], v[222:225], v[42:45], v[14:17]
	v_mul_f32_e64 v44, v104, v138
	v_mul_f32_e64 v45, v105, v138
	v_pk_mul_f32 v[42:43], v[102:103], v[138:139] op_sel_hi:[1,0]
	s_nop 0
	s_waitcnt lgkmcnt(2)
	v_mfma_f32_16x16x32_bf16 v[10:13], v[222:225], v[210:213], v[10:13]
	v_mul_f32_e64 v104, v128, v138
	v_mul_f32_e64 v105, v129, v138
	v_pk_mul_f32 v[102:103], v[126:127], v[138:139] op_sel_hi:[1,0]
	ds_read_b128 v[210:213], v179 offset:23104
	v_mfma_f32_16x16x32_bf16 v[34:37], v[222:225], v[206:209], v[42:45]
	ds_read_b128 v[206:209], v179 offset:25664
	s_nop 2
	s_nop 0
	s_waitcnt lgkmcnt(3)
	v_mfma_f32_16x16x32_bf16 v[38:41], v[222:225], v[214:217], v[102:105]
	ds_read_b128 v[214:217], v179 offset:28224
	ds_read_b128 v[130:133], v176 offset:51200
	s_nop 0
	s_waitcnt lgkmcnt(4)
	v_mfma_f32_16x16x32_bf16 v[106:109], v[134:137], v[218:221], v[14:17]
	s_nop 2
	s_nop 0
	s_waitcnt lgkmcnt(3)
	v_mfma_f32_16x16x32_bf16 v[102:105], v[134:137], v[210:213], v[34:37]
	s_nop 0
	s_waitcnt lgkmcnt(2)
	v_mfma_f32_16x16x32_bf16 v[42:45], v[134:137], v[206:209], v[10:13]
	s_nop 2
	s_nop 0
	s_nop 0
	s_waitcnt lgkmcnt(1)
	v_mfma_f32_16x16x32_bf16 v[126:129], v[134:137], v[214:217], v[38:41]
	v_cvt_pk_bf16_f32 v10, v106, v107
	v_cvt_pk_bf16_f32 v11, v108, v109
	v_cvt_pk_bf16_f32 v12, v102, v103
	v_cvt_pk_bf16_f32 v13, v104, v105
	ds_write2st64_b64 v174, v[10:11], v[12:13] offset1:9
	v_cvt_pk_bf16_f32 v10, v42, v43
	v_cvt_pk_bf16_f32 v11, v44, v45
	s_nop 0
	v_cvt_pk_bf16_f32 v12, v126, v127
	v_cvt_pk_bf16_f32 v13, v128, v129
	ds_write2st64_b64 v174, v[10:11], v[12:13] offset0:18 offset1:27
	s_waitcnt vmcnt(19)
	ds_write_b128 v171, v[62:65] offset:51456
	s_waitcnt vmcnt(18)
	ds_write_b128 v171, v[66:69] offset:61696
	s_waitcnt vmcnt(17)
	ds_write_b128 v172, v[70:73]
	s_waitcnt vmcnt(16)
	ds_write_b128 v173, v[74:77]
	s_waitcnt vmcnt(15)
	ds_write_b128 v175, v[98:101]
	s_and_saveexec_b64 s[8:9], vcc
	s_cbranch_execz .LBB0_1561
	s_waitcnt vmcnt(14)
	ds_write_b128 v185, v[78:81]
.LBB0_1561:
	s_or_b64 exec, exec, s[8:9]
	s_or_b32 s7, s34, 9
	s_lshl_b32 s0, s7, 5
	s_or_b32 s8, s0, s78
	s_lshl_b32 s0, s8, 13
	s_mov_b32 s1, s61
	v_lshl_add_u64 v[10:11], v[168:169], 0, s[0:1]
	v_lshl_add_u64 v[12:13], v[166:167], 0, s[0:1]
	global_load_dwordx4 v[62:65], v[10:11], off
	global_load_dwordx4 v[66:69], v[12:13], off
	v_lshl_add_u64 v[10:11], v[164:165], 0, s[0:1]
	s_lshl_b32 s0, s7, 16
	s_or_b32 s0, s0, s5
	s_add_u32 s0, s77, s0
	s_addc_u32 s1, s28, 0
	v_lshl_add_u64 v[12:13], s[0:1], 0, v[156:157]
	global_load_dwordx4 v[70:73], v[10:11], off
	global_load_dwordx4 v[74:77], v[12:13], off
	v_lshl_add_u64 v[10:11], s[0:1], 0, v[158:159]
	s_lshl_b32 s0, s8, 8
	s_mov_b32 s1, s61
	v_lshl_add_u64 v[12:13], v[162:163], 0, s[0:1]
	s_or_b32 s50, s6, 0x240
	s_mov_b32 s51, s61
	global_load_dwordx4 v[98:101], v[10:11], off
	global_load_dwordx4 v[78:81], v[12:13], off
	v_lshl_add_u64 v[10:11], v[160:161], 0, s[50:51]
	v_mov_b64_e32 v[12:13], s[80:81]
	v_mad_u64_u32 v[12:13], s[0:1], v10, s19, v[12:13]
	v_mad_i32_i24 v13, v11, s19, v13
	v_lshl_add_u64 v[10:11], v[12:13], 0, s[60:61]
	v_lshl_add_u64 v[10:11], v[10:11], 0, v[196:197]
	s_waitcnt lgkmcnt(7)
	v_pk_fma_f32 v[110:111], v[130:131], v[110:111], v[114:115]
	v_add_co_u32_e64 v16, s[44:45], s14, v10
	v_lshl_add_u64 v[114:115], v[152:153], 0, s[52:53]
	v_cvt_pk_bf16_f32 v110, v110, v110
	v_lshl_add_u64 v[14:15], v[10:11], 0, s[20:21]
	v_addc_co_u32_e64 v17, s[44:45], 0, v11, s[44:45]
	v_pk_fma_f32 v[112:113], v[132:133], v[112:113], v[116:117]
	v_lshlrev_b64 v[114:115], 12, v[114:115]
	v_and_b32_e32 v110, 0xffff, v110
	global_load_dwordx4 v[34:37], v[14:15], off offset:64
	global_load_dwordx4 v[10:13], v[14:15], off offset:128
	global_load_dwordx4 v[38:41], v[16:17], off offset:1024
	s_nop 0
	global_load_dwordx4 v[14:17], v[14:15], off offset:192
	v_lshl_add_u64 v[114:115], v[154:155], 0, v[114:115]
	global_store_short v[114:115], v110, off
	v_cvt_pk_bf16_f32 v110, v111, v111
	v_cvt_pk_bf16_f32 v112, v112, v112
	v_lshl_add_u64 v[116:117], v[114:115], 0, s[86:87]
	v_and_b32_e32 v110, 0xffff, v110
	global_store_short v[116:117], v110, off
	v_and_b32_e32 v112, 0xffff, v112
	v_lshl_add_u64 v[110:111], v[114:115], 0, s[74:75]
	global_store_short v[110:111], v112, off
	v_cvt_pk_bf16_f32 v112, v113, v113
	v_pk_fma_f32 v[118:119], v[130:131], v[118:119], v[122:123]
	v_and_b32_e32 v112, 0xffff, v112
	v_lshl_add_u64 v[110:111], v[114:115], 0, s[66:67]
	global_store_short v[110:111], v112, off
	v_cvt_pk_bf16_f32 v112, v118, v118
	v_and_b32_e32 v112, 0xffff, v112
	v_lshl_add_u64 v[110:111], v[114:115], 0, 32
	global_store_short v[110:111], v112, off
	v_cvt_pk_bf16_f32 v112, v119, v119
	v_pk_fma_f32 v[120:121], v[132:133], v[120:121], v[124:125]
	v_and_b32_e32 v112, 0xffff, v112
	v_lshl_add_u64 v[110:111], v[114:115], 0, s[22:23]
	global_store_short v[110:111], v112, off
	v_cvt_pk_bf16_f32 v112, v120, v120
	v_and_b32_e32 v112, 0xffff, v112
	v_lshl_add_u64 v[110:111], v[114:115], 0, s[12:13]
	global_store_short v[110:111], v112, off
	v_cvt_pk_bf16_f32 v112, v121, v121
	v_lshl_add_u64 v[110:111], v[114:115], 0, s[56:57]
	v_and_b32_e32 v112, 0xffff, v112
	global_store_short v[110:111], v112, off
	s_waitcnt lgkmcnt(0)
	s_barrier
	ds_read_b128 v[110:113], v188
	ds_read_b128 v[114:117], v188 offset:64
	ds_read_b128 v[206:209], v188 offset:128
	ds_read_b128 v[122:125], v150 offset:51456
	ds_read_b128 v[210:213], v188 offset:192
	ds_read_b128 v[118:121], v186 offset:61696
	ds_read_b128 v[130:133], v150 offset:51520
	ds_read_b128 v[214:217], v186 offset:61760
	ds_read_b128 v[218:221], v188 offset:4608
	ds_read_b128 v[222:225], v188 offset:4672
	s_waitcnt vmcnt(21) lgkmcnt(9)
	v_mfma_f32_16x16x32_bf16 v[110:113], v[46:49], v[110:113], 0
	v_readlane_b32 s0, v253, 18
	s_waitcnt lgkmcnt(8)
	v_mfma_f32_16x16x32_bf16 v[110:113], v[26:29], v[114:117], v[110:113]
	s_nop 0
	s_nop 0
	s_waitcnt lgkmcnt(7)
	v_mfma_f32_16x16x32_bf16 v[110:113], v[18:21], v[206:209], v[110:113]
	ds_read_b128 v[206:209], v188 offset:4736
	s_nop 0
	s_nop 0
	s_nop 0
	s_waitcnt vmcnt(20) lgkmcnt(6)
	v_mfma_f32_16x16x32_bf16 v[110:113], v[22:25], v[210:213], v[110:113]
	ds_read_b128 v[210:213], v188 offset:4800
	s_waitcnt lgkmcnt(6)
	v_mfma_f32_16x16x32_bf16 v[114:117], v[122:125], v[118:121], 0
	s_nop 0
	s_waitcnt lgkmcnt(4)
	v_mfma_f32_16x16x32_bf16 v[114:117], v[130:133], v[214:217], v[114:117]
	ds_read_b128 v[214:217], v186 offset:64256
	s_nop 0
	s_waitcnt lgkmcnt(4)
	v_mfma_f32_16x16x32_bf16 v[46:49], v[46:49], v[218:221], 0
	ds_read_b128 v[218:221], v186 offset:64320
	s_nop 0
	s_waitcnt lgkmcnt(4)
	v_mfma_f32_16x16x32_bf16 v[26:29], v[26:29], v[222:225], v[46:49]
	ds_read_b128 v[222:225], v183
	s_nop 4
	s_nop 0
	s_waitcnt lgkmcnt(4)
	v_mfma_f32_16x16x32_bf16 v[18:21], v[18:21], v[206:209], v[26:29]
	s_nop 2
	s_nop 0
	v_mov_b32_e32 v46, s0
	ds_read_b32 v134, v46
	ds_read_b128 v[206:209], v184
	s_waitcnt lgkmcnt(5)
	v_mfma_f32_16x16x32_bf16 v[118:121], v[22:25], v[210:213], v[18:21]
	ds_read_b128 v[210:213], v184 offset:2560
	s_nop 2
	s_nop 0
	s_nop 0
	s_nop 0
	s_nop 0
	s_nop 0
	s_waitcnt lgkmcnt(2)
	v_pk_mul_f32 v[44:45], v[44:45], v[134:135] op_sel_hi:[1,0]
	v_mfma_f32_16x16x32_bf16 v[18:21], v[122:125], v[214:217], 0
	ds_read_b128 v[214:217], v183 offset:64
	v_mul_f32_e64 v42, v42, v134
	v_mul_f32_e64 v43, v43, v134
	v_mfma_f32_16x16x32_bf16 v[122:125], v[130:133], v[218:221], v[18:21]
	ds_read_b128 v[218:221], v184 offset:5120
	s_nop 0
	s_nop 0
	s_nop 2
	v_pk_mul_f32 v[20:21], v[108:109], v[134:135] op_sel_hi:[1,0]
	v_pk_mul_f32 v[18:19], v[106:107], v[134:135] op_sel_hi:[1,0]
	s_waitcnt lgkmcnt(3)
	s_nop 0
	v_mfma_f32_16x16x32_bf16 v[18:21], v[222:225], v[206:209], v[18:21]
	v_mul_f32_e64 v48, v104, v134
	v_mul_f32_e64 v49, v105, v134
	v_pk_mul_f32 v[46:47], v[102:103], v[134:135] op_sel_hi:[1,0]
	ds_read_b128 v[206:209], v184 offset:7680
	s_nop 0
	s_waitcnt lgkmcnt(1)
	v_mfma_f32_16x16x32_bf16 v[42:45], v[222:225], v[218:221], v[42:45]
	v_mul_f32_e64 v104, v128, v134
	v_mul_f32_e64 v105, v129, v134
	v_pk_mul_f32 v[102:103], v[126:127], v[134:135] op_sel_hi:[1,0]
	ds_read_b128 v[218:221], v182
	v_mfma_f32_16x16x32_bf16 v[22:25], v[222:225], v[210:213], v[46:49]
	ds_read_b128 v[210:213], v182 offset:2560
	s_nop 2
	s_nop 0
	s_waitcnt lgkmcnt(2)
	v_mfma_f32_16x16x32_bf16 v[26:29], v[222:225], v[206:209], v[102:105]
	ds_read_b128 v[206:209], v182 offset:5120
	ds_read_b128 v[222:225], v182 offset:7680
	ds_read_b128 v[126:129], v181
	s_nop 0
	s_waitcnt lgkmcnt(4)
	v_mfma_f32_16x16x32_bf16 v[106:109], v[214:217], v[218:221], v[18:21]
	s_nop 2
	s_nop 0
	s_waitcnt lgkmcnt(3)
	v_mfma_f32_16x16x32_bf16 v[102:105], v[214:217], v[210:213], v[22:25]
	s_nop 0
	s_waitcnt lgkmcnt(2)
	v_mfma_f32_16x16x32_bf16 v[46:49], v[214:217], v[206:209], v[42:45]
	s_nop 0
	s_nop 0
	s_waitcnt lgkmcnt(1)
	v_mfma_f32_16x16x32_bf16 v[130:133], v[214:217], v[222:225], v[26:29]
	v_cvt_pk_bf16_f32 v18, v106, v107
	v_cvt_pk_bf16_f32 v19, v108, v109
	v_cvt_pk_bf16_f32 v20, v102, v103
	v_cvt_pk_bf16_f32 v21, v104, v105
	ds_write2st64_b64 v187, v[18:19], v[20:21] offset1:9
	v_cvt_pk_bf16_f32 v18, v46, v47
	v_cvt_pk_bf16_f32 v19, v48, v49
	s_nop 0
	v_cvt_pk_bf16_f32 v20, v130, v131
	v_cvt_pk_bf16_f32 v21, v132, v133
	ds_write2st64_b64 v187, v[18:19], v[20:21] offset0:18 offset1:27
	s_waitcnt vmcnt(19)
	ds_write_b128 v171, v[54:57]
	s_waitcnt vmcnt(18)
	ds_write_b128 v171, v[58:61] offset:10240
	s_waitcnt vmcnt(17)
	ds_write_b128 v171, v[82:85] offset:20480
	s_waitcnt vmcnt(16)
	ds_write_b128 v171, v[86:89] offset:30720
	s_waitcnt vmcnt(15)
	ds_write_b128 v178, v[94:97] offset:30720
	s_and_saveexec_b64 s[8:9], vcc
	s_cbranch_execz .LBB0_1563
	s_waitcnt vmcnt(14)
	ds_write_b128 v177, v[90:93] offset:51200
.LBB0_1563:
	s_or_b64 exec, exec, s[8:9]
	s_or_b32 s7, s34, 10
	s_lshl_b32 s0, s7, 5
	s_or_b32 s8, s0, s78
	s_lshl_b32 s0, s8, 13
	s_mov_b32 s1, s61
	v_lshl_add_u64 v[18:19], v[168:169], 0, s[0:1]
	v_lshl_add_u64 v[20:21], v[166:167], 0, s[0:1]
	global_load_dwordx4 v[54:57], v[18:19], off
	global_load_dwordx4 v[58:61], v[20:21], off
	v_lshl_add_u64 v[18:19], v[164:165], 0, s[0:1]
	s_lshl_b32 s0, s7, 16
	s_or_b32 s0, s0, s5
	s_add_u32 s0, s77, s0
	s_addc_u32 s1, s28, 0
	v_lshl_add_u64 v[20:21], s[0:1], 0, v[156:157]
	global_load_dwordx4 v[82:85], v[18:19], off
	global_load_dwordx4 v[86:89], v[20:21], off
	v_lshl_add_u64 v[18:19], s[0:1], 0, v[158:159]
	s_lshl_b32 s0, s8, 8
	s_mov_b32 s1, s61
	v_lshl_add_u64 v[20:21], v[162:163], 0, s[0:1]
	s_or_b32 s48, s6, 0x280
	s_mov_b32 s49, s61
	global_load_dwordx4 v[94:97], v[18:19], off
	global_load_dwordx4 v[90:93], v[20:21], off
	v_lshl_add_u64 v[18:19], v[160:161], 0, s[48:49]
	v_mov_b64_e32 v[20:21], s[80:81]
	v_mad_u64_u32 v[20:21], s[0:1], v18, s19, v[20:21]
	v_mad_i32_i24 v21, v19, s19, v21
	v_lshl_add_u64 v[18:19], v[20:21], 0, s[60:61]
	v_lshl_add_u64 v[18:19], v[18:19], 0, v[196:197]
	s_waitcnt lgkmcnt(7)
	v_pk_fma_f32 v[110:111], v[126:127], v[110:111], v[114:115]
	v_add_co_u32_e64 v24, s[44:45], s14, v18
	v_lshl_add_u64 v[114:115], v[152:153], 0, s[96:97]
	v_cvt_pk_bf16_f32 v110, v110, v110
	v_lshl_add_u64 v[22:23], v[18:19], 0, s[20:21]
	v_addc_co_u32_e64 v25, s[44:45], 0, v19, s[44:45]
	v_pk_fma_f32 v[112:113], v[128:129], v[112:113], v[116:117]
	v_lshlrev_b64 v[114:115], 12, v[114:115]
	v_and_b32_e32 v110, 0xffff, v110
	global_load_dwordx4 v[26:29], v[22:23], off offset:64
	global_load_dwordx4 v[18:21], v[22:23], off offset:128
	global_load_dwordx4 v[42:45], v[24:25], off offset:1024
	s_nop 0
	global_load_dwordx4 v[22:25], v[22:23], off offset:192
	v_lshl_add_u64 v[114:115], v[154:155], 0, v[114:115]
	global_store_short v[114:115], v110, off
	v_cvt_pk_bf16_f32 v110, v111, v111
	v_cvt_pk_bf16_f32 v112, v112, v112
	v_lshl_add_u64 v[116:117], v[114:115], 0, s[86:87]
	v_and_b32_e32 v110, 0xffff, v110
	global_store_short v[116:117], v110, off
	v_and_b32_e32 v112, 0xffff, v112
	v_lshl_add_u64 v[110:111], v[114:115], 0, s[74:75]
	global_store_short v[110:111], v112, off
	v_cvt_pk_bf16_f32 v112, v113, v113
	v_pk_fma_f32 v[118:119], v[126:127], v[118:119], v[122:123]
	v_and_b32_e32 v112, 0xffff, v112
	v_lshl_add_u64 v[110:111], v[114:115], 0, s[66:67]
	global_store_short v[110:111], v112, off
	v_cvt_pk_bf16_f32 v112, v118, v118
	v_and_b32_e32 v112, 0xffff, v112
	v_lshl_add_u64 v[110:111], v[114:115], 0, 32
	global_store_short v[110:111], v112, off
	v_cvt_pk_bf16_f32 v112, v119, v119
	v_pk_fma_f32 v[120:121], v[128:129], v[120:121], v[124:125]
	v_and_b32_e32 v112, 0xffff, v112
	v_lshl_add_u64 v[110:111], v[114:115], 0, s[22:23]
	global_store_short v[110:111], v112, off
	v_cvt_pk_bf16_f32 v112, v120, v120
	v_and_b32_e32 v112, 0xffff, v112
	v_lshl_add_u64 v[110:111], v[114:115], 0, s[12:13]
	global_store_short v[110:111], v112, off
	v_cvt_pk_bf16_f32 v112, v121, v121
	v_lshl_add_u64 v[110:111], v[114:115], 0, s[56:57]
	v_and_b32_e32 v112, 0xffff, v112
	global_store_short v[110:111], v112, off
	s_waitcnt lgkmcnt(0)
	s_barrier
	ds_read_b128 v[110:113], v189
	ds_read_b128 v[114:117], v189 offset:64
	ds_read_b128 v[206:209], v189 offset:128
	ds_read_b128 v[126:129], v150
	ds_read_b128 v[210:213], v189 offset:192
	ds_read_b128 v[118:121], v186 offset:10240
	ds_read_b128 v[122:125], v186 offset:10304
	ds_read_b128 v[214:217], v150 offset:64
	ds_read_b128 v[218:221], v189 offset:4608
	ds_read_b128 v[222:225], v189 offset:4672
	s_waitcnt vmcnt(21) lgkmcnt(9)
	v_mfma_f32_16x16x32_bf16 v[110:113], v[50:53], v[110:113], 0
	s_waitcnt lgkmcnt(8)
	v_mfma_f32_16x16x32_bf16 v[110:113], v[30:33], v[114:117], v[110:113]
	s_nop 0
	s_nop 0
	s_waitcnt lgkmcnt(7)
	v_mfma_f32_16x16x32_bf16 v[110:113], v[2:5], v[206:209], v[110:113]
	ds_read_b128 v[206:209], v189 offset:4736
	s_nop 0
	s_nop 0
	s_nop 0
	s_waitcnt vmcnt(20) lgkmcnt(6)
	v_mfma_f32_16x16x32_bf16 v[114:117], v[6:9], v[210:213], v[110:113]
	ds_read_b128 v[210:213], v189 offset:4800
	s_nop 2
	s_nop 0
	s_waitcnt lgkmcnt(6)
	v_mfma_f32_16x16x32_bf16 v[118:121], v[126:129], v[118:121], 0
	s_waitcnt lgkmcnt(4)
	v_mfma_f32_16x16x32_bf16 v[118:121], v[214:217], v[122:125], v[118:121]
	s_nop 0
	s_waitcnt lgkmcnt(3)
	v_mfma_f32_16x16x32_bf16 v[50:53], v[50:53], v[218:221], 0
	ds_read_b128 v[218:221], v186 offset:12800
	s_nop 0
	s_waitcnt lgkmcnt(3)
	v_mfma_f32_16x16x32_bf16 v[30:33], v[30:33], v[222:225], v[50:53]
	ds_read_b128 v[222:225], v186 offset:12864
	s_nop 4
	s_nop 0
	s_waitcnt lgkmcnt(3)
	v_mfma_f32_16x16x32_bf16 v[2:5], v[2:5], v[206:209], v[30:33]
	ds_read_b128 v[206:209], v180 offset:30720
	ds_read_b32 v134, v197 offset:51452
	ds_read_b128 v[50:53], v179 offset:20480
	ds_read_b128 v[138:141], v180 offset:30784
	s_nop 2
	s_nop 0
	s_waitcnt lgkmcnt(6)
	v_mfma_f32_16x16x32_bf16 v[122:125], v[6:9], v[210:213], v[2:5]
	ds_read_b128 v[210:213], v179 offset:23040
	s_nop 2
	s_nop 0
	s_nop 0
	s_nop 0
	s_nop 0
	s_nop 0
	s_nop 0
	s_waitcnt lgkmcnt(6)
	v_mfma_f32_16x16x32_bf16 v[2:5], v[126:129], v[218:221], 0
	ds_read_b128 v[218:221], v179 offset:25600
	s_waitcnt lgkmcnt(4)
	v_pk_mul_f32 v[48:49], v[48:49], v[134:135] op_sel_hi:[1,0]
	v_pk_mul_f32 v[46:47], v[46:47], v[134:135] op_sel_hi:[1,0]
	v_mfma_f32_16x16x32_bf16 v[126:129], v[214:217], v[222:225], v[2:5]
	ds_read_b128 v[214:217], v179 offset:28160
	ds_read_b128 v[222:225], v179 offset:20544
	s_nop 0
	s_nop 2
	v_pk_mul_f32 v[4:5], v[108:109], v[134:135] op_sel_hi:[1,0]
	v_pk_mul_f32 v[2:3], v[106:107], v[134:135] op_sel_hi:[1,0]
	s_waitcnt lgkmcnt(5)
	s_nop 0
	v_mfma_f32_16x16x32_bf16 v[2:5], v[206:209], v[50:53], v[2:5]
	v_mul_f32_e64 v52, v104, v134
	v_mul_f32_e64 v53, v105, v134
	v_pk_mul_f32 v[50:51], v[102:103], v[134:135] op_sel_hi:[1,0]
	s_nop 0
	s_waitcnt lgkmcnt(2)
	v_mfma_f32_16x16x32_bf16 v[46:49], v[206:209], v[218:221], v[46:49]
	v_mul_f32_e64 v104, v132, v134
	v_mul_f32_e64 v105, v133, v134
	v_pk_mul_f32 v[102:103], v[130:131], v[134:135] op_sel_hi:[1,0]
	ds_read_b128 v[218:221], v179 offset:23104
	v_mfma_f32_16x16x32_bf16 v[6:9], v[206:209], v[210:213], v[50:53]
	ds_read_b128 v[210:213], v179 offset:25664
	s_nop 2
	s_nop 0
	s_waitcnt lgkmcnt(3)
	v_mfma_f32_16x16x32_bf16 v[30:33], v[206:209], v[214:217], v[102:105]
	ds_read_b128 v[206:209], v179 offset:28224
	ds_read_b128 v[134:137], v176 offset:51200
	s_nop 0
	s_waitcnt lgkmcnt(4)
	v_mfma_f32_16x16x32_bf16 v[110:113], v[138:141], v[222:225], v[2:5]
	s_nop 2
	s_nop 0
	s_waitcnt lgkmcnt(3)
	v_mfma_f32_16x16x32_bf16 v[106:109], v[138:141], v[218:221], v[6:9]
	s_nop 0
	s_waitcnt lgkmcnt(2)
	v_mfma_f32_16x16x32_bf16 v[102:105], v[138:141], v[210:213], v[46:49]
	s_nop 0
	s_nop 0
	s_waitcnt lgkmcnt(1)
	v_mfma_f32_16x16x32_bf16 v[130:133], v[138:141], v[206:209], v[30:33]
	v_cvt_pk_bf16_f32 v2, v110, v111
	v_cvt_pk_bf16_f32 v3, v112, v113
	v_cvt_pk_bf16_f32 v4, v106, v107
	v_cvt_pk_bf16_f32 v5, v108, v109
	ds_write2st64_b64 v174, v[2:3], v[4:5] offset1:9
	v_cvt_pk_bf16_f32 v2, v102, v103
	v_cvt_pk_bf16_f32 v3, v104, v105
	s_nop 0
	v_cvt_pk_bf16_f32 v4, v130, v131
	v_cvt_pk_bf16_f32 v5, v132, v133
	ds_write2st64_b64 v174, v[2:3], v[4:5] offset0:18 offset1:27
	s_waitcnt vmcnt(19)
	ds_write_b128 v171, v[62:65] offset:51456
	s_waitcnt vmcnt(18)
	ds_write_b128 v171, v[66:69] offset:61696
	s_waitcnt vmcnt(17)
	ds_write_b128 v172, v[70:73]
	s_waitcnt vmcnt(16)
	ds_write_b128 v173, v[74:77]
	s_waitcnt vmcnt(15)
	ds_write_b128 v175, v[98:101]
	s_and_saveexec_b64 s[8:9], vcc
	s_cbranch_execz .LBB0_1565
	s_waitcnt vmcnt(14)
	ds_write_b128 v185, v[78:81]
.LBB0_1565:
	s_or_b64 exec, exec, s[8:9]
	s_or_b32 s7, s34, 11
	s_lshl_b32 s0, s7, 5
	s_or_b32 s8, s0, s78
	s_lshl_b32 s0, s8, 13
	s_mov_b32 s1, s61
	v_lshl_add_u64 v[2:3], v[168:169], 0, s[0:1]
	v_lshl_add_u64 v[4:5], v[166:167], 0, s[0:1]
	global_load_dwordx4 v[50:53], v[2:3], off
	global_load_dwordx4 v[62:65], v[4:5], off
	v_lshl_add_u64 v[2:3], v[164:165], 0, s[0:1]
	s_lshl_b32 s0, s7, 16
	s_or_b32 s0, s0, s5
	s_add_u32 s0, s77, s0
	s_addc_u32 s1, s28, 0
	v_lshl_add_u64 v[4:5], s[0:1], 0, v[156:157]
	global_load_dwordx4 v[66:69], v[2:3], off
	global_load_dwordx4 v[70:73], v[4:5], off
	v_lshl_add_u64 v[2:3], s[0:1], 0, v[158:159]
	s_lshl_b32 s0, s8, 8
	s_mov_b32 s1, s61
	v_lshl_add_u64 v[4:5], v[162:163], 0, s[0:1]
	s_or_b32 s52, s6, 0x2c0
	s_mov_b32 s53, s61
	global_load_dwordx4 v[98:101], v[2:3], off
	global_load_dwordx4 v[74:77], v[4:5], off
	v_lshl_add_u64 v[2:3], v[160:161], 0, s[52:53]
	v_mov_b64_e32 v[4:5], s[80:81]
	v_mad_u64_u32 v[4:5], s[0:1], v2, s19, v[4:5]
	v_mad_i32_i24 v5, v3, s19, v5
	v_lshl_add_u64 v[2:3], v[4:5], 0, s[60:61]
	v_lshl_add_u64 v[2:3], v[2:3], 0, v[196:197]
	s_waitcnt lgkmcnt(7)
	v_pk_fma_f32 v[114:115], v[134:135], v[114:115], v[118:119]
	v_add_co_u32_e64 v8, s[44:45], s14, v2
	v_lshl_add_u64 v[118:119], v[152:153], 0, s[46:47]
	v_cvt_pk_bf16_f32 v114, v114, v114
	v_lshl_add_u64 v[6:7], v[2:3], 0, s[20:21]
	v_addc_co_u32_e64 v9, s[44:45], 0, v3, s[44:45]
	v_pk_fma_f32 v[116:117], v[136:137], v[116:117], v[120:121]
	v_lshlrev_b64 v[118:119], 12, v[118:119]
	v_and_b32_e32 v114, 0xffff, v114
	global_load_dwordx4 v[30:33], v[6:7], off offset:64
	global_load_dwordx4 v[2:5], v[6:7], off offset:128
	global_load_dwordx4 v[46:49], v[8:9], off offset:1024
	s_nop 0
	global_load_dwordx4 v[6:9], v[6:7], off offset:192
	v_lshl_add_u64 v[118:119], v[154:155], 0, v[118:119]
	global_store_short v[118:119], v114, off
	v_cvt_pk_bf16_f32 v114, v115, v115
	v_cvt_pk_bf16_f32 v116, v116, v116
	s_waitcnt vmcnt(24)
	v_pk_fma_f32 v[80:81], v[134:135], v[122:123], v[126:127]
	v_lshl_add_u64 v[120:121], v[118:119], 0, s[86:87]
	v_and_b32_e32 v114, 0xffff, v114
	global_store_short v[120:121], v114, off
	v_and_b32_e32 v116, 0xffff, v116
	v_lshl_add_u64 v[114:115], v[118:119], 0, s[74:75]
	global_store_short v[114:115], v116, off
	v_cvt_pk_bf16_f32 v116, v117, v117
	v_cvt_pk_bf16_f32 v80, v80, v80
	v_pk_fma_f32 v[78:79], v[136:137], v[124:125], v[128:129]
	v_lshl_add_u64 v[114:115], v[118:119], 0, s[66:67]
	v_and_b32_e32 v116, 0xffff, v116
	global_store_short v[114:115], v116, off
	v_and_b32_e32 v80, 0xffff, v80
	v_lshl_add_u64 v[114:115], v[118:119], 0, 32
	global_store_short v[114:115], v80, off
	v_cvt_pk_bf16_f32 v80, v81, v81
	v_cvt_pk_bf16_f32 v78, v78, v78
	v_lshl_add_u64 v[114:115], v[118:119], 0, s[22:23]
	v_and_b32_e32 v80, 0xffff, v80
	global_store_short v[114:115], v80, off
	v_and_b32_e32 v78, 0xffff, v78
	v_lshl_add_u64 v[80:81], v[118:119], 0, s[12:13]
	global_store_short v[80:81], v78, off
	v_cvt_pk_bf16_f32 v78, v79, v79
	v_lshl_add_u64 v[80:81], v[118:119], 0, s[56:57]
	v_and_b32_e32 v78, 0xffff, v78
	global_store_short v[80:81], v78, off
	s_waitcnt lgkmcnt(0)
	s_barrier
	ds_read_b128 v[78:81], v188
	ds_read_b128 v[114:117], v188 offset:64
	ds_read_b128 v[206:209], v188 offset:128
	ds_read_b128 v[126:129], v150 offset:51456
	ds_read_b128 v[210:213], v188 offset:192
	ds_read_b128 v[118:121], v186 offset:61696
	ds_read_b128 v[122:125], v186 offset:61760
	ds_read_b128 v[214:217], v150 offset:51520
	ds_read_b128 v[218:221], v188 offset:4608
	ds_read_b128 v[222:225], v188 offset:4672
	s_waitcnt vmcnt(21) lgkmcnt(9)
	v_mfma_f32_16x16x32_bf16 v[78:81], v[38:41], v[78:81], 0
	v_readlane_b32 s0, v253, 18
	s_waitcnt lgkmcnt(8)
	v_mfma_f32_16x16x32_bf16 v[78:81], v[34:37], v[114:117], v[78:81]
	s_nop 0
	s_nop 0
	s_waitcnt lgkmcnt(7)
	v_mfma_f32_16x16x32_bf16 v[78:81], v[10:13], v[206:209], v[78:81]
	ds_read_b128 v[206:209], v188 offset:4736
	s_nop 0
	s_nop 0
	s_nop 0
	s_waitcnt vmcnt(20) lgkmcnt(6)
	v_mfma_f32_16x16x32_bf16 v[114:117], v[14:17], v[210:213], v[78:81]
	ds_read_b128 v[210:213], v188 offset:4800
	s_nop 2
	s_nop 0
	s_waitcnt lgkmcnt(6)
	v_mfma_f32_16x16x32_bf16 v[118:121], v[126:129], v[118:121], 0
	s_waitcnt lgkmcnt(4)
	v_mfma_f32_16x16x32_bf16 v[118:121], v[214:217], v[122:125], v[118:121]
	s_nop 0
	s_waitcnt lgkmcnt(3)
	v_mfma_f32_16x16x32_bf16 v[38:41], v[38:41], v[218:221], 0
	ds_read_b128 v[218:221], v186 offset:64256
	s_nop 0
	s_waitcnt lgkmcnt(3)
	v_mfma_f32_16x16x32_bf16 v[34:37], v[34:37], v[222:225], v[38:41]
	ds_read_b128 v[222:225], v186 offset:64320
	s_nop 4
	s_nop 0
	s_waitcnt lgkmcnt(3)
	v_mfma_f32_16x16x32_bf16 v[10:13], v[10:13], v[206:209], v[34:37]
	ds_read_b128 v[206:209], v183
	s_nop 2
	s_nop 0
	v_mov_b32_e32 v38, s0
	ds_read_b32 v134, v38
	s_waitcnt lgkmcnt(4)
	v_mfma_f32_16x16x32_bf16 v[122:125], v[14:17], v[210:213], v[10:13]
	ds_read_b128 v[210:213], v184
	s_nop 2
	s_nop 0
	s_nop 0
	s_nop 0
	s_nop 0
	s_nop 0
	s_waitcnt lgkmcnt(4)
	v_mfma_f32_16x16x32_bf16 v[10:13], v[126:129], v[218:221], 0
	ds_read_b128 v[218:221], v184 offset:2560
	s_waitcnt lgkmcnt(4)
	v_mfma_f32_16x16x32_bf16 v[126:129], v[214:217], v[222:225], v[10:13]
	ds_read_b128 v[78:81], v184 offset:5120
	ds_read_b128 v[214:217], v184 offset:7680
	ds_read_b128 v[222:225], v183 offset:64
	s_nop 0
	s_nop 0
	s_waitcnt lgkmcnt(5)
	s_nop 2
	v_pk_mul_f32 v[12:13], v[112:113], v[134:135] op_sel_hi:[1,0]
	v_pk_mul_f32 v[10:11], v[110:111], v[134:135] op_sel_hi:[1,0]
	s_waitcnt lgkmcnt(4)
	s_nop 0
	v_mfma_f32_16x16x32_bf16 v[10:13], v[206:209], v[210:213], v[10:13]
	v_mul_f32_e64 v40, v108, v134
	v_mul_f32_e64 v41, v109, v134
	v_pk_mul_f32 v[38:39], v[106:107], v[134:135] op_sel_hi:[1,0]
	ds_read_b128 v[210:213], v182
	v_pk_mul_f32 v[108:109], v[132:133], v[134:135] op_sel_hi:[1,0]
	v_pk_mul_f32 v[106:107], v[130:131], v[134:135] op_sel_hi:[1,0]
	s_waitcnt lgkmcnt(4)
	v_mfma_f32_16x16x32_bf16 v[14:17], v[206:209], v[218:221], v[38:41]
	ds_read_b128 v[218:221], v182 offset:2560
	s_nop 2
	v_mul_f32_e64 v40, v104, v134
	v_mul_f32_e64 v41, v105, v134
	v_pk_mul_f32 v[38:39], v[102:103], v[134:135] op_sel_hi:[1,0]
	s_nop 0
	s_waitcnt lgkmcnt(4)
	v_mfma_f32_16x16x32_bf16 v[38:41], v[206:209], v[78:81], v[38:41]
	s_nop 0
	s_waitcnt lgkmcnt(3)
	v_mfma_f32_16x16x32_bf16 v[34:37], v[206:209], v[214:217], v[106:109]
	ds_read_b128 v[206:209], v182 offset:5120
	ds_read_b128 v[214:217], v182 offset:7680
	ds_read_b128 v[134:137], v181
	s_nop 0
	s_waitcnt lgkmcnt(4)
	v_mfma_f32_16x16x32_bf16 v[110:113], v[222:225], v[210:213], v[10:13]
	s_nop 2
	s_nop 0
	s_waitcnt lgkmcnt(3)
	v_mfma_f32_16x16x32_bf16 v[106:109], v[222:225], v[218:221], v[14:17]
	s_nop 0
	s_waitcnt lgkmcnt(2)
	v_mfma_f32_16x16x32_bf16 v[102:105], v[222:225], v[206:209], v[38:41]
	s_nop 0
	s_nop 0
	s_waitcnt lgkmcnt(1)
	v_mfma_f32_16x16x32_bf16 v[130:133], v[222:225], v[214:217], v[34:37]
	v_cvt_pk_bf16_f32 v10, v110, v111
	v_cvt_pk_bf16_f32 v11, v112, v113
	v_cvt_pk_bf16_f32 v12, v106, v107
	v_cvt_pk_bf16_f32 v13, v108, v109
	ds_write2st64_b64 v187, v[10:11], v[12:13] offset1:9
	v_cvt_pk_bf16_f32 v10, v102, v103
	v_cvt_pk_bf16_f32 v11, v104, v105
	s_nop 0
	v_cvt_pk_bf16_f32 v12, v130, v131
	v_cvt_pk_bf16_f32 v13, v132, v133
	ds_write2st64_b64 v187, v[10:11], v[12:13] offset0:18 offset1:27
	s_waitcnt vmcnt(19)
	ds_write_b128 v171, v[54:57]
	s_waitcnt vmcnt(18)
	ds_write_b128 v171, v[58:61] offset:10240
	s_waitcnt vmcnt(17)
	ds_write_b128 v171, v[82:85] offset:20480
	s_waitcnt vmcnt(16)
	ds_write_b128 v171, v[86:89] offset:30720
	s_waitcnt vmcnt(15)
	ds_write_b128 v178, v[94:97] offset:30720
	s_and_saveexec_b64 s[8:9], vcc
	s_cbranch_execz .LBB0_1567
	s_waitcnt vmcnt(14)
	ds_write_b128 v177, v[90:93] offset:51200
.LBB0_1567:
	s_or_b64 exec, exec, s[8:9]
	s_or_b32 s7, s34, 12
	s_lshl_b32 s0, s7, 5
	s_or_b32 s8, s0, s78
	s_lshl_b32 s0, s8, 13
	s_mov_b32 s1, s61
	v_lshl_add_u64 v[10:11], v[168:169], 0, s[0:1]
	v_lshl_add_u64 v[12:13], v[166:167], 0, s[0:1]
	global_load_dwordx4 v[54:57], v[10:11], off
	global_load_dwordx4 v[58:61], v[12:13], off
	v_lshl_add_u64 v[10:11], v[164:165], 0, s[0:1]
	s_lshl_b32 s0, s7, 16
	s_or_b32 s0, s0, s5
	s_add_u32 s0, s77, s0
	s_addc_u32 s1, s28, 0
	v_lshl_add_u64 v[12:13], s[0:1], 0, v[156:157]
	global_load_dwordx4 v[78:81], v[10:11], off
	global_load_dwordx4 v[82:85], v[12:13], off
	v_lshl_add_u64 v[10:11], s[0:1], 0, v[158:159]
	s_lshl_b32 s0, s8, 8
	s_mov_b32 s1, s61
	v_lshl_add_u64 v[12:13], v[162:163], 0, s[0:1]
	s_or_b32 s46, s6, 0x300
	s_mov_b32 s47, s61
	global_load_dwordx4 v[90:93], v[10:11], off
	global_load_dwordx4 v[86:89], v[12:13], off
	v_lshl_add_u64 v[10:11], v[160:161], 0, s[46:47]
	v_mov_b64_e32 v[12:13], s[80:81]
	v_mad_u64_u32 v[12:13], s[0:1], v10, s19, v[12:13]
	v_mad_i32_i24 v13, v11, s19, v13
	v_lshl_add_u64 v[10:11], v[12:13], 0, s[60:61]
	v_lshl_add_u64 v[10:11], v[10:11], 0, v[196:197]
	s_waitcnt lgkmcnt(7)
	v_pk_fma_f32 v[114:115], v[134:135], v[114:115], v[118:119]
	v_add_co_u32_e64 v16, s[44:45], s14, v10
	v_lshl_add_u64 v[118:119], v[152:153], 0, s[50:51]
	v_cvt_pk_bf16_f32 v114, v114, v114
	v_lshl_add_u64 v[14:15], v[10:11], 0, s[20:21]
	v_addc_co_u32_e64 v17, s[44:45], 0, v11, s[44:45]
	v_pk_fma_f32 v[116:117], v[136:137], v[116:117], v[120:121]
	v_lshlrev_b64 v[118:119], 12, v[118:119]
	v_and_b32_e32 v114, 0xffff, v114
	global_load_dwordx4 v[34:37], v[14:15], off offset:64
	global_load_dwordx4 v[10:13], v[14:15], off offset:128
	global_load_dwordx4 v[38:41], v[16:17], off offset:1024
	s_nop 0
	global_load_dwordx4 v[14:17], v[14:15], off offset:192
	v_lshl_add_u64 v[118:119], v[154:155], 0, v[118:119]
	global_store_short v[118:119], v114, off
	v_cvt_pk_bf16_f32 v114, v115, v115
	v_cvt_pk_bf16_f32 v116, v116, v116
	v_pk_fma_f32 v[96:97], v[134:135], v[122:123], v[126:127]
	v_lshl_add_u64 v[120:121], v[118:119], 0, s[86:87]
	v_and_b32_e32 v114, 0xffff, v114
	global_store_short v[120:121], v114, off
	v_and_b32_e32 v116, 0xffff, v116
	v_lshl_add_u64 v[114:115], v[118:119], 0, s[74:75]
	global_store_short v[114:115], v116, off
	v_cvt_pk_bf16_f32 v116, v117, v117
	v_cvt_pk_bf16_f32 v96, v96, v96
	v_pk_fma_f32 v[94:95], v[136:137], v[124:125], v[128:129]
	v_lshl_add_u64 v[114:115], v[118:119], 0, s[66:67]
	v_and_b32_e32 v116, 0xffff, v116
	global_store_short v[114:115], v116, off
	v_and_b32_e32 v96, 0xffff, v96
	v_lshl_add_u64 v[114:115], v[118:119], 0, 32
	global_store_short v[114:115], v96, off
	v_cvt_pk_bf16_f32 v96, v97, v97
	v_cvt_pk_bf16_f32 v94, v94, v94
	v_lshl_add_u64 v[114:115], v[118:119], 0, s[22:23]
	v_and_b32_e32 v96, 0xffff, v96
	global_store_short v[114:115], v96, off
	v_and_b32_e32 v94, 0xffff, v94
	v_lshl_add_u64 v[96:97], v[118:119], 0, s[12:13]
	global_store_short v[96:97], v94, off
	v_cvt_pk_bf16_f32 v94, v95, v95
	v_lshl_add_u64 v[96:97], v[118:119], 0, s[56:57]
	v_and_b32_e32 v94, 0xffff, v94
	global_store_short v[96:97], v94, off
	s_waitcnt lgkmcnt(0)
	s_barrier
	ds_read_b128 v[94:97], v189
	ds_read_b128 v[114:117], v189 offset:64
	ds_read_b128 v[206:209], v189 offset:128
	ds_read_b128 v[126:129], v150
	ds_read_b128 v[210:213], v189 offset:192
	ds_read_b128 v[118:121], v186 offset:10240
	ds_read_b128 v[122:125], v186 offset:10304
	ds_read_b128 v[214:217], v150 offset:64
	ds_read_b128 v[218:221], v189 offset:4608
	ds_read_b128 v[222:225], v189 offset:4672
	s_waitcnt vmcnt(21) lgkmcnt(9)
	v_mfma_f32_16x16x32_bf16 v[94:97], v[42:45], v[94:97], 0
	s_waitcnt lgkmcnt(8)
	v_mfma_f32_16x16x32_bf16 v[94:97], v[26:29], v[114:117], v[94:97]
	s_nop 0
	s_nop 0
	s_waitcnt lgkmcnt(7)
	v_mfma_f32_16x16x32_bf16 v[94:97], v[18:21], v[206:209], v[94:97]
	ds_read_b128 v[206:209], v189 offset:4736
	s_nop 0
	s_nop 0
	s_nop 0
	s_waitcnt vmcnt(20) lgkmcnt(6)
	v_mfma_f32_16x16x32_bf16 v[114:117], v[22:25], v[210:213], v[94:97]
	ds_read_b128 v[210:213], v189 offset:4800
	s_nop 2
	s_nop 0
	s_waitcnt lgkmcnt(6)
	v_mfma_f32_16x16x32_bf16 v[118:121], v[126:129], v[118:121], 0
	s_waitcnt lgkmcnt(4)
	v_mfma_f32_16x16x32_bf16 v[118:121], v[214:217], v[122:125], v[118:121]
	s_nop 0
	s_waitcnt lgkmcnt(3)
	v_mfma_f32_16x16x32_bf16 v[42:45], v[42:45], v[218:221], 0
	ds_read_b128 v[218:221], v186 offset:12800
	s_nop 0
	s_waitcnt lgkmcnt(3)
	v_mfma_f32_16x16x32_bf16 v[26:29], v[26:29], v[222:225], v[42:45]
	ds_read_b128 v[222:225], v186 offset:12864
	s_nop 4
	s_nop 0
	s_waitcnt lgkmcnt(3)
	v_mfma_f32_16x16x32_bf16 v[18:21], v[18:21], v[206:209], v[26:29]
	ds_read_b128 v[206:209], v180 offset:30720
	ds_read_b32 v134, v197 offset:51452
	ds_read_b128 v[42:45], v179 offset:20480
	s_nop 2
	s_nop 0
	s_waitcnt lgkmcnt(5)
	v_mfma_f32_16x16x32_bf16 v[122:125], v[22:25], v[210:213], v[18:21]
	ds_read_b128 v[210:213], v179 offset:23040
	s_nop 2
	s_nop 0
	s_nop 0
	s_nop 0
	s_nop 0
	s_nop 0
	s_waitcnt lgkmcnt(5)
	v_mfma_f32_16x16x32_bf16 v[18:21], v[126:129], v[218:221], 0
	ds_read_b128 v[218:221], v179 offset:25600
	s_waitcnt lgkmcnt(5)
	v_mfma_f32_16x16x32_bf16 v[126:129], v[214:217], v[222:225], v[18:21]
	ds_read_b128 v[214:217], v179 offset:28160
	ds_read_b128 v[222:225], v180 offset:30784
	s_nop 0
	s_nop 0
	s_waitcnt lgkmcnt(5)
	s_nop 2
	v_pk_mul_f32 v[20:21], v[112:113], v[134:135] op_sel_hi:[1,0]
	v_pk_mul_f32 v[18:19], v[110:111], v[134:135] op_sel_hi:[1,0]
	s_waitcnt lgkmcnt(4)
	s_nop 0
	v_mfma_f32_16x16x32_bf16 v[18:21], v[206:209], v[42:45], v[18:21]
	v_mul_f32_e64 v44, v108, v134
	v_mul_f32_e64 v45, v109, v134
	v_pk_mul_f32 v[42:43], v[106:107], v[134:135] op_sel_hi:[1,0]
	v_pk_mul_f32 v[108:109], v[132:133], v[134:135] op_sel_hi:[1,0]
	v_pk_mul_f32 v[106:107], v[130:131], v[134:135] op_sel_hi:[1,0]
	s_waitcnt lgkmcnt(3)
	v_mfma_f32_16x16x32_bf16 v[22:25], v[206:209], v[210:213], v[42:45]
	ds_read_b128 v[210:213], v179 offset:20544
	s_nop 2
	v_mul_f32_e64 v44, v104, v134
	v_mul_f32_e64 v45, v105, v134
	v_pk_mul_f32 v[42:43], v[102:103], v[134:135] op_sel_hi:[1,0]
	s_nop 0
	s_waitcnt lgkmcnt(3)
	v_mfma_f32_16x16x32_bf16 v[42:45], v[206:209], v[218:221], v[42:45]
	ds_read_b128 v[218:221], v179 offset:23104
	s_nop 0
	s_waitcnt lgkmcnt(3)
	v_mfma_f32_16x16x32_bf16 v[26:29], v[206:209], v[214:217], v[106:109]
	ds_read_b128 v[206:209], v179 offset:25664
	ds_read_b128 v[214:217], v179 offset:28224
	ds_read_b128 v[134:137], v176 offset:51200
	s_nop 0
	s_waitcnt lgkmcnt(4)
	v_mfma_f32_16x16x32_bf16 v[110:113], v[222:225], v[210:213], v[18:21]
	s_nop 2
	s_nop 0
	s_waitcnt lgkmcnt(3)
	v_mfma_f32_16x16x32_bf16 v[106:109], v[222:225], v[218:221], v[22:25]
	s_nop 0
	s_waitcnt lgkmcnt(2)
	v_mfma_f32_16x16x32_bf16 v[102:105], v[222:225], v[206:209], v[42:45]
	s_nop 0
	s_nop 0
	s_waitcnt lgkmcnt(1)
	v_mfma_f32_16x16x32_bf16 v[130:133], v[222:225], v[214:217], v[26:29]
	v_cvt_pk_bf16_f32 v18, v110, v111
	v_cvt_pk_bf16_f32 v19, v112, v113
	v_cvt_pk_bf16_f32 v20, v106, v107
	v_cvt_pk_bf16_f32 v21, v108, v109
	ds_write2st64_b64 v174, v[18:19], v[20:21] offset1:9
	v_cvt_pk_bf16_f32 v18, v102, v103
	v_cvt_pk_bf16_f32 v19, v104, v105
	s_nop 0
	v_cvt_pk_bf16_f32 v20, v130, v131
	v_cvt_pk_bf16_f32 v21, v132, v133
	ds_write2st64_b64 v174, v[18:19], v[20:21] offset0:18 offset1:27
	s_waitcnt vmcnt(19)
	ds_write_b128 v171, v[50:53] offset:51456
	s_waitcnt vmcnt(18)
	ds_write_b128 v171, v[62:65] offset:61696
	s_waitcnt vmcnt(17)
	ds_write_b128 v172, v[66:69]
	s_waitcnt vmcnt(16)
	ds_write_b128 v173, v[70:73]
	s_waitcnt vmcnt(15)
	ds_write_b128 v175, v[98:101]
	s_and_saveexec_b64 s[8:9], vcc
	s_cbranch_execz .LBB0_1569
	s_waitcnt vmcnt(14)
	ds_write_b128 v185, v[74:77]
.LBB0_1569:
	s_or_b64 exec, exec, s[8:9]
	s_or_b32 s7, s34, 13
	s_lshl_b32 s0, s7, 5
	s_or_b32 s8, s0, s78
	s_lshl_b32 s0, s8, 13
	s_mov_b32 s1, s61
	v_lshl_add_u64 v[18:19], v[168:169], 0, s[0:1]
	v_lshl_add_u64 v[20:21], v[166:167], 0, s[0:1]
	global_load_dwordx4 v[50:53], v[18:19], off
	global_load_dwordx4 v[62:65], v[20:21], off
	v_lshl_add_u64 v[18:19], v[164:165], 0, s[0:1]
	s_lshl_b32 s0, s7, 16
	s_or_b32 s0, s0, s5
	s_add_u32 s0, s77, s0
	s_addc_u32 s1, s28, 0
	v_lshl_add_u64 v[20:21], s[0:1], 0, v[156:157]
	global_load_dwordx4 v[66:69], v[18:19], off
	global_load_dwordx4 v[70:73], v[20:21], off
	v_lshl_add_u64 v[18:19], s[0:1], 0, v[158:159]
	s_lshl_b32 s0, s8, 8
	s_mov_b32 s1, s61
	v_lshl_add_u64 v[20:21], v[162:163], 0, s[0:1]
	s_or_b32 s50, s6, 0x340
	s_mov_b32 s51, s61
	global_load_dwordx4 v[94:97], v[18:19], off
	global_load_dwordx4 v[74:77], v[20:21], off
	v_lshl_add_u64 v[18:19], v[160:161], 0, s[50:51]
	v_mov_b64_e32 v[20:21], s[80:81]
	v_mad_u64_u32 v[20:21], s[0:1], v18, s19, v[20:21]
	v_mad_i32_i24 v21, v19, s19, v21
	v_lshl_add_u64 v[18:19], v[20:21], 0, s[60:61]
	v_lshl_add_u64 v[18:19], v[18:19], 0, v[196:197]
	s_waitcnt lgkmcnt(7)
	v_pk_fma_f32 v[114:115], v[134:135], v[114:115], v[118:119]
	v_add_co_u32_e64 v24, s[44:45], s14, v18
	v_lshl_add_u64 v[118:119], v[152:153], 0, s[48:49]
	v_cvt_pk_bf16_f32 v114, v114, v114
	v_lshl_add_u64 v[22:23], v[18:19], 0, s[20:21]
	v_addc_co_u32_e64 v25, s[44:45], 0, v19, s[44:45]
	v_pk_fma_f32 v[116:117], v[136:137], v[116:117], v[120:121]
	v_lshlrev_b64 v[118:119], 12, v[118:119]
	v_and_b32_e32 v114, 0xffff, v114
	global_load_dwordx4 v[26:29], v[22:23], off offset:64
	global_load_dwordx4 v[18:21], v[22:23], off offset:128
	global_load_dwordx4 v[42:45], v[24:25], off offset:1024
	s_nop 0
	global_load_dwordx4 v[22:25], v[22:23], off offset:192
	v_lshl_add_u64 v[118:119], v[154:155], 0, v[118:119]
	global_store_short v[118:119], v114, off
	v_cvt_pk_bf16_f32 v114, v115, v115
	v_cvt_pk_bf16_f32 v116, v116, v116
	v_pk_fma_f32 v[100:101], v[134:135], v[122:123], v[126:127]
	v_lshl_add_u64 v[120:121], v[118:119], 0, s[86:87]
	v_and_b32_e32 v114, 0xffff, v114
	global_store_short v[120:121], v114, off
	v_and_b32_e32 v116, 0xffff, v116
	v_lshl_add_u64 v[114:115], v[118:119], 0, s[74:75]
	global_store_short v[114:115], v116, off
	v_cvt_pk_bf16_f32 v116, v117, v117
	v_cvt_pk_bf16_f32 v100, v100, v100
	v_pk_fma_f32 v[98:99], v[136:137], v[124:125], v[128:129]
	v_lshl_add_u64 v[114:115], v[118:119], 0, s[66:67]
	v_and_b32_e32 v116, 0xffff, v116
	global_store_short v[114:115], v116, off
	v_and_b32_e32 v100, 0xffff, v100
	v_lshl_add_u64 v[114:115], v[118:119], 0, 32
	global_store_short v[114:115], v100, off
	v_cvt_pk_bf16_f32 v100, v101, v101
	v_cvt_pk_bf16_f32 v98, v98, v98
	v_lshl_add_u64 v[114:115], v[118:119], 0, s[22:23]
	v_and_b32_e32 v100, 0xffff, v100
	global_store_short v[114:115], v100, off
	v_and_b32_e32 v98, 0xffff, v98
	v_lshl_add_u64 v[100:101], v[118:119], 0, s[12:13]
	global_store_short v[100:101], v98, off
	v_cvt_pk_bf16_f32 v98, v99, v99
	v_lshl_add_u64 v[100:101], v[118:119], 0, s[56:57]
	v_and_b32_e32 v98, 0xffff, v98
	global_store_short v[100:101], v98, off
	s_waitcnt lgkmcnt(0)
	s_barrier
	ds_read_b128 v[98:101], v188
	ds_read_b128 v[114:117], v188 offset:64
	ds_read_b128 v[206:209], v188 offset:128
	ds_read_b128 v[126:129], v150 offset:51456
	ds_read_b128 v[210:213], v188 offset:192
	ds_read_b128 v[118:121], v186 offset:61696
	ds_read_b128 v[122:125], v186 offset:61760
	ds_read_b128 v[214:217], v150 offset:51520
	ds_read_b128 v[218:221], v188 offset:4608
	ds_read_b128 v[222:225], v188 offset:4672
	s_waitcnt vmcnt(21) lgkmcnt(9)
	v_mfma_f32_16x16x32_bf16 v[98:101], v[46:49], v[98:101], 0
	v_readlane_b32 s0, v253, 18
	s_waitcnt lgkmcnt(8)
	v_mfma_f32_16x16x32_bf16 v[98:101], v[30:33], v[114:117], v[98:101]
	s_nop 0
	s_nop 0
	s_waitcnt lgkmcnt(7)
	v_mfma_f32_16x16x32_bf16 v[98:101], v[2:5], v[206:209], v[98:101]
	ds_read_b128 v[206:209], v188 offset:4736
	s_nop 0
	s_nop 0
	s_nop 0
	s_waitcnt vmcnt(20) lgkmcnt(6)
	v_mfma_f32_16x16x32_bf16 v[114:117], v[6:9], v[210:213], v[98:101]
	ds_read_b128 v[210:213], v188 offset:4800
	s_nop 2
	s_nop 0
	s_waitcnt lgkmcnt(6)
	v_mfma_f32_16x16x32_bf16 v[118:121], v[126:129], v[118:121], 0
	s_waitcnt lgkmcnt(4)
	v_mfma_f32_16x16x32_bf16 v[118:121], v[214:217], v[122:125], v[118:121]
	s_nop 0
	s_waitcnt lgkmcnt(3)
	v_mfma_f32_16x16x32_bf16 v[46:49], v[46:49], v[218:221], 0
	ds_read_b128 v[218:221], v186 offset:64256
	s_nop 0
	s_waitcnt lgkmcnt(3)
	v_mfma_f32_16x16x32_bf16 v[30:33], v[30:33], v[222:225], v[46:49]
	ds_read_b128 v[222:225], v186 offset:64320
	s_nop 4
	s_nop 0
	s_waitcnt lgkmcnt(3)
	v_mfma_f32_16x16x32_bf16 v[2:5], v[2:5], v[206:209], v[30:33]
	ds_read_b128 v[206:209], v183
	s_nop 2
	s_nop 0
	v_mov_b32_e32 v46, s0
	ds_read_b32 v138, v46
	s_waitcnt lgkmcnt(4)
	v_mfma_f32_16x16x32_bf16 v[122:125], v[6:9], v[210:213], v[2:5]
	ds_read_b128 v[210:213], v184
	ds_read_b128 v[134:137], v183 offset:64
	s_nop 2
	s_nop 0
	s_nop 0
	s_nop 0
	s_nop 0
	s_nop 0
	s_nop 0
	s_waitcnt lgkmcnt(5)
	v_mfma_f32_16x16x32_bf16 v[2:5], v[126:129], v[218:221], 0
	ds_read_b128 v[218:221], v184 offset:2560
	s_waitcnt lgkmcnt(5)
	v_mfma_f32_16x16x32_bf16 v[126:129], v[214:217], v[222:225], v[2:5]
	ds_read_b128 v[98:101], v184 offset:5120
	ds_read_b128 v[214:217], v184 offset:7680
	ds_read_b128 v[222:225], v182
	s_nop 0
	s_nop 0
	s_waitcnt lgkmcnt(6)
	s_nop 2
	v_pk_mul_f32 v[4:5], v[112:113], v[138:139] op_sel_hi:[1,0]
	v_pk_mul_f32 v[2:3], v[110:111], v[138:139] op_sel_hi:[1,0]
	s_waitcnt lgkmcnt(5)
	s_nop 0
	v_mfma_f32_16x16x32_bf16 v[2:5], v[206:209], v[210:213], v[2:5]
	v_mul_f32_e64 v48, v108, v138
	v_mul_f32_e64 v49, v109, v138
	v_pk_mul_f32 v[46:47], v[106:107], v[138:139] op_sel_hi:[1,0]
	ds_read_b128 v[210:213], v182 offset:2560
	s_waitcnt lgkmcnt(4)
	s_nop 0
	v_mfma_f32_16x16x32_bf16 v[6:9], v[206:209], v[218:221], v[46:49]
	ds_read_b128 v[218:221], v182 offset:5120
	s_nop 2
	v_mul_f32_e64 v48, v104, v138
	v_mul_f32_e64 v49, v105, v138
	v_pk_mul_f32 v[46:47], v[102:103], v[138:139] op_sel_hi:[1,0]
	s_nop 0
	s_waitcnt lgkmcnt(4)
	v_mfma_f32_16x16x32_bf16 v[46:49], v[206:209], v[98:101], v[46:49]
	v_mul_f32_e64 v100, v132, v138
	v_mul_f32_e64 v101, v133, v138
	v_pk_mul_f32 v[98:99], v[130:131], v[138:139] op_sel_hi:[1,0]
	s_waitcnt lgkmcnt(3)
	s_nop 0
	v_mfma_f32_16x16x32_bf16 v[30:33], v[206:209], v[214:217], v[98:101]
	ds_read_b128 v[206:209], v182 offset:7680
	ds_read_b128 v[110:113], v181
	s_nop 2
	s_nop 0
	s_waitcnt lgkmcnt(4)
	v_mfma_f32_16x16x32_bf16 v[106:109], v[134:137], v[222:225], v[2:5]
	s_nop 2
	s_nop 0
	s_waitcnt lgkmcnt(3)
	v_mfma_f32_16x16x32_bf16 v[102:105], v[134:137], v[210:213], v[6:9]
	s_nop 0
	s_waitcnt lgkmcnt(2)
	v_mfma_f32_16x16x32_bf16 v[98:101], v[134:137], v[218:221], v[46:49]
	s_nop 0
	s_nop 0
	s_waitcnt lgkmcnt(1)
	v_mfma_f32_16x16x32_bf16 v[130:133], v[134:137], v[206:209], v[30:33]
	v_cvt_pk_bf16_f32 v2, v106, v107
	v_cvt_pk_bf16_f32 v3, v108, v109
	v_cvt_pk_bf16_f32 v4, v102, v103
	v_cvt_pk_bf16_f32 v5, v104, v105
	ds_write2st64_b64 v187, v[2:3], v[4:5] offset1:9
	v_cvt_pk_bf16_f32 v2, v98, v99
	v_cvt_pk_bf16_f32 v3, v100, v101
	s_nop 0
	v_cvt_pk_bf16_f32 v4, v130, v131
	v_cvt_pk_bf16_f32 v5, v132, v133
	ds_write2st64_b64 v187, v[2:3], v[4:5] offset0:18 offset1:27
	s_waitcnt vmcnt(19)
	ds_write_b128 v171, v[54:57]
	s_waitcnt vmcnt(18)
	ds_write_b128 v171, v[58:61] offset:10240
	s_waitcnt vmcnt(17)
	ds_write_b128 v171, v[78:81] offset:20480
	s_waitcnt vmcnt(16)
	ds_write_b128 v171, v[82:85] offset:30720
	s_waitcnt vmcnt(15)
	ds_write_b128 v178, v[90:93] offset:30720
	s_and_saveexec_b64 s[8:9], vcc
	s_cbranch_execz .LBB0_1571
	s_waitcnt vmcnt(14)
	ds_write_b128 v177, v[86:89] offset:51200
.LBB0_1571:
	s_or_b64 exec, exec, s[8:9]
	s_or_b32 s7, s34, 14
	s_lshl_b32 s0, s7, 5
	s_or_b32 s8, s0, s78
	s_lshl_b32 s0, s8, 13
	s_mov_b32 s1, s61
	v_lshl_add_u64 v[2:3], v[168:169], 0, s[0:1]
	v_lshl_add_u64 v[4:5], v[166:167], 0, s[0:1]
	global_load_dwordx4 v[54:57], v[2:3], off
	global_load_dwordx4 v[58:61], v[4:5], off
	v_lshl_add_u64 v[2:3], v[164:165], 0, s[0:1]
	s_lshl_b32 s0, s7, 16
	s_or_b32 s0, s0, s5
	s_add_u32 s0, s77, s0
	s_addc_u32 s1, s28, 0
	v_lshl_add_u64 v[4:5], s[0:1], 0, v[156:157]
	global_load_dwordx4 v[78:81], v[2:3], off
	global_load_dwordx4 v[82:85], v[4:5], off
	v_lshl_add_u64 v[2:3], s[0:1], 0, v[158:159]
	s_lshl_b32 s0, s8, 8
	s_mov_b32 s1, s61
	v_lshl_add_u64 v[4:5], v[162:163], 0, s[0:1]
	s_or_b32 s48, s6, 0x380
	s_mov_b32 s49, s61
	global_load_dwordx4 v[90:93], v[2:3], off
	global_load_dwordx4 v[86:89], v[4:5], off
	v_lshl_add_u64 v[2:3], v[160:161], 0, s[48:49]
	v_mov_b64_e32 v[4:5], s[80:81]
	v_mad_u64_u32 v[4:5], s[0:1], v2, s19, v[4:5]
	v_mad_i32_i24 v5, v3, s19, v5
	v_lshl_add_u64 v[2:3], v[4:5], 0, s[60:61]
	v_lshl_add_u64 v[2:3], v[2:3], 0, v[196:197]
	s_waitcnt lgkmcnt(7)
	v_pk_fma_f32 v[122:123], v[110:111], v[122:123], v[126:127]
	v_pk_fma_f32 v[110:111], v[110:111], v[114:115], v[118:119]
	v_add_co_u32_e64 v8, s[44:45], s14, v2
	v_lshl_add_u64 v[114:115], v[152:153], 0, s[52:53]
	v_cvt_pk_bf16_f32 v110, v110, v110
	v_lshl_add_u64 v[6:7], v[2:3], 0, s[20:21]
	v_addc_co_u32_e64 v9, s[44:45], 0, v3, s[44:45]
	v_pk_fma_f32 v[124:125], v[112:113], v[124:125], v[128:129]
	v_pk_fma_f32 v[112:113], v[112:113], v[116:117], v[120:121]
	v_lshlrev_b64 v[114:115], 12, v[114:115]
	v_and_b32_e32 v110, 0xffff, v110
	global_load_dwordx4 v[30:33], v[6:7], off offset:64
	global_load_dwordx4 v[2:5], v[6:7], off offset:128
	global_load_dwordx4 v[46:49], v[8:9], off offset:1024
	s_nop 0
	global_load_dwordx4 v[6:9], v[6:7], off offset:192
	v_lshl_add_u64 v[114:115], v[154:155], 0, v[114:115]
	global_store_short v[114:115], v110, off
	v_cvt_pk_bf16_f32 v110, v111, v111
	v_cvt_pk_bf16_f32 v112, v112, v112
	v_lshl_add_u64 v[116:117], v[114:115], 0, s[86:87]
	v_and_b32_e32 v110, 0xffff, v110
	global_store_short v[116:117], v110, off
	v_and_b32_e32 v112, 0xffff, v112
	v_lshl_add_u64 v[110:111], v[114:115], 0, s[74:75]
	global_store_short v[110:111], v112, off
	v_cvt_pk_bf16_f32 v112, v113, v113
	v_and_b32_e32 v112, 0xffff, v112
	v_lshl_add_u64 v[110:111], v[114:115], 0, s[66:67]
	global_store_short v[110:111], v112, off
	v_cvt_pk_bf16_f32 v112, v122, v122
	v_and_b32_e32 v112, 0xffff, v112
	v_lshl_add_u64 v[110:111], v[114:115], 0, 32
	global_store_short v[110:111], v112, off
	v_cvt_pk_bf16_f32 v112, v123, v123
	v_and_b32_e32 v112, 0xffff, v112
	v_lshl_add_u64 v[110:111], v[114:115], 0, s[22:23]
	global_store_short v[110:111], v112, off
	v_cvt_pk_bf16_f32 v112, v124, v124
	v_and_b32_e32 v112, 0xffff, v112
	v_lshl_add_u64 v[110:111], v[114:115], 0, s[12:13]
	global_store_short v[110:111], v112, off
	v_cvt_pk_bf16_f32 v112, v125, v125
	v_lshl_add_u64 v[110:111], v[114:115], 0, s[56:57]
	v_and_b32_e32 v112, 0xffff, v112
	global_store_short v[110:111], v112, off
	s_waitcnt lgkmcnt(0)
	s_barrier
	ds_read_b128 v[110:113], v189
	ds_read_b128 v[114:117], v189 offset:64
	ds_read_b128 v[206:209], v189 offset:128
	ds_read_b128 v[122:125], v150
	ds_read_b128 v[210:213], v189 offset:192
	ds_read_b128 v[118:121], v186 offset:10240
	ds_read_b128 v[126:129], v150 offset:64
	ds_read_b128 v[214:217], v186 offset:10304
	ds_read_b128 v[218:221], v189 offset:4608
	ds_read_b128 v[222:225], v189 offset:4672
	s_waitcnt vmcnt(21) lgkmcnt(9)
	v_mfma_f32_16x16x32_bf16 v[110:113], v[38:41], v[110:113], 0
	s_waitcnt lgkmcnt(8)
	v_mfma_f32_16x16x32_bf16 v[110:113], v[34:37], v[114:117], v[110:113]
	s_nop 0
	s_nop 0
	s_waitcnt lgkmcnt(7)
	v_mfma_f32_16x16x32_bf16 v[110:113], v[10:13], v[206:209], v[110:113]
	ds_read_b128 v[206:209], v189 offset:4736
	s_nop 0
	s_nop 0
	s_nop 0
	s_waitcnt vmcnt(20) lgkmcnt(6)
	v_mfma_f32_16x16x32_bf16 v[110:113], v[14:17], v[210:213], v[110:113]
	ds_read_b128 v[210:213], v189 offset:4800
	s_waitcnt lgkmcnt(6)
	v_mfma_f32_16x16x32_bf16 v[114:117], v[122:125], v[118:121], 0
	s_nop 0
	s_waitcnt lgkmcnt(4)
	v_mfma_f32_16x16x32_bf16 v[114:117], v[126:129], v[214:217], v[114:117]
	ds_read_b128 v[214:217], v186 offset:12800
	s_nop 0
	s_waitcnt lgkmcnt(4)
	v_mfma_f32_16x16x32_bf16 v[38:41], v[38:41], v[218:221], 0
	ds_read_b128 v[218:221], v186 offset:12864
	s_nop 0
	s_waitcnt lgkmcnt(4)
	v_mfma_f32_16x16x32_bf16 v[34:37], v[34:37], v[222:225], v[38:41]
	ds_read_b128 v[222:225], v180 offset:30720
	ds_read_b32 v134, v197 offset:51452
	s_nop 4
	s_nop 0
	s_waitcnt lgkmcnt(5)
	v_mfma_f32_16x16x32_bf16 v[10:13], v[10:13], v[206:209], v[34:37]
	ds_read_b128 v[38:41], v179 offset:20480
	ds_read_b128 v[206:209], v179 offset:23040
	s_nop 2
	s_nop 0
	s_waitcnt lgkmcnt(6)
	v_mfma_f32_16x16x32_bf16 v[118:121], v[14:17], v[210:213], v[10:13]
	ds_read_b128 v[210:213], v180 offset:30784
	s_nop 2
	s_nop 0
	s_nop 0
	s_nop 0
	s_nop 0
	s_nop 0
	s_waitcnt lgkmcnt(6)
	v_mfma_f32_16x16x32_bf16 v[10:13], v[122:125], v[214:217], 0
	ds_read_b128 v[214:217], v179 offset:25600
	s_waitcnt lgkmcnt(6)
	v_mfma_f32_16x16x32_bf16 v[122:125], v[126:129], v[218:221], v[10:13]
	ds_read_b128 v[218:221], v179 offset:28160
	s_nop 0
	s_nop 0
	s_waitcnt lgkmcnt(5)
	s_nop 2
	v_pk_mul_f32 v[12:13], v[108:109], v[134:135] op_sel_hi:[1,0]
	v_pk_mul_f32 v[10:11], v[106:107], v[134:135] op_sel_hi:[1,0]
	s_waitcnt lgkmcnt(4)
	s_nop 0
	v_mfma_f32_16x16x32_bf16 v[10:13], v[222:225], v[38:41], v[10:13]
	v_mul_f32_e64 v40, v104, v134
	v_mul_f32_e64 v41, v105, v134
	v_pk_mul_f32 v[38:39], v[102:103], v[134:135] op_sel_hi:[1,0]
	s_nop 0
	s_waitcnt lgkmcnt(3)
	v_mfma_f32_16x16x32_bf16 v[14:17], v[222:225], v[206:209], v[38:41]
	ds_read_b128 v[206:209], v179 offset:20544
	s_nop 2
	v_mul_f32_e64 v40, v100, v134
	v_mul_f32_e64 v41, v101, v134
	v_pk_mul_f32 v[38:39], v[98:99], v[134:135] op_sel_hi:[1,0]
	s_nop 0
	s_waitcnt lgkmcnt(2)
	v_mfma_f32_16x16x32_bf16 v[38:41], v[222:225], v[214:217], v[38:41]
	v_mul_f32_e64 v104, v132, v134
	v_mul_f32_e64 v105, v133, v134
	v_pk_mul_f32 v[102:103], v[130:131], v[134:135] op_sel_hi:[1,0]
	ds_read_b128 v[214:217], v179 offset:23104
	s_waitcnt lgkmcnt(2)
	s_nop 0
	v_mfma_f32_16x16x32_bf16 v[34:37], v[222:225], v[218:221], v[102:105]
	ds_read_b128 v[218:221], v179 offset:25664
	ds_read_b128 v[222:225], v179 offset:28224
	ds_read_b128 v[130:133], v176 offset:51200
	s_nop 0
	s_waitcnt lgkmcnt(4)
	v_mfma_f32_16x16x32_bf16 v[106:109], v[210:213], v[206:209], v[10:13]
	s_nop 2
	s_nop 0
	s_waitcnt lgkmcnt(3)
	v_mfma_f32_16x16x32_bf16 v[102:105], v[210:213], v[214:217], v[14:17]
	s_nop 0
	s_waitcnt lgkmcnt(2)
	v_mfma_f32_16x16x32_bf16 v[98:101], v[210:213], v[218:221], v[38:41]
	s_nop 0
	s_nop 0
	s_waitcnt lgkmcnt(1)
	v_mfma_f32_16x16x32_bf16 v[126:129], v[210:213], v[222:225], v[34:37]
	v_cvt_pk_bf16_f32 v10, v106, v107
	v_cvt_pk_bf16_f32 v11, v108, v109
	v_cvt_pk_bf16_f32 v12, v102, v103
	v_cvt_pk_bf16_f32 v13, v104, v105
	ds_write2st64_b64 v174, v[10:11], v[12:13] offset1:9
	v_cvt_pk_bf16_f32 v10, v98, v99
	v_cvt_pk_bf16_f32 v11, v100, v101
	s_nop 0
	v_cvt_pk_bf16_f32 v12, v126, v127
	v_cvt_pk_bf16_f32 v13, v128, v129
	ds_write2st64_b64 v174, v[10:11], v[12:13] offset0:18 offset1:27
	s_waitcnt vmcnt(19)
	ds_write_b128 v171, v[50:53] offset:51456
	s_waitcnt vmcnt(18)
	ds_write_b128 v171, v[62:65] offset:61696
	s_waitcnt vmcnt(17)
	ds_write_b128 v172, v[66:69]
	s_waitcnt vmcnt(16)
	ds_write_b128 v173, v[70:73]
	s_waitcnt vmcnt(15)
	ds_write_b128 v175, v[94:97]
	s_and_saveexec_b64 s[8:9], vcc
	s_cbranch_execz .LBB0_1573
	s_waitcnt vmcnt(14)
	ds_write_b128 v185, v[74:77]
.LBB0_1573:
	s_or_b64 exec, exec, s[8:9]
	s_or_b32 s7, s34, 15
	s_lshl_b32 s0, s7, 5
	s_or_b32 s8, s0, s78
	s_lshl_b32 s0, s8, 13
	s_mov_b32 s1, s61
	v_lshl_add_u64 v[10:11], v[168:169], 0, s[0:1]
	v_lshl_add_u64 v[12:13], v[166:167], 0, s[0:1]
	global_load_dwordx4 v[50:53], v[10:11], off
	global_load_dwordx4 v[62:65], v[12:13], off
	v_lshl_add_u64 v[10:11], v[164:165], 0, s[0:1]
	s_lshl_b32 s0, s7, 16
	s_or_b32 s0, s0, s5
	s_add_u32 s0, s77, s0
	s_addc_u32 s1, s28, 0
	v_lshl_add_u64 v[12:13], s[0:1], 0, v[156:157]
	global_load_dwordx4 v[66:69], v[10:11], off
	global_load_dwordx4 v[70:73], v[12:13], off
	v_lshl_add_u64 v[10:11], s[0:1], 0, v[158:159]
	s_lshl_b32 s0, s8, 8
	s_mov_b32 s1, s61
	v_lshl_add_u64 v[12:13], v[162:163], 0, s[0:1]
	s_or_b32 s52, s6, 0x3c0
	s_mov_b32 s53, s61
	global_load_dwordx4 v[94:97], v[10:11], off
	global_load_dwordx4 v[74:77], v[12:13], off
	v_lshl_add_u64 v[10:11], v[160:161], 0, s[52:53]
	v_mov_b64_e32 v[12:13], s[80:81]
	v_mad_u64_u32 v[12:13], s[0:1], v10, s19, v[12:13]
	v_mad_i32_i24 v13, v11, s19, v13
	v_lshl_add_u64 v[10:11], v[12:13], 0, s[60:61]
	v_lshl_add_u64 v[10:11], v[10:11], 0, v[196:197]
	s_waitcnt lgkmcnt(7)
	v_pk_fma_f32 v[110:111], v[130:131], v[110:111], v[114:115]
	v_add_co_u32_e64 v16, s[44:45], s14, v10
	v_lshl_add_u64 v[114:115], v[152:153], 0, s[46:47]
	v_cvt_pk_bf16_f32 v110, v110, v110
	v_lshl_add_u64 v[14:15], v[10:11], 0, s[20:21]
	v_addc_co_u32_e64 v17, s[44:45], 0, v11, s[44:45]
	v_pk_fma_f32 v[112:113], v[132:133], v[112:113], v[116:117]
	v_lshlrev_b64 v[114:115], 12, v[114:115]
	v_and_b32_e32 v110, 0xffff, v110
	global_load_dwordx4 v[34:37], v[14:15], off offset:64
	global_load_dwordx4 v[10:13], v[14:15], off offset:128
	global_load_dwordx4 v[38:41], v[16:17], off offset:1024
	s_nop 0
	global_load_dwordx4 v[14:17], v[14:15], off offset:192
	v_lshl_add_u64 v[114:115], v[154:155], 0, v[114:115]
	global_store_short v[114:115], v110, off
	v_cvt_pk_bf16_f32 v110, v111, v111
	v_cvt_pk_bf16_f32 v112, v112, v112
	v_lshl_add_u64 v[116:117], v[114:115], 0, s[86:87]
	v_and_b32_e32 v110, 0xffff, v110
	global_store_short v[116:117], v110, off
	v_and_b32_e32 v112, 0xffff, v112
	v_lshl_add_u64 v[110:111], v[114:115], 0, s[74:75]
	global_store_short v[110:111], v112, off
	v_cvt_pk_bf16_f32 v112, v113, v113
	v_pk_fma_f32 v[118:119], v[130:131], v[118:119], v[122:123]
	v_and_b32_e32 v112, 0xffff, v112
	v_lshl_add_u64 v[110:111], v[114:115], 0, s[66:67]
	global_store_short v[110:111], v112, off
	v_cvt_pk_bf16_f32 v112, v118, v118
	v_and_b32_e32 v112, 0xffff, v112
	v_lshl_add_u64 v[110:111], v[114:115], 0, 32
	global_store_short v[110:111], v112, off
	v_cvt_pk_bf16_f32 v112, v119, v119
	v_pk_fma_f32 v[120:121], v[132:133], v[120:121], v[124:125]
	v_and_b32_e32 v112, 0xffff, v112
	v_lshl_add_u64 v[110:111], v[114:115], 0, s[22:23]
	global_store_short v[110:111], v112, off
	v_cvt_pk_bf16_f32 v112, v120, v120
	v_and_b32_e32 v112, 0xffff, v112
	v_lshl_add_u64 v[110:111], v[114:115], 0, s[12:13]
	global_store_short v[110:111], v112, off
	v_cvt_pk_bf16_f32 v112, v121, v121
	v_lshl_add_u64 v[110:111], v[114:115], 0, s[56:57]
	v_and_b32_e32 v112, 0xffff, v112
	global_store_short v[110:111], v112, off
	s_waitcnt lgkmcnt(0)
	s_barrier
	ds_read_b128 v[110:113], v188
	ds_read_b128 v[114:117], v188 offset:64
	ds_read_b128 v[206:209], v188 offset:128
	ds_read_b128 v[122:125], v150 offset:51456
	ds_read_b128 v[210:213], v188 offset:192
	ds_read_b128 v[118:121], v186 offset:61696
	ds_read_b128 v[130:133], v150 offset:51520
	ds_read_b128 v[214:217], v186 offset:61760
	ds_read_b128 v[218:221], v188 offset:4608
	ds_read_b128 v[222:225], v188 offset:4672
	s_waitcnt vmcnt(21) lgkmcnt(9)
	v_mfma_f32_16x16x32_bf16 v[110:113], v[42:45], v[110:113], 0
	v_readlane_b32 s0, v253, 18
	s_waitcnt lgkmcnt(8)
	v_mfma_f32_16x16x32_bf16 v[110:113], v[26:29], v[114:117], v[110:113]
	s_nop 0
	s_nop 0
	s_waitcnt lgkmcnt(7)
	v_mfma_f32_16x16x32_bf16 v[110:113], v[18:21], v[206:209], v[110:113]
	ds_read_b128 v[206:209], v188 offset:4736
	s_nop 0
	s_nop 0
	s_nop 0
	s_waitcnt vmcnt(20) lgkmcnt(6)
	v_mfma_f32_16x16x32_bf16 v[110:113], v[22:25], v[210:213], v[110:113]
	ds_read_b128 v[210:213], v188 offset:4800
	s_waitcnt lgkmcnt(6)
	v_mfma_f32_16x16x32_bf16 v[114:117], v[122:125], v[118:121], 0
	s_nop 0
	s_waitcnt lgkmcnt(4)
	v_mfma_f32_16x16x32_bf16 v[114:117], v[130:133], v[214:217], v[114:117]
	ds_read_b128 v[214:217], v186 offset:64256
	s_nop 0
	s_waitcnt lgkmcnt(4)
	v_mfma_f32_16x16x32_bf16 v[42:45], v[42:45], v[218:221], 0
	ds_read_b128 v[218:221], v186 offset:64320
	s_nop 0
	s_waitcnt lgkmcnt(4)
	v_mfma_f32_16x16x32_bf16 v[26:29], v[26:29], v[222:225], v[42:45]
	ds_read_b128 v[222:225], v183
	s_nop 4
	s_nop 0
	s_waitcnt lgkmcnt(4)
	v_mfma_f32_16x16x32_bf16 v[18:21], v[18:21], v[206:209], v[26:29]
	s_nop 2
	s_nop 0
	v_mov_b32_e32 v42, s0
	ds_read_b32 v138, v42
	ds_read_b128 v[206:209], v184
	ds_read_b128 v[134:137], v183 offset:64
	s_waitcnt lgkmcnt(6)
	v_mfma_f32_16x16x32_bf16 v[118:121], v[22:25], v[210:213], v[18:21]
	ds_read_b128 v[210:213], v184 offset:2560
	s_nop 2
	s_nop 0
	s_nop 0
	s_nop 0
	s_nop 0
	s_nop 0
	s_nop 0
	s_waitcnt lgkmcnt(6)
	v_mfma_f32_16x16x32_bf16 v[18:21], v[122:125], v[214:217], 0
	ds_read_b128 v[214:217], v184 offset:5120
	s_waitcnt lgkmcnt(6)
	v_mfma_f32_16x16x32_bf16 v[122:125], v[130:133], v[218:221], v[18:21]
	ds_read_b128 v[218:221], v184 offset:7680
	s_nop 0
	s_waitcnt lgkmcnt(5)
	s_nop 3
	v_pk_mul_f32 v[20:21], v[108:109], v[138:139] op_sel_hi:[1,0]
	v_pk_mul_f32 v[18:19], v[106:107], v[138:139] op_sel_hi:[1,0]
	s_waitcnt lgkmcnt(4)
	s_nop 0
	v_mfma_f32_16x16x32_bf16 v[18:21], v[222:225], v[206:209], v[18:21]
	v_mul_f32_e64 v44, v104, v138
	v_mul_f32_e64 v45, v105, v138
	v_pk_mul_f32 v[42:43], v[102:103], v[138:139] op_sel_hi:[1,0]
	ds_read_b128 v[206:209], v182
	s_nop 0
	s_waitcnt lgkmcnt(3)
	v_mfma_f32_16x16x32_bf16 v[22:25], v[222:225], v[210:213], v[42:45]
	ds_read_b128 v[210:213], v182 offset:2560
	s_nop 2
	v_mul_f32_e64 v44, v100, v138
	v_mul_f32_e64 v45, v101, v138
	v_pk_mul_f32 v[42:43], v[98:99], v[138:139] op_sel_hi:[1,0]
	s_nop 0
	s_waitcnt lgkmcnt(3)
	v_mfma_f32_16x16x32_bf16 v[42:45], v[222:225], v[214:217], v[42:45]
	v_mul_f32_e64 v104, v128, v138
	v_mul_f32_e64 v105, v129, v138
	v_pk_mul_f32 v[102:103], v[126:127], v[138:139] op_sel_hi:[1,0]
	ds_read_b128 v[214:217], v182 offset:5120
	s_waitcnt lgkmcnt(3)
	s_nop 0
	v_mfma_f32_16x16x32_bf16 v[26:29], v[222:225], v[218:221], v[102:105]
	ds_read_b128 v[218:221], v182 offset:7680
	ds_read_b128 v[130:133], v181
	s_nop 0
	s_waitcnt lgkmcnt(4)
	v_mfma_f32_16x16x32_bf16 v[106:109], v[134:137], v[206:209], v[18:21]
	s_nop 2
	s_nop 0
	s_waitcnt lgkmcnt(3)
	v_mfma_f32_16x16x32_bf16 v[102:105], v[134:137], v[210:213], v[22:25]
	s_nop 0
	s_waitcnt lgkmcnt(2)
	v_mfma_f32_16x16x32_bf16 v[98:101], v[134:137], v[214:217], v[42:45]
	s_nop 0
	s_nop 0
	s_waitcnt lgkmcnt(1)
	v_mfma_f32_16x16x32_bf16 v[126:129], v[134:137], v[218:221], v[26:29]
	v_cvt_pk_bf16_f32 v18, v106, v107
	v_cvt_pk_bf16_f32 v19, v108, v109
	v_cvt_pk_bf16_f32 v20, v102, v103
	v_cvt_pk_bf16_f32 v21, v104, v105
	ds_write2st64_b64 v187, v[18:19], v[20:21] offset1:9
	v_cvt_pk_bf16_f32 v18, v98, v99
	v_cvt_pk_bf16_f32 v19, v100, v101
	s_nop 0
	v_cvt_pk_bf16_f32 v20, v126, v127
	v_cvt_pk_bf16_f32 v21, v128, v129
	ds_write2st64_b64 v187, v[18:19], v[20:21] offset0:18 offset1:27
	s_waitcnt vmcnt(19)
	ds_write_b128 v171, v[54:57]
	s_waitcnt vmcnt(18)
	ds_write_b128 v171, v[58:61] offset:10240
	s_waitcnt vmcnt(17)
	ds_write_b128 v171, v[78:81] offset:20480
	s_waitcnt vmcnt(16)
	ds_write_b128 v171, v[82:85] offset:30720
	s_waitcnt vmcnt(15)
	ds_write_b128 v178, v[90:93] offset:30720
	s_and_saveexec_b64 s[8:9], vcc
	s_cbranch_execz .LBB0_1575
	s_waitcnt vmcnt(14)
	ds_write_b128 v177, v[86:89] offset:51200
.LBB0_1575:
	s_or_b64 exec, exec, s[8:9]
	s_or_b32 s7, s34, 16
	s_lshl_b32 s0, s7, 5
	s_or_b32 s8, s0, s78
	s_lshl_b32 s0, s8, 13
	s_mov_b32 s1, s61
	v_lshl_add_u64 v[18:19], v[168:169], 0, s[0:1]
	v_lshl_add_u64 v[20:21], v[166:167], 0, s[0:1]
	global_load_dwordx4 v[54:57], v[18:19], off
	global_load_dwordx4 v[58:61], v[20:21], off
	v_lshl_add_u64 v[18:19], v[164:165], 0, s[0:1]
	s_lshl_b32 s0, s7, 16
	s_or_b32 s0, s0, s5
	s_add_u32 s0, s77, s0
	s_addc_u32 s1, s28, 0
	v_lshl_add_u64 v[20:21], s[0:1], 0, v[156:157]
	global_load_dwordx4 v[78:81], v[18:19], off
	global_load_dwordx4 v[82:85], v[20:21], off
	v_lshl_add_u64 v[18:19], s[0:1], 0, v[158:159]
	s_lshl_b32 s0, s8, 8
	s_mov_b32 s1, s61
	v_lshl_add_u64 v[20:21], v[162:163], 0, s[0:1]
	s_or_b32 s46, s6, 0x400
	s_mov_b32 s47, s61
	global_load_dwordx4 v[90:93], v[18:19], off
	global_load_dwordx4 v[86:89], v[20:21], off
	v_lshl_add_u64 v[18:19], v[160:161], 0, s[46:47]
	v_mov_b64_e32 v[20:21], s[80:81]
	v_mad_u64_u32 v[20:21], s[0:1], v18, s19, v[20:21]
	v_mad_i32_i24 v21, v19, s19, v21
	v_lshl_add_u64 v[18:19], v[20:21], 0, s[60:61]
	v_lshl_add_u64 v[18:19], v[18:19], 0, v[196:197]
	s_waitcnt lgkmcnt(7)
	v_pk_fma_f32 v[110:111], v[130:131], v[110:111], v[114:115]
	v_add_co_u32_e64 v24, s[44:45], s14, v18
	v_lshl_add_u64 v[114:115], v[152:153], 0, s[50:51]
	v_cvt_pk_bf16_f32 v110, v110, v110
	v_lshl_add_u64 v[22:23], v[18:19], 0, s[20:21]
	v_addc_co_u32_e64 v25, s[44:45], 0, v19, s[44:45]
	v_pk_fma_f32 v[112:113], v[132:133], v[112:113], v[116:117]
	v_lshlrev_b64 v[114:115], 12, v[114:115]
	v_and_b32_e32 v110, 0xffff, v110
	global_load_dwordx4 v[26:29], v[22:23], off offset:64
	global_load_dwordx4 v[18:21], v[22:23], off offset:128
	global_load_dwordx4 v[42:45], v[24:25], off offset:1024
	s_nop 0
	global_load_dwordx4 v[22:25], v[22:23], off offset:192
	v_lshl_add_u64 v[114:115], v[154:155], 0, v[114:115]
	global_store_short v[114:115], v110, off
	v_cvt_pk_bf16_f32 v110, v111, v111
	v_cvt_pk_bf16_f32 v112, v112, v112
	v_lshl_add_u64 v[116:117], v[114:115], 0, s[86:87]
	v_and_b32_e32 v110, 0xffff, v110
	global_store_short v[116:117], v110, off
	v_and_b32_e32 v112, 0xffff, v112
	v_lshl_add_u64 v[110:111], v[114:115], 0, s[74:75]
	global_store_short v[110:111], v112, off
	v_cvt_pk_bf16_f32 v112, v113, v113
	v_pk_fma_f32 v[118:119], v[130:131], v[118:119], v[122:123]
	v_and_b32_e32 v112, 0xffff, v112
	v_lshl_add_u64 v[110:111], v[114:115], 0, s[66:67]
	global_store_short v[110:111], v112, off
	v_cvt_pk_bf16_f32 v112, v118, v118
	v_and_b32_e32 v112, 0xffff, v112
	v_lshl_add_u64 v[110:111], v[114:115], 0, 32
	global_store_short v[110:111], v112, off
	v_cvt_pk_bf16_f32 v112, v119, v119
	v_pk_fma_f32 v[120:121], v[132:133], v[120:121], v[124:125]
	v_and_b32_e32 v112, 0xffff, v112
	v_lshl_add_u64 v[110:111], v[114:115], 0, s[22:23]
	global_store_short v[110:111], v112, off
	v_cvt_pk_bf16_f32 v112, v120, v120
	v_and_b32_e32 v112, 0xffff, v112
	v_lshl_add_u64 v[110:111], v[114:115], 0, s[12:13]
	global_store_short v[110:111], v112, off
	v_cvt_pk_bf16_f32 v112, v121, v121
	v_lshl_add_u64 v[110:111], v[114:115], 0, s[56:57]
	v_and_b32_e32 v112, 0xffff, v112
	global_store_short v[110:111], v112, off
	s_waitcnt lgkmcnt(0)
	s_barrier
	ds_read_b128 v[110:113], v189
	ds_read_b128 v[114:117], v189 offset:64
	ds_read_b128 v[206:209], v189 offset:128
	ds_read_b128 v[122:125], v150
	ds_read_b128 v[210:213], v189 offset:192
	ds_read_b128 v[118:121], v186 offset:10240
	ds_read_b128 v[130:133], v150 offset:64
	ds_read_b128 v[214:217], v186 offset:10304
	ds_read_b128 v[218:221], v189 offset:4608
	ds_read_b128 v[222:225], v189 offset:4672
	s_waitcnt vmcnt(21) lgkmcnt(9)
	v_mfma_f32_16x16x32_bf16 v[110:113], v[46:49], v[110:113], 0
	s_waitcnt lgkmcnt(8)
	v_mfma_f32_16x16x32_bf16 v[110:113], v[30:33], v[114:117], v[110:113]
	s_nop 0
	s_nop 0
	s_waitcnt lgkmcnt(7)
	v_mfma_f32_16x16x32_bf16 v[110:113], v[2:5], v[206:209], v[110:113]
	ds_read_b128 v[206:209], v189 offset:4736
	s_nop 0
	s_nop 0
	s_nop 0
	s_waitcnt vmcnt(20) lgkmcnt(6)
	v_mfma_f32_16x16x32_bf16 v[110:113], v[6:9], v[210:213], v[110:113]
	ds_read_b128 v[210:213], v189 offset:4800
	s_waitcnt lgkmcnt(6)
	v_mfma_f32_16x16x32_bf16 v[114:117], v[122:125], v[118:121], 0
	s_nop 0
	s_waitcnt lgkmcnt(4)
	v_mfma_f32_16x16x32_bf16 v[114:117], v[130:133], v[214:217], v[114:117]
	ds_read_b128 v[214:217], v186 offset:12800
	s_nop 0
	s_waitcnt lgkmcnt(4)
	v_mfma_f32_16x16x32_bf16 v[46:49], v[46:49], v[218:221], 0
	ds_read_b128 v[218:221], v186 offset:12864
	s_nop 0
	s_waitcnt lgkmcnt(4)
	v_mfma_f32_16x16x32_bf16 v[30:33], v[30:33], v[222:225], v[46:49]
	ds_read_b128 v[222:225], v180 offset:30720
	ds_read_b32 v138, v197 offset:51452
	s_nop 4
	s_nop 0
	s_waitcnt lgkmcnt(5)
	v_mfma_f32_16x16x32_bf16 v[2:5], v[2:5], v[206:209], v[30:33]
	ds_read_b128 v[46:49], v179 offset:20480
	ds_read_b128 v[134:137], v180 offset:30784
	ds_read_b128 v[206:209], v179 offset:23040
	s_nop 2
	s_nop 0
	s_waitcnt lgkmcnt(7)
	v_mfma_f32_16x16x32_bf16 v[118:121], v[6:9], v[210:213], v[2:5]
	ds_read_b128 v[210:213], v179 offset:25600
	s_nop 2
	s_nop 0
	s_nop 0
	s_nop 0
	s_nop 0
	s_nop 0
	s_nop 0
	s_waitcnt lgkmcnt(7)
	v_mfma_f32_16x16x32_bf16 v[2:5], v[122:125], v[214:217], 0
	ds_read_b128 v[214:217], v179 offset:28160
	s_waitcnt lgkmcnt(7)
	v_mfma_f32_16x16x32_bf16 v[122:125], v[130:133], v[218:221], v[2:5]
	ds_read_b128 v[218:221], v179 offset:20544
	s_nop 0
	s_waitcnt lgkmcnt(6)
	s_nop 3
	v_pk_mul_f32 v[4:5], v[108:109], v[138:139] op_sel_hi:[1,0]
	v_pk_mul_f32 v[2:3], v[106:107], v[138:139] op_sel_hi:[1,0]
	s_waitcnt lgkmcnt(5)
	s_nop 0
	v_mfma_f32_16x16x32_bf16 v[2:5], v[222:225], v[46:49], v[2:5]
	v_mul_f32_e64 v48, v104, v138
	v_mul_f32_e64 v49, v105, v138
	v_pk_mul_f32 v[46:47], v[102:103], v[138:139] op_sel_hi:[1,0]
	s_nop 0
	s_waitcnt lgkmcnt(3)
	v_mfma_f32_16x16x32_bf16 v[6:9], v[222:225], v[206:209], v[46:49]
	ds_read_b128 v[206:209], v179 offset:23104
	s_nop 2
	v_mul_f32_e64 v48, v100, v138
	v_mul_f32_e64 v49, v101, v138
	v_pk_mul_f32 v[46:47], v[98:99], v[138:139] op_sel_hi:[1,0]
	s_nop 0
	s_waitcnt lgkmcnt(3)
	v_mfma_f32_16x16x32_bf16 v[46:49], v[222:225], v[210:213], v[46:49]
	v_mul_f32_e64 v104, v128, v138
	v_mul_f32_e64 v105, v129, v138
	v_pk_mul_f32 v[102:103], v[126:127], v[138:139] op_sel_hi:[1,0]
	ds_read_b128 v[210:213], v179 offset:25664
	s_waitcnt lgkmcnt(3)
	s_nop 0
	v_mfma_f32_16x16x32_bf16 v[30:33], v[222:225], v[214:217], v[102:105]
	ds_read_b128 v[214:217], v179 offset:28224
	ds_read_b128 v[130:133], v176 offset:51200
	s_nop 0
	s_waitcnt lgkmcnt(4)
	v_mfma_f32_16x16x32_bf16 v[106:109], v[134:137], v[218:221], v[2:5]
	s_nop 2
	s_nop 0
	s_waitcnt lgkmcnt(3)
	v_mfma_f32_16x16x32_bf16 v[102:105], v[134:137], v[206:209], v[6:9]
	s_nop 0
	s_waitcnt lgkmcnt(2)
	v_mfma_f32_16x16x32_bf16 v[98:101], v[134:137], v[210:213], v[46:49]
	s_nop 0
	s_nop 0
	s_waitcnt lgkmcnt(1)
	v_mfma_f32_16x16x32_bf16 v[126:129], v[134:137], v[214:217], v[30:33]
	v_cvt_pk_bf16_f32 v2, v106, v107
	v_cvt_pk_bf16_f32 v3, v108, v109
	v_cvt_pk_bf16_f32 v4, v102, v103
	v_cvt_pk_bf16_f32 v5, v104, v105
	ds_write2st64_b64 v174, v[2:3], v[4:5] offset1:9
	v_cvt_pk_bf16_f32 v2, v98, v99
	v_cvt_pk_bf16_f32 v3, v100, v101
	s_nop 0
	v_cvt_pk_bf16_f32 v4, v126, v127
	v_cvt_pk_bf16_f32 v5, v128, v129
	ds_write2st64_b64 v174, v[2:3], v[4:5] offset0:18 offset1:27
	s_waitcnt vmcnt(19)
	ds_write_b128 v171, v[50:53] offset:51456
	s_waitcnt vmcnt(18)
	ds_write_b128 v171, v[62:65] offset:61696
	s_waitcnt vmcnt(17)
	ds_write_b128 v172, v[66:69]
	s_waitcnt vmcnt(16)
	ds_write_b128 v173, v[70:73]
	s_waitcnt vmcnt(15)
	ds_write_b128 v175, v[94:97]
	s_and_saveexec_b64 s[8:9], vcc
	s_cbranch_execz .LBB0_1577
	s_waitcnt vmcnt(14)
	ds_write_b128 v185, v[74:77]
.LBB0_1577:
	s_or_b64 exec, exec, s[8:9]
	s_or_b32 s7, s34, 17
	s_lshl_b32 s0, s7, 5
	s_or_b32 s8, s0, s78
	s_lshl_b32 s0, s8, 13
	s_mov_b32 s1, s61
	v_lshl_add_u64 v[2:3], v[168:169], 0, s[0:1]
	v_lshl_add_u64 v[4:5], v[166:167], 0, s[0:1]
	global_load_dwordx4 v[50:53], v[2:3], off
	global_load_dwordx4 v[62:65], v[4:5], off
	v_lshl_add_u64 v[2:3], v[164:165], 0, s[0:1]
	s_lshl_b32 s0, s7, 16
	s_or_b32 s0, s0, s5
	s_add_u32 s0, s77, s0
	s_addc_u32 s1, s28, 0
	v_lshl_add_u64 v[4:5], s[0:1], 0, v[156:157]
	global_load_dwordx4 v[66:69], v[2:3], off
	global_load_dwordx4 v[70:73], v[4:5], off
	v_lshl_add_u64 v[2:3], s[0:1], 0, v[158:159]
	s_lshl_b32 s0, s8, 8
	s_mov_b32 s1, s61
	v_lshl_add_u64 v[4:5], v[162:163], 0, s[0:1]
	s_or_b32 s50, s6, 0x440
	s_mov_b32 s51, s61
	global_load_dwordx4 v[94:97], v[2:3], off
	global_load_dwordx4 v[74:77], v[4:5], off
	v_lshl_add_u64 v[2:3], v[160:161], 0, s[50:51]
	v_mov_b64_e32 v[4:5], s[80:81]
	v_mad_u64_u32 v[4:5], s[0:1], v2, s19, v[4:5]
	v_mad_i32_i24 v5, v3, s19, v5
	v_lshl_add_u64 v[2:3], v[4:5], 0, s[60:61]
	v_lshl_add_u64 v[2:3], v[2:3], 0, v[196:197]
	s_waitcnt lgkmcnt(7)
	v_pk_fma_f32 v[110:111], v[130:131], v[110:111], v[114:115]
	v_add_co_u32_e64 v8, s[44:45], s14, v2
	v_lshl_add_u64 v[114:115], v[152:153], 0, s[48:49]
	v_cvt_pk_bf16_f32 v110, v110, v110
	v_lshl_add_u64 v[6:7], v[2:3], 0, s[20:21]
	v_addc_co_u32_e64 v9, s[44:45], 0, v3, s[44:45]
	v_pk_fma_f32 v[112:113], v[132:133], v[112:113], v[116:117]
	v_lshlrev_b64 v[114:115], 12, v[114:115]
	v_and_b32_e32 v110, 0xffff, v110
	global_load_dwordx4 v[30:33], v[6:7], off offset:64
	global_load_dwordx4 v[2:5], v[6:7], off offset:128
	global_load_dwordx4 v[46:49], v[8:9], off offset:1024
	s_nop 0
	global_load_dwordx4 v[6:9], v[6:7], off offset:192
	v_lshl_add_u64 v[114:115], v[154:155], 0, v[114:115]
	global_store_short v[114:115], v110, off
	v_cvt_pk_bf16_f32 v110, v111, v111
	v_cvt_pk_bf16_f32 v112, v112, v112
	v_lshl_add_u64 v[116:117], v[114:115], 0, s[86:87]
	v_and_b32_e32 v110, 0xffff, v110
	global_store_short v[116:117], v110, off
	v_and_b32_e32 v112, 0xffff, v112
	v_lshl_add_u64 v[110:111], v[114:115], 0, s[74:75]
	global_store_short v[110:111], v112, off
	v_cvt_pk_bf16_f32 v112, v113, v113
	v_pk_fma_f32 v[118:119], v[130:131], v[118:119], v[122:123]
	v_and_b32_e32 v112, 0xffff, v112
	v_lshl_add_u64 v[110:111], v[114:115], 0, s[66:67]
	global_store_short v[110:111], v112, off
	v_cvt_pk_bf16_f32 v112, v118, v118
	v_and_b32_e32 v112, 0xffff, v112
	v_lshl_add_u64 v[110:111], v[114:115], 0, 32
	global_store_short v[110:111], v112, off
	v_cvt_pk_bf16_f32 v112, v119, v119
	v_pk_fma_f32 v[120:121], v[132:133], v[120:121], v[124:125]
	v_and_b32_e32 v112, 0xffff, v112
	v_lshl_add_u64 v[110:111], v[114:115], 0, s[22:23]
	global_store_short v[110:111], v112, off
	v_cvt_pk_bf16_f32 v112, v120, v120
	v_and_b32_e32 v112, 0xffff, v112
	v_lshl_add_u64 v[110:111], v[114:115], 0, s[12:13]
	global_store_short v[110:111], v112, off
	v_cvt_pk_bf16_f32 v112, v121, v121
	v_lshl_add_u64 v[110:111], v[114:115], 0, s[56:57]
	v_and_b32_e32 v112, 0xffff, v112
	global_store_short v[110:111], v112, off
	s_waitcnt lgkmcnt(0)
	s_barrier
	ds_read_b128 v[110:113], v188
	ds_read_b128 v[114:117], v188 offset:64
	ds_read_b128 v[206:209], v188 offset:128
	ds_read_b128 v[122:125], v150 offset:51456
	ds_read_b128 v[210:213], v188 offset:192
	ds_read_b128 v[118:121], v186 offset:61696
	ds_read_b128 v[130:133], v150 offset:51520
	ds_read_b128 v[214:217], v186 offset:61760
	ds_read_b128 v[218:221], v188 offset:4608
	ds_read_b128 v[222:225], v188 offset:4672
	s_waitcnt vmcnt(21) lgkmcnt(9)
	v_mfma_f32_16x16x32_bf16 v[110:113], v[38:41], v[110:113], 0
	v_readlane_b32 s0, v253, 18
	s_waitcnt lgkmcnt(8)
	v_mfma_f32_16x16x32_bf16 v[110:113], v[34:37], v[114:117], v[110:113]
	s_nop 0
	s_nop 0
	s_waitcnt lgkmcnt(7)
	v_mfma_f32_16x16x32_bf16 v[110:113], v[10:13], v[206:209], v[110:113]
	ds_read_b128 v[206:209], v188 offset:4736
	s_nop 0
	s_nop 0
	s_nop 0
	s_waitcnt vmcnt(20) lgkmcnt(6)
	v_mfma_f32_16x16x32_bf16 v[110:113], v[14:17], v[210:213], v[110:113]
	ds_read_b128 v[210:213], v188 offset:4800
	s_waitcnt lgkmcnt(6)
	v_mfma_f32_16x16x32_bf16 v[114:117], v[122:125], v[118:121], 0
	s_nop 0
	s_waitcnt lgkmcnt(4)
	v_mfma_f32_16x16x32_bf16 v[114:117], v[130:133], v[214:217], v[114:117]
	ds_read_b128 v[214:217], v186 offset:64256
	s_nop 0
	s_waitcnt lgkmcnt(4)
	v_mfma_f32_16x16x32_bf16 v[38:41], v[38:41], v[218:221], 0
	ds_read_b128 v[218:221], v186 offset:64320
	s_nop 0
	s_waitcnt lgkmcnt(4)
	v_mfma_f32_16x16x32_bf16 v[34:37], v[34:37], v[222:225], v[38:41]
	ds_read_b128 v[222:225], v183
	s_nop 4
	s_nop 0
	s_waitcnt lgkmcnt(4)
	v_mfma_f32_16x16x32_bf16 v[10:13], v[10:13], v[206:209], v[34:37]
	s_nop 2
	s_nop 0
	v_mov_b32_e32 v38, s0
	ds_read_b32 v138, v38
	ds_read_b128 v[206:209], v184
	ds_read_b128 v[134:137], v183 offset:64
	s_waitcnt lgkmcnt(6)
	v_mfma_f32_16x16x32_bf16 v[118:121], v[14:17], v[210:213], v[10:13]
	ds_read_b128 v[210:213], v184 offset:2560
	s_nop 2
	s_nop 0
	s_nop 0
	s_nop 0
	s_nop 0
	s_nop 0
	s_nop 0
	s_waitcnt lgkmcnt(6)
	v_mfma_f32_16x16x32_bf16 v[10:13], v[122:125], v[214:217], 0
	ds_read_b128 v[214:217], v184 offset:5120
	s_waitcnt lgkmcnt(6)
	v_mfma_f32_16x16x32_bf16 v[122:125], v[130:133], v[218:221], v[10:13]
	ds_read_b128 v[218:221], v184 offset:7680
	s_nop 0
	s_waitcnt lgkmcnt(5)
	s_nop 3
	v_pk_mul_f32 v[12:13], v[108:109], v[138:139] op_sel_hi:[1,0]
	v_pk_mul_f32 v[10:11], v[106:107], v[138:139] op_sel_hi:[1,0]
	s_waitcnt lgkmcnt(4)
	s_nop 0
	v_mfma_f32_16x16x32_bf16 v[10:13], v[222:225], v[206:209], v[10:13]
	v_mul_f32_e64 v40, v104, v138
	v_mul_f32_e64 v41, v105, v138
	v_pk_mul_f32 v[38:39], v[102:103], v[138:139] op_sel_hi:[1,0]
	ds_read_b128 v[206:209], v182
	s_nop 0
	s_waitcnt lgkmcnt(3)
	v_mfma_f32_16x16x32_bf16 v[14:17], v[222:225], v[210:213], v[38:41]
	ds_read_b128 v[210:213], v182 offset:2560
	s_nop 2
	v_mul_f32_e64 v40, v100, v138
	v_mul_f32_e64 v41, v101, v138
	v_pk_mul_f32 v[38:39], v[98:99], v[138:139] op_sel_hi:[1,0]
	s_nop 0
	s_waitcnt lgkmcnt(3)
	v_mfma_f32_16x16x32_bf16 v[38:41], v[222:225], v[214:217], v[38:41]
	v_mul_f32_e64 v104, v128, v138
	v_mul_f32_e64 v105, v129, v138
	v_pk_mul_f32 v[102:103], v[126:127], v[138:139] op_sel_hi:[1,0]
	ds_read_b128 v[214:217], v182 offset:5120
	s_waitcnt lgkmcnt(3)
	s_nop 0
	v_mfma_f32_16x16x32_bf16 v[34:37], v[222:225], v[218:221], v[102:105]
	ds_read_b128 v[218:221], v182 offset:7680
	ds_read_b128 v[130:133], v181
	s_nop 0
	s_waitcnt lgkmcnt(4)
	v_mfma_f32_16x16x32_bf16 v[106:109], v[134:137], v[206:209], v[10:13]
	s_nop 2
	s_nop 0
	s_waitcnt lgkmcnt(3)
	v_mfma_f32_16x16x32_bf16 v[102:105], v[134:137], v[210:213], v[14:17]
	s_nop 0
	s_waitcnt lgkmcnt(2)
	v_mfma_f32_16x16x32_bf16 v[98:101], v[134:137], v[214:217], v[38:41]
	s_nop 0
	s_nop 0
	s_waitcnt lgkmcnt(1)
	v_mfma_f32_16x16x32_bf16 v[126:129], v[134:137], v[218:221], v[34:37]
	v_cvt_pk_bf16_f32 v10, v106, v107
	v_cvt_pk_bf16_f32 v11, v108, v109
	v_cvt_pk_bf16_f32 v12, v102, v103
	v_cvt_pk_bf16_f32 v13, v104, v105
	ds_write2st64_b64 v187, v[10:11], v[12:13] offset1:9
	v_cvt_pk_bf16_f32 v10, v98, v99
	v_cvt_pk_bf16_f32 v11, v100, v101
	s_nop 0
	v_cvt_pk_bf16_f32 v12, v126, v127
	v_cvt_pk_bf16_f32 v13, v128, v129
	ds_write2st64_b64 v187, v[10:11], v[12:13] offset0:18 offset1:27
	s_waitcnt vmcnt(19)
	ds_write_b128 v171, v[54:57]
	s_waitcnt vmcnt(18)
	ds_write_b128 v171, v[58:61] offset:10240
	s_waitcnt vmcnt(17)
	ds_write_b128 v171, v[78:81] offset:20480
	s_waitcnt vmcnt(16)
	ds_write_b128 v171, v[82:85] offset:30720
	s_waitcnt vmcnt(15)
	ds_write_b128 v178, v[90:93] offset:30720
	s_and_saveexec_b64 s[8:9], vcc
	s_cbranch_execz .LBB0_1579
	s_waitcnt vmcnt(14)
	ds_write_b128 v177, v[86:89] offset:51200
.LBB0_1579:
	s_or_b64 exec, exec, s[8:9]
	s_or_b32 s7, s34, 18
	s_lshl_b32 s0, s7, 5
	s_or_b32 s8, s0, s78
	s_lshl_b32 s0, s8, 13
	s_mov_b32 s1, s61
	v_lshl_add_u64 v[10:11], v[168:169], 0, s[0:1]
	v_lshl_add_u64 v[12:13], v[166:167], 0, s[0:1]
	global_load_dwordx4 v[54:57], v[10:11], off
	global_load_dwordx4 v[58:61], v[12:13], off
	v_lshl_add_u64 v[10:11], v[164:165], 0, s[0:1]
	s_lshl_b32 s0, s7, 16
	s_or_b32 s0, s0, s5
	s_add_u32 s0, s77, s0
	s_addc_u32 s1, s28, 0
	v_lshl_add_u64 v[12:13], s[0:1], 0, v[156:157]
	global_load_dwordx4 v[78:81], v[10:11], off
	global_load_dwordx4 v[82:85], v[12:13], off
	v_lshl_add_u64 v[10:11], s[0:1], 0, v[158:159]
	s_lshl_b32 s0, s8, 8
	s_mov_b32 s1, s61
	v_lshl_add_u64 v[12:13], v[162:163], 0, s[0:1]
	s_or_b32 s48, s6, 0x480
	s_mov_b32 s49, s61
	global_load_dwordx4 v[90:93], v[10:11], off
	global_load_dwordx4 v[86:89], v[12:13], off
	v_lshl_add_u64 v[10:11], v[160:161], 0, s[48:49]
	v_mov_b64_e32 v[12:13], s[80:81]
	v_mad_u64_u32 v[12:13], s[0:1], v10, s19, v[12:13]
	v_mad_i32_i24 v13, v11, s19, v13
	v_lshl_add_u64 v[10:11], v[12:13], 0, s[60:61]
	v_lshl_add_u64 v[10:11], v[10:11], 0, v[196:197]
	s_waitcnt lgkmcnt(7)
	v_pk_fma_f32 v[110:111], v[130:131], v[110:111], v[114:115]
	v_add_co_u32_e64 v16, s[44:45], s14, v10
	v_lshl_add_u64 v[114:115], v[152:153], 0, s[52:53]
	v_cvt_pk_bf16_f32 v110, v110, v110
	v_lshl_add_u64 v[14:15], v[10:11], 0, s[20:21]
	v_addc_co_u32_e64 v17, s[44:45], 0, v11, s[44:45]
	v_pk_fma_f32 v[112:113], v[132:133], v[112:113], v[116:117]
	v_lshlrev_b64 v[114:115], 12, v[114:115]
	v_and_b32_e32 v110, 0xffff, v110
	global_load_dwordx4 v[34:37], v[14:15], off offset:64
	global_load_dwordx4 v[10:13], v[14:15], off offset:128
	global_load_dwordx4 v[38:41], v[16:17], off offset:1024
	s_nop 0
	global_load_dwordx4 v[14:17], v[14:15], off offset:192
	v_lshl_add_u64 v[114:115], v[154:155], 0, v[114:115]
	global_store_short v[114:115], v110, off
	v_cvt_pk_bf16_f32 v110, v111, v111
	v_cvt_pk_bf16_f32 v112, v112, v112
	v_lshl_add_u64 v[116:117], v[114:115], 0, s[86:87]
	v_and_b32_e32 v110, 0xffff, v110
	global_store_short v[116:117], v110, off
	v_and_b32_e32 v112, 0xffff, v112
	v_lshl_add_u64 v[110:111], v[114:115], 0, s[74:75]
	global_store_short v[110:111], v112, off
	v_cvt_pk_bf16_f32 v112, v113, v113
	v_pk_fma_f32 v[118:119], v[130:131], v[118:119], v[122:123]
	v_and_b32_e32 v112, 0xffff, v112
	v_lshl_add_u64 v[110:111], v[114:115], 0, s[66:67]
	global_store_short v[110:111], v112, off
	v_cvt_pk_bf16_f32 v112, v118, v118
	v_and_b32_e32 v112, 0xffff, v112
	v_lshl_add_u64 v[110:111], v[114:115], 0, 32
	global_store_short v[110:111], v112, off
	v_cvt_pk_bf16_f32 v112, v119, v119
	v_pk_fma_f32 v[120:121], v[132:133], v[120:121], v[124:125]
	v_and_b32_e32 v112, 0xffff, v112
	v_lshl_add_u64 v[110:111], v[114:115], 0, s[22:23]
	global_store_short v[110:111], v112, off
	v_cvt_pk_bf16_f32 v112, v120, v120
	v_and_b32_e32 v112, 0xffff, v112
	v_lshl_add_u64 v[110:111], v[114:115], 0, s[12:13]
	global_store_short v[110:111], v112, off
	v_cvt_pk_bf16_f32 v112, v121, v121
	v_lshl_add_u64 v[110:111], v[114:115], 0, s[56:57]
	v_and_b32_e32 v112, 0xffff, v112
	global_store_short v[110:111], v112, off
	s_waitcnt lgkmcnt(0)
	s_barrier
	ds_read_b128 v[110:113], v189
	ds_read_b128 v[114:117], v189 offset:64
	ds_read_b128 v[206:209], v189 offset:128
	ds_read_b128 v[122:125], v150
	ds_read_b128 v[210:213], v189 offset:192
	ds_read_b128 v[118:121], v186 offset:10240
	ds_read_b128 v[130:133], v150 offset:64
	ds_read_b128 v[214:217], v186 offset:10304
	ds_read_b128 v[218:221], v189 offset:4608
	ds_read_b128 v[222:225], v189 offset:4672
	s_waitcnt vmcnt(21) lgkmcnt(9)
	v_mfma_f32_16x16x32_bf16 v[110:113], v[42:45], v[110:113], 0
	s_waitcnt lgkmcnt(8)
	v_mfma_f32_16x16x32_bf16 v[110:113], v[26:29], v[114:117], v[110:113]
	s_nop 0
	s_nop 0
	s_waitcnt lgkmcnt(7)
	v_mfma_f32_16x16x32_bf16 v[110:113], v[18:21], v[206:209], v[110:113]
	ds_read_b128 v[206:209], v189 offset:4736
	s_nop 0
	s_nop 0
	s_nop 0
	s_waitcnt vmcnt(20) lgkmcnt(6)
	v_mfma_f32_16x16x32_bf16 v[110:113], v[22:25], v[210:213], v[110:113]
	ds_read_b128 v[210:213], v189 offset:4800
	s_waitcnt lgkmcnt(6)
	v_mfma_f32_16x16x32_bf16 v[114:117], v[122:125], v[118:121], 0
	s_nop 0
	s_waitcnt lgkmcnt(4)
	v_mfma_f32_16x16x32_bf16 v[114:117], v[130:133], v[214:217], v[114:117]
	ds_read_b128 v[214:217], v186 offset:12800
	s_nop 0
	s_waitcnt lgkmcnt(4)
	v_mfma_f32_16x16x32_bf16 v[42:45], v[42:45], v[218:221], 0
	ds_read_b128 v[218:221], v186 offset:12864
	s_nop 0
	s_waitcnt lgkmcnt(4)
	v_mfma_f32_16x16x32_bf16 v[26:29], v[26:29], v[222:225], v[42:45]
	ds_read_b128 v[222:225], v180 offset:30720
	ds_read_b32 v138, v197 offset:51452
	s_nop 4
	s_nop 0
	s_waitcnt lgkmcnt(5)
	v_mfma_f32_16x16x32_bf16 v[18:21], v[18:21], v[206:209], v[26:29]
	ds_read_b128 v[42:45], v179 offset:20480
	ds_read_b128 v[134:137], v180 offset:30784
	ds_read_b128 v[206:209], v179 offset:23040
	s_nop 2
	s_nop 0
	s_waitcnt lgkmcnt(7)
	v_mfma_f32_16x16x32_bf16 v[118:121], v[22:25], v[210:213], v[18:21]
	ds_read_b128 v[210:213], v179 offset:25600
	s_nop 2
	s_nop 0
	s_nop 0
	s_nop 0
	s_nop 0
	s_nop 0
	s_nop 0
	s_waitcnt lgkmcnt(7)
	v_mfma_f32_16x16x32_bf16 v[18:21], v[122:125], v[214:217], 0
	ds_read_b128 v[214:217], v179 offset:28160
	s_waitcnt lgkmcnt(7)
	v_mfma_f32_16x16x32_bf16 v[122:125], v[130:133], v[218:221], v[18:21]
	ds_read_b128 v[218:221], v179 offset:20544
	s_nop 0
	s_waitcnt lgkmcnt(6)
	s_nop 3
	v_pk_mul_f32 v[20:21], v[108:109], v[138:139] op_sel_hi:[1,0]
	v_pk_mul_f32 v[18:19], v[106:107], v[138:139] op_sel_hi:[1,0]
	s_waitcnt lgkmcnt(5)
	s_nop 0
	v_mfma_f32_16x16x32_bf16 v[18:21], v[222:225], v[42:45], v[18:21]
	v_mul_f32_e64 v44, v104, v138
	v_mul_f32_e64 v45, v105, v138
	v_pk_mul_f32 v[42:43], v[102:103], v[138:139] op_sel_hi:[1,0]
	s_nop 0
	s_waitcnt lgkmcnt(3)
	v_mfma_f32_16x16x32_bf16 v[22:25], v[222:225], v[206:209], v[42:45]
	ds_read_b128 v[206:209], v179 offset:23104
	s_nop 2
	v_mul_f32_e64 v44, v100, v138
	v_mul_f32_e64 v45, v101, v138
	v_pk_mul_f32 v[42:43], v[98:99], v[138:139] op_sel_hi:[1,0]
	s_nop 0
	s_waitcnt lgkmcnt(3)
	v_mfma_f32_16x16x32_bf16 v[42:45], v[222:225], v[210:213], v[42:45]
	v_mul_f32_e64 v104, v128, v138
	v_mul_f32_e64 v105, v129, v138
	v_pk_mul_f32 v[102:103], v[126:127], v[138:139] op_sel_hi:[1,0]
	ds_read_b128 v[210:213], v179 offset:25664
	s_waitcnt lgkmcnt(3)
	s_nop 0
	v_mfma_f32_16x16x32_bf16 v[26:29], v[222:225], v[214:217], v[102:105]
	ds_read_b128 v[214:217], v179 offset:28224
	ds_read_b128 v[130:133], v176 offset:51200
	s_nop 0
	s_waitcnt lgkmcnt(4)
	v_mfma_f32_16x16x32_bf16 v[106:109], v[134:137], v[218:221], v[18:21]
	s_nop 2
	s_nop 0
	s_waitcnt lgkmcnt(3)
	v_mfma_f32_16x16x32_bf16 v[102:105], v[134:137], v[206:209], v[22:25]
	s_nop 0
	s_waitcnt lgkmcnt(2)
	v_mfma_f32_16x16x32_bf16 v[98:101], v[134:137], v[210:213], v[42:45]
	s_nop 0
	s_nop 0
	s_waitcnt lgkmcnt(1)
	v_mfma_f32_16x16x32_bf16 v[126:129], v[134:137], v[214:217], v[26:29]
	v_cvt_pk_bf16_f32 v18, v106, v107
	v_cvt_pk_bf16_f32 v19, v108, v109
	v_cvt_pk_bf16_f32 v20, v102, v103
	v_cvt_pk_bf16_f32 v21, v104, v105
	ds_write2st64_b64 v174, v[18:19], v[20:21] offset1:9
	v_cvt_pk_bf16_f32 v18, v98, v99
	v_cvt_pk_bf16_f32 v19, v100, v101
	s_nop 0
	v_cvt_pk_bf16_f32 v20, v126, v127
	v_cvt_pk_bf16_f32 v21, v128, v129
	ds_write2st64_b64 v174, v[18:19], v[20:21] offset0:18 offset1:27
	s_waitcnt vmcnt(19)
	ds_write_b128 v171, v[50:53] offset:51456
	s_waitcnt vmcnt(18)
	ds_write_b128 v171, v[62:65] offset:61696
	s_waitcnt vmcnt(17)
	ds_write_b128 v172, v[66:69]
	s_waitcnt vmcnt(16)
	ds_write_b128 v173, v[70:73]
	s_waitcnt vmcnt(15)
	ds_write_b128 v175, v[94:97]
	s_and_saveexec_b64 s[8:9], vcc
	s_cbranch_execz .LBB0_1581
	s_waitcnt vmcnt(14)
	ds_write_b128 v185, v[74:77]
.LBB0_1581:
	s_or_b64 exec, exec, s[8:9]
	s_or_b32 s7, s34, 19
	s_lshl_b32 s0, s7, 5
	s_or_b32 s8, s0, s78
	s_lshl_b32 s0, s8, 13
	s_mov_b32 s1, s61
	v_lshl_add_u64 v[18:19], v[168:169], 0, s[0:1]
	v_lshl_add_u64 v[20:21], v[166:167], 0, s[0:1]
	global_load_dwordx4 v[50:53], v[18:19], off
	global_load_dwordx4 v[62:65], v[20:21], off
	v_lshl_add_u64 v[18:19], v[164:165], 0, s[0:1]
	s_lshl_b32 s0, s7, 16
	s_or_b32 s0, s0, s5
	s_add_u32 s0, s77, s0
	s_addc_u32 s1, s28, 0
	v_lshl_add_u64 v[20:21], s[0:1], 0, v[156:157]
	global_load_dwordx4 v[66:69], v[18:19], off
	global_load_dwordx4 v[70:73], v[20:21], off
	v_lshl_add_u64 v[18:19], s[0:1], 0, v[158:159]
	s_lshl_b32 s0, s8, 8
	s_mov_b32 s1, s61
	v_lshl_add_u64 v[20:21], v[162:163], 0, s[0:1]
	s_or_b32 s52, s6, 0x4c0
	s_mov_b32 s53, s61
	global_load_dwordx4 v[94:97], v[18:19], off
	global_load_dwordx4 v[74:77], v[20:21], off
	v_lshl_add_u64 v[18:19], v[160:161], 0, s[52:53]
	v_mov_b64_e32 v[20:21], s[80:81]
	v_mad_u64_u32 v[20:21], s[0:1], v18, s19, v[20:21]
	v_mad_i32_i24 v21, v19, s19, v21
	v_lshl_add_u64 v[18:19], v[20:21], 0, s[60:61]
	v_lshl_add_u64 v[18:19], v[18:19], 0, v[196:197]
	s_waitcnt lgkmcnt(7)
	v_pk_fma_f32 v[110:111], v[130:131], v[110:111], v[114:115]
	v_add_co_u32_e64 v24, s[44:45], s14, v18
	v_lshl_add_u64 v[114:115], v[152:153], 0, s[46:47]
	v_cvt_pk_bf16_f32 v110, v110, v110
	v_lshl_add_u64 v[22:23], v[18:19], 0, s[20:21]
	v_addc_co_u32_e64 v25, s[44:45], 0, v19, s[44:45]
	v_pk_fma_f32 v[112:113], v[132:133], v[112:113], v[116:117]
	v_lshlrev_b64 v[114:115], 12, v[114:115]
	v_and_b32_e32 v110, 0xffff, v110
	global_load_dwordx4 v[26:29], v[22:23], off offset:64
	global_load_dwordx4 v[18:21], v[22:23], off offset:128
	global_load_dwordx4 v[42:45], v[24:25], off offset:1024
	s_nop 0
	global_load_dwordx4 v[22:25], v[22:23], off offset:192
	v_lshl_add_u64 v[114:115], v[154:155], 0, v[114:115]
	global_store_short v[114:115], v110, off
	v_cvt_pk_bf16_f32 v110, v111, v111
	v_cvt_pk_bf16_f32 v112, v112, v112
	v_lshl_add_u64 v[116:117], v[114:115], 0, s[86:87]
	v_and_b32_e32 v110, 0xffff, v110
	global_store_short v[116:117], v110, off
	v_and_b32_e32 v112, 0xffff, v112
	v_lshl_add_u64 v[110:111], v[114:115], 0, s[74:75]
	global_store_short v[110:111], v112, off
	v_cvt_pk_bf16_f32 v112, v113, v113
	v_pk_fma_f32 v[118:119], v[130:131], v[118:119], v[122:123]
	v_and_b32_e32 v112, 0xffff, v112
	v_lshl_add_u64 v[110:111], v[114:115], 0, s[66:67]
	global_store_short v[110:111], v112, off
	v_cvt_pk_bf16_f32 v112, v118, v118
	v_and_b32_e32 v112, 0xffff, v112
	v_lshl_add_u64 v[110:111], v[114:115], 0, 32
	global_store_short v[110:111], v112, off
	v_cvt_pk_bf16_f32 v112, v119, v119
	v_pk_fma_f32 v[120:121], v[132:133], v[120:121], v[124:125]
	v_and_b32_e32 v112, 0xffff, v112
	v_lshl_add_u64 v[110:111], v[114:115], 0, s[22:23]
	global_store_short v[110:111], v112, off
	v_cvt_pk_bf16_f32 v112, v120, v120
	v_and_b32_e32 v112, 0xffff, v112
	v_lshl_add_u64 v[110:111], v[114:115], 0, s[12:13]
	global_store_short v[110:111], v112, off
	v_cvt_pk_bf16_f32 v112, v121, v121
	v_lshl_add_u64 v[110:111], v[114:115], 0, s[56:57]
	v_and_b32_e32 v112, 0xffff, v112
	global_store_short v[110:111], v112, off
	s_waitcnt lgkmcnt(0)
	s_barrier
	ds_read_b128 v[110:113], v188
	ds_read_b128 v[114:117], v188 offset:64
	ds_read_b128 v[206:209], v188 offset:128
	ds_read_b128 v[122:125], v150 offset:51456
	ds_read_b128 v[210:213], v188 offset:192
	ds_read_b128 v[118:121], v186 offset:61696
	ds_read_b128 v[130:133], v150 offset:51520
	ds_read_b128 v[214:217], v186 offset:61760
	ds_read_b128 v[218:221], v188 offset:4608
	ds_read_b128 v[222:225], v188 offset:4672
	s_waitcnt vmcnt(21) lgkmcnt(9)
	v_mfma_f32_16x16x32_bf16 v[110:113], v[46:49], v[110:113], 0
	v_readlane_b32 s0, v253, 18
	s_waitcnt lgkmcnt(8)
	v_mfma_f32_16x16x32_bf16 v[110:113], v[30:33], v[114:117], v[110:113]
	s_nop 0
	s_nop 0
	s_waitcnt lgkmcnt(7)
	v_mfma_f32_16x16x32_bf16 v[110:113], v[2:5], v[206:209], v[110:113]
	ds_read_b128 v[206:209], v188 offset:4736
	s_nop 0
	s_nop 0
	s_nop 0
	s_waitcnt vmcnt(20) lgkmcnt(6)
	v_mfma_f32_16x16x32_bf16 v[110:113], v[6:9], v[210:213], v[110:113]
	ds_read_b128 v[210:213], v188 offset:4800
	s_waitcnt lgkmcnt(6)
	v_mfma_f32_16x16x32_bf16 v[114:117], v[122:125], v[118:121], 0
	s_nop 0
	s_waitcnt lgkmcnt(4)
	v_mfma_f32_16x16x32_bf16 v[114:117], v[130:133], v[214:217], v[114:117]
	ds_read_b128 v[214:217], v186 offset:64256
	s_nop 0
	s_waitcnt lgkmcnt(4)
	v_mfma_f32_16x16x32_bf16 v[46:49], v[46:49], v[218:221], 0
	ds_read_b128 v[218:221], v186 offset:64320
	s_nop 0
	s_waitcnt lgkmcnt(4)
	v_mfma_f32_16x16x32_bf16 v[30:33], v[30:33], v[222:225], v[46:49]
	ds_read_b128 v[222:225], v183
	s_nop 4
	s_nop 0
	s_waitcnt lgkmcnt(4)
	v_mfma_f32_16x16x32_bf16 v[2:5], v[2:5], v[206:209], v[30:33]
	s_nop 2
	s_nop 0
	v_mov_b32_e32 v46, s0
	ds_read_b32 v138, v46
	ds_read_b128 v[206:209], v184
	ds_read_b128 v[134:137], v183 offset:64
	s_waitcnt lgkmcnt(6)
	v_mfma_f32_16x16x32_bf16 v[118:121], v[6:9], v[210:213], v[2:5]
	ds_read_b128 v[210:213], v184 offset:2560
	s_nop 2
	s_nop 0
	s_nop 0
	s_nop 0
	s_nop 0
	s_nop 0
	s_nop 0
	s_waitcnt lgkmcnt(6)
	v_mfma_f32_16x16x32_bf16 v[2:5], v[122:125], v[214:217], 0
	ds_read_b128 v[214:217], v184 offset:5120
	s_waitcnt lgkmcnt(6)
	v_mfma_f32_16x16x32_bf16 v[122:125], v[130:133], v[218:221], v[2:5]
	ds_read_b128 v[218:221], v184 offset:7680
	s_nop 0
	s_waitcnt lgkmcnt(5)
	s_nop 3
	v_pk_mul_f32 v[4:5], v[108:109], v[138:139] op_sel_hi:[1,0]
	v_pk_mul_f32 v[2:3], v[106:107], v[138:139] op_sel_hi:[1,0]
	s_waitcnt lgkmcnt(4)
	s_nop 0
	v_mfma_f32_16x16x32_bf16 v[2:5], v[222:225], v[206:209], v[2:5]
	v_mul_f32_e64 v48, v104, v138
	v_mul_f32_e64 v49, v105, v138
	v_pk_mul_f32 v[46:47], v[102:103], v[138:139] op_sel_hi:[1,0]
	ds_read_b128 v[206:209], v182
	s_nop 0
	s_waitcnt lgkmcnt(3)
	v_mfma_f32_16x16x32_bf16 v[6:9], v[222:225], v[210:213], v[46:49]
	ds_read_b128 v[210:213], v182 offset:2560
	s_nop 2
	v_mul_f32_e64 v48, v100, v138
	v_mul_f32_e64 v49, v101, v138
	v_pk_mul_f32 v[46:47], v[98:99], v[138:139] op_sel_hi:[1,0]
	s_nop 0
	s_waitcnt lgkmcnt(3)
	v_mfma_f32_16x16x32_bf16 v[46:49], v[222:225], v[214:217], v[46:49]
	v_mul_f32_e64 v104, v128, v138
	v_mul_f32_e64 v105, v129, v138
	v_pk_mul_f32 v[102:103], v[126:127], v[138:139] op_sel_hi:[1,0]
	ds_read_b128 v[214:217], v182 offset:5120
	s_waitcnt lgkmcnt(3)
	s_nop 0
	v_mfma_f32_16x16x32_bf16 v[30:33], v[222:225], v[218:221], v[102:105]
	ds_read_b128 v[218:221], v182 offset:7680
	ds_read_b128 v[130:133], v181
	s_nop 0
	s_waitcnt lgkmcnt(4)
	v_mfma_f32_16x16x32_bf16 v[106:109], v[134:137], v[206:209], v[2:5]
	s_nop 2
	s_nop 0
	s_waitcnt lgkmcnt(3)
	v_mfma_f32_16x16x32_bf16 v[102:105], v[134:137], v[210:213], v[6:9]
	s_nop 0
	s_waitcnt lgkmcnt(2)
	v_mfma_f32_16x16x32_bf16 v[98:101], v[134:137], v[214:217], v[46:49]
	s_nop 0
	s_nop 0
	s_waitcnt lgkmcnt(1)
	v_mfma_f32_16x16x32_bf16 v[126:129], v[134:137], v[218:221], v[30:33]
	v_cvt_pk_bf16_f32 v2, v106, v107
	v_cvt_pk_bf16_f32 v3, v108, v109
	v_cvt_pk_bf16_f32 v4, v102, v103
	v_cvt_pk_bf16_f32 v5, v104, v105
	ds_write2st64_b64 v187, v[2:3], v[4:5] offset1:9
	v_cvt_pk_bf16_f32 v2, v98, v99
	v_cvt_pk_bf16_f32 v3, v100, v101
	s_nop 0
	v_cvt_pk_bf16_f32 v4, v126, v127
	v_cvt_pk_bf16_f32 v5, v128, v129
	ds_write2st64_b64 v187, v[2:3], v[4:5] offset0:18 offset1:27
	s_waitcnt vmcnt(19)
	ds_write_b128 v171, v[54:57]
	s_waitcnt vmcnt(18)
	ds_write_b128 v171, v[58:61] offset:10240
	s_waitcnt vmcnt(17)
	ds_write_b128 v171, v[78:81] offset:20480
	s_waitcnt vmcnt(16)
	ds_write_b128 v171, v[82:85] offset:30720
	s_waitcnt vmcnt(15)
	ds_write_b128 v178, v[90:93] offset:30720
	s_and_saveexec_b64 s[8:9], vcc
	s_cbranch_execz .LBB0_1583
	s_waitcnt vmcnt(14)
	ds_write_b128 v177, v[86:89] offset:51200
.LBB0_1583:
	s_or_b64 exec, exec, s[8:9]
	s_or_b32 s7, s34, 20
	s_lshl_b32 s0, s7, 5
	s_or_b32 s8, s0, s78
	s_lshl_b32 s0, s8, 13
	s_mov_b32 s1, s61
	v_lshl_add_u64 v[2:3], v[168:169], 0, s[0:1]
	v_lshl_add_u64 v[4:5], v[166:167], 0, s[0:1]
	global_load_dwordx4 v[54:57], v[2:3], off
	global_load_dwordx4 v[58:61], v[4:5], off
	v_lshl_add_u64 v[2:3], v[164:165], 0, s[0:1]
	s_lshl_b32 s0, s7, 16
	s_or_b32 s0, s0, s5
	s_add_u32 s0, s77, s0
	s_addc_u32 s1, s28, 0
	v_lshl_add_u64 v[4:5], s[0:1], 0, v[156:157]
	global_load_dwordx4 v[78:81], v[2:3], off
	global_load_dwordx4 v[82:85], v[4:5], off
	v_lshl_add_u64 v[2:3], s[0:1], 0, v[158:159]
	s_lshl_b32 s0, s8, 8
	s_mov_b32 s1, s61
	v_lshl_add_u64 v[4:5], v[162:163], 0, s[0:1]
	s_or_b32 s46, s6, 0x500
	s_mov_b32 s47, s61
	global_load_dwordx4 v[90:93], v[2:3], off
	global_load_dwordx4 v[86:89], v[4:5], off
	v_lshl_add_u64 v[2:3], v[160:161], 0, s[46:47]
	v_mov_b64_e32 v[4:5], s[80:81]
	v_mad_u64_u32 v[4:5], s[0:1], v2, s19, v[4:5]
	v_mad_i32_i24 v5, v3, s19, v5
	v_lshl_add_u64 v[2:3], v[4:5], 0, s[60:61]
	v_lshl_add_u64 v[2:3], v[2:3], 0, v[196:197]
	s_waitcnt lgkmcnt(7)
	v_pk_fma_f32 v[110:111], v[130:131], v[110:111], v[114:115]
	v_add_co_u32_e64 v8, s[44:45], s14, v2
	v_lshl_add_u64 v[114:115], v[152:153], 0, s[50:51]
	v_cvt_pk_bf16_f32 v110, v110, v110
	v_lshl_add_u64 v[6:7], v[2:3], 0, s[20:21]
	v_addc_co_u32_e64 v9, s[44:45], 0, v3, s[44:45]
	v_pk_fma_f32 v[112:113], v[132:133], v[112:113], v[116:117]
	v_lshlrev_b64 v[114:115], 12, v[114:115]
	v_and_b32_e32 v110, 0xffff, v110
	global_load_dwordx4 v[30:33], v[6:7], off offset:64
	global_load_dwordx4 v[2:5], v[6:7], off offset:128
	global_load_dwordx4 v[46:49], v[8:9], off offset:1024
	s_nop 0
	global_load_dwordx4 v[6:9], v[6:7], off offset:192
	v_lshl_add_u64 v[114:115], v[154:155], 0, v[114:115]
	global_store_short v[114:115], v110, off
	v_cvt_pk_bf16_f32 v110, v111, v111
	v_cvt_pk_bf16_f32 v112, v112, v112
	v_lshl_add_u64 v[116:117], v[114:115], 0, s[86:87]
	v_and_b32_e32 v110, 0xffff, v110
	global_store_short v[116:117], v110, off
	v_and_b32_e32 v112, 0xffff, v112
	v_lshl_add_u64 v[110:111], v[114:115], 0, s[74:75]
	global_store_short v[110:111], v112, off
	v_cvt_pk_bf16_f32 v112, v113, v113
	v_pk_fma_f32 v[118:119], v[130:131], v[118:119], v[122:123]
	v_and_b32_e32 v112, 0xffff, v112
	v_lshl_add_u64 v[110:111], v[114:115], 0, s[66:67]
	global_store_short v[110:111], v112, off
	v_cvt_pk_bf16_f32 v112, v118, v118
	v_and_b32_e32 v112, 0xffff, v112
	v_lshl_add_u64 v[110:111], v[114:115], 0, 32
	global_store_short v[110:111], v112, off
	v_cvt_pk_bf16_f32 v112, v119, v119
	v_pk_fma_f32 v[120:121], v[132:133], v[120:121], v[124:125]
	v_and_b32_e32 v112, 0xffff, v112
	v_lshl_add_u64 v[110:111], v[114:115], 0, s[22:23]
	global_store_short v[110:111], v112, off
	v_cvt_pk_bf16_f32 v112, v120, v120
	v_and_b32_e32 v112, 0xffff, v112
	v_lshl_add_u64 v[110:111], v[114:115], 0, s[12:13]
	global_store_short v[110:111], v112, off
	v_cvt_pk_bf16_f32 v112, v121, v121
	v_lshl_add_u64 v[110:111], v[114:115], 0, s[56:57]
	v_and_b32_e32 v112, 0xffff, v112
	global_store_short v[110:111], v112, off
	s_waitcnt lgkmcnt(0)
	s_barrier
	ds_read_b128 v[110:113], v189
	ds_read_b128 v[114:117], v189 offset:64
	ds_read_b128 v[206:209], v189 offset:128
	ds_read_b128 v[122:125], v150
	ds_read_b128 v[210:213], v189 offset:192
	ds_read_b128 v[118:121], v186 offset:10240
	ds_read_b128 v[130:133], v150 offset:64
	ds_read_b128 v[214:217], v186 offset:10304
	ds_read_b128 v[218:221], v189 offset:4608
	ds_read_b128 v[222:225], v189 offset:4672
	s_waitcnt vmcnt(21) lgkmcnt(9)
	v_mfma_f32_16x16x32_bf16 v[110:113], v[38:41], v[110:113], 0
	s_waitcnt lgkmcnt(8)
	v_mfma_f32_16x16x32_bf16 v[110:113], v[34:37], v[114:117], v[110:113]
	s_nop 0
	s_nop 0
	s_waitcnt lgkmcnt(7)
	v_mfma_f32_16x16x32_bf16 v[110:113], v[10:13], v[206:209], v[110:113]
	ds_read_b128 v[206:209], v189 offset:4736
	s_nop 0
	s_nop 0
	s_nop 0
	s_waitcnt vmcnt(20) lgkmcnt(6)
	v_mfma_f32_16x16x32_bf16 v[110:113], v[14:17], v[210:213], v[110:113]
	ds_read_b128 v[210:213], v189 offset:4800
	s_waitcnt lgkmcnt(6)
	v_mfma_f32_16x16x32_bf16 v[114:117], v[122:125], v[118:121], 0
	s_nop 0
	s_waitcnt lgkmcnt(4)
	v_mfma_f32_16x16x32_bf16 v[114:117], v[130:133], v[214:217], v[114:117]
	ds_read_b128 v[214:217], v186 offset:12800
	s_nop 0
	s_waitcnt lgkmcnt(4)
	v_mfma_f32_16x16x32_bf16 v[38:41], v[38:41], v[218:221], 0
	ds_read_b128 v[218:221], v186 offset:12864
	s_nop 0
	s_waitcnt lgkmcnt(4)
	v_mfma_f32_16x16x32_bf16 v[34:37], v[34:37], v[222:225], v[38:41]
	ds_read_b128 v[222:225], v180 offset:30720
	ds_read_b32 v138, v197 offset:51452
	s_nop 4
	s_nop 0
	s_waitcnt lgkmcnt(5)
	v_mfma_f32_16x16x32_bf16 v[10:13], v[10:13], v[206:209], v[34:37]
	ds_read_b128 v[38:41], v179 offset:20480
	ds_read_b128 v[134:137], v180 offset:30784
	ds_read_b128 v[206:209], v179 offset:23040
	s_nop 2
	s_nop 0
	s_waitcnt lgkmcnt(7)
	v_mfma_f32_16x16x32_bf16 v[118:121], v[14:17], v[210:213], v[10:13]
	ds_read_b128 v[210:213], v179 offset:25600
	s_nop 2
	s_nop 0
	s_nop 0
	s_nop 0
	s_nop 0
	s_nop 0
	s_nop 0
	s_waitcnt lgkmcnt(7)
	v_mfma_f32_16x16x32_bf16 v[10:13], v[122:125], v[214:217], 0
	ds_read_b128 v[214:217], v179 offset:28160
	s_waitcnt lgkmcnt(7)
	v_mfma_f32_16x16x32_bf16 v[122:125], v[130:133], v[218:221], v[10:13]
	ds_read_b128 v[218:221], v179 offset:20544
	s_nop 0
	s_waitcnt lgkmcnt(6)
	s_nop 3
	v_pk_mul_f32 v[12:13], v[108:109], v[138:139] op_sel_hi:[1,0]
	v_pk_mul_f32 v[10:11], v[106:107], v[138:139] op_sel_hi:[1,0]
	s_waitcnt lgkmcnt(5)
	s_nop 0
	v_mfma_f32_16x16x32_bf16 v[10:13], v[222:225], v[38:41], v[10:13]
	v_mul_f32_e64 v40, v104, v138
	v_mul_f32_e64 v41, v105, v138
	v_pk_mul_f32 v[38:39], v[102:103], v[138:139] op_sel_hi:[1,0]
	s_nop 0
	s_waitcnt lgkmcnt(3)
	v_mfma_f32_16x16x32_bf16 v[14:17], v[222:225], v[206:209], v[38:41]
	ds_read_b128 v[206:209], v179 offset:23104
	s_nop 2
	v_mul_f32_e64 v40, v100, v138
	v_mul_f32_e64 v41, v101, v138
	v_pk_mul_f32 v[38:39], v[98:99], v[138:139] op_sel_hi:[1,0]
	s_nop 0
	s_waitcnt lgkmcnt(3)
	v_mfma_f32_16x16x32_bf16 v[38:41], v[222:225], v[210:213], v[38:41]
	v_mul_f32_e64 v104, v128, v138
	v_mul_f32_e64 v105, v129, v138
	v_pk_mul_f32 v[102:103], v[126:127], v[138:139] op_sel_hi:[1,0]
	ds_read_b128 v[210:213], v179 offset:25664
	s_waitcnt lgkmcnt(3)
	s_nop 0
	v_mfma_f32_16x16x32_bf16 v[34:37], v[222:225], v[214:217], v[102:105]
	ds_read_b128 v[214:217], v179 offset:28224
	ds_read_b128 v[130:133], v176 offset:51200
	s_nop 0
	s_waitcnt lgkmcnt(4)
	v_mfma_f32_16x16x32_bf16 v[106:109], v[134:137], v[218:221], v[10:13]
	s_nop 2
	s_nop 0
	s_waitcnt lgkmcnt(3)
	v_mfma_f32_16x16x32_bf16 v[102:105], v[134:137], v[206:209], v[14:17]
	s_nop 0
	s_waitcnt lgkmcnt(2)
	v_mfma_f32_16x16x32_bf16 v[98:101], v[134:137], v[210:213], v[38:41]
	s_nop 0
	s_nop 0
	s_waitcnt lgkmcnt(1)
	v_mfma_f32_16x16x32_bf16 v[126:129], v[134:137], v[214:217], v[34:37]
	v_cvt_pk_bf16_f32 v10, v106, v107
	v_cvt_pk_bf16_f32 v11, v108, v109
	v_cvt_pk_bf16_f32 v12, v102, v103
	v_cvt_pk_bf16_f32 v13, v104, v105
	ds_write2st64_b64 v174, v[10:11], v[12:13] offset1:9
	v_cvt_pk_bf16_f32 v10, v98, v99
	v_cvt_pk_bf16_f32 v11, v100, v101
	s_nop 0
	v_cvt_pk_bf16_f32 v12, v126, v127
	v_cvt_pk_bf16_f32 v13, v128, v129
	ds_write2st64_b64 v174, v[10:11], v[12:13] offset0:18 offset1:27
	s_waitcnt vmcnt(19)
	ds_write_b128 v171, v[50:53] offset:51456
	s_waitcnt vmcnt(18)
	ds_write_b128 v171, v[62:65] offset:61696
	s_waitcnt vmcnt(17)
	ds_write_b128 v172, v[66:69]
	s_waitcnt vmcnt(16)
	ds_write_b128 v173, v[70:73]
	s_waitcnt vmcnt(15)
	ds_write_b128 v175, v[94:97]
	s_and_saveexec_b64 s[8:9], vcc
	s_cbranch_execz .LBB0_1585
	s_waitcnt vmcnt(14)
	ds_write_b128 v185, v[74:77]
.LBB0_1585:
	s_or_b64 exec, exec, s[8:9]
	s_or_b32 s7, s34, 21
	s_lshl_b32 s0, s7, 5
	s_or_b32 s8, s0, s78
	s_lshl_b32 s0, s8, 13
	s_mov_b32 s1, s61
	v_lshl_add_u64 v[10:11], v[168:169], 0, s[0:1]
	v_lshl_add_u64 v[12:13], v[166:167], 0, s[0:1]
	global_load_dwordx4 v[50:53], v[10:11], off
	global_load_dwordx4 v[62:65], v[12:13], off
	v_lshl_add_u64 v[10:11], v[164:165], 0, s[0:1]
	s_lshl_b32 s0, s7, 16
	s_or_b32 s0, s0, s5
	s_add_u32 s0, s77, s0
	s_addc_u32 s1, s28, 0
	v_lshl_add_u64 v[12:13], s[0:1], 0, v[156:157]
	global_load_dwordx4 v[66:69], v[10:11], off
	global_load_dwordx4 v[70:73], v[12:13], off
	v_lshl_add_u64 v[10:11], s[0:1], 0, v[158:159]
	s_lshl_b32 s0, s8, 8
	s_mov_b32 s1, s61
	v_lshl_add_u64 v[12:13], v[162:163], 0, s[0:1]
	s_or_b32 s50, s6, 0x540
	s_mov_b32 s51, s61
	global_load_dwordx4 v[94:97], v[10:11], off
	global_load_dwordx4 v[74:77], v[12:13], off
	v_lshl_add_u64 v[10:11], v[160:161], 0, s[50:51]
	v_mov_b64_e32 v[12:13], s[80:81]
	v_mad_u64_u32 v[12:13], s[0:1], v10, s19, v[12:13]
	v_mad_i32_i24 v13, v11, s19, v13
	v_lshl_add_u64 v[10:11], v[12:13], 0, s[60:61]
	v_lshl_add_u64 v[10:11], v[10:11], 0, v[196:197]
	s_waitcnt lgkmcnt(7)
	v_pk_fma_f32 v[110:111], v[130:131], v[110:111], v[114:115]
	v_add_co_u32_e64 v16, s[44:45], s14, v10
	v_lshl_add_u64 v[114:115], v[152:153], 0, s[48:49]
	v_cvt_pk_bf16_f32 v110, v110, v110
	v_lshl_add_u64 v[14:15], v[10:11], 0, s[20:21]
	v_addc_co_u32_e64 v17, s[44:45], 0, v11, s[44:45]
	v_pk_fma_f32 v[112:113], v[132:133], v[112:113], v[116:117]
	v_lshlrev_b64 v[114:115], 12, v[114:115]
	v_and_b32_e32 v110, 0xffff, v110
	global_load_dwordx4 v[34:37], v[14:15], off offset:64
	global_load_dwordx4 v[10:13], v[14:15], off offset:128
	global_load_dwordx4 v[38:41], v[16:17], off offset:1024
	s_nop 0
	global_load_dwordx4 v[14:17], v[14:15], off offset:192
	v_lshl_add_u64 v[114:115], v[154:155], 0, v[114:115]
	global_store_short v[114:115], v110, off
	v_cvt_pk_bf16_f32 v110, v111, v111
	v_cvt_pk_bf16_f32 v112, v112, v112
	v_lshl_add_u64 v[116:117], v[114:115], 0, s[86:87]
	v_and_b32_e32 v110, 0xffff, v110
	global_store_short v[116:117], v110, off
	v_and_b32_e32 v112, 0xffff, v112
	v_lshl_add_u64 v[110:111], v[114:115], 0, s[74:75]
	global_store_short v[110:111], v112, off
	v_cvt_pk_bf16_f32 v112, v113, v113
	v_pk_fma_f32 v[118:119], v[130:131], v[118:119], v[122:123]
	v_and_b32_e32 v112, 0xffff, v112
	v_lshl_add_u64 v[110:111], v[114:115], 0, s[66:67]
	global_store_short v[110:111], v112, off
	v_cvt_pk_bf16_f32 v112, v118, v118
	v_and_b32_e32 v112, 0xffff, v112
	v_lshl_add_u64 v[110:111], v[114:115], 0, 32
	global_store_short v[110:111], v112, off
	v_cvt_pk_bf16_f32 v112, v119, v119
	v_pk_fma_f32 v[120:121], v[132:133], v[120:121], v[124:125]
	v_and_b32_e32 v112, 0xffff, v112
	v_lshl_add_u64 v[110:111], v[114:115], 0, s[22:23]
	global_store_short v[110:111], v112, off
	v_cvt_pk_bf16_f32 v112, v120, v120
	v_and_b32_e32 v112, 0xffff, v112
	v_lshl_add_u64 v[110:111], v[114:115], 0, s[12:13]
	global_store_short v[110:111], v112, off
	v_cvt_pk_bf16_f32 v112, v121, v121
	v_lshl_add_u64 v[110:111], v[114:115], 0, s[56:57]
	v_and_b32_e32 v112, 0xffff, v112
	global_store_short v[110:111], v112, off
	s_waitcnt lgkmcnt(0)
	s_barrier
	ds_read_b128 v[110:113], v188
	ds_read_b128 v[114:117], v188 offset:64
	ds_read_b128 v[206:209], v188 offset:128
	ds_read_b128 v[122:125], v150 offset:51456
	ds_read_b128 v[210:213], v188 offset:192
	ds_read_b128 v[118:121], v186 offset:61696
	ds_read_b128 v[130:133], v150 offset:51520
	ds_read_b128 v[214:217], v186 offset:61760
	ds_read_b128 v[218:221], v188 offset:4608
	ds_read_b128 v[222:225], v188 offset:4672
	s_waitcnt vmcnt(21) lgkmcnt(9)
	v_mfma_f32_16x16x32_bf16 v[110:113], v[42:45], v[110:113], 0
	v_readlane_b32 s0, v253, 18
	s_waitcnt lgkmcnt(8)
	v_mfma_f32_16x16x32_bf16 v[110:113], v[26:29], v[114:117], v[110:113]
	s_nop 0
	s_nop 0
	s_waitcnt lgkmcnt(7)
	v_mfma_f32_16x16x32_bf16 v[110:113], v[18:21], v[206:209], v[110:113]
	ds_read_b128 v[206:209], v188 offset:4736
	s_nop 0
	s_nop 0
	s_nop 0
	s_waitcnt vmcnt(20) lgkmcnt(6)
	v_mfma_f32_16x16x32_bf16 v[110:113], v[22:25], v[210:213], v[110:113]
	ds_read_b128 v[210:213], v188 offset:4800
	s_waitcnt lgkmcnt(6)
	v_mfma_f32_16x16x32_bf16 v[114:117], v[122:125], v[118:121], 0
	s_nop 0
	s_waitcnt lgkmcnt(4)
	v_mfma_f32_16x16x32_bf16 v[114:117], v[130:133], v[214:217], v[114:117]
	ds_read_b128 v[214:217], v186 offset:64256
	s_nop 0
	s_waitcnt lgkmcnt(4)
	v_mfma_f32_16x16x32_bf16 v[42:45], v[42:45], v[218:221], 0
	ds_read_b128 v[218:221], v186 offset:64320
	s_nop 0
	s_waitcnt lgkmcnt(4)
	v_mfma_f32_16x16x32_bf16 v[26:29], v[26:29], v[222:225], v[42:45]
	ds_read_b128 v[222:225], v183
	s_nop 4
	s_nop 0
	s_waitcnt lgkmcnt(4)
	v_mfma_f32_16x16x32_bf16 v[18:21], v[18:21], v[206:209], v[26:29]
	s_nop 2
	s_nop 0
	v_mov_b32_e32 v42, s0
	ds_read_b32 v138, v42
	ds_read_b128 v[206:209], v184
	ds_read_b128 v[134:137], v183 offset:64
	s_waitcnt lgkmcnt(6)
	v_mfma_f32_16x16x32_bf16 v[118:121], v[22:25], v[210:213], v[18:21]
	ds_read_b128 v[210:213], v184 offset:2560
	s_nop 2
	s_nop 0
	s_nop 0
	s_nop 0
	s_nop 0
	s_nop 0
	s_nop 0
	s_waitcnt lgkmcnt(6)
	v_mfma_f32_16x16x32_bf16 v[18:21], v[122:125], v[214:217], 0
	ds_read_b128 v[214:217], v184 offset:5120
	s_waitcnt lgkmcnt(6)
	v_mfma_f32_16x16x32_bf16 v[122:125], v[130:133], v[218:221], v[18:21]
	ds_read_b128 v[218:221], v184 offset:7680
	s_nop 0
	s_waitcnt lgkmcnt(5)
	s_nop 3
	v_pk_mul_f32 v[20:21], v[108:109], v[138:139] op_sel_hi:[1,0]
	v_pk_mul_f32 v[18:19], v[106:107], v[138:139] op_sel_hi:[1,0]
	s_waitcnt lgkmcnt(4)
	s_nop 0
	v_mfma_f32_16x16x32_bf16 v[18:21], v[222:225], v[206:209], v[18:21]
	v_mul_f32_e64 v44, v104, v138
	v_mul_f32_e64 v45, v105, v138
	v_pk_mul_f32 v[42:43], v[102:103], v[138:139] op_sel_hi:[1,0]
	ds_read_b128 v[206:209], v182
	s_nop 0
	s_waitcnt lgkmcnt(3)
	v_mfma_f32_16x16x32_bf16 v[22:25], v[222:225], v[210:213], v[42:45]
	ds_read_b128 v[210:213], v182 offset:2560
	s_nop 2
	v_mul_f32_e64 v44, v100, v138
	v_mul_f32_e64 v45, v101, v138
	v_pk_mul_f32 v[42:43], v[98:99], v[138:139] op_sel_hi:[1,0]
	s_nop 0
	s_waitcnt lgkmcnt(3)
	v_mfma_f32_16x16x32_bf16 v[42:45], v[222:225], v[214:217], v[42:45]
	v_mul_f32_e64 v104, v128, v138
	v_mul_f32_e64 v105, v129, v138
	v_pk_mul_f32 v[102:103], v[126:127], v[138:139] op_sel_hi:[1,0]
	ds_read_b128 v[214:217], v182 offset:5120
	s_waitcnt lgkmcnt(3)
	s_nop 0
	v_mfma_f32_16x16x32_bf16 v[26:29], v[222:225], v[218:221], v[102:105]
	ds_read_b128 v[218:221], v182 offset:7680
	ds_read_b128 v[130:133], v181
	s_nop 0
	s_waitcnt lgkmcnt(4)
	v_mfma_f32_16x16x32_bf16 v[106:109], v[134:137], v[206:209], v[18:21]
	s_nop 2
	s_nop 0
	s_waitcnt lgkmcnt(3)
	v_mfma_f32_16x16x32_bf16 v[102:105], v[134:137], v[210:213], v[22:25]
	s_nop 0
	s_waitcnt lgkmcnt(2)
	v_mfma_f32_16x16x32_bf16 v[98:101], v[134:137], v[214:217], v[42:45]
	s_nop 0
	s_nop 0
	s_waitcnt lgkmcnt(1)
	v_mfma_f32_16x16x32_bf16 v[126:129], v[134:137], v[218:221], v[26:29]
	v_cvt_pk_bf16_f32 v18, v106, v107
	v_cvt_pk_bf16_f32 v19, v108, v109
	v_cvt_pk_bf16_f32 v20, v102, v103
	v_cvt_pk_bf16_f32 v21, v104, v105
	ds_write2st64_b64 v187, v[18:19], v[20:21] offset1:9
	v_cvt_pk_bf16_f32 v18, v98, v99
	v_cvt_pk_bf16_f32 v19, v100, v101
	s_nop 0
	v_cvt_pk_bf16_f32 v20, v126, v127
	v_cvt_pk_bf16_f32 v21, v128, v129
	ds_write2st64_b64 v187, v[18:19], v[20:21] offset0:18 offset1:27
	s_waitcnt vmcnt(19)
	ds_write_b128 v171, v[54:57]
	s_waitcnt vmcnt(18)
	ds_write_b128 v171, v[58:61] offset:10240
	s_waitcnt vmcnt(17)
	ds_write_b128 v171, v[78:81] offset:20480
	s_waitcnt vmcnt(16)
	ds_write_b128 v171, v[82:85] offset:30720
	s_waitcnt vmcnt(15)
	ds_write_b128 v178, v[90:93] offset:30720
	s_and_saveexec_b64 s[8:9], vcc
	s_cbranch_execz .LBB0_1587
	s_waitcnt vmcnt(14)
	ds_write_b128 v177, v[86:89] offset:51200
.LBB0_1587:
	s_or_b64 exec, exec, s[8:9]
	s_or_b32 s7, s34, 22
	s_lshl_b32 s0, s7, 5
	s_or_b32 s8, s0, s78
	s_lshl_b32 s0, s8, 13
	s_mov_b32 s1, s61
	v_lshl_add_u64 v[18:19], v[168:169], 0, s[0:1]
	v_lshl_add_u64 v[20:21], v[166:167], 0, s[0:1]
	global_load_dwordx4 v[54:57], v[18:19], off
	global_load_dwordx4 v[58:61], v[20:21], off
	v_lshl_add_u64 v[18:19], v[164:165], 0, s[0:1]
	s_lshl_b32 s0, s7, 16
	s_or_b32 s0, s0, s5
	s_add_u32 s0, s77, s0
	s_addc_u32 s1, s28, 0
	v_lshl_add_u64 v[20:21], s[0:1], 0, v[156:157]
	global_load_dwordx4 v[78:81], v[18:19], off
	global_load_dwordx4 v[82:85], v[20:21], off
	v_lshl_add_u64 v[18:19], s[0:1], 0, v[158:159]
	s_lshl_b32 s0, s8, 8
	s_mov_b32 s1, s61
	v_lshl_add_u64 v[20:21], v[162:163], 0, s[0:1]
	s_or_b32 s48, s6, 0x580
	s_mov_b32 s49, s61
	global_load_dwordx4 v[90:93], v[18:19], off
	global_load_dwordx4 v[86:89], v[20:21], off
	v_lshl_add_u64 v[18:19], v[160:161], 0, s[48:49]
	v_mov_b64_e32 v[20:21], s[80:81]
	v_mad_u64_u32 v[20:21], s[0:1], v18, s19, v[20:21]
	v_mad_i32_i24 v21, v19, s19, v21
	v_lshl_add_u64 v[18:19], v[20:21], 0, s[60:61]
	v_lshl_add_u64 v[18:19], v[18:19], 0, v[196:197]
	s_waitcnt lgkmcnt(7)
	v_pk_fma_f32 v[110:111], v[130:131], v[110:111], v[114:115]
	v_add_co_u32_e64 v24, s[44:45], s14, v18
	v_lshl_add_u64 v[114:115], v[152:153], 0, s[52:53]
	v_cvt_pk_bf16_f32 v110, v110, v110
	v_lshl_add_u64 v[22:23], v[18:19], 0, s[20:21]
	v_addc_co_u32_e64 v25, s[44:45], 0, v19, s[44:45]
	v_pk_fma_f32 v[112:113], v[132:133], v[112:113], v[116:117]
	v_lshlrev_b64 v[114:115], 12, v[114:115]
	v_and_b32_e32 v110, 0xffff, v110
	global_load_dwordx4 v[26:29], v[22:23], off offset:64
	global_load_dwordx4 v[18:21], v[22:23], off offset:128
	global_load_dwordx4 v[42:45], v[24:25], off offset:1024
	s_nop 0
	global_load_dwordx4 v[22:25], v[22:23], off offset:192
	v_lshl_add_u64 v[114:115], v[154:155], 0, v[114:115]
	global_store_short v[114:115], v110, off
	v_cvt_pk_bf16_f32 v110, v111, v111
	v_cvt_pk_bf16_f32 v112, v112, v112
	v_lshl_add_u64 v[116:117], v[114:115], 0, s[86:87]
	v_and_b32_e32 v110, 0xffff, v110
	global_store_short v[116:117], v110, off
	v_and_b32_e32 v112, 0xffff, v112
	v_lshl_add_u64 v[110:111], v[114:115], 0, s[74:75]
	global_store_short v[110:111], v112, off
	v_cvt_pk_bf16_f32 v112, v113, v113
	v_pk_fma_f32 v[118:119], v[130:131], v[118:119], v[122:123]
	v_and_b32_e32 v112, 0xffff, v112
	v_lshl_add_u64 v[110:111], v[114:115], 0, s[66:67]
	global_store_short v[110:111], v112, off
	v_cvt_pk_bf16_f32 v112, v118, v118
	v_and_b32_e32 v112, 0xffff, v112
	v_lshl_add_u64 v[110:111], v[114:115], 0, 32
	global_store_short v[110:111], v112, off
	v_cvt_pk_bf16_f32 v112, v119, v119
	v_pk_fma_f32 v[120:121], v[132:133], v[120:121], v[124:125]
	v_and_b32_e32 v112, 0xffff, v112
	v_lshl_add_u64 v[110:111], v[114:115], 0, s[22:23]
	global_store_short v[110:111], v112, off
	v_cvt_pk_bf16_f32 v112, v120, v120
	v_and_b32_e32 v112, 0xffff, v112
	v_lshl_add_u64 v[110:111], v[114:115], 0, s[12:13]
	global_store_short v[110:111], v112, off
	v_cvt_pk_bf16_f32 v112, v121, v121
	v_lshl_add_u64 v[110:111], v[114:115], 0, s[56:57]
	v_and_b32_e32 v112, 0xffff, v112
	global_store_short v[110:111], v112, off
	s_waitcnt lgkmcnt(0)
	s_barrier
	ds_read_b128 v[110:113], v189
	ds_read_b128 v[114:117], v189 offset:64
	ds_read_b128 v[206:209], v189 offset:128
	ds_read_b128 v[122:125], v150
	ds_read_b128 v[210:213], v189 offset:192
	ds_read_b128 v[118:121], v186 offset:10240
	ds_read_b128 v[130:133], v150 offset:64
	ds_read_b128 v[214:217], v186 offset:10304
	ds_read_b128 v[218:221], v189 offset:4608
	ds_read_b128 v[222:225], v189 offset:4672
	s_waitcnt vmcnt(21) lgkmcnt(9)
	v_mfma_f32_16x16x32_bf16 v[110:113], v[46:49], v[110:113], 0
	s_waitcnt lgkmcnt(8)
	v_mfma_f32_16x16x32_bf16 v[110:113], v[30:33], v[114:117], v[110:113]
	s_nop 0
	s_nop 0
	s_waitcnt lgkmcnt(7)
	v_mfma_f32_16x16x32_bf16 v[110:113], v[2:5], v[206:209], v[110:113]
	ds_read_b128 v[206:209], v189 offset:4736
	s_nop 0
	s_nop 0
	s_nop 0
	s_waitcnt vmcnt(20) lgkmcnt(6)
	v_mfma_f32_16x16x32_bf16 v[110:113], v[6:9], v[210:213], v[110:113]
	ds_read_b128 v[210:213], v189 offset:4800
	s_waitcnt lgkmcnt(6)
	v_mfma_f32_16x16x32_bf16 v[114:117], v[122:125], v[118:121], 0
	s_nop 0
	s_waitcnt lgkmcnt(4)
	v_mfma_f32_16x16x32_bf16 v[114:117], v[130:133], v[214:217], v[114:117]
	ds_read_b128 v[214:217], v186 offset:12800
	s_nop 0
	s_waitcnt lgkmcnt(4)
	v_mfma_f32_16x16x32_bf16 v[46:49], v[46:49], v[218:221], 0
	ds_read_b128 v[218:221], v186 offset:12864
	s_nop 0
	s_waitcnt lgkmcnt(4)
	v_mfma_f32_16x16x32_bf16 v[30:33], v[30:33], v[222:225], v[46:49]
	ds_read_b128 v[222:225], v180 offset:30720
	ds_read_b32 v138, v197 offset:51452
	s_nop 4
	s_nop 0
	s_waitcnt lgkmcnt(5)
	v_mfma_f32_16x16x32_bf16 v[2:5], v[2:5], v[206:209], v[30:33]
	ds_read_b128 v[46:49], v179 offset:20480
	ds_read_b128 v[134:137], v180 offset:30784
	ds_read_b128 v[206:209], v179 offset:23040
	s_nop 2
	s_nop 0
	s_waitcnt lgkmcnt(7)
	v_mfma_f32_16x16x32_bf16 v[118:121], v[6:9], v[210:213], v[2:5]
	ds_read_b128 v[210:213], v179 offset:25600
	s_nop 2
	s_nop 0
	s_nop 0
	s_nop 0
	s_nop 0
	s_nop 0
	s_nop 0
	s_waitcnt lgkmcnt(7)
	v_mfma_f32_16x16x32_bf16 v[2:5], v[122:125], v[214:217], 0
	ds_read_b128 v[214:217], v179 offset:28160
	s_waitcnt lgkmcnt(7)
	v_mfma_f32_16x16x32_bf16 v[122:125], v[130:133], v[218:221], v[2:5]
	ds_read_b128 v[218:221], v179 offset:20544
	s_nop 0
	s_waitcnt lgkmcnt(6)
	s_nop 3
	v_pk_mul_f32 v[4:5], v[108:109], v[138:139] op_sel_hi:[1,0]
	v_pk_mul_f32 v[2:3], v[106:107], v[138:139] op_sel_hi:[1,0]
	s_waitcnt lgkmcnt(5)
	s_nop 0
	v_mfma_f32_16x16x32_bf16 v[2:5], v[222:225], v[46:49], v[2:5]
	v_mul_f32_e64 v48, v104, v138
	v_mul_f32_e64 v49, v105, v138
	v_pk_mul_f32 v[46:47], v[102:103], v[138:139] op_sel_hi:[1,0]
	s_nop 0
	s_waitcnt lgkmcnt(3)
	v_mfma_f32_16x16x32_bf16 v[6:9], v[222:225], v[206:209], v[46:49]
	ds_read_b128 v[206:209], v179 offset:23104
	s_nop 2
	v_mul_f32_e64 v48, v100, v138
	v_mul_f32_e64 v49, v101, v138
	v_pk_mul_f32 v[46:47], v[98:99], v[138:139] op_sel_hi:[1,0]
	s_nop 0
	s_waitcnt lgkmcnt(3)
	v_mfma_f32_16x16x32_bf16 v[46:49], v[222:225], v[210:213], v[46:49]
	v_mul_f32_e64 v104, v128, v138
	v_mul_f32_e64 v105, v129, v138
	v_pk_mul_f32 v[102:103], v[126:127], v[138:139] op_sel_hi:[1,0]
	ds_read_b128 v[210:213], v179 offset:25664
	s_waitcnt lgkmcnt(3)
	s_nop 0
	v_mfma_f32_16x16x32_bf16 v[30:33], v[222:225], v[214:217], v[102:105]
	ds_read_b128 v[214:217], v179 offset:28224
	ds_read_b128 v[130:133], v176 offset:51200
	s_nop 0
	s_waitcnt lgkmcnt(4)
	v_mfma_f32_16x16x32_bf16 v[106:109], v[134:137], v[218:221], v[2:5]
	s_nop 2
	s_nop 0
	s_waitcnt lgkmcnt(3)
	v_mfma_f32_16x16x32_bf16 v[102:105], v[134:137], v[206:209], v[6:9]
	s_nop 0
	s_waitcnt lgkmcnt(2)
	v_mfma_f32_16x16x32_bf16 v[98:101], v[134:137], v[210:213], v[46:49]
	s_nop 0
	s_nop 0
	s_waitcnt lgkmcnt(1)
	v_mfma_f32_16x16x32_bf16 v[126:129], v[134:137], v[214:217], v[30:33]
	v_cvt_pk_bf16_f32 v2, v106, v107
	v_cvt_pk_bf16_f32 v3, v108, v109
	v_cvt_pk_bf16_f32 v4, v102, v103
	v_cvt_pk_bf16_f32 v5, v104, v105
	ds_write2st64_b64 v174, v[2:3], v[4:5] offset1:9
	v_cvt_pk_bf16_f32 v2, v98, v99
	v_cvt_pk_bf16_f32 v3, v100, v101
	s_nop 0
	v_cvt_pk_bf16_f32 v4, v126, v127
	v_cvt_pk_bf16_f32 v5, v128, v129
	ds_write2st64_b64 v174, v[2:3], v[4:5] offset0:18 offset1:27
	s_waitcnt vmcnt(19)
	ds_write_b128 v171, v[50:53] offset:51456
	s_waitcnt vmcnt(18)
	ds_write_b128 v171, v[62:65] offset:61696
	s_waitcnt vmcnt(17)
	ds_write_b128 v172, v[66:69]
	s_waitcnt vmcnt(16)
	ds_write_b128 v173, v[70:73]
	s_waitcnt vmcnt(15)
	ds_write_b128 v175, v[94:97]
	s_and_saveexec_b64 s[8:9], vcc
	s_cbranch_execz .LBB0_1589
	s_waitcnt vmcnt(14)
	ds_write_b128 v185, v[74:77]
.LBB0_1589:
	s_or_b64 exec, exec, s[8:9]
	s_or_b32 s7, s34, 23
	s_lshl_b32 s0, s7, 5
	s_or_b32 s8, s0, s78
	s_lshl_b32 s0, s8, 13
	s_mov_b32 s1, s61
	v_lshl_add_u64 v[2:3], v[168:169], 0, s[0:1]
	v_lshl_add_u64 v[4:5], v[166:167], 0, s[0:1]
	global_load_dwordx4 v[50:53], v[2:3], off
	global_load_dwordx4 v[62:65], v[4:5], off
	v_lshl_add_u64 v[2:3], v[164:165], 0, s[0:1]
	s_lshl_b32 s0, s7, 16
	s_or_b32 s0, s0, s5
	s_add_u32 s0, s77, s0
	s_addc_u32 s1, s28, 0
	v_lshl_add_u64 v[4:5], s[0:1], 0, v[156:157]
	global_load_dwordx4 v[66:69], v[2:3], off
	global_load_dwordx4 v[70:73], v[4:5], off
	v_lshl_add_u64 v[2:3], s[0:1], 0, v[158:159]
	s_lshl_b32 s0, s8, 8
	s_mov_b32 s1, s61
	v_lshl_add_u64 v[4:5], v[162:163], 0, s[0:1]
	s_or_b32 s52, s6, 0x5c0
	s_mov_b32 s53, s61
	global_load_dwordx4 v[94:97], v[2:3], off
	global_load_dwordx4 v[74:77], v[4:5], off
	v_lshl_add_u64 v[2:3], v[160:161], 0, s[52:53]
	v_mov_b64_e32 v[4:5], s[80:81]
	v_mad_u64_u32 v[4:5], s[0:1], v2, s19, v[4:5]
	v_mad_i32_i24 v5, v3, s19, v5
	v_lshl_add_u64 v[2:3], v[4:5], 0, s[60:61]
	v_lshl_add_u64 v[2:3], v[2:3], 0, v[196:197]
	s_waitcnt lgkmcnt(7)
	v_pk_fma_f32 v[110:111], v[130:131], v[110:111], v[114:115]
	v_add_co_u32_e64 v8, s[44:45], s14, v2
	v_lshl_add_u64 v[114:115], v[152:153], 0, s[46:47]
	v_cvt_pk_bf16_f32 v110, v110, v110
	v_lshl_add_u64 v[6:7], v[2:3], 0, s[20:21]
	v_addc_co_u32_e64 v9, s[44:45], 0, v3, s[44:45]
	v_pk_fma_f32 v[112:113], v[132:133], v[112:113], v[116:117]
	v_lshlrev_b64 v[114:115], 12, v[114:115]
	v_and_b32_e32 v110, 0xffff, v110
	global_load_dwordx4 v[30:33], v[6:7], off offset:64
	global_load_dwordx4 v[2:5], v[6:7], off offset:128
	global_load_dwordx4 v[46:49], v[8:9], off offset:1024
	s_nop 0
	global_load_dwordx4 v[6:9], v[6:7], off offset:192
	v_lshl_add_u64 v[114:115], v[154:155], 0, v[114:115]
	global_store_short v[114:115], v110, off
	v_cvt_pk_bf16_f32 v110, v111, v111
	v_cvt_pk_bf16_f32 v112, v112, v112
	v_lshl_add_u64 v[116:117], v[114:115], 0, s[86:87]
	v_and_b32_e32 v110, 0xffff, v110
	global_store_short v[116:117], v110, off
	v_and_b32_e32 v112, 0xffff, v112
	v_lshl_add_u64 v[110:111], v[114:115], 0, s[74:75]
	global_store_short v[110:111], v112, off
	v_cvt_pk_bf16_f32 v112, v113, v113
	v_pk_fma_f32 v[118:119], v[130:131], v[118:119], v[122:123]
	v_and_b32_e32 v112, 0xffff, v112
	v_lshl_add_u64 v[110:111], v[114:115], 0, s[66:67]
	global_store_short v[110:111], v112, off
	v_cvt_pk_bf16_f32 v112, v118, v118
	v_and_b32_e32 v112, 0xffff, v112
	v_lshl_add_u64 v[110:111], v[114:115], 0, 32
	global_store_short v[110:111], v112, off
	v_cvt_pk_bf16_f32 v112, v119, v119
	v_pk_fma_f32 v[120:121], v[132:133], v[120:121], v[124:125]
	v_and_b32_e32 v112, 0xffff, v112
	v_lshl_add_u64 v[110:111], v[114:115], 0, s[22:23]
	global_store_short v[110:111], v112, off
	v_cvt_pk_bf16_f32 v112, v120, v120
	v_and_b32_e32 v112, 0xffff, v112
	v_lshl_add_u64 v[110:111], v[114:115], 0, s[12:13]
	global_store_short v[110:111], v112, off
	v_cvt_pk_bf16_f32 v112, v121, v121
	v_lshl_add_u64 v[110:111], v[114:115], 0, s[56:57]
	v_and_b32_e32 v112, 0xffff, v112
	global_store_short v[110:111], v112, off
	s_waitcnt lgkmcnt(0)
	s_barrier
	ds_read_b128 v[110:113], v188
	ds_read_b128 v[114:117], v188 offset:64
	ds_read_b128 v[206:209], v188 offset:128
	ds_read_b128 v[122:125], v150 offset:51456
	ds_read_b128 v[210:213], v188 offset:192
	ds_read_b128 v[118:121], v186 offset:61696
	ds_read_b128 v[130:133], v150 offset:51520
	ds_read_b128 v[214:217], v186 offset:61760
	ds_read_b128 v[218:221], v188 offset:4608
	ds_read_b128 v[222:225], v188 offset:4672
	s_waitcnt vmcnt(21) lgkmcnt(9)
	v_mfma_f32_16x16x32_bf16 v[110:113], v[38:41], v[110:113], 0
	v_readlane_b32 s0, v253, 18
	s_waitcnt lgkmcnt(8)
	v_mfma_f32_16x16x32_bf16 v[110:113], v[34:37], v[114:117], v[110:113]
	s_nop 0
	s_nop 0
	s_waitcnt lgkmcnt(7)
	v_mfma_f32_16x16x32_bf16 v[110:113], v[10:13], v[206:209], v[110:113]
	ds_read_b128 v[206:209], v188 offset:4736
	s_nop 0
	s_nop 0
	s_nop 0
	s_waitcnt vmcnt(20) lgkmcnt(6)
	v_mfma_f32_16x16x32_bf16 v[110:113], v[14:17], v[210:213], v[110:113]
	ds_read_b128 v[210:213], v188 offset:4800
	s_waitcnt lgkmcnt(6)
	v_mfma_f32_16x16x32_bf16 v[114:117], v[122:125], v[118:121], 0
	s_nop 0
	s_waitcnt lgkmcnt(4)
	v_mfma_f32_16x16x32_bf16 v[114:117], v[130:133], v[214:217], v[114:117]
	ds_read_b128 v[214:217], v186 offset:64256
	s_nop 0
	s_waitcnt lgkmcnt(4)
	v_mfma_f32_16x16x32_bf16 v[38:41], v[38:41], v[218:221], 0
	ds_read_b128 v[218:221], v186 offset:64320
	s_nop 0
	s_waitcnt lgkmcnt(4)
	v_mfma_f32_16x16x32_bf16 v[34:37], v[34:37], v[222:225], v[38:41]
	ds_read_b128 v[222:225], v183
	s_nop 4
	s_nop 0
	s_waitcnt lgkmcnt(4)
	v_mfma_f32_16x16x32_bf16 v[10:13], v[10:13], v[206:209], v[34:37]
	s_nop 2
	s_nop 0
	v_mov_b32_e32 v38, s0
	ds_read_b32 v138, v38
	ds_read_b128 v[206:209], v184
	ds_read_b128 v[134:137], v183 offset:64
	s_waitcnt lgkmcnt(6)
	v_mfma_f32_16x16x32_bf16 v[118:121], v[14:17], v[210:213], v[10:13]
	ds_read_b128 v[210:213], v184 offset:2560
	s_nop 2
	s_nop 0
	s_nop 0
	s_nop 0
	s_nop 0
	s_nop 0
	s_nop 0
	s_waitcnt lgkmcnt(6)
	v_mfma_f32_16x16x32_bf16 v[10:13], v[122:125], v[214:217], 0
	ds_read_b128 v[214:217], v184 offset:5120
	s_waitcnt lgkmcnt(6)
	v_mfma_f32_16x16x32_bf16 v[122:125], v[130:133], v[218:221], v[10:13]
	ds_read_b128 v[218:221], v184 offset:7680
	s_nop 0
	s_waitcnt lgkmcnt(5)
	s_nop 3
	v_pk_mul_f32 v[12:13], v[108:109], v[138:139] op_sel_hi:[1,0]
	v_pk_mul_f32 v[10:11], v[106:107], v[138:139] op_sel_hi:[1,0]
	s_waitcnt lgkmcnt(4)
	s_nop 0
	v_mfma_f32_16x16x32_bf16 v[10:13], v[222:225], v[206:209], v[10:13]
	v_mul_f32_e64 v40, v104, v138
	v_mul_f32_e64 v41, v105, v138
	v_pk_mul_f32 v[38:39], v[102:103], v[138:139] op_sel_hi:[1,0]
	ds_read_b128 v[206:209], v182
	s_nop 0
	s_waitcnt lgkmcnt(3)
	v_mfma_f32_16x16x32_bf16 v[14:17], v[222:225], v[210:213], v[38:41]
	ds_read_b128 v[210:213], v182 offset:2560
	s_nop 2
	v_mul_f32_e64 v40, v100, v138
	v_mul_f32_e64 v41, v101, v138
	v_pk_mul_f32 v[38:39], v[98:99], v[138:139] op_sel_hi:[1,0]
	s_nop 0
	s_waitcnt lgkmcnt(3)
	v_mfma_f32_16x16x32_bf16 v[38:41], v[222:225], v[214:217], v[38:41]
	v_mul_f32_e64 v104, v128, v138
	v_mul_f32_e64 v105, v129, v138
	v_pk_mul_f32 v[102:103], v[126:127], v[138:139] op_sel_hi:[1,0]
	ds_read_b128 v[214:217], v182 offset:5120
	s_waitcnt lgkmcnt(3)
	s_nop 0
	v_mfma_f32_16x16x32_bf16 v[34:37], v[222:225], v[218:221], v[102:105]
	ds_read_b128 v[218:221], v182 offset:7680
	ds_read_b128 v[130:133], v181
	s_nop 0
	s_waitcnt lgkmcnt(4)
	v_mfma_f32_16x16x32_bf16 v[106:109], v[134:137], v[206:209], v[10:13]
	s_nop 2
	s_nop 0
	s_waitcnt lgkmcnt(3)
	v_mfma_f32_16x16x32_bf16 v[102:105], v[134:137], v[210:213], v[14:17]
	s_nop 0
	s_waitcnt lgkmcnt(2)
	v_mfma_f32_16x16x32_bf16 v[98:101], v[134:137], v[214:217], v[38:41]
	s_nop 0
	s_nop 0
	s_waitcnt lgkmcnt(1)
	v_mfma_f32_16x16x32_bf16 v[126:129], v[134:137], v[218:221], v[34:37]
	v_cvt_pk_bf16_f32 v10, v106, v107
	v_cvt_pk_bf16_f32 v11, v108, v109
	v_cvt_pk_bf16_f32 v12, v102, v103
	v_cvt_pk_bf16_f32 v13, v104, v105
	ds_write2st64_b64 v187, v[10:11], v[12:13] offset1:9
	v_cvt_pk_bf16_f32 v10, v98, v99
	v_cvt_pk_bf16_f32 v11, v100, v101
	s_nop 0
	v_cvt_pk_bf16_f32 v12, v126, v127
	v_cvt_pk_bf16_f32 v13, v128, v129
	ds_write2st64_b64 v187, v[10:11], v[12:13] offset0:18 offset1:27
	s_waitcnt vmcnt(19)
	ds_write_b128 v171, v[54:57]
	s_waitcnt vmcnt(18)
	ds_write_b128 v171, v[58:61] offset:10240
	s_waitcnt vmcnt(17)
	ds_write_b128 v171, v[78:81] offset:20480
	s_waitcnt vmcnt(16)
	ds_write_b128 v171, v[82:85] offset:30720
	s_waitcnt vmcnt(15)
	ds_write_b128 v178, v[90:93] offset:30720
	s_and_saveexec_b64 s[8:9], vcc
	s_cbranch_execz .LBB0_1591
	s_waitcnt vmcnt(14)
	ds_write_b128 v177, v[86:89] offset:51200
.LBB0_1591:
	s_or_b64 exec, exec, s[8:9]
	s_or_b32 s7, s34, 24
	s_lshl_b32 s0, s7, 5
	s_or_b32 s8, s0, s78
	s_lshl_b32 s0, s8, 13
	s_mov_b32 s1, s61
	v_lshl_add_u64 v[10:11], v[168:169], 0, s[0:1]
	v_lshl_add_u64 v[12:13], v[166:167], 0, s[0:1]
	global_load_dwordx4 v[54:57], v[10:11], off
	global_load_dwordx4 v[58:61], v[12:13], off
	v_lshl_add_u64 v[10:11], v[164:165], 0, s[0:1]
	s_lshl_b32 s0, s7, 16
	s_or_b32 s0, s0, s5
	s_add_u32 s0, s77, s0
	s_addc_u32 s1, s28, 0
	v_lshl_add_u64 v[12:13], s[0:1], 0, v[156:157]
	global_load_dwordx4 v[78:81], v[10:11], off
	global_load_dwordx4 v[82:85], v[12:13], off
	v_lshl_add_u64 v[10:11], s[0:1], 0, v[158:159]
	s_lshl_b32 s0, s8, 8
	s_mov_b32 s1, s61
	v_lshl_add_u64 v[12:13], v[162:163], 0, s[0:1]
	s_or_b32 s46, s6, 0x600
	s_mov_b32 s47, s61
	global_load_dwordx4 v[90:93], v[10:11], off
	global_load_dwordx4 v[86:89], v[12:13], off
	v_lshl_add_u64 v[10:11], v[160:161], 0, s[46:47]
	v_mov_b64_e32 v[12:13], s[80:81]
	v_mad_u64_u32 v[12:13], s[0:1], v10, s19, v[12:13]
	v_mad_i32_i24 v13, v11, s19, v13
	v_lshl_add_u64 v[10:11], v[12:13], 0, s[60:61]
	v_lshl_add_u64 v[10:11], v[10:11], 0, v[196:197]
	s_waitcnt lgkmcnt(7)
	v_pk_fma_f32 v[110:111], v[130:131], v[110:111], v[114:115]
	v_add_co_u32_e64 v16, s[44:45], s14, v10
	v_lshl_add_u64 v[114:115], v[152:153], 0, s[50:51]
	v_cvt_pk_bf16_f32 v110, v110, v110
	v_lshl_add_u64 v[14:15], v[10:11], 0, s[20:21]
	v_addc_co_u32_e64 v17, s[44:45], 0, v11, s[44:45]
	v_pk_fma_f32 v[112:113], v[132:133], v[112:113], v[116:117]
	v_lshlrev_b64 v[114:115], 12, v[114:115]
	v_and_b32_e32 v110, 0xffff, v110
	global_load_dwordx4 v[34:37], v[14:15], off offset:64
	global_load_dwordx4 v[10:13], v[14:15], off offset:128
	global_load_dwordx4 v[38:41], v[16:17], off offset:1024
	s_nop 0
	global_load_dwordx4 v[14:17], v[14:15], off offset:192
	v_lshl_add_u64 v[114:115], v[154:155], 0, v[114:115]
	global_store_short v[114:115], v110, off
	v_cvt_pk_bf16_f32 v110, v111, v111
	v_cvt_pk_bf16_f32 v112, v112, v112
	v_lshl_add_u64 v[116:117], v[114:115], 0, s[86:87]
	v_and_b32_e32 v110, 0xffff, v110
	global_store_short v[116:117], v110, off
	v_and_b32_e32 v112, 0xffff, v112
	v_lshl_add_u64 v[110:111], v[114:115], 0, s[74:75]
	global_store_short v[110:111], v112, off
	v_cvt_pk_bf16_f32 v112, v113, v113
	v_pk_fma_f32 v[118:119], v[130:131], v[118:119], v[122:123]
	v_and_b32_e32 v112, 0xffff, v112
	v_lshl_add_u64 v[110:111], v[114:115], 0, s[66:67]
	global_store_short v[110:111], v112, off
	v_cvt_pk_bf16_f32 v112, v118, v118
	v_and_b32_e32 v112, 0xffff, v112
	v_lshl_add_u64 v[110:111], v[114:115], 0, 32
	global_store_short v[110:111], v112, off
	v_cvt_pk_bf16_f32 v112, v119, v119
	v_pk_fma_f32 v[120:121], v[132:133], v[120:121], v[124:125]
	v_and_b32_e32 v112, 0xffff, v112
	v_lshl_add_u64 v[110:111], v[114:115], 0, s[22:23]
	global_store_short v[110:111], v112, off
	v_cvt_pk_bf16_f32 v112, v120, v120
	v_and_b32_e32 v112, 0xffff, v112
	v_lshl_add_u64 v[110:111], v[114:115], 0, s[12:13]
	global_store_short v[110:111], v112, off
	v_cvt_pk_bf16_f32 v112, v121, v121
	v_lshl_add_u64 v[110:111], v[114:115], 0, s[56:57]
	v_and_b32_e32 v112, 0xffff, v112
	global_store_short v[110:111], v112, off
	s_waitcnt lgkmcnt(0)
	s_barrier
	ds_read_b128 v[110:113], v189
	ds_read_b128 v[114:117], v189 offset:64
	ds_read_b128 v[206:209], v189 offset:128
	ds_read_b128 v[122:125], v150
	ds_read_b128 v[210:213], v189 offset:192
	ds_read_b128 v[118:121], v186 offset:10240
	ds_read_b128 v[130:133], v150 offset:64
	ds_read_b128 v[214:217], v186 offset:10304
	ds_read_b128 v[218:221], v189 offset:4608
	ds_read_b128 v[222:225], v189 offset:4672
	s_waitcnt vmcnt(21) lgkmcnt(9)
	v_mfma_f32_16x16x32_bf16 v[110:113], v[42:45], v[110:113], 0
	s_waitcnt lgkmcnt(8)
	v_mfma_f32_16x16x32_bf16 v[110:113], v[26:29], v[114:117], v[110:113]
	s_nop 0
	s_nop 0
	s_waitcnt lgkmcnt(7)
	v_mfma_f32_16x16x32_bf16 v[110:113], v[18:21], v[206:209], v[110:113]
	ds_read_b128 v[206:209], v189 offset:4736
	s_nop 0
	s_nop 0
	s_nop 0
	s_waitcnt vmcnt(20) lgkmcnt(6)
	v_mfma_f32_16x16x32_bf16 v[110:113], v[22:25], v[210:213], v[110:113]
	ds_read_b128 v[210:213], v189 offset:4800
	s_waitcnt lgkmcnt(6)
	v_mfma_f32_16x16x32_bf16 v[114:117], v[122:125], v[118:121], 0
	s_nop 0
	s_waitcnt lgkmcnt(4)
	v_mfma_f32_16x16x32_bf16 v[114:117], v[130:133], v[214:217], v[114:117]
	ds_read_b128 v[214:217], v186 offset:12800
	s_nop 0
	s_waitcnt lgkmcnt(4)
	v_mfma_f32_16x16x32_bf16 v[42:45], v[42:45], v[218:221], 0
	ds_read_b128 v[218:221], v186 offset:12864
	s_nop 0
	s_waitcnt lgkmcnt(4)
	v_mfma_f32_16x16x32_bf16 v[26:29], v[26:29], v[222:225], v[42:45]
	ds_read_b128 v[222:225], v180 offset:30720
	ds_read_b32 v138, v197 offset:51452
	s_nop 4
	s_nop 0
	s_waitcnt lgkmcnt(5)
	v_mfma_f32_16x16x32_bf16 v[18:21], v[18:21], v[206:209], v[26:29]
	ds_read_b128 v[42:45], v179 offset:20480
	ds_read_b128 v[134:137], v180 offset:30784
	ds_read_b128 v[206:209], v179 offset:23040
	s_nop 2
	s_nop 0
	s_waitcnt lgkmcnt(7)
	v_mfma_f32_16x16x32_bf16 v[118:121], v[22:25], v[210:213], v[18:21]
	ds_read_b128 v[210:213], v179 offset:25600
	s_nop 2
	s_nop 0
	s_nop 0
	s_nop 0
	s_nop 0
	s_nop 0
	s_nop 0
	s_waitcnt lgkmcnt(7)
	v_mfma_f32_16x16x32_bf16 v[18:21], v[122:125], v[214:217], 0
	ds_read_b128 v[214:217], v179 offset:28160
	s_waitcnt lgkmcnt(7)
	v_mfma_f32_16x16x32_bf16 v[122:125], v[130:133], v[218:221], v[18:21]
	ds_read_b128 v[218:221], v179 offset:20544
	s_nop 0
	s_waitcnt lgkmcnt(6)
	s_nop 3
	v_pk_mul_f32 v[20:21], v[108:109], v[138:139] op_sel_hi:[1,0]
	v_pk_mul_f32 v[18:19], v[106:107], v[138:139] op_sel_hi:[1,0]
	s_waitcnt lgkmcnt(5)
	s_nop 0
	v_mfma_f32_16x16x32_bf16 v[18:21], v[222:225], v[42:45], v[18:21]
	v_mul_f32_e64 v44, v104, v138
	v_mul_f32_e64 v45, v105, v138
	v_pk_mul_f32 v[42:43], v[102:103], v[138:139] op_sel_hi:[1,0]
	s_nop 0
	s_waitcnt lgkmcnt(3)
	v_mfma_f32_16x16x32_bf16 v[22:25], v[222:225], v[206:209], v[42:45]
	ds_read_b128 v[206:209], v179 offset:23104
	s_nop 2
	v_mul_f32_e64 v44, v100, v138
	v_mul_f32_e64 v45, v101, v138
	v_pk_mul_f32 v[42:43], v[98:99], v[138:139] op_sel_hi:[1,0]
	s_nop 0
	s_waitcnt lgkmcnt(3)
	v_mfma_f32_16x16x32_bf16 v[42:45], v[222:225], v[210:213], v[42:45]
	v_mul_f32_e64 v104, v128, v138
	v_mul_f32_e64 v105, v129, v138
	v_pk_mul_f32 v[102:103], v[126:127], v[138:139] op_sel_hi:[1,0]
	ds_read_b128 v[210:213], v179 offset:25664
	s_waitcnt lgkmcnt(3)
	s_nop 0
	v_mfma_f32_16x16x32_bf16 v[26:29], v[222:225], v[214:217], v[102:105]
	ds_read_b128 v[214:217], v179 offset:28224
	ds_read_b128 v[130:133], v176 offset:51200
	s_nop 0
	s_waitcnt lgkmcnt(4)
	v_mfma_f32_16x16x32_bf16 v[106:109], v[134:137], v[218:221], v[18:21]
	s_nop 2
	s_nop 0
	s_waitcnt lgkmcnt(3)
	v_mfma_f32_16x16x32_bf16 v[102:105], v[134:137], v[206:209], v[22:25]
	s_nop 0
	s_waitcnt lgkmcnt(2)
	v_mfma_f32_16x16x32_bf16 v[98:101], v[134:137], v[210:213], v[42:45]
	s_nop 0
	s_nop 0
	s_waitcnt lgkmcnt(1)
	v_mfma_f32_16x16x32_bf16 v[126:129], v[134:137], v[214:217], v[26:29]
	v_cvt_pk_bf16_f32 v18, v106, v107
	v_cvt_pk_bf16_f32 v19, v108, v109
	v_cvt_pk_bf16_f32 v20, v102, v103
	v_cvt_pk_bf16_f32 v21, v104, v105
	ds_write2st64_b64 v174, v[18:19], v[20:21] offset1:9
	v_cvt_pk_bf16_f32 v18, v98, v99
	v_cvt_pk_bf16_f32 v19, v100, v101
	s_nop 0
	v_cvt_pk_bf16_f32 v20, v126, v127
	v_cvt_pk_bf16_f32 v21, v128, v129
	ds_write2st64_b64 v174, v[18:19], v[20:21] offset0:18 offset1:27
	s_waitcnt vmcnt(19)
	ds_write_b128 v171, v[50:53] offset:51456
	s_waitcnt vmcnt(18)
	ds_write_b128 v171, v[62:65] offset:61696
	s_waitcnt vmcnt(17)
	ds_write_b128 v172, v[66:69]
	s_waitcnt vmcnt(16)
	ds_write_b128 v173, v[70:73]
	s_waitcnt vmcnt(15)
	ds_write_b128 v175, v[94:97]
	s_and_saveexec_b64 s[8:9], vcc
	s_cbranch_execz .LBB0_1593
	s_waitcnt vmcnt(14)
	ds_write_b128 v185, v[74:77]
.LBB0_1593:
	s_or_b64 exec, exec, s[8:9]
	s_or_b32 s7, s34, 25
	s_lshl_b32 s0, s7, 5
	s_or_b32 s8, s0, s78
	s_lshl_b32 s0, s8, 13
	s_mov_b32 s1, s61
	v_lshl_add_u64 v[18:19], v[168:169], 0, s[0:1]
	v_lshl_add_u64 v[20:21], v[166:167], 0, s[0:1]
	global_load_dwordx4 v[50:53], v[18:19], off
	global_load_dwordx4 v[62:65], v[20:21], off
	v_lshl_add_u64 v[18:19], v[164:165], 0, s[0:1]
	s_lshl_b32 s0, s7, 16
	s_or_b32 s0, s0, s5
	s_add_u32 s0, s77, s0
	s_addc_u32 s1, s28, 0
	v_lshl_add_u64 v[20:21], s[0:1], 0, v[156:157]
	global_load_dwordx4 v[66:69], v[18:19], off
	global_load_dwordx4 v[70:73], v[20:21], off
	v_lshl_add_u64 v[18:19], s[0:1], 0, v[158:159]
	s_lshl_b32 s0, s8, 8
	s_mov_b32 s1, s61
	v_lshl_add_u64 v[20:21], v[162:163], 0, s[0:1]
	s_or_b32 s50, s6, 0x640
	s_mov_b32 s51, s61
	global_load_dwordx4 v[94:97], v[18:19], off
	global_load_dwordx4 v[74:77], v[20:21], off
	v_lshl_add_u64 v[18:19], v[160:161], 0, s[50:51]
	v_mov_b64_e32 v[20:21], s[80:81]
	v_mad_u64_u32 v[20:21], s[0:1], v18, s19, v[20:21]
	v_mad_i32_i24 v21, v19, s19, v21
	v_lshl_add_u64 v[18:19], v[20:21], 0, s[60:61]
	v_lshl_add_u64 v[18:19], v[18:19], 0, v[196:197]
	s_waitcnt lgkmcnt(7)
	v_pk_fma_f32 v[110:111], v[130:131], v[110:111], v[114:115]
	v_add_co_u32_e64 v24, s[44:45], s14, v18
	v_lshl_add_u64 v[114:115], v[152:153], 0, s[48:49]
	v_cvt_pk_bf16_f32 v110, v110, v110
	v_lshl_add_u64 v[22:23], v[18:19], 0, s[20:21]
	v_addc_co_u32_e64 v25, s[44:45], 0, v19, s[44:45]
	v_pk_fma_f32 v[112:113], v[132:133], v[112:113], v[116:117]
	v_lshlrev_b64 v[114:115], 12, v[114:115]
	v_and_b32_e32 v110, 0xffff, v110
	global_load_dwordx4 v[26:29], v[22:23], off offset:64
	global_load_dwordx4 v[18:21], v[22:23], off offset:128
	global_load_dwordx4 v[42:45], v[24:25], off offset:1024
	s_nop 0
	global_load_dwordx4 v[22:25], v[22:23], off offset:192
	v_lshl_add_u64 v[114:115], v[154:155], 0, v[114:115]
	global_store_short v[114:115], v110, off
	v_cvt_pk_bf16_f32 v110, v111, v111
	v_cvt_pk_bf16_f32 v112, v112, v112
	v_lshl_add_u64 v[116:117], v[114:115], 0, s[86:87]
	v_and_b32_e32 v110, 0xffff, v110
	global_store_short v[116:117], v110, off
	v_and_b32_e32 v112, 0xffff, v112
	v_lshl_add_u64 v[110:111], v[114:115], 0, s[74:75]
	global_store_short v[110:111], v112, off
	v_cvt_pk_bf16_f32 v112, v113, v113
	v_pk_fma_f32 v[118:119], v[130:131], v[118:119], v[122:123]
	v_and_b32_e32 v112, 0xffff, v112
	v_lshl_add_u64 v[110:111], v[114:115], 0, s[66:67]
	global_store_short v[110:111], v112, off
	v_cvt_pk_bf16_f32 v112, v118, v118
	v_and_b32_e32 v112, 0xffff, v112
	v_lshl_add_u64 v[110:111], v[114:115], 0, 32
	global_store_short v[110:111], v112, off
	v_cvt_pk_bf16_f32 v112, v119, v119
	v_pk_fma_f32 v[120:121], v[132:133], v[120:121], v[124:125]
	v_and_b32_e32 v112, 0xffff, v112
	v_lshl_add_u64 v[110:111], v[114:115], 0, s[22:23]
	global_store_short v[110:111], v112, off
	v_cvt_pk_bf16_f32 v112, v120, v120
	v_and_b32_e32 v112, 0xffff, v112
	v_lshl_add_u64 v[110:111], v[114:115], 0, s[12:13]
	global_store_short v[110:111], v112, off
	v_cvt_pk_bf16_f32 v112, v121, v121
	v_lshl_add_u64 v[110:111], v[114:115], 0, s[56:57]
	v_and_b32_e32 v112, 0xffff, v112
	global_store_short v[110:111], v112, off
	s_waitcnt lgkmcnt(0)
	s_barrier
	ds_read_b128 v[110:113], v188
	ds_read_b128 v[114:117], v188 offset:64
	ds_read_b128 v[206:209], v188 offset:128
	ds_read_b128 v[122:125], v150 offset:51456
	ds_read_b128 v[210:213], v188 offset:192
	ds_read_b128 v[118:121], v186 offset:61696
	ds_read_b128 v[130:133], v150 offset:51520
	ds_read_b128 v[214:217], v186 offset:61760
	ds_read_b128 v[218:221], v188 offset:4608
	ds_read_b128 v[222:225], v188 offset:4672
	s_waitcnt vmcnt(21) lgkmcnt(9)
	v_mfma_f32_16x16x32_bf16 v[110:113], v[46:49], v[110:113], 0
	v_readlane_b32 s0, v253, 18
	s_waitcnt lgkmcnt(8)
	v_mfma_f32_16x16x32_bf16 v[110:113], v[30:33], v[114:117], v[110:113]
	s_nop 0
	s_nop 0
	s_waitcnt lgkmcnt(7)
	v_mfma_f32_16x16x32_bf16 v[110:113], v[2:5], v[206:209], v[110:113]
	ds_read_b128 v[206:209], v188 offset:4736
	s_nop 0
	s_nop 0
	s_nop 0
	s_waitcnt vmcnt(20) lgkmcnt(6)
	v_mfma_f32_16x16x32_bf16 v[110:113], v[6:9], v[210:213], v[110:113]
	ds_read_b128 v[210:213], v188 offset:4800
	s_waitcnt lgkmcnt(6)
	v_mfma_f32_16x16x32_bf16 v[114:117], v[122:125], v[118:121], 0
	s_nop 0
	s_waitcnt lgkmcnt(4)
	v_mfma_f32_16x16x32_bf16 v[114:117], v[130:133], v[214:217], v[114:117]
	ds_read_b128 v[214:217], v186 offset:64256
	s_nop 0
	s_waitcnt lgkmcnt(4)
	v_mfma_f32_16x16x32_bf16 v[46:49], v[46:49], v[218:221], 0
	ds_read_b128 v[218:221], v186 offset:64320
	s_nop 0
	s_waitcnt lgkmcnt(4)
	v_mfma_f32_16x16x32_bf16 v[30:33], v[30:33], v[222:225], v[46:49]
	ds_read_b128 v[222:225], v183
	s_nop 4
	s_nop 0
	s_waitcnt lgkmcnt(4)
	v_mfma_f32_16x16x32_bf16 v[2:5], v[2:5], v[206:209], v[30:33]
	s_nop 2
	s_nop 0
	v_mov_b32_e32 v46, s0
	ds_read_b32 v138, v46
	ds_read_b128 v[206:209], v184
	ds_read_b128 v[134:137], v183 offset:64
	s_waitcnt lgkmcnt(6)
	v_mfma_f32_16x16x32_bf16 v[118:121], v[6:9], v[210:213], v[2:5]
	ds_read_b128 v[210:213], v184 offset:2560
	s_nop 2
	s_nop 0
	s_nop 0
	s_nop 0
	s_nop 0
	s_nop 0
	s_nop 0
	s_waitcnt lgkmcnt(6)
	v_mfma_f32_16x16x32_bf16 v[2:5], v[122:125], v[214:217], 0
	ds_read_b128 v[214:217], v184 offset:5120
	s_waitcnt lgkmcnt(6)
	v_mfma_f32_16x16x32_bf16 v[122:125], v[130:133], v[218:221], v[2:5]
	ds_read_b128 v[218:221], v184 offset:7680
	s_nop 0
	s_waitcnt lgkmcnt(5)
	s_nop 3
	v_pk_mul_f32 v[4:5], v[108:109], v[138:139] op_sel_hi:[1,0]
	v_pk_mul_f32 v[2:3], v[106:107], v[138:139] op_sel_hi:[1,0]
	s_waitcnt lgkmcnt(4)
	s_nop 0
	v_mfma_f32_16x16x32_bf16 v[2:5], v[222:225], v[206:209], v[2:5]
	v_mul_f32_e64 v48, v104, v138
	v_mul_f32_e64 v49, v105, v138
	v_pk_mul_f32 v[46:47], v[102:103], v[138:139] op_sel_hi:[1,0]
	ds_read_b128 v[206:209], v182
	s_nop 0
	s_waitcnt lgkmcnt(3)
	v_mfma_f32_16x16x32_bf16 v[6:9], v[222:225], v[210:213], v[46:49]
	ds_read_b128 v[210:213], v182 offset:2560
	s_nop 2
	v_mul_f32_e64 v48, v100, v138
	v_mul_f32_e64 v49, v101, v138
	v_pk_mul_f32 v[46:47], v[98:99], v[138:139] op_sel_hi:[1,0]
	s_nop 0
	s_waitcnt lgkmcnt(3)
	v_mfma_f32_16x16x32_bf16 v[46:49], v[222:225], v[214:217], v[46:49]
	v_mul_f32_e64 v104, v128, v138
	v_mul_f32_e64 v105, v129, v138
	v_pk_mul_f32 v[102:103], v[126:127], v[138:139] op_sel_hi:[1,0]
	ds_read_b128 v[214:217], v182 offset:5120
	s_waitcnt lgkmcnt(3)
	s_nop 0
	v_mfma_f32_16x16x32_bf16 v[30:33], v[222:225], v[218:221], v[102:105]
	ds_read_b128 v[218:221], v182 offset:7680
	ds_read_b128 v[130:133], v181
	s_nop 0
	s_waitcnt lgkmcnt(4)
	v_mfma_f32_16x16x32_bf16 v[106:109], v[134:137], v[206:209], v[2:5]
	s_nop 2
	s_nop 0
	s_waitcnt lgkmcnt(3)
	v_mfma_f32_16x16x32_bf16 v[102:105], v[134:137], v[210:213], v[6:9]
	s_nop 0
	s_waitcnt lgkmcnt(2)
	v_mfma_f32_16x16x32_bf16 v[98:101], v[134:137], v[214:217], v[46:49]
	s_nop 0
	s_nop 0
	s_waitcnt lgkmcnt(1)
	v_mfma_f32_16x16x32_bf16 v[126:129], v[134:137], v[218:221], v[30:33]
	v_cvt_pk_bf16_f32 v2, v106, v107
	v_cvt_pk_bf16_f32 v3, v108, v109
	v_cvt_pk_bf16_f32 v4, v102, v103
	v_cvt_pk_bf16_f32 v5, v104, v105
	ds_write2st64_b64 v187, v[2:3], v[4:5] offset1:9
	v_cvt_pk_bf16_f32 v2, v98, v99
	v_cvt_pk_bf16_f32 v3, v100, v101
	s_nop 0
	v_cvt_pk_bf16_f32 v4, v126, v127
	v_cvt_pk_bf16_f32 v5, v128, v129
	ds_write2st64_b64 v187, v[2:3], v[4:5] offset0:18 offset1:27
	s_waitcnt vmcnt(19)
	ds_write_b128 v171, v[54:57]
	s_waitcnt vmcnt(18)
	ds_write_b128 v171, v[58:61] offset:10240
	s_waitcnt vmcnt(17)
	ds_write_b128 v171, v[78:81] offset:20480
	s_waitcnt vmcnt(16)
	ds_write_b128 v171, v[82:85] offset:30720
	s_waitcnt vmcnt(15)
	ds_write_b128 v178, v[90:93] offset:30720
	s_and_saveexec_b64 s[8:9], vcc
	s_cbranch_execz .LBB0_1595
	s_waitcnt vmcnt(14)
	ds_write_b128 v177, v[86:89] offset:51200
.LBB0_1595:
	s_or_b64 exec, exec, s[8:9]
	s_or_b32 s7, s34, 26
	s_lshl_b32 s0, s7, 5
	s_or_b32 s8, s0, s78
	s_lshl_b32 s0, s8, 13
	s_mov_b32 s1, s61
	v_lshl_add_u64 v[2:3], v[168:169], 0, s[0:1]
	v_lshl_add_u64 v[4:5], v[166:167], 0, s[0:1]
	global_load_dwordx4 v[54:57], v[2:3], off
	global_load_dwordx4 v[58:61], v[4:5], off
	v_lshl_add_u64 v[2:3], v[164:165], 0, s[0:1]
	s_lshl_b32 s0, s7, 16
	s_or_b32 s0, s0, s5
	s_add_u32 s0, s77, s0
	s_addc_u32 s1, s28, 0
	v_lshl_add_u64 v[4:5], s[0:1], 0, v[156:157]
	global_load_dwordx4 v[78:81], v[2:3], off
	global_load_dwordx4 v[82:85], v[4:5], off
	v_lshl_add_u64 v[2:3], s[0:1], 0, v[158:159]
	s_lshl_b32 s0, s8, 8
	s_mov_b32 s1, s61
	v_lshl_add_u64 v[4:5], v[162:163], 0, s[0:1]
	s_or_b32 s48, s6, 0x680
	s_mov_b32 s49, s61
	global_load_dwordx4 v[90:93], v[2:3], off
	global_load_dwordx4 v[86:89], v[4:5], off
	v_lshl_add_u64 v[2:3], v[160:161], 0, s[48:49]
	v_mov_b64_e32 v[4:5], s[80:81]
	v_mad_u64_u32 v[4:5], s[0:1], v2, s19, v[4:5]
	v_mad_i32_i24 v5, v3, s19, v5
	v_lshl_add_u64 v[2:3], v[4:5], 0, s[60:61]
	v_lshl_add_u64 v[2:3], v[2:3], 0, v[196:197]
	s_waitcnt lgkmcnt(7)
	v_pk_fma_f32 v[110:111], v[130:131], v[110:111], v[114:115]
	v_add_co_u32_e64 v8, s[44:45], s14, v2
	v_lshl_add_u64 v[114:115], v[152:153], 0, s[52:53]
	v_cvt_pk_bf16_f32 v110, v110, v110
	v_lshl_add_u64 v[6:7], v[2:3], 0, s[20:21]
	v_addc_co_u32_e64 v9, s[44:45], 0, v3, s[44:45]
	v_pk_fma_f32 v[112:113], v[132:133], v[112:113], v[116:117]
	v_lshlrev_b64 v[114:115], 12, v[114:115]
	v_and_b32_e32 v110, 0xffff, v110
	global_load_dwordx4 v[30:33], v[6:7], off offset:64
	global_load_dwordx4 v[2:5], v[6:7], off offset:128
	global_load_dwordx4 v[46:49], v[8:9], off offset:1024
	s_nop 0
	global_load_dwordx4 v[6:9], v[6:7], off offset:192
	v_lshl_add_u64 v[114:115], v[154:155], 0, v[114:115]
	global_store_short v[114:115], v110, off
	v_cvt_pk_bf16_f32 v110, v111, v111
	v_cvt_pk_bf16_f32 v112, v112, v112
	v_lshl_add_u64 v[116:117], v[114:115], 0, s[86:87]
	v_and_b32_e32 v110, 0xffff, v110
	global_store_short v[116:117], v110, off
	v_and_b32_e32 v112, 0xffff, v112
	v_lshl_add_u64 v[110:111], v[114:115], 0, s[74:75]
	global_store_short v[110:111], v112, off
	v_cvt_pk_bf16_f32 v112, v113, v113
	v_pk_fma_f32 v[118:119], v[130:131], v[118:119], v[122:123]
	v_and_b32_e32 v112, 0xffff, v112
	v_lshl_add_u64 v[110:111], v[114:115], 0, s[66:67]
	global_store_short v[110:111], v112, off
	v_cvt_pk_bf16_f32 v112, v118, v118
	v_and_b32_e32 v112, 0xffff, v112
	v_lshl_add_u64 v[110:111], v[114:115], 0, 32
	global_store_short v[110:111], v112, off
	v_cvt_pk_bf16_f32 v112, v119, v119
	v_pk_fma_f32 v[120:121], v[132:133], v[120:121], v[124:125]
	v_and_b32_e32 v112, 0xffff, v112
	v_lshl_add_u64 v[110:111], v[114:115], 0, s[22:23]
	global_store_short v[110:111], v112, off
	v_cvt_pk_bf16_f32 v112, v120, v120
	v_and_b32_e32 v112, 0xffff, v112
	v_lshl_add_u64 v[110:111], v[114:115], 0, s[12:13]
	global_store_short v[110:111], v112, off
	v_cvt_pk_bf16_f32 v112, v121, v121
	v_lshl_add_u64 v[110:111], v[114:115], 0, s[56:57]
	v_and_b32_e32 v112, 0xffff, v112
	global_store_short v[110:111], v112, off
	s_waitcnt lgkmcnt(0)
	s_barrier
	ds_read_b128 v[110:113], v189
	ds_read_b128 v[114:117], v189 offset:64
	ds_read_b128 v[206:209], v189 offset:128
	ds_read_b128 v[122:125], v150
	ds_read_b128 v[210:213], v189 offset:192
	ds_read_b128 v[118:121], v186 offset:10240
	ds_read_b128 v[130:133], v150 offset:64
	ds_read_b128 v[214:217], v186 offset:10304
	ds_read_b128 v[218:221], v189 offset:4608
	ds_read_b128 v[222:225], v189 offset:4672
	s_waitcnt vmcnt(21) lgkmcnt(9)
	v_mfma_f32_16x16x32_bf16 v[110:113], v[38:41], v[110:113], 0
	s_waitcnt lgkmcnt(8)
	v_mfma_f32_16x16x32_bf16 v[110:113], v[34:37], v[114:117], v[110:113]
	s_nop 0
	s_nop 0
	s_waitcnt lgkmcnt(7)
	v_mfma_f32_16x16x32_bf16 v[110:113], v[10:13], v[206:209], v[110:113]
	ds_read_b128 v[206:209], v189 offset:4736
	s_nop 0
	s_nop 0
	s_nop 0
	s_waitcnt vmcnt(20) lgkmcnt(6)
	v_mfma_f32_16x16x32_bf16 v[110:113], v[14:17], v[210:213], v[110:113]
	ds_read_b128 v[210:213], v189 offset:4800
	s_waitcnt lgkmcnt(6)
	v_mfma_f32_16x16x32_bf16 v[114:117], v[122:125], v[118:121], 0
	s_nop 0
	s_waitcnt lgkmcnt(4)
	v_mfma_f32_16x16x32_bf16 v[114:117], v[130:133], v[214:217], v[114:117]
	ds_read_b128 v[214:217], v186 offset:12800
	s_nop 0
	s_waitcnt lgkmcnt(4)
	v_mfma_f32_16x16x32_bf16 v[38:41], v[38:41], v[218:221], 0
	ds_read_b128 v[218:221], v186 offset:12864
	s_nop 0
	s_waitcnt lgkmcnt(4)
	v_mfma_f32_16x16x32_bf16 v[34:37], v[34:37], v[222:225], v[38:41]
	ds_read_b128 v[222:225], v180 offset:30720
	ds_read_b32 v138, v197 offset:51452
	s_nop 4
	s_nop 0
	s_waitcnt lgkmcnt(5)
	v_mfma_f32_16x16x32_bf16 v[10:13], v[10:13], v[206:209], v[34:37]
	ds_read_b128 v[38:41], v179 offset:20480
	ds_read_b128 v[134:137], v180 offset:30784
	ds_read_b128 v[206:209], v179 offset:23040
	s_nop 2
	s_nop 0
	s_waitcnt lgkmcnt(7)
	v_mfma_f32_16x16x32_bf16 v[118:121], v[14:17], v[210:213], v[10:13]
	ds_read_b128 v[210:213], v179 offset:25600
	s_nop 2
	s_nop 0
	s_nop 0
	s_nop 0
	s_nop 0
	s_nop 0
	s_nop 0
	s_waitcnt lgkmcnt(7)
	v_mfma_f32_16x16x32_bf16 v[10:13], v[122:125], v[214:217], 0
	ds_read_b128 v[214:217], v179 offset:28160
	s_waitcnt lgkmcnt(7)
	v_mfma_f32_16x16x32_bf16 v[122:125], v[130:133], v[218:221], v[10:13]
	ds_read_b128 v[218:221], v179 offset:20544
	s_nop 0
	s_waitcnt lgkmcnt(6)
	s_nop 3
	v_pk_mul_f32 v[12:13], v[108:109], v[138:139] op_sel_hi:[1,0]
	v_pk_mul_f32 v[10:11], v[106:107], v[138:139] op_sel_hi:[1,0]
	s_waitcnt lgkmcnt(5)
	s_nop 0
	v_mfma_f32_16x16x32_bf16 v[10:13], v[222:225], v[38:41], v[10:13]
	v_mul_f32_e64 v40, v104, v138
	v_mul_f32_e64 v41, v105, v138
	v_pk_mul_f32 v[38:39], v[102:103], v[138:139] op_sel_hi:[1,0]
	s_nop 0
	s_waitcnt lgkmcnt(3)
	v_mfma_f32_16x16x32_bf16 v[14:17], v[222:225], v[206:209], v[38:41]
	ds_read_b128 v[206:209], v179 offset:23104
	s_nop 2
	v_mul_f32_e64 v40, v100, v138
	v_mul_f32_e64 v41, v101, v138
	v_pk_mul_f32 v[38:39], v[98:99], v[138:139] op_sel_hi:[1,0]
	s_nop 0
	s_waitcnt lgkmcnt(3)
	v_mfma_f32_16x16x32_bf16 v[38:41], v[222:225], v[210:213], v[38:41]
	v_mul_f32_e64 v104, v128, v138
	v_mul_f32_e64 v105, v129, v138
	v_pk_mul_f32 v[102:103], v[126:127], v[138:139] op_sel_hi:[1,0]
	ds_read_b128 v[210:213], v179 offset:25664
	s_waitcnt lgkmcnt(3)
	s_nop 0
	v_mfma_f32_16x16x32_bf16 v[34:37], v[222:225], v[214:217], v[102:105]
	ds_read_b128 v[214:217], v179 offset:28224
	ds_read_b128 v[130:133], v176 offset:51200
	s_nop 0
	s_waitcnt lgkmcnt(4)
	v_mfma_f32_16x16x32_bf16 v[106:109], v[134:137], v[218:221], v[10:13]
	s_nop 2
	s_nop 0
	s_waitcnt lgkmcnt(3)
	v_mfma_f32_16x16x32_bf16 v[102:105], v[134:137], v[206:209], v[14:17]
	s_nop 0
	s_waitcnt lgkmcnt(2)
	v_mfma_f32_16x16x32_bf16 v[98:101], v[134:137], v[210:213], v[38:41]
	s_nop 0
	s_nop 0
	s_waitcnt lgkmcnt(1)
	v_mfma_f32_16x16x32_bf16 v[126:129], v[134:137], v[214:217], v[34:37]
	v_cvt_pk_bf16_f32 v10, v106, v107
	v_cvt_pk_bf16_f32 v11, v108, v109
	v_cvt_pk_bf16_f32 v12, v102, v103
	v_cvt_pk_bf16_f32 v13, v104, v105
	ds_write2st64_b64 v174, v[10:11], v[12:13] offset1:9
	v_cvt_pk_bf16_f32 v10, v98, v99
	v_cvt_pk_bf16_f32 v11, v100, v101
	s_nop 0
	v_cvt_pk_bf16_f32 v12, v126, v127
	v_cvt_pk_bf16_f32 v13, v128, v129
	ds_write2st64_b64 v174, v[10:11], v[12:13] offset0:18 offset1:27
	s_waitcnt vmcnt(19)
	ds_write_b128 v171, v[50:53] offset:51456
	s_waitcnt vmcnt(18)
	ds_write_b128 v171, v[62:65] offset:61696
	s_waitcnt vmcnt(17)
	ds_write_b128 v172, v[66:69]
	s_waitcnt vmcnt(16)
	ds_write_b128 v173, v[70:73]
	s_waitcnt vmcnt(15)
	ds_write_b128 v175, v[94:97]
	s_and_saveexec_b64 s[8:9], vcc
	s_cbranch_execz .LBB0_1597
	s_waitcnt vmcnt(14)
	ds_write_b128 v185, v[74:77]
.LBB0_1597:
	s_or_b64 exec, exec, s[8:9]
	s_or_b32 s7, s34, 27
	s_lshl_b32 s0, s7, 5
	s_or_b32 s8, s0, s78
	s_lshl_b32 s0, s8, 13
	s_mov_b32 s1, s61
	v_lshl_add_u64 v[10:11], v[168:169], 0, s[0:1]
	v_lshl_add_u64 v[12:13], v[166:167], 0, s[0:1]
	global_load_dwordx4 v[50:53], v[10:11], off
	global_load_dwordx4 v[62:65], v[12:13], off
	v_lshl_add_u64 v[10:11], v[164:165], 0, s[0:1]
	s_lshl_b32 s0, s7, 16
	s_or_b32 s0, s0, s5
	s_add_u32 s0, s77, s0
	s_addc_u32 s1, s28, 0
	v_lshl_add_u64 v[12:13], s[0:1], 0, v[156:157]
	global_load_dwordx4 v[66:69], v[10:11], off
	global_load_dwordx4 v[70:73], v[12:13], off
	v_lshl_add_u64 v[10:11], s[0:1], 0, v[158:159]
	s_lshl_b32 s0, s8, 8
	s_mov_b32 s1, s61
	v_lshl_add_u64 v[12:13], v[162:163], 0, s[0:1]
	s_or_b32 s52, s6, 0x6c0
	s_mov_b32 s53, s61
	global_load_dwordx4 v[94:97], v[10:11], off
	global_load_dwordx4 v[74:77], v[12:13], off
	v_lshl_add_u64 v[10:11], v[160:161], 0, s[52:53]
	v_mov_b64_e32 v[12:13], s[80:81]
	v_mad_u64_u32 v[12:13], s[0:1], v10, s19, v[12:13]
	v_mad_i32_i24 v13, v11, s19, v13
	v_lshl_add_u64 v[10:11], v[12:13], 0, s[60:61]
	v_lshl_add_u64 v[10:11], v[10:11], 0, v[196:197]
	s_waitcnt lgkmcnt(7)
	v_pk_fma_f32 v[110:111], v[130:131], v[110:111], v[114:115]
	v_add_co_u32_e64 v16, s[44:45], s14, v10
	v_lshl_add_u64 v[114:115], v[152:153], 0, s[46:47]
	v_cvt_pk_bf16_f32 v110, v110, v110
	v_lshl_add_u64 v[14:15], v[10:11], 0, s[20:21]
	v_addc_co_u32_e64 v17, s[44:45], 0, v11, s[44:45]
	v_pk_fma_f32 v[112:113], v[132:133], v[112:113], v[116:117]
	v_lshlrev_b64 v[114:115], 12, v[114:115]
	v_and_b32_e32 v110, 0xffff, v110
	global_load_dwordx4 v[34:37], v[14:15], off offset:64
	global_load_dwordx4 v[10:13], v[14:15], off offset:128
	global_load_dwordx4 v[38:41], v[16:17], off offset:1024
	s_nop 0
	global_load_dwordx4 v[14:17], v[14:15], off offset:192
	v_lshl_add_u64 v[114:115], v[154:155], 0, v[114:115]
	global_store_short v[114:115], v110, off
	v_cvt_pk_bf16_f32 v110, v111, v111
	v_cvt_pk_bf16_f32 v112, v112, v112
	v_lshl_add_u64 v[116:117], v[114:115], 0, s[86:87]
	v_and_b32_e32 v110, 0xffff, v110
	global_store_short v[116:117], v110, off
	v_and_b32_e32 v112, 0xffff, v112
	v_lshl_add_u64 v[110:111], v[114:115], 0, s[74:75]
	global_store_short v[110:111], v112, off
	v_cvt_pk_bf16_f32 v112, v113, v113
	v_pk_fma_f32 v[118:119], v[130:131], v[118:119], v[122:123]
	v_and_b32_e32 v112, 0xffff, v112
	v_lshl_add_u64 v[110:111], v[114:115], 0, s[66:67]
	global_store_short v[110:111], v112, off
	v_cvt_pk_bf16_f32 v112, v118, v118
	v_and_b32_e32 v112, 0xffff, v112
	v_lshl_add_u64 v[110:111], v[114:115], 0, 32
	global_store_short v[110:111], v112, off
	v_cvt_pk_bf16_f32 v112, v119, v119
	v_pk_fma_f32 v[120:121], v[132:133], v[120:121], v[124:125]
	v_and_b32_e32 v112, 0xffff, v112
	v_lshl_add_u64 v[110:111], v[114:115], 0, s[22:23]
	global_store_short v[110:111], v112, off
	v_cvt_pk_bf16_f32 v112, v120, v120
	v_and_b32_e32 v112, 0xffff, v112
	v_lshl_add_u64 v[110:111], v[114:115], 0, s[12:13]
	global_store_short v[110:111], v112, off
	v_cvt_pk_bf16_f32 v112, v121, v121
	v_lshl_add_u64 v[110:111], v[114:115], 0, s[56:57]
	v_and_b32_e32 v112, 0xffff, v112
	global_store_short v[110:111], v112, off
	s_waitcnt lgkmcnt(0)
	s_barrier
	ds_read_b128 v[110:113], v188
	ds_read_b128 v[114:117], v188 offset:64
	ds_read_b128 v[206:209], v188 offset:128
	ds_read_b128 v[122:125], v150 offset:51456
	ds_read_b128 v[210:213], v188 offset:192
	ds_read_b128 v[118:121], v186 offset:61696
	ds_read_b128 v[130:133], v150 offset:51520
	ds_read_b128 v[214:217], v186 offset:61760
	ds_read_b128 v[218:221], v188 offset:4608
	ds_read_b128 v[222:225], v188 offset:4672
	s_waitcnt vmcnt(21) lgkmcnt(9)
	v_mfma_f32_16x16x32_bf16 v[110:113], v[42:45], v[110:113], 0
	v_readlane_b32 s0, v253, 18
	s_waitcnt lgkmcnt(8)
	v_mfma_f32_16x16x32_bf16 v[110:113], v[26:29], v[114:117], v[110:113]
	s_nop 0
	s_nop 0
	s_waitcnt lgkmcnt(7)
	v_mfma_f32_16x16x32_bf16 v[110:113], v[18:21], v[206:209], v[110:113]
	ds_read_b128 v[206:209], v188 offset:4736
	s_nop 0
	s_nop 0
	s_nop 0
	s_waitcnt vmcnt(20) lgkmcnt(6)
	v_mfma_f32_16x16x32_bf16 v[110:113], v[22:25], v[210:213], v[110:113]
	ds_read_b128 v[210:213], v188 offset:4800
	s_waitcnt lgkmcnt(6)
	v_mfma_f32_16x16x32_bf16 v[114:117], v[122:125], v[118:121], 0
	s_nop 0
	s_waitcnt lgkmcnt(4)
	v_mfma_f32_16x16x32_bf16 v[114:117], v[130:133], v[214:217], v[114:117]
	ds_read_b128 v[214:217], v186 offset:64256
	s_nop 0
	s_waitcnt lgkmcnt(4)
	v_mfma_f32_16x16x32_bf16 v[42:45], v[42:45], v[218:221], 0
	ds_read_b128 v[218:221], v186 offset:64320
	s_nop 0
	s_waitcnt lgkmcnt(4)
	v_mfma_f32_16x16x32_bf16 v[26:29], v[26:29], v[222:225], v[42:45]
	ds_read_b128 v[222:225], v183
	s_nop 4
	s_nop 0
	s_waitcnt lgkmcnt(4)
	v_mfma_f32_16x16x32_bf16 v[18:21], v[18:21], v[206:209], v[26:29]
	s_nop 2
	s_nop 0
	v_mov_b32_e32 v42, s0
	ds_read_b32 v138, v42
	ds_read_b128 v[206:209], v184
	ds_read_b128 v[134:137], v183 offset:64
	s_waitcnt lgkmcnt(6)
	v_mfma_f32_16x16x32_bf16 v[118:121], v[22:25], v[210:213], v[18:21]
	ds_read_b128 v[210:213], v184 offset:2560
	s_nop 2
	s_nop 0
	s_nop 0
	s_nop 0
	s_nop 0
	s_nop 0
	s_nop 0
	s_waitcnt lgkmcnt(6)
	v_mfma_f32_16x16x32_bf16 v[18:21], v[122:125], v[214:217], 0
	ds_read_b128 v[214:217], v184 offset:5120
	s_waitcnt lgkmcnt(6)
	v_mfma_f32_16x16x32_bf16 v[122:125], v[130:133], v[218:221], v[18:21]
	ds_read_b128 v[218:221], v184 offset:7680
	s_nop 0
	s_waitcnt lgkmcnt(5)
	s_nop 3
	v_pk_mul_f32 v[20:21], v[108:109], v[138:139] op_sel_hi:[1,0]
	v_pk_mul_f32 v[18:19], v[106:107], v[138:139] op_sel_hi:[1,0]
	s_waitcnt lgkmcnt(4)
	s_nop 0
	v_mfma_f32_16x16x32_bf16 v[18:21], v[222:225], v[206:209], v[18:21]
	v_mul_f32_e64 v44, v104, v138
	v_mul_f32_e64 v45, v105, v138
	v_pk_mul_f32 v[42:43], v[102:103], v[138:139] op_sel_hi:[1,0]
	ds_read_b128 v[206:209], v182
	s_nop 0
	s_waitcnt lgkmcnt(3)
	v_mfma_f32_16x16x32_bf16 v[22:25], v[222:225], v[210:213], v[42:45]
	ds_read_b128 v[210:213], v182 offset:2560
	s_nop 2
	v_mul_f32_e64 v44, v100, v138
	v_mul_f32_e64 v45, v101, v138
	v_pk_mul_f32 v[42:43], v[98:99], v[138:139] op_sel_hi:[1,0]
	s_nop 0
	s_waitcnt lgkmcnt(3)
	v_mfma_f32_16x16x32_bf16 v[42:45], v[222:225], v[214:217], v[42:45]
	v_mul_f32_e64 v104, v128, v138
	v_mul_f32_e64 v105, v129, v138
	v_pk_mul_f32 v[102:103], v[126:127], v[138:139] op_sel_hi:[1,0]
	ds_read_b128 v[214:217], v182 offset:5120
	s_waitcnt lgkmcnt(3)
	s_nop 0
	v_mfma_f32_16x16x32_bf16 v[26:29], v[222:225], v[218:221], v[102:105]
	ds_read_b128 v[218:221], v182 offset:7680
	ds_read_b128 v[130:133], v181
	s_nop 0
	s_waitcnt lgkmcnt(4)
	v_mfma_f32_16x16x32_bf16 v[106:109], v[134:137], v[206:209], v[18:21]
	s_nop 2
	s_nop 0
	s_waitcnt lgkmcnt(3)
	v_mfma_f32_16x16x32_bf16 v[102:105], v[134:137], v[210:213], v[22:25]
	s_nop 0
	s_waitcnt lgkmcnt(2)
	v_mfma_f32_16x16x32_bf16 v[98:101], v[134:137], v[214:217], v[42:45]
	s_nop 0
	s_nop 0
	s_waitcnt lgkmcnt(1)
	v_mfma_f32_16x16x32_bf16 v[126:129], v[134:137], v[218:221], v[26:29]
	v_cvt_pk_bf16_f32 v18, v106, v107
	v_cvt_pk_bf16_f32 v19, v108, v109
	v_cvt_pk_bf16_f32 v20, v102, v103
	v_cvt_pk_bf16_f32 v21, v104, v105
	ds_write2st64_b64 v187, v[18:19], v[20:21] offset1:9
	v_cvt_pk_bf16_f32 v18, v98, v99
	v_cvt_pk_bf16_f32 v19, v100, v101
	s_nop 0
	v_cvt_pk_bf16_f32 v20, v126, v127
	v_cvt_pk_bf16_f32 v21, v128, v129
	ds_write2st64_b64 v187, v[18:19], v[20:21] offset0:18 offset1:27
	s_waitcnt vmcnt(19)
	ds_write_b128 v171, v[54:57]
	s_waitcnt vmcnt(18)
	ds_write_b128 v171, v[58:61] offset:10240
	s_waitcnt vmcnt(17)
	ds_write_b128 v171, v[78:81] offset:20480
	s_waitcnt vmcnt(16)
	ds_write_b128 v171, v[82:85] offset:30720
	s_waitcnt vmcnt(15)
	ds_write_b128 v178, v[90:93] offset:30720
	s_and_saveexec_b64 s[8:9], vcc
	s_cbranch_execz .LBB0_1599
	s_waitcnt vmcnt(14)
	ds_write_b128 v177, v[86:89] offset:51200
.LBB0_1599:
	s_or_b64 exec, exec, s[8:9]
	s_or_b32 s7, s34, 28
	s_lshl_b32 s0, s7, 5
	s_or_b32 s8, s0, s78
	s_lshl_b32 s0, s8, 13
	s_mov_b32 s1, s61
	v_lshl_add_u64 v[18:19], v[168:169], 0, s[0:1]
	v_lshl_add_u64 v[20:21], v[166:167], 0, s[0:1]
	global_load_dwordx4 v[54:57], v[18:19], off
	global_load_dwordx4 v[58:61], v[20:21], off
	v_lshl_add_u64 v[18:19], v[164:165], 0, s[0:1]
	s_lshl_b32 s0, s7, 16
	s_or_b32 s0, s0, s5
	s_add_u32 s0, s77, s0
	s_addc_u32 s1, s28, 0
	v_lshl_add_u64 v[20:21], s[0:1], 0, v[156:157]
	global_load_dwordx4 v[78:81], v[18:19], off
	global_load_dwordx4 v[82:85], v[20:21], off
	v_lshl_add_u64 v[18:19], s[0:1], 0, v[158:159]
	s_lshl_b32 s0, s8, 8
	s_mov_b32 s1, s61
	v_lshl_add_u64 v[20:21], v[162:163], 0, s[0:1]
	s_or_b32 s46, s6, 0x700
	s_mov_b32 s47, s61
	global_load_dwordx4 v[90:93], v[18:19], off
	global_load_dwordx4 v[86:89], v[20:21], off
	v_lshl_add_u64 v[18:19], v[160:161], 0, s[46:47]
	v_mov_b64_e32 v[20:21], s[80:81]
	v_mad_u64_u32 v[20:21], s[0:1], v18, s19, v[20:21]
	v_mad_i32_i24 v21, v19, s19, v21
	v_lshl_add_u64 v[18:19], v[20:21], 0, s[60:61]
	v_lshl_add_u64 v[18:19], v[18:19], 0, v[196:197]
	s_waitcnt lgkmcnt(7)
	v_pk_fma_f32 v[110:111], v[130:131], v[110:111], v[114:115]
	v_add_co_u32_e64 v24, s[44:45], s14, v18
	v_lshl_add_u64 v[114:115], v[152:153], 0, s[50:51]
	v_cvt_pk_bf16_f32 v110, v110, v110
	v_lshl_add_u64 v[22:23], v[18:19], 0, s[20:21]
	v_addc_co_u32_e64 v25, s[44:45], 0, v19, s[44:45]
	v_pk_fma_f32 v[112:113], v[132:133], v[112:113], v[116:117]
	v_lshlrev_b64 v[114:115], 12, v[114:115]
	v_and_b32_e32 v110, 0xffff, v110
	global_load_dwordx4 v[26:29], v[22:23], off offset:64
	global_load_dwordx4 v[18:21], v[22:23], off offset:128
	global_load_dwordx4 v[42:45], v[24:25], off offset:1024
	s_nop 0
	global_load_dwordx4 v[22:25], v[22:23], off offset:192
	v_lshl_add_u64 v[114:115], v[154:155], 0, v[114:115]
	global_store_short v[114:115], v110, off
	v_cvt_pk_bf16_f32 v110, v111, v111
	v_cvt_pk_bf16_f32 v112, v112, v112
	v_lshl_add_u64 v[116:117], v[114:115], 0, s[86:87]
	v_and_b32_e32 v110, 0xffff, v110
	global_store_short v[116:117], v110, off
	v_and_b32_e32 v112, 0xffff, v112
	v_lshl_add_u64 v[110:111], v[114:115], 0, s[74:75]
	global_store_short v[110:111], v112, off
	v_cvt_pk_bf16_f32 v112, v113, v113
	v_pk_fma_f32 v[118:119], v[130:131], v[118:119], v[122:123]
	v_and_b32_e32 v112, 0xffff, v112
	v_lshl_add_u64 v[110:111], v[114:115], 0, s[66:67]
	global_store_short v[110:111], v112, off
	v_cvt_pk_bf16_f32 v112, v118, v118
	v_and_b32_e32 v112, 0xffff, v112
	v_lshl_add_u64 v[110:111], v[114:115], 0, 32
	global_store_short v[110:111], v112, off
	v_cvt_pk_bf16_f32 v112, v119, v119
	v_pk_fma_f32 v[120:121], v[132:133], v[120:121], v[124:125]
	v_and_b32_e32 v112, 0xffff, v112
	v_lshl_add_u64 v[110:111], v[114:115], 0, s[22:23]
	global_store_short v[110:111], v112, off
	v_cvt_pk_bf16_f32 v112, v120, v120
	v_and_b32_e32 v112, 0xffff, v112
	v_lshl_add_u64 v[110:111], v[114:115], 0, s[12:13]
	global_store_short v[110:111], v112, off
	v_cvt_pk_bf16_f32 v112, v121, v121
	v_lshl_add_u64 v[110:111], v[114:115], 0, s[56:57]
	v_and_b32_e32 v112, 0xffff, v112
	global_store_short v[110:111], v112, off
	s_waitcnt lgkmcnt(0)
	s_barrier
	ds_read_b128 v[110:113], v189
	ds_read_b128 v[114:117], v189 offset:64
	ds_read_b128 v[206:209], v189 offset:128
	ds_read_b128 v[122:125], v150
	ds_read_b128 v[210:213], v189 offset:192
	ds_read_b128 v[118:121], v186 offset:10240
	ds_read_b128 v[130:133], v150 offset:64
	ds_read_b128 v[214:217], v186 offset:10304
	ds_read_b128 v[218:221], v189 offset:4608
	ds_read_b128 v[222:225], v189 offset:4672
	s_waitcnt vmcnt(21) lgkmcnt(9)
	v_mfma_f32_16x16x32_bf16 v[110:113], v[46:49], v[110:113], 0
	s_waitcnt lgkmcnt(8)
	v_mfma_f32_16x16x32_bf16 v[110:113], v[30:33], v[114:117], v[110:113]
	s_nop 0
	s_nop 0
	s_waitcnt lgkmcnt(7)
	v_mfma_f32_16x16x32_bf16 v[110:113], v[2:5], v[206:209], v[110:113]
	ds_read_b128 v[206:209], v189 offset:4736
	s_nop 0
	s_nop 0
	s_nop 0
	s_waitcnt vmcnt(20) lgkmcnt(6)
	v_mfma_f32_16x16x32_bf16 v[110:113], v[6:9], v[210:213], v[110:113]
	ds_read_b128 v[210:213], v189 offset:4800
	s_waitcnt lgkmcnt(6)
	v_mfma_f32_16x16x32_bf16 v[114:117], v[122:125], v[118:121], 0
	s_nop 0
	s_waitcnt lgkmcnt(4)
	v_mfma_f32_16x16x32_bf16 v[114:117], v[130:133], v[214:217], v[114:117]
	ds_read_b128 v[214:217], v186 offset:12800
	s_nop 0
	s_waitcnt lgkmcnt(4)
	v_mfma_f32_16x16x32_bf16 v[46:49], v[46:49], v[218:221], 0
	ds_read_b128 v[218:221], v186 offset:12864
	s_nop 0
	s_waitcnt lgkmcnt(4)
	v_mfma_f32_16x16x32_bf16 v[30:33], v[30:33], v[222:225], v[46:49]
	ds_read_b128 v[222:225], v180 offset:30720
	ds_read_b32 v138, v197 offset:51452
	s_nop 4
	s_nop 0
	s_waitcnt lgkmcnt(5)
	v_mfma_f32_16x16x32_bf16 v[2:5], v[2:5], v[206:209], v[30:33]
	ds_read_b128 v[46:49], v179 offset:20480
	ds_read_b128 v[134:137], v180 offset:30784
	ds_read_b128 v[206:209], v179 offset:23040
	s_nop 2
	s_nop 0
	s_waitcnt lgkmcnt(7)
	v_mfma_f32_16x16x32_bf16 v[118:121], v[6:9], v[210:213], v[2:5]
	ds_read_b128 v[210:213], v179 offset:25600
	s_nop 2
	s_nop 0
	s_nop 0
	s_nop 0
	s_nop 0
	s_nop 0
	s_nop 0
	s_waitcnt lgkmcnt(7)
	v_mfma_f32_16x16x32_bf16 v[2:5], v[122:125], v[214:217], 0
	ds_read_b128 v[214:217], v179 offset:28160
	s_waitcnt lgkmcnt(7)
	v_mfma_f32_16x16x32_bf16 v[122:125], v[130:133], v[218:221], v[2:5]
	ds_read_b128 v[218:221], v179 offset:20544
	s_nop 0
	s_waitcnt lgkmcnt(6)
	s_nop 3
	v_pk_mul_f32 v[4:5], v[108:109], v[138:139] op_sel_hi:[1,0]
	v_pk_mul_f32 v[2:3], v[106:107], v[138:139] op_sel_hi:[1,0]
	s_waitcnt lgkmcnt(5)
	s_nop 0
	v_mfma_f32_16x16x32_bf16 v[2:5], v[222:225], v[46:49], v[2:5]
	v_mul_f32_e64 v48, v104, v138
	v_mul_f32_e64 v49, v105, v138
	v_pk_mul_f32 v[46:47], v[102:103], v[138:139] op_sel_hi:[1,0]
	s_nop 0
	s_waitcnt lgkmcnt(3)
	v_mfma_f32_16x16x32_bf16 v[6:9], v[222:225], v[206:209], v[46:49]
	ds_read_b128 v[206:209], v179 offset:23104
	s_nop 2
	v_mul_f32_e64 v48, v100, v138
	v_mul_f32_e64 v49, v101, v138
	v_pk_mul_f32 v[46:47], v[98:99], v[138:139] op_sel_hi:[1,0]
	s_nop 0
	s_waitcnt lgkmcnt(3)
	v_mfma_f32_16x16x32_bf16 v[46:49], v[222:225], v[210:213], v[46:49]
	v_mul_f32_e64 v104, v128, v138
	v_mul_f32_e64 v105, v129, v138
	v_pk_mul_f32 v[102:103], v[126:127], v[138:139] op_sel_hi:[1,0]
	ds_read_b128 v[210:213], v179 offset:25664
	s_waitcnt lgkmcnt(3)
	s_nop 0
	v_mfma_f32_16x16x32_bf16 v[30:33], v[222:225], v[214:217], v[102:105]
	ds_read_b128 v[214:217], v179 offset:28224
	ds_read_b128 v[130:133], v176 offset:51200
	s_nop 0
	s_waitcnt lgkmcnt(4)
	v_mfma_f32_16x16x32_bf16 v[106:109], v[134:137], v[218:221], v[2:5]
	s_nop 2
	s_nop 0
	s_waitcnt lgkmcnt(3)
	v_mfma_f32_16x16x32_bf16 v[102:105], v[134:137], v[206:209], v[6:9]
	s_nop 0
	s_waitcnt lgkmcnt(2)
	v_mfma_f32_16x16x32_bf16 v[98:101], v[134:137], v[210:213], v[46:49]
	s_nop 0
	s_nop 0
	s_waitcnt lgkmcnt(1)
	v_mfma_f32_16x16x32_bf16 v[126:129], v[134:137], v[214:217], v[30:33]
	v_cvt_pk_bf16_f32 v2, v106, v107
	v_cvt_pk_bf16_f32 v3, v108, v109
	v_cvt_pk_bf16_f32 v4, v102, v103
	v_cvt_pk_bf16_f32 v5, v104, v105
	ds_write2st64_b64 v174, v[2:3], v[4:5] offset1:9
	v_cvt_pk_bf16_f32 v2, v98, v99
	v_cvt_pk_bf16_f32 v3, v100, v101
	s_nop 0
	v_cvt_pk_bf16_f32 v4, v126, v127
	v_cvt_pk_bf16_f32 v5, v128, v129
	ds_write2st64_b64 v174, v[2:3], v[4:5] offset0:18 offset1:27
	s_waitcnt vmcnt(19)
	ds_write_b128 v171, v[50:53] offset:51456
	s_waitcnt vmcnt(18)
	ds_write_b128 v171, v[62:65] offset:61696
	s_waitcnt vmcnt(17)
	ds_write_b128 v172, v[66:69]
	s_waitcnt vmcnt(16)
	ds_write_b128 v173, v[70:73]
	s_waitcnt vmcnt(15)
	ds_write_b128 v175, v[94:97]
	s_and_saveexec_b64 s[8:9], vcc
	s_cbranch_execz .LBB0_1601
	s_waitcnt vmcnt(14)
	ds_write_b128 v185, v[74:77]
.LBB0_1601:
	s_or_b64 exec, exec, s[8:9]
	s_or_b32 s7, s34, 29
	s_lshl_b32 s0, s7, 5
	s_or_b32 s8, s0, s78
	s_lshl_b32 s0, s8, 13
	s_mov_b32 s1, s61
	v_lshl_add_u64 v[2:3], v[168:169], 0, s[0:1]
	v_lshl_add_u64 v[4:5], v[166:167], 0, s[0:1]
	global_load_dwordx4 v[50:53], v[2:3], off
	global_load_dwordx4 v[62:65], v[4:5], off
	v_lshl_add_u64 v[2:3], v[164:165], 0, s[0:1]
	s_lshl_b32 s0, s7, 16
	s_or_b32 s0, s0, s5
	s_add_u32 s0, s77, s0
	s_addc_u32 s1, s28, 0
	v_lshl_add_u64 v[4:5], s[0:1], 0, v[156:157]
	global_load_dwordx4 v[66:69], v[2:3], off
	global_load_dwordx4 v[70:73], v[4:5], off
	v_lshl_add_u64 v[2:3], s[0:1], 0, v[158:159]
	s_lshl_b32 s0, s8, 8
	s_mov_b32 s1, s61
	v_lshl_add_u64 v[4:5], v[162:163], 0, s[0:1]
	s_or_b32 s50, s6, 0x740
	s_mov_b32 s51, s61
	global_load_dwordx4 v[94:97], v[2:3], off
	global_load_dwordx4 v[74:77], v[4:5], off
	v_lshl_add_u64 v[2:3], v[160:161], 0, s[50:51]
	v_mov_b64_e32 v[4:5], s[80:81]
	v_mad_u64_u32 v[4:5], s[0:1], v2, s19, v[4:5]
	v_mad_i32_i24 v5, v3, s19, v5
	v_lshl_add_u64 v[2:3], v[4:5], 0, s[60:61]
	v_lshl_add_u64 v[2:3], v[2:3], 0, v[196:197]
	s_waitcnt lgkmcnt(7)
	v_pk_fma_f32 v[110:111], v[130:131], v[110:111], v[114:115]
	v_add_co_u32_e64 v8, s[44:45], s14, v2
	v_lshl_add_u64 v[114:115], v[152:153], 0, s[48:49]
	v_cvt_pk_bf16_f32 v110, v110, v110
	v_lshl_add_u64 v[6:7], v[2:3], 0, s[20:21]
	v_addc_co_u32_e64 v9, s[44:45], 0, v3, s[44:45]
	v_pk_fma_f32 v[112:113], v[132:133], v[112:113], v[116:117]
	v_lshlrev_b64 v[114:115], 12, v[114:115]
	v_and_b32_e32 v110, 0xffff, v110
	global_load_dwordx4 v[30:33], v[6:7], off offset:64
	global_load_dwordx4 v[2:5], v[6:7], off offset:128
	global_load_dwordx4 v[46:49], v[8:9], off offset:1024
	s_nop 0
	global_load_dwordx4 v[6:9], v[6:7], off offset:192
	v_lshl_add_u64 v[114:115], v[154:155], 0, v[114:115]
	global_store_short v[114:115], v110, off
	v_cvt_pk_bf16_f32 v110, v111, v111
	v_cvt_pk_bf16_f32 v112, v112, v112
	v_lshl_add_u64 v[116:117], v[114:115], 0, s[86:87]
	v_and_b32_e32 v110, 0xffff, v110
	global_store_short v[116:117], v110, off
	v_and_b32_e32 v112, 0xffff, v112
	v_lshl_add_u64 v[110:111], v[114:115], 0, s[74:75]
	global_store_short v[110:111], v112, off
	v_cvt_pk_bf16_f32 v112, v113, v113
	v_pk_fma_f32 v[118:119], v[130:131], v[118:119], v[122:123]
	v_and_b32_e32 v112, 0xffff, v112
	v_lshl_add_u64 v[110:111], v[114:115], 0, s[66:67]
	global_store_short v[110:111], v112, off
	v_cvt_pk_bf16_f32 v112, v118, v118
	v_and_b32_e32 v112, 0xffff, v112
	v_lshl_add_u64 v[110:111], v[114:115], 0, 32
	global_store_short v[110:111], v112, off
	v_cvt_pk_bf16_f32 v112, v119, v119
	v_pk_fma_f32 v[120:121], v[132:133], v[120:121], v[124:125]
	v_and_b32_e32 v112, 0xffff, v112
	v_lshl_add_u64 v[110:111], v[114:115], 0, s[22:23]
	global_store_short v[110:111], v112, off
	v_cvt_pk_bf16_f32 v112, v120, v120
	v_and_b32_e32 v112, 0xffff, v112
	v_lshl_add_u64 v[110:111], v[114:115], 0, s[12:13]
	global_store_short v[110:111], v112, off
	v_cvt_pk_bf16_f32 v112, v121, v121
	v_lshl_add_u64 v[110:111], v[114:115], 0, s[56:57]
	v_and_b32_e32 v112, 0xffff, v112
	global_store_short v[110:111], v112, off
	s_waitcnt lgkmcnt(0)
	s_barrier
	ds_read_b128 v[110:113], v188
	ds_read_b128 v[114:117], v188 offset:64
	ds_read_b128 v[206:209], v188 offset:128
	ds_read_b128 v[122:125], v150 offset:51456
	ds_read_b128 v[210:213], v188 offset:192
	ds_read_b128 v[118:121], v186 offset:61696
	ds_read_b128 v[130:133], v150 offset:51520
	ds_read_b128 v[214:217], v186 offset:61760
	ds_read_b128 v[218:221], v188 offset:4608
	ds_read_b128 v[222:225], v188 offset:4672
	s_waitcnt vmcnt(21) lgkmcnt(9)
	v_mfma_f32_16x16x32_bf16 v[110:113], v[38:41], v[110:113], 0
	v_readlane_b32 s0, v253, 18
	s_waitcnt lgkmcnt(8)
	v_mfma_f32_16x16x32_bf16 v[110:113], v[34:37], v[114:117], v[110:113]
	s_nop 0
	s_nop 0
	s_waitcnt lgkmcnt(7)
	v_mfma_f32_16x16x32_bf16 v[110:113], v[10:13], v[206:209], v[110:113]
	ds_read_b128 v[206:209], v188 offset:4736
	s_nop 0
	s_nop 0
	s_nop 0
	s_waitcnt vmcnt(20) lgkmcnt(6)
	v_mfma_f32_16x16x32_bf16 v[110:113], v[14:17], v[210:213], v[110:113]
	ds_read_b128 v[210:213], v188 offset:4800
	s_waitcnt lgkmcnt(6)
	v_mfma_f32_16x16x32_bf16 v[114:117], v[122:125], v[118:121], 0
	s_nop 0
	s_waitcnt lgkmcnt(4)
	v_mfma_f32_16x16x32_bf16 v[114:117], v[130:133], v[214:217], v[114:117]
	ds_read_b128 v[214:217], v186 offset:64256
	s_nop 0
	s_waitcnt lgkmcnt(4)
	v_mfma_f32_16x16x32_bf16 v[38:41], v[38:41], v[218:221], 0
	ds_read_b128 v[218:221], v186 offset:64320
	s_nop 0
	s_waitcnt lgkmcnt(4)
	v_mfma_f32_16x16x32_bf16 v[34:37], v[34:37], v[222:225], v[38:41]
	ds_read_b128 v[222:225], v183
	s_nop 4
	s_nop 0
	s_waitcnt lgkmcnt(4)
	v_mfma_f32_16x16x32_bf16 v[10:13], v[10:13], v[206:209], v[34:37]
	s_nop 2
	s_nop 0
	v_mov_b32_e32 v38, s0
	ds_read_b32 v138, v38
	ds_read_b128 v[206:209], v184
	ds_read_b128 v[134:137], v183 offset:64
	s_waitcnt lgkmcnt(6)
	v_mfma_f32_16x16x32_bf16 v[118:121], v[14:17], v[210:213], v[10:13]
	ds_read_b128 v[210:213], v184 offset:2560
	s_nop 2
	s_nop 0
	s_nop 0
	s_nop 0
	s_nop 0
	s_nop 0
	s_nop 0
	s_waitcnt lgkmcnt(6)
	v_mfma_f32_16x16x32_bf16 v[10:13], v[122:125], v[214:217], 0
	ds_read_b128 v[214:217], v184 offset:5120
	s_waitcnt lgkmcnt(6)
	v_mfma_f32_16x16x32_bf16 v[122:125], v[130:133], v[218:221], v[10:13]
	ds_read_b128 v[218:221], v184 offset:7680
	s_nop 0
	s_waitcnt lgkmcnt(5)
	s_nop 3
	v_pk_mul_f32 v[12:13], v[108:109], v[138:139] op_sel_hi:[1,0]
	v_pk_mul_f32 v[10:11], v[106:107], v[138:139] op_sel_hi:[1,0]
	s_waitcnt lgkmcnt(4)
	s_nop 0
	v_mfma_f32_16x16x32_bf16 v[10:13], v[222:225], v[206:209], v[10:13]
	v_mul_f32_e64 v40, v104, v138
	v_mul_f32_e64 v41, v105, v138
	v_pk_mul_f32 v[38:39], v[102:103], v[138:139] op_sel_hi:[1,0]
	ds_read_b128 v[206:209], v182
	s_nop 0
	s_waitcnt lgkmcnt(3)
	v_mfma_f32_16x16x32_bf16 v[14:17], v[222:225], v[210:213], v[38:41]
	ds_read_b128 v[210:213], v182 offset:2560
	s_nop 2
	v_mul_f32_e64 v40, v100, v138
	v_mul_f32_e64 v41, v101, v138
	v_pk_mul_f32 v[38:39], v[98:99], v[138:139] op_sel_hi:[1,0]
	s_nop 0
	s_waitcnt lgkmcnt(3)
	v_mfma_f32_16x16x32_bf16 v[38:41], v[222:225], v[214:217], v[38:41]
	v_mul_f32_e64 v104, v128, v138
	v_mul_f32_e64 v105, v129, v138
	v_pk_mul_f32 v[102:103], v[126:127], v[138:139] op_sel_hi:[1,0]
	ds_read_b128 v[214:217], v182 offset:5120
	s_waitcnt lgkmcnt(3)
	s_nop 0
	v_mfma_f32_16x16x32_bf16 v[34:37], v[222:225], v[218:221], v[102:105]
	ds_read_b128 v[218:221], v182 offset:7680
	ds_read_b128 v[130:133], v181
	s_nop 0
	s_waitcnt lgkmcnt(4)
	v_mfma_f32_16x16x32_bf16 v[106:109], v[134:137], v[206:209], v[10:13]
	s_nop 2
	s_nop 0
	s_waitcnt lgkmcnt(3)
	v_mfma_f32_16x16x32_bf16 v[102:105], v[134:137], v[210:213], v[14:17]
	s_nop 0
	s_waitcnt lgkmcnt(2)
	v_mfma_f32_16x16x32_bf16 v[98:101], v[134:137], v[214:217], v[38:41]
	s_nop 0
	s_nop 0
	s_waitcnt lgkmcnt(1)
	v_mfma_f32_16x16x32_bf16 v[126:129], v[134:137], v[218:221], v[34:37]
	v_cvt_pk_bf16_f32 v10, v106, v107
	v_cvt_pk_bf16_f32 v11, v108, v109
	v_cvt_pk_bf16_f32 v12, v102, v103
	v_cvt_pk_bf16_f32 v13, v104, v105
	ds_write2st64_b64 v187, v[10:11], v[12:13] offset1:9
	v_cvt_pk_bf16_f32 v10, v98, v99
	v_cvt_pk_bf16_f32 v11, v100, v101
	s_nop 0
	v_cvt_pk_bf16_f32 v12, v126, v127
	v_cvt_pk_bf16_f32 v13, v128, v129
	ds_write2st64_b64 v187, v[10:11], v[12:13] offset0:18 offset1:27
	s_waitcnt vmcnt(19)
	ds_write_b128 v171, v[54:57]
	s_waitcnt vmcnt(18)
	ds_write_b128 v171, v[58:61] offset:10240
	s_waitcnt vmcnt(17)
	ds_write_b128 v171, v[78:81] offset:20480
	s_waitcnt vmcnt(16)
	ds_write_b128 v171, v[82:85] offset:30720
	s_waitcnt vmcnt(15)
	ds_write_b128 v178, v[90:93] offset:30720
	s_and_saveexec_b64 s[8:9], vcc
	s_cbranch_execz .LBB0_1603
	s_waitcnt vmcnt(14)
	ds_write_b128 v177, v[86:89] offset:51200
.LBB0_1603:
	s_or_b64 exec, exec, s[8:9]
	s_or_b32 s7, s34, 30
	s_lshl_b32 s0, s7, 5
	s_or_b32 s8, s0, s78
	s_lshl_b32 s0, s8, 13
	s_mov_b32 s1, s61
	v_lshl_add_u64 v[10:11], v[168:169], 0, s[0:1]
	v_lshl_add_u64 v[12:13], v[166:167], 0, s[0:1]
	global_load_dwordx4 v[54:57], v[10:11], off
	global_load_dwordx4 v[58:61], v[12:13], off
	v_lshl_add_u64 v[10:11], v[164:165], 0, s[0:1]
	s_lshl_b32 s0, s7, 16
	s_or_b32 s0, s0, s5
	s_add_u32 s0, s77, s0
	s_addc_u32 s1, s28, 0
	v_lshl_add_u64 v[12:13], s[0:1], 0, v[156:157]
	global_load_dwordx4 v[78:81], v[10:11], off
	global_load_dwordx4 v[82:85], v[12:13], off
	v_lshl_add_u64 v[10:11], s[0:1], 0, v[158:159]
	s_lshl_b32 s0, s8, 8
	s_mov_b32 s1, s61
	v_lshl_add_u64 v[12:13], v[162:163], 0, s[0:1]
	s_or_b32 s48, s6, 0x780
	s_mov_b32 s49, s61
	global_load_dwordx4 v[90:93], v[10:11], off
	global_load_dwordx4 v[86:89], v[12:13], off
	v_lshl_add_u64 v[10:11], v[160:161], 0, s[48:49]
	v_mov_b64_e32 v[12:13], s[80:81]
	v_mad_u64_u32 v[12:13], s[0:1], v10, s19, v[12:13]
	v_mad_i32_i24 v13, v11, s19, v13
	v_lshl_add_u64 v[10:11], v[12:13], 0, s[60:61]
	v_lshl_add_u64 v[10:11], v[10:11], 0, v[196:197]
	s_waitcnt lgkmcnt(7)
	v_pk_fma_f32 v[110:111], v[130:131], v[110:111], v[114:115]
	v_add_co_u32_e64 v16, s[44:45], s14, v10
	v_lshl_add_u64 v[114:115], v[152:153], 0, s[52:53]
	v_cvt_pk_bf16_f32 v110, v110, v110
	v_lshl_add_u64 v[14:15], v[10:11], 0, s[20:21]
	v_addc_co_u32_e64 v17, s[44:45], 0, v11, s[44:45]
	v_pk_fma_f32 v[112:113], v[132:133], v[112:113], v[116:117]
	v_lshlrev_b64 v[114:115], 12, v[114:115]
	v_and_b32_e32 v110, 0xffff, v110
	global_load_dwordx4 v[34:37], v[14:15], off offset:64
	global_load_dwordx4 v[10:13], v[14:15], off offset:128
	global_load_dwordx4 v[38:41], v[16:17], off offset:1024
	s_nop 0
	global_load_dwordx4 v[14:17], v[14:15], off offset:192
	v_lshl_add_u64 v[114:115], v[154:155], 0, v[114:115]
	global_store_short v[114:115], v110, off
	v_cvt_pk_bf16_f32 v110, v111, v111
	v_cvt_pk_bf16_f32 v112, v112, v112
	v_lshl_add_u64 v[116:117], v[114:115], 0, s[86:87]
	v_and_b32_e32 v110, 0xffff, v110
	global_store_short v[116:117], v110, off
	v_and_b32_e32 v112, 0xffff, v112
	v_lshl_add_u64 v[110:111], v[114:115], 0, s[74:75]
	global_store_short v[110:111], v112, off
	v_cvt_pk_bf16_f32 v112, v113, v113
	v_pk_fma_f32 v[118:119], v[130:131], v[118:119], v[122:123]
	v_and_b32_e32 v112, 0xffff, v112
	v_lshl_add_u64 v[110:111], v[114:115], 0, s[66:67]
	global_store_short v[110:111], v112, off
	v_cvt_pk_bf16_f32 v112, v118, v118
	v_and_b32_e32 v112, 0xffff, v112
	v_lshl_add_u64 v[110:111], v[114:115], 0, 32
	global_store_short v[110:111], v112, off
	v_cvt_pk_bf16_f32 v112, v119, v119
	v_pk_fma_f32 v[120:121], v[132:133], v[120:121], v[124:125]
	v_and_b32_e32 v112, 0xffff, v112
	v_lshl_add_u64 v[110:111], v[114:115], 0, s[22:23]
	global_store_short v[110:111], v112, off
	v_cvt_pk_bf16_f32 v112, v120, v120
	v_and_b32_e32 v112, 0xffff, v112
	v_lshl_add_u64 v[110:111], v[114:115], 0, s[12:13]
	global_store_short v[110:111], v112, off
	v_cvt_pk_bf16_f32 v112, v121, v121
	v_lshl_add_u64 v[110:111], v[114:115], 0, s[56:57]
	v_and_b32_e32 v112, 0xffff, v112
	global_store_short v[110:111], v112, off
	s_waitcnt lgkmcnt(0)
	s_barrier
	ds_read_b128 v[110:113], v189
	ds_read_b128 v[114:117], v189 offset:64
	ds_read_b128 v[206:209], v189 offset:128
	ds_read_b128 v[122:125], v150
	ds_read_b128 v[210:213], v189 offset:192
	ds_read_b128 v[118:121], v186 offset:10240
	ds_read_b128 v[130:133], v150 offset:64
	ds_read_b128 v[214:217], v186 offset:10304
	ds_read_b128 v[218:221], v189 offset:4608
	ds_read_b128 v[222:225], v189 offset:4672
	s_waitcnt vmcnt(21) lgkmcnt(9)
	v_mfma_f32_16x16x32_bf16 v[110:113], v[42:45], v[110:113], 0
	s_waitcnt lgkmcnt(8)
	v_mfma_f32_16x16x32_bf16 v[110:113], v[26:29], v[114:117], v[110:113]
	s_nop 0
	s_nop 0
	s_waitcnt lgkmcnt(7)
	v_mfma_f32_16x16x32_bf16 v[110:113], v[18:21], v[206:209], v[110:113]
	ds_read_b128 v[206:209], v189 offset:4736
	s_nop 0
	s_nop 0
	s_nop 0
	s_waitcnt vmcnt(20) lgkmcnt(6)
	v_mfma_f32_16x16x32_bf16 v[110:113], v[22:25], v[210:213], v[110:113]
	ds_read_b128 v[210:213], v189 offset:4800
	s_waitcnt lgkmcnt(6)
	v_mfma_f32_16x16x32_bf16 v[114:117], v[122:125], v[118:121], 0
	s_nop 0
	s_waitcnt lgkmcnt(4)
	v_mfma_f32_16x16x32_bf16 v[114:117], v[130:133], v[214:217], v[114:117]
	ds_read_b128 v[214:217], v186 offset:12800
	s_nop 0
	s_waitcnt lgkmcnt(4)
	v_mfma_f32_16x16x32_bf16 v[42:45], v[42:45], v[218:221], 0
	ds_read_b128 v[218:221], v186 offset:12864
	s_nop 0
	s_waitcnt lgkmcnt(4)
	v_mfma_f32_16x16x32_bf16 v[26:29], v[26:29], v[222:225], v[42:45]
	ds_read_b128 v[222:225], v180 offset:30720
	ds_read_b32 v138, v197 offset:51452
	s_nop 4
	s_nop 0
	s_waitcnt lgkmcnt(5)
	v_mfma_f32_16x16x32_bf16 v[18:21], v[18:21], v[206:209], v[26:29]
	ds_read_b128 v[42:45], v179 offset:20480
	ds_read_b128 v[134:137], v180 offset:30784
	ds_read_b128 v[206:209], v179 offset:23040
	s_nop 2
	s_nop 0
	s_waitcnt lgkmcnt(7)
	v_mfma_f32_16x16x32_bf16 v[118:121], v[22:25], v[210:213], v[18:21]
	ds_read_b128 v[210:213], v179 offset:25600
	s_nop 2
	s_nop 0
	s_nop 0
	s_nop 0
	s_nop 0
	s_nop 0
	s_nop 0
	s_waitcnt lgkmcnt(7)
	v_mfma_f32_16x16x32_bf16 v[18:21], v[122:125], v[214:217], 0
	ds_read_b128 v[214:217], v179 offset:28160
	s_waitcnt lgkmcnt(7)
	v_mfma_f32_16x16x32_bf16 v[122:125], v[130:133], v[218:221], v[18:21]
	ds_read_b128 v[218:221], v179 offset:20544
	s_nop 0
	s_waitcnt lgkmcnt(6)
	s_nop 3
	v_pk_mul_f32 v[20:21], v[108:109], v[138:139] op_sel_hi:[1,0]
	v_pk_mul_f32 v[18:19], v[106:107], v[138:139] op_sel_hi:[1,0]
	s_waitcnt lgkmcnt(5)
	s_nop 0
	v_mfma_f32_16x16x32_bf16 v[18:21], v[222:225], v[42:45], v[18:21]
	v_mul_f32_e64 v44, v104, v138
	v_mul_f32_e64 v45, v105, v138
	v_pk_mul_f32 v[42:43], v[102:103], v[138:139] op_sel_hi:[1,0]
	s_nop 0
	s_waitcnt lgkmcnt(3)
	v_mfma_f32_16x16x32_bf16 v[22:25], v[222:225], v[206:209], v[42:45]
	ds_read_b128 v[206:209], v179 offset:23104
	s_nop 2
	v_mul_f32_e64 v44, v100, v138
	v_mul_f32_e64 v45, v101, v138
	v_pk_mul_f32 v[42:43], v[98:99], v[138:139] op_sel_hi:[1,0]
	s_nop 0
	s_waitcnt lgkmcnt(3)
	v_mfma_f32_16x16x32_bf16 v[42:45], v[222:225], v[210:213], v[42:45]
	v_mul_f32_e64 v104, v128, v138
	v_mul_f32_e64 v105, v129, v138
	v_pk_mul_f32 v[102:103], v[126:127], v[138:139] op_sel_hi:[1,0]
	ds_read_b128 v[210:213], v179 offset:25664
	s_waitcnt lgkmcnt(3)
	s_nop 0
	v_mfma_f32_16x16x32_bf16 v[26:29], v[222:225], v[214:217], v[102:105]
	ds_read_b128 v[214:217], v179 offset:28224
	ds_read_b128 v[130:133], v176 offset:51200
	s_nop 0
	s_waitcnt lgkmcnt(4)
	v_mfma_f32_16x16x32_bf16 v[106:109], v[134:137], v[218:221], v[18:21]
	s_nop 2
	s_nop 0
	s_waitcnt lgkmcnt(3)
	v_mfma_f32_16x16x32_bf16 v[102:105], v[134:137], v[206:209], v[22:25]
	s_nop 0
	s_waitcnt lgkmcnt(2)
	v_mfma_f32_16x16x32_bf16 v[98:101], v[134:137], v[210:213], v[42:45]
	s_nop 0
	s_nop 0
	s_waitcnt lgkmcnt(1)
	v_mfma_f32_16x16x32_bf16 v[126:129], v[134:137], v[214:217], v[26:29]
	v_cvt_pk_bf16_f32 v18, v106, v107
	v_cvt_pk_bf16_f32 v19, v108, v109
	v_cvt_pk_bf16_f32 v20, v102, v103
	v_cvt_pk_bf16_f32 v21, v104, v105
	ds_write2st64_b64 v174, v[18:19], v[20:21] offset1:9
	v_cvt_pk_bf16_f32 v18, v98, v99
	v_cvt_pk_bf16_f32 v19, v100, v101
	s_nop 0
	v_cvt_pk_bf16_f32 v20, v126, v127
	v_cvt_pk_bf16_f32 v21, v128, v129
	ds_write2st64_b64 v174, v[18:19], v[20:21] offset0:18 offset1:27
	s_waitcnt vmcnt(19)
	ds_write_b128 v171, v[50:53] offset:51456
	s_waitcnt vmcnt(18)
	ds_write_b128 v171, v[62:65] offset:61696
	s_waitcnt vmcnt(17)
	ds_write_b128 v172, v[66:69]
	s_waitcnt vmcnt(16)
	ds_write_b128 v173, v[70:73]
	s_waitcnt vmcnt(15)
	ds_write_b128 v175, v[94:97]
	s_and_saveexec_b64 s[8:9], vcc
	s_cbranch_execz .LBB0_1605
	s_waitcnt vmcnt(14)
	ds_write_b128 v185, v[74:77]
.LBB0_1605:
	s_or_b64 exec, exec, s[8:9]
	s_or_b32 s7, s79, 31
	s_lshl_b32 s0, s7, 5
	s_or_b32 s0, s0, s78
	s_mov_b32 s1, s61
	s_lshl_b64 s[8:9], s[0:1], 13
	s_lshl_b32 s7, s7, 16
	v_lshl_add_u64 v[18:19], v[168:169], 0, s[8:9]
	s_or_b32 s5, s7, s5
	v_lshl_add_u64 v[20:21], v[166:167], 0, s[8:9]
	global_load_dwordx4 v[50:53], v[18:19], off
	global_load_dwordx4 v[62:65], v[20:21], off
	v_lshl_add_u64 v[18:19], v[164:165], 0, s[8:9]
	s_add_u32 s8, s77, s5
	s_addc_u32 s9, s28, 0
	v_lshl_add_u64 v[20:21], s[8:9], 0, v[156:157]
	s_lshl_b64 s[0:1], s[0:1], 8
	global_load_dwordx4 v[70:73], v[18:19], off
	global_load_dwordx4 v[74:77], v[20:21], off
	v_lshl_add_u64 v[18:19], s[8:9], 0, v[158:159]
	v_lshl_add_u64 v[20:21], v[162:163], 0, s[0:1]
	s_or_b32 s6, s6, 0x7c0
	s_mov_b32 s7, s61
	global_load_dwordx4 v[94:97], v[18:19], off
	global_load_dwordx4 v[66:69], v[20:21], off
	v_lshl_add_u64 v[18:19], v[160:161], 0, s[6:7]
	v_mov_b64_e32 v[20:21], s[80:81]
	v_mad_u64_u32 v[20:21], s[0:1], v18, s19, v[20:21]
	v_mad_i32_i24 v21, v19, s19, v21
	v_lshl_add_u64 v[18:19], v[20:21], 0, s[60:61]
	v_lshl_add_u64 v[18:19], v[18:19], 0, v[196:197]
	s_waitcnt lgkmcnt(7)
	v_pk_fma_f32 v[110:111], v[130:131], v[110:111], v[114:115]
	v_add_co_u32_e64 v24, s[44:45], s14, v18
	v_lshl_add_u64 v[114:115], v[152:153], 0, s[46:47]
	v_cvt_pk_bf16_f32 v110, v110, v110
	v_lshl_add_u64 v[22:23], v[18:19], 0, s[20:21]
	v_addc_co_u32_e64 v25, s[44:45], 0, v19, s[44:45]
	v_pk_fma_f32 v[112:113], v[132:133], v[112:113], v[116:117]
	v_lshlrev_b64 v[114:115], 12, v[114:115]
	v_and_b32_e32 v110, 0xffff, v110
	global_load_dwordx4 v[26:29], v[22:23], off offset:64
	global_load_dwordx4 v[18:21], v[22:23], off offset:128
	global_load_dwordx4 v[42:45], v[24:25], off offset:1024
	s_nop 0
	global_load_dwordx4 v[22:25], v[22:23], off offset:192
	v_lshl_add_u64 v[114:115], v[154:155], 0, v[114:115]
	global_store_short v[114:115], v110, off
	v_cvt_pk_bf16_f32 v110, v111, v111
	v_cvt_pk_bf16_f32 v112, v112, v112
	v_lshl_add_u64 v[116:117], v[114:115], 0, s[86:87]
	v_and_b32_e32 v110, 0xffff, v110
	global_store_short v[116:117], v110, off
	v_and_b32_e32 v112, 0xffff, v112
	v_lshl_add_u64 v[110:111], v[114:115], 0, s[74:75]
	global_store_short v[110:111], v112, off
	v_cvt_pk_bf16_f32 v112, v113, v113
	v_pk_fma_f32 v[118:119], v[130:131], v[118:119], v[122:123]
	v_and_b32_e32 v112, 0xffff, v112
	v_lshl_add_u64 v[110:111], v[114:115], 0, s[66:67]
	global_store_short v[110:111], v112, off
	v_cvt_pk_bf16_f32 v112, v118, v118
	v_and_b32_e32 v112, 0xffff, v112
	v_lshl_add_u64 v[110:111], v[114:115], 0, 32
	global_store_short v[110:111], v112, off
	v_cvt_pk_bf16_f32 v112, v119, v119
	v_pk_fma_f32 v[120:121], v[132:133], v[120:121], v[124:125]
	v_and_b32_e32 v112, 0xffff, v112
	v_lshl_add_u64 v[110:111], v[114:115], 0, s[22:23]
	global_store_short v[110:111], v112, off
	v_cvt_pk_bf16_f32 v112, v120, v120
	v_and_b32_e32 v112, 0xffff, v112
	v_lshl_add_u64 v[110:111], v[114:115], 0, s[12:13]
	global_store_short v[110:111], v112, off
	v_cvt_pk_bf16_f32 v112, v121, v121
	v_lshl_add_u64 v[110:111], v[114:115], 0, s[56:57]
	v_and_b32_e32 v112, 0xffff, v112
	global_store_short v[110:111], v112, off
	s_waitcnt lgkmcnt(0)
	s_barrier
	ds_read_b128 v[110:113], v188
	ds_read_b128 v[114:117], v188 offset:64
	ds_read_b128 v[206:209], v188 offset:128
	ds_read_b128 v[118:121], v150 offset:51456
	ds_read_b128 v[210:213], v188 offset:192
	ds_read_b128 v[122:125], v186 offset:61696
	ds_read_b128 v[130:133], v150 offset:51520
	ds_read_b128 v[214:217], v186 offset:61760
	ds_read_b128 v[218:221], v188 offset:4608
	ds_read_b128 v[222:225], v188 offset:4672
	s_waitcnt vmcnt(21) lgkmcnt(9)
	v_mfma_f32_16x16x32_bf16 v[110:113], v[46:49], v[110:113], 0
	v_readlane_b32 s0, v253, 18
	s_waitcnt lgkmcnt(8)
	v_mfma_f32_16x16x32_bf16 v[110:113], v[30:33], v[114:117], v[110:113]
	s_nop 0
	s_nop 0
	s_waitcnt lgkmcnt(7)
	v_mfma_f32_16x16x32_bf16 v[110:113], v[2:5], v[206:209], v[110:113]
	ds_read_b128 v[206:209], v188 offset:4736
	s_nop 0
	s_nop 0
	s_nop 0
	s_waitcnt vmcnt(20) lgkmcnt(6)
	v_mfma_f32_16x16x32_bf16 v[110:113], v[6:9], v[210:213], v[110:113]
	ds_read_b128 v[210:213], v188 offset:4800
	s_waitcnt lgkmcnt(6)
	v_mfma_f32_16x16x32_bf16 v[114:117], v[118:121], v[122:125], 0
	s_nop 0
	s_waitcnt lgkmcnt(4)
	v_mfma_f32_16x16x32_bf16 v[114:117], v[130:133], v[214:217], v[114:117]
	ds_read_b128 v[214:217], v186 offset:64256
	s_nop 0
	s_waitcnt lgkmcnt(4)
	v_mfma_f32_16x16x32_bf16 v[46:49], v[46:49], v[218:221], 0
	ds_read_b128 v[218:221], v186 offset:64320
	s_nop 0
	s_waitcnt lgkmcnt(4)
	v_mfma_f32_16x16x32_bf16 v[30:33], v[30:33], v[222:225], v[46:49]
	ds_read_b128 v[222:225], v183
	v_mov_b32_e32 v122, s0
	ds_read_b32 v134, v122
	s_nop 3
	s_nop 0
	s_waitcnt lgkmcnt(5)
	v_mfma_f32_16x16x32_bf16 v[2:5], v[2:5], v[206:209], v[30:33]
	ds_read_b128 v[206:209], v184
	s_nop 2
	s_nop 0
	s_waitcnt lgkmcnt(5)
	v_mfma_f32_16x16x32_bf16 v[46:49], v[6:9], v[210:213], v[2:5]
	ds_read_b128 v[210:213], v184 offset:2560
	s_nop 2
	s_nop 0
	s_nop 0
	s_nop 0
	s_nop 0
	s_nop 0
	s_waitcnt lgkmcnt(2)
	v_pk_mul_f32 v[104:105], v[104:105], v[134:135] op_sel_hi:[1,0]
	v_mfma_f32_16x16x32_bf16 v[2:5], v[118:121], v[214:217], 0
	ds_read_b128 v[214:217], v184 offset:5120
	v_mul_f32_e64 v102, v102, v134
	v_mul_f32_e64 v103, v103, v134
	v_pk_mul_f32 v[100:101], v[100:101], v[134:135] op_sel_hi:[1,0]
	v_pk_mul_f32 v[98:99], v[98:99], v[134:135] op_sel_hi:[1,0]
	v_mfma_f32_16x16x32_bf16 v[118:121], v[130:133], v[218:221], v[2:5]
	ds_read_b128 v[218:221], v184 offset:7680
	s_nop 0
	s_nop 1
	v_pk_mul_f32 v[4:5], v[108:109], v[134:135] op_sel_hi:[1,0]
	v_pk_mul_f32 v[2:3], v[106:107], v[134:135] op_sel_hi:[1,0]
	s_nop 0
	s_waitcnt lgkmcnt(2)
	v_mfma_f32_16x16x32_bf16 v[6:9], v[222:225], v[210:213], v[102:105]
	ds_read_b128 v[210:213], v183 offset:64
	s_nop 2
	s_nop 0
	s_waitcnt lgkmcnt(2)
	v_mfma_f32_16x16x32_bf16 v[98:101], v[222:225], v[214:217], v[98:101]
	ds_read_b128 v[214:217], v182
	s_nop 0
	v_mfma_f32_16x16x32_bf16 v[2:5], v[222:225], v[206:209], v[2:5]
	v_mul_f32_e64 v124, v128, v134
	v_mul_f32_e64 v125, v129, v134
	v_pk_mul_f32 v[122:123], v[126:127], v[134:135] op_sel_hi:[1,0]
	ds_read_b128 v[206:209], v182 offset:2560
	s_waitcnt lgkmcnt(3)
	s_nop 0
	v_mfma_f32_16x16x32_bf16 v[122:125], v[222:225], v[218:221], v[122:125]
	ds_read_b128 v[218:221], v182 offset:5120
	ds_read_b128 v[222:225], v182 offset:7680
	ds_read_b128 v[102:105], v181
	s_nop 0
	s_waitcnt lgkmcnt(4)
	v_mfma_f32_16x16x32_bf16 v[30:33], v[210:213], v[214:217], v[2:5]
	s_nop 2
	s_nop 0
	s_waitcnt lgkmcnt(3)
	v_mfma_f32_16x16x32_bf16 v[6:9], v[210:213], v[206:209], v[6:9]
	s_nop 0
	s_waitcnt lgkmcnt(2)
	v_mfma_f32_16x16x32_bf16 v[2:5], v[210:213], v[218:221], v[98:101]
	s_nop 2
	s_nop 0
	s_nop 0
	s_waitcnt lgkmcnt(1)
	v_mfma_f32_16x16x32_bf16 v[98:101], v[210:213], v[222:225], v[122:125]
	v_cvt_pk_bf16_f32 v106, v30, v31
	v_cvt_pk_bf16_f32 v107, v32, v33
	v_cvt_pk_bf16_f32 v108, v6, v7
	v_cvt_pk_bf16_f32 v109, v8, v9
	ds_write2st64_b64 v187, v[106:107], v[108:109] offset1:9
	v_cvt_pk_bf16_f32 v106, v2, v3
	v_cvt_pk_bf16_f32 v107, v4, v5
	s_nop 0
	v_cvt_pk_bf16_f32 v108, v98, v99
	v_cvt_pk_bf16_f32 v109, v100, v101
	ds_write2st64_b64 v187, v[106:107], v[108:109] offset0:18 offset1:27
	s_waitcnt vmcnt(19)
	ds_write_b128 v171, v[54:57]
	s_waitcnt vmcnt(18)
	ds_write_b128 v171, v[58:61] offset:10240
	s_waitcnt vmcnt(17)
	ds_write_b128 v171, v[78:81] offset:20480
	s_waitcnt vmcnt(16)
	ds_write_b128 v171, v[82:85] offset:30720
	s_waitcnt vmcnt(15)
	ds_write_b128 v178, v[90:93] offset:30720
	s_and_saveexec_b64 s[8:9], vcc
	s_cbranch_execz .LBB0_1607
	s_waitcnt vmcnt(14)
	ds_write_b128 v177, v[86:89] offset:51200
.LBB0_1607:
	s_or_b64 exec, exec, s[8:9]
	s_waitcnt lgkmcnt(7)
	v_pk_fma_f32 v[56:57], v[102:103], v[110:111], v[114:115]
	v_lshl_add_u64 v[58:59], v[152:153], 0, s[50:51]
	v_cvt_pk_bf16_f32 v56, v56, v56
	v_pk_fma_f32 v[54:55], v[104:105], v[112:113], v[116:117]
	v_lshlrev_b64 v[58:59], 12, v[58:59]
	v_and_b32_e32 v56, 0xffff, v56
	v_lshl_add_u64 v[58:59], v[154:155], 0, v[58:59]
	global_store_short v[58:59], v56, off
	v_cvt_pk_bf16_f32 v56, v57, v57
	v_cvt_pk_bf16_f32 v54, v54, v54
	v_pk_fma_f32 v[46:47], v[102:103], v[46:47], v[118:119]
	v_lshl_add_u64 v[60:61], v[58:59], 0, s[86:87]
	v_and_b32_e32 v56, 0xffff, v56
	global_store_short v[60:61], v56, off
	v_and_b32_e32 v54, 0xffff, v54
	v_lshl_add_u64 v[56:57], v[58:59], 0, s[74:75]
	global_store_short v[56:57], v54, off
	v_cvt_pk_bf16_f32 v54, v55, v55
	v_cvt_pk_bf16_f32 v46, v46, v46
	v_pk_fma_f32 v[48:49], v[104:105], v[48:49], v[120:121]
	v_lshl_add_u64 v[56:57], v[58:59], 0, s[66:67]
	v_and_b32_e32 v54, 0xffff, v54
	global_store_short v[56:57], v54, off
	v_and_b32_e32 v46, 0xffff, v46
	v_lshl_add_u64 v[54:55], v[58:59], 0, 32
	global_store_short v[54:55], v46, off
	v_cvt_pk_bf16_f32 v46, v47, v47
	v_cvt_pk_bf16_f32 v48, v48, v48
	v_lshl_add_u64 v[54:55], v[58:59], 0, s[22:23]
	v_and_b32_e32 v46, 0xffff, v46
	global_store_short v[54:55], v46, off
	v_and_b32_e32 v48, 0xffff, v48
	v_lshl_add_u64 v[46:47], v[58:59], 0, s[12:13]
	global_store_short v[46:47], v48, off
	v_cvt_pk_bf16_f32 v48, v49, v49
	v_lshl_add_u64 v[46:47], v[58:59], 0, s[56:57]
	v_and_b32_e32 v48, 0xffff, v48
	global_store_short v[46:47], v48, off
	s_waitcnt lgkmcnt(0)
	s_barrier
	ds_read_b128 v[46:49], v189
	ds_read_b128 v[54:57], v189 offset:64
	ds_read_b128 v[206:209], v189 offset:128
	ds_read_b128 v[58:61], v150
	ds_read_b128 v[210:213], v189 offset:192
	ds_read_b128 v[78:81], v186 offset:10240
	ds_read_b128 v[82:85], v150 offset:64
	ds_read_b128 v[214:217], v186 offset:10304
	ds_read_b128 v[218:221], v189 offset:4608
	s_waitcnt vmcnt(11) lgkmcnt(8)
	v_mfma_f32_16x16x32_bf16 v[46:49], v[38:41], v[46:49], 0
	s_waitcnt lgkmcnt(7)
	v_mfma_f32_16x16x32_bf16 v[46:49], v[34:37], v[54:57], v[46:49]
	s_nop 0
	s_nop 0
	s_waitcnt lgkmcnt(6)
	v_mfma_f32_16x16x32_bf16 v[46:49], v[10:13], v[206:209], v[46:49]
	s_nop 0
	s_nop 0
	s_nop 0
	s_waitcnt vmcnt(10) lgkmcnt(4)
	v_mfma_f32_16x16x32_bf16 v[46:49], v[14:17], v[210:213], v[46:49]
	s_waitcnt lgkmcnt(3)
	v_mfma_f32_16x16x32_bf16 v[54:57], v[58:61], v[78:81], 0
	s_nop 0
	s_waitcnt lgkmcnt(1)
	v_mfma_f32_16x16x32_bf16 v[54:57], v[82:85], v[214:217], v[54:57]
	s_nop 0
	s_waitcnt lgkmcnt(0)
	v_mfma_f32_16x16x32_bf16 v[38:41], v[38:41], v[218:221], 0
	ds_read_b128 v[78:81], v189 offset:4672
	ds_read_b128 v[206:209], v189 offset:4736
	ds_read_b128 v[210:213], v189 offset:4800
	ds_read_b128 v[214:217], v186 offset:12800
	ds_read_b128 v[218:221], v186 offset:12864
	ds_read_b128 v[222:225], v180 offset:30720
	s_waitcnt lgkmcnt(5)
	v_mfma_f32_16x16x32_bf16 v[34:37], v[34:37], v[78:81], v[38:41]
	ds_read_b32 v78, v197 offset:51452
	s_nop 4
	s_nop 0
	s_waitcnt lgkmcnt(5)
	v_mfma_f32_16x16x32_bf16 v[10:13], v[10:13], v[206:209], v[34:37]
	ds_read_b128 v[206:209], v179 offset:20480
	s_nop 2
	s_nop 0
	s_waitcnt lgkmcnt(5)
	v_mfma_f32_16x16x32_bf16 v[14:17], v[14:17], v[210:213], v[10:13]
	ds_read_b128 v[210:213], v179 offset:23040
	s_nop 2
	s_nop 0
	s_nop 0
	s_waitcnt lgkmcnt(5)
	v_mfma_f32_16x16x32_bf16 v[10:13], v[58:61], v[214:217], 0
	ds_read_b128 v[214:217], v179 offset:25600
	s_nop 0
	s_nop 0
	s_nop 0
	s_waitcnt lgkmcnt(3)
	v_pk_mul_f32 v[8:9], v[8:9], v[78:79] op_sel_hi:[1,0]
	v_mfma_f32_16x16x32_bf16 v[34:37], v[82:85], v[218:221], v[10:13]
	ds_read_b128 v[218:221], v179 offset:28160
	v_mul_f32_e64 v6, v6, v78
	v_mul_f32_e64 v7, v7, v78
	v_pk_mul_f32 v[4:5], v[4:5], v[78:79] op_sel_hi:[1,0]
	v_pk_mul_f32 v[2:3], v[2:3], v[78:79] op_sel_hi:[1,0]
	v_pk_mul_f32 v[12:13], v[32:33], v[78:79] op_sel_hi:[1,0]
	v_pk_mul_f32 v[10:11], v[30:31], v[78:79] op_sel_hi:[1,0]
	s_nop 0
	v_pk_mul_f32 v[80:81], v[100:101], v[78:79] op_sel_hi:[1,0]
	s_waitcnt lgkmcnt(3)
	v_mfma_f32_16x16x32_bf16 v[10:13], v[222:225], v[206:209], v[10:13]
	ds_read_b128 v[206:209], v180 offset:30784
	s_nop 0
	v_pk_mul_f32 v[78:79], v[98:99], v[78:79] op_sel_hi:[1,0]
	s_waitcnt lgkmcnt(3)
	v_mfma_f32_16x16x32_bf16 v[6:9], v[222:225], v[210:213], v[6:9]
	ds_read_b128 v[210:213], v179 offset:20544
	s_nop 0
	s_waitcnt lgkmcnt(3)
	v_mfma_f32_16x16x32_bf16 v[2:5], v[222:225], v[214:217], v[2:5]
	ds_read_b128 v[214:217], v179 offset:23104
	s_nop 0
	s_waitcnt lgkmcnt(3)
	v_mfma_f32_16x16x32_bf16 v[38:41], v[222:225], v[218:221], v[78:81]
	ds_read_b128 v[218:221], v179 offset:25664
	ds_read_b128 v[78:81], v179 offset:28224
	s_nop 0
	s_waitcnt lgkmcnt(3)
	v_mfma_f32_16x16x32_bf16 v[10:13], v[206:209], v[210:213], v[10:13]
	s_nop 0
	s_waitcnt lgkmcnt(2)
	v_mfma_f32_16x16x32_bf16 v[6:9], v[206:209], v[214:217], v[6:9]
	s_nop 0
	s_waitcnt lgkmcnt(1)
	v_mfma_f32_16x16x32_bf16 v[2:5], v[206:209], v[218:221], v[2:5]
	ds_read_b128 v[30:33], v176 offset:51200
	s_nop 0
	s_nop 0
	s_waitcnt lgkmcnt(1)
	v_mfma_f32_16x16x32_bf16 v[38:41], v[206:209], v[78:81], v[38:41]
	v_cvt_pk_bf16_f32 v58, v10, v11
	v_cvt_pk_bf16_f32 v59, v12, v13
	v_cvt_pk_bf16_f32 v60, v6, v7
	v_cvt_pk_bf16_f32 v61, v8, v9
	ds_write2st64_b64 v174, v[58:59], v[60:61] offset1:9
	v_cvt_pk_bf16_f32 v58, v2, v3
	v_cvt_pk_bf16_f32 v59, v4, v5
	s_nop 0
	v_cvt_pk_bf16_f32 v60, v38, v39
	v_cvt_pk_bf16_f32 v61, v40, v41
	ds_write2st64_b64 v174, v[58:59], v[60:61] offset0:18 offset1:27
	s_waitcnt vmcnt(9)
	ds_write_b128 v171, v[50:53] offset:51456
	s_waitcnt vmcnt(8)
	ds_write_b128 v171, v[62:65] offset:61696
	s_waitcnt vmcnt(7)
	ds_write_b128 v172, v[70:73]
	s_waitcnt vmcnt(6)
	ds_write_b128 v173, v[74:77]
	s_waitcnt vmcnt(5)
	ds_write_b128 v175, v[94:97]
	s_and_saveexec_b64 s[8:9], vcc
	s_cbranch_execz .LBB0_1609
	s_waitcnt vmcnt(4)
	ds_write_b128 v185, v[66:69]
.LBB0_1609:
	s_or_b64 exec, exec, s[8:9]
	s_waitcnt lgkmcnt(7)
	v_pk_fma_f32 v[14:15], v[30:31], v[14:15], v[34:35]
	v_pk_fma_f32 v[30:31], v[30:31], v[46:47], v[54:55]
	v_lshl_add_u64 v[34:35], v[152:153], 0, s[48:49]
	v_cvt_pk_bf16_f32 v30, v30, v30
	v_pk_fma_f32 v[16:17], v[32:33], v[16:17], v[36:37]
	v_pk_fma_f32 v[32:33], v[32:33], v[48:49], v[56:57]
	v_lshlrev_b64 v[34:35], 12, v[34:35]
	v_and_b32_e32 v30, 0xffff, v30
	v_lshl_add_u64 v[34:35], v[154:155], 0, v[34:35]
	global_store_short v[34:35], v30, off
	s_mov_b64 s[8:9], 0x1000
	v_cvt_pk_bf16_f32 v30, v31, v31
	v_cvt_pk_bf16_f32 v32, v32, v32
	v_lshl_add_u64 v[36:37], v[34:35], 0, s[8:9]
	v_and_b32_e32 v30, 0xffff, v30
	global_store_short v[36:37], v30, off
	s_mov_b64 s[0:1], 0x2000
	v_and_b32_e32 v32, 0xffff, v32
	v_lshl_add_u64 v[30:31], v[34:35], 0, s[0:1]
	global_store_short v[30:31], v32, off
	v_cvt_pk_bf16_f32 v32, v33, v33
	v_cvt_pk_bf16_f32 v14, v14, v14
	v_lshl_add_u64 v[30:31], v[34:35], 0, s[66:67]
	v_and_b32_e32 v32, 0xffff, v32
	global_store_short v[30:31], v32, off
	v_and_b32_e32 v14, 0xffff, v14
	v_lshl_add_u64 v[30:31], v[34:35], 0, 32
	global_store_short v[30:31], v14, off
	s_mov_b64 s[34:35], 0x1020
	v_cvt_pk_bf16_f32 v14, v15, v15
	v_cvt_pk_bf16_f32 v16, v16, v16
	v_lshl_add_u64 v[30:31], v[34:35], 0, s[34:35]
	v_and_b32_e32 v14, 0xffff, v14
	global_store_short v[30:31], v14, off
	s_mov_b64 s[44:45], 0x2020
	v_and_b32_e32 v16, 0xffff, v16
	v_lshl_add_u64 v[14:15], v[34:35], 0, s[44:45]
	global_store_short v[14:15], v16, off
	s_mov_b64 s[46:47], 0x3020
	v_cvt_pk_bf16_f32 v16, v17, v17
	v_lshl_add_u64 v[14:15], v[34:35], 0, s[46:47]
	v_and_b32_e32 v16, 0xffff, v16
	global_store_short v[14:15], v16, off
	s_waitcnt lgkmcnt(0)
	s_barrier
	ds_read_b128 v[14:17], v188
	ds_read_b128 v[30:33], v188 offset:64
	ds_read_b128 v[206:209], v188 offset:128
	ds_read_b128 v[34:37], v150 offset:51456
	ds_read_b128 v[210:213], v188 offset:192
	ds_read_b128 v[46:49], v186 offset:61696
	ds_read_b128 v[50:53], v150 offset:51520
	ds_read_b128 v[214:217], v186 offset:61760
	ds_read_b128 v[218:221], v188 offset:4608
	s_waitcnt vmcnt(1) lgkmcnt(8)
	v_mfma_f32_16x16x32_bf16 v[14:17], v[42:45], v[14:17], 0
	v_readlane_b32 s5, v253, 18
	v_lshlrev_b32_e32 v196, 2, v151
	s_mov_b64 s[86:87], 0x1000
	s_waitcnt lgkmcnt(7)
	v_mfma_f32_16x16x32_bf16 v[14:17], v[26:29], v[30:33], v[14:17]
	s_nop 0
	s_nop 0
	s_mov_b64 s[74:75], 0x2000
	s_mov_b64 s[22:23], 0x1020
	s_waitcnt lgkmcnt(6)
	v_mfma_f32_16x16x32_bf16 v[14:17], v[18:21], v[206:209], v[14:17]
	s_nop 0
	s_nop 0
	s_nop 0
	s_mov_b64 s[12:13], 0x2020
	s_waitcnt vmcnt(0) lgkmcnt(4)
	v_mfma_f32_16x16x32_bf16 v[14:17], v[22:25], v[210:213], v[14:17]
	s_mov_b64 s[56:57], 0x3020
	s_waitcnt lgkmcnt(3)
	v_mfma_f32_16x16x32_bf16 v[30:33], v[34:37], v[46:49], 0
	s_nop 0
	s_waitcnt lgkmcnt(1)
	v_mfma_f32_16x16x32_bf16 v[30:33], v[50:53], v[214:217], v[30:33]
	s_nop 0
	s_waitcnt lgkmcnt(0)
	v_mfma_f32_16x16x32_bf16 v[42:45], v[42:45], v[218:221], 0
	ds_read_b128 v[46:49], v188 offset:4672
	ds_read_b128 v[206:209], v188 offset:4736
	ds_read_b128 v[210:213], v188 offset:4800
	ds_read_b128 v[214:217], v186 offset:64256
	ds_read_b128 v[218:221], v186 offset:64320
	ds_read_b128 v[222:225], v183
	s_waitcnt lgkmcnt(5)
	v_mfma_f32_16x16x32_bf16 v[26:29], v[26:29], v[46:49], v[42:45]
	s_nop 4
	s_nop 0
	s_waitcnt lgkmcnt(4)
	v_mfma_f32_16x16x32_bf16 v[18:21], v[18:21], v[206:209], v[26:29]
	s_nop 2
	s_nop 0
	v_mov_b32_e32 v42, s5
	ds_read_b32 v46, v42
	ds_read_b128 v[206:209], v184
	s_waitcnt lgkmcnt(5)
	v_mfma_f32_16x16x32_bf16 v[18:21], v[22:25], v[210:213], v[18:21]
	ds_read_b128 v[210:213], v184 offset:2560
	s_nop 0
	s_nop 0
	s_waitcnt lgkmcnt(5)
	v_mfma_f32_16x16x32_bf16 v[22:25], v[34:37], v[214:217], 0
	ds_read_b128 v[214:217], v184 offset:5120
	s_nop 0
	s_nop 0
	s_nop 0
	s_waitcnt lgkmcnt(3)
	v_pk_mul_f32 v[12:13], v[12:13], v[46:47] op_sel_hi:[1,0]
	v_mfma_f32_16x16x32_bf16 v[22:25], v[50:53], v[218:221], v[22:25]
	ds_read_b128 v[218:221], v184 offset:7680
	v_mul_f32_e64 v10, v10, v46
	v_mul_f32_e64 v11, v11, v46
	s_nop 0
	v_pk_mul_f32 v[8:9], v[8:9], v[46:47] op_sel_hi:[1,0]
	s_waitcnt lgkmcnt(3)
	v_mfma_f32_16x16x32_bf16 v[10:13], v[222:225], v[206:209], v[10:13]
	ds_read_b128 v[206:209], v183 offset:64
	s_nop 0
	v_pk_mul_f32 v[6:7], v[6:7], v[46:47] op_sel_hi:[1,0]
	v_pk_mul_f32 v[4:5], v[4:5], v[46:47] op_sel_hi:[1,0]
	v_pk_mul_f32 v[2:3], v[2:3], v[46:47] op_sel_hi:[1,0]
	s_waitcnt lgkmcnt(3)
	v_mfma_f32_16x16x32_bf16 v[6:9], v[222:225], v[210:213], v[6:9]
	ds_read_b128 v[210:213], v182
	s_nop 0
	v_pk_mul_f32 v[40:41], v[40:41], v[46:47] op_sel_hi:[1,0]
	v_pk_mul_f32 v[38:39], v[38:39], v[46:47] op_sel_hi:[1,0]
	s_waitcnt lgkmcnt(3)
	v_mfma_f32_16x16x32_bf16 v[2:5], v[222:225], v[214:217], v[2:5]
	ds_read_b128 v[214:217], v182 offset:2560
	s_nop 0
	s_waitcnt lgkmcnt(3)
	v_mfma_f32_16x16x32_bf16 v[26:29], v[222:225], v[218:221], v[38:41]
	ds_read_b128 v[218:221], v182 offset:5120
	ds_read_b128 v[222:225], v182 offset:7680
	ds_read_b128 v[38:41], v181
	s_nop 0
	s_waitcnt lgkmcnt(4)
	v_mfma_f32_16x16x32_bf16 v[10:13], v[206:209], v[210:213], v[10:13]
	s_nop 0
	s_waitcnt lgkmcnt(3)
	v_mfma_f32_16x16x32_bf16 v[6:9], v[206:209], v[214:217], v[6:9]
	s_nop 0
	s_waitcnt lgkmcnt(2)
	v_mfma_f32_16x16x32_bf16 v[2:5], v[206:209], v[218:221], v[2:5]
	s_nop 0
	s_nop 0
	s_waitcnt lgkmcnt(0)
	v_pk_fma_f32 v[14:15], v[38:39], v[14:15], v[30:31]
	v_mfma_f32_16x16x32_bf16 v[26:29], v[206:209], v[222:225], v[26:29]
	v_cvt_pk_bf16_f32 v34, v10, v11
	v_cvt_pk_bf16_f32 v35, v12, v13
	v_cvt_pk_bf16_f32 v36, v6, v7
	v_cvt_pk_bf16_f32 v37, v8, v9
	ds_write2st64_b64 v187, v[34:35], v[36:37] offset1:9
	v_cvt_pk_bf16_f32 v34, v2, v3
	v_cvt_pk_bf16_f32 v35, v4, v5
	s_nop 0
	v_cvt_pk_bf16_f32 v36, v26, v27
	v_cvt_pk_bf16_f32 v37, v28, v29
	v_pk_fma_f32 v[18:19], v[38:39], v[18:19], v[22:23]
	v_lshl_add_u64 v[22:23], v[152:153], 0, s[6:7]
	v_cvt_pk_bf16_f32 v14, v14, v14
	ds_write2st64_b64 v187, v[34:35], v[36:37] offset0:18 offset1:27
	v_pk_fma_f32 v[16:17], v[40:41], v[16:17], v[32:33]
	v_lshlrev_b64 v[22:23], 12, v[22:23]
	v_and_b32_e32 v14, 0xffff, v14
	v_lshl_add_u64 v[22:23], v[154:155], 0, v[22:23]
	global_store_short v[22:23], v14, off
	v_cvt_pk_bf16_f32 v14, v15, v15
	v_cvt_pk_bf16_f32 v16, v16, v16
	v_pk_fma_f32 v[20:21], v[40:41], v[20:21], v[24:25]
	v_lshl_add_u64 v[24:25], v[22:23], 0, s[8:9]
	v_and_b32_e32 v14, 0xffff, v14
	global_store_short v[24:25], v14, off
	v_and_b32_e32 v16, 0xffff, v16
	v_lshl_add_u64 v[14:15], v[22:23], 0, s[0:1]
	global_store_short v[14:15], v16, off
	v_cvt_pk_bf16_f32 v16, v17, v17
	v_and_b32_e32 v16, 0xffff, v16
	s_lshl_b32 s0, s31, 20
	v_readlane_b32 s1, v255, 2
	v_lshl_add_u64 v[14:15], v[22:23], 0, s[66:67]
	global_store_short v[14:15], v16, off
	v_cvt_pk_bf16_f32 v16, v18, v18
	s_add_i32 s0, s0, s1
	v_readlane_b32 s1, v255, 21
	v_and_b32_e32 v16, 0xffff, v16
	s_add_u32 s0, s1, s0
	v_readlane_b32 s1, v255, 22
	v_lshl_add_u64 v[14:15], v[22:23], 0, 32
	global_store_short v[14:15], v16, off
	v_cvt_pk_bf16_f32 v16, v19, v19
	s_addc_u32 s1, s1, 0
	s_lshl_b32 s5, s78, 15
	v_and_b32_e32 v16, 0xffff, v16
	s_add_u32 s6, s0, s5
	v_lshl_add_u64 v[14:15], v[22:23], 0, s[34:35]
	global_store_short v[14:15], v16, off
	v_cvt_pk_bf16_f32 v16, v20, v20
	s_addc_u32 s7, s1, 0
	s_ashr_i32 s5, s4, 31
	v_and_b32_e32 v16, 0xffff, v16
	s_lshl_b64 s[0:1], s[4:5], 2
	v_lshl_add_u64 v[14:15], v[22:23], 0, s[44:45]
	global_store_short v[14:15], v16, off
	v_cvt_pk_bf16_f32 v16, v21, v21
	s_add_u32 s0, s6, s0
	v_lshl_add_u64 v[14:15], v[22:23], 0, s[46:47]
	v_and_b32_e32 v16, 0xffff, v16
	s_addc_u32 s1, s7, s1
	global_store_short v[14:15], v16, off
	v_lshlrev_b32_e32 v14, 9, v170
	v_lshl_add_u64 v[16:17], s[0:1], 0, v[196:197]
	v_mov_b32_e32 v15, v197
	v_lshl_add_u64 v[14:15], v[16:17], 0, v[14:15]
	s_movk_i32 s0, 0x2000
	global_store_dwordx4 v[14:15], v[10:13], off
	s_mov_b64 s[4:5], 0
	s_nop 0
	v_add_co_u32_e32 v10, vcc, s0, v14
	s_nop 1
	v_addc_co_u32_e32 v11, vcc, 0, v15, vcc
	global_store_dwordx4 v[10:11], v[6:9], off
	s_nop 1
	v_add_co_u32_e32 v6, vcc, 0x4000, v14
	s_nop 1
	v_addc_co_u32_e32 v7, vcc, 0, v15, vcc
	global_store_dwordx4 v[6:7], v[2:5], off
	s_nop 1
	v_add_co_u32_e32 v2, vcc, 0x6000, v14
	s_nop 1
	v_addc_co_u32_e32 v3, vcc, 0, v15, vcc
	global_store_dwordx4 v[2:3], v[26:29], off
	s_waitcnt lgkmcnt(0)
	s_barrier

.LBB0_1627:
	s_lshl_b64 s[8:9], s[8:9], 8
	s_add_u32 s8, s84, s8
	v_lshl_add_u64 v[2:3], v[4:5], 0, s[48:49]
	s_addc_u32 s9, s85, s9
	global_load_dwordx4 v[6:9], v[4:5], off
	global_load_dword v138, v196, s[8:9]
	v_lshrrev_b32_e32 v106, 1, v106
	global_load_dwordx4 v[2:5], v[2:3], off
	v_or_b32_e32 v141, s4, v159
	s_movk_i32 s0, 0x120
	v_and_b32_e32 v151, 24, v106
	v_mul_lo_u32 v107, v141, s0
	s_add_i32 s0, 0, 0x1c000
	v_lshlrev_b32_e32 v139, 1, v151
	v_add3_u32 v143, s0, v139, v137
	v_readlane_b32 s0, v253, 19
	v_add_u32_e32 v162, 0, v107
	s_waitcnt lgkmcnt(0)
	s_barrier
	v_mov_b32_e32 v106, s0
	v_add_u32_e32 v168, v162, v139
	ds_read_b128 v[178:181], v168
	ds_read_b128 v[110:113], v143
	ds_read_b128 v[116:119], v143 offset:4608
	ds_read_b128 v[182:185], v168 offset:64
	ds_read_b128 v[120:123], v143 offset:64
	ds_read_b128 v[186:189], v143 offset:4672
	ds_read_b128 v[190:193], v168 offset:128
	ds_read_b128 v[206:209], v143 offset:128
	ds_read_b128 v[210:213], v143 offset:4736
	ds_read_b128 v[214:217], v168 offset:192
	ds_read_b128 v[218:221], v143 offset:192
	ds_read_b128 v[222:225], v143 offset:4800
	v_mad_u32_u24 v114, v159, s26, v106
	s_nop 0
	s_nop 0
	s_nop 0
	s_waitcnt lgkmcnt(10)
	v_mfma_f32_16x16x32_bf16 v[110:113], v[178:181], v[110:113], 0
	v_add_u32_e32 v115, s50, v114
	s_and_b64 vcc, exec, s[44:45]
	v_add_u32_e32 v170, v115, v130
	s_waitcnt lgkmcnt(9)
	v_mfma_f32_16x16x32_bf16 v[106:109], v[178:181], v[116:119], 0
	s_nop 0
	s_nop 0
	s_waitcnt lgkmcnt(7)
	v_mfma_f32_16x16x32_bf16 v[110:113], v[182:185], v[120:123], v[110:113]
	s_nop 0
	s_waitcnt lgkmcnt(6)
	v_mfma_f32_16x16x32_bf16 v[106:109], v[182:185], v[186:189], v[106:109]
	s_nop 0
	s_nop 0
	s_waitcnt lgkmcnt(4)
	v_mfma_f32_16x16x32_bf16 v[110:113], v[190:193], v[206:209], v[110:113]
	s_nop 0
	s_waitcnt lgkmcnt(3)
	v_mfma_f32_16x16x32_bf16 v[116:119], v[190:193], v[210:213], v[106:109]
	s_nop 0
	s_nop 1
	s_nop 0
	s_waitcnt lgkmcnt(1)
	v_mfma_f32_16x16x32_bf16 v[106:109], v[214:217], v[218:221], v[110:113]
	s_nop 2
	s_nop 0
	s_waitcnt lgkmcnt(0)
	v_mfma_f32_16x16x32_bf16 v[110:113], v[214:217], v[222:225], v[116:119]
	s_cbranch_vccz .LBB0_1629
	s_nop 0
	v_sub_f32_e32 v115, v81, v109
	v_sub_f32_e32 v117, v80, v108
	v_sub_f32_e32 v116, v79, v107
	v_sub_f32_e32 v118, v78, v106
	v_cvt_pk_bf16_f32 v116, v118, v116
	v_cvt_pk_bf16_f32 v117, v117, v115
	v_sub_f32_e32 v115, v69, v113
	v_sub_f32_e32 v119, v68, v112
	v_sub_f32_e32 v118, v67, v111
	v_sub_f32_e32 v120, v66, v110
	v_cvt_pk_bf16_f32 v118, v120, v118
	v_cvt_pk_bf16_f32 v119, v119, v115
	ds_write2st64_b64 v170, v[116:117], v[118:119] offset1:5

.LBB0_1631:
	v_mul_u32_u24_e32 v152, 0xa0, v159
	v_readlane_b32 s0, v253, 19
	s_andn2_b64 vcc, exec, s[46:47]
	s_nop 0
	v_add3_u32 v169, s0, v139, v152
	s_cbranch_vccnz .LBB0_1633
	ds_read_b128 v[118:121], v169
	ds_read_b128 v[114:117], v169 offset:64
	ds_read_b128 v[126:129], v169 offset:2560
	ds_read_b128 v[122:125], v169 offset:2624
	s_waitcnt lgkmcnt(7)
	s_nop 0
	s_waitcnt lgkmcnt(6)
	s_nop 0
	s_waitcnt lgkmcnt(5)
	s_nop 0
	s_waitcnt lgkmcnt(4)
	s_nop 0
	s_waitcnt lgkmcnt(3)
	v_mfma_f32_16x16x32_bf16 v[106:109], v[78:81], v[118:121], v[106:109]
	s_waitcnt lgkmcnt(1)
	v_mfma_f32_16x16x32_bf16 v[78:81], v[78:81], v[126:129], v[110:113]
	v_mfma_f32_16x16x32_bf16 v[106:109], v[66:69], v[114:117], v[106:109]
	s_waitcnt lgkmcnt(0)
	v_mfma_f32_16x16x32_bf16 v[110:113], v[66:69], v[122:125], v[78:81]
.LBB0_1633:
	s_nop 4
	v_lshlrev_b32_e32 v78, 7, v141
	v_sub_u32_e32 v78, v162, v78
	v_add_u32_e32 v66, s4, v159
	v_lshl_add_u32 v173, v151, 1, v78
	ds_read_b128 v[78:81], v173 offset:36864
	ds_read_b128 v[178:181], v173 offset:36928
	v_subrev_u32_e32 v66, 64, v66
	s_nop 0
	v_ashrrev_i32_e32 v67, 31, v66
	v_lshlrev_b64 v[66:67], 7, v[66:67]
	v_lshl_add_u64 v[152:153], s[84:85], 0, v[196:197]
	v_lshl_add_u64 v[66:67], s[82:83], 0, v[66:67]
	v_lshlrev_b32_e32 v196, 1, v130
	v_lshl_add_u64 v[154:155], v[66:67], 0, v[196:197]
	v_lshl_add_u64 v[66:67], s[64:65], 0, v[132:133]
	s_ashr_i32 s53, s52, 31
	v_lshl_add_u64 v[66:67], v[134:135], 2, v[66:67]
	s_lshl_b64 s[96:97], s[52:53], 11
	v_lshl_add_u64 v[156:157], v[144:145], 2, v[66:67]
	v_or_b32_e32 v67, s97, v145
	v_or_b32_e32 v66, s96, v144
	v_lshl_add_u64 v[132:133], v[66:67], 0, s[60:61]
	s_waitcnt vmcnt(27)
	v_mul_f32_e32 v66, 0, v140
	v_mov_b32_e32 v67, v66
	v_mov_b32_e32 v68, v66
	v_mov_b32_e32 v69, v66
	v_add_u32_e32 v137, s34, v137
	s_or_b32 s46, s6, 32
	s_waitcnt lgkmcnt(1)
	v_mfma_f32_16x16x32_bf16 v[118:121], v[78:81], v[118:121], v[66:69]
	s_lshl_b32 s0, s31, 8
	v_readlane_b32 s34, v253, 62
	v_readlane_b32 s35, v253, 63
	v_mfma_f32_16x16x32_bf16 v[66:69], v[78:81], v[126:129], v[66:69]
	s_nop 0
	s_add_u32 s0, s34, s0
	s_addc_u32 s1, s35, 0
	s_lshl_b32 s5, s78, 6
	s_add_u32 s34, s0, s5
	s_waitcnt lgkmcnt(0)
	v_mfma_f32_16x16x32_bf16 v[118:121], v[178:181], v[114:117], v[118:121]
	s_addc_u32 s35, s1, 0
	v_lshlrev_b32_e32 v196, 1, v159
	s_ashr_i32 s47, s46, 31
	v_mfma_f32_16x16x32_bf16 v[114:117], v[178:181], v[122:125], v[66:69]
	v_lshl_add_u64 v[134:135], s[34:35], 0, v[196:197]
	s_lshl_b64 s[34:35], s[46:47], 13
	s_lshl_b64 s[50:51], s[46:47], 14
	v_add_u32_e32 v150, 0x4800, v150
	s_add_u32 vcc_lo, s95, s50
	v_cvt_pk_bf16_f32 v66, v118, v119
	v_cvt_pk_bf16_f32 v67, v120, v121
	v_add_u32_e32 v172, v137, v130
	v_cvt_pk_bf16_f32 v68, v114, v115
	v_cvt_pk_bf16_f32 v69, v116, v117
	v_add_u32_e32 v174, 0, v150
	v_readlane_b32 s0, v253, 20
	s_addc_u32 vcc_hi, s3, s51
	ds_write2st64_b64 v172, v[66:67], v[68:69] offset1:9
	s_waitcnt vmcnt(26)
	ds_write_b128 v161, v[10:13] offset:57344
	s_waitcnt vmcnt(25)
	ds_write_b128 v163, v[14:17] offset:57344
	s_waitcnt vmcnt(24)
	ds_write_b128 v174, v[58:61] offset:57344
	s_waitcnt vmcnt(23)
	ds_write_b128 v165, v[70:73] offset:57344
	v_add_u32_e32 v175, s0, v131
	v_add_u32_e32 v176, s0, v136
	s_add_u32 s0, s29, s50
	v_lshl_add_u64 v[10:11], vcc, 0, v[146:147]
	s_addc_u32 s1, s94, s51
	global_load_dwordx4 v[58:61], v[10:11], off
	v_lshl_add_u64 v[10:11], vcc, 0, v[148:149]
	s_waitcnt vmcnt(23)
	ds_write_b128 v175, v[62:65]
	s_add_u32 s50, s2, s50
	global_load_dwordx4 v[62:65], v[10:11], off
	v_lshl_add_u64 v[10:11], s[0:1], 0, v[146:147]
	s_addc_u32 s51, s10, s51
	global_load_dwordx4 v[66:69], v[10:11], off
	v_lshl_add_u64 v[10:11], s[0:1], 0, v[148:149]
	global_load_dwordx4 v[70:73], v[10:11], off
	v_lshl_add_u64 v[10:11], s[50:51], 0, v[146:147]
	s_waitcnt vmcnt(25)
	ds_write_b128 v176, v[74:77]
	global_load_dwordx4 v[74:77], v[10:11], off
	v_lshl_add_u64 v[10:11], s[50:51], 0, v[148:149]
	s_lshl_b64 s[0:1], s[46:47], 15
	global_load_dwordx4 v[78:81], v[10:11], off
	v_lshl_add_u64 v[10:11], v[156:157], 0, s[0:1]
	v_lshl_add_u64 v[12:13], v[154:155], 0, s[34:35]
	s_and_b64 s[0:1], exec, s[44:45]
	s_cselect_b32 s60, 0x1000, 64
	v_cndmask_b32_e64 v11, v13, v11, s[44:45]
	v_cndmask_b32_e64 v10, v12, v10, s[44:45]
	s_lshl_b64 s[0:1], s[46:47], 8
	global_load_dwordx4 v[14:17], v[10:11], off
	v_lshl_add_u64 v[10:11], v[10:11], 0, s[60:61]
	v_lshl_add_u64 v[122:123], v[152:153], 0, s[0:1]
	global_load_dwordx4 v[10:13], v[10:11], off
	s_andn2_b64 vcc, exec, s[48:49]
	global_load_dword v140, v[122:123], off
	v_cndmask_b32_e64 v122, 0, 1, s[48:49]
	v_cmp_ne_u32_e64 s[46:47], 1, v122
	v_lshlrev_b64 v[122:123], 11, v[132:133]
	v_lshl_add_u64 v[150:151], v[134:135], 0, v[122:123]
	s_cbranch_vccnz .LBB0_1635
	v_cvt_pk_bf16_f32 v106, v106, v106
	v_and_b32_e32 v106, 0xffff, v106
	global_store_short v[150:151], v106, off
	s_mov_b64 s[0:1], 0x800
	v_cvt_pk_bf16_f32 v106, v107, v107
	v_cvt_pk_bf16_f32 v108, v108, v108
	v_lshl_add_u64 v[122:123], v[150:151], 0, s[0:1]
	v_and_b32_e32 v106, 0xffff, v106
	global_store_short v[122:123], v106, off
	v_and_b32_e32 v108, 0xffff, v108
	v_lshl_add_u64 v[106:107], v[150:151], 0, s[86:87]
	global_store_short v[106:107], v108, off
	v_cvt_pk_bf16_f32 v108, v109, v109
	s_mov_b64 s[0:1], 0x1800
	v_and_b32_e32 v108, 0xffff, v108
	v_lshl_add_u64 v[106:107], v[150:151], 0, s[0:1]
	global_store_short v[106:107], v108, off
	v_cvt_pk_bf16_f32 v108, v110, v110
	v_and_b32_e32 v108, 0xffff, v108
	v_lshl_add_u64 v[106:107], v[150:151], 0, 32
	global_store_short v[106:107], v108, off
	v_cvt_pk_bf16_f32 v108, v111, v111
	s_mov_b64 s[0:1], 0x820
	v_and_b32_e32 v108, 0xffff, v108
	v_lshl_add_u64 v[106:107], v[150:151], 0, s[0:1]
	global_store_short v[106:107], v108, off
	v_cvt_pk_bf16_f32 v108, v112, v112
	v_and_b32_e32 v108, 0xffff, v108
	v_lshl_add_u64 v[106:107], v[150:151], 0, s[22:23]
	global_store_short v[106:107], v108, off
	s_mov_b64 s[0:1], 0x1820
	v_cvt_pk_bf16_f32 v108, v113, v113
	v_lshl_add_u64 v[106:107], v[150:151], 0, s[0:1]
	v_and_b32_e32 v108, 0xffff, v108
	global_store_short v[106:107], v108, off
.LBB0_1635:
	s_waitcnt lgkmcnt(0)
	s_barrier
	ds_read_b128 v[106:109], v168 offset:57344
	ds_read_b128 v[110:113], v143
	ds_read_b128 v[122:125], v143 offset:4608
	ds_read_b128 v[178:181], v168 offset:57408
	ds_read_b128 v[126:129], v143 offset:64
	ds_read_b128 v[182:185], v143 offset:4672
	ds_read_b128 v[186:189], v168 offset:57472
	ds_read_b128 v[190:193], v143 offset:128
	ds_read_b128 v[206:209], v143 offset:4736
	ds_read_b128 v[210:213], v168 offset:57536
	ds_read_b128 v[214:217], v143 offset:192
	ds_read_b128 v[218:221], v143 offset:4800
	s_andn2_b64 vcc, exec, s[44:45]
	s_waitcnt lgkmcnt(10)
	v_mfma_f32_16x16x32_bf16 v[110:113], v[106:109], v[110:113], 0
	s_waitcnt lgkmcnt(9)
	v_mfma_f32_16x16x32_bf16 v[106:109], v[106:109], v[122:125], 0
	s_nop 0
	s_nop 0
	s_waitcnt lgkmcnt(7)
	v_mfma_f32_16x16x32_bf16 v[110:113], v[178:181], v[126:129], v[110:113]
	s_nop 0
	s_waitcnt lgkmcnt(6)
	v_mfma_f32_16x16x32_bf16 v[106:109], v[178:181], v[182:185], v[106:109]
	s_nop 0
	s_nop 0
	s_waitcnt lgkmcnt(4)
	v_mfma_f32_16x16x32_bf16 v[110:113], v[186:189], v[190:193], v[110:113]
	s_nop 0
	s_waitcnt lgkmcnt(3)
	v_mfma_f32_16x16x32_bf16 v[106:109], v[186:189], v[206:209], v[106:109]
	s_nop 0
	s_nop 0
	s_waitcnt lgkmcnt(1)
	v_mfma_f32_16x16x32_bf16 v[122:125], v[210:213], v[214:217], v[110:113]
	s_nop 2
	s_nop 0
	s_waitcnt lgkmcnt(0)
	v_mfma_f32_16x16x32_bf16 v[126:129], v[210:213], v[218:221], v[106:109]
	s_nop 2
	v_cndmask_b32_e64 v106, 0, 1, s[44:45]
	v_cmp_ne_u32_e64 s[48:49], 1, v106
	s_cbranch_vccnz .LBB0_1637
	s_waitcnt vmcnt(28)
	v_sub_f32_e32 v107, v105, v125
	v_sub_f32_e32 v108, v104, v124
	v_sub_f32_e32 v106, v103, v123
	v_sub_f32_e32 v109, v102, v122
	v_cvt_pk_bf16_f32 v106, v109, v106
	v_cvt_pk_bf16_f32 v107, v108, v107
	s_waitcnt vmcnt(27)
	v_sub_f32_e32 v109, v101, v129
	v_sub_f32_e32 v110, v100, v128
	v_sub_f32_e32 v108, v99, v127
	v_sub_f32_e32 v111, v98, v126
	v_cvt_pk_bf16_f32 v108, v111, v108
	v_cvt_pk_bf16_f32 v109, v110, v109
	ds_write2st64_b64 v170, v[106:107], v[108:109] offset1:5

.LBB0_1639:
	s_andn2_b64 vcc, exec, s[8:9]
	s_cbranch_vccnz .LBB0_1641
	ds_read_b128 v[110:113], v169
	ds_read_b128 v[106:109], v169 offset:64
	ds_read_b128 v[130:133], v169 offset:2560
	ds_read_b128 v[134:137], v169 offset:2624
	s_waitcnt lgkmcnt(7)
	s_nop 0
	s_waitcnt lgkmcnt(6)
	s_nop 0
	s_waitcnt lgkmcnt(5)
	s_nop 0
	s_waitcnt lgkmcnt(4)
	s_nop 0
	s_waitcnt vmcnt(28) lgkmcnt(3)
	v_mfma_f32_16x16x32_bf16 v[122:125], v[102:105], v[110:113], v[122:125]
	s_waitcnt lgkmcnt(1)
	v_mfma_f32_16x16x32_bf16 v[102:105], v[102:105], v[130:133], v[126:129]
	s_waitcnt vmcnt(27)
	v_mfma_f32_16x16x32_bf16 v[122:125], v[98:101], v[106:109], v[122:125]
	s_waitcnt lgkmcnt(0)
	v_mfma_f32_16x16x32_bf16 v[126:129], v[98:101], v[134:137], v[102:105]
.LBB0_1641:
	v_mul_lo_u32 v141, v141, s26
	v_readlane_b32 s0, v253, 20
	s_waitcnt vmcnt(28)
	s_nop 0
	v_pk_mul_f32 v[104:105], v[158:159], v[116:117] op_sel_hi:[0,1]
	v_pk_mul_f32 v[102:103], v[158:159], v[114:115] op_sel_hi:[0,1]
	v_add3_u32 v177, s0, v141, v139
	ds_read_b128 v[114:117], v177
	ds_read_b128 v[178:181], v177 offset:64
	s_waitcnt vmcnt(27)
	v_pk_mul_f32 v[100:101], v[158:159], v[120:121] op_sel_hi:[0,1]
	v_pk_mul_f32 v[98:99], v[158:159], v[118:119] op_sel_hi:[0,1]
	s_or_b32 s0, s6, 40
	s_ashr_i32 s1, s0, 31
	s_lshl_b64 s[8:9], s[0:1], 13
	s_waitcnt lgkmcnt(1)
	v_mfma_f32_16x16x32_bf16 v[98:101], v[114:117], v[110:113], v[98:101]
	s_lshl_b64 s[34:35], s[0:1], 14
	s_add_u32 vcc_lo, s95, s34
	s_addc_u32 vcc_hi, s3, s35
	v_mfma_f32_16x16x32_bf16 v[102:105], v[114:117], v[130:133], v[102:105]
	s_nop 0
	s_add_u32 s68, s29, s34
	s_addc_u32 s69, s94, s35
	s_waitcnt lgkmcnt(0)
	v_mfma_f32_16x16x32_bf16 v[110:113], v[178:181], v[106:109], v[98:101]
	s_add_u32 s34, s2, s34
	s_addc_u32 s35, s10, s35
	s_nop 5
	v_cvt_pk_bf16_f32 v98, v110, v111
	v_mfma_f32_16x16x32_bf16 v[102:105], v[178:181], v[134:137], v[102:105]
	v_cvt_pk_bf16_f32 v99, v112, v113
	s_nop 6
	v_cvt_pk_bf16_f32 v100, v102, v103
	v_cvt_pk_bf16_f32 v101, v104, v105
	ds_write2st64_b64 v172, v[98:99], v[100:101] offset1:9
	s_waitcnt vmcnt(26)
	ds_write_b128 v161, v[18:21]
	s_waitcnt vmcnt(25)
	ds_write_b128 v163, v[26:29]
	s_waitcnt vmcnt(24)
	ds_write_b128 v161, v[82:85] offset:18432
	s_waitcnt vmcnt(23)
	ds_write_b128 v165, v[86:89]
	s_waitcnt vmcnt(22)
	ds_write_b128 v166, v[90:93] offset:36864
	s_waitcnt vmcnt(21)
	ds_write_b128 v167, v[94:97] offset:36864
	v_lshl_add_u64 v[18:19], vcc, 0, v[146:147]
	global_load_dwordx4 v[82:85], v[18:19], off
	v_lshl_add_u64 v[18:19], vcc, 0, v[148:149]
	global_load_dwordx4 v[86:89], v[18:19], off
	v_lshl_add_u64 v[18:19], s[68:69], 0, v[146:147]
	global_load_dwordx4 v[90:93], v[18:19], off
	v_lshl_add_u64 v[18:19], s[68:69], 0, v[148:149]
	global_load_dwordx4 v[98:101], v[18:19], off
	v_lshl_add_u64 v[18:19], s[34:35], 0, v[146:147]
	global_load_dwordx4 v[106:109], v[18:19], off
	v_lshl_add_u64 v[18:19], s[34:35], 0, v[148:149]
	s_lshl_b64 s[34:35], s[0:1], 15
	s_lshl_b64 s[0:1], s[0:1], 8
	v_lshl_add_u64 v[94:95], v[152:153], 0, s[0:1]
	global_load_dwordx4 v[118:121], v[18:19], off
	global_load_dword v158, v[94:95], off
	v_lshl_add_u64 v[18:19], v[156:157], 0, s[34:35]
	v_lshl_add_u64 v[20:21], v[154:155], 0, s[8:9]
	v_cndmask_b32_e64 v19, v21, v19, s[44:45]
	v_cndmask_b32_e64 v18, v20, v18, s[44:45]
	global_load_dwordx4 v[26:29], v[18:19], off
	v_lshl_add_u64 v[18:19], v[18:19], 0, s[60:61]
	global_load_dwordx4 v[18:21], v[18:19], off
	s_and_b64 vcc, exec, s[46:47]
	s_cbranch_vccnz .LBB0_1643
	v_cvt_pk_bf16_f32 v96, v122, v122
	s_mov_b64 s[0:1], 0x20000
	v_and_b32_e32 v96, 0xffff, v96
	v_lshl_add_u64 v[94:95], v[150:151], 0, s[0:1]
	global_store_short v[94:95], v96, off
	v_cvt_pk_bf16_f32 v96, v123, v123
	s_mov_b64 s[0:1], 0x20800
	v_and_b32_e32 v96, 0xffff, v96
	v_lshl_add_u64 v[94:95], v[150:151], 0, s[0:1]
	global_store_short v[94:95], v96, off
	v_cvt_pk_bf16_f32 v96, v124, v124
	s_mov_b64 s[0:1], 0x21000
	v_and_b32_e32 v96, 0xffff, v96
	v_lshl_add_u64 v[94:95], v[150:151], 0, s[0:1]
	global_store_short v[94:95], v96, off
	v_cvt_pk_bf16_f32 v96, v125, v125
	s_mov_b64 s[0:1], 0x21800
	v_and_b32_e32 v96, 0xffff, v96
	v_lshl_add_u64 v[94:95], v[150:151], 0, s[0:1]
	global_store_short v[94:95], v96, off
	v_cvt_pk_bf16_f32 v96, v126, v126
	s_mov_b64 s[0:1], 0x20020
	v_and_b32_e32 v96, 0xffff, v96
	v_lshl_add_u64 v[94:95], v[150:151], 0, s[0:1]
	global_store_short v[94:95], v96, off
	v_cvt_pk_bf16_f32 v96, v127, v127
	s_mov_b64 s[0:1], 0x20820
	v_and_b32_e32 v96, 0xffff, v96
	v_lshl_add_u64 v[94:95], v[150:151], 0, s[0:1]
	global_store_short v[94:95], v96, off
	v_cvt_pk_bf16_f32 v96, v128, v128
	s_mov_b64 s[0:1], 0x21020
	v_and_b32_e32 v96, 0xffff, v96
	v_lshl_add_u64 v[94:95], v[150:151], 0, s[0:1]
	global_store_short v[94:95], v96, off
	s_mov_b64 s[0:1], 0x21820
	v_cvt_pk_bf16_f32 v96, v129, v129
	v_lshl_add_u64 v[94:95], v[150:151], 0, s[0:1]
	v_and_b32_e32 v96, 0xffff, v96
	global_store_short v[94:95], v96, off
.LBB0_1643:
	s_waitcnt lgkmcnt(0)
	s_barrier
	ds_read_b128 v[94:97], v168
	ds_read_b128 v[114:117], v143
	ds_read_b128 v[122:125], v143 offset:4608
	ds_read_b128 v[178:181], v168 offset:64
	ds_read_b128 v[126:129], v143 offset:64
	ds_read_b128 v[182:185], v143 offset:4672
	ds_read_b128 v[186:189], v168 offset:128
	ds_read_b128 v[190:193], v143 offset:128
	ds_read_b128 v[206:209], v143 offset:4736
	ds_read_b128 v[210:213], v168 offset:192
	ds_read_b128 v[214:217], v143 offset:192
	ds_read_b128 v[218:221], v143 offset:4800
	s_and_b64 vcc, exec, s[48:49]
	s_waitcnt lgkmcnt(10)
	v_mfma_f32_16x16x32_bf16 v[114:117], v[94:97], v[114:117], 0
	s_waitcnt lgkmcnt(9)
	v_mfma_f32_16x16x32_bf16 v[94:97], v[94:97], v[122:125], 0
	s_nop 0
	s_nop 0
	s_waitcnt lgkmcnt(7)
	v_mfma_f32_16x16x32_bf16 v[114:117], v[178:181], v[126:129], v[114:117]
	s_nop 0
	s_waitcnt lgkmcnt(6)
	v_mfma_f32_16x16x32_bf16 v[94:97], v[178:181], v[182:185], v[94:97]
	s_nop 0
	s_nop 0
	s_waitcnt lgkmcnt(4)
	v_mfma_f32_16x16x32_bf16 v[114:117], v[186:189], v[190:193], v[114:117]
	s_nop 0
	s_waitcnt lgkmcnt(3)
	v_mfma_f32_16x16x32_bf16 v[94:97], v[186:189], v[206:209], v[94:97]
	s_nop 0
	s_nop 0
	s_waitcnt lgkmcnt(1)
	v_mfma_f32_16x16x32_bf16 v[126:129], v[210:213], v[214:217], v[114:117]
	s_nop 2
	s_nop 0
	s_waitcnt lgkmcnt(0)
	v_mfma_f32_16x16x32_bf16 v[130:133], v[210:213], v[218:221], v[94:97]
	s_cbranch_vccnz .LBB0_1645
	s_waitcnt vmcnt(28)
	s_nop 0
	v_sub_f32_e32 v95, v57, v129
	v_sub_f32_e32 v96, v56, v128
	v_sub_f32_e32 v94, v55, v127
	v_sub_f32_e32 v97, v54, v126
	v_cvt_pk_bf16_f32 v94, v97, v94
	v_cvt_pk_bf16_f32 v95, v96, v95
	s_waitcnt vmcnt(27)
	v_sub_f32_e32 v97, v53, v133
	v_sub_f32_e32 v114, v52, v132
	v_sub_f32_e32 v96, v51, v131
	v_sub_f32_e32 v115, v50, v130
	v_cvt_pk_bf16_f32 v96, v115, v96
	v_cvt_pk_bf16_f32 v97, v114, v97
	ds_write2st64_b64 v170, v[94:95], v[96:97] offset1:5

.LBB0_1647:
	s_andn2_b64 vcc, exec, s[8:9]
	s_cbranch_vccnz .LBB0_1649
	ds_read_b128 v[114:117], v169
	ds_read_b128 v[94:97], v169 offset:64
	ds_read_b128 v[122:125], v169 offset:2560
	ds_read_b128 v[134:137], v169 offset:2624
	s_waitcnt lgkmcnt(7)
	s_nop 0
	s_waitcnt lgkmcnt(6)
	s_nop 0
	s_waitcnt lgkmcnt(5)
	s_nop 0
	s_waitcnt lgkmcnt(4)
	s_nop 0
	s_waitcnt vmcnt(28) lgkmcnt(3)
	v_mfma_f32_16x16x32_bf16 v[126:129], v[54:57], v[114:117], v[126:129]
	s_waitcnt lgkmcnt(1)
	v_mfma_f32_16x16x32_bf16 v[54:57], v[54:57], v[122:125], v[130:133]
	s_waitcnt vmcnt(27)
	v_mfma_f32_16x16x32_bf16 v[126:129], v[50:53], v[94:97], v[126:129]
	s_waitcnt lgkmcnt(0)
	v_mfma_f32_16x16x32_bf16 v[130:133], v[50:53], v[134:137], v[54:57]
.LBB0_1649:
	ds_read_b128 v[178:181], v173 offset:36864
	ds_read_b128 v[182:185], v173 offset:36928
	s_waitcnt vmcnt(28)
	s_nop 2
	v_pk_mul_f32 v[56:57], v[160:161], v[104:105] op_sel_hi:[0,1]
	v_pk_mul_f32 v[54:55], v[160:161], v[102:103] op_sel_hi:[0,1]
	s_nop 0
	s_waitcnt vmcnt(27)
	v_pk_mul_f32 v[52:53], v[160:161], v[112:113] op_sel_hi:[0,1]
	v_pk_mul_f32 v[50:51], v[160:161], v[110:111] op_sel_hi:[0,1]
	s_or_b32 s0, s6, 48
	s_ashr_i32 s1, s0, 31
	s_lshl_b64 s[8:9], s[0:1], 13
	s_lshl_b64 s[34:35], s[0:1], 14
	s_waitcnt lgkmcnt(1)
	v_mfma_f32_16x16x32_bf16 v[50:53], v[178:181], v[114:117], v[50:53]
	s_add_u32 s68, s95, s34
	s_addc_u32 s69, s3, s35
	s_add_u32 s70, s29, s34
	v_mfma_f32_16x16x32_bf16 v[54:57], v[178:181], v[122:125], v[54:57]
	s_nop 0
	s_addc_u32 s71, s94, s35
	s_add_u32 s34, s2, s34
	s_waitcnt lgkmcnt(0)
	v_mfma_f32_16x16x32_bf16 v[114:117], v[182:185], v[94:97], v[50:53]
	s_addc_u32 s35, s10, s35
	s_and_b64 vcc, exec, s[46:47]
	v_mfma_f32_16x16x32_bf16 v[50:53], v[182:185], v[134:137], v[54:57]
	s_nop 4
	v_cvt_pk_bf16_f32 v54, v114, v115
	v_cvt_pk_bf16_f32 v55, v116, v117
	s_nop 0
	v_cvt_pk_bf16_f32 v56, v50, v51
	v_cvt_pk_bf16_f32 v57, v52, v53
	ds_write2st64_b64 v172, v[54:55], v[56:57] offset1:9
	s_waitcnt vmcnt(26)
	ds_write_b128 v161, v[22:25] offset:57344
	s_waitcnt vmcnt(25)
	ds_write_b128 v163, v[30:33] offset:57344
	s_waitcnt vmcnt(24)
	ds_write_b128 v174, v[34:37] offset:57344
	s_waitcnt vmcnt(23)
	ds_write_b128 v165, v[38:41] offset:57344
	s_waitcnt vmcnt(22)
	ds_write_b128 v175, v[42:45]
	s_waitcnt vmcnt(21)
	ds_write_b128 v176, v[46:49]
	v_lshl_add_u64 v[22:23], s[68:69], 0, v[146:147]
	global_load_dwordx4 v[42:45], v[22:23], off
	v_lshl_add_u64 v[22:23], s[68:69], 0, v[148:149]
	global_load_dwordx4 v[54:57], v[22:23], off
	v_lshl_add_u64 v[22:23], s[70:71], 0, v[146:147]
	global_load_dwordx4 v[94:97], v[22:23], off
	v_lshl_add_u64 v[22:23], s[70:71], 0, v[148:149]
	global_load_dwordx4 v[102:105], v[22:23], off
	v_lshl_add_u64 v[22:23], s[34:35], 0, v[146:147]
	global_load_dwordx4 v[110:113], v[22:23], off
	v_lshl_add_u64 v[22:23], s[34:35], 0, v[148:149]
	s_lshl_b64 s[34:35], s[0:1], 15
	s_lshl_b64 s[0:1], s[0:1], 8
	v_lshl_add_u64 v[34:35], v[152:153], 0, s[0:1]
	global_load_dwordx4 v[122:125], v[22:23], off
	global_load_dword v160, v[34:35], off
	v_lshl_add_u64 v[22:23], v[156:157], 0, s[34:35]
	v_lshl_add_u64 v[24:25], v[154:155], 0, s[8:9]
	v_cndmask_b32_e64 v23, v25, v23, s[44:45]
	v_cndmask_b32_e64 v22, v24, v22, s[44:45]
	global_load_dwordx4 v[30:33], v[22:23], off
	v_lshl_add_u64 v[22:23], v[22:23], 0, s[60:61]
	global_load_dwordx4 v[22:25], v[22:23], off
	s_cbranch_vccnz .LBB0_1651
	v_cvt_pk_bf16_f32 v36, v126, v126
	s_mov_b64 s[0:1], 0x40000
	v_and_b32_e32 v36, 0xffff, v36
	v_lshl_add_u64 v[34:35], v[150:151], 0, s[0:1]
	global_store_short v[34:35], v36, off
	v_cvt_pk_bf16_f32 v36, v127, v127
	s_mov_b64 s[0:1], 0x40800
	v_and_b32_e32 v36, 0xffff, v36
	v_lshl_add_u64 v[34:35], v[150:151], 0, s[0:1]
	global_store_short v[34:35], v36, off
	v_cvt_pk_bf16_f32 v36, v128, v128
	s_mov_b64 s[0:1], 0x41000
	v_and_b32_e32 v36, 0xffff, v36
	v_lshl_add_u64 v[34:35], v[150:151], 0, s[0:1]
	global_store_short v[34:35], v36, off
	v_cvt_pk_bf16_f32 v36, v129, v129
	s_mov_b64 s[0:1], 0x41800
	v_and_b32_e32 v36, 0xffff, v36
	v_lshl_add_u64 v[34:35], v[150:151], 0, s[0:1]
	global_store_short v[34:35], v36, off
	v_cvt_pk_bf16_f32 v36, v130, v130
	s_mov_b64 s[0:1], 0x40020
	v_and_b32_e32 v36, 0xffff, v36
	v_lshl_add_u64 v[34:35], v[150:151], 0, s[0:1]
	global_store_short v[34:35], v36, off
	v_cvt_pk_bf16_f32 v36, v131, v131
	s_mov_b64 s[0:1], 0x40820
	v_and_b32_e32 v36, 0xffff, v36
	v_lshl_add_u64 v[34:35], v[150:151], 0, s[0:1]
	global_store_short v[34:35], v36, off
	v_cvt_pk_bf16_f32 v36, v132, v132
	s_mov_b64 s[0:1], 0x41020
	v_and_b32_e32 v36, 0xffff, v36
	v_lshl_add_u64 v[34:35], v[150:151], 0, s[0:1]
	global_store_short v[34:35], v36, off
	s_mov_b64 s[0:1], 0x41820
	v_cvt_pk_bf16_f32 v36, v133, v133
	v_lshl_add_u64 v[34:35], v[150:151], 0, s[0:1]
	v_and_b32_e32 v36, 0xffff, v36
	global_store_short v[34:35], v36, off
.LBB0_1651:
	s_waitcnt lgkmcnt(0)
	s_barrier
	ds_read_b128 v[34:37], v168 offset:57344
	ds_read_b128 v[38:41], v143
	ds_read_b128 v[46:49], v143 offset:4608
	ds_read_b128 v[178:181], v168 offset:57408
	ds_read_b128 v[126:129], v143 offset:64
	ds_read_b128 v[182:185], v143 offset:4672
	ds_read_b128 v[186:189], v168 offset:57472
	ds_read_b128 v[190:193], v143 offset:128
	ds_read_b128 v[206:209], v143 offset:4736
	ds_read_b128 v[210:213], v168 offset:57536
	ds_read_b128 v[214:217], v143 offset:192
	ds_read_b128 v[218:221], v143 offset:4800
	s_and_b64 vcc, exec, s[48:49]
	s_waitcnt lgkmcnt(10)
	v_mfma_f32_16x16x32_bf16 v[38:41], v[34:37], v[38:41], 0
	s_waitcnt lgkmcnt(9)
	v_mfma_f32_16x16x32_bf16 v[34:37], v[34:37], v[46:49], 0
	s_nop 0
	s_nop 0
	s_waitcnt lgkmcnt(7)
	v_mfma_f32_16x16x32_bf16 v[38:41], v[178:181], v[126:129], v[38:41]
	s_nop 0
	s_waitcnt lgkmcnt(6)
	v_mfma_f32_16x16x32_bf16 v[34:37], v[178:181], v[182:185], v[34:37]
	s_nop 0
	s_nop 0
	s_waitcnt lgkmcnt(4)
	v_mfma_f32_16x16x32_bf16 v[38:41], v[186:189], v[190:193], v[38:41]
	s_nop 0
	s_waitcnt lgkmcnt(3)
	v_mfma_f32_16x16x32_bf16 v[34:37], v[186:189], v[206:209], v[34:37]
	s_nop 0
	s_nop 0
	s_waitcnt lgkmcnt(1)
	v_mfma_f32_16x16x32_bf16 v[130:133], v[210:213], v[214:217], v[38:41]
	s_nop 2
	s_nop 0
	s_waitcnt lgkmcnt(0)
	v_mfma_f32_16x16x32_bf16 v[134:137], v[210:213], v[218:221], v[34:37]
	s_cbranch_vccnz .LBB0_1653
	s_waitcnt vmcnt(29)
	s_nop 0
	v_sub_f32_e32 v35, v9, v133
	v_sub_f32_e32 v36, v8, v132
	v_sub_f32_e32 v34, v7, v131
	v_sub_f32_e32 v37, v6, v130
	v_cvt_pk_bf16_f32 v34, v37, v34
	v_cvt_pk_bf16_f32 v35, v36, v35
	s_waitcnt vmcnt(27)
	v_sub_f32_e32 v37, v5, v137
	v_sub_f32_e32 v38, v4, v136
	v_sub_f32_e32 v36, v3, v135
	v_sub_f32_e32 v39, v2, v134
	v_cvt_pk_bf16_f32 v36, v39, v36
	v_cvt_pk_bf16_f32 v37, v38, v37
	ds_write2st64_b64 v170, v[34:35], v[36:37] offset1:5

.LBB0_1655:
	s_andn2_b64 vcc, exec, s[8:9]
	s_cbranch_vccnz .LBB0_1657
	ds_read_b128 v[38:41], v169
	ds_read_b128 v[34:37], v169 offset:64
	ds_read_b128 v[46:49], v169 offset:2560
	s_waitcnt lgkmcnt(6)
	s_nop 0
	s_waitcnt lgkmcnt(5)
	s_nop 0
	s_waitcnt lgkmcnt(4)
	s_nop 0
	s_waitcnt vmcnt(29) lgkmcnt(2)
	v_mfma_f32_16x16x32_bf16 v[126:129], v[6:9], v[38:41], v[130:133]
	s_waitcnt vmcnt(27) lgkmcnt(1)
	v_mfma_f32_16x16x32_bf16 v[130:133], v[2:5], v[34:37], v[126:129]
	ds_read_b128 v[126:129], v169 offset:2624
	s_nop 5
	s_nop 0
	s_waitcnt lgkmcnt(1)
	v_mfma_f32_16x16x32_bf16 v[6:9], v[6:9], v[46:49], v[134:137]
	s_waitcnt lgkmcnt(0)
	v_mfma_f32_16x16x32_bf16 v[134:137], v[2:5], v[126:129], v[6:9]
.LBB0_1657:
	ds_read_b128 v[178:181], v177
	ds_read_b128 v[182:185], v177 offset:64
	s_waitcnt vmcnt(28)
	s_nop 4
	v_pk_mul_f32 v[8:9], v[138:139], v[52:53] op_sel_hi:[0,1]
	v_pk_mul_f32 v[6:7], v[138:139], v[50:51] op_sel_hi:[0,1]
	s_nop 0
	s_waitcnt vmcnt(27)
	v_pk_mul_f32 v[4:5], v[138:139], v[116:117] op_sel_hi:[0,1]
	v_pk_mul_f32 v[2:3], v[138:139], v[114:115] op_sel_hi:[0,1]
	s_or_b32 s0, s6, 56
	s_ashr_i32 s1, s0, 31
	s_lshl_b64 s[8:9], s[0:1], 13
	s_lshl_b64 s[34:35], s[0:1], 14
	s_waitcnt lgkmcnt(1)
	v_mfma_f32_16x16x32_bf16 v[6:9], v[178:181], v[46:49], v[6:9]
	s_nop 0
	s_add_u32 s68, s95, s34
	s_addc_u32 s69, s3, s35
	v_mfma_f32_16x16x32_bf16 v[2:5], v[178:181], v[38:41], v[2:5]
	s_add_u32 s70, s29, s34
	s_addc_u32 s71, s94, s35
	s_add_u32 s34, s2, s34
	s_waitcnt lgkmcnt(0)
	v_mfma_f32_16x16x32_bf16 v[38:41], v[182:185], v[34:37], v[2:5]
	s_addc_u32 s35, s10, s35
	s_and_b64 vcc, exec, s[46:47]
	v_mfma_f32_16x16x32_bf16 v[6:9], v[182:185], v[126:129], v[6:9]
	s_nop 4
	v_cvt_pk_bf16_f32 v2, v38, v39
	v_cvt_pk_bf16_f32 v3, v40, v41
	s_nop 0
	v_cvt_pk_bf16_f32 v4, v6, v7
	v_cvt_pk_bf16_f32 v5, v8, v9
	ds_write2st64_b64 v172, v[2:3], v[4:5] offset1:9
	s_waitcnt vmcnt(26)
	ds_write_b128 v161, v[58:61]
	s_waitcnt vmcnt(25)
	ds_write_b128 v163, v[62:65]
	s_waitcnt vmcnt(24)
	ds_write_b128 v161, v[66:69] offset:18432
	s_waitcnt vmcnt(23)
	ds_write_b128 v165, v[70:73]
	s_waitcnt vmcnt(22)
	ds_write_b128 v166, v[74:77] offset:36864
	s_waitcnt vmcnt(21)
	ds_write_b128 v167, v[78:81] offset:36864
	v_lshl_add_u64 v[2:3], s[68:69], 0, v[146:147]
	global_load_dwordx4 v[46:49], v[2:3], off
	v_lshl_add_u64 v[2:3], s[68:69], 0, v[148:149]
	global_load_dwordx4 v[58:61], v[2:3], off
	v_lshl_add_u64 v[2:3], s[70:71], 0, v[146:147]
	global_load_dwordx4 v[66:69], v[2:3], off
	v_lshl_add_u64 v[2:3], s[70:71], 0, v[148:149]
	global_load_dwordx4 v[78:81], v[2:3], off
	v_lshl_add_u64 v[2:3], s[34:35], 0, v[146:147]
	global_load_dwordx4 v[114:117], v[2:3], off
	v_lshl_add_u64 v[2:3], s[34:35], 0, v[148:149]
	s_lshl_b64 s[34:35], s[0:1], 15
	s_lshl_b64 s[0:1], s[0:1], 8
	v_lshl_add_u64 v[50:51], v[152:153], 0, s[0:1]
	global_load_dwordx4 v[126:129], v[2:3], off
	global_load_dword v138, v[50:51], off
	v_lshl_add_u64 v[2:3], v[156:157], 0, s[34:35]
	v_lshl_add_u64 v[4:5], v[154:155], 0, s[8:9]
	v_cndmask_b32_e64 v3, v5, v3, s[44:45]
	v_cndmask_b32_e64 v2, v4, v2, s[44:45]
	global_load_dwordx4 v[34:37], v[2:3], off
	v_lshl_add_u64 v[2:3], v[2:3], 0, s[60:61]
	global_load_dwordx4 v[2:5], v[2:3], off
	s_cbranch_vccnz .LBB0_1659
	v_cvt_pk_bf16_f32 v52, v130, v130
	s_mov_b64 s[0:1], 0x60000
	v_and_b32_e32 v52, 0xffff, v52
	v_lshl_add_u64 v[50:51], v[150:151], 0, s[0:1]
	global_store_short v[50:51], v52, off
	v_cvt_pk_bf16_f32 v52, v131, v131
	s_mov_b64 s[0:1], 0x60800
	v_and_b32_e32 v52, 0xffff, v52
	v_lshl_add_u64 v[50:51], v[150:151], 0, s[0:1]
	global_store_short v[50:51], v52, off
	v_cvt_pk_bf16_f32 v52, v132, v132
	s_mov_b64 s[0:1], 0x61000
	v_and_b32_e32 v52, 0xffff, v52
	v_lshl_add_u64 v[50:51], v[150:151], 0, s[0:1]
	global_store_short v[50:51], v52, off
	v_cvt_pk_bf16_f32 v52, v133, v133
	s_mov_b64 s[0:1], 0x61800
	v_and_b32_e32 v52, 0xffff, v52
	v_lshl_add_u64 v[50:51], v[150:151], 0, s[0:1]
	global_store_short v[50:51], v52, off
	v_cvt_pk_bf16_f32 v52, v134, v134
	s_mov_b64 s[0:1], 0x60020
	v_and_b32_e32 v52, 0xffff, v52
	v_lshl_add_u64 v[50:51], v[150:151], 0, s[0:1]
	global_store_short v[50:51], v52, off
	v_cvt_pk_bf16_f32 v52, v135, v135
	s_mov_b64 s[0:1], 0x60820
	v_and_b32_e32 v52, 0xffff, v52
	v_lshl_add_u64 v[50:51], v[150:151], 0, s[0:1]
	global_store_short v[50:51], v52, off
	v_cvt_pk_bf16_f32 v52, v136, v136
	s_mov_b64 s[0:1], 0x61020
	v_and_b32_e32 v52, 0xffff, v52
	v_lshl_add_u64 v[50:51], v[150:151], 0, s[0:1]
	global_store_short v[50:51], v52, off
	s_mov_b64 s[0:1], 0x61820
	v_cvt_pk_bf16_f32 v52, v137, v137
	v_lshl_add_u64 v[50:51], v[150:151], 0, s[0:1]
	v_and_b32_e32 v52, 0xffff, v52
	global_store_short v[50:51], v52, off
.LBB0_1659:
	s_waitcnt lgkmcnt(0)
	s_barrier
	ds_read_b128 v[50:53], v168
	ds_read_b128 v[62:65], v143
	ds_read_b128 v[70:73], v143 offset:4608
	ds_read_b128 v[178:181], v168 offset:64
	ds_read_b128 v[74:77], v143 offset:64
	ds_read_b128 v[182:185], v143 offset:4672
	ds_read_b128 v[186:189], v168 offset:128
	ds_read_b128 v[190:193], v143 offset:128
	ds_read_b128 v[206:209], v143 offset:4736
	ds_read_b128 v[210:213], v168 offset:192
	ds_read_b128 v[214:217], v143 offset:192
	ds_read_b128 v[218:221], v143 offset:4800
	s_and_b64 vcc, exec, s[48:49]
	s_waitcnt lgkmcnt(10)
	v_mfma_f32_16x16x32_bf16 v[62:65], v[50:53], v[62:65], 0
	s_waitcnt lgkmcnt(9)
	v_mfma_f32_16x16x32_bf16 v[50:53], v[50:53], v[70:73], 0
	s_nop 0
	s_nop 0
	s_waitcnt lgkmcnt(7)
	v_mfma_f32_16x16x32_bf16 v[62:65], v[178:181], v[74:77], v[62:65]
	s_nop 0
	s_waitcnt lgkmcnt(6)
	v_mfma_f32_16x16x32_bf16 v[50:53], v[178:181], v[182:185], v[50:53]
	s_nop 0
	s_nop 0
	s_waitcnt lgkmcnt(4)
	v_mfma_f32_16x16x32_bf16 v[62:65], v[186:189], v[190:193], v[62:65]
	s_nop 0
	s_waitcnt lgkmcnt(3)
	v_mfma_f32_16x16x32_bf16 v[50:53], v[186:189], v[206:209], v[50:53]
	s_nop 0
	s_nop 0
	s_waitcnt lgkmcnt(1)
	v_mfma_f32_16x16x32_bf16 v[74:77], v[210:213], v[214:217], v[62:65]
	s_nop 2
	s_nop 0
	s_waitcnt lgkmcnt(0)
	v_mfma_f32_16x16x32_bf16 v[130:133], v[210:213], v[218:221], v[50:53]
	s_cbranch_vccnz .LBB0_1661
	s_waitcnt vmcnt(29)
	s_nop 0
	v_sub_f32_e32 v51, v17, v77
	v_sub_f32_e32 v52, v16, v76
	v_sub_f32_e32 v50, v15, v75
	v_sub_f32_e32 v53, v14, v74
	v_cvt_pk_bf16_f32 v50, v53, v50
	v_cvt_pk_bf16_f32 v51, v52, v51
	s_waitcnt vmcnt(28)
	v_sub_f32_e32 v53, v13, v133
	v_sub_f32_e32 v62, v12, v132
	v_sub_f32_e32 v52, v11, v131
	v_sub_f32_e32 v63, v10, v130
	v_cvt_pk_bf16_f32 v52, v63, v52
	v_cvt_pk_bf16_f32 v53, v62, v53
	ds_write2st64_b64 v170, v[50:51], v[52:53] offset1:5

.LBB0_1663:
	s_andn2_b64 vcc, exec, s[8:9]
	s_cbranch_vccnz .LBB0_1665
	ds_read_b128 v[62:65], v169
	ds_read_b128 v[50:53], v169 offset:64
	ds_read_b128 v[70:73], v169 offset:2560
	ds_read_b128 v[134:137], v169 offset:2624
	s_waitcnt lgkmcnt(7)
	s_nop 0
	s_waitcnt lgkmcnt(6)
	s_nop 0
	s_waitcnt lgkmcnt(5)
	s_nop 0
	s_waitcnt lgkmcnt(4)
	s_nop 0
	s_waitcnt vmcnt(29) lgkmcnt(3)
	v_mfma_f32_16x16x32_bf16 v[74:77], v[14:17], v[62:65], v[74:77]
	s_waitcnt lgkmcnt(1)
	v_mfma_f32_16x16x32_bf16 v[14:17], v[14:17], v[70:73], v[130:133]
	s_waitcnt vmcnt(28)
	v_mfma_f32_16x16x32_bf16 v[74:77], v[10:13], v[50:53], v[74:77]
	s_waitcnt lgkmcnt(0)
	v_mfma_f32_16x16x32_bf16 v[130:133], v[10:13], v[134:137], v[14:17]
.LBB0_1665:
	ds_read_b128 v[14:17], v173 offset:36864
	ds_read_b128 v[178:181], v173 offset:36928
	s_waitcnt vmcnt(29)
	s_nop 2
	s_nop 0
	s_waitcnt vmcnt(27)
	v_pk_mul_f32 v[12:13], v[140:141], v[40:41] op_sel_hi:[0,1]
	v_pk_mul_f32 v[10:11], v[140:141], v[38:39] op_sel_hi:[0,1]
	s_nop 0
	v_pk_mul_f32 v[8:9], v[140:141], v[8:9] op_sel_hi:[0,1]
	v_pk_mul_f32 v[6:7], v[140:141], v[6:7] op_sel_hi:[0,1]
	s_or_b32 s0, s6, 64
	s_ashr_i32 s1, s0, 31
	s_lshl_b64 s[8:9], s[0:1], 13
	s_waitcnt lgkmcnt(1)
	v_mfma_f32_16x16x32_bf16 v[10:13], v[14:17], v[62:65], v[10:13]
	s_lshl_b64 s[34:35], s[0:1], 14
	s_add_u32 s68, s95, s34
	s_addc_u32 s69, s3, s35
	v_mfma_f32_16x16x32_bf16 v[6:9], v[14:17], v[70:73], v[6:9]
	s_add_u32 s70, s29, s34
	s_addc_u32 s71, s94, s35
	s_add_u32 s34, s2, s34
	s_waitcnt lgkmcnt(0)
	v_mfma_f32_16x16x32_bf16 v[14:17], v[178:181], v[50:53], v[10:13]
	s_addc_u32 s35, s10, s35
	s_and_b64 vcc, exec, s[46:47]
	v_mfma_f32_16x16x32_bf16 v[10:13], v[178:181], v[134:137], v[6:9]
	s_nop 4
	v_cvt_pk_bf16_f32 v6, v14, v15
	v_cvt_pk_bf16_f32 v7, v16, v17
	s_nop 0
	v_cvt_pk_bf16_f32 v8, v10, v11
	v_cvt_pk_bf16_f32 v9, v12, v13
	ds_write2st64_b64 v172, v[6:7], v[8:9] offset1:9
	s_waitcnt vmcnt(26)
	ds_write_b128 v161, v[82:85] offset:57344
	s_waitcnt vmcnt(25)
	ds_write_b128 v163, v[86:89] offset:57344
	s_waitcnt vmcnt(24)
	ds_write_b128 v174, v[90:93] offset:57344
	s_waitcnt vmcnt(23)
	ds_write_b128 v165, v[98:101] offset:57344
	s_waitcnt vmcnt(22)
	ds_write_b128 v175, v[106:109]
	s_waitcnt vmcnt(21)
	ds_write_b128 v176, v[118:121]
	v_lshl_add_u64 v[6:7], s[68:69], 0, v[146:147]
	global_load_dwordx4 v[50:53], v[6:7], off
	v_lshl_add_u64 v[6:7], s[68:69], 0, v[148:149]
	global_load_dwordx4 v[62:65], v[6:7], off
	v_lshl_add_u64 v[6:7], s[70:71], 0, v[146:147]
	global_load_dwordx4 v[70:73], v[6:7], off
	v_lshl_add_u64 v[6:7], s[70:71], 0, v[148:149]
	global_load_dwordx4 v[82:85], v[6:7], off
	v_lshl_add_u64 v[6:7], s[34:35], 0, v[146:147]
	global_load_dwordx4 v[90:93], v[6:7], off
	v_lshl_add_u64 v[6:7], s[34:35], 0, v[148:149]
	s_lshl_b64 s[34:35], s[0:1], 15
	s_lshl_b64 s[0:1], s[0:1], 8
	v_lshl_add_u64 v[86:87], v[152:153], 0, s[0:1]
	global_load_dwordx4 v[106:109], v[6:7], off
	global_load_dword v140, v[86:87], off
	v_lshl_add_u64 v[6:7], v[156:157], 0, s[34:35]
	v_lshl_add_u64 v[8:9], v[154:155], 0, s[8:9]
	v_cndmask_b32_e64 v7, v9, v7, s[44:45]
	v_cndmask_b32_e64 v6, v8, v6, s[44:45]
	global_load_dwordx4 v[38:41], v[6:7], off
	v_lshl_add_u64 v[6:7], v[6:7], 0, s[60:61]
	global_load_dwordx4 v[6:9], v[6:7], off
	s_cbranch_vccnz .LBB0_1667
	v_cvt_pk_bf16_f32 v74, v74, v74
	s_mov_b64 s[0:1], 0x80000
	v_and_b32_e32 v74, 0xffff, v74
	v_lshl_add_u64 v[86:87], v[150:151], 0, s[0:1]
	global_store_short v[86:87], v74, off
	s_mov_b64 s[0:1], 0x80800
	v_cvt_pk_bf16_f32 v74, v75, v75
	v_cvt_pk_bf16_f32 v76, v76, v76
	v_lshl_add_u64 v[86:87], v[150:151], 0, s[0:1]
	v_and_b32_e32 v74, 0xffff, v74
	global_store_short v[86:87], v74, off
	s_mov_b64 s[0:1], 0x81000
	v_and_b32_e32 v76, 0xffff, v76
	v_lshl_add_u64 v[74:75], v[150:151], 0, s[0:1]
	global_store_short v[74:75], v76, off
	v_cvt_pk_bf16_f32 v76, v77, v77
	s_mov_b64 s[0:1], 0x81800
	v_and_b32_e32 v76, 0xffff, v76
	v_lshl_add_u64 v[74:75], v[150:151], 0, s[0:1]
	global_store_short v[74:75], v76, off
	v_cvt_pk_bf16_f32 v76, v130, v130
	s_mov_b64 s[0:1], 0x80020
	v_and_b32_e32 v76, 0xffff, v76
	v_lshl_add_u64 v[74:75], v[150:151], 0, s[0:1]
	global_store_short v[74:75], v76, off
	v_cvt_pk_bf16_f32 v76, v131, v131
	s_mov_b64 s[0:1], 0x80820
	v_and_b32_e32 v76, 0xffff, v76
	v_lshl_add_u64 v[74:75], v[150:151], 0, s[0:1]
	global_store_short v[74:75], v76, off
	v_cvt_pk_bf16_f32 v76, v132, v132
	s_mov_b64 s[0:1], 0x81020
	v_and_b32_e32 v76, 0xffff, v76
	v_lshl_add_u64 v[74:75], v[150:151], 0, s[0:1]
	global_store_short v[74:75], v76, off
	s_mov_b64 s[0:1], 0x81820
	v_cvt_pk_bf16_f32 v76, v133, v133
	v_lshl_add_u64 v[74:75], v[150:151], 0, s[0:1]
	v_and_b32_e32 v76, 0xffff, v76
	global_store_short v[74:75], v76, off
.LBB0_1667:
	s_waitcnt lgkmcnt(0)
	s_barrier
	ds_read_b128 v[74:77], v168 offset:57344
	ds_read_b128 v[86:89], v143
	ds_read_b128 v[98:101], v143 offset:4608
	ds_read_b128 v[178:181], v168 offset:57408
	ds_read_b128 v[118:121], v143 offset:64
	ds_read_b128 v[182:185], v143 offset:4672
	ds_read_b128 v[186:189], v168 offset:57472
	ds_read_b128 v[190:193], v143 offset:128
	ds_read_b128 v[206:209], v143 offset:4736
	ds_read_b128 v[210:213], v168 offset:57536
	ds_read_b128 v[214:217], v143 offset:192
	ds_read_b128 v[218:221], v143 offset:4800
	s_and_b64 vcc, exec, s[48:49]
	s_waitcnt lgkmcnt(10)
	v_mfma_f32_16x16x32_bf16 v[86:89], v[74:77], v[86:89], 0
	s_waitcnt lgkmcnt(9)
	v_mfma_f32_16x16x32_bf16 v[74:77], v[74:77], v[98:101], 0
	s_nop 0
	s_nop 0
	s_waitcnt lgkmcnt(7)
	v_mfma_f32_16x16x32_bf16 v[86:89], v[178:181], v[118:121], v[86:89]
	s_nop 0
	s_waitcnt lgkmcnt(6)
	v_mfma_f32_16x16x32_bf16 v[74:77], v[178:181], v[182:185], v[74:77]
	s_nop 0
	s_nop 0
	s_waitcnt lgkmcnt(4)
	v_mfma_f32_16x16x32_bf16 v[86:89], v[186:189], v[190:193], v[86:89]
	s_nop 0
	s_waitcnt lgkmcnt(3)
	v_mfma_f32_16x16x32_bf16 v[74:77], v[186:189], v[206:209], v[74:77]
	s_nop 0
	s_nop 0
	s_waitcnt lgkmcnt(1)
	v_mfma_f32_16x16x32_bf16 v[98:101], v[210:213], v[214:217], v[86:89]
	s_nop 2
	s_nop 0
	s_waitcnt lgkmcnt(0)
	v_mfma_f32_16x16x32_bf16 v[118:121], v[210:213], v[218:221], v[74:77]
	s_cbranch_vccnz .LBB0_1669
	s_waitcnt vmcnt(28)
	s_nop 0
	v_sub_f32_e32 v75, v29, v101
	v_sub_f32_e32 v76, v28, v100
	v_sub_f32_e32 v74, v27, v99
	v_sub_f32_e32 v77, v26, v98
	v_cvt_pk_bf16_f32 v74, v77, v74
	v_cvt_pk_bf16_f32 v75, v76, v75
	s_waitcnt vmcnt(27)
	v_sub_f32_e32 v77, v21, v121
	v_sub_f32_e32 v86, v20, v120
	v_sub_f32_e32 v76, v19, v119
	v_sub_f32_e32 v87, v18, v118
	v_cvt_pk_bf16_f32 v76, v87, v76
	v_cvt_pk_bf16_f32 v77, v86, v77
	ds_write2st64_b64 v170, v[74:75], v[76:77] offset1:5

.LBB0_1671:
	s_andn2_b64 vcc, exec, s[8:9]
	s_cbranch_vccnz .LBB0_1673
	ds_read_b128 v[86:89], v169
	ds_read_b128 v[74:77], v169 offset:64
	ds_read_b128 v[130:133], v169 offset:2560
	ds_read_b128 v[134:137], v169 offset:2624
	s_waitcnt lgkmcnt(7)
	s_nop 0
	s_waitcnt lgkmcnt(6)
	s_nop 0
	s_waitcnt lgkmcnt(5)
	s_nop 0
	s_waitcnt lgkmcnt(4)
	s_nop 0
	s_waitcnt vmcnt(28) lgkmcnt(3)
	v_mfma_f32_16x16x32_bf16 v[98:101], v[26:29], v[86:89], v[98:101]
	s_waitcnt lgkmcnt(1)
	v_mfma_f32_16x16x32_bf16 v[26:29], v[26:29], v[130:133], v[118:121]
	s_waitcnt vmcnt(27)
	v_mfma_f32_16x16x32_bf16 v[98:101], v[18:21], v[74:77], v[98:101]
	s_waitcnt lgkmcnt(0)
	v_mfma_f32_16x16x32_bf16 v[118:121], v[18:21], v[134:137], v[26:29]
.LBB0_1673:
	ds_read_b128 v[18:21], v177
	ds_read_b128 v[178:181], v177 offset:64
	s_waitcnt vmcnt(27)
	s_nop 0
	v_pk_mul_f32 v[16:17], v[158:159], v[16:17] op_sel_hi:[0,1]
	v_pk_mul_f32 v[14:15], v[158:159], v[14:15] op_sel_hi:[0,1]
	v_pk_mul_f32 v[12:13], v[158:159], v[12:13] op_sel_hi:[0,1]
	v_pk_mul_f32 v[10:11], v[158:159], v[10:11] op_sel_hi:[0,1]
	s_or_b32 s0, s6, 0x48
	s_ashr_i32 s1, s0, 31
	s_lshl_b64 s[8:9], s[0:1], 13
	s_lshl_b64 s[34:35], s[0:1], 14
	s_waitcnt lgkmcnt(1)
	v_mfma_f32_16x16x32_bf16 v[14:17], v[18:21], v[86:89], v[14:17]
	s_add_u32 s68, s95, s34
	s_addc_u32 s69, s3, s35
	s_add_u32 s70, s29, s34
	v_mfma_f32_16x16x32_bf16 v[10:13], v[18:21], v[130:133], v[10:13]
	s_nop 0
	s_addc_u32 s71, s94, s35
	s_add_u32 s34, s2, s34
	s_addc_u32 s35, s10, s35
	s_waitcnt lgkmcnt(0)
	v_mfma_f32_16x16x32_bf16 v[26:29], v[178:181], v[74:77], v[14:17]
	s_and_b64 vcc, exec, s[46:47]
	v_mfma_f32_16x16x32_bf16 v[14:17], v[178:181], v[134:137], v[10:13]
	s_nop 5
	v_cvt_pk_bf16_f32 v10, v26, v27
	v_cvt_pk_bf16_f32 v11, v28, v29
	v_cvt_pk_bf16_f32 v12, v14, v15
	v_cvt_pk_bf16_f32 v13, v16, v17
	ds_write2st64_b64 v172, v[10:11], v[12:13] offset1:9
	s_waitcnt vmcnt(26)
	ds_write_b128 v161, v[42:45]
	s_waitcnt vmcnt(25)
	ds_write_b128 v163, v[54:57]
	s_waitcnt vmcnt(24)
	ds_write_b128 v161, v[94:97] offset:18432
	s_waitcnt vmcnt(23)
	ds_write_b128 v165, v[102:105]
	s_waitcnt vmcnt(22)
	ds_write_b128 v166, v[110:113] offset:36864
	s_waitcnt vmcnt(21)
	ds_write_b128 v167, v[122:125] offset:36864
	v_lshl_add_u64 v[10:11], s[68:69], 0, v[146:147]
	global_load_dwordx4 v[42:45], v[10:11], off
	v_lshl_add_u64 v[10:11], s[68:69], 0, v[148:149]
	global_load_dwordx4 v[54:57], v[10:11], off
	v_lshl_add_u64 v[10:11], s[70:71], 0, v[146:147]
	global_load_dwordx4 v[74:77], v[10:11], off
	v_lshl_add_u64 v[10:11], s[70:71], 0, v[148:149]
	global_load_dwordx4 v[86:89], v[10:11], off
	v_lshl_add_u64 v[10:11], s[34:35], 0, v[146:147]
	global_load_dwordx4 v[94:97], v[10:11], off
	v_lshl_add_u64 v[10:11], s[34:35], 0, v[148:149]
	s_lshl_b64 s[34:35], s[0:1], 15
	s_lshl_b64 s[0:1], s[0:1], 8
	v_lshl_add_u64 v[110:111], v[152:153], 0, s[0:1]
	global_load_dwordx4 v[102:105], v[10:11], off
	global_load_dword v158, v[110:111], off
	v_lshl_add_u64 v[10:11], v[156:157], 0, s[34:35]
	v_lshl_add_u64 v[12:13], v[154:155], 0, s[8:9]
	v_cndmask_b32_e64 v11, v13, v11, s[44:45]
	v_cndmask_b32_e64 v10, v12, v10, s[44:45]
	global_load_dwordx4 v[18:21], v[10:11], off
	v_lshl_add_u64 v[10:11], v[10:11], 0, s[60:61]
	global_load_dwordx4 v[10:13], v[10:11], off
	s_cbranch_vccnz .LBB0_1675
	v_cvt_pk_bf16_f32 v98, v98, v98
	s_mov_b64 s[0:1], 0xa0000
	v_and_b32_e32 v98, 0xffff, v98
	v_lshl_add_u64 v[110:111], v[150:151], 0, s[0:1]
	global_store_short v[110:111], v98, off
	s_mov_b64 s[0:1], 0xa0800
	v_cvt_pk_bf16_f32 v98, v99, v99
	v_cvt_pk_bf16_f32 v100, v100, v100
	v_lshl_add_u64 v[110:111], v[150:151], 0, s[0:1]
	v_and_b32_e32 v98, 0xffff, v98
	global_store_short v[110:111], v98, off
	s_mov_b64 s[0:1], 0xa1000
	v_and_b32_e32 v100, 0xffff, v100
	v_lshl_add_u64 v[98:99], v[150:151], 0, s[0:1]
	global_store_short v[98:99], v100, off
	v_cvt_pk_bf16_f32 v100, v101, v101
	s_mov_b64 s[0:1], 0xa1800
	v_and_b32_e32 v100, 0xffff, v100
	v_lshl_add_u64 v[98:99], v[150:151], 0, s[0:1]
	global_store_short v[98:99], v100, off
	v_cvt_pk_bf16_f32 v100, v118, v118
	s_mov_b64 s[0:1], 0xa0020
	v_and_b32_e32 v100, 0xffff, v100
	v_lshl_add_u64 v[98:99], v[150:151], 0, s[0:1]
	global_store_short v[98:99], v100, off
	v_cvt_pk_bf16_f32 v100, v119, v119
	s_mov_b64 s[0:1], 0xa0820
	v_and_b32_e32 v100, 0xffff, v100
	v_lshl_add_u64 v[98:99], v[150:151], 0, s[0:1]
	global_store_short v[98:99], v100, off
	v_cvt_pk_bf16_f32 v100, v120, v120
	s_mov_b64 s[0:1], 0xa1020
	v_and_b32_e32 v100, 0xffff, v100
	v_lshl_add_u64 v[98:99], v[150:151], 0, s[0:1]
	global_store_short v[98:99], v100, off
	s_mov_b64 s[0:1], 0xa1820
	v_cvt_pk_bf16_f32 v100, v121, v121
	v_lshl_add_u64 v[98:99], v[150:151], 0, s[0:1]
	v_and_b32_e32 v100, 0xffff, v100
	global_store_short v[98:99], v100, off
.LBB0_1675:
	s_waitcnt lgkmcnt(0)
	s_barrier
	ds_read_b128 v[98:101], v168
	ds_read_b128 v[110:113], v143
	ds_read_b128 v[118:121], v143 offset:4608
	ds_read_b128 v[178:181], v168 offset:64
	ds_read_b128 v[122:125], v143 offset:64
	ds_read_b128 v[182:185], v143 offset:4672
	ds_read_b128 v[186:189], v168 offset:128
	ds_read_b128 v[190:193], v143 offset:128
	ds_read_b128 v[206:209], v143 offset:4736
	ds_read_b128 v[210:213], v168 offset:192
	ds_read_b128 v[214:217], v143 offset:192
	ds_read_b128 v[218:221], v143 offset:4800
	s_and_b64 vcc, exec, s[48:49]
	s_waitcnt lgkmcnt(10)
	v_mfma_f32_16x16x32_bf16 v[110:113], v[98:101], v[110:113], 0
	s_waitcnt lgkmcnt(9)
	v_mfma_f32_16x16x32_bf16 v[98:101], v[98:101], v[118:121], 0
	s_nop 0
	s_nop 0
	s_waitcnt lgkmcnt(7)
	v_mfma_f32_16x16x32_bf16 v[110:113], v[178:181], v[122:125], v[110:113]
	s_nop 0
	s_waitcnt lgkmcnt(6)
	v_mfma_f32_16x16x32_bf16 v[98:101], v[178:181], v[182:185], v[98:101]
	s_nop 0
	s_nop 0
	s_waitcnt lgkmcnt(4)
	v_mfma_f32_16x16x32_bf16 v[110:113], v[186:189], v[190:193], v[110:113]
	s_nop 0
	s_waitcnt lgkmcnt(3)
	v_mfma_f32_16x16x32_bf16 v[98:101], v[186:189], v[206:209], v[98:101]
	s_nop 0
	s_nop 0
	s_waitcnt lgkmcnt(1)
	v_mfma_f32_16x16x32_bf16 v[118:121], v[210:213], v[214:217], v[110:113]
	s_nop 2
	s_nop 0
	s_waitcnt lgkmcnt(0)
	v_mfma_f32_16x16x32_bf16 v[122:125], v[210:213], v[218:221], v[98:101]
	s_cbranch_vccnz .LBB0_1677
	s_waitcnt vmcnt(28)
	s_nop 0
	v_sub_f32_e32 v99, v33, v121
	v_sub_f32_e32 v100, v32, v120
	v_sub_f32_e32 v98, v31, v119
	v_sub_f32_e32 v101, v30, v118
	v_cvt_pk_bf16_f32 v98, v101, v98
	v_cvt_pk_bf16_f32 v99, v100, v99
	s_waitcnt vmcnt(27)
	v_sub_f32_e32 v101, v25, v125
	v_sub_f32_e32 v110, v24, v124
	v_sub_f32_e32 v100, v23, v123
	v_sub_f32_e32 v111, v22, v122
	v_cvt_pk_bf16_f32 v100, v111, v100
	v_cvt_pk_bf16_f32 v101, v110, v101
	ds_write2st64_b64 v170, v[98:99], v[100:101] offset1:5

.LBB0_1679:
	s_andn2_b64 vcc, exec, s[8:9]
	s_cbranch_vccnz .LBB0_1681
	ds_read_b128 v[110:113], v169
	ds_read_b128 v[98:101], v169 offset:64
	ds_read_b128 v[130:133], v169 offset:2560
	ds_read_b128 v[134:137], v169 offset:2624
	s_waitcnt lgkmcnt(7)
	s_nop 0
	s_waitcnt lgkmcnt(6)
	s_nop 0
	s_waitcnt lgkmcnt(5)
	s_nop 0
	s_waitcnt lgkmcnt(4)
	s_nop 0
	s_waitcnt vmcnt(28) lgkmcnt(3)
	v_mfma_f32_16x16x32_bf16 v[118:121], v[30:33], v[110:113], v[118:121]
	s_waitcnt lgkmcnt(1)
	v_mfma_f32_16x16x32_bf16 v[30:33], v[30:33], v[130:133], v[122:125]
	s_waitcnt vmcnt(27)
	v_mfma_f32_16x16x32_bf16 v[118:121], v[22:25], v[98:101], v[118:121]
	s_waitcnt lgkmcnt(0)
	v_mfma_f32_16x16x32_bf16 v[122:125], v[22:25], v[134:137], v[30:33]
.LBB0_1681:
	ds_read_b128 v[178:181], v173 offset:36864
	ds_read_b128 v[182:185], v173 offset:36928
	s_waitcnt vmcnt(27)
	v_pk_mul_f32 v[24:25], v[160:161], v[28:29] op_sel_hi:[0,1]
	v_pk_mul_f32 v[22:23], v[160:161], v[26:27] op_sel_hi:[0,1]
	s_nop 0
	v_pk_mul_f32 v[16:17], v[160:161], v[16:17] op_sel_hi:[0,1]
	v_pk_mul_f32 v[14:15], v[160:161], v[14:15] op_sel_hi:[0,1]
	s_or_b32 s0, s6, 0x50
	s_ashr_i32 s1, s0, 31
	s_lshl_b64 s[8:9], s[0:1], 13
	s_lshl_b64 s[34:35], s[0:1], 14
	s_waitcnt lgkmcnt(1)
	v_mfma_f32_16x16x32_bf16 v[22:25], v[178:181], v[110:113], v[22:25]
	s_add_u32 s68, s95, s34
	s_addc_u32 s69, s3, s35
	s_add_u32 s70, s29, s34
	v_mfma_f32_16x16x32_bf16 v[14:17], v[178:181], v[130:133], v[14:17]
	s_nop 0
	s_addc_u32 s71, s94, s35
	s_add_u32 s34, s2, s34
	s_waitcnt lgkmcnt(0)
	v_mfma_f32_16x16x32_bf16 v[30:33], v[182:185], v[98:101], v[22:25]
	s_addc_u32 s35, s10, s35
	s_and_b64 vcc, exec, s[46:47]
	v_mfma_f32_16x16x32_bf16 v[26:29], v[182:185], v[134:137], v[14:17]
	s_nop 4
	v_cvt_pk_bf16_f32 v14, v30, v31
	v_cvt_pk_bf16_f32 v15, v32, v33
	s_nop 0
	v_cvt_pk_bf16_f32 v16, v26, v27
	v_cvt_pk_bf16_f32 v17, v28, v29
	ds_write2st64_b64 v172, v[14:15], v[16:17] offset1:9
	s_waitcnt vmcnt(26)
	ds_write_b128 v161, v[46:49] offset:57344
	s_waitcnt vmcnt(25)
	ds_write_b128 v163, v[58:61] offset:57344
	s_waitcnt vmcnt(24)
	ds_write_b128 v174, v[66:69] offset:57344
	s_waitcnt vmcnt(23)
	ds_write_b128 v165, v[78:81] offset:57344
	s_waitcnt vmcnt(22)
	ds_write_b128 v175, v[114:117]
	s_waitcnt vmcnt(21)
	ds_write_b128 v176, v[126:129]
	v_lshl_add_u64 v[14:15], s[68:69], 0, v[146:147]
	global_load_dwordx4 v[46:49], v[14:15], off
	v_lshl_add_u64 v[14:15], s[68:69], 0, v[148:149]
	global_load_dwordx4 v[58:61], v[14:15], off
	v_lshl_add_u64 v[14:15], s[70:71], 0, v[146:147]
	global_load_dwordx4 v[66:69], v[14:15], off
	v_lshl_add_u64 v[14:15], s[70:71], 0, v[148:149]
	global_load_dwordx4 v[78:81], v[14:15], off
	v_lshl_add_u64 v[14:15], s[34:35], 0, v[146:147]
	global_load_dwordx4 v[98:101], v[14:15], off
	v_lshl_add_u64 v[14:15], s[34:35], 0, v[148:149]
	s_lshl_b64 s[34:35], s[0:1], 15
	s_lshl_b64 s[0:1], s[0:1], 8
	v_lshl_add_u64 v[114:115], v[152:153], 0, s[0:1]
	global_load_dwordx4 v[110:113], v[14:15], off
	global_load_dword v160, v[114:115], off
	v_lshl_add_u64 v[14:15], v[156:157], 0, s[34:35]
	v_lshl_add_u64 v[16:17], v[154:155], 0, s[8:9]
	v_cndmask_b32_e64 v15, v17, v15, s[44:45]
	v_cndmask_b32_e64 v14, v16, v14, s[44:45]
	global_load_dwordx4 v[22:25], v[14:15], off
	v_lshl_add_u64 v[14:15], v[14:15], 0, s[60:61]
	global_load_dwordx4 v[14:17], v[14:15], off
	s_cbranch_vccnz .LBB0_1683
	v_cvt_pk_bf16_f32 v116, v118, v118
	s_mov_b64 s[0:1], 0xc0000
	v_and_b32_e32 v116, 0xffff, v116
	v_lshl_add_u64 v[114:115], v[150:151], 0, s[0:1]
	global_store_short v[114:115], v116, off
	v_cvt_pk_bf16_f32 v116, v119, v119
	s_mov_b64 s[0:1], 0xc0800
	v_and_b32_e32 v116, 0xffff, v116
	v_lshl_add_u64 v[114:115], v[150:151], 0, s[0:1]
	global_store_short v[114:115], v116, off
	v_cvt_pk_bf16_f32 v116, v120, v120
	s_mov_b64 s[0:1], 0xc1000
	v_and_b32_e32 v116, 0xffff, v116
	v_lshl_add_u64 v[114:115], v[150:151], 0, s[0:1]
	global_store_short v[114:115], v116, off
	v_cvt_pk_bf16_f32 v116, v121, v121
	s_mov_b64 s[0:1], 0xc1800
	v_and_b32_e32 v116, 0xffff, v116
	v_lshl_add_u64 v[114:115], v[150:151], 0, s[0:1]
	global_store_short v[114:115], v116, off
	v_cvt_pk_bf16_f32 v116, v122, v122
	s_mov_b64 s[0:1], 0xc0020
	v_and_b32_e32 v116, 0xffff, v116
	v_lshl_add_u64 v[114:115], v[150:151], 0, s[0:1]
	global_store_short v[114:115], v116, off
	v_cvt_pk_bf16_f32 v116, v123, v123
	s_mov_b64 s[0:1], 0xc0820
	v_and_b32_e32 v116, 0xffff, v116
	v_lshl_add_u64 v[114:115], v[150:151], 0, s[0:1]
	global_store_short v[114:115], v116, off
	v_cvt_pk_bf16_f32 v116, v124, v124
	s_mov_b64 s[0:1], 0xc1020
	v_and_b32_e32 v116, 0xffff, v116
	v_lshl_add_u64 v[114:115], v[150:151], 0, s[0:1]
	global_store_short v[114:115], v116, off
	s_mov_b64 s[0:1], 0xc1820
	v_cvt_pk_bf16_f32 v116, v125, v125
	v_lshl_add_u64 v[114:115], v[150:151], 0, s[0:1]
	v_and_b32_e32 v116, 0xffff, v116
	global_store_short v[114:115], v116, off
.LBB0_1683:
	s_waitcnt lgkmcnt(0)
	s_barrier
	ds_read_b128 v[114:117], v168 offset:57344
	ds_read_b128 v[118:121], v143
	ds_read_b128 v[122:125], v143 offset:4608
	ds_read_b128 v[178:181], v168 offset:57408
	ds_read_b128 v[126:129], v143 offset:64
	ds_read_b128 v[182:185], v143 offset:4672
	ds_read_b128 v[186:189], v168 offset:57472
	ds_read_b128 v[190:193], v143 offset:128
	ds_read_b128 v[206:209], v143 offset:4736
	ds_read_b128 v[210:213], v168 offset:57536
	ds_read_b128 v[214:217], v143 offset:192
	ds_read_b128 v[218:221], v143 offset:4800
	s_and_b64 vcc, exec, s[48:49]
	s_waitcnt lgkmcnt(10)
	v_mfma_f32_16x16x32_bf16 v[118:121], v[114:117], v[118:121], 0
	s_waitcnt lgkmcnt(9)
	v_mfma_f32_16x16x32_bf16 v[114:117], v[114:117], v[122:125], 0
	s_nop 0
	s_nop 0
	s_waitcnt lgkmcnt(7)
	v_mfma_f32_16x16x32_bf16 v[118:121], v[178:181], v[126:129], v[118:121]
	s_nop 0
	s_waitcnt lgkmcnt(6)
	v_mfma_f32_16x16x32_bf16 v[114:117], v[178:181], v[182:185], v[114:117]
	s_nop 0
	s_nop 0
	s_waitcnt lgkmcnt(4)
	v_mfma_f32_16x16x32_bf16 v[118:121], v[186:189], v[190:193], v[118:121]
	s_nop 0
	s_waitcnt lgkmcnt(3)
	v_mfma_f32_16x16x32_bf16 v[114:117], v[186:189], v[206:209], v[114:117]
	s_nop 0
	s_nop 0
	s_waitcnt lgkmcnt(1)
	v_mfma_f32_16x16x32_bf16 v[118:121], v[210:213], v[214:217], v[118:121]
	s_nop 0
	s_waitcnt lgkmcnt(0)
	v_mfma_f32_16x16x32_bf16 v[122:125], v[210:213], v[218:221], v[114:117]
	s_cbranch_vccnz .LBB0_1685
	s_waitcnt vmcnt(28)
	s_nop 2
	v_sub_f32_e32 v115, v37, v121
	v_sub_f32_e32 v116, v36, v120
	v_sub_f32_e32 v114, v35, v119
	v_sub_f32_e32 v117, v34, v118
	v_cvt_pk_bf16_f32 v114, v117, v114
	v_cvt_pk_bf16_f32 v115, v116, v115
	s_waitcnt vmcnt(27)
	v_sub_f32_e32 v117, v5, v125
	v_sub_f32_e32 v126, v4, v124
	v_sub_f32_e32 v116, v3, v123
	v_sub_f32_e32 v127, v2, v122
	v_cvt_pk_bf16_f32 v116, v127, v116
	v_cvt_pk_bf16_f32 v117, v126, v117
	ds_write2st64_b64 v170, v[114:115], v[116:117] offset1:5

.LBB0_1687:
	s_andn2_b64 vcc, exec, s[8:9]
	s_cbranch_vccnz .LBB0_1689
	ds_read_b128 v[126:129], v169
	ds_read_b128 v[114:117], v169 offset:64
	ds_read_b128 v[130:133], v169 offset:2560
	ds_read_b128 v[134:137], v169 offset:2624
	s_waitcnt lgkmcnt(7)
	s_nop 0
	s_waitcnt lgkmcnt(6)
	s_nop 0
	s_waitcnt lgkmcnt(5)
	s_nop 0
	s_waitcnt lgkmcnt(4)
	s_nop 0
	s_waitcnt vmcnt(28) lgkmcnt(3)
	v_mfma_f32_16x16x32_bf16 v[118:121], v[34:37], v[126:129], v[118:121]
	s_waitcnt lgkmcnt(1)
	v_mfma_f32_16x16x32_bf16 v[34:37], v[34:37], v[130:133], v[122:125]
	s_waitcnt vmcnt(27)
	v_mfma_f32_16x16x32_bf16 v[118:121], v[2:5], v[114:117], v[118:121]
	s_waitcnt lgkmcnt(0)
	v_mfma_f32_16x16x32_bf16 v[122:125], v[2:5], v[134:137], v[34:37]
.LBB0_1689:
	ds_read_b128 v[178:181], v177
	ds_read_b128 v[182:185], v177 offset:64
	s_waitcnt vmcnt(27)
	v_pk_mul_f32 v[4:5], v[138:139], v[32:33] op_sel_hi:[0,1]
	v_pk_mul_f32 v[2:3], v[138:139], v[30:31] op_sel_hi:[0,1]
	s_nop 0
	v_pk_mul_f32 v[28:29], v[138:139], v[28:29] op_sel_hi:[0,1]
	v_pk_mul_f32 v[26:27], v[138:139], v[26:27] op_sel_hi:[0,1]
	s_or_b32 s0, s6, 0x58
	s_ashr_i32 s1, s0, 31
	s_lshl_b64 s[8:9], s[0:1], 13
	s_lshl_b64 s[34:35], s[0:1], 14
	s_waitcnt lgkmcnt(1)
	v_mfma_f32_16x16x32_bf16 v[2:5], v[178:181], v[126:129], v[2:5]
	s_add_u32 s68, s95, s34
	s_addc_u32 s69, s3, s35
	s_add_u32 s70, s29, s34
	v_mfma_f32_16x16x32_bf16 v[26:29], v[178:181], v[130:133], v[26:29]
	s_nop 0
	s_addc_u32 s71, s94, s35
	s_add_u32 s34, s2, s34
	s_waitcnt lgkmcnt(0)
	v_mfma_f32_16x16x32_bf16 v[114:117], v[182:185], v[114:117], v[2:5]
	s_addc_u32 s35, s10, s35
	s_and_b64 vcc, exec, s[46:47]
	s_nop 5
	v_cvt_pk_bf16_f32 v2, v114, v115
	v_mfma_f32_16x16x32_bf16 v[30:33], v[182:185], v[134:137], v[26:29]
	v_cvt_pk_bf16_f32 v3, v116, v117
	s_nop 6
	v_cvt_pk_bf16_f32 v4, v30, v31
	v_cvt_pk_bf16_f32 v5, v32, v33
	ds_write2st64_b64 v172, v[2:3], v[4:5] offset1:9
	s_waitcnt vmcnt(26)
	ds_write_b128 v161, v[50:53]
	s_waitcnt vmcnt(25)
	ds_write_b128 v163, v[62:65]
	s_waitcnt vmcnt(24)
	ds_write_b128 v161, v[70:73] offset:18432
	s_waitcnt vmcnt(23)
	ds_write_b128 v165, v[82:85]
	s_waitcnt vmcnt(22)
	ds_write_b128 v166, v[90:93] offset:36864
	s_waitcnt vmcnt(21)
	ds_write_b128 v167, v[106:109] offset:36864
	v_lshl_add_u64 v[2:3], s[68:69], 0, v[146:147]
	global_load_dwordx4 v[34:37], v[2:3], off
	v_lshl_add_u64 v[2:3], s[68:69], 0, v[148:149]
	global_load_dwordx4 v[50:53], v[2:3], off
	v_lshl_add_u64 v[2:3], s[70:71], 0, v[146:147]
	global_load_dwordx4 v[62:65], v[2:3], off
	v_lshl_add_u64 v[2:3], s[70:71], 0, v[148:149]
	global_load_dwordx4 v[82:85], v[2:3], off
	v_lshl_add_u64 v[2:3], s[34:35], 0, v[146:147]
	global_load_dwordx4 v[90:93], v[2:3], off
	v_lshl_add_u64 v[2:3], s[34:35], 0, v[148:149]
	s_lshl_b64 s[34:35], s[0:1], 15
	s_lshl_b64 s[0:1], s[0:1], 8
	v_lshl_add_u64 v[70:71], v[152:153], 0, s[0:1]
	global_load_dwordx4 v[106:109], v[2:3], off
	global_load_dword v138, v[70:71], off
	v_lshl_add_u64 v[2:3], v[156:157], 0, s[34:35]
	v_lshl_add_u64 v[4:5], v[154:155], 0, s[8:9]
	v_cndmask_b32_e64 v3, v5, v3, s[44:45]
	v_cndmask_b32_e64 v2, v4, v2, s[44:45]
	global_load_dwordx4 v[26:29], v[2:3], off
	v_lshl_add_u64 v[2:3], v[2:3], 0, s[60:61]
	global_load_dwordx4 v[2:5], v[2:3], off
	s_cbranch_vccnz .LBB0_1691
	v_cvt_pk_bf16_f32 v72, v118, v118
	s_mov_b64 s[0:1], 0xe0000
	v_and_b32_e32 v72, 0xffff, v72
	v_lshl_add_u64 v[70:71], v[150:151], 0, s[0:1]
	global_store_short v[70:71], v72, off
	v_cvt_pk_bf16_f32 v72, v119, v119
	s_mov_b64 s[0:1], 0xe0800
	v_and_b32_e32 v72, 0xffff, v72
	v_lshl_add_u64 v[70:71], v[150:151], 0, s[0:1]
	global_store_short v[70:71], v72, off
	v_cvt_pk_bf16_f32 v72, v120, v120
	s_mov_b64 s[0:1], 0xe1000
	v_and_b32_e32 v72, 0xffff, v72
	v_lshl_add_u64 v[70:71], v[150:151], 0, s[0:1]
	global_store_short v[70:71], v72, off
	v_cvt_pk_bf16_f32 v72, v121, v121
	s_mov_b64 s[0:1], 0xe1800
	v_and_b32_e32 v72, 0xffff, v72
	v_lshl_add_u64 v[70:71], v[150:151], 0, s[0:1]
	global_store_short v[70:71], v72, off
	v_cvt_pk_bf16_f32 v72, v122, v122
	s_mov_b64 s[0:1], 0xe0020
	v_and_b32_e32 v72, 0xffff, v72
	v_lshl_add_u64 v[70:71], v[150:151], 0, s[0:1]
	global_store_short v[70:71], v72, off
	v_cvt_pk_bf16_f32 v72, v123, v123
	s_mov_b64 s[0:1], 0xe0820
	v_and_b32_e32 v72, 0xffff, v72
	v_lshl_add_u64 v[70:71], v[150:151], 0, s[0:1]
	global_store_short v[70:71], v72, off
	v_cvt_pk_bf16_f32 v72, v124, v124
	s_mov_b64 s[0:1], 0xe1020
	v_and_b32_e32 v72, 0xffff, v72
	v_lshl_add_u64 v[70:71], v[150:151], 0, s[0:1]
	global_store_short v[70:71], v72, off
	s_mov_b64 s[0:1], 0xe1820
	v_cvt_pk_bf16_f32 v72, v125, v125
	v_lshl_add_u64 v[70:71], v[150:151], 0, s[0:1]
	v_and_b32_e32 v72, 0xffff, v72
	global_store_short v[70:71], v72, off
.LBB0_1691:
	s_waitcnt lgkmcnt(0)
	s_barrier
	ds_read_b128 v[70:73], v168
	ds_read_b128 v[118:121], v143
	ds_read_b128 v[122:125], v143 offset:4608
	ds_read_b128 v[178:181], v168 offset:64
	ds_read_b128 v[126:129], v143 offset:64
	ds_read_b128 v[182:185], v143 offset:4672
	ds_read_b128 v[186:189], v168 offset:128
	ds_read_b128 v[190:193], v143 offset:128
	ds_read_b128 v[206:209], v143 offset:4736
	ds_read_b128 v[210:213], v168 offset:192
	ds_read_b128 v[214:217], v143 offset:192
	ds_read_b128 v[218:221], v143 offset:4800
	s_and_b64 vcc, exec, s[48:49]
	s_waitcnt lgkmcnt(10)
	v_mfma_f32_16x16x32_bf16 v[118:121], v[70:73], v[118:121], 0
	s_waitcnt lgkmcnt(9)
	v_mfma_f32_16x16x32_bf16 v[70:73], v[70:73], v[122:125], 0
	s_nop 0
	s_nop 0
	s_waitcnt lgkmcnt(7)
	v_mfma_f32_16x16x32_bf16 v[118:121], v[178:181], v[126:129], v[118:121]
	s_nop 0
	s_waitcnt lgkmcnt(6)
	v_mfma_f32_16x16x32_bf16 v[70:73], v[178:181], v[182:185], v[70:73]
	s_nop 0
	s_nop 0
	s_waitcnt lgkmcnt(4)
	v_mfma_f32_16x16x32_bf16 v[118:121], v[186:189], v[190:193], v[118:121]
	s_nop 0
	s_waitcnt lgkmcnt(3)
	v_mfma_f32_16x16x32_bf16 v[70:73], v[186:189], v[206:209], v[70:73]
	s_nop 0
	s_nop 0
	s_waitcnt lgkmcnt(1)
	v_mfma_f32_16x16x32_bf16 v[122:125], v[210:213], v[214:217], v[118:121]
	s_nop 2
	s_nop 0
	s_waitcnt lgkmcnt(0)
	v_mfma_f32_16x16x32_bf16 v[126:129], v[210:213], v[218:221], v[70:73]
	s_cbranch_vccnz .LBB0_1693
	s_waitcnt vmcnt(28)
	s_nop 0
	v_sub_f32_e32 v71, v41, v125
	v_sub_f32_e32 v72, v40, v124
	v_sub_f32_e32 v70, v39, v123
	v_sub_f32_e32 v73, v38, v122
	v_cvt_pk_bf16_f32 v70, v73, v70
	v_cvt_pk_bf16_f32 v71, v72, v71
	s_waitcnt vmcnt(27)
	v_sub_f32_e32 v73, v9, v129
	v_sub_f32_e32 v118, v8, v128
	v_sub_f32_e32 v72, v7, v127
	v_sub_f32_e32 v119, v6, v126
	v_cvt_pk_bf16_f32 v72, v119, v72
	v_cvt_pk_bf16_f32 v73, v118, v73
	ds_write2st64_b64 v170, v[70:71], v[72:73] offset1:5

.LBB0_1695:
	s_andn2_b64 vcc, exec, s[8:9]
	s_cbranch_vccnz .LBB0_1697
	ds_read_b128 v[118:121], v169
	ds_read_b128 v[70:73], v169 offset:64
	ds_read_b128 v[130:133], v169 offset:2560
	ds_read_b128 v[134:137], v169 offset:2624
	s_waitcnt lgkmcnt(7)
	s_nop 0
	s_waitcnt lgkmcnt(6)
	s_nop 0
	s_waitcnt lgkmcnt(5)
	s_nop 0
	s_waitcnt lgkmcnt(4)
	s_nop 0
	s_waitcnt vmcnt(28) lgkmcnt(3)
	v_mfma_f32_16x16x32_bf16 v[122:125], v[38:41], v[118:121], v[122:125]
	s_waitcnt lgkmcnt(1)
	v_mfma_f32_16x16x32_bf16 v[38:41], v[38:41], v[130:133], v[126:129]
	s_waitcnt vmcnt(27)
	v_mfma_f32_16x16x32_bf16 v[122:125], v[6:9], v[70:73], v[122:125]
	s_waitcnt lgkmcnt(0)
	v_mfma_f32_16x16x32_bf16 v[126:129], v[6:9], v[134:137], v[38:41]
.LBB0_1697:
	ds_read_b128 v[38:41], v173 offset:36864
	ds_read_b128 v[178:181], v173 offset:36928
	s_waitcnt vmcnt(28)
	s_nop 2
	s_nop 0
	s_waitcnt vmcnt(27)
	v_pk_mul_f32 v[8:9], v[140:141], v[116:117] op_sel_hi:[0,1]
	v_pk_mul_f32 v[6:7], v[140:141], v[114:115] op_sel_hi:[0,1]
	v_pk_mul_f32 v[32:33], v[140:141], v[32:33] op_sel_hi:[0,1]
	v_pk_mul_f32 v[30:31], v[140:141], v[30:31] op_sel_hi:[0,1]
	s_or_b32 s0, s6, 0x60
	s_ashr_i32 s1, s0, 31
	s_lshl_b64 s[8:9], s[0:1], 13
	s_lshl_b64 s[34:35], s[0:1], 14
	s_waitcnt lgkmcnt(1)
	v_mfma_f32_16x16x32_bf16 v[6:9], v[38:41], v[118:121], v[6:9]
	s_add_u32 s68, s95, s34
	s_addc_u32 s69, s3, s35
	s_add_u32 s70, s29, s34
	v_mfma_f32_16x16x32_bf16 v[30:33], v[38:41], v[130:133], v[30:33]
	s_nop 0
	s_addc_u32 s71, s94, s35
	s_add_u32 s34, s2, s34
	s_addc_u32 s35, s10, s35
	s_waitcnt lgkmcnt(0)
	v_mfma_f32_16x16x32_bf16 v[118:121], v[178:181], v[70:73], v[6:9]
	s_and_b64 vcc, exec, s[46:47]
	s_nop 6
	v_cvt_pk_bf16_f32 v6, v118, v119
	v_mfma_f32_16x16x32_bf16 v[114:117], v[178:181], v[134:137], v[30:33]
	v_cvt_pk_bf16_f32 v7, v120, v121
	s_nop 6
	v_cvt_pk_bf16_f32 v8, v114, v115
	v_cvt_pk_bf16_f32 v9, v116, v117
	ds_write2st64_b64 v172, v[6:7], v[8:9] offset1:9
	s_waitcnt vmcnt(26)
	ds_write_b128 v161, v[42:45] offset:57344
	s_waitcnt vmcnt(25)
	ds_write_b128 v163, v[54:57] offset:57344
	s_waitcnt vmcnt(24)
	ds_write_b128 v174, v[74:77] offset:57344
	s_waitcnt vmcnt(23)
	ds_write_b128 v165, v[86:89] offset:57344
	s_waitcnt vmcnt(22)
	ds_write_b128 v175, v[94:97]
	s_waitcnt vmcnt(21)
	ds_write_b128 v176, v[102:105]
	v_lshl_add_u64 v[6:7], s[68:69], 0, v[146:147]
	global_load_dwordx4 v[38:41], v[6:7], off
	v_lshl_add_u64 v[6:7], s[68:69], 0, v[148:149]
	global_load_dwordx4 v[54:57], v[6:7], off
	v_lshl_add_u64 v[6:7], s[70:71], 0, v[146:147]
	global_load_dwordx4 v[70:73], v[6:7], off
	v_lshl_add_u64 v[6:7], s[70:71], 0, v[148:149]
	global_load_dwordx4 v[74:77], v[6:7], off
	v_lshl_add_u64 v[6:7], s[34:35], 0, v[146:147]
	global_load_dwordx4 v[86:89], v[6:7], off
	v_lshl_add_u64 v[6:7], s[34:35], 0, v[148:149]
	s_lshl_b64 s[34:35], s[0:1], 15
	s_lshl_b64 s[0:1], s[0:1], 8
	v_lshl_add_u64 v[42:43], v[152:153], 0, s[0:1]
	global_load_dwordx4 v[102:105], v[6:7], off
	global_load_dword v140, v[42:43], off
	v_lshl_add_u64 v[6:7], v[156:157], 0, s[34:35]
	v_lshl_add_u64 v[8:9], v[154:155], 0, s[8:9]
	v_cndmask_b32_e64 v7, v9, v7, s[44:45]
	v_cndmask_b32_e64 v6, v8, v6, s[44:45]
	global_load_dwordx4 v[30:33], v[6:7], off
	v_lshl_add_u64 v[6:7], v[6:7], 0, s[60:61]
	global_load_dwordx4 v[6:9], v[6:7], off
	s_cbranch_vccnz .LBB0_1699
	v_cvt_pk_bf16_f32 v44, v122, v122
	s_mov_b64 s[0:1], 0x100000
	v_and_b32_e32 v44, 0xffff, v44
	v_lshl_add_u64 v[42:43], v[150:151], 0, s[0:1]
	global_store_short v[42:43], v44, off
	v_cvt_pk_bf16_f32 v44, v123, v123
	s_mov_b64 s[0:1], 0x100800
	v_and_b32_e32 v44, 0xffff, v44
	v_lshl_add_u64 v[42:43], v[150:151], 0, s[0:1]
	global_store_short v[42:43], v44, off
	v_cvt_pk_bf16_f32 v44, v124, v124
	s_mov_b64 s[0:1], 0x101000
	v_and_b32_e32 v44, 0xffff, v44
	v_lshl_add_u64 v[42:43], v[150:151], 0, s[0:1]
	global_store_short v[42:43], v44, off
	v_cvt_pk_bf16_f32 v44, v125, v125
	s_mov_b64 s[0:1], 0x101800
	v_and_b32_e32 v44, 0xffff, v44
	v_lshl_add_u64 v[42:43], v[150:151], 0, s[0:1]
	global_store_short v[42:43], v44, off
	v_cvt_pk_bf16_f32 v44, v126, v126
	s_mov_b64 s[0:1], 0x100020
	v_and_b32_e32 v44, 0xffff, v44
	v_lshl_add_u64 v[42:43], v[150:151], 0, s[0:1]
	global_store_short v[42:43], v44, off
	v_cvt_pk_bf16_f32 v44, v127, v127
	s_mov_b64 s[0:1], 0x100820
	v_and_b32_e32 v44, 0xffff, v44
	v_lshl_add_u64 v[42:43], v[150:151], 0, s[0:1]
	global_store_short v[42:43], v44, off
	v_cvt_pk_bf16_f32 v44, v128, v128
	s_mov_b64 s[0:1], 0x101020
	v_and_b32_e32 v44, 0xffff, v44
	v_lshl_add_u64 v[42:43], v[150:151], 0, s[0:1]
	global_store_short v[42:43], v44, off
	s_mov_b64 s[0:1], 0x101820
	v_cvt_pk_bf16_f32 v44, v129, v129
	v_lshl_add_u64 v[42:43], v[150:151], 0, s[0:1]
	v_and_b32_e32 v44, 0xffff, v44
	global_store_short v[42:43], v44, off
.LBB0_1699:
	s_waitcnt lgkmcnt(0)
	s_barrier
	ds_read_b128 v[42:45], v168 offset:57344
	ds_read_b128 v[94:97], v143
	ds_read_b128 v[122:125], v143 offset:4608
	ds_read_b128 v[178:181], v168 offset:57408
	ds_read_b128 v[126:129], v143 offset:64
	ds_read_b128 v[182:185], v143 offset:4672
	ds_read_b128 v[186:189], v168 offset:57472
	ds_read_b128 v[190:193], v143 offset:128
	ds_read_b128 v[206:209], v143 offset:4736
	ds_read_b128 v[210:213], v168 offset:57536
	ds_read_b128 v[214:217], v143 offset:192
	ds_read_b128 v[218:221], v143 offset:4800
	s_and_b64 vcc, exec, s[48:49]
	s_waitcnt lgkmcnt(10)
	v_mfma_f32_16x16x32_bf16 v[94:97], v[42:45], v[94:97], 0
	s_waitcnt lgkmcnt(9)
	v_mfma_f32_16x16x32_bf16 v[42:45], v[42:45], v[122:125], 0
	s_nop 0
	s_nop 0
	s_waitcnt lgkmcnt(7)
	v_mfma_f32_16x16x32_bf16 v[94:97], v[178:181], v[126:129], v[94:97]
	s_nop 0
	s_waitcnt lgkmcnt(6)
	v_mfma_f32_16x16x32_bf16 v[42:45], v[178:181], v[182:185], v[42:45]
	s_nop 0
	s_nop 0
	s_waitcnt lgkmcnt(4)
	v_mfma_f32_16x16x32_bf16 v[94:97], v[186:189], v[190:193], v[94:97]
	s_nop 0
	s_waitcnt lgkmcnt(3)
	v_mfma_f32_16x16x32_bf16 v[42:45], v[186:189], v[206:209], v[42:45]
	s_nop 0
	s_nop 0
	s_waitcnt lgkmcnt(1)
	v_mfma_f32_16x16x32_bf16 v[122:125], v[210:213], v[214:217], v[94:97]
	s_nop 2
	s_nop 0
	s_waitcnt lgkmcnt(0)
	v_mfma_f32_16x16x32_bf16 v[126:129], v[210:213], v[218:221], v[42:45]
	s_cbranch_vccnz .LBB0_1701
	s_waitcnt vmcnt(28)
	s_nop 0
	v_sub_f32_e32 v43, v21, v125
	v_sub_f32_e32 v44, v20, v124
	v_sub_f32_e32 v42, v19, v123
	v_sub_f32_e32 v45, v18, v122
	v_cvt_pk_bf16_f32 v42, v45, v42
	v_cvt_pk_bf16_f32 v43, v44, v43
	s_waitcnt vmcnt(27)
	v_sub_f32_e32 v45, v13, v129
	v_sub_f32_e32 v94, v12, v128
	v_sub_f32_e32 v44, v11, v127
	v_sub_f32_e32 v95, v10, v126
	v_cvt_pk_bf16_f32 v44, v95, v44
	v_cvt_pk_bf16_f32 v45, v94, v45
	ds_write2st64_b64 v170, v[42:43], v[44:45] offset1:5

.LBB0_1703:
	s_andn2_b64 vcc, exec, s[8:9]
	s_cbranch_vccnz .LBB0_1705
	ds_read_b128 v[94:97], v169
	ds_read_b128 v[42:45], v169 offset:64
	ds_read_b128 v[130:133], v169 offset:2560
	ds_read_b128 v[134:137], v169 offset:2624
	s_waitcnt lgkmcnt(7)
	s_nop 0
	s_waitcnt lgkmcnt(6)
	s_nop 0
	s_waitcnt lgkmcnt(5)
	s_nop 0
	s_waitcnt lgkmcnt(4)
	s_nop 0
	s_waitcnt vmcnt(28) lgkmcnt(3)
	v_mfma_f32_16x16x32_bf16 v[122:125], v[18:21], v[94:97], v[122:125]
	s_waitcnt lgkmcnt(1)
	v_mfma_f32_16x16x32_bf16 v[18:21], v[18:21], v[130:133], v[126:129]
	s_waitcnt vmcnt(27)
	v_mfma_f32_16x16x32_bf16 v[122:125], v[10:13], v[42:45], v[122:125]
	s_waitcnt lgkmcnt(0)
	v_mfma_f32_16x16x32_bf16 v[126:129], v[10:13], v[134:137], v[18:21]
.LBB0_1705:
	ds_read_b128 v[178:181], v177
	ds_read_b128 v[182:185], v177 offset:64
	s_waitcnt vmcnt(28)
	s_nop 2
	v_pk_mul_f32 v[20:21], v[158:159], v[116:117] op_sel_hi:[0,1]
	v_pk_mul_f32 v[18:19], v[158:159], v[114:115] op_sel_hi:[0,1]
	s_nop 0
	s_waitcnt vmcnt(27)
	v_pk_mul_f32 v[12:13], v[158:159], v[120:121] op_sel_hi:[0,1]
	v_pk_mul_f32 v[10:11], v[158:159], v[118:119] op_sel_hi:[0,1]
	s_or_b32 s0, s6, 0x68
	s_ashr_i32 s1, s0, 31
	s_lshl_b64 s[8:9], s[0:1], 13
	s_lshl_b64 s[34:35], s[0:1], 14
	s_waitcnt lgkmcnt(1)
	v_mfma_f32_16x16x32_bf16 v[10:13], v[178:181], v[94:97], v[10:13]
	s_nop 0
	s_add_u32 s68, s95, s34
	s_addc_u32 s69, s3, s35
	v_mfma_f32_16x16x32_bf16 v[18:21], v[178:181], v[130:133], v[18:21]
	s_add_u32 s70, s29, s34
	s_addc_u32 s71, s94, s35
	s_add_u32 s34, s2, s34
	s_waitcnt lgkmcnt(0)
	v_mfma_f32_16x16x32_bf16 v[118:121], v[182:185], v[42:45], v[10:13]
	s_addc_u32 s35, s10, s35
	s_and_b64 vcc, exec, s[46:47]
	v_mfma_f32_16x16x32_bf16 v[114:117], v[182:185], v[134:137], v[18:21]
	s_nop 4
	v_cvt_pk_bf16_f32 v10, v118, v119
	v_cvt_pk_bf16_f32 v11, v120, v121
	s_nop 0
	v_cvt_pk_bf16_f32 v12, v114, v115
	v_cvt_pk_bf16_f32 v13, v116, v117
	ds_write2st64_b64 v172, v[10:11], v[12:13] offset1:9
	s_waitcnt vmcnt(26)
	ds_write_b128 v161, v[46:49]
	s_waitcnt vmcnt(25)
	ds_write_b128 v163, v[58:61]
	s_waitcnt vmcnt(24)
	ds_write_b128 v161, v[66:69] offset:18432
	s_waitcnt vmcnt(23)
	ds_write_b128 v165, v[78:81]
	s_waitcnt vmcnt(22)
	ds_write_b128 v166, v[98:101] offset:36864
	s_waitcnt vmcnt(21)
	ds_write_b128 v167, v[110:113] offset:36864
	v_lshl_add_u64 v[10:11], s[68:69], 0, v[146:147]
	global_load_dwordx4 v[42:45], v[10:11], off
	v_lshl_add_u64 v[10:11], s[68:69], 0, v[148:149]
	global_load_dwordx4 v[46:49], v[10:11], off
	v_lshl_add_u64 v[10:11], s[70:71], 0, v[146:147]
	global_load_dwordx4 v[58:61], v[10:11], off
	v_lshl_add_u64 v[10:11], s[70:71], 0, v[148:149]
	global_load_dwordx4 v[78:81], v[10:11], off
	v_lshl_add_u64 v[10:11], s[34:35], 0, v[146:147]
	global_load_dwordx4 v[94:97], v[10:11], off
	v_lshl_add_u64 v[10:11], s[34:35], 0, v[148:149]
	s_lshl_b64 s[34:35], s[0:1], 15
	s_lshl_b64 s[0:1], s[0:1], 8
	v_lshl_add_u64 v[66:67], v[152:153], 0, s[0:1]
	global_load_dwordx4 v[98:101], v[10:11], off
	global_load_dword v158, v[66:67], off
	v_lshl_add_u64 v[10:11], v[156:157], 0, s[34:35]
	v_lshl_add_u64 v[12:13], v[154:155], 0, s[8:9]
	v_cndmask_b32_e64 v11, v13, v11, s[44:45]
	v_cndmask_b32_e64 v10, v12, v10, s[44:45]
	global_load_dwordx4 v[18:21], v[10:11], off
	v_lshl_add_u64 v[10:11], v[10:11], 0, s[60:61]
	global_load_dwordx4 v[10:13], v[10:11], off
	s_cbranch_vccnz .LBB0_1707
	v_cvt_pk_bf16_f32 v68, v122, v122
	s_mov_b64 s[0:1], 0x120000
	v_and_b32_e32 v68, 0xffff, v68
	v_lshl_add_u64 v[66:67], v[150:151], 0, s[0:1]
	global_store_short v[66:67], v68, off
	v_cvt_pk_bf16_f32 v68, v123, v123
	s_mov_b64 s[0:1], 0x120800
	v_and_b32_e32 v68, 0xffff, v68
	v_lshl_add_u64 v[66:67], v[150:151], 0, s[0:1]
	global_store_short v[66:67], v68, off
	v_cvt_pk_bf16_f32 v68, v124, v124
	s_mov_b64 s[0:1], 0x121000
	v_and_b32_e32 v68, 0xffff, v68
	v_lshl_add_u64 v[66:67], v[150:151], 0, s[0:1]
	global_store_short v[66:67], v68, off
	v_cvt_pk_bf16_f32 v68, v125, v125
	s_mov_b64 s[0:1], 0x121800
	v_and_b32_e32 v68, 0xffff, v68
	v_lshl_add_u64 v[66:67], v[150:151], 0, s[0:1]
	global_store_short v[66:67], v68, off
	v_cvt_pk_bf16_f32 v68, v126, v126
	s_mov_b64 s[0:1], 0x120020
	v_and_b32_e32 v68, 0xffff, v68
	v_lshl_add_u64 v[66:67], v[150:151], 0, s[0:1]
	global_store_short v[66:67], v68, off
	v_cvt_pk_bf16_f32 v68, v127, v127
	s_mov_b64 s[0:1], 0x120820
	v_and_b32_e32 v68, 0xffff, v68
	v_lshl_add_u64 v[66:67], v[150:151], 0, s[0:1]
	global_store_short v[66:67], v68, off
	v_cvt_pk_bf16_f32 v68, v128, v128
	s_mov_b64 s[0:1], 0x121020
	v_and_b32_e32 v68, 0xffff, v68
	v_lshl_add_u64 v[66:67], v[150:151], 0, s[0:1]
	global_store_short v[66:67], v68, off
	s_mov_b64 s[0:1], 0x121820
	v_cvt_pk_bf16_f32 v68, v129, v129
	v_lshl_add_u64 v[66:67], v[150:151], 0, s[0:1]
	v_and_b32_e32 v68, 0xffff, v68
	global_store_short v[66:67], v68, off
.LBB0_1707:
	s_waitcnt lgkmcnt(0)
	s_barrier
	ds_read_b128 v[66:69], v168
	ds_read_b128 v[110:113], v143
	ds_read_b128 v[122:125], v143 offset:4608
	ds_read_b128 v[178:181], v168 offset:64
	ds_read_b128 v[126:129], v143 offset:64
	ds_read_b128 v[182:185], v143 offset:4672
	ds_read_b128 v[186:189], v168 offset:128
	ds_read_b128 v[190:193], v143 offset:128
	ds_read_b128 v[206:209], v143 offset:4736
	ds_read_b128 v[210:213], v168 offset:192
	ds_read_b128 v[214:217], v143 offset:192
	ds_read_b128 v[218:221], v143 offset:4800
	s_and_b64 vcc, exec, s[48:49]
	s_waitcnt lgkmcnt(10)
	v_mfma_f32_16x16x32_bf16 v[110:113], v[66:69], v[110:113], 0
	s_waitcnt lgkmcnt(9)
	v_mfma_f32_16x16x32_bf16 v[66:69], v[66:69], v[122:125], 0
	s_nop 0
	s_nop 0
	s_waitcnt lgkmcnt(7)
	v_mfma_f32_16x16x32_bf16 v[110:113], v[178:181], v[126:129], v[110:113]
	s_nop 0
	s_waitcnt lgkmcnt(6)
	v_mfma_f32_16x16x32_bf16 v[66:69], v[178:181], v[182:185], v[66:69]
	s_nop 0
	s_nop 0
	s_waitcnt lgkmcnt(4)
	v_mfma_f32_16x16x32_bf16 v[110:113], v[186:189], v[190:193], v[110:113]
	s_nop 0
	s_waitcnt lgkmcnt(3)
	v_mfma_f32_16x16x32_bf16 v[66:69], v[186:189], v[206:209], v[66:69]
	s_nop 0
	s_nop 0
	s_waitcnt lgkmcnt(1)
	v_mfma_f32_16x16x32_bf16 v[122:125], v[210:213], v[214:217], v[110:113]
	s_nop 2
	s_nop 0
	s_waitcnt lgkmcnt(0)
	v_mfma_f32_16x16x32_bf16 v[126:129], v[210:213], v[218:221], v[66:69]
	s_cbranch_vccnz .LBB0_1709
	s_waitcnt vmcnt(28)
	s_nop 0
	v_sub_f32_e32 v67, v25, v125
	v_sub_f32_e32 v68, v24, v124
	v_sub_f32_e32 v66, v23, v123
	v_sub_f32_e32 v69, v22, v122
	v_cvt_pk_bf16_f32 v66, v69, v66
	v_cvt_pk_bf16_f32 v67, v68, v67
	s_waitcnt vmcnt(27)
	v_sub_f32_e32 v69, v17, v129
	v_sub_f32_e32 v110, v16, v128
	v_sub_f32_e32 v68, v15, v127
	v_sub_f32_e32 v111, v14, v126
	v_cvt_pk_bf16_f32 v68, v111, v68
	v_cvt_pk_bf16_f32 v69, v110, v69
	ds_write2st64_b64 v170, v[66:67], v[68:69] offset1:5

.LBB0_1711:
	s_andn2_b64 vcc, exec, s[8:9]
	s_cbranch_vccnz .LBB0_1713
	ds_read_b128 v[110:113], v169
	ds_read_b128 v[66:69], v169 offset:64
	ds_read_b128 v[130:133], v169 offset:2560
	ds_read_b128 v[134:137], v169 offset:2624
	s_waitcnt lgkmcnt(7)
	s_nop 0
	s_waitcnt lgkmcnt(6)
	s_nop 0
	s_waitcnt lgkmcnt(5)
	s_nop 0
	s_waitcnt lgkmcnt(4)
	s_nop 0
	s_waitcnt vmcnt(28) lgkmcnt(3)
	v_mfma_f32_16x16x32_bf16 v[122:125], v[22:25], v[110:113], v[122:125]
	s_waitcnt lgkmcnt(1)
	v_mfma_f32_16x16x32_bf16 v[22:25], v[22:25], v[130:133], v[126:129]
	s_waitcnt vmcnt(27)
	v_mfma_f32_16x16x32_bf16 v[122:125], v[14:17], v[66:69], v[122:125]
	s_waitcnt lgkmcnt(0)
	v_mfma_f32_16x16x32_bf16 v[126:129], v[14:17], v[134:137], v[22:25]
.LBB0_1713:
	ds_read_b128 v[178:181], v173 offset:36864
	ds_read_b128 v[182:185], v173 offset:36928
	s_waitcnt vmcnt(28)
	s_nop 2
	v_pk_mul_f32 v[24:25], v[160:161], v[116:117] op_sel_hi:[0,1]
	v_pk_mul_f32 v[22:23], v[160:161], v[114:115] op_sel_hi:[0,1]
	s_nop 0
	s_waitcnt vmcnt(27)
	v_pk_mul_f32 v[16:17], v[160:161], v[120:121] op_sel_hi:[0,1]
	v_pk_mul_f32 v[14:15], v[160:161], v[118:119] op_sel_hi:[0,1]
	s_or_b32 s0, s6, 0x70
	s_ashr_i32 s1, s0, 31
	s_lshl_b64 s[8:9], s[0:1], 13
	s_lshl_b64 s[34:35], s[0:1], 14
	s_waitcnt lgkmcnt(1)
	v_mfma_f32_16x16x32_bf16 v[14:17], v[178:181], v[110:113], v[14:17]
	s_add_u32 s68, s95, s34
	s_addc_u32 s69, s3, s35
	s_add_u32 s70, s29, s34
	v_mfma_f32_16x16x32_bf16 v[22:25], v[178:181], v[130:133], v[22:25]
	s_nop 0
	s_addc_u32 s71, s94, s35
	s_add_u32 s34, s2, s34
	s_waitcnt lgkmcnt(0)
	v_mfma_f32_16x16x32_bf16 v[110:113], v[182:185], v[66:69], v[14:17]
	s_addc_u32 s35, s10, s35
	s_and_b64 vcc, exec, s[46:47]
	s_nop 5
	v_cvt_pk_bf16_f32 v14, v110, v111
	v_mfma_f32_16x16x32_bf16 v[66:69], v[182:185], v[134:137], v[22:25]
	v_cvt_pk_bf16_f32 v15, v112, v113
	s_nop 6
	v_cvt_pk_bf16_f32 v16, v66, v67
	v_cvt_pk_bf16_f32 v17, v68, v69
	ds_write2st64_b64 v172, v[14:15], v[16:17] offset1:9
	s_waitcnt vmcnt(26)
	ds_write_b128 v161, v[34:37] offset:57344
	s_waitcnt vmcnt(25)
	ds_write_b128 v163, v[50:53] offset:57344
	s_waitcnt vmcnt(24)
	ds_write_b128 v174, v[62:65] offset:57344
	s_waitcnt vmcnt(23)
	ds_write_b128 v165, v[82:85] offset:57344
	s_waitcnt vmcnt(22)
	ds_write_b128 v175, v[90:93]
	s_waitcnt vmcnt(21)
	ds_write_b128 v176, v[106:109]
	v_lshl_add_u64 v[14:15], s[68:69], 0, v[146:147]
	global_load_dwordx4 v[34:37], v[14:15], off
	v_lshl_add_u64 v[14:15], s[68:69], 0, v[148:149]
	global_load_dwordx4 v[50:53], v[14:15], off
	v_lshl_add_u64 v[14:15], s[70:71], 0, v[146:147]
	global_load_dwordx4 v[62:65], v[14:15], off
	v_lshl_add_u64 v[14:15], s[70:71], 0, v[148:149]
	global_load_dwordx4 v[82:85], v[14:15], off
	v_lshl_add_u64 v[14:15], s[34:35], 0, v[146:147]
	global_load_dwordx4 v[90:93], v[14:15], off
	v_lshl_add_u64 v[14:15], s[34:35], 0, v[148:149]
	s_lshl_b64 s[34:35], s[0:1], 15
	s_lshl_b64 s[0:1], s[0:1], 8
	v_lshl_add_u64 v[114:115], v[152:153], 0, s[0:1]
	global_load_dwordx4 v[106:109], v[14:15], off
	global_load_dword v160, v[114:115], off
	v_lshl_add_u64 v[14:15], v[156:157], 0, s[34:35]
	v_lshl_add_u64 v[16:17], v[154:155], 0, s[8:9]
	v_cndmask_b32_e64 v15, v17, v15, s[44:45]
	v_cndmask_b32_e64 v14, v16, v14, s[44:45]
	global_load_dwordx4 v[22:25], v[14:15], off
	v_lshl_add_u64 v[14:15], v[14:15], 0, s[60:61]
	global_load_dwordx4 v[14:17], v[14:15], off
	s_cbranch_vccnz .LBB0_1715
	v_cvt_pk_bf16_f32 v116, v122, v122
	s_mov_b64 s[0:1], 0x140000
	v_and_b32_e32 v116, 0xffff, v116
	v_lshl_add_u64 v[114:115], v[150:151], 0, s[0:1]
	global_store_short v[114:115], v116, off
	v_cvt_pk_bf16_f32 v116, v123, v123
	s_mov_b64 s[0:1], 0x140800
	v_and_b32_e32 v116, 0xffff, v116
	v_lshl_add_u64 v[114:115], v[150:151], 0, s[0:1]
	global_store_short v[114:115], v116, off
	v_cvt_pk_bf16_f32 v116, v124, v124
	s_mov_b64 s[0:1], 0x141000
	v_and_b32_e32 v116, 0xffff, v116
	v_lshl_add_u64 v[114:115], v[150:151], 0, s[0:1]
	global_store_short v[114:115], v116, off
	v_cvt_pk_bf16_f32 v116, v125, v125
	s_mov_b64 s[0:1], 0x141800
	v_and_b32_e32 v116, 0xffff, v116
	v_lshl_add_u64 v[114:115], v[150:151], 0, s[0:1]
	global_store_short v[114:115], v116, off
	v_cvt_pk_bf16_f32 v116, v126, v126
	s_mov_b64 s[0:1], 0x140020
	v_and_b32_e32 v116, 0xffff, v116
	v_lshl_add_u64 v[114:115], v[150:151], 0, s[0:1]
	global_store_short v[114:115], v116, off
	v_cvt_pk_bf16_f32 v116, v127, v127
	s_mov_b64 s[0:1], 0x140820
	v_and_b32_e32 v116, 0xffff, v116
	v_lshl_add_u64 v[114:115], v[150:151], 0, s[0:1]
	global_store_short v[114:115], v116, off
	v_cvt_pk_bf16_f32 v116, v128, v128
	s_mov_b64 s[0:1], 0x141020
	v_and_b32_e32 v116, 0xffff, v116
	v_lshl_add_u64 v[114:115], v[150:151], 0, s[0:1]
	global_store_short v[114:115], v116, off
	s_mov_b64 s[0:1], 0x141820
	v_cvt_pk_bf16_f32 v116, v129, v129
	v_lshl_add_u64 v[114:115], v[150:151], 0, s[0:1]
	v_and_b32_e32 v116, 0xffff, v116
	global_store_short v[114:115], v116, off
.LBB0_1715:
	s_waitcnt lgkmcnt(0)
	s_barrier
	ds_read_b128 v[114:117], v168 offset:57344
	ds_read_b128 v[118:121], v143
	ds_read_b128 v[122:125], v143 offset:4608
	ds_read_b128 v[178:181], v168 offset:57408
	ds_read_b128 v[126:129], v143 offset:64
	ds_read_b128 v[182:185], v143 offset:4672
	ds_read_b128 v[186:189], v168 offset:57472
	ds_read_b128 v[190:193], v143 offset:128
	ds_read_b128 v[206:209], v143 offset:4736
	ds_read_b128 v[210:213], v168 offset:57536
	ds_read_b128 v[214:217], v143 offset:192
	ds_read_b128 v[218:221], v143 offset:4800
	s_and_b64 vcc, exec, s[48:49]
	s_waitcnt lgkmcnt(10)
	v_mfma_f32_16x16x32_bf16 v[118:121], v[114:117], v[118:121], 0
	s_waitcnt lgkmcnt(9)
	v_mfma_f32_16x16x32_bf16 v[114:117], v[114:117], v[122:125], 0
	s_nop 0
	s_nop 0
	s_waitcnt lgkmcnt(7)
	v_mfma_f32_16x16x32_bf16 v[118:121], v[178:181], v[126:129], v[118:121]
	s_nop 0
	s_waitcnt lgkmcnt(6)
	v_mfma_f32_16x16x32_bf16 v[114:117], v[178:181], v[182:185], v[114:117]
	s_nop 0
	s_nop 0
	s_waitcnt lgkmcnt(4)
	v_mfma_f32_16x16x32_bf16 v[118:121], v[186:189], v[190:193], v[118:121]
	s_nop 0
	s_waitcnt lgkmcnt(3)
	v_mfma_f32_16x16x32_bf16 v[114:117], v[186:189], v[206:209], v[114:117]
	s_nop 0
	s_nop 0
	s_waitcnt lgkmcnt(1)
	v_mfma_f32_16x16x32_bf16 v[118:121], v[210:213], v[214:217], v[118:121]
	s_nop 0
	s_waitcnt lgkmcnt(0)
	v_mfma_f32_16x16x32_bf16 v[122:125], v[210:213], v[218:221], v[114:117]
	s_cbranch_vccnz .LBB0_1717
	s_waitcnt vmcnt(28)
	s_nop 2
	v_sub_f32_e32 v115, v29, v121
	v_sub_f32_e32 v116, v28, v120
	v_sub_f32_e32 v114, v27, v119
	v_sub_f32_e32 v117, v26, v118
	v_cvt_pk_bf16_f32 v114, v117, v114
	v_cvt_pk_bf16_f32 v115, v116, v115
	s_waitcnt vmcnt(27)
	v_sub_f32_e32 v117, v5, v125
	v_sub_f32_e32 v126, v4, v124
	v_sub_f32_e32 v116, v3, v123
	v_sub_f32_e32 v127, v2, v122
	v_cvt_pk_bf16_f32 v116, v127, v116
	v_cvt_pk_bf16_f32 v117, v126, v117
	ds_write2st64_b64 v170, v[114:115], v[116:117] offset1:5

.LBB0_1719:
	s_andn2_b64 vcc, exec, s[8:9]
	s_cbranch_vccnz .LBB0_1721
	ds_read_b128 v[126:129], v169
	ds_read_b128 v[114:117], v169 offset:64
	ds_read_b128 v[130:133], v169 offset:2560
	ds_read_b128 v[134:137], v169 offset:2624
	s_waitcnt lgkmcnt(7)
	s_nop 0
	s_waitcnt lgkmcnt(6)
	s_nop 0
	s_waitcnt lgkmcnt(5)
	s_nop 0
	s_waitcnt lgkmcnt(4)
	s_nop 0
	s_waitcnt vmcnt(28) lgkmcnt(3)
	v_mfma_f32_16x16x32_bf16 v[118:121], v[26:29], v[126:129], v[118:121]
	s_waitcnt lgkmcnt(1)
	v_mfma_f32_16x16x32_bf16 v[26:29], v[26:29], v[130:133], v[122:125]
	s_waitcnt vmcnt(27)
	v_mfma_f32_16x16x32_bf16 v[118:121], v[2:5], v[114:117], v[118:121]
	s_waitcnt lgkmcnt(0)
	v_mfma_f32_16x16x32_bf16 v[122:125], v[2:5], v[134:137], v[26:29]
.LBB0_1721:
	ds_read_b128 v[178:181], v177
	ds_read_b128 v[182:185], v177 offset:64
	s_waitcnt vmcnt(28)
	s_nop 2
	v_pk_mul_f32 v[28:29], v[138:139], v[68:69] op_sel_hi:[0,1]
	v_pk_mul_f32 v[26:27], v[138:139], v[66:67] op_sel_hi:[0,1]
	s_nop 0
	s_waitcnt vmcnt(27)
	v_pk_mul_f32 v[4:5], v[138:139], v[112:113] op_sel_hi:[0,1]
	v_pk_mul_f32 v[2:3], v[138:139], v[110:111] op_sel_hi:[0,1]
	s_or_b32 s0, s6, 0x78
	s_ashr_i32 s1, s0, 31
	s_lshl_b64 s[8:9], s[0:1], 13
	s_lshl_b64 s[34:35], s[0:1], 14
	s_waitcnt lgkmcnt(1)
	v_mfma_f32_16x16x32_bf16 v[2:5], v[178:181], v[126:129], v[2:5]
	s_add_u32 s68, s95, s34
	s_addc_u32 s69, s3, s35
	s_add_u32 s70, s29, s34
	v_mfma_f32_16x16x32_bf16 v[26:29], v[178:181], v[130:133], v[26:29]
	s_nop 0
	s_addc_u32 s71, s94, s35
	s_add_u32 s34, s2, s34
	s_waitcnt lgkmcnt(0)
	v_mfma_f32_16x16x32_bf16 v[114:117], v[182:185], v[114:117], v[2:5]
	s_addc_u32 s35, s10, s35
	s_and_b64 vcc, exec, s[46:47]
	s_nop 5
	v_cvt_pk_bf16_f32 v2, v114, v115
	v_mfma_f32_16x16x32_bf16 v[110:113], v[182:185], v[134:137], v[26:29]
	v_cvt_pk_bf16_f32 v3, v116, v117
	s_nop 6
	v_cvt_pk_bf16_f32 v4, v110, v111
	v_cvt_pk_bf16_f32 v5, v112, v113
	ds_write2st64_b64 v172, v[2:3], v[4:5] offset1:9
	s_waitcnt vmcnt(26)
	ds_write_b128 v161, v[38:41]
	s_waitcnt vmcnt(25)
	ds_write_b128 v163, v[54:57]
	s_waitcnt vmcnt(24)
	ds_write_b128 v161, v[70:73] offset:18432
	s_waitcnt vmcnt(23)
	ds_write_b128 v165, v[74:77]
	s_waitcnt vmcnt(22)
	ds_write_b128 v166, v[86:89] offset:36864
	s_waitcnt vmcnt(21)
	ds_write_b128 v167, v[102:105] offset:36864
	v_lshl_add_u64 v[2:3], s[68:69], 0, v[146:147]
	global_load_dwordx4 v[38:41], v[2:3], off
	v_lshl_add_u64 v[2:3], s[68:69], 0, v[148:149]
	global_load_dwordx4 v[54:57], v[2:3], off
	v_lshl_add_u64 v[2:3], s[70:71], 0, v[146:147]
	global_load_dwordx4 v[66:69], v[2:3], off
	v_lshl_add_u64 v[2:3], s[70:71], 0, v[148:149]
	global_load_dwordx4 v[70:73], v[2:3], off
	v_lshl_add_u64 v[2:3], s[34:35], 0, v[146:147]
	global_load_dwordx4 v[86:89], v[2:3], off
	v_lshl_add_u64 v[2:3], s[34:35], 0, v[148:149]
	s_lshl_b64 s[34:35], s[0:1], 15
	s_lshl_b64 s[0:1], s[0:1], 8
	v_lshl_add_u64 v[74:75], v[152:153], 0, s[0:1]
	global_load_dwordx4 v[102:105], v[2:3], off
	global_load_dword v138, v[74:75], off
	v_lshl_add_u64 v[2:3], v[156:157], 0, s[34:35]
	v_lshl_add_u64 v[4:5], v[154:155], 0, s[8:9]
	v_cndmask_b32_e64 v3, v5, v3, s[44:45]
	v_cndmask_b32_e64 v2, v4, v2, s[44:45]
	global_load_dwordx4 v[26:29], v[2:3], off
	v_lshl_add_u64 v[2:3], v[2:3], 0, s[60:61]
	global_load_dwordx4 v[2:5], v[2:3], off
	s_cbranch_vccnz .LBB0_1723
	v_cvt_pk_bf16_f32 v76, v118, v118
	s_mov_b64 s[0:1], 0x160000
	v_and_b32_e32 v76, 0xffff, v76
	v_lshl_add_u64 v[74:75], v[150:151], 0, s[0:1]
	global_store_short v[74:75], v76, off
	v_cvt_pk_bf16_f32 v76, v119, v119
	s_mov_b64 s[0:1], 0x160800
	v_and_b32_e32 v76, 0xffff, v76
	v_lshl_add_u64 v[74:75], v[150:151], 0, s[0:1]
	global_store_short v[74:75], v76, off
	v_cvt_pk_bf16_f32 v76, v120, v120
	s_mov_b64 s[0:1], 0x161000
	v_and_b32_e32 v76, 0xffff, v76
	v_lshl_add_u64 v[74:75], v[150:151], 0, s[0:1]
	global_store_short v[74:75], v76, off
	v_cvt_pk_bf16_f32 v76, v121, v121
	s_mov_b64 s[0:1], 0x161800
	v_and_b32_e32 v76, 0xffff, v76
	v_lshl_add_u64 v[74:75], v[150:151], 0, s[0:1]
	global_store_short v[74:75], v76, off
	v_cvt_pk_bf16_f32 v76, v122, v122
	s_mov_b64 s[0:1], 0x160020
	v_and_b32_e32 v76, 0xffff, v76
	v_lshl_add_u64 v[74:75], v[150:151], 0, s[0:1]
	global_store_short v[74:75], v76, off
	v_cvt_pk_bf16_f32 v76, v123, v123
	s_mov_b64 s[0:1], 0x160820
	v_and_b32_e32 v76, 0xffff, v76
	v_lshl_add_u64 v[74:75], v[150:151], 0, s[0:1]
	global_store_short v[74:75], v76, off
	v_cvt_pk_bf16_f32 v76, v124, v124
	s_mov_b64 s[0:1], 0x161020
	v_and_b32_e32 v76, 0xffff, v76
	v_lshl_add_u64 v[74:75], v[150:151], 0, s[0:1]
	global_store_short v[74:75], v76, off
	s_mov_b64 s[0:1], 0x161820
	v_cvt_pk_bf16_f32 v76, v125, v125
	v_lshl_add_u64 v[74:75], v[150:151], 0, s[0:1]
	v_and_b32_e32 v76, 0xffff, v76
	global_store_short v[74:75], v76, off
.LBB0_1723:
	s_waitcnt lgkmcnt(0)
	s_barrier
	ds_read_b128 v[74:77], v168
	ds_read_b128 v[118:121], v143
	ds_read_b128 v[122:125], v143 offset:4608
	ds_read_b128 v[178:181], v168 offset:64
	ds_read_b128 v[126:129], v143 offset:64
	ds_read_b128 v[182:185], v143 offset:4672
	ds_read_b128 v[186:189], v168 offset:128
	ds_read_b128 v[190:193], v143 offset:128
	ds_read_b128 v[206:209], v143 offset:4736
	ds_read_b128 v[210:213], v168 offset:192
	ds_read_b128 v[214:217], v143 offset:192
	ds_read_b128 v[218:221], v143 offset:4800
	s_and_b64 vcc, exec, s[48:49]
	s_waitcnt lgkmcnt(10)
	v_mfma_f32_16x16x32_bf16 v[118:121], v[74:77], v[118:121], 0
	s_waitcnt lgkmcnt(9)
	v_mfma_f32_16x16x32_bf16 v[74:77], v[74:77], v[122:125], 0
	s_nop 0
	s_nop 0
	s_waitcnt lgkmcnt(7)
	v_mfma_f32_16x16x32_bf16 v[118:121], v[178:181], v[126:129], v[118:121]
	s_nop 0
	s_waitcnt lgkmcnt(6)
	v_mfma_f32_16x16x32_bf16 v[74:77], v[178:181], v[182:185], v[74:77]
	s_nop 0
	s_nop 0
	s_waitcnt lgkmcnt(4)
	v_mfma_f32_16x16x32_bf16 v[118:121], v[186:189], v[190:193], v[118:121]
	s_nop 0
	s_waitcnt lgkmcnt(3)
	v_mfma_f32_16x16x32_bf16 v[74:77], v[186:189], v[206:209], v[74:77]
	s_nop 0
	s_nop 0
	s_waitcnt lgkmcnt(1)
	v_mfma_f32_16x16x32_bf16 v[118:121], v[210:213], v[214:217], v[118:121]
	s_nop 0
	s_waitcnt lgkmcnt(0)
	v_mfma_f32_16x16x32_bf16 v[122:125], v[210:213], v[218:221], v[74:77]
	s_cbranch_vccnz .LBB0_1725
	s_waitcnt vmcnt(28)
	s_nop 2
	v_sub_f32_e32 v75, v33, v121
	v_sub_f32_e32 v76, v32, v120
	v_sub_f32_e32 v74, v31, v119
	v_sub_f32_e32 v77, v30, v118
	v_cvt_pk_bf16_f32 v74, v77, v74
	v_cvt_pk_bf16_f32 v75, v76, v75
	s_waitcnt vmcnt(27)
	v_sub_f32_e32 v77, v9, v125
	v_sub_f32_e32 v126, v8, v124
	v_sub_f32_e32 v76, v7, v123
	v_sub_f32_e32 v127, v6, v122
	v_cvt_pk_bf16_f32 v76, v127, v76
	v_cvt_pk_bf16_f32 v77, v126, v77
	ds_write2st64_b64 v170, v[74:75], v[76:77] offset1:5

.LBB0_1727:
	s_andn2_b64 vcc, exec, s[8:9]
	s_cbranch_vccnz .LBB0_1729
	ds_read_b128 v[126:129], v169
	ds_read_b128 v[74:77], v169 offset:64
	ds_read_b128 v[130:133], v169 offset:2560
	ds_read_b128 v[134:137], v169 offset:2624
	s_waitcnt lgkmcnt(7)
	s_nop 0
	s_waitcnt lgkmcnt(6)
	s_nop 0
	s_waitcnt lgkmcnt(5)
	s_nop 0
	s_waitcnt lgkmcnt(4)
	s_nop 0
	s_waitcnt vmcnt(28) lgkmcnt(3)
	v_mfma_f32_16x16x32_bf16 v[118:121], v[30:33], v[126:129], v[118:121]
	s_waitcnt lgkmcnt(1)
	v_mfma_f32_16x16x32_bf16 v[30:33], v[30:33], v[130:133], v[122:125]
	s_waitcnt vmcnt(27)
	v_mfma_f32_16x16x32_bf16 v[118:121], v[6:9], v[74:77], v[118:121]
	s_waitcnt lgkmcnt(0)
	v_mfma_f32_16x16x32_bf16 v[122:125], v[6:9], v[134:137], v[30:33]
.LBB0_1729:
	ds_read_b128 v[178:181], v173 offset:36864
	ds_read_b128 v[182:185], v173 offset:36928
	s_waitcnt vmcnt(28)
	s_nop 2
	v_pk_mul_f32 v[32:33], v[140:141], v[112:113] op_sel_hi:[0,1]
	v_pk_mul_f32 v[30:31], v[140:141], v[110:111] op_sel_hi:[0,1]
	s_nop 0
	s_waitcnt vmcnt(27)
	v_pk_mul_f32 v[8:9], v[140:141], v[116:117] op_sel_hi:[0,1]
	v_pk_mul_f32 v[6:7], v[140:141], v[114:115] op_sel_hi:[0,1]
	s_or_b32 s0, s6, 0x80
	s_ashr_i32 s1, s0, 31
	s_lshl_b64 s[8:9], s[0:1], 13
	s_lshl_b64 s[34:35], s[0:1], 14
	s_waitcnt lgkmcnt(1)
	v_mfma_f32_16x16x32_bf16 v[6:9], v[178:181], v[126:129], v[6:9]
	s_add_u32 s68, s95, s34
	s_addc_u32 s69, s3, s35
	s_add_u32 s70, s29, s34
	v_mfma_f32_16x16x32_bf16 v[30:33], v[178:181], v[130:133], v[30:33]
	s_nop 0
	s_addc_u32 s71, s94, s35
	s_add_u32 s34, s2, s34
	s_waitcnt lgkmcnt(0)
	v_mfma_f32_16x16x32_bf16 v[114:117], v[182:185], v[74:77], v[6:9]
	s_addc_u32 s35, s10, s35
	s_and_b64 vcc, exec, s[46:47]
	s_nop 5
	v_cvt_pk_bf16_f32 v6, v114, v115
	v_mfma_f32_16x16x32_bf16 v[110:113], v[182:185], v[134:137], v[30:33]
	v_cvt_pk_bf16_f32 v7, v116, v117
	s_nop 6
	v_cvt_pk_bf16_f32 v8, v110, v111
	v_cvt_pk_bf16_f32 v9, v112, v113
	ds_write2st64_b64 v172, v[6:7], v[8:9] offset1:9
	s_waitcnt vmcnt(26)
	ds_write_b128 v161, v[42:45] offset:57344
	s_waitcnt vmcnt(25)
	ds_write_b128 v163, v[46:49] offset:57344
	s_waitcnt vmcnt(24)
	ds_write_b128 v174, v[58:61] offset:57344
	s_waitcnt vmcnt(23)
	ds_write_b128 v165, v[78:81] offset:57344
	s_waitcnt vmcnt(22)
	ds_write_b128 v175, v[94:97]
	s_waitcnt vmcnt(21)
	ds_write_b128 v176, v[98:101]
	v_lshl_add_u64 v[6:7], s[68:69], 0, v[146:147]
	global_load_dwordx4 v[42:45], v[6:7], off
	v_lshl_add_u64 v[6:7], s[68:69], 0, v[148:149]
	global_load_dwordx4 v[46:49], v[6:7], off
	v_lshl_add_u64 v[6:7], s[70:71], 0, v[146:147]
	global_load_dwordx4 v[58:61], v[6:7], off
	v_lshl_add_u64 v[6:7], s[70:71], 0, v[148:149]
	global_load_dwordx4 v[74:77], v[6:7], off
	v_lshl_add_u64 v[6:7], s[34:35], 0, v[146:147]
	global_load_dwordx4 v[94:97], v[6:7], off
	v_lshl_add_u64 v[6:7], s[34:35], 0, v[148:149]
	s_lshl_b64 s[34:35], s[0:1], 15
	s_lshl_b64 s[0:1], s[0:1], 8
	v_lshl_add_u64 v[78:79], v[152:153], 0, s[0:1]
	global_load_dwordx4 v[98:101], v[6:7], off
	global_load_dword v140, v[78:79], off
	v_lshl_add_u64 v[6:7], v[156:157], 0, s[34:35]
	v_lshl_add_u64 v[8:9], v[154:155], 0, s[8:9]
	v_cndmask_b32_e64 v7, v9, v7, s[44:45]
	v_cndmask_b32_e64 v6, v8, v6, s[44:45]
	global_load_dwordx4 v[30:33], v[6:7], off
	v_lshl_add_u64 v[6:7], v[6:7], 0, s[60:61]
	global_load_dwordx4 v[6:9], v[6:7], off
	s_cbranch_vccnz .LBB0_1731
	v_cvt_pk_bf16_f32 v80, v118, v118
	s_mov_b64 s[0:1], 0x180000
	v_and_b32_e32 v80, 0xffff, v80
	v_lshl_add_u64 v[78:79], v[150:151], 0, s[0:1]
	global_store_short v[78:79], v80, off
	v_cvt_pk_bf16_f32 v80, v119, v119
	s_mov_b64 s[0:1], 0x180800
	v_and_b32_e32 v80, 0xffff, v80
	v_lshl_add_u64 v[78:79], v[150:151], 0, s[0:1]
	global_store_short v[78:79], v80, off
	v_cvt_pk_bf16_f32 v80, v120, v120
	s_mov_b64 s[0:1], 0x181000
	v_and_b32_e32 v80, 0xffff, v80
	v_lshl_add_u64 v[78:79], v[150:151], 0, s[0:1]
	global_store_short v[78:79], v80, off
	v_cvt_pk_bf16_f32 v80, v121, v121
	s_mov_b64 s[0:1], 0x181800
	v_and_b32_e32 v80, 0xffff, v80
	v_lshl_add_u64 v[78:79], v[150:151], 0, s[0:1]
	global_store_short v[78:79], v80, off
	v_cvt_pk_bf16_f32 v80, v122, v122
	s_mov_b64 s[0:1], 0x180020
	v_and_b32_e32 v80, 0xffff, v80
	v_lshl_add_u64 v[78:79], v[150:151], 0, s[0:1]
	global_store_short v[78:79], v80, off
	v_cvt_pk_bf16_f32 v80, v123, v123
	s_mov_b64 s[0:1], 0x180820
	v_and_b32_e32 v80, 0xffff, v80
	v_lshl_add_u64 v[78:79], v[150:151], 0, s[0:1]
	global_store_short v[78:79], v80, off
	v_cvt_pk_bf16_f32 v80, v124, v124
	s_mov_b64 s[0:1], 0x181020
	v_and_b32_e32 v80, 0xffff, v80
	v_lshl_add_u64 v[78:79], v[150:151], 0, s[0:1]
	global_store_short v[78:79], v80, off
	s_mov_b64 s[0:1], 0x181820
	v_cvt_pk_bf16_f32 v80, v125, v125
	v_lshl_add_u64 v[78:79], v[150:151], 0, s[0:1]
	v_and_b32_e32 v80, 0xffff, v80
	global_store_short v[78:79], v80, off
.LBB0_1731:
	s_waitcnt lgkmcnt(0)
	s_barrier
	ds_read_b128 v[78:81], v168 offset:57344
	ds_read_b128 v[118:121], v143
	ds_read_b128 v[122:125], v143 offset:4608
	ds_read_b128 v[178:181], v168 offset:57408
	ds_read_b128 v[126:129], v143 offset:64
	ds_read_b128 v[182:185], v143 offset:4672
	ds_read_b128 v[186:189], v168 offset:57472
	ds_read_b128 v[190:193], v143 offset:128
	ds_read_b128 v[206:209], v143 offset:4736
	ds_read_b128 v[210:213], v168 offset:57536
	ds_read_b128 v[214:217], v143 offset:192
	ds_read_b128 v[218:221], v143 offset:4800
	s_and_b64 vcc, exec, s[48:49]
	s_waitcnt lgkmcnt(10)
	v_mfma_f32_16x16x32_bf16 v[118:121], v[78:81], v[118:121], 0
	s_waitcnt lgkmcnt(9)
	v_mfma_f32_16x16x32_bf16 v[78:81], v[78:81], v[122:125], 0
	s_nop 0
	s_nop 0
	s_waitcnt lgkmcnt(7)
	v_mfma_f32_16x16x32_bf16 v[118:121], v[178:181], v[126:129], v[118:121]
	s_nop 0
	s_waitcnt lgkmcnt(6)
	v_mfma_f32_16x16x32_bf16 v[78:81], v[178:181], v[182:185], v[78:81]
	s_nop 0
	s_nop 0
	s_waitcnt lgkmcnt(4)
	v_mfma_f32_16x16x32_bf16 v[118:121], v[186:189], v[190:193], v[118:121]
	s_nop 0
	s_waitcnt lgkmcnt(3)
	v_mfma_f32_16x16x32_bf16 v[78:81], v[186:189], v[206:209], v[78:81]
	s_nop 0
	s_nop 0
	s_waitcnt lgkmcnt(1)
	v_mfma_f32_16x16x32_bf16 v[118:121], v[210:213], v[214:217], v[118:121]
	s_nop 0
	s_waitcnt lgkmcnt(0)
	v_mfma_f32_16x16x32_bf16 v[122:125], v[210:213], v[218:221], v[78:81]
	s_cbranch_vccnz .LBB0_1733
	s_waitcnt vmcnt(28)
	s_nop 2
	v_sub_f32_e32 v79, v21, v121
	v_sub_f32_e32 v80, v20, v120
	v_sub_f32_e32 v78, v19, v119
	v_sub_f32_e32 v81, v18, v118
	v_cvt_pk_bf16_f32 v78, v81, v78
	v_cvt_pk_bf16_f32 v79, v80, v79
	s_waitcnt vmcnt(27)
	v_sub_f32_e32 v81, v13, v125
	v_sub_f32_e32 v126, v12, v124
	v_sub_f32_e32 v80, v11, v123
	v_sub_f32_e32 v127, v10, v122
	v_cvt_pk_bf16_f32 v80, v127, v80
	v_cvt_pk_bf16_f32 v81, v126, v81
	ds_write2st64_b64 v170, v[78:79], v[80:81] offset1:5

.LBB0_1735:
	s_andn2_b64 vcc, exec, s[8:9]
	s_cbranch_vccnz .LBB0_1737
	ds_read_b128 v[126:129], v169
	ds_read_b128 v[78:81], v169 offset:64
	ds_read_b128 v[130:133], v169 offset:2560
	ds_read_b128 v[134:137], v169 offset:2624
	s_waitcnt lgkmcnt(7)
	s_nop 0
	s_waitcnt lgkmcnt(6)
	s_nop 0
	s_waitcnt lgkmcnt(5)
	s_nop 0
	s_waitcnt lgkmcnt(4)
	s_nop 0
	s_waitcnt vmcnt(28) lgkmcnt(3)
	v_mfma_f32_16x16x32_bf16 v[118:121], v[18:21], v[126:129], v[118:121]
	s_waitcnt lgkmcnt(1)
	v_mfma_f32_16x16x32_bf16 v[18:21], v[18:21], v[130:133], v[122:125]
	s_waitcnt vmcnt(27)
	v_mfma_f32_16x16x32_bf16 v[118:121], v[10:13], v[78:81], v[118:121]
	s_waitcnt lgkmcnt(0)
	v_mfma_f32_16x16x32_bf16 v[122:125], v[10:13], v[134:137], v[18:21]
.LBB0_1737:
	ds_read_b128 v[178:181], v177
	ds_read_b128 v[182:185], v177 offset:64
	s_waitcnt vmcnt(28)
	s_nop 2
	v_pk_mul_f32 v[20:21], v[158:159], v[112:113] op_sel_hi:[0,1]
	v_pk_mul_f32 v[18:19], v[158:159], v[110:111] op_sel_hi:[0,1]
	s_nop 0
	s_waitcnt vmcnt(27)
	v_pk_mul_f32 v[12:13], v[158:159], v[116:117] op_sel_hi:[0,1]
	v_pk_mul_f32 v[10:11], v[158:159], v[114:115] op_sel_hi:[0,1]
	s_or_b32 s0, s6, 0x88
	s_ashr_i32 s1, s0, 31
	s_lshl_b64 s[8:9], s[0:1], 13
	s_lshl_b64 s[34:35], s[0:1], 14
	s_waitcnt lgkmcnt(1)
	v_mfma_f32_16x16x32_bf16 v[10:13], v[178:181], v[126:129], v[10:13]
	s_add_u32 s68, s95, s34
	s_addc_u32 s69, s3, s35
	s_add_u32 s70, s29, s34
	v_mfma_f32_16x16x32_bf16 v[18:21], v[178:181], v[130:133], v[18:21]
	s_nop 0
	s_addc_u32 s71, s94, s35
	s_add_u32 s34, s2, s34
	s_waitcnt lgkmcnt(0)
	v_mfma_f32_16x16x32_bf16 v[114:117], v[182:185], v[78:81], v[10:13]
	s_addc_u32 s35, s10, s35
	s_and_b64 vcc, exec, s[46:47]
	s_nop 5
	v_cvt_pk_bf16_f32 v10, v114, v115
	v_mfma_f32_16x16x32_bf16 v[110:113], v[182:185], v[134:137], v[18:21]
	v_cvt_pk_bf16_f32 v11, v116, v117
	s_nop 6
	v_cvt_pk_bf16_f32 v12, v110, v111
	v_cvt_pk_bf16_f32 v13, v112, v113
	ds_write2st64_b64 v172, v[10:11], v[12:13] offset1:9
	s_waitcnt vmcnt(26)
	ds_write_b128 v161, v[34:37]
	s_waitcnt vmcnt(25)
	ds_write_b128 v163, v[50:53]
	s_waitcnt vmcnt(24)
	ds_write_b128 v161, v[62:65] offset:18432
	s_waitcnt vmcnt(23)
	ds_write_b128 v165, v[82:85]
	s_waitcnt vmcnt(22)
	ds_write_b128 v166, v[90:93] offset:36864
	s_waitcnt vmcnt(21)
	ds_write_b128 v167, v[106:109] offset:36864
	v_lshl_add_u64 v[10:11], s[68:69], 0, v[146:147]
	global_load_dwordx4 v[34:37], v[10:11], off
	v_lshl_add_u64 v[10:11], s[68:69], 0, v[148:149]
	global_load_dwordx4 v[50:53], v[10:11], off
	v_lshl_add_u64 v[10:11], s[70:71], 0, v[146:147]
	global_load_dwordx4 v[62:65], v[10:11], off
	v_lshl_add_u64 v[10:11], s[70:71], 0, v[148:149]
	global_load_dwordx4 v[78:81], v[10:11], off
	v_lshl_add_u64 v[10:11], s[34:35], 0, v[146:147]
	global_load_dwordx4 v[82:85], v[10:11], off
	v_lshl_add_u64 v[10:11], s[34:35], 0, v[148:149]
	s_lshl_b64 s[34:35], s[0:1], 15
	s_lshl_b64 s[0:1], s[0:1], 8
	v_lshl_add_u64 v[90:91], v[152:153], 0, s[0:1]
	global_load_dwordx4 v[106:109], v[10:11], off
	global_load_dword v158, v[90:91], off
	v_lshl_add_u64 v[10:11], v[156:157], 0, s[34:35]
	v_lshl_add_u64 v[12:13], v[154:155], 0, s[8:9]
	v_cndmask_b32_e64 v11, v13, v11, s[44:45]
	v_cndmask_b32_e64 v10, v12, v10, s[44:45]
	global_load_dwordx4 v[18:21], v[10:11], off
	v_lshl_add_u64 v[10:11], v[10:11], 0, s[60:61]
	global_load_dwordx4 v[10:13], v[10:11], off
	s_cbranch_vccnz .LBB0_1739
	v_cvt_pk_bf16_f32 v92, v118, v118
	s_mov_b64 s[0:1], 0x1a0000
	v_and_b32_e32 v92, 0xffff, v92
	v_lshl_add_u64 v[90:91], v[150:151], 0, s[0:1]
	global_store_short v[90:91], v92, off
	v_cvt_pk_bf16_f32 v92, v119, v119
	s_mov_b64 s[0:1], 0x1a0800
	v_and_b32_e32 v92, 0xffff, v92
	v_lshl_add_u64 v[90:91], v[150:151], 0, s[0:1]
	global_store_short v[90:91], v92, off
	v_cvt_pk_bf16_f32 v92, v120, v120
	s_mov_b64 s[0:1], 0x1a1000
	v_and_b32_e32 v92, 0xffff, v92
	v_lshl_add_u64 v[90:91], v[150:151], 0, s[0:1]
	global_store_short v[90:91], v92, off
	v_cvt_pk_bf16_f32 v92, v121, v121
	s_mov_b64 s[0:1], 0x1a1800
	v_and_b32_e32 v92, 0xffff, v92
	v_lshl_add_u64 v[90:91], v[150:151], 0, s[0:1]
	global_store_short v[90:91], v92, off
	v_cvt_pk_bf16_f32 v92, v122, v122
	s_mov_b64 s[0:1], 0x1a0020
	v_and_b32_e32 v92, 0xffff, v92
	v_lshl_add_u64 v[90:91], v[150:151], 0, s[0:1]
	global_store_short v[90:91], v92, off
	v_cvt_pk_bf16_f32 v92, v123, v123
	s_mov_b64 s[0:1], 0x1a0820
	v_and_b32_e32 v92, 0xffff, v92
	v_lshl_add_u64 v[90:91], v[150:151], 0, s[0:1]
	global_store_short v[90:91], v92, off
	v_cvt_pk_bf16_f32 v92, v124, v124
	s_mov_b64 s[0:1], 0x1a1020
	v_and_b32_e32 v92, 0xffff, v92
	v_lshl_add_u64 v[90:91], v[150:151], 0, s[0:1]
	global_store_short v[90:91], v92, off
	s_mov_b64 s[0:1], 0x1a1820
	v_cvt_pk_bf16_f32 v92, v125, v125
	v_lshl_add_u64 v[90:91], v[150:151], 0, s[0:1]
	v_and_b32_e32 v92, 0xffff, v92
	global_store_short v[90:91], v92, off
.LBB0_1739:
	s_waitcnt lgkmcnt(0)
	s_barrier
	ds_read_b128 v[90:93], v168
	ds_read_b128 v[118:121], v143
	ds_read_b128 v[122:125], v143 offset:4608
	ds_read_b128 v[178:181], v168 offset:64
	ds_read_b128 v[126:129], v143 offset:64
	ds_read_b128 v[182:185], v143 offset:4672
	ds_read_b128 v[186:189], v168 offset:128
	ds_read_b128 v[190:193], v143 offset:128
	ds_read_b128 v[206:209], v143 offset:4736
	ds_read_b128 v[210:213], v168 offset:192
	ds_read_b128 v[214:217], v143 offset:192
	ds_read_b128 v[218:221], v143 offset:4800
	s_and_b64 vcc, exec, s[48:49]
	s_waitcnt lgkmcnt(10)
	v_mfma_f32_16x16x32_bf16 v[118:121], v[90:93], v[118:121], 0
	s_waitcnt lgkmcnt(9)
	v_mfma_f32_16x16x32_bf16 v[90:93], v[90:93], v[122:125], 0
	s_nop 0
	s_nop 0
	s_waitcnt lgkmcnt(7)
	v_mfma_f32_16x16x32_bf16 v[118:121], v[178:181], v[126:129], v[118:121]
	s_nop 0
	s_waitcnt lgkmcnt(6)
	v_mfma_f32_16x16x32_bf16 v[90:93], v[178:181], v[182:185], v[90:93]
	s_nop 0
	s_nop 0
	s_waitcnt lgkmcnt(4)
	v_mfma_f32_16x16x32_bf16 v[118:121], v[186:189], v[190:193], v[118:121]
	s_nop 0
	s_waitcnt lgkmcnt(3)
	v_mfma_f32_16x16x32_bf16 v[90:93], v[186:189], v[206:209], v[90:93]
	s_nop 0
	s_nop 0
	s_waitcnt lgkmcnt(1)
	v_mfma_f32_16x16x32_bf16 v[118:121], v[210:213], v[214:217], v[118:121]
	s_nop 0
	s_waitcnt lgkmcnt(0)
	v_mfma_f32_16x16x32_bf16 v[122:125], v[210:213], v[218:221], v[90:93]
	s_cbranch_vccnz .LBB0_1741
	s_waitcnt vmcnt(28)
	s_nop 2
	v_sub_f32_e32 v91, v25, v121
	v_sub_f32_e32 v92, v24, v120
	v_sub_f32_e32 v90, v23, v119
	v_sub_f32_e32 v93, v22, v118
	v_cvt_pk_bf16_f32 v90, v93, v90
	v_cvt_pk_bf16_f32 v91, v92, v91
	s_waitcnt vmcnt(27)
	v_sub_f32_e32 v93, v17, v125
	v_sub_f32_e32 v126, v16, v124
	v_sub_f32_e32 v92, v15, v123
	v_sub_f32_e32 v127, v14, v122
	v_cvt_pk_bf16_f32 v92, v127, v92
	v_cvt_pk_bf16_f32 v93, v126, v93
	ds_write2st64_b64 v170, v[90:91], v[92:93] offset1:5

.LBB0_1743:
	s_andn2_b64 vcc, exec, s[8:9]
	s_cbranch_vccnz .LBB0_1745
	ds_read_b128 v[126:129], v169
	ds_read_b128 v[90:93], v169 offset:64
	ds_read_b128 v[130:133], v169 offset:2560
	ds_read_b128 v[134:137], v169 offset:2624
	s_waitcnt lgkmcnt(7)
	s_nop 0
	s_waitcnt lgkmcnt(6)
	s_nop 0
	s_waitcnt lgkmcnt(5)
	s_nop 0
	s_waitcnt lgkmcnt(4)
	s_nop 0
	s_waitcnt vmcnt(28) lgkmcnt(3)
	v_mfma_f32_16x16x32_bf16 v[118:121], v[22:25], v[126:129], v[118:121]
	s_waitcnt lgkmcnt(1)
	v_mfma_f32_16x16x32_bf16 v[22:25], v[22:25], v[130:133], v[122:125]
	s_waitcnt vmcnt(27)
	v_mfma_f32_16x16x32_bf16 v[118:121], v[14:17], v[90:93], v[118:121]
	s_waitcnt lgkmcnt(0)
	v_mfma_f32_16x16x32_bf16 v[122:125], v[14:17], v[134:137], v[22:25]
.LBB0_1745:
	ds_read_b128 v[178:181], v173 offset:36864
	ds_read_b128 v[182:185], v173 offset:36928
	s_waitcnt vmcnt(28)
	s_nop 2
	v_pk_mul_f32 v[24:25], v[160:161], v[112:113] op_sel_hi:[0,1]
	v_pk_mul_f32 v[22:23], v[160:161], v[110:111] op_sel_hi:[0,1]
	s_nop 0
	s_waitcnt vmcnt(27)
	v_pk_mul_f32 v[16:17], v[160:161], v[116:117] op_sel_hi:[0,1]
	v_pk_mul_f32 v[14:15], v[160:161], v[114:115] op_sel_hi:[0,1]
	s_nop 0
	s_or_b32 s0, s6, 0x90
	s_ashr_i32 s1, s0, 31
	s_lshl_b64 s[8:9], s[0:1], 13
	s_waitcnt lgkmcnt(1)
	v_mfma_f32_16x16x32_bf16 v[14:17], v[178:181], v[126:129], v[14:17]
	s_lshl_b64 s[34:35], s[0:1], 14
	s_add_u32 s68, s95, s34
	s_addc_u32 s69, s3, s35
	v_mfma_f32_16x16x32_bf16 v[22:25], v[178:181], v[130:133], v[22:25]
	s_add_u32 s70, s29, s34
	s_addc_u32 s71, s94, s35
	s_add_u32 s34, s2, s34
	s_waitcnt lgkmcnt(0)
	v_mfma_f32_16x16x32_bf16 v[110:113], v[182:185], v[90:93], v[14:17]
	s_addc_u32 s35, s10, s35
	s_and_b64 vcc, exec, s[46:47]
	v_mfma_f32_16x16x32_bf16 v[90:93], v[182:185], v[134:137], v[22:25]
	s_nop 4
	v_cvt_pk_bf16_f32 v14, v110, v111
	v_cvt_pk_bf16_f32 v15, v112, v113
	s_nop 0
	v_cvt_pk_bf16_f32 v16, v90, v91
	v_cvt_pk_bf16_f32 v17, v92, v93
	ds_write2st64_b64 v172, v[14:15], v[16:17] offset1:9
	s_waitcnt vmcnt(26)
	ds_write_b128 v161, v[38:41] offset:57344
	s_waitcnt vmcnt(25)
	ds_write_b128 v163, v[54:57] offset:57344
	s_waitcnt vmcnt(24)
	ds_write_b128 v174, v[66:69] offset:57344
	s_waitcnt vmcnt(23)
	ds_write_b128 v165, v[70:73] offset:57344
	s_waitcnt vmcnt(22)
	ds_write_b128 v175, v[86:89]
	s_waitcnt vmcnt(21)
	ds_write_b128 v176, v[102:105]
	v_lshl_add_u64 v[14:15], s[68:69], 0, v[146:147]
	global_load_dwordx4 v[38:41], v[14:15], off
	v_lshl_add_u64 v[14:15], s[68:69], 0, v[148:149]
	global_load_dwordx4 v[54:57], v[14:15], off
	v_lshl_add_u64 v[14:15], s[70:71], 0, v[146:147]
	global_load_dwordx4 v[66:69], v[14:15], off
	v_lshl_add_u64 v[14:15], s[70:71], 0, v[148:149]
	global_load_dwordx4 v[70:73], v[14:15], off
	v_lshl_add_u64 v[14:15], s[34:35], 0, v[146:147]
	global_load_dwordx4 v[86:89], v[14:15], off
	v_lshl_add_u64 v[14:15], s[34:35], 0, v[148:149]
	s_lshl_b64 s[34:35], s[0:1], 15
	s_lshl_b64 s[0:1], s[0:1], 8
	v_lshl_add_u64 v[114:115], v[152:153], 0, s[0:1]
	global_load_dwordx4 v[102:105], v[14:15], off
	global_load_dword v160, v[114:115], off
	v_lshl_add_u64 v[14:15], v[156:157], 0, s[34:35]
	v_lshl_add_u64 v[16:17], v[154:155], 0, s[8:9]
	v_cndmask_b32_e64 v15, v17, v15, s[44:45]
	v_cndmask_b32_e64 v14, v16, v14, s[44:45]
	global_load_dwordx4 v[22:25], v[14:15], off
	v_lshl_add_u64 v[14:15], v[14:15], 0, s[60:61]
	global_load_dwordx4 v[14:17], v[14:15], off
	s_cbranch_vccnz .LBB0_1747
	v_cvt_pk_bf16_f32 v116, v118, v118
	s_mov_b64 s[0:1], 0x1c0000
	v_and_b32_e32 v116, 0xffff, v116
	v_lshl_add_u64 v[114:115], v[150:151], 0, s[0:1]
	global_store_short v[114:115], v116, off
	v_cvt_pk_bf16_f32 v116, v119, v119
	s_mov_b64 s[0:1], 0x1c0800
	v_and_b32_e32 v116, 0xffff, v116
	v_lshl_add_u64 v[114:115], v[150:151], 0, s[0:1]
	global_store_short v[114:115], v116, off
	v_cvt_pk_bf16_f32 v116, v120, v120
	s_mov_b64 s[0:1], 0x1c1000
	v_and_b32_e32 v116, 0xffff, v116
	v_lshl_add_u64 v[114:115], v[150:151], 0, s[0:1]
	global_store_short v[114:115], v116, off
	v_cvt_pk_bf16_f32 v116, v121, v121
	s_mov_b64 s[0:1], 0x1c1800
	v_and_b32_e32 v116, 0xffff, v116
	v_lshl_add_u64 v[114:115], v[150:151], 0, s[0:1]
	global_store_short v[114:115], v116, off
	v_cvt_pk_bf16_f32 v116, v122, v122
	s_mov_b64 s[0:1], 0x1c0020
	v_and_b32_e32 v116, 0xffff, v116
	v_lshl_add_u64 v[114:115], v[150:151], 0, s[0:1]
	global_store_short v[114:115], v116, off
	v_cvt_pk_bf16_f32 v116, v123, v123
	s_mov_b64 s[0:1], 0x1c0820
	v_and_b32_e32 v116, 0xffff, v116
	v_lshl_add_u64 v[114:115], v[150:151], 0, s[0:1]
	global_store_short v[114:115], v116, off
	v_cvt_pk_bf16_f32 v116, v124, v124
	s_mov_b64 s[0:1], 0x1c1020
	v_and_b32_e32 v116, 0xffff, v116
	v_lshl_add_u64 v[114:115], v[150:151], 0, s[0:1]
	global_store_short v[114:115], v116, off
	s_mov_b64 s[0:1], 0x1c1820
	v_cvt_pk_bf16_f32 v116, v125, v125
	v_lshl_add_u64 v[114:115], v[150:151], 0, s[0:1]
	v_and_b32_e32 v116, 0xffff, v116
	global_store_short v[114:115], v116, off

.LBB0_1753:
	ds_read_b128 v[178:181], v177
	ds_read_b128 v[182:185], v177 offset:64
	s_waitcnt vmcnt(28)
	s_nop 2
	v_pk_mul_f32 v[28:29], v[138:139], v[92:93] op_sel_hi:[0,1]
	v_pk_mul_f32 v[26:27], v[138:139], v[90:91] op_sel_hi:[0,1]
	s_nop 0
	s_waitcnt vmcnt(27)
	v_pk_mul_f32 v[4:5], v[138:139], v[112:113] op_sel_hi:[0,1]
	v_pk_mul_f32 v[2:3], v[138:139], v[110:111] op_sel_hi:[0,1]
	s_or_b32 s0, s6, 0x98
	s_ashr_i32 s1, s0, 31
	s_lshl_b64 s[8:9], s[0:1], 13
	s_lshl_b64 s[34:35], s[0:1], 14
	s_waitcnt lgkmcnt(1)
	v_mfma_f32_16x16x32_bf16 v[2:5], v[178:181], v[126:129], v[2:5]
	s_add_u32 s68, s95, s34
	s_addc_u32 s69, s3, s35
	s_add_u32 s70, s29, s34
	v_mfma_f32_16x16x32_bf16 v[26:29], v[178:181], v[130:133], v[26:29]
	s_nop 0
	s_addc_u32 s71, s94, s35
	s_add_u32 s34, s2, s34
	s_waitcnt lgkmcnt(0)
	v_mfma_f32_16x16x32_bf16 v[114:117], v[182:185], v[114:117], v[2:5]
	s_addc_u32 s35, s10, s35
	s_and_b64 vcc, exec, s[46:47]
	s_nop 5
	v_cvt_pk_bf16_f32 v2, v114, v115
	v_mfma_f32_16x16x32_bf16 v[110:113], v[182:185], v[134:137], v[26:29]
	v_cvt_pk_bf16_f32 v3, v116, v117
	s_nop 6
	v_cvt_pk_bf16_f32 v4, v110, v111
	v_cvt_pk_bf16_f32 v5, v112, v113
	ds_write2st64_b64 v172, v[2:3], v[4:5] offset1:9
	s_waitcnt vmcnt(26)
	ds_write_b128 v161, v[42:45]
	s_waitcnt vmcnt(25)
	ds_write_b128 v163, v[46:49]
	s_waitcnt vmcnt(24)
	ds_write_b128 v161, v[58:61] offset:18432
	s_waitcnt vmcnt(23)
	ds_write_b128 v165, v[74:77]
	s_waitcnt vmcnt(22)
	ds_write_b128 v166, v[94:97] offset:36864
	s_waitcnt vmcnt(21)
	ds_write_b128 v167, v[98:101] offset:36864
	v_lshl_add_u64 v[2:3], s[68:69], 0, v[146:147]
	global_load_dwordx4 v[42:45], v[2:3], off
	v_lshl_add_u64 v[2:3], s[68:69], 0, v[148:149]
	global_load_dwordx4 v[46:49], v[2:3], off
	v_lshl_add_u64 v[2:3], s[70:71], 0, v[146:147]
	global_load_dwordx4 v[58:61], v[2:3], off
	v_lshl_add_u64 v[2:3], s[70:71], 0, v[148:149]
	global_load_dwordx4 v[74:77], v[2:3], off
	v_lshl_add_u64 v[2:3], s[34:35], 0, v[146:147]
	global_load_dwordx4 v[90:93], v[2:3], off
	v_lshl_add_u64 v[2:3], s[34:35], 0, v[148:149]
	s_lshl_b64 s[34:35], s[0:1], 15
	s_lshl_b64 s[0:1], s[0:1], 8
	v_lshl_add_u64 v[98:99], v[152:153], 0, s[0:1]
	global_load_dwordx4 v[94:97], v[2:3], off
	global_load_dword v138, v[98:99], off
	v_lshl_add_u64 v[2:3], v[156:157], 0, s[34:35]
	v_lshl_add_u64 v[4:5], v[154:155], 0, s[8:9]
	v_cndmask_b32_e64 v3, v5, v3, s[44:45]
	v_cndmask_b32_e64 v2, v4, v2, s[44:45]
	global_load_dwordx4 v[26:29], v[2:3], off
	v_lshl_add_u64 v[2:3], v[2:3], 0, s[60:61]
	global_load_dwordx4 v[2:5], v[2:3], off
	s_cbranch_vccnz .LBB0_1755
	v_cvt_pk_bf16_f32 v100, v118, v118
	s_mov_b64 s[0:1], 0x1e0000
	v_and_b32_e32 v100, 0xffff, v100
	v_lshl_add_u64 v[98:99], v[150:151], 0, s[0:1]
	global_store_short v[98:99], v100, off
	v_cvt_pk_bf16_f32 v100, v119, v119
	s_mov_b64 s[0:1], 0x1e0800
	v_and_b32_e32 v100, 0xffff, v100
	v_lshl_add_u64 v[98:99], v[150:151], 0, s[0:1]
	global_store_short v[98:99], v100, off
	v_cvt_pk_bf16_f32 v100, v120, v120
	s_mov_b64 s[0:1], 0x1e1000
	v_and_b32_e32 v100, 0xffff, v100
	v_lshl_add_u64 v[98:99], v[150:151], 0, s[0:1]
	global_store_short v[98:99], v100, off
	v_cvt_pk_bf16_f32 v100, v121, v121
	s_mov_b64 s[0:1], 0x1e1800
	v_and_b32_e32 v100, 0xffff, v100
	v_lshl_add_u64 v[98:99], v[150:151], 0, s[0:1]
	global_store_short v[98:99], v100, off
	v_cvt_pk_bf16_f32 v100, v122, v122
	s_mov_b64 s[0:1], 0x1e0020
	v_and_b32_e32 v100, 0xffff, v100
	v_lshl_add_u64 v[98:99], v[150:151], 0, s[0:1]
	global_store_short v[98:99], v100, off
	v_cvt_pk_bf16_f32 v100, v123, v123
	s_mov_b64 s[0:1], 0x1e0820
	v_and_b32_e32 v100, 0xffff, v100
	v_lshl_add_u64 v[98:99], v[150:151], 0, s[0:1]
	global_store_short v[98:99], v100, off
	v_cvt_pk_bf16_f32 v100, v124, v124
	s_mov_b64 s[0:1], 0x1e1020
	v_and_b32_e32 v100, 0xffff, v100
	v_lshl_add_u64 v[98:99], v[150:151], 0, s[0:1]
	global_store_short v[98:99], v100, off
	s_mov_b64 s[0:1], 0x1e1820
	v_cvt_pk_bf16_f32 v100, v125, v125
	v_lshl_add_u64 v[98:99], v[150:151], 0, s[0:1]
	v_and_b32_e32 v100, 0xffff, v100
	global_store_short v[98:99], v100, off
.LBB0_1755:
	s_waitcnt lgkmcnt(0)
	s_barrier
	ds_read_b128 v[98:101], v168
	ds_read_b128 v[118:121], v143
	ds_read_b128 v[122:125], v143 offset:4608
	ds_read_b128 v[178:181], v168 offset:64
	ds_read_b128 v[126:129], v143 offset:64
	ds_read_b128 v[182:185], v143 offset:4672
	ds_read_b128 v[186:189], v168 offset:128
	ds_read_b128 v[190:193], v143 offset:128
	ds_read_b128 v[206:209], v143 offset:4736
	ds_read_b128 v[210:213], v168 offset:192
	ds_read_b128 v[214:217], v143 offset:192
	ds_read_b128 v[218:221], v143 offset:4800
	s_and_b64 vcc, exec, s[48:49]
	s_waitcnt lgkmcnt(10)
	v_mfma_f32_16x16x32_bf16 v[118:121], v[98:101], v[118:121], 0
	s_waitcnt lgkmcnt(9)
	v_mfma_f32_16x16x32_bf16 v[98:101], v[98:101], v[122:125], 0
	s_nop 0
	s_nop 0
	s_waitcnt lgkmcnt(7)
	v_mfma_f32_16x16x32_bf16 v[118:121], v[178:181], v[126:129], v[118:121]
	s_nop 0
	s_waitcnt lgkmcnt(6)
	v_mfma_f32_16x16x32_bf16 v[98:101], v[178:181], v[182:185], v[98:101]
	s_nop 0
	s_nop 0
	s_waitcnt lgkmcnt(4)
	v_mfma_f32_16x16x32_bf16 v[118:121], v[186:189], v[190:193], v[118:121]
	s_nop 0
	s_waitcnt lgkmcnt(3)
	v_mfma_f32_16x16x32_bf16 v[98:101], v[186:189], v[206:209], v[98:101]
	s_nop 0
	s_nop 0
	s_waitcnt lgkmcnt(1)
	v_mfma_f32_16x16x32_bf16 v[118:121], v[210:213], v[214:217], v[118:121]
	s_nop 0
	s_waitcnt lgkmcnt(0)
	v_mfma_f32_16x16x32_bf16 v[122:125], v[210:213], v[218:221], v[98:101]
	s_cbranch_vccnz .LBB0_1757
	s_waitcnt vmcnt(28)
	s_nop 2
	v_sub_f32_e32 v99, v33, v121
	v_sub_f32_e32 v100, v32, v120
	v_sub_f32_e32 v98, v31, v119
	v_sub_f32_e32 v101, v30, v118
	v_cvt_pk_bf16_f32 v98, v101, v98
	v_cvt_pk_bf16_f32 v99, v100, v99
	s_waitcnt vmcnt(27)
	v_sub_f32_e32 v101, v9, v125
	v_sub_f32_e32 v126, v8, v124
	v_sub_f32_e32 v100, v7, v123
	v_sub_f32_e32 v127, v6, v122
	v_cvt_pk_bf16_f32 v100, v127, v100
	v_cvt_pk_bf16_f32 v101, v126, v101
	ds_write2st64_b64 v170, v[98:99], v[100:101] offset1:5

.LBB0_1759:
	s_andn2_b64 vcc, exec, s[8:9]
	s_cbranch_vccnz .LBB0_1761
	ds_read_b128 v[126:129], v169
	ds_read_b128 v[98:101], v169 offset:64
	ds_read_b128 v[130:133], v169 offset:2560
	ds_read_b128 v[134:137], v169 offset:2624
	s_waitcnt lgkmcnt(7)
	s_nop 0
	s_waitcnt lgkmcnt(6)
	s_nop 0
	s_waitcnt lgkmcnt(5)
	s_nop 0
	s_waitcnt lgkmcnt(4)
	s_nop 0
	s_waitcnt vmcnt(28) lgkmcnt(3)
	v_mfma_f32_16x16x32_bf16 v[118:121], v[30:33], v[126:129], v[118:121]
	s_waitcnt lgkmcnt(1)
	v_mfma_f32_16x16x32_bf16 v[30:33], v[30:33], v[130:133], v[122:125]
	s_waitcnt vmcnt(27)
	v_mfma_f32_16x16x32_bf16 v[118:121], v[6:9], v[98:101], v[118:121]
	s_waitcnt lgkmcnt(0)
	v_mfma_f32_16x16x32_bf16 v[122:125], v[6:9], v[134:137], v[30:33]
.LBB0_1761:
	ds_read_b128 v[178:181], v173 offset:36864
	ds_read_b128 v[182:185], v173 offset:36928
	s_waitcnt vmcnt(28)
	s_nop 2
	v_pk_mul_f32 v[32:33], v[140:141], v[112:113] op_sel_hi:[0,1]
	v_pk_mul_f32 v[30:31], v[140:141], v[110:111] op_sel_hi:[0,1]
	s_nop 0
	s_waitcnt vmcnt(27)
	v_pk_mul_f32 v[8:9], v[140:141], v[116:117] op_sel_hi:[0,1]
	v_pk_mul_f32 v[6:7], v[140:141], v[114:115] op_sel_hi:[0,1]
	s_or_b32 s0, s6, 0xa0
	s_ashr_i32 s1, s0, 31
	s_lshl_b64 s[8:9], s[0:1], 13
	s_lshl_b64 s[34:35], s[0:1], 14
	s_waitcnt lgkmcnt(1)
	v_mfma_f32_16x16x32_bf16 v[6:9], v[178:181], v[126:129], v[6:9]
	s_add_u32 s68, s95, s34
	s_addc_u32 s69, s3, s35
	s_add_u32 s70, s29, s34
	v_mfma_f32_16x16x32_bf16 v[30:33], v[178:181], v[130:133], v[30:33]
	s_nop 0
	s_addc_u32 s71, s94, s35
	s_add_u32 s34, s2, s34
	s_waitcnt lgkmcnt(0)
	v_mfma_f32_16x16x32_bf16 v[114:117], v[182:185], v[98:101], v[6:9]
	s_addc_u32 s35, s10, s35
	s_and_b64 vcc, exec, s[46:47]
	s_nop 5
	v_cvt_pk_bf16_f32 v6, v114, v115
	v_mfma_f32_16x16x32_bf16 v[110:113], v[182:185], v[134:137], v[30:33]
	v_cvt_pk_bf16_f32 v7, v116, v117
	s_nop 6
	v_cvt_pk_bf16_f32 v8, v110, v111
	v_cvt_pk_bf16_f32 v9, v112, v113
	ds_write2st64_b64 v172, v[6:7], v[8:9] offset1:9
	s_waitcnt vmcnt(26)
	ds_write_b128 v161, v[34:37] offset:57344
	s_waitcnt vmcnt(25)
	ds_write_b128 v163, v[50:53] offset:57344
	s_waitcnt vmcnt(24)
	ds_write_b128 v174, v[62:65] offset:57344
	s_waitcnt vmcnt(23)
	ds_write_b128 v165, v[78:81] offset:57344
	s_waitcnt vmcnt(22)
	ds_write_b128 v175, v[82:85]
	s_waitcnt vmcnt(21)
	ds_write_b128 v176, v[106:109]
	v_lshl_add_u64 v[6:7], s[68:69], 0, v[146:147]
	global_load_dwordx4 v[34:37], v[6:7], off
	v_lshl_add_u64 v[6:7], s[68:69], 0, v[148:149]
	global_load_dwordx4 v[50:53], v[6:7], off
	v_lshl_add_u64 v[6:7], s[70:71], 0, v[146:147]
	global_load_dwordx4 v[62:65], v[6:7], off
	v_lshl_add_u64 v[6:7], s[70:71], 0, v[148:149]
	global_load_dwordx4 v[78:81], v[6:7], off
	v_lshl_add_u64 v[6:7], s[34:35], 0, v[146:147]
	global_load_dwordx4 v[82:85], v[6:7], off
	v_lshl_add_u64 v[6:7], s[34:35], 0, v[148:149]
	s_lshl_b64 s[34:35], s[0:1], 15
	s_lshl_b64 s[0:1], s[0:1], 8
	v_lshl_add_u64 v[106:107], v[152:153], 0, s[0:1]
	global_load_dwordx4 v[98:101], v[6:7], off
	global_load_dword v140, v[106:107], off
	v_lshl_add_u64 v[6:7], v[156:157], 0, s[34:35]
	v_lshl_add_u64 v[8:9], v[154:155], 0, s[8:9]
	v_cndmask_b32_e64 v7, v9, v7, s[44:45]
	v_cndmask_b32_e64 v6, v8, v6, s[44:45]
	global_load_dwordx4 v[30:33], v[6:7], off
	v_lshl_add_u64 v[6:7], v[6:7], 0, s[60:61]
	global_load_dwordx4 v[6:9], v[6:7], off
	s_cbranch_vccnz .LBB0_1763
	v_cvt_pk_bf16_f32 v108, v118, v118
	s_mov_b64 s[0:1], 0x200000
	v_and_b32_e32 v108, 0xffff, v108
	v_lshl_add_u64 v[106:107], v[150:151], 0, s[0:1]
	global_store_short v[106:107], v108, off
	v_cvt_pk_bf16_f32 v108, v119, v119
	s_mov_b64 s[0:1], 0x200800
	v_and_b32_e32 v108, 0xffff, v108
	v_lshl_add_u64 v[106:107], v[150:151], 0, s[0:1]
	global_store_short v[106:107], v108, off
	v_cvt_pk_bf16_f32 v108, v120, v120
	s_mov_b64 s[0:1], 0x201000
	v_and_b32_e32 v108, 0xffff, v108
	v_lshl_add_u64 v[106:107], v[150:151], 0, s[0:1]
	global_store_short v[106:107], v108, off
	v_cvt_pk_bf16_f32 v108, v121, v121
	s_mov_b64 s[0:1], 0x201800
	v_and_b32_e32 v108, 0xffff, v108
	v_lshl_add_u64 v[106:107], v[150:151], 0, s[0:1]
	global_store_short v[106:107], v108, off
	v_cvt_pk_bf16_f32 v108, v122, v122
	s_mov_b64 s[0:1], 0x200020
	v_and_b32_e32 v108, 0xffff, v108
	v_lshl_add_u64 v[106:107], v[150:151], 0, s[0:1]
	global_store_short v[106:107], v108, off
	v_cvt_pk_bf16_f32 v108, v123, v123
	s_mov_b64 s[0:1], 0x200820
	v_and_b32_e32 v108, 0xffff, v108
	v_lshl_add_u64 v[106:107], v[150:151], 0, s[0:1]
	global_store_short v[106:107], v108, off
	v_cvt_pk_bf16_f32 v108, v124, v124
	s_mov_b64 s[0:1], 0x201020
	v_and_b32_e32 v108, 0xffff, v108
	v_lshl_add_u64 v[106:107], v[150:151], 0, s[0:1]
	global_store_short v[106:107], v108, off
	s_mov_b64 s[0:1], 0x201820
	v_cvt_pk_bf16_f32 v108, v125, v125
	v_lshl_add_u64 v[106:107], v[150:151], 0, s[0:1]
	v_and_b32_e32 v108, 0xffff, v108
	global_store_short v[106:107], v108, off
.LBB0_1763:
	s_waitcnt lgkmcnt(0)
	s_barrier
	ds_read_b128 v[106:109], v168 offset:57344
	ds_read_b128 v[118:121], v143
	ds_read_b128 v[122:125], v143 offset:4608
	ds_read_b128 v[178:181], v168 offset:57408
	ds_read_b128 v[126:129], v143 offset:64
	ds_read_b128 v[182:185], v143 offset:4672
	ds_read_b128 v[186:189], v168 offset:57472
	ds_read_b128 v[190:193], v143 offset:128
	ds_read_b128 v[206:209], v143 offset:4736
	ds_read_b128 v[210:213], v168 offset:57536
	ds_read_b128 v[214:217], v143 offset:192
	ds_read_b128 v[218:221], v143 offset:4800
	s_and_b64 vcc, exec, s[48:49]
	s_waitcnt lgkmcnt(10)
	v_mfma_f32_16x16x32_bf16 v[118:121], v[106:109], v[118:121], 0
	s_waitcnt lgkmcnt(9)
	v_mfma_f32_16x16x32_bf16 v[106:109], v[106:109], v[122:125], 0
	s_nop 0
	s_nop 0
	s_waitcnt lgkmcnt(7)
	v_mfma_f32_16x16x32_bf16 v[118:121], v[178:181], v[126:129], v[118:121]
	s_nop 0
	s_waitcnt lgkmcnt(6)
	v_mfma_f32_16x16x32_bf16 v[106:109], v[178:181], v[182:185], v[106:109]
	s_nop 0
	s_nop 0
	s_waitcnt lgkmcnt(4)
	v_mfma_f32_16x16x32_bf16 v[118:121], v[186:189], v[190:193], v[118:121]
	s_nop 0
	s_waitcnt lgkmcnt(3)
	v_mfma_f32_16x16x32_bf16 v[106:109], v[186:189], v[206:209], v[106:109]
	s_nop 0
	s_nop 0
	s_waitcnt lgkmcnt(1)
	v_mfma_f32_16x16x32_bf16 v[118:121], v[210:213], v[214:217], v[118:121]
	s_nop 0
	s_waitcnt lgkmcnt(0)
	v_mfma_f32_16x16x32_bf16 v[122:125], v[210:213], v[218:221], v[106:109]
	s_cbranch_vccnz .LBB0_1765
	s_waitcnt vmcnt(28)
	s_nop 2
	v_sub_f32_e32 v107, v21, v121
	v_sub_f32_e32 v108, v20, v120
	v_sub_f32_e32 v106, v19, v119
	v_sub_f32_e32 v109, v18, v118
	v_cvt_pk_bf16_f32 v106, v109, v106
	v_cvt_pk_bf16_f32 v107, v108, v107
	s_waitcnt vmcnt(27)
	v_sub_f32_e32 v109, v13, v125
	v_sub_f32_e32 v126, v12, v124
	v_sub_f32_e32 v108, v11, v123
	v_sub_f32_e32 v127, v10, v122
	v_cvt_pk_bf16_f32 v108, v127, v108
	v_cvt_pk_bf16_f32 v109, v126, v109
	ds_write2st64_b64 v170, v[106:107], v[108:109] offset1:5

.LBB0_1767:
	s_andn2_b64 vcc, exec, s[8:9]
	s_cbranch_vccnz .LBB0_1769
	ds_read_b128 v[126:129], v169
	ds_read_b128 v[106:109], v169 offset:64
	ds_read_b128 v[130:133], v169 offset:2560
	ds_read_b128 v[134:137], v169 offset:2624
	s_waitcnt lgkmcnt(7)
	s_nop 0
	s_waitcnt lgkmcnt(6)
	s_nop 0
	s_waitcnt lgkmcnt(5)
	s_nop 0
	s_waitcnt lgkmcnt(4)
	s_nop 0
	s_waitcnt vmcnt(28) lgkmcnt(3)
	v_mfma_f32_16x16x32_bf16 v[118:121], v[18:21], v[126:129], v[118:121]
	s_waitcnt lgkmcnt(1)
	v_mfma_f32_16x16x32_bf16 v[18:21], v[18:21], v[130:133], v[122:125]
	s_waitcnt vmcnt(27)
	v_mfma_f32_16x16x32_bf16 v[118:121], v[10:13], v[106:109], v[118:121]
	s_waitcnt lgkmcnt(0)
	v_mfma_f32_16x16x32_bf16 v[122:125], v[10:13], v[134:137], v[18:21]
.LBB0_1769:
	ds_read_b128 v[178:181], v177
	ds_read_b128 v[182:185], v177 offset:64
	s_waitcnt vmcnt(28)
	s_nop 2
	v_pk_mul_f32 v[20:21], v[158:159], v[112:113] op_sel_hi:[0,1]
	v_pk_mul_f32 v[18:19], v[158:159], v[110:111] op_sel_hi:[0,1]
	s_nop 0
	s_waitcnt vmcnt(27)
	v_pk_mul_f32 v[12:13], v[158:159], v[116:117] op_sel_hi:[0,1]
	v_pk_mul_f32 v[10:11], v[158:159], v[114:115] op_sel_hi:[0,1]
	s_nop 0
	s_or_b32 s0, s6, 0xa8
	s_ashr_i32 s1, s0, 31
	s_lshl_b64 s[8:9], s[0:1], 13
	s_waitcnt lgkmcnt(1)
	v_mfma_f32_16x16x32_bf16 v[10:13], v[178:181], v[126:129], v[10:13]
	s_lshl_b64 s[34:35], s[0:1], 14
	s_add_u32 s68, s95, s34
	s_addc_u32 s69, s3, s35
	v_mfma_f32_16x16x32_bf16 v[18:21], v[178:181], v[130:133], v[18:21]
	s_add_u32 s70, s29, s34
	s_addc_u32 s71, s94, s35
	s_add_u32 s34, s2, s34
	s_waitcnt lgkmcnt(0)
	v_mfma_f32_16x16x32_bf16 v[110:113], v[182:185], v[106:109], v[10:13]
	s_addc_u32 s35, s10, s35
	s_and_b64 vcc, exec, s[46:47]
	v_mfma_f32_16x16x32_bf16 v[106:109], v[182:185], v[134:137], v[18:21]
	s_nop 4
	v_cvt_pk_bf16_f32 v10, v110, v111
	v_cvt_pk_bf16_f32 v11, v112, v113
	s_nop 0
	v_cvt_pk_bf16_f32 v12, v106, v107
	v_cvt_pk_bf16_f32 v13, v108, v109
	ds_write2st64_b64 v172, v[10:11], v[12:13] offset1:9
	s_waitcnt vmcnt(26)
	ds_write_b128 v161, v[38:41]
	s_waitcnt vmcnt(25)
	ds_write_b128 v163, v[54:57]
	s_waitcnt vmcnt(24)
	ds_write_b128 v161, v[66:69] offset:18432
	s_waitcnt vmcnt(23)
	ds_write_b128 v165, v[70:73]
	s_waitcnt vmcnt(22)
	ds_write_b128 v166, v[86:89] offset:36864
	s_waitcnt vmcnt(21)
	ds_write_b128 v167, v[102:105] offset:36864
	v_lshl_add_u64 v[10:11], s[68:69], 0, v[146:147]
	global_load_dwordx4 v[38:41], v[10:11], off
	v_lshl_add_u64 v[10:11], s[68:69], 0, v[148:149]
	global_load_dwordx4 v[54:57], v[10:11], off
	v_lshl_add_u64 v[10:11], s[70:71], 0, v[146:147]
	global_load_dwordx4 v[66:69], v[10:11], off
	v_lshl_add_u64 v[10:11], s[70:71], 0, v[148:149]
	global_load_dwordx4 v[70:73], v[10:11], off
	v_lshl_add_u64 v[10:11], s[34:35], 0, v[146:147]
	global_load_dwordx4 v[86:89], v[10:11], off
	v_lshl_add_u64 v[10:11], s[34:35], 0, v[148:149]
	s_lshl_b64 s[34:35], s[0:1], 15
	s_lshl_b64 s[0:1], s[0:1], 8
	v_lshl_add_u64 v[114:115], v[152:153], 0, s[0:1]
	global_load_dwordx4 v[102:105], v[10:11], off
	global_load_dword v158, v[114:115], off
	v_lshl_add_u64 v[10:11], v[156:157], 0, s[34:35]
	v_lshl_add_u64 v[12:13], v[154:155], 0, s[8:9]
	v_cndmask_b32_e64 v11, v13, v11, s[44:45]
	v_cndmask_b32_e64 v10, v12, v10, s[44:45]
	global_load_dwordx4 v[18:21], v[10:11], off
	v_lshl_add_u64 v[10:11], v[10:11], 0, s[60:61]
	global_load_dwordx4 v[10:13], v[10:11], off
	s_cbranch_vccnz .LBB0_1771
	v_cvt_pk_bf16_f32 v116, v118, v118
	s_mov_b64 s[0:1], 0x220000
	v_and_b32_e32 v116, 0xffff, v116
	v_lshl_add_u64 v[114:115], v[150:151], 0, s[0:1]
	global_store_short v[114:115], v116, off
	v_cvt_pk_bf16_f32 v116, v119, v119
	s_mov_b64 s[0:1], 0x220800
	v_and_b32_e32 v116, 0xffff, v116
	v_lshl_add_u64 v[114:115], v[150:151], 0, s[0:1]
	global_store_short v[114:115], v116, off
	v_cvt_pk_bf16_f32 v116, v120, v120
	s_mov_b64 s[0:1], 0x221000
	v_and_b32_e32 v116, 0xffff, v116
	v_lshl_add_u64 v[114:115], v[150:151], 0, s[0:1]
	global_store_short v[114:115], v116, off
	v_cvt_pk_bf16_f32 v116, v121, v121
	s_mov_b64 s[0:1], 0x221800
	v_and_b32_e32 v116, 0xffff, v116
	v_lshl_add_u64 v[114:115], v[150:151], 0, s[0:1]
	global_store_short v[114:115], v116, off
	v_cvt_pk_bf16_f32 v116, v122, v122
	s_mov_b64 s[0:1], 0x220020
	v_and_b32_e32 v116, 0xffff, v116
	v_lshl_add_u64 v[114:115], v[150:151], 0, s[0:1]
	global_store_short v[114:115], v116, off
	v_cvt_pk_bf16_f32 v116, v123, v123
	s_mov_b64 s[0:1], 0x220820
	v_and_b32_e32 v116, 0xffff, v116
	v_lshl_add_u64 v[114:115], v[150:151], 0, s[0:1]
	global_store_short v[114:115], v116, off
	v_cvt_pk_bf16_f32 v116, v124, v124
	s_mov_b64 s[0:1], 0x221020
	v_and_b32_e32 v116, 0xffff, v116
	v_lshl_add_u64 v[114:115], v[150:151], 0, s[0:1]
	global_store_short v[114:115], v116, off
	s_mov_b64 s[0:1], 0x221820
	v_cvt_pk_bf16_f32 v116, v125, v125
	v_lshl_add_u64 v[114:115], v[150:151], 0, s[0:1]
	v_and_b32_e32 v116, 0xffff, v116
	global_store_short v[114:115], v116, off
.LBB0_1771:
	s_waitcnt lgkmcnt(0)
	s_barrier
	ds_read_b128 v[114:117], v168
	ds_read_b128 v[118:121], v143
	ds_read_b128 v[122:125], v143 offset:4608
	ds_read_b128 v[178:181], v168 offset:64
	ds_read_b128 v[126:129], v143 offset:64
	ds_read_b128 v[182:185], v143 offset:4672
	ds_read_b128 v[186:189], v168 offset:128
	ds_read_b128 v[190:193], v143 offset:128
	ds_read_b128 v[206:209], v143 offset:4736
	ds_read_b128 v[210:213], v168 offset:192
	ds_read_b128 v[214:217], v143 offset:192
	ds_read_b128 v[218:221], v143 offset:4800
	s_and_b64 vcc, exec, s[48:49]
	s_waitcnt lgkmcnt(10)
	v_mfma_f32_16x16x32_bf16 v[118:121], v[114:117], v[118:121], 0
	s_waitcnt lgkmcnt(9)
	v_mfma_f32_16x16x32_bf16 v[114:117], v[114:117], v[122:125], 0
	s_nop 0
	s_nop 0
	s_waitcnt lgkmcnt(7)
	v_mfma_f32_16x16x32_bf16 v[118:121], v[178:181], v[126:129], v[118:121]
	s_nop 0
	s_waitcnt lgkmcnt(6)
	v_mfma_f32_16x16x32_bf16 v[114:117], v[178:181], v[182:185], v[114:117]
	s_nop 0
	s_nop 0
	s_waitcnt lgkmcnt(4)
	v_mfma_f32_16x16x32_bf16 v[118:121], v[186:189], v[190:193], v[118:121]
	s_nop 0
	s_waitcnt lgkmcnt(3)
	v_mfma_f32_16x16x32_bf16 v[114:117], v[186:189], v[206:209], v[114:117]
	s_nop 0
	s_nop 0
	s_waitcnt lgkmcnt(1)
	v_mfma_f32_16x16x32_bf16 v[118:121], v[210:213], v[214:217], v[118:121]
	s_nop 0
	s_waitcnt lgkmcnt(0)
	v_mfma_f32_16x16x32_bf16 v[122:125], v[210:213], v[218:221], v[114:117]
	s_cbranch_vccnz .LBB0_1773
	s_waitcnt vmcnt(28)
	s_nop 2
	v_sub_f32_e32 v115, v25, v121
	v_sub_f32_e32 v116, v24, v120
	v_sub_f32_e32 v114, v23, v119
	v_sub_f32_e32 v117, v22, v118
	v_cvt_pk_bf16_f32 v114, v117, v114
	v_cvt_pk_bf16_f32 v115, v116, v115
	s_waitcnt vmcnt(27)
	v_sub_f32_e32 v117, v17, v125
	v_sub_f32_e32 v126, v16, v124
	v_sub_f32_e32 v116, v15, v123
	v_sub_f32_e32 v127, v14, v122
	v_cvt_pk_bf16_f32 v116, v127, v116
	v_cvt_pk_bf16_f32 v117, v126, v117
	ds_write2st64_b64 v170, v[114:115], v[116:117] offset1:5

.LBB0_1775:
	s_andn2_b64 vcc, exec, s[8:9]
	s_cbranch_vccnz .LBB0_1777
	ds_read_b128 v[126:129], v169
	ds_read_b128 v[114:117], v169 offset:64
	ds_read_b128 v[130:133], v169 offset:2560
	ds_read_b128 v[134:137], v169 offset:2624
	s_waitcnt lgkmcnt(7)
	s_nop 0
	s_waitcnt lgkmcnt(6)
	s_nop 0
	s_waitcnt lgkmcnt(5)
	s_nop 0
	s_waitcnt lgkmcnt(4)
	s_nop 0
	s_waitcnt vmcnt(28) lgkmcnt(3)
	v_mfma_f32_16x16x32_bf16 v[118:121], v[22:25], v[126:129], v[118:121]
	s_waitcnt lgkmcnt(1)
	v_mfma_f32_16x16x32_bf16 v[22:25], v[22:25], v[130:133], v[122:125]
	s_waitcnt vmcnt(27)
	v_mfma_f32_16x16x32_bf16 v[118:121], v[14:17], v[114:117], v[118:121]
	s_waitcnt lgkmcnt(0)
	v_mfma_f32_16x16x32_bf16 v[122:125], v[14:17], v[134:137], v[22:25]
.LBB0_1777:
	ds_read_b128 v[178:181], v173 offset:36864
	ds_read_b128 v[182:185], v173 offset:36928
	s_waitcnt vmcnt(28)
	s_nop 2
	v_pk_mul_f32 v[24:25], v[160:161], v[108:109] op_sel_hi:[0,1]
	v_pk_mul_f32 v[22:23], v[160:161], v[106:107] op_sel_hi:[0,1]
	s_nop 0
	s_waitcnt vmcnt(27)
	v_pk_mul_f32 v[16:17], v[160:161], v[112:113] op_sel_hi:[0,1]
	v_pk_mul_f32 v[14:15], v[160:161], v[110:111] op_sel_hi:[0,1]
	s_or_b32 s0, s6, 0xb0
	s_ashr_i32 s1, s0, 31
	s_lshl_b64 s[8:9], s[0:1], 13
	s_lshl_b64 s[34:35], s[0:1], 14
	s_waitcnt lgkmcnt(1)
	v_mfma_f32_16x16x32_bf16 v[14:17], v[178:181], v[126:129], v[14:17]
	s_add_u32 s68, s95, s34
	s_addc_u32 s69, s3, s35
	s_add_u32 s70, s29, s34
	v_mfma_f32_16x16x32_bf16 v[22:25], v[178:181], v[130:133], v[22:25]
	s_nop 0
	s_addc_u32 s71, s94, s35
	s_add_u32 s34, s2, s34
	s_waitcnt lgkmcnt(0)
	v_mfma_f32_16x16x32_bf16 v[114:117], v[182:185], v[114:117], v[14:17]
	s_addc_u32 s35, s10, s35
	s_and_b64 vcc, exec, s[46:47]
	s_nop 5
	v_cvt_pk_bf16_f32 v14, v114, v115
	v_mfma_f32_16x16x32_bf16 v[110:113], v[182:185], v[134:137], v[22:25]
	v_cvt_pk_bf16_f32 v15, v116, v117
	s_nop 6
	v_cvt_pk_bf16_f32 v16, v110, v111
	v_cvt_pk_bf16_f32 v17, v112, v113
	ds_write2st64_b64 v172, v[14:15], v[16:17] offset1:9
	s_waitcnt vmcnt(26)
	ds_write_b128 v161, v[42:45] offset:57344
	s_waitcnt vmcnt(25)
	ds_write_b128 v163, v[46:49] offset:57344
	s_waitcnt vmcnt(24)
	ds_write_b128 v174, v[58:61] offset:57344
	s_waitcnt vmcnt(23)
	ds_write_b128 v165, v[74:77] offset:57344
	s_waitcnt vmcnt(22)
	ds_write_b128 v175, v[90:93]
	s_waitcnt vmcnt(21)
	ds_write_b128 v176, v[94:97]
	v_lshl_add_u64 v[14:15], s[68:69], 0, v[146:147]
	global_load_dwordx4 v[42:45], v[14:15], off
	v_lshl_add_u64 v[14:15], s[68:69], 0, v[148:149]
	global_load_dwordx4 v[46:49], v[14:15], off
	v_lshl_add_u64 v[14:15], s[70:71], 0, v[146:147]
	global_load_dwordx4 v[58:61], v[14:15], off
	v_lshl_add_u64 v[14:15], s[70:71], 0, v[148:149]
	global_load_dwordx4 v[74:77], v[14:15], off
	v_lshl_add_u64 v[14:15], s[34:35], 0, v[146:147]
	global_load_dwordx4 v[90:93], v[14:15], off
	v_lshl_add_u64 v[14:15], s[34:35], 0, v[148:149]
	s_lshl_b64 s[34:35], s[0:1], 15
	s_lshl_b64 s[0:1], s[0:1], 8
	v_lshl_add_u64 v[94:95], v[152:153], 0, s[0:1]
	global_load_dwordx4 v[106:109], v[14:15], off
	global_load_dword v160, v[94:95], off
	v_lshl_add_u64 v[14:15], v[156:157], 0, s[34:35]
	v_lshl_add_u64 v[16:17], v[154:155], 0, s[8:9]
	v_cndmask_b32_e64 v15, v17, v15, s[44:45]
	v_cndmask_b32_e64 v14, v16, v14, s[44:45]
	global_load_dwordx4 v[22:25], v[14:15], off
	v_lshl_add_u64 v[14:15], v[14:15], 0, s[60:61]
	global_load_dwordx4 v[14:17], v[14:15], off
	s_cbranch_vccnz .LBB0_1779
	v_cvt_pk_bf16_f32 v96, v118, v118
	s_mov_b64 s[0:1], 0x240000
	v_and_b32_e32 v96, 0xffff, v96
	v_lshl_add_u64 v[94:95], v[150:151], 0, s[0:1]
	global_store_short v[94:95], v96, off
	v_cvt_pk_bf16_f32 v96, v119, v119
	s_mov_b64 s[0:1], 0x240800
	v_and_b32_e32 v96, 0xffff, v96
	v_lshl_add_u64 v[94:95], v[150:151], 0, s[0:1]
	global_store_short v[94:95], v96, off
	v_cvt_pk_bf16_f32 v96, v120, v120
	s_mov_b64 s[0:1], 0x241000
	v_and_b32_e32 v96, 0xffff, v96
	v_lshl_add_u64 v[94:95], v[150:151], 0, s[0:1]
	global_store_short v[94:95], v96, off
	v_cvt_pk_bf16_f32 v96, v121, v121
	s_mov_b64 s[0:1], 0x241800
	v_and_b32_e32 v96, 0xffff, v96
	v_lshl_add_u64 v[94:95], v[150:151], 0, s[0:1]
	global_store_short v[94:95], v96, off
	v_cvt_pk_bf16_f32 v96, v122, v122
	s_mov_b64 s[0:1], 0x240020
	v_and_b32_e32 v96, 0xffff, v96
	v_lshl_add_u64 v[94:95], v[150:151], 0, s[0:1]
	global_store_short v[94:95], v96, off
	v_cvt_pk_bf16_f32 v96, v123, v123
	s_mov_b64 s[0:1], 0x240820
	v_and_b32_e32 v96, 0xffff, v96
	v_lshl_add_u64 v[94:95], v[150:151], 0, s[0:1]
	global_store_short v[94:95], v96, off
	v_cvt_pk_bf16_f32 v96, v124, v124
	s_mov_b64 s[0:1], 0x241020
	v_and_b32_e32 v96, 0xffff, v96
	v_lshl_add_u64 v[94:95], v[150:151], 0, s[0:1]
	global_store_short v[94:95], v96, off
	s_mov_b64 s[0:1], 0x241820
	v_cvt_pk_bf16_f32 v96, v125, v125
	v_lshl_add_u64 v[94:95], v[150:151], 0, s[0:1]
	v_and_b32_e32 v96, 0xffff, v96
	global_store_short v[94:95], v96, off
.LBB0_1779:
	s_waitcnt lgkmcnt(0)
	s_barrier
	ds_read_b128 v[94:97], v168 offset:57344
	ds_read_b128 v[118:121], v143
	ds_read_b128 v[122:125], v143 offset:4608
	ds_read_b128 v[178:181], v168 offset:57408
	ds_read_b128 v[126:129], v143 offset:64
	ds_read_b128 v[182:185], v143 offset:4672
	ds_read_b128 v[186:189], v168 offset:57472
	ds_read_b128 v[190:193], v143 offset:128
	ds_read_b128 v[206:209], v143 offset:4736
	ds_read_b128 v[210:213], v168 offset:57536
	ds_read_b128 v[214:217], v143 offset:192
	ds_read_b128 v[218:221], v143 offset:4800
	s_and_b64 vcc, exec, s[48:49]
	s_waitcnt lgkmcnt(10)
	v_mfma_f32_16x16x32_bf16 v[118:121], v[94:97], v[118:121], 0
	s_waitcnt lgkmcnt(9)
	v_mfma_f32_16x16x32_bf16 v[94:97], v[94:97], v[122:125], 0
	s_nop 0
	s_nop 0
	s_waitcnt lgkmcnt(7)
	v_mfma_f32_16x16x32_bf16 v[118:121], v[178:181], v[126:129], v[118:121]
	s_nop 0
	s_waitcnt lgkmcnt(6)
	v_mfma_f32_16x16x32_bf16 v[94:97], v[178:181], v[182:185], v[94:97]
	s_nop 0
	s_nop 0
	s_waitcnt lgkmcnt(4)
	v_mfma_f32_16x16x32_bf16 v[118:121], v[186:189], v[190:193], v[118:121]
	s_nop 0
	s_waitcnt lgkmcnt(3)
	v_mfma_f32_16x16x32_bf16 v[94:97], v[186:189], v[206:209], v[94:97]
	s_nop 0
	s_nop 0
	s_waitcnt lgkmcnt(1)
	v_mfma_f32_16x16x32_bf16 v[122:125], v[210:213], v[214:217], v[118:121]
	s_nop 2
	s_nop 0
	s_waitcnt lgkmcnt(0)
	v_mfma_f32_16x16x32_bf16 v[126:129], v[210:213], v[218:221], v[94:97]
	s_cbranch_vccnz .LBB0_1781
	s_waitcnt vmcnt(28)
	s_nop 0
	v_sub_f32_e32 v95, v29, v125
	v_sub_f32_e32 v96, v28, v124
	v_sub_f32_e32 v94, v27, v123
	v_sub_f32_e32 v97, v26, v122
	v_cvt_pk_bf16_f32 v94, v97, v94
	v_cvt_pk_bf16_f32 v95, v96, v95
	s_waitcnt vmcnt(27)
	v_sub_f32_e32 v97, v5, v129
	v_sub_f32_e32 v118, v4, v128
	v_sub_f32_e32 v96, v3, v127
	v_sub_f32_e32 v119, v2, v126
	v_cvt_pk_bf16_f32 v96, v119, v96
	v_cvt_pk_bf16_f32 v97, v118, v97
	ds_write2st64_b64 v170, v[94:95], v[96:97] offset1:5

.LBB0_1783:
	s_andn2_b64 vcc, exec, s[8:9]
	s_cbranch_vccnz .LBB0_1785
	ds_read_b128 v[118:121], v169
	ds_read_b128 v[94:97], v169 offset:64
	ds_read_b128 v[130:133], v169 offset:2560
	ds_read_b128 v[134:137], v169 offset:2624
	s_waitcnt lgkmcnt(7)
	s_nop 0
	s_waitcnt lgkmcnt(6)
	s_nop 0
	s_waitcnt lgkmcnt(5)
	s_nop 0
	s_waitcnt lgkmcnt(4)
	s_nop 0
	s_waitcnt vmcnt(28) lgkmcnt(3)
	v_mfma_f32_16x16x32_bf16 v[122:125], v[26:29], v[118:121], v[122:125]
	s_waitcnt lgkmcnt(1)
	v_mfma_f32_16x16x32_bf16 v[26:29], v[26:29], v[130:133], v[126:129]
	s_waitcnt vmcnt(27)
	v_mfma_f32_16x16x32_bf16 v[122:125], v[2:5], v[94:97], v[122:125]
	s_waitcnt lgkmcnt(0)
	v_mfma_f32_16x16x32_bf16 v[126:129], v[2:5], v[134:137], v[26:29]
.LBB0_1785:
	ds_read_b128 v[178:181], v177
	ds_read_b128 v[182:185], v177 offset:64
	s_waitcnt vmcnt(28)
	s_nop 2
	v_pk_mul_f32 v[28:29], v[138:139], v[112:113] op_sel_hi:[0,1]
	v_pk_mul_f32 v[26:27], v[138:139], v[110:111] op_sel_hi:[0,1]
	s_nop 0
	s_waitcnt vmcnt(27)
	v_pk_mul_f32 v[4:5], v[138:139], v[116:117] op_sel_hi:[0,1]
	v_pk_mul_f32 v[2:3], v[138:139], v[114:115] op_sel_hi:[0,1]
	s_or_b32 s0, s6, 0xb8
	s_ashr_i32 s1, s0, 31
	s_lshl_b64 s[8:9], s[0:1], 13
	s_lshl_b64 s[34:35], s[0:1], 14
	s_waitcnt lgkmcnt(1)
	v_mfma_f32_16x16x32_bf16 v[2:5], v[178:181], v[118:121], v[2:5]
	s_add_u32 s68, s95, s34
	s_addc_u32 s69, s3, s35
	s_add_u32 s70, s29, s34
	v_mfma_f32_16x16x32_bf16 v[26:29], v[178:181], v[130:133], v[26:29]
	s_nop 0
	s_addc_u32 s71, s94, s35
	s_add_u32 s34, s2, s34
	s_waitcnt lgkmcnt(0)
	v_mfma_f32_16x16x32_bf16 v[118:121], v[182:185], v[94:97], v[2:5]
	s_addc_u32 s35, s10, s35
	s_and_b64 vcc, exec, s[46:47]
	s_nop 5
	v_cvt_pk_bf16_f32 v2, v118, v119
	v_mfma_f32_16x16x32_bf16 v[114:117], v[182:185], v[134:137], v[26:29]
	v_cvt_pk_bf16_f32 v3, v120, v121
	s_nop 6
	v_cvt_pk_bf16_f32 v4, v114, v115
	v_cvt_pk_bf16_f32 v5, v116, v117
	ds_write2st64_b64 v172, v[2:3], v[4:5] offset1:9
	s_waitcnt vmcnt(26)
	ds_write_b128 v161, v[34:37]
	s_waitcnt vmcnt(25)
	ds_write_b128 v163, v[50:53]
	s_waitcnt vmcnt(24)
	ds_write_b128 v161, v[62:65] offset:18432
	s_waitcnt vmcnt(23)
	ds_write_b128 v165, v[78:81]
	s_waitcnt vmcnt(22)
	ds_write_b128 v166, v[82:85] offset:36864
	s_waitcnt vmcnt(21)
	ds_write_b128 v167, v[98:101] offset:36864
	v_lshl_add_u64 v[2:3], s[68:69], 0, v[146:147]
	global_load_dwordx4 v[34:37], v[2:3], off
	v_lshl_add_u64 v[2:3], s[68:69], 0, v[148:149]
	global_load_dwordx4 v[50:53], v[2:3], off
	v_lshl_add_u64 v[2:3], s[70:71], 0, v[146:147]
	global_load_dwordx4 v[62:65], v[2:3], off
	v_lshl_add_u64 v[2:3], s[70:71], 0, v[148:149]
	global_load_dwordx4 v[78:81], v[2:3], off
	v_lshl_add_u64 v[2:3], s[34:35], 0, v[146:147]
	global_load_dwordx4 v[94:97], v[2:3], off
	v_lshl_add_u64 v[2:3], s[34:35], 0, v[148:149]
	s_lshl_b64 s[34:35], s[0:1], 15
	s_lshl_b64 s[0:1], s[0:1], 8
	v_lshl_add_u64 v[82:83], v[152:153], 0, s[0:1]
	global_load_dwordx4 v[110:113], v[2:3], off
	global_load_dword v162, v[82:83], off
	v_lshl_add_u64 v[2:3], v[156:157], 0, s[34:35]
	v_lshl_add_u64 v[4:5], v[154:155], 0, s[8:9]
	v_cndmask_b32_e64 v3, v5, v3, s[44:45]
	v_cndmask_b32_e64 v2, v4, v2, s[44:45]
	global_load_dwordx4 v[26:29], v[2:3], off
	v_lshl_add_u64 v[2:3], v[2:3], 0, s[60:61]
	global_load_dwordx4 v[2:5], v[2:3], off
	s_cbranch_vccnz .LBB0_1787
	v_cvt_pk_bf16_f32 v84, v122, v122
	s_mov_b64 s[0:1], 0x260000
	v_and_b32_e32 v84, 0xffff, v84
	v_lshl_add_u64 v[82:83], v[150:151], 0, s[0:1]
	global_store_short v[82:83], v84, off
	v_cvt_pk_bf16_f32 v84, v123, v123
	s_mov_b64 s[0:1], 0x260800
	v_and_b32_e32 v84, 0xffff, v84
	v_lshl_add_u64 v[82:83], v[150:151], 0, s[0:1]
	global_store_short v[82:83], v84, off
	v_cvt_pk_bf16_f32 v84, v124, v124
	s_mov_b64 s[0:1], 0x261000
	v_and_b32_e32 v84, 0xffff, v84
	v_lshl_add_u64 v[82:83], v[150:151], 0, s[0:1]
	global_store_short v[82:83], v84, off
	v_cvt_pk_bf16_f32 v84, v125, v125
	s_mov_b64 s[0:1], 0x261800
	v_and_b32_e32 v84, 0xffff, v84
	v_lshl_add_u64 v[82:83], v[150:151], 0, s[0:1]
	global_store_short v[82:83], v84, off
	v_cvt_pk_bf16_f32 v84, v126, v126
	s_mov_b64 s[0:1], 0x260020
	v_and_b32_e32 v84, 0xffff, v84
	v_lshl_add_u64 v[82:83], v[150:151], 0, s[0:1]
	global_store_short v[82:83], v84, off
	v_cvt_pk_bf16_f32 v84, v127, v127
	s_mov_b64 s[0:1], 0x260820
	v_and_b32_e32 v84, 0xffff, v84
	v_lshl_add_u64 v[82:83], v[150:151], 0, s[0:1]
	global_store_short v[82:83], v84, off
	v_cvt_pk_bf16_f32 v84, v128, v128
	s_mov_b64 s[0:1], 0x261020
	v_and_b32_e32 v84, 0xffff, v84
	v_lshl_add_u64 v[82:83], v[150:151], 0, s[0:1]
	global_store_short v[82:83], v84, off
	s_mov_b64 s[0:1], 0x261820
	v_cvt_pk_bf16_f32 v84, v129, v129
	v_lshl_add_u64 v[82:83], v[150:151], 0, s[0:1]
	v_and_b32_e32 v84, 0xffff, v84
	global_store_short v[82:83], v84, off
.LBB0_1787:
	s_waitcnt lgkmcnt(0)
	s_barrier
	ds_read_b128 v[82:85], v168
	ds_read_b128 v[98:101], v143
	ds_read_b128 v[122:125], v143 offset:4608
	ds_read_b128 v[178:181], v168 offset:64
	ds_read_b128 v[126:129], v143 offset:64
	ds_read_b128 v[182:185], v143 offset:4672
	ds_read_b128 v[186:189], v168 offset:128
	ds_read_b128 v[190:193], v143 offset:128
	ds_read_b128 v[206:209], v143 offset:4736
	ds_read_b128 v[210:213], v168 offset:192
	ds_read_b128 v[214:217], v143 offset:192
	ds_read_b128 v[218:221], v143 offset:4800
	s_and_b64 vcc, exec, s[48:49]
	s_waitcnt lgkmcnt(10)
	v_mfma_f32_16x16x32_bf16 v[98:101], v[82:85], v[98:101], 0
	s_waitcnt lgkmcnt(9)
	v_mfma_f32_16x16x32_bf16 v[82:85], v[82:85], v[122:125], 0
	s_nop 0
	s_nop 0
	s_waitcnt lgkmcnt(7)
	v_mfma_f32_16x16x32_bf16 v[98:101], v[178:181], v[126:129], v[98:101]
	s_nop 0
	s_waitcnt lgkmcnt(6)
	v_mfma_f32_16x16x32_bf16 v[82:85], v[178:181], v[182:185], v[82:85]
	s_nop 0
	s_nop 0
	s_waitcnt lgkmcnt(4)
	v_mfma_f32_16x16x32_bf16 v[98:101], v[186:189], v[190:193], v[98:101]
	s_nop 0
	s_waitcnt lgkmcnt(3)
	v_mfma_f32_16x16x32_bf16 v[82:85], v[186:189], v[206:209], v[82:85]
	s_nop 0
	s_nop 0
	s_waitcnt lgkmcnt(1)
	v_mfma_f32_16x16x32_bf16 v[126:129], v[210:213], v[214:217], v[98:101]
	s_nop 2
	s_nop 0
	s_waitcnt lgkmcnt(0)
	v_mfma_f32_16x16x32_bf16 v[130:133], v[210:213], v[218:221], v[82:85]
	s_cbranch_vccnz .LBB0_1789
	s_waitcnt vmcnt(28)
	s_nop 0
	v_sub_f32_e32 v83, v33, v129
	v_sub_f32_e32 v84, v32, v128
	v_sub_f32_e32 v82, v31, v127
	v_sub_f32_e32 v85, v30, v126
	v_cvt_pk_bf16_f32 v82, v85, v82
	v_cvt_pk_bf16_f32 v83, v84, v83
	s_waitcnt vmcnt(27)
	v_sub_f32_e32 v85, v9, v133
	v_sub_f32_e32 v98, v8, v132
	v_sub_f32_e32 v84, v7, v131
	v_sub_f32_e32 v99, v6, v130
	v_cvt_pk_bf16_f32 v84, v99, v84
	v_cvt_pk_bf16_f32 v85, v98, v85
	ds_write2st64_b64 v170, v[82:83], v[84:85] offset1:5

.LBB0_1791:
	s_andn2_b64 vcc, exec, s[8:9]
	s_cbranch_vccnz .LBB0_1793
	ds_read_b128 v[98:101], v169
	ds_read_b128 v[82:85], v169 offset:64
	ds_read_b128 v[122:125], v169 offset:2560
	ds_read_b128 v[134:137], v169 offset:2624
	s_waitcnt lgkmcnt(7)
	s_nop 0
	s_waitcnt lgkmcnt(6)
	s_nop 0
	s_waitcnt lgkmcnt(5)
	s_nop 0
	s_waitcnt lgkmcnt(4)
	s_nop 0
	s_waitcnt vmcnt(28) lgkmcnt(3)
	v_mfma_f32_16x16x32_bf16 v[126:129], v[30:33], v[98:101], v[126:129]
	s_waitcnt lgkmcnt(1)
	v_mfma_f32_16x16x32_bf16 v[30:33], v[30:33], v[122:125], v[130:133]
	s_waitcnt vmcnt(27)
	v_mfma_f32_16x16x32_bf16 v[126:129], v[6:9], v[82:85], v[126:129]
	s_waitcnt lgkmcnt(0)
	v_mfma_f32_16x16x32_bf16 v[130:133], v[6:9], v[134:137], v[30:33]
.LBB0_1793:
	ds_read_b128 v[178:181], v173 offset:36864
	ds_read_b128 v[182:185], v173 offset:36928
	s_waitcnt vmcnt(28)
	s_nop 2
	v_pk_mul_f32 v[32:33], v[140:141], v[116:117] op_sel_hi:[0,1]
	v_pk_mul_f32 v[30:31], v[140:141], v[114:115] op_sel_hi:[0,1]
	s_nop 0
	s_waitcnt vmcnt(27)
	v_pk_mul_f32 v[8:9], v[140:141], v[120:121] op_sel_hi:[0,1]
	v_pk_mul_f32 v[6:7], v[140:141], v[118:119] op_sel_hi:[0,1]
	s_or_b32 s0, s6, 0xc0
	s_ashr_i32 s1, s0, 31
	s_lshl_b64 s[8:9], s[0:1], 13
	s_lshl_b64 s[34:35], s[0:1], 14
	s_waitcnt lgkmcnt(1)
	v_mfma_f32_16x16x32_bf16 v[6:9], v[178:181], v[98:101], v[6:9]
	s_nop 0
	s_add_u32 s68, s95, s34
	s_addc_u32 s69, s3, s35
	v_mfma_f32_16x16x32_bf16 v[30:33], v[178:181], v[122:125], v[30:33]
	s_add_u32 s70, s29, s34
	s_addc_u32 s71, s94, s35
	s_add_u32 s34, s2, s34
	s_waitcnt lgkmcnt(0)
	v_mfma_f32_16x16x32_bf16 v[122:125], v[182:185], v[82:85], v[6:9]
	s_addc_u32 s35, s10, s35
	s_and_b64 vcc, exec, s[46:47]
	v_mfma_f32_16x16x32_bf16 v[118:121], v[182:185], v[134:137], v[30:33]
	s_nop 4
	v_cvt_pk_bf16_f32 v6, v122, v123
	v_cvt_pk_bf16_f32 v7, v124, v125
	s_nop 0
	v_cvt_pk_bf16_f32 v8, v118, v119
	v_cvt_pk_bf16_f32 v9, v120, v121
	ds_write2st64_b64 v172, v[6:7], v[8:9] offset1:9
	s_waitcnt vmcnt(26)
	ds_write_b128 v161, v[38:41] offset:57344
	s_waitcnt vmcnt(25)
	ds_write_b128 v163, v[54:57] offset:57344
	s_waitcnt vmcnt(24)
	ds_write_b128 v174, v[66:69] offset:57344
	s_waitcnt vmcnt(23)
	ds_write_b128 v165, v[70:73] offset:57344
	s_waitcnt vmcnt(22)
	ds_write_b128 v175, v[86:89]
	s_waitcnt vmcnt(21)
	ds_write_b128 v176, v[102:105]
	v_lshl_add_u64 v[6:7], s[68:69], 0, v[146:147]
	global_load_dwordx4 v[38:41], v[6:7], off
	v_lshl_add_u64 v[6:7], s[68:69], 0, v[148:149]
	global_load_dwordx4 v[54:57], v[6:7], off
	v_lshl_add_u64 v[6:7], s[70:71], 0, v[146:147]
	global_load_dwordx4 v[66:69], v[6:7], off
	v_lshl_add_u64 v[6:7], s[70:71], 0, v[148:149]
	global_load_dwordx4 v[82:85], v[6:7], off
	v_lshl_add_u64 v[6:7], s[34:35], 0, v[146:147]
	global_load_dwordx4 v[98:101], v[6:7], off
	v_lshl_add_u64 v[6:7], s[34:35], 0, v[148:149]
	s_lshl_b64 s[34:35], s[0:1], 15
	s_lshl_b64 s[0:1], s[0:1], 8
	v_lshl_add_u64 v[70:71], v[152:153], 0, s[0:1]
	global_load_dwordx4 v[114:117], v[6:7], off
	global_load_dword v164, v[70:71], off
	v_lshl_add_u64 v[6:7], v[156:157], 0, s[34:35]
	v_lshl_add_u64 v[8:9], v[154:155], 0, s[8:9]
	v_cndmask_b32_e64 v7, v9, v7, s[44:45]
	v_cndmask_b32_e64 v6, v8, v6, s[44:45]
	global_load_dwordx4 v[30:33], v[6:7], off
	v_lshl_add_u64 v[6:7], v[6:7], 0, s[60:61]
	global_load_dwordx4 v[6:9], v[6:7], off
	s_cbranch_vccnz .LBB0_1795
	v_cvt_pk_bf16_f32 v72, v126, v126
	s_mov_b64 s[0:1], 0x280000
	v_and_b32_e32 v72, 0xffff, v72
	v_lshl_add_u64 v[70:71], v[150:151], 0, s[0:1]
	global_store_short v[70:71], v72, off
	v_cvt_pk_bf16_f32 v72, v127, v127
	s_mov_b64 s[0:1], 0x280800
	v_and_b32_e32 v72, 0xffff, v72
	v_lshl_add_u64 v[70:71], v[150:151], 0, s[0:1]
	global_store_short v[70:71], v72, off
	v_cvt_pk_bf16_f32 v72, v128, v128
	s_mov_b64 s[0:1], 0x281000
	v_and_b32_e32 v72, 0xffff, v72
	v_lshl_add_u64 v[70:71], v[150:151], 0, s[0:1]
	global_store_short v[70:71], v72, off
	v_cvt_pk_bf16_f32 v72, v129, v129
	s_mov_b64 s[0:1], 0x281800
	v_and_b32_e32 v72, 0xffff, v72
	v_lshl_add_u64 v[70:71], v[150:151], 0, s[0:1]
	global_store_short v[70:71], v72, off
	v_cvt_pk_bf16_f32 v72, v130, v130
	s_mov_b64 s[0:1], 0x280020
	v_and_b32_e32 v72, 0xffff, v72
	v_lshl_add_u64 v[70:71], v[150:151], 0, s[0:1]
	global_store_short v[70:71], v72, off
	v_cvt_pk_bf16_f32 v72, v131, v131
	s_mov_b64 s[0:1], 0x280820
	v_and_b32_e32 v72, 0xffff, v72
	v_lshl_add_u64 v[70:71], v[150:151], 0, s[0:1]
	global_store_short v[70:71], v72, off
	v_cvt_pk_bf16_f32 v72, v132, v132
	s_mov_b64 s[0:1], 0x281020
	v_and_b32_e32 v72, 0xffff, v72
	v_lshl_add_u64 v[70:71], v[150:151], 0, s[0:1]
	global_store_short v[70:71], v72, off
	s_mov_b64 s[0:1], 0x281820
	v_cvt_pk_bf16_f32 v72, v133, v133
	v_lshl_add_u64 v[70:71], v[150:151], 0, s[0:1]
	v_and_b32_e32 v72, 0xffff, v72
	global_store_short v[70:71], v72, off
.LBB0_1795:
	s_waitcnt lgkmcnt(0)
	s_barrier
	ds_read_b128 v[70:73], v168 offset:57344
	ds_read_b128 v[86:89], v143
	ds_read_b128 v[102:105], v143 offset:4608
	ds_read_b128 v[178:181], v168 offset:57408
	ds_read_b128 v[126:129], v143 offset:64
	ds_read_b128 v[182:185], v143 offset:4672
	ds_read_b128 v[186:189], v168 offset:57472
	ds_read_b128 v[190:193], v143 offset:128
	ds_read_b128 v[206:209], v143 offset:4736
	ds_read_b128 v[210:213], v168 offset:57536
	ds_read_b128 v[214:217], v143 offset:192
	ds_read_b128 v[218:221], v143 offset:4800
	s_and_b64 vcc, exec, s[48:49]
	s_waitcnt lgkmcnt(10)
	v_mfma_f32_16x16x32_bf16 v[86:89], v[70:73], v[86:89], 0
	s_waitcnt lgkmcnt(9)
	v_mfma_f32_16x16x32_bf16 v[70:73], v[70:73], v[102:105], 0
	s_nop 0
	s_nop 0
	s_waitcnt lgkmcnt(7)
	v_mfma_f32_16x16x32_bf16 v[86:89], v[178:181], v[126:129], v[86:89]
	s_nop 0
	s_waitcnt lgkmcnt(6)
	v_mfma_f32_16x16x32_bf16 v[70:73], v[178:181], v[182:185], v[70:73]
	s_nop 0
	s_nop 0
	s_waitcnt lgkmcnt(4)
	v_mfma_f32_16x16x32_bf16 v[86:89], v[186:189], v[190:193], v[86:89]
	s_nop 0
	s_waitcnt lgkmcnt(3)
	v_mfma_f32_16x16x32_bf16 v[70:73], v[186:189], v[206:209], v[70:73]
	s_nop 0
	s_nop 0
	s_waitcnt lgkmcnt(1)
	v_mfma_f32_16x16x32_bf16 v[130:133], v[210:213], v[214:217], v[86:89]
	s_nop 2
	s_nop 0
	s_waitcnt lgkmcnt(0)
	v_mfma_f32_16x16x32_bf16 v[134:137], v[210:213], v[218:221], v[70:73]
	s_cbranch_vccnz .LBB0_1797
	s_waitcnt vmcnt(28)
	s_nop 0
	v_sub_f32_e32 v71, v21, v133
	v_sub_f32_e32 v72, v20, v132
	v_sub_f32_e32 v70, v19, v131
	v_sub_f32_e32 v73, v18, v130
	v_cvt_pk_bf16_f32 v70, v73, v70
	v_cvt_pk_bf16_f32 v71, v72, v71
	s_waitcnt vmcnt(27)
	v_sub_f32_e32 v73, v13, v137
	v_sub_f32_e32 v86, v12, v136
	v_sub_f32_e32 v72, v11, v135
	v_sub_f32_e32 v87, v10, v134
	v_cvt_pk_bf16_f32 v72, v87, v72
	v_cvt_pk_bf16_f32 v73, v86, v73
	ds_write2st64_b64 v170, v[70:71], v[72:73] offset1:5

.LBB0_1799:
	s_andn2_b64 vcc, exec, s[8:9]
	s_cbranch_vccnz .LBB0_1801
	ds_read_b128 v[86:89], v169
	ds_read_b128 v[70:73], v169 offset:64
	ds_read_b128 v[102:105], v169 offset:2560
	ds_read_b128 v[138:141], v169 offset:2624
	s_waitcnt lgkmcnt(7)
	s_nop 0
	s_waitcnt lgkmcnt(6)
	s_nop 0
	s_waitcnt lgkmcnt(5)
	s_nop 0
	s_waitcnt lgkmcnt(4)
	s_nop 0
	s_waitcnt vmcnt(28) lgkmcnt(3)
	v_mfma_f32_16x16x32_bf16 v[126:129], v[18:21], v[86:89], v[130:133]
	s_waitcnt lgkmcnt(1)
	v_mfma_f32_16x16x32_bf16 v[18:21], v[18:21], v[102:105], v[134:137]
	s_waitcnt vmcnt(27)
	v_mfma_f32_16x16x32_bf16 v[130:133], v[10:13], v[70:73], v[126:129]
	s_waitcnt lgkmcnt(0)
	v_mfma_f32_16x16x32_bf16 v[134:137], v[10:13], v[138:141], v[18:21]
.LBB0_1801:
	ds_read_b128 v[178:181], v177
	ds_read_b128 v[182:185], v177 offset:64
	s_waitcnt vmcnt(28)
	s_nop 2
	v_pk_mul_f32 v[20:21], v[158:159], v[120:121] op_sel_hi:[0,1]
	v_pk_mul_f32 v[18:19], v[158:159], v[118:119] op_sel_hi:[0,1]
	s_nop 0
	s_waitcnt vmcnt(27)
	v_pk_mul_f32 v[12:13], v[158:159], v[124:125] op_sel_hi:[0,1]
	v_pk_mul_f32 v[10:11], v[158:159], v[122:123] op_sel_hi:[0,1]
	s_or_b32 s0, s6, 0xc8
	s_ashr_i32 s1, s0, 31
	s_lshl_b64 s[8:9], s[0:1], 13
	s_lshl_b64 s[34:35], s[0:1], 14
	s_waitcnt lgkmcnt(1)
	v_mfma_f32_16x16x32_bf16 v[10:13], v[178:181], v[86:89], v[10:13]
	s_nop 0
	s_add_u32 s68, s95, s34
	s_addc_u32 s69, s3, s35
	v_mfma_f32_16x16x32_bf16 v[18:21], v[178:181], v[102:105], v[18:21]
	s_add_u32 s70, s29, s34
	s_addc_u32 s71, s94, s35
	s_add_u32 s34, s2, s34
	s_waitcnt lgkmcnt(0)
	v_mfma_f32_16x16x32_bf16 v[126:129], v[182:185], v[70:73], v[10:13]
	s_addc_u32 s35, s10, s35
	s_and_b64 vcc, exec, s[46:47]
	v_mfma_f32_16x16x32_bf16 v[122:125], v[182:185], v[138:141], v[18:21]
	s_nop 4
	v_cvt_pk_bf16_f32 v10, v126, v127
	v_cvt_pk_bf16_f32 v11, v128, v129
	s_nop 0
	v_cvt_pk_bf16_f32 v12, v122, v123
	v_cvt_pk_bf16_f32 v13, v124, v125
	ds_write2st64_b64 v172, v[10:11], v[12:13] offset1:9
	s_waitcnt vmcnt(26)
	ds_write_b128 v161, v[42:45]
	s_waitcnt vmcnt(25)
	ds_write_b128 v163, v[46:49]
	s_waitcnt vmcnt(24)
	ds_write_b128 v161, v[58:61] offset:18432
	s_waitcnt vmcnt(23)
	ds_write_b128 v165, v[74:77]
	s_waitcnt vmcnt(22)
	ds_write_b128 v166, v[90:93] offset:36864
	s_waitcnt vmcnt(21)
	ds_write_b128 v167, v[106:109] offset:36864
	v_lshl_add_u64 v[10:11], s[68:69], 0, v[146:147]
	global_load_dwordx4 v[42:45], v[10:11], off
	v_lshl_add_u64 v[10:11], s[68:69], 0, v[148:149]
	global_load_dwordx4 v[58:61], v[10:11], off
	v_lshl_add_u64 v[10:11], s[70:71], 0, v[146:147]
	global_load_dwordx4 v[70:73], v[10:11], off
	v_lshl_add_u64 v[10:11], s[70:71], 0, v[148:149]
	global_load_dwordx4 v[86:89], v[10:11], off
	v_lshl_add_u64 v[10:11], s[34:35], 0, v[146:147]
	global_load_dwordx4 v[102:105], v[10:11], off
	v_lshl_add_u64 v[10:11], s[34:35], 0, v[148:149]
	s_lshl_b64 s[34:35], s[0:1], 15
	s_lshl_b64 s[0:1], s[0:1], 8
	v_lshl_add_u64 v[46:47], v[152:153], 0, s[0:1]
	global_load_dwordx4 v[118:121], v[10:11], off
	global_load_dword v158, v[46:47], off
	v_lshl_add_u64 v[10:11], v[156:157], 0, s[34:35]
	v_lshl_add_u64 v[12:13], v[154:155], 0, s[8:9]
	v_cndmask_b32_e64 v11, v13, v11, s[44:45]
	v_cndmask_b32_e64 v10, v12, v10, s[44:45]
	global_load_dwordx4 v[18:21], v[10:11], off
	v_lshl_add_u64 v[10:11], v[10:11], 0, s[60:61]
	global_load_dwordx4 v[10:13], v[10:11], off
	s_cbranch_vccnz .LBB0_1803
	v_cvt_pk_bf16_f32 v48, v130, v130
	s_mov_b64 s[0:1], 0x2a0000
	v_and_b32_e32 v48, 0xffff, v48
	v_lshl_add_u64 v[46:47], v[150:151], 0, s[0:1]
	global_store_short v[46:47], v48, off
	v_cvt_pk_bf16_f32 v48, v131, v131
	s_mov_b64 s[0:1], 0x2a0800
	v_and_b32_e32 v48, 0xffff, v48
	v_lshl_add_u64 v[46:47], v[150:151], 0, s[0:1]
	global_store_short v[46:47], v48, off
	v_cvt_pk_bf16_f32 v48, v132, v132
	s_mov_b64 s[0:1], 0x2a1000
	v_and_b32_e32 v48, 0xffff, v48
	v_lshl_add_u64 v[46:47], v[150:151], 0, s[0:1]
	global_store_short v[46:47], v48, off
	v_cvt_pk_bf16_f32 v48, v133, v133
	s_mov_b64 s[0:1], 0x2a1800
	v_and_b32_e32 v48, 0xffff, v48
	v_lshl_add_u64 v[46:47], v[150:151], 0, s[0:1]
	global_store_short v[46:47], v48, off
	v_cvt_pk_bf16_f32 v48, v134, v134
	s_mov_b64 s[0:1], 0x2a0020
	v_and_b32_e32 v48, 0xffff, v48
	v_lshl_add_u64 v[46:47], v[150:151], 0, s[0:1]
	global_store_short v[46:47], v48, off
	v_cvt_pk_bf16_f32 v48, v135, v135
	s_mov_b64 s[0:1], 0x2a0820
	v_and_b32_e32 v48, 0xffff, v48
	v_lshl_add_u64 v[46:47], v[150:151], 0, s[0:1]
	global_store_short v[46:47], v48, off
	v_cvt_pk_bf16_f32 v48, v136, v136
	s_mov_b64 s[0:1], 0x2a1020
	v_and_b32_e32 v48, 0xffff, v48
	v_lshl_add_u64 v[46:47], v[150:151], 0, s[0:1]
	global_store_short v[46:47], v48, off
	s_mov_b64 s[0:1], 0x2a1820
	v_cvt_pk_bf16_f32 v48, v137, v137
	v_lshl_add_u64 v[46:47], v[150:151], 0, s[0:1]
	v_and_b32_e32 v48, 0xffff, v48
	global_store_short v[46:47], v48, off
.LBB0_1803:
	s_waitcnt lgkmcnt(0)
	s_barrier
	ds_read_b128 v[46:49], v168
	ds_read_b128 v[74:77], v143
	ds_read_b128 v[90:93], v143 offset:4608
	ds_read_b128 v[178:181], v168 offset:64
	ds_read_b128 v[106:109], v143 offset:64
	ds_read_b128 v[182:185], v143 offset:4672
	ds_read_b128 v[186:189], v168 offset:128
	ds_read_b128 v[190:193], v143 offset:128
	ds_read_b128 v[206:209], v143 offset:4736
	ds_read_b128 v[210:213], v168 offset:192
	ds_read_b128 v[214:217], v143 offset:192
	ds_read_b128 v[218:221], v143 offset:4800
	s_and_b64 vcc, exec, s[48:49]
	s_waitcnt lgkmcnt(10)
	v_mfma_f32_16x16x32_bf16 v[74:77], v[46:49], v[74:77], 0
	s_waitcnt lgkmcnt(9)
	v_mfma_f32_16x16x32_bf16 v[46:49], v[46:49], v[90:93], 0
	s_nop 0
	s_nop 0
	s_waitcnt lgkmcnt(7)
	v_mfma_f32_16x16x32_bf16 v[74:77], v[178:181], v[106:109], v[74:77]
	s_nop 0
	s_waitcnt lgkmcnt(6)
	v_mfma_f32_16x16x32_bf16 v[46:49], v[178:181], v[182:185], v[46:49]
	s_nop 0
	s_nop 0
	s_waitcnt lgkmcnt(4)
	v_mfma_f32_16x16x32_bf16 v[74:77], v[186:189], v[190:193], v[74:77]
	s_nop 0
	s_waitcnt lgkmcnt(3)
	v_mfma_f32_16x16x32_bf16 v[46:49], v[186:189], v[206:209], v[46:49]
	s_nop 0
	s_nop 0
	s_waitcnt lgkmcnt(1)
	v_mfma_f32_16x16x32_bf16 v[130:133], v[210:213], v[214:217], v[74:77]
	s_nop 2
	s_nop 0
	s_waitcnt lgkmcnt(0)
	v_mfma_f32_16x16x32_bf16 v[134:137], v[210:213], v[218:221], v[46:49]
	s_cbranch_vccnz .LBB0_1805
	s_waitcnt vmcnt(28)
	s_nop 0
	v_sub_f32_e32 v47, v25, v133
	v_sub_f32_e32 v48, v24, v132
	v_sub_f32_e32 v46, v23, v131
	v_sub_f32_e32 v49, v22, v130
	v_cvt_pk_bf16_f32 v46, v49, v46
	v_cvt_pk_bf16_f32 v47, v48, v47
	s_waitcnt vmcnt(27)
	v_sub_f32_e32 v49, v17, v137
	v_sub_f32_e32 v74, v16, v136
	v_sub_f32_e32 v48, v15, v135
	v_sub_f32_e32 v75, v14, v134
	v_cvt_pk_bf16_f32 v48, v75, v48
	v_cvt_pk_bf16_f32 v49, v74, v49
	ds_write2st64_b64 v170, v[46:47], v[48:49] offset1:5

.LBB0_1807:
	s_andn2_b64 vcc, exec, s[8:9]
	s_cbranch_vccnz .LBB0_1809
	ds_read_b128 v[74:77], v169
	ds_read_b128 v[46:49], v169 offset:64
	ds_read_b128 v[90:93], v169 offset:2560
	s_waitcnt lgkmcnt(6)
	s_nop 0
	s_waitcnt lgkmcnt(5)
	s_nop 0
	s_waitcnt lgkmcnt(4)
	s_nop 0
	s_waitcnt vmcnt(28) lgkmcnt(2)
	v_mfma_f32_16x16x32_bf16 v[106:109], v[22:25], v[74:77], v[130:133]
	s_waitcnt vmcnt(27) lgkmcnt(1)
	v_mfma_f32_16x16x32_bf16 v[130:133], v[14:17], v[46:49], v[106:109]
	ds_read_b128 v[106:109], v169 offset:2624
	s_nop 5
	s_nop 0
	s_waitcnt lgkmcnt(1)
	v_mfma_f32_16x16x32_bf16 v[22:25], v[22:25], v[90:93], v[134:137]
	s_waitcnt lgkmcnt(0)
	v_mfma_f32_16x16x32_bf16 v[134:137], v[14:17], v[106:109], v[22:25]
.LBB0_1809:
	ds_read_b128 v[178:181], v173 offset:36864
	ds_read_b128 v[182:185], v173 offset:36928
	s_waitcnt vmcnt(28)
	s_nop 4
	v_pk_mul_f32 v[24:25], v[160:161], v[124:125] op_sel_hi:[0,1]
	v_pk_mul_f32 v[22:23], v[160:161], v[122:123] op_sel_hi:[0,1]
	s_nop 0
	s_waitcnt vmcnt(27)
	v_pk_mul_f32 v[16:17], v[160:161], v[128:129] op_sel_hi:[0,1]
	v_pk_mul_f32 v[14:15], v[160:161], v[126:127] op_sel_hi:[0,1]
	s_or_b32 s0, s6, 0xd0
	s_ashr_i32 s1, s0, 31
	s_lshl_b64 s[8:9], s[0:1], 13
	s_lshl_b64 s[34:35], s[0:1], 14
	s_waitcnt lgkmcnt(1)
	v_mfma_f32_16x16x32_bf16 v[14:17], v[178:181], v[74:77], v[14:17]
	s_nop 0
	s_add_u32 s68, s95, s34
	s_addc_u32 s69, s3, s35
	v_mfma_f32_16x16x32_bf16 v[22:25], v[178:181], v[90:93], v[22:25]
	s_add_u32 s70, s29, s34
	s_addc_u32 s71, s94, s35
	s_add_u32 s34, s2, s34
	s_waitcnt lgkmcnt(0)
	v_mfma_f32_16x16x32_bf16 v[122:125], v[182:185], v[46:49], v[14:17]
	s_addc_u32 s35, s10, s35
	s_and_b64 vcc, exec, s[46:47]
	v_mfma_f32_16x16x32_bf16 v[46:49], v[182:185], v[106:109], v[22:25]
	s_nop 4
	v_cvt_pk_bf16_f32 v14, v122, v123
	v_cvt_pk_bf16_f32 v15, v124, v125
	s_nop 0
	v_cvt_pk_bf16_f32 v16, v46, v47
	v_cvt_pk_bf16_f32 v17, v48, v49
	ds_write2st64_b64 v172, v[14:15], v[16:17] offset1:9
	s_waitcnt vmcnt(26)
	ds_write_b128 v161, v[34:37] offset:57344
	s_waitcnt vmcnt(25)
	ds_write_b128 v163, v[50:53] offset:57344
	s_waitcnt vmcnt(24)
	ds_write_b128 v174, v[62:65] offset:57344
	s_waitcnt vmcnt(23)
	ds_write_b128 v165, v[78:81] offset:57344
	s_waitcnt vmcnt(22)
	ds_write_b128 v175, v[94:97]
	s_waitcnt vmcnt(21)
	ds_write_b128 v176, v[110:113]
	v_lshl_add_u64 v[14:15], s[68:69], 0, v[146:147]
	global_load_dwordx4 v[34:37], v[14:15], off
	v_lshl_add_u64 v[14:15], s[68:69], 0, v[148:149]
	global_load_dwordx4 v[62:65], v[14:15], off
	v_lshl_add_u64 v[14:15], s[70:71], 0, v[146:147]
	global_load_dwordx4 v[74:77], v[14:15], off
	v_lshl_add_u64 v[14:15], s[70:71], 0, v[148:149]
	global_load_dwordx4 v[90:93], v[14:15], off
	v_lshl_add_u64 v[14:15], s[34:35], 0, v[146:147]
	global_load_dwordx4 v[106:109], v[14:15], off
	v_lshl_add_u64 v[14:15], s[34:35], 0, v[148:149]
	s_lshl_b64 s[34:35], s[0:1], 15
	s_lshl_b64 s[0:1], s[0:1], 8
	v_lshl_add_u64 v[50:51], v[152:153], 0, s[0:1]
	global_load_dwordx4 v[110:113], v[14:15], off
	global_load_dword v160, v[50:51], off
	v_lshl_add_u64 v[14:15], v[156:157], 0, s[34:35]
	v_lshl_add_u64 v[16:17], v[154:155], 0, s[8:9]
	v_cndmask_b32_e64 v15, v17, v15, s[44:45]
	v_cndmask_b32_e64 v14, v16, v14, s[44:45]
	global_load_dwordx4 v[22:25], v[14:15], off
	v_lshl_add_u64 v[14:15], v[14:15], 0, s[60:61]
	global_load_dwordx4 v[14:17], v[14:15], off
	s_cbranch_vccnz .LBB0_1811
	v_cvt_pk_bf16_f32 v52, v130, v130
	s_mov_b64 s[0:1], 0x2c0000
	v_and_b32_e32 v52, 0xffff, v52
	v_lshl_add_u64 v[50:51], v[150:151], 0, s[0:1]
	global_store_short v[50:51], v52, off
	v_cvt_pk_bf16_f32 v52, v131, v131
	s_mov_b64 s[0:1], 0x2c0800
	v_and_b32_e32 v52, 0xffff, v52
	v_lshl_add_u64 v[50:51], v[150:151], 0, s[0:1]
	global_store_short v[50:51], v52, off
	v_cvt_pk_bf16_f32 v52, v132, v132
	s_mov_b64 s[0:1], 0x2c1000
	v_and_b32_e32 v52, 0xffff, v52
	v_lshl_add_u64 v[50:51], v[150:151], 0, s[0:1]
	global_store_short v[50:51], v52, off
	v_cvt_pk_bf16_f32 v52, v133, v133
	s_mov_b64 s[0:1], 0x2c1800
	v_and_b32_e32 v52, 0xffff, v52
	v_lshl_add_u64 v[50:51], v[150:151], 0, s[0:1]
	global_store_short v[50:51], v52, off
	v_cvt_pk_bf16_f32 v52, v134, v134
	s_mov_b64 s[0:1], 0x2c0020
	v_and_b32_e32 v52, 0xffff, v52
	v_lshl_add_u64 v[50:51], v[150:151], 0, s[0:1]
	global_store_short v[50:51], v52, off
	v_cvt_pk_bf16_f32 v52, v135, v135
	s_mov_b64 s[0:1], 0x2c0820
	v_and_b32_e32 v52, 0xffff, v52
	v_lshl_add_u64 v[50:51], v[150:151], 0, s[0:1]
	global_store_short v[50:51], v52, off
	v_cvt_pk_bf16_f32 v52, v136, v136
	s_mov_b64 s[0:1], 0x2c1020
	v_and_b32_e32 v52, 0xffff, v52
	v_lshl_add_u64 v[50:51], v[150:151], 0, s[0:1]
	global_store_short v[50:51], v52, off
	s_mov_b64 s[0:1], 0x2c1820
	v_cvt_pk_bf16_f32 v52, v137, v137
	v_lshl_add_u64 v[50:51], v[150:151], 0, s[0:1]
	v_and_b32_e32 v52, 0xffff, v52
	global_store_short v[50:51], v52, off
.LBB0_1811:
	s_waitcnt lgkmcnt(0)
	s_barrier
	ds_read_b128 v[50:53], v168 offset:57344
	ds_read_b128 v[78:81], v143
	ds_read_b128 v[94:97], v143 offset:4608
	ds_read_b128 v[178:181], v168 offset:57408
	ds_read_b128 v[126:129], v143 offset:64
	ds_read_b128 v[182:185], v143 offset:4672
	ds_read_b128 v[186:189], v168 offset:57472
	ds_read_b128 v[190:193], v143 offset:128
	ds_read_b128 v[206:209], v143 offset:4736
	ds_read_b128 v[210:213], v168 offset:57536
	ds_read_b128 v[214:217], v143 offset:192
	ds_read_b128 v[218:221], v143 offset:4800
	s_and_b64 vcc, exec, s[48:49]
	s_waitcnt lgkmcnt(10)
	v_mfma_f32_16x16x32_bf16 v[78:81], v[50:53], v[78:81], 0
	s_waitcnt lgkmcnt(9)
	v_mfma_f32_16x16x32_bf16 v[50:53], v[50:53], v[94:97], 0
	s_nop 0
	s_nop 0
	s_waitcnt lgkmcnt(7)
	v_mfma_f32_16x16x32_bf16 v[78:81], v[178:181], v[126:129], v[78:81]
	s_nop 0
	s_waitcnt lgkmcnt(6)
	v_mfma_f32_16x16x32_bf16 v[50:53], v[178:181], v[182:185], v[50:53]
	s_nop 0
	s_nop 0
	s_waitcnt lgkmcnt(4)
	v_mfma_f32_16x16x32_bf16 v[78:81], v[186:189], v[190:193], v[78:81]
	s_nop 0
	s_waitcnt lgkmcnt(3)
	v_mfma_f32_16x16x32_bf16 v[50:53], v[186:189], v[206:209], v[50:53]
	s_nop 0
	s_nop 0
	s_waitcnt lgkmcnt(1)
	v_mfma_f32_16x16x32_bf16 v[126:129], v[210:213], v[214:217], v[78:81]
	s_nop 2
	s_nop 0
	s_waitcnt lgkmcnt(0)
	v_mfma_f32_16x16x32_bf16 v[130:133], v[210:213], v[218:221], v[50:53]
	s_cbranch_vccnz .LBB0_1813
	s_waitcnt vmcnt(28)
	s_nop 0
	v_sub_f32_e32 v51, v29, v129
	v_sub_f32_e32 v52, v28, v128
	v_sub_f32_e32 v50, v27, v127
	v_sub_f32_e32 v53, v26, v126
	v_cvt_pk_bf16_f32 v50, v53, v50
	v_cvt_pk_bf16_f32 v51, v52, v51
	s_waitcnt vmcnt(27)
	v_sub_f32_e32 v53, v5, v133
	v_sub_f32_e32 v78, v4, v132
	v_sub_f32_e32 v52, v3, v131
	v_sub_f32_e32 v79, v2, v130
	v_cvt_pk_bf16_f32 v52, v79, v52
	v_cvt_pk_bf16_f32 v53, v78, v53
	ds_write2st64_b64 v170, v[50:51], v[52:53] offset1:5

.LBB0_1815:
	s_andn2_b64 vcc, exec, s[8:9]
	s_cbranch_vccnz .LBB0_1817
	ds_read_b128 v[78:81], v169
	ds_read_b128 v[50:53], v169 offset:64
	ds_read_b128 v[94:97], v169 offset:2560
	ds_read_b128 v[134:137], v169 offset:2624
	s_waitcnt lgkmcnt(7)
	s_nop 0
	s_waitcnt lgkmcnt(6)
	s_nop 0
	s_waitcnt lgkmcnt(5)
	s_nop 0
	s_waitcnt lgkmcnt(4)
	s_nop 0
	s_waitcnt vmcnt(28) lgkmcnt(3)
	v_mfma_f32_16x16x32_bf16 v[126:129], v[26:29], v[78:81], v[126:129]
	s_waitcnt lgkmcnt(1)
	v_mfma_f32_16x16x32_bf16 v[26:29], v[26:29], v[94:97], v[130:133]
	s_waitcnt vmcnt(27)
	v_mfma_f32_16x16x32_bf16 v[126:129], v[2:5], v[50:53], v[126:129]
	s_waitcnt lgkmcnt(0)
	v_mfma_f32_16x16x32_bf16 v[130:133], v[2:5], v[134:137], v[26:29]
.LBB0_1817:
	ds_read_b128 v[178:181], v177
	ds_read_b128 v[182:185], v177 offset:64
	s_waitcnt vmcnt(28)
	s_nop 2
	v_pk_mul_f32 v[28:29], v[162:163], v[48:49] op_sel_hi:[0,1]
	v_pk_mul_f32 v[26:27], v[162:163], v[46:47] op_sel_hi:[0,1]
	s_nop 0
	s_waitcnt vmcnt(27)
	v_pk_mul_f32 v[4:5], v[162:163], v[124:125] op_sel_hi:[0,1]
	v_pk_mul_f32 v[2:3], v[162:163], v[122:123] op_sel_hi:[0,1]
	s_or_b32 s0, s6, 0xd8
	s_ashr_i32 s1, s0, 31
	s_lshl_b64 s[8:9], s[0:1], 13
	s_lshl_b64 s[34:35], s[0:1], 14
	s_waitcnt lgkmcnt(1)
	v_mfma_f32_16x16x32_bf16 v[2:5], v[178:181], v[78:81], v[2:5]
	s_add_u32 s68, s95, s34
	s_addc_u32 s69, s3, s35
	s_add_u32 s70, s29, s34
	v_mfma_f32_16x16x32_bf16 v[26:29], v[178:181], v[94:97], v[26:29]
	s_nop 0
	s_addc_u32 s71, s94, s35
	s_add_u32 s34, s2, s34
	s_waitcnt lgkmcnt(0)
	v_mfma_f32_16x16x32_bf16 v[122:125], v[182:185], v[50:53], v[2:5]
	s_addc_u32 s35, s10, s35
	s_and_b64 vcc, exec, s[46:47]
	s_nop 5
	v_cvt_pk_bf16_f32 v2, v122, v123
	v_mfma_f32_16x16x32_bf16 v[50:53], v[182:185], v[134:137], v[26:29]
	v_cvt_pk_bf16_f32 v3, v124, v125
	s_nop 6
	v_cvt_pk_bf16_f32 v4, v50, v51
	v_cvt_pk_bf16_f32 v5, v52, v53
	ds_write2st64_b64 v172, v[2:3], v[4:5] offset1:9
	s_waitcnt vmcnt(26)
	ds_write_b128 v161, v[38:41]
	s_waitcnt vmcnt(25)
	ds_write_b128 v163, v[54:57]
	s_waitcnt vmcnt(24)
	ds_write_b128 v161, v[66:69] offset:18432
	s_waitcnt vmcnt(23)
	ds_write_b128 v165, v[82:85]
	s_waitcnt vmcnt(22)
	ds_write_b128 v166, v[98:101] offset:36864
	s_waitcnt vmcnt(21)
	ds_write_b128 v167, v[114:117] offset:36864
	v_lshl_add_u64 v[2:3], s[68:69], 0, v[146:147]
	global_load_dwordx4 v[46:49], v[2:3], off
	v_lshl_add_u64 v[2:3], s[68:69], 0, v[148:149]
	global_load_dwordx4 v[66:69], v[2:3], off
	v_lshl_add_u64 v[2:3], s[70:71], 0, v[146:147]
	global_load_dwordx4 v[78:81], v[2:3], off
	v_lshl_add_u64 v[2:3], s[70:71], 0, v[148:149]
	global_load_dwordx4 v[94:97], v[2:3], off
	v_lshl_add_u64 v[2:3], s[34:35], 0, v[146:147]
	global_load_dwordx4 v[98:101], v[2:3], off
	v_lshl_add_u64 v[2:3], s[34:35], 0, v[148:149]
	s_lshl_b64 s[34:35], s[0:1], 15
	s_lshl_b64 s[0:1], s[0:1], 8
	v_lshl_add_u64 v[38:39], v[152:153], 0, s[0:1]
	global_load_dwordx4 v[114:117], v[2:3], off
	global_load_dword v162, v[38:39], off
	v_lshl_add_u64 v[2:3], v[156:157], 0, s[34:35]
	v_lshl_add_u64 v[4:5], v[154:155], 0, s[8:9]
	v_cndmask_b32_e64 v3, v5, v3, s[44:45]
	v_cndmask_b32_e64 v2, v4, v2, s[44:45]
	global_load_dwordx4 v[26:29], v[2:3], off
	v_lshl_add_u64 v[2:3], v[2:3], 0, s[60:61]
	global_load_dwordx4 v[2:5], v[2:3], off
	s_cbranch_vccnz .LBB0_1819
	v_cvt_pk_bf16_f32 v40, v126, v126
	s_mov_b64 s[0:1], 0x2e0000
	v_and_b32_e32 v40, 0xffff, v40
	v_lshl_add_u64 v[38:39], v[150:151], 0, s[0:1]
	global_store_short v[38:39], v40, off
	v_cvt_pk_bf16_f32 v40, v127, v127
	s_mov_b64 s[0:1], 0x2e0800
	v_and_b32_e32 v40, 0xffff, v40
	v_lshl_add_u64 v[38:39], v[150:151], 0, s[0:1]
	global_store_short v[38:39], v40, off
	v_cvt_pk_bf16_f32 v40, v128, v128
	s_mov_b64 s[0:1], 0x2e1000
	v_and_b32_e32 v40, 0xffff, v40
	v_lshl_add_u64 v[38:39], v[150:151], 0, s[0:1]
	global_store_short v[38:39], v40, off
	v_cvt_pk_bf16_f32 v40, v129, v129
	s_mov_b64 s[0:1], 0x2e1800
	v_and_b32_e32 v40, 0xffff, v40
	v_lshl_add_u64 v[38:39], v[150:151], 0, s[0:1]
	global_store_short v[38:39], v40, off
	v_cvt_pk_bf16_f32 v40, v130, v130
	s_mov_b64 s[0:1], 0x2e0020
	v_and_b32_e32 v40, 0xffff, v40
	v_lshl_add_u64 v[38:39], v[150:151], 0, s[0:1]
	global_store_short v[38:39], v40, off
	v_cvt_pk_bf16_f32 v40, v131, v131
	s_mov_b64 s[0:1], 0x2e0820
	v_and_b32_e32 v40, 0xffff, v40
	v_lshl_add_u64 v[38:39], v[150:151], 0, s[0:1]
	global_store_short v[38:39], v40, off
	v_cvt_pk_bf16_f32 v40, v132, v132
	s_mov_b64 s[0:1], 0x2e1020
	v_and_b32_e32 v40, 0xffff, v40
	v_lshl_add_u64 v[38:39], v[150:151], 0, s[0:1]
	global_store_short v[38:39], v40, off
	s_mov_b64 s[0:1], 0x2e1820
	v_cvt_pk_bf16_f32 v40, v133, v133
	v_lshl_add_u64 v[38:39], v[150:151], 0, s[0:1]
	v_and_b32_e32 v40, 0xffff, v40
	global_store_short v[38:39], v40, off
.LBB0_1819:
	s_waitcnt lgkmcnt(0)
	s_barrier
	ds_read_b128 v[38:41], v168
	ds_read_b128 v[54:57], v143
	ds_read_b128 v[82:85], v143 offset:4608
	ds_read_b128 v[178:181], v168 offset:64
	ds_read_b128 v[126:129], v143 offset:64
	ds_read_b128 v[182:185], v143 offset:4672
	ds_read_b128 v[186:189], v168 offset:128
	ds_read_b128 v[190:193], v143 offset:128
	ds_read_b128 v[206:209], v143 offset:4736
	ds_read_b128 v[210:213], v168 offset:192
	ds_read_b128 v[214:217], v143 offset:192
	ds_read_b128 v[218:221], v143 offset:4800
	s_and_b64 vcc, exec, s[48:49]
	s_waitcnt lgkmcnt(10)
	v_mfma_f32_16x16x32_bf16 v[54:57], v[38:41], v[54:57], 0
	s_waitcnt lgkmcnt(9)
	v_mfma_f32_16x16x32_bf16 v[38:41], v[38:41], v[82:85], 0
	s_nop 0
	s_nop 0
	s_waitcnt lgkmcnt(7)
	v_mfma_f32_16x16x32_bf16 v[54:57], v[178:181], v[126:129], v[54:57]
	s_nop 0
	s_waitcnt lgkmcnt(6)
	v_mfma_f32_16x16x32_bf16 v[38:41], v[178:181], v[182:185], v[38:41]
	s_nop 0
	s_nop 0
	s_waitcnt lgkmcnt(4)
	v_mfma_f32_16x16x32_bf16 v[54:57], v[186:189], v[190:193], v[54:57]
	s_nop 0
	s_waitcnt lgkmcnt(3)
	v_mfma_f32_16x16x32_bf16 v[38:41], v[186:189], v[206:209], v[38:41]
	s_nop 0
	s_nop 0
	s_waitcnt lgkmcnt(1)
	v_mfma_f32_16x16x32_bf16 v[126:129], v[210:213], v[214:217], v[54:57]
	s_nop 2
	s_nop 0
	s_waitcnt lgkmcnt(0)
	v_mfma_f32_16x16x32_bf16 v[130:133], v[210:213], v[218:221], v[38:41]
	s_cbranch_vccnz .LBB0_1821
	s_waitcnt vmcnt(28)
	s_nop 0
	v_sub_f32_e32 v39, v33, v129
	v_sub_f32_e32 v40, v32, v128
	v_sub_f32_e32 v38, v31, v127
	v_sub_f32_e32 v41, v30, v126
	v_cvt_pk_bf16_f32 v38, v41, v38
	v_cvt_pk_bf16_f32 v39, v40, v39
	s_waitcnt vmcnt(27)
	v_sub_f32_e32 v41, v9, v133
	v_sub_f32_e32 v54, v8, v132
	v_sub_f32_e32 v40, v7, v131
	v_sub_f32_e32 v55, v6, v130
	v_cvt_pk_bf16_f32 v40, v55, v40
	v_cvt_pk_bf16_f32 v41, v54, v41
	ds_write2st64_b64 v170, v[38:39], v[40:41] offset1:5

.LBB0_1823:
	s_andn2_b64 vcc, exec, s[8:9]
	s_cbranch_vccnz .LBB0_1825
	ds_read_b128 v[54:57], v169
	ds_read_b128 v[38:41], v169 offset:64
	ds_read_b128 v[82:85], v169 offset:2560
	ds_read_b128 v[134:137], v169 offset:2624
	s_waitcnt lgkmcnt(7)
	s_nop 0
	s_waitcnt lgkmcnt(6)
	s_nop 0
	s_waitcnt lgkmcnt(5)
	s_nop 0
	s_waitcnt lgkmcnt(4)
	s_nop 0
	s_waitcnt vmcnt(28) lgkmcnt(3)
	v_mfma_f32_16x16x32_bf16 v[126:129], v[30:33], v[54:57], v[126:129]
	s_waitcnt lgkmcnt(1)
	v_mfma_f32_16x16x32_bf16 v[30:33], v[30:33], v[82:85], v[130:133]
	s_waitcnt vmcnt(27)
	v_mfma_f32_16x16x32_bf16 v[126:129], v[6:9], v[38:41], v[126:129]
	s_waitcnt lgkmcnt(0)
	v_mfma_f32_16x16x32_bf16 v[130:133], v[6:9], v[134:137], v[30:33]
.LBB0_1825:
	ds_read_b128 v[178:181], v173 offset:36864
	ds_read_b128 v[182:185], v173 offset:36928
	s_waitcnt vmcnt(28)
	s_nop 2
	v_pk_mul_f32 v[32:33], v[164:165], v[52:53] op_sel_hi:[0,1]
	v_pk_mul_f32 v[30:31], v[164:165], v[50:51] op_sel_hi:[0,1]
	s_nop 0
	s_waitcnt vmcnt(27)
	v_pk_mul_f32 v[8:9], v[164:165], v[124:125] op_sel_hi:[0,1]
	v_pk_mul_f32 v[6:7], v[164:165], v[122:123] op_sel_hi:[0,1]
	s_or_b32 s0, s6, 0xe0
	s_ashr_i32 s1, s0, 31
	s_lshl_b64 s[8:9], s[0:1], 13
	s_lshl_b64 s[34:35], s[0:1], 14
	s_waitcnt lgkmcnt(1)
	v_mfma_f32_16x16x32_bf16 v[6:9], v[178:181], v[54:57], v[6:9]
	s_add_u32 s68, s95, s34
	s_addc_u32 s69, s3, s35
	s_add_u32 s70, s29, s34
	v_mfma_f32_16x16x32_bf16 v[30:33], v[178:181], v[82:85], v[30:33]
	s_nop 0
	s_addc_u32 s71, s94, s35
	s_add_u32 s34, s2, s34
	s_waitcnt lgkmcnt(0)
	v_mfma_f32_16x16x32_bf16 v[54:57], v[182:185], v[38:41], v[6:9]
	s_addc_u32 s35, s10, s35
	s_and_b64 vcc, exec, s[46:47]
	s_nop 5
	v_cvt_pk_bf16_f32 v6, v54, v55
	v_mfma_f32_16x16x32_bf16 v[38:41], v[182:185], v[134:137], v[30:33]
	v_cvt_pk_bf16_f32 v7, v56, v57
	s_nop 6
	v_cvt_pk_bf16_f32 v8, v38, v39
	v_cvt_pk_bf16_f32 v9, v40, v41
	ds_write2st64_b64 v172, v[6:7], v[8:9] offset1:9
	s_waitcnt vmcnt(26)
	ds_write_b128 v161, v[42:45] offset:57344
	s_waitcnt vmcnt(25)
	ds_write_b128 v163, v[58:61] offset:57344
	s_waitcnt vmcnt(24)
	ds_write_b128 v174, v[70:73] offset:57344
	s_waitcnt vmcnt(23)
	ds_write_b128 v165, v[86:89] offset:57344
	s_waitcnt vmcnt(22)
	ds_write_b128 v175, v[102:105]
	s_waitcnt vmcnt(21)
	ds_write_b128 v176, v[118:121]
	v_lshl_add_u64 v[6:7], s[68:69], 0, v[146:147]
	global_load_dwordx4 v[50:53], v[6:7], off
	v_lshl_add_u64 v[6:7], s[68:69], 0, v[148:149]
	global_load_dwordx4 v[70:73], v[6:7], off
	v_lshl_add_u64 v[6:7], s[70:71], 0, v[146:147]
	global_load_dwordx4 v[82:85], v[6:7], off
	v_lshl_add_u64 v[6:7], s[70:71], 0, v[148:149]
	global_load_dwordx4 v[86:89], v[6:7], off
	v_lshl_add_u64 v[6:7], s[34:35], 0, v[146:147]
	global_load_dwordx4 v[102:105], v[6:7], off
	v_lshl_add_u64 v[6:7], s[34:35], 0, v[148:149]
	s_lshl_b64 s[34:35], s[0:1], 15
	s_lshl_b64 s[0:1], s[0:1], 8
	v_lshl_add_u64 v[42:43], v[152:153], 0, s[0:1]
	global_load_dwordx4 v[118:121], v[6:7], off
	global_load_dword v164, v[42:43], off
	v_lshl_add_u64 v[6:7], v[156:157], 0, s[34:35]
	v_lshl_add_u64 v[8:9], v[154:155], 0, s[8:9]
	v_cndmask_b32_e64 v7, v9, v7, s[44:45]
	v_cndmask_b32_e64 v6, v8, v6, s[44:45]
	global_load_dwordx4 v[30:33], v[6:7], off
	v_lshl_add_u64 v[6:7], v[6:7], 0, s[60:61]
	global_load_dwordx4 v[6:9], v[6:7], off
	s_cbranch_vccnz .LBB0_1827
	v_cvt_pk_bf16_f32 v44, v126, v126
	s_mov_b64 s[0:1], 0x300000
	v_and_b32_e32 v44, 0xffff, v44
	v_lshl_add_u64 v[42:43], v[150:151], 0, s[0:1]
	global_store_short v[42:43], v44, off
	v_cvt_pk_bf16_f32 v44, v127, v127
	s_mov_b64 s[0:1], 0x300800
	v_and_b32_e32 v44, 0xffff, v44
	v_lshl_add_u64 v[42:43], v[150:151], 0, s[0:1]
	global_store_short v[42:43], v44, off
	v_cvt_pk_bf16_f32 v44, v128, v128
	s_mov_b64 s[0:1], 0x301000
	v_and_b32_e32 v44, 0xffff, v44
	v_lshl_add_u64 v[42:43], v[150:151], 0, s[0:1]
	global_store_short v[42:43], v44, off
	v_cvt_pk_bf16_f32 v44, v129, v129
	s_mov_b64 s[0:1], 0x301800
	v_and_b32_e32 v44, 0xffff, v44
	v_lshl_add_u64 v[42:43], v[150:151], 0, s[0:1]
	global_store_short v[42:43], v44, off
	v_cvt_pk_bf16_f32 v44, v130, v130
	s_mov_b64 s[0:1], 0x300020
	v_and_b32_e32 v44, 0xffff, v44
	v_lshl_add_u64 v[42:43], v[150:151], 0, s[0:1]
	global_store_short v[42:43], v44, off
	v_cvt_pk_bf16_f32 v44, v131, v131
	s_mov_b64 s[0:1], 0x300820
	v_and_b32_e32 v44, 0xffff, v44
	v_lshl_add_u64 v[42:43], v[150:151], 0, s[0:1]
	global_store_short v[42:43], v44, off
	v_cvt_pk_bf16_f32 v44, v132, v132
	s_mov_b64 s[0:1], 0x301020
	v_and_b32_e32 v44, 0xffff, v44
	v_lshl_add_u64 v[42:43], v[150:151], 0, s[0:1]
	global_store_short v[42:43], v44, off
	s_mov_b64 s[0:1], 0x301820
	v_cvt_pk_bf16_f32 v44, v133, v133
	v_lshl_add_u64 v[42:43], v[150:151], 0, s[0:1]
	v_and_b32_e32 v44, 0xffff, v44
	global_store_short v[42:43], v44, off
.LBB0_1827:
	s_waitcnt lgkmcnt(0)
	s_barrier
	ds_read_b128 v[42:45], v168 offset:57344
	ds_read_b128 v[58:61], v143
	ds_read_b128 v[122:125], v143 offset:4608
	ds_read_b128 v[178:181], v168 offset:57408
	ds_read_b128 v[126:129], v143 offset:64
	ds_read_b128 v[182:185], v143 offset:4672
	ds_read_b128 v[186:189], v168 offset:57472
	ds_read_b128 v[190:193], v143 offset:128
	ds_read_b128 v[206:209], v143 offset:4736
	ds_read_b128 v[210:213], v168 offset:57536
	ds_read_b128 v[214:217], v143 offset:192
	ds_read_b128 v[218:221], v143 offset:4800
	s_and_b64 vcc, exec, s[48:49]
	s_waitcnt lgkmcnt(10)
	v_mfma_f32_16x16x32_bf16 v[58:61], v[42:45], v[58:61], 0
	s_waitcnt lgkmcnt(9)
	v_mfma_f32_16x16x32_bf16 v[42:45], v[42:45], v[122:125], 0
	s_nop 0
	s_nop 0
	s_waitcnt lgkmcnt(7)
	v_mfma_f32_16x16x32_bf16 v[58:61], v[178:181], v[126:129], v[58:61]
	s_nop 0
	s_waitcnt lgkmcnt(6)
	v_mfma_f32_16x16x32_bf16 v[42:45], v[178:181], v[182:185], v[42:45]
	s_nop 0
	s_nop 0
	s_waitcnt lgkmcnt(4)
	v_mfma_f32_16x16x32_bf16 v[58:61], v[186:189], v[190:193], v[58:61]
	s_nop 0
	s_waitcnt lgkmcnt(3)
	v_mfma_f32_16x16x32_bf16 v[42:45], v[186:189], v[206:209], v[42:45]
	s_nop 0
	s_nop 0
	s_waitcnt lgkmcnt(1)
	v_mfma_f32_16x16x32_bf16 v[130:133], v[210:213], v[214:217], v[58:61]
	s_nop 2
	s_nop 0
	s_waitcnt lgkmcnt(0)
	v_mfma_f32_16x16x32_bf16 v[134:137], v[210:213], v[218:221], v[42:45]
	s_cbranch_vccnz .LBB0_1829
	s_waitcnt vmcnt(28)
	s_nop 0
	v_sub_f32_e32 v43, v21, v133
	v_sub_f32_e32 v44, v20, v132
	v_sub_f32_e32 v42, v19, v131
	v_sub_f32_e32 v45, v18, v130
	v_cvt_pk_bf16_f32 v42, v45, v42
	v_cvt_pk_bf16_f32 v43, v44, v43
	s_waitcnt vmcnt(27)
	v_sub_f32_e32 v45, v13, v137
	v_sub_f32_e32 v58, v12, v136
	v_sub_f32_e32 v44, v11, v135
	v_sub_f32_e32 v59, v10, v134
	v_cvt_pk_bf16_f32 v44, v59, v44
	v_cvt_pk_bf16_f32 v45, v58, v45
	ds_write2st64_b64 v170, v[42:43], v[44:45] offset1:5

.LBB0_1831:
	s_andn2_b64 vcc, exec, s[8:9]
	s_cbranch_vccnz .LBB0_1833
	ds_read_b128 v[58:61], v169
	ds_read_b128 v[42:45], v169 offset:64
	ds_read_b128 v[122:125], v169 offset:2560
	ds_read_b128 v[138:141], v169 offset:2624
	s_waitcnt lgkmcnt(7)
	s_nop 0
	s_waitcnt lgkmcnt(6)
	s_nop 0
	s_waitcnt lgkmcnt(5)
	s_nop 0
	s_waitcnt lgkmcnt(4)
	s_nop 0
	s_waitcnt vmcnt(28) lgkmcnt(3)
	v_mfma_f32_16x16x32_bf16 v[126:129], v[18:21], v[58:61], v[130:133]
	s_waitcnt lgkmcnt(1)
	v_mfma_f32_16x16x32_bf16 v[18:21], v[18:21], v[122:125], v[134:137]
	s_waitcnt vmcnt(27)
	v_mfma_f32_16x16x32_bf16 v[130:133], v[10:13], v[42:45], v[126:129]
	s_waitcnt lgkmcnt(0)
	v_mfma_f32_16x16x32_bf16 v[134:137], v[10:13], v[138:141], v[18:21]
.LBB0_1833:
	ds_read_b128 v[178:181], v177
	ds_read_b128 v[182:185], v177 offset:64
	s_waitcnt vmcnt(28)
	s_nop 2
	v_pk_mul_f32 v[20:21], v[158:159], v[40:41] op_sel_hi:[0,1]
	v_pk_mul_f32 v[18:19], v[158:159], v[38:39] op_sel_hi:[0,1]
	s_nop 0
	s_waitcnt vmcnt(27)
	v_pk_mul_f32 v[12:13], v[158:159], v[56:57] op_sel_hi:[0,1]
	v_pk_mul_f32 v[10:11], v[158:159], v[54:55] op_sel_hi:[0,1]
	s_or_b32 s0, s6, 0xe8
	s_ashr_i32 s1, s0, 31
	s_lshl_b64 s[8:9], s[0:1], 13
	s_lshl_b64 s[34:35], s[0:1], 14
	s_waitcnt lgkmcnt(1)
	v_mfma_f32_16x16x32_bf16 v[10:13], v[178:181], v[58:61], v[10:13]
	s_add_u32 s68, s95, s34
	s_addc_u32 s69, s3, s35
	s_add_u32 s70, s29, s34
	v_mfma_f32_16x16x32_bf16 v[18:21], v[178:181], v[122:125], v[18:21]
	s_nop 0
	s_addc_u32 s71, s94, s35
	s_add_u32 s34, s2, s34
	s_waitcnt lgkmcnt(0)
	v_mfma_f32_16x16x32_bf16 v[126:129], v[182:185], v[42:45], v[10:13]
	s_addc_u32 s35, s10, s35
	s_and_b64 vcc, exec, s[46:47]
	s_nop 5
	v_cvt_pk_bf16_f32 v10, v126, v127
	v_mfma_f32_16x16x32_bf16 v[122:125], v[182:185], v[138:141], v[18:21]
	v_cvt_pk_bf16_f32 v11, v128, v129
	s_nop 6
	v_cvt_pk_bf16_f32 v12, v122, v123
	v_cvt_pk_bf16_f32 v13, v124, v125
	ds_write2st64_b64 v172, v[10:11], v[12:13] offset1:9
	s_waitcnt vmcnt(26)
	ds_write_b128 v161, v[34:37]
	s_waitcnt vmcnt(25)
	ds_write_b128 v163, v[62:65]
	s_waitcnt vmcnt(24)
	ds_write_b128 v161, v[74:77] offset:18432
	s_waitcnt vmcnt(23)
	ds_write_b128 v165, v[90:93]
	s_waitcnt vmcnt(22)
	ds_write_b128 v166, v[106:109] offset:36864
	s_waitcnt vmcnt(21)
	ds_write_b128 v167, v[110:113] offset:36864
	v_lshl_add_u64 v[10:11], s[68:69], 0, v[146:147]
	global_load_dwordx4 v[34:37], v[10:11], off
	v_lshl_add_u64 v[10:11], s[68:69], 0, v[148:149]
	global_load_dwordx4 v[38:41], v[10:11], off
	v_lshl_add_u64 v[10:11], s[70:71], 0, v[146:147]
	global_load_dwordx4 v[42:45], v[10:11], off
	v_lshl_add_u64 v[10:11], s[70:71], 0, v[148:149]
	global_load_dwordx4 v[54:57], v[10:11], off
	v_lshl_add_u64 v[10:11], s[34:35], 0, v[146:147]
	global_load_dwordx4 v[58:61], v[10:11], off
	v_lshl_add_u64 v[10:11], s[34:35], 0, v[148:149]
	s_lshl_b64 s[34:35], s[0:1], 15
	s_lshl_b64 s[0:1], s[0:1], 8
	v_lshl_add_u64 v[74:75], v[152:153], 0, s[0:1]
	global_load_dwordx4 v[62:65], v[10:11], off
	global_load_dword v158, v[74:75], off
	v_lshl_add_u64 v[10:11], v[156:157], 0, s[34:35]
	v_lshl_add_u64 v[12:13], v[154:155], 0, s[8:9]
	v_cndmask_b32_e64 v11, v13, v11, s[44:45]
	v_cndmask_b32_e64 v10, v12, v10, s[44:45]
	global_load_dwordx4 v[18:21], v[10:11], off
	v_lshl_add_u64 v[10:11], v[10:11], 0, s[60:61]
	global_load_dwordx4 v[10:13], v[10:11], off
	s_cbranch_vccnz .LBB0_1835
	v_cvt_pk_bf16_f32 v76, v130, v130
	s_mov_b64 s[0:1], 0x320000
	v_and_b32_e32 v76, 0xffff, v76
	v_lshl_add_u64 v[74:75], v[150:151], 0, s[0:1]
	global_store_short v[74:75], v76, off
	v_cvt_pk_bf16_f32 v76, v131, v131
	s_mov_b64 s[0:1], 0x320800
	v_and_b32_e32 v76, 0xffff, v76
	v_lshl_add_u64 v[74:75], v[150:151], 0, s[0:1]
	global_store_short v[74:75], v76, off
	v_cvt_pk_bf16_f32 v76, v132, v132
	s_mov_b64 s[0:1], 0x321000
	v_and_b32_e32 v76, 0xffff, v76
	v_lshl_add_u64 v[74:75], v[150:151], 0, s[0:1]
	global_store_short v[74:75], v76, off
	v_cvt_pk_bf16_f32 v76, v133, v133
	s_mov_b64 s[0:1], 0x321800
	v_and_b32_e32 v76, 0xffff, v76
	v_lshl_add_u64 v[74:75], v[150:151], 0, s[0:1]
	global_store_short v[74:75], v76, off
	v_cvt_pk_bf16_f32 v76, v134, v134
	s_mov_b64 s[0:1], 0x320020
	v_and_b32_e32 v76, 0xffff, v76
	v_lshl_add_u64 v[74:75], v[150:151], 0, s[0:1]
	global_store_short v[74:75], v76, off
	v_cvt_pk_bf16_f32 v76, v135, v135
	s_mov_b64 s[0:1], 0x320820
	v_and_b32_e32 v76, 0xffff, v76
	v_lshl_add_u64 v[74:75], v[150:151], 0, s[0:1]
	global_store_short v[74:75], v76, off
	v_cvt_pk_bf16_f32 v76, v136, v136
	s_mov_b64 s[0:1], 0x321020
	v_and_b32_e32 v76, 0xffff, v76
	v_lshl_add_u64 v[74:75], v[150:151], 0, s[0:1]
	global_store_short v[74:75], v76, off
	s_mov_b64 s[0:1], 0x321820
	v_cvt_pk_bf16_f32 v76, v137, v137
	v_lshl_add_u64 v[74:75], v[150:151], 0, s[0:1]
	v_and_b32_e32 v76, 0xffff, v76
	global_store_short v[74:75], v76, off
.LBB0_1835:
	s_waitcnt lgkmcnt(0)
	s_barrier
	ds_read_b128 v[74:77], v168
	ds_read_b128 v[90:93], v143
	ds_read_b128 v[106:109], v143 offset:4608
	ds_read_b128 v[178:181], v168 offset:64
	ds_read_b128 v[110:113], v143 offset:64
	ds_read_b128 v[182:185], v143 offset:4672
	ds_read_b128 v[186:189], v168 offset:128
	ds_read_b128 v[190:193], v143 offset:128
	ds_read_b128 v[206:209], v143 offset:4736
	ds_read_b128 v[210:213], v168 offset:192
	ds_read_b128 v[214:217], v143 offset:192
	ds_read_b128 v[218:221], v143 offset:4800
	s_and_b64 vcc, exec, s[48:49]
	s_waitcnt lgkmcnt(10)
	v_mfma_f32_16x16x32_bf16 v[90:93], v[74:77], v[90:93], 0
	s_waitcnt lgkmcnt(9)
	v_mfma_f32_16x16x32_bf16 v[74:77], v[74:77], v[106:109], 0
	s_nop 0
	s_nop 0
	s_waitcnt lgkmcnt(7)
	v_mfma_f32_16x16x32_bf16 v[90:93], v[178:181], v[110:113], v[90:93]
	s_nop 0
	s_waitcnt lgkmcnt(6)
	v_mfma_f32_16x16x32_bf16 v[74:77], v[178:181], v[182:185], v[74:77]
	s_nop 0
	s_nop 0
	s_waitcnt lgkmcnt(4)
	v_mfma_f32_16x16x32_bf16 v[90:93], v[186:189], v[190:193], v[90:93]
	s_nop 0
	s_waitcnt lgkmcnt(3)
	v_mfma_f32_16x16x32_bf16 v[74:77], v[186:189], v[206:209], v[74:77]
	s_nop 0
	s_nop 0
	s_waitcnt lgkmcnt(1)
	v_mfma_f32_16x16x32_bf16 v[130:133], v[210:213], v[214:217], v[90:93]
	s_nop 2
	s_nop 0
	s_waitcnt lgkmcnt(0)
	v_mfma_f32_16x16x32_bf16 v[134:137], v[210:213], v[218:221], v[74:77]
	s_cbranch_vccnz .LBB0_1837
	s_waitcnt vmcnt(28)
	s_nop 0
	v_sub_f32_e32 v75, v25, v133
	v_sub_f32_e32 v76, v24, v132
	v_sub_f32_e32 v74, v23, v131
	v_sub_f32_e32 v77, v22, v130
	v_cvt_pk_bf16_f32 v74, v77, v74
	v_cvt_pk_bf16_f32 v75, v76, v75
	s_waitcnt vmcnt(27)
	v_sub_f32_e32 v77, v17, v137
	v_sub_f32_e32 v90, v16, v136
	v_sub_f32_e32 v76, v15, v135
	v_sub_f32_e32 v91, v14, v134
	v_cvt_pk_bf16_f32 v76, v91, v76
	v_cvt_pk_bf16_f32 v77, v90, v77
	ds_write2st64_b64 v170, v[74:75], v[76:77] offset1:5

.LBB0_1839:
	s_andn2_b64 vcc, exec, s[8:9]
	s_cbranch_vccnz .LBB0_1841
	ds_read_b128 v[90:93], v169
	ds_read_b128 v[74:77], v169 offset:64
	ds_read_b128 v[106:109], v169 offset:2560
	ds_read_b128 v[138:141], v169 offset:2624
	s_waitcnt lgkmcnt(7)
	s_nop 0
	s_waitcnt lgkmcnt(6)
	s_nop 0
	s_waitcnt lgkmcnt(5)
	s_nop 0
	s_waitcnt lgkmcnt(4)
	s_nop 0
	s_waitcnt vmcnt(28) lgkmcnt(3)
	v_mfma_f32_16x16x32_bf16 v[110:113], v[22:25], v[90:93], v[130:133]
	s_waitcnt lgkmcnt(1)
	v_mfma_f32_16x16x32_bf16 v[22:25], v[22:25], v[106:109], v[134:137]
	s_waitcnt vmcnt(27)
	v_mfma_f32_16x16x32_bf16 v[130:133], v[14:17], v[74:77], v[110:113]
	s_waitcnt lgkmcnt(0)
	v_mfma_f32_16x16x32_bf16 v[134:137], v[14:17], v[138:141], v[22:25]
.LBB0_1841:
	ds_read_b128 v[110:113], v173 offset:36864
	ds_read_b128 v[178:181], v173 offset:36928
	s_nop 1
	s_nop 0
	s_waitcnt vmcnt(27)
	v_pk_mul_f32 v[16:17], v[160:161], v[128:129] op_sel_hi:[0,1]
	v_pk_mul_f32 v[14:15], v[160:161], v[126:127] op_sel_hi:[0,1]
	v_pk_mul_f32 v[24:25], v[160:161], v[124:125] op_sel_hi:[0,1]
	v_pk_mul_f32 v[22:23], v[160:161], v[122:123] op_sel_hi:[0,1]
	s_or_b32 s0, s6, 0xf0
	s_ashr_i32 s1, s0, 31
	s_lshl_b64 s[8:9], s[0:1], 13
	s_lshl_b64 s[34:35], s[0:1], 14
	s_waitcnt lgkmcnt(1)
	v_mfma_f32_16x16x32_bf16 v[14:17], v[110:113], v[90:93], v[14:17]
	s_nop 0
	s_add_u32 s68, s95, s34
	s_addc_u32 s69, s3, s35
	v_mfma_f32_16x16x32_bf16 v[22:25], v[110:113], v[106:109], v[22:25]
	s_add_u32 s70, s29, s34
	s_addc_u32 s71, s94, s35
	s_add_u32 s34, s2, s34
	s_addc_u32 s35, s10, s35
	s_waitcnt lgkmcnt(0)
	v_mfma_f32_16x16x32_bf16 v[110:113], v[178:181], v[74:77], v[14:17]
	s_and_b64 vcc, exec, s[46:47]
	v_mfma_f32_16x16x32_bf16 v[106:109], v[178:181], v[138:141], v[22:25]
	s_nop 5
	v_cvt_pk_bf16_f32 v14, v110, v111
	v_cvt_pk_bf16_f32 v15, v112, v113
	v_cvt_pk_bf16_f32 v16, v106, v107
	v_cvt_pk_bf16_f32 v17, v108, v109
	ds_write2st64_b64 v172, v[14:15], v[16:17] offset1:9
	s_waitcnt vmcnt(26)
	ds_write_b128 v161, v[46:49] offset:57344
	s_waitcnt vmcnt(25)
	ds_write_b128 v163, v[66:69] offset:57344
	s_waitcnt vmcnt(24)
	ds_write_b128 v174, v[78:81] offset:57344
	s_waitcnt vmcnt(23)
	ds_write_b128 v165, v[94:97] offset:57344
	s_waitcnt vmcnt(22)
	ds_write_b128 v175, v[98:101]
	s_waitcnt vmcnt(21)
	ds_write_b128 v176, v[114:117]
	v_lshl_add_u64 v[14:15], s[68:69], 0, v[146:147]
	global_load_dwordx4 v[46:49], v[14:15], off
	v_lshl_add_u64 v[14:15], s[68:69], 0, v[148:149]
	global_load_dwordx4 v[66:69], v[14:15], off
	v_lshl_add_u64 v[14:15], s[70:71], 0, v[146:147]
	global_load_dwordx4 v[74:77], v[14:15], off
	v_lshl_add_u64 v[14:15], s[70:71], 0, v[148:149]
	global_load_dwordx4 v[78:81], v[14:15], off
	v_lshl_add_u64 v[14:15], s[34:35], 0, v[146:147]
	global_load_dwordx4 v[90:93], v[14:15], off
	v_lshl_add_u64 v[14:15], s[34:35], 0, v[148:149]
	s_lshl_b64 s[34:35], s[0:1], 15
	s_lshl_b64 s[0:1], s[0:1], 8
	v_lshl_add_u64 v[98:99], v[152:153], 0, s[0:1]
	global_load_dwordx4 v[94:97], v[14:15], off
	global_load_dword v138, v[98:99], off
	v_lshl_add_u64 v[14:15], v[156:157], 0, s[34:35]
	v_lshl_add_u64 v[16:17], v[154:155], 0, s[8:9]
	v_cndmask_b32_e64 v15, v17, v15, s[44:45]
	v_cndmask_b32_e64 v14, v16, v14, s[44:45]
	global_load_dwordx4 v[22:25], v[14:15], off
	v_lshl_add_u64 v[14:15], v[14:15], 0, s[60:61]
	global_load_dwordx4 v[14:17], v[14:15], off
	s_cbranch_vccnz .LBB0_1843
	v_cvt_pk_bf16_f32 v100, v130, v130
	s_mov_b64 s[0:1], 0x340000
	v_and_b32_e32 v100, 0xffff, v100
	v_lshl_add_u64 v[98:99], v[150:151], 0, s[0:1]
	global_store_short v[98:99], v100, off
	v_cvt_pk_bf16_f32 v100, v131, v131
	s_mov_b64 s[0:1], 0x340800
	v_and_b32_e32 v100, 0xffff, v100
	v_lshl_add_u64 v[98:99], v[150:151], 0, s[0:1]
	global_store_short v[98:99], v100, off
	v_cvt_pk_bf16_f32 v100, v132, v132
	s_mov_b64 s[0:1], 0x341000
	v_and_b32_e32 v100, 0xffff, v100
	v_lshl_add_u64 v[98:99], v[150:151], 0, s[0:1]
	global_store_short v[98:99], v100, off
	v_cvt_pk_bf16_f32 v100, v133, v133
	s_mov_b64 s[0:1], 0x341800
	v_and_b32_e32 v100, 0xffff, v100
	v_lshl_add_u64 v[98:99], v[150:151], 0, s[0:1]
	global_store_short v[98:99], v100, off
	v_cvt_pk_bf16_f32 v100, v134, v134
	s_mov_b64 s[0:1], 0x340020
	v_and_b32_e32 v100, 0xffff, v100
	v_lshl_add_u64 v[98:99], v[150:151], 0, s[0:1]
	global_store_short v[98:99], v100, off
	v_cvt_pk_bf16_f32 v100, v135, v135
	s_mov_b64 s[0:1], 0x340820
	v_and_b32_e32 v100, 0xffff, v100
	v_lshl_add_u64 v[98:99], v[150:151], 0, s[0:1]
	global_store_short v[98:99], v100, off
	v_cvt_pk_bf16_f32 v100, v136, v136
	s_mov_b64 s[0:1], 0x341020
	v_and_b32_e32 v100, 0xffff, v100
	v_lshl_add_u64 v[98:99], v[150:151], 0, s[0:1]
	global_store_short v[98:99], v100, off
	s_mov_b64 s[0:1], 0x341820
	v_cvt_pk_bf16_f32 v100, v137, v137
	v_lshl_add_u64 v[98:99], v[150:151], 0, s[0:1]
	v_and_b32_e32 v100, 0xffff, v100
	global_store_short v[98:99], v100, off
.LBB0_1843:
	s_waitcnt lgkmcnt(0)
	s_barrier
	ds_read_b128 v[98:101], v168 offset:57344
	ds_read_b128 v[114:117], v143
	ds_read_b128 v[122:125], v143 offset:4608
	ds_read_b128 v[178:181], v168 offset:57408
	ds_read_b128 v[126:129], v143 offset:64
	ds_read_b128 v[182:185], v143 offset:4672
	ds_read_b128 v[186:189], v168 offset:57472
	ds_read_b128 v[190:193], v143 offset:128
	ds_read_b128 v[206:209], v143 offset:4736
	ds_read_b128 v[210:213], v168 offset:57536
	ds_read_b128 v[214:217], v143 offset:192
	ds_read_b128 v[218:221], v143 offset:4800
	s_and_b64 vcc, exec, s[48:49]
	s_waitcnt lgkmcnt(10)
	v_mfma_f32_16x16x32_bf16 v[114:117], v[98:101], v[114:117], 0
	s_waitcnt lgkmcnt(9)
	v_mfma_f32_16x16x32_bf16 v[98:101], v[98:101], v[122:125], 0
	s_nop 0
	s_nop 0
	s_waitcnt lgkmcnt(7)
	v_mfma_f32_16x16x32_bf16 v[114:117], v[178:181], v[126:129], v[114:117]
	s_nop 0
	s_waitcnt lgkmcnt(6)
	v_mfma_f32_16x16x32_bf16 v[98:101], v[178:181], v[182:185], v[98:101]
	s_nop 0
	s_nop 0
	s_waitcnt lgkmcnt(4)
	v_mfma_f32_16x16x32_bf16 v[114:117], v[186:189], v[190:193], v[114:117]
	s_nop 0
	s_waitcnt lgkmcnt(3)
	v_mfma_f32_16x16x32_bf16 v[98:101], v[186:189], v[206:209], v[98:101]
	s_nop 0
	s_nop 0
	s_waitcnt lgkmcnt(1)
	v_mfma_f32_16x16x32_bf16 v[114:117], v[210:213], v[214:217], v[114:117]
	s_nop 0
	s_waitcnt lgkmcnt(0)
	v_mfma_f32_16x16x32_bf16 v[122:125], v[210:213], v[218:221], v[98:101]
	s_cbranch_vccnz .LBB0_1845
	s_waitcnt vmcnt(28)
	s_nop 2
	v_sub_f32_e32 v99, v29, v117
	v_sub_f32_e32 v100, v28, v116
	v_sub_f32_e32 v98, v27, v115
	v_sub_f32_e32 v101, v26, v114
	v_cvt_pk_bf16_f32 v98, v101, v98
	v_cvt_pk_bf16_f32 v99, v100, v99
	s_waitcnt vmcnt(27)
	v_sub_f32_e32 v101, v5, v125
	v_sub_f32_e32 v126, v4, v124
	v_sub_f32_e32 v100, v3, v123
	v_sub_f32_e32 v127, v2, v122
	v_cvt_pk_bf16_f32 v100, v127, v100
	v_cvt_pk_bf16_f32 v101, v126, v101
	ds_write2st64_b64 v170, v[98:99], v[100:101] offset1:5

.LBB0_1847:
	s_andn2_b64 vcc, exec, s[8:9]
	s_cbranch_vccnz .LBB0_1849
	ds_read_b128 v[126:129], v169
	ds_read_b128 v[98:101], v169 offset:64
	ds_read_b128 v[130:133], v169 offset:2560
	ds_read_b128 v[134:137], v169 offset:2624
	s_waitcnt lgkmcnt(7)
	s_nop 0
	s_waitcnt lgkmcnt(6)
	s_nop 0
	s_waitcnt lgkmcnt(5)
	s_nop 0
	s_waitcnt lgkmcnt(4)
	s_nop 0
	s_waitcnt vmcnt(28) lgkmcnt(3)
	v_mfma_f32_16x16x32_bf16 v[114:117], v[26:29], v[126:129], v[114:117]
	s_waitcnt lgkmcnt(1)
	v_mfma_f32_16x16x32_bf16 v[26:29], v[26:29], v[130:133], v[122:125]
	s_waitcnt vmcnt(27)
	v_mfma_f32_16x16x32_bf16 v[114:117], v[2:5], v[98:101], v[114:117]
	s_waitcnt lgkmcnt(0)
	v_mfma_f32_16x16x32_bf16 v[122:125], v[2:5], v[134:137], v[26:29]
.LBB0_1849:
	ds_read_b128 v[178:181], v177
	ds_read_b128 v[182:185], v177 offset:64
	s_waitcnt vmcnt(28)
	s_nop 2
	v_pk_mul_f32 v[28:29], v[162:163], v[108:109] op_sel_hi:[0,1]
	v_pk_mul_f32 v[26:27], v[162:163], v[106:107] op_sel_hi:[0,1]
	s_nop 0
	s_waitcnt vmcnt(27)
	v_pk_mul_f32 v[4:5], v[162:163], v[112:113] op_sel_hi:[0,1]
	v_pk_mul_f32 v[2:3], v[162:163], v[110:111] op_sel_hi:[0,1]
	s_or_b32 s0, s6, 0xf8
	s_ashr_i32 s1, s0, 31
	s_lshl_b64 s[6:7], s[0:1], 13
	s_lshl_b64 s[8:9], s[0:1], 14
	s_waitcnt lgkmcnt(1)
	v_mfma_f32_16x16x32_bf16 v[2:5], v[178:181], v[126:129], v[2:5]
	s_add_u32 s34, s95, s8
	s_addc_u32 s35, s3, s9
	s_add_u32 s68, s29, s8
	v_mfma_f32_16x16x32_bf16 v[26:29], v[178:181], v[130:133], v[26:29]
	s_nop 0
	s_addc_u32 s69, s94, s9
	s_add_u32 s8, s2, s8
	s_waitcnt lgkmcnt(0)
	v_mfma_f32_16x16x32_bf16 v[110:113], v[182:185], v[98:101], v[2:5]
	s_addc_u32 s9, s10, s9
	s_and_b64 vcc, exec, s[46:47]
	s_nop 5
	v_cvt_pk_bf16_f32 v2, v110, v111
	v_mfma_f32_16x16x32_bf16 v[106:109], v[182:185], v[134:137], v[26:29]
	v_cvt_pk_bf16_f32 v3, v112, v113
	s_nop 6
	v_cvt_pk_bf16_f32 v4, v106, v107
	v_cvt_pk_bf16_f32 v5, v108, v109
	ds_write2st64_b64 v172, v[2:3], v[4:5] offset1:9
	s_waitcnt vmcnt(26)
	ds_write_b128 v161, v[50:53]
	s_waitcnt vmcnt(25)
	ds_write_b128 v163, v[70:73]
	s_waitcnt vmcnt(24)
	ds_write_b128 v161, v[82:85] offset:18432
	s_waitcnt vmcnt(23)
	ds_write_b128 v165, v[86:89]
	s_waitcnt vmcnt(22)
	ds_write_b128 v166, v[102:105] offset:36864
	s_waitcnt vmcnt(21)
	ds_write_b128 v167, v[118:121] offset:36864
	v_lshl_add_u64 v[2:3], s[34:35], 0, v[146:147]
	global_load_dwordx4 v[50:53], v[2:3], off
	v_lshl_add_u64 v[2:3], s[34:35], 0, v[148:149]
	global_load_dwordx4 v[70:73], v[2:3], off
	v_lshl_add_u64 v[2:3], s[68:69], 0, v[146:147]
	global_load_dwordx4 v[82:85], v[2:3], off
	v_lshl_add_u64 v[2:3], s[68:69], 0, v[148:149]
	global_load_dwordx4 v[86:89], v[2:3], off
	v_lshl_add_u64 v[2:3], s[8:9], 0, v[146:147]
	global_load_dwordx4 v[98:101], v[2:3], off
	v_lshl_add_u64 v[2:3], s[8:9], 0, v[148:149]
	s_lshl_b64 s[8:9], s[0:1], 15
	s_lshl_b64 s[0:1], s[0:1], 8
	v_lshl_add_u64 v[118:119], v[152:153], 0, s[0:1]
	global_load_dwordx4 v[102:105], v[2:3], off
	global_load_dword v140, v[118:119], off
	v_lshl_add_u64 v[2:3], v[156:157], 0, s[8:9]
	v_lshl_add_u64 v[4:5], v[154:155], 0, s[6:7]
	v_cndmask_b32_e64 v3, v5, v3, s[44:45]
	v_cndmask_b32_e64 v2, v4, v2, s[44:45]
	global_load_dwordx4 v[26:29], v[2:3], off
	v_lshl_add_u64 v[2:3], v[2:3], 0, s[60:61]
	global_load_dwordx4 v[2:5], v[2:3], off
	s_cbranch_vccnz .LBB0_1851
	v_cvt_pk_bf16_f32 v114, v114, v114
	s_mov_b64 s[0:1], 0x360000
	v_and_b32_e32 v114, 0xffff, v114
	v_lshl_add_u64 v[118:119], v[150:151], 0, s[0:1]
	global_store_short v[118:119], v114, off
	s_mov_b64 s[0:1], 0x360800
	v_cvt_pk_bf16_f32 v114, v115, v115
	v_cvt_pk_bf16_f32 v116, v116, v116
	v_lshl_add_u64 v[118:119], v[150:151], 0, s[0:1]
	v_and_b32_e32 v114, 0xffff, v114
	global_store_short v[118:119], v114, off
	s_mov_b64 s[0:1], 0x361000
	v_and_b32_e32 v116, 0xffff, v116
	v_lshl_add_u64 v[114:115], v[150:151], 0, s[0:1]
	global_store_short v[114:115], v116, off
	v_cvt_pk_bf16_f32 v116, v117, v117
	s_mov_b64 s[0:1], 0x361800
	v_and_b32_e32 v116, 0xffff, v116
	v_lshl_add_u64 v[114:115], v[150:151], 0, s[0:1]
	global_store_short v[114:115], v116, off
	v_cvt_pk_bf16_f32 v116, v122, v122
	s_mov_b64 s[0:1], 0x360020
	v_and_b32_e32 v116, 0xffff, v116
	v_lshl_add_u64 v[114:115], v[150:151], 0, s[0:1]
	global_store_short v[114:115], v116, off
	v_cvt_pk_bf16_f32 v116, v123, v123
	s_mov_b64 s[0:1], 0x360820
	v_and_b32_e32 v116, 0xffff, v116
	v_lshl_add_u64 v[114:115], v[150:151], 0, s[0:1]
	global_store_short v[114:115], v116, off
	v_cvt_pk_bf16_f32 v116, v124, v124
	s_mov_b64 s[0:1], 0x361020
	v_and_b32_e32 v116, 0xffff, v116
	v_lshl_add_u64 v[114:115], v[150:151], 0, s[0:1]
	global_store_short v[114:115], v116, off
	s_mov_b64 s[0:1], 0x361820
	v_cvt_pk_bf16_f32 v116, v125, v125
	v_lshl_add_u64 v[114:115], v[150:151], 0, s[0:1]
	v_and_b32_e32 v116, 0xffff, v116
	global_store_short v[114:115], v116, off
.LBB0_1851:
	s_waitcnt lgkmcnt(0)
	s_barrier
	ds_read_b128 v[114:117], v168
	ds_read_b128 v[118:121], v143
	ds_read_b128 v[122:125], v143 offset:4608
	ds_read_b128 v[178:181], v168 offset:64
	ds_read_b128 v[126:129], v143 offset:64
	ds_read_b128 v[182:185], v143 offset:4672
	ds_read_b128 v[186:189], v168 offset:128
	ds_read_b128 v[190:193], v143 offset:128
	ds_read_b128 v[206:209], v143 offset:4736
	ds_read_b128 v[210:213], v168 offset:192
	ds_read_b128 v[214:217], v143 offset:192
	ds_read_b128 v[218:221], v143 offset:4800
	s_and_b64 vcc, exec, s[48:49]
	s_waitcnt lgkmcnt(10)
	v_mfma_f32_16x16x32_bf16 v[118:121], v[114:117], v[118:121], 0
	s_waitcnt lgkmcnt(9)
	v_mfma_f32_16x16x32_bf16 v[114:117], v[114:117], v[122:125], 0
	s_nop 0
	s_nop 0
	s_waitcnt lgkmcnt(7)
	v_mfma_f32_16x16x32_bf16 v[118:121], v[178:181], v[126:129], v[118:121]
	s_nop 0
	s_waitcnt lgkmcnt(6)
	v_mfma_f32_16x16x32_bf16 v[114:117], v[178:181], v[182:185], v[114:117]
	s_nop 0
	s_nop 0
	s_waitcnt lgkmcnt(4)
	v_mfma_f32_16x16x32_bf16 v[118:121], v[186:189], v[190:193], v[118:121]
	s_nop 0
	s_waitcnt lgkmcnt(3)
	v_mfma_f32_16x16x32_bf16 v[122:125], v[186:189], v[206:209], v[114:117]
	s_nop 0
	s_nop 1
	s_nop 0
	s_waitcnt lgkmcnt(1)
	v_mfma_f32_16x16x32_bf16 v[114:117], v[210:213], v[214:217], v[118:121]
	s_nop 2
	s_nop 0
	s_waitcnt lgkmcnt(0)
	v_mfma_f32_16x16x32_bf16 v[118:121], v[210:213], v[218:221], v[122:125]
	s_cbranch_vccnz .LBB0_1853
	s_waitcnt vmcnt(28)
	s_nop 0
	v_sub_f32_e32 v123, v33, v117
	v_sub_f32_e32 v124, v32, v116
	v_sub_f32_e32 v122, v31, v115
	v_sub_f32_e32 v125, v30, v114
	v_cvt_pk_bf16_f32 v122, v125, v122
	v_cvt_pk_bf16_f32 v123, v124, v123
	s_waitcnt vmcnt(27)
	v_sub_f32_e32 v125, v9, v121
	v_sub_f32_e32 v126, v8, v120
	v_sub_f32_e32 v124, v7, v119
	v_sub_f32_e32 v127, v6, v118
	v_cvt_pk_bf16_f32 v124, v127, v124
	v_cvt_pk_bf16_f32 v125, v126, v125
	ds_write2st64_b64 v170, v[122:123], v[124:125] offset1:5

.LBB0_1855:
	s_andn2_b64 vcc, exec, s[6:7]
	s_cbranch_vccnz .LBB0_1857
	ds_read_b128 v[130:133], v169
	ds_read_b128 v[122:125], v169 offset:64
	ds_read_b128 v[134:137], v169 offset:2560
	ds_read_b128 v[126:129], v169 offset:2624
	s_waitcnt lgkmcnt(7)
	s_nop 0
	s_waitcnt lgkmcnt(6)
	s_nop 0
	s_waitcnt lgkmcnt(5)
	s_nop 0
	s_waitcnt lgkmcnt(4)
	s_nop 0
	s_waitcnt vmcnt(28) lgkmcnt(3)
	v_mfma_f32_16x16x32_bf16 v[114:117], v[30:33], v[130:133], v[114:117]
	s_waitcnt lgkmcnt(1)
	v_mfma_f32_16x16x32_bf16 v[30:33], v[30:33], v[134:137], v[118:121]
	s_waitcnt vmcnt(27)
	v_mfma_f32_16x16x32_bf16 v[114:117], v[6:9], v[122:125], v[114:117]
	s_waitcnt lgkmcnt(0)
	v_mfma_f32_16x16x32_bf16 v[118:121], v[6:9], v[126:129], v[30:33]
.LBB0_1857:
	ds_read_b128 v[178:181], v173 offset:36864
	s_waitcnt vmcnt(28)
	s_nop 2
	v_pk_mul_f32 v[32:33], v[164:165], v[108:109] op_sel_hi:[0,1]
	v_pk_mul_f32 v[30:31], v[164:165], v[106:107] op_sel_hi:[0,1]
	s_nop 0
	s_waitcnt vmcnt(27)
	v_pk_mul_f32 v[8:9], v[164:165], v[112:113] op_sel_hi:[0,1]
	v_pk_mul_f32 v[6:7], v[164:165], v[110:111] op_sel_hi:[0,1]
	ds_read_b128 v[110:113], v173 offset:36928
	s_and_b64 vcc, exec, s[46:47]
	s_waitcnt lgkmcnt(1)
	v_mfma_f32_16x16x32_bf16 v[6:9], v[178:181], v[130:133], v[6:9]
	v_mfma_f32_16x16x32_bf16 v[106:109], v[178:181], v[134:137], v[30:33]
	s_waitcnt lgkmcnt(0)
	v_mfma_f32_16x16x32_bf16 v[30:33], v[110:113], v[122:125], v[6:9]
	v_mfma_f32_16x16x32_bf16 v[6:9], v[110:113], v[126:129], v[106:109]
	s_nop 6
	v_cvt_pk_bf16_f32 v106, v30, v31
	v_cvt_pk_bf16_f32 v107, v32, v33
	v_cvt_pk_bf16_f32 v108, v6, v7
	v_cvt_pk_bf16_f32 v109, v8, v9
	ds_write2st64_b64 v172, v[106:107], v[108:109] offset1:9
	s_waitcnt vmcnt(26)
	ds_write_b128 v161, v[34:37] offset:57344
	s_waitcnt vmcnt(25)
	ds_write_b128 v163, v[38:41] offset:57344
	s_waitcnt vmcnt(24)
	ds_write_b128 v174, v[42:45] offset:57344
	s_waitcnt vmcnt(23)
	ds_write_b128 v165, v[54:57] offset:57344
	s_waitcnt vmcnt(22)
	ds_write_b128 v175, v[58:61]
	s_waitcnt vmcnt(21)
	ds_write_b128 v176, v[62:65]
	s_cbranch_vccnz .LBB0_1859
	v_cvt_pk_bf16_f32 v36, v114, v114
	s_mov_b64 s[0:1], 0x380000
	v_and_b32_e32 v36, 0xffff, v36
	v_lshl_add_u64 v[34:35], v[150:151], 0, s[0:1]
	global_store_short v[34:35], v36, off
	v_cvt_pk_bf16_f32 v36, v115, v115
	s_mov_b64 s[0:1], 0x380800
	v_and_b32_e32 v36, 0xffff, v36
	v_lshl_add_u64 v[34:35], v[150:151], 0, s[0:1]
	global_store_short v[34:35], v36, off
	v_cvt_pk_bf16_f32 v36, v116, v116
	s_mov_b64 s[0:1], 0x381000
	v_and_b32_e32 v36, 0xffff, v36
	v_lshl_add_u64 v[34:35], v[150:151], 0, s[0:1]
	global_store_short v[34:35], v36, off
	v_cvt_pk_bf16_f32 v36, v117, v117
	s_mov_b64 s[0:1], 0x381800
	v_and_b32_e32 v36, 0xffff, v36
	v_lshl_add_u64 v[34:35], v[150:151], 0, s[0:1]
	global_store_short v[34:35], v36, off
	v_cvt_pk_bf16_f32 v36, v118, v118
	s_mov_b64 s[0:1], 0x380020
	v_and_b32_e32 v36, 0xffff, v36
	v_lshl_add_u64 v[34:35], v[150:151], 0, s[0:1]
	global_store_short v[34:35], v36, off
	v_cvt_pk_bf16_f32 v36, v119, v119
	s_mov_b64 s[0:1], 0x380820
	v_and_b32_e32 v36, 0xffff, v36
	v_lshl_add_u64 v[34:35], v[150:151], 0, s[0:1]
	global_store_short v[34:35], v36, off
	v_cvt_pk_bf16_f32 v36, v120, v120
	s_mov_b64 s[0:1], 0x381020
	v_and_b32_e32 v36, 0xffff, v36
	v_lshl_add_u64 v[34:35], v[150:151], 0, s[0:1]
	global_store_short v[34:35], v36, off
	s_mov_b64 s[0:1], 0x381820
	v_cvt_pk_bf16_f32 v36, v121, v121
	v_lshl_add_u64 v[34:35], v[150:151], 0, s[0:1]
	v_and_b32_e32 v36, 0xffff, v36
	global_store_short v[34:35], v36, off
.LBB0_1859:
	s_waitcnt lgkmcnt(0)
	s_barrier
	ds_read_b128 v[34:37], v168 offset:57344
	ds_read_b128 v[38:41], v143
	ds_read_b128 v[42:45], v143 offset:4608
	ds_read_b128 v[178:181], v168 offset:57408
	ds_read_b128 v[54:57], v143 offset:64
	ds_read_b128 v[182:185], v143 offset:4672
	ds_read_b128 v[186:189], v168 offset:57472
	ds_read_b128 v[190:193], v143 offset:128
	ds_read_b128 v[206:209], v143 offset:4736
	ds_read_b128 v[210:213], v168 offset:57536
	ds_read_b128 v[214:217], v143 offset:192
	ds_read_b128 v[218:221], v143 offset:4800
	s_and_b64 vcc, exec, s[48:49]
	s_waitcnt lgkmcnt(10)
	v_mfma_f32_16x16x32_bf16 v[38:41], v[34:37], v[38:41], 0
	s_waitcnt lgkmcnt(9)
	v_mfma_f32_16x16x32_bf16 v[34:37], v[34:37], v[42:45], 0
	s_nop 0
	s_nop 0
	s_waitcnt lgkmcnt(7)
	v_mfma_f32_16x16x32_bf16 v[38:41], v[178:181], v[54:57], v[38:41]
	s_nop 0
	s_waitcnt lgkmcnt(6)
	v_mfma_f32_16x16x32_bf16 v[34:37], v[178:181], v[182:185], v[34:37]
	s_nop 0
	s_nop 0
	s_waitcnt lgkmcnt(4)
	v_mfma_f32_16x16x32_bf16 v[38:41], v[186:189], v[190:193], v[38:41]
	s_nop 0
	s_waitcnt lgkmcnt(3)
	v_mfma_f32_16x16x32_bf16 v[42:45], v[186:189], v[206:209], v[34:37]
	s_nop 0
	s_nop 1
	s_nop 0
	s_waitcnt lgkmcnt(1)
	v_mfma_f32_16x16x32_bf16 v[34:37], v[210:213], v[214:217], v[38:41]
	s_nop 2
	s_nop 0
	s_waitcnt lgkmcnt(0)
	v_mfma_f32_16x16x32_bf16 v[38:41], v[210:213], v[218:221], v[42:45]
	s_cbranch_vccnz .LBB0_1861
	s_waitcnt vmcnt(19)
	s_nop 0
	v_sub_f32_e32 v43, v21, v37
	v_sub_f32_e32 v44, v20, v36
	v_sub_f32_e32 v42, v19, v35
	v_sub_f32_e32 v45, v18, v34
	v_cvt_pk_bf16_f32 v42, v45, v42
	v_cvt_pk_bf16_f32 v43, v44, v43
	s_waitcnt vmcnt(18)
	v_sub_f32_e32 v45, v13, v41
	v_sub_f32_e32 v54, v12, v40
	v_sub_f32_e32 v44, v11, v39
	v_sub_f32_e32 v55, v10, v38
	v_cvt_pk_bf16_f32 v44, v55, v44
	v_cvt_pk_bf16_f32 v45, v54, v45
	ds_write2st64_b64 v170, v[42:43], v[44:45] offset1:5

.LBB0_1863:
	s_andn2_b64 vcc, exec, s[6:7]
	s_cbranch_vccnz .LBB0_1865
	ds_read_b128 v[58:61], v169
	ds_read_b128 v[42:45], v169 offset:64
	ds_read_b128 v[62:65], v169 offset:2560
	ds_read_b128 v[54:57], v169 offset:2624
	s_waitcnt lgkmcnt(7)
	s_nop 0
	s_waitcnt lgkmcnt(6)
	s_nop 0
	s_waitcnt lgkmcnt(5)
	s_nop 0
	s_waitcnt lgkmcnt(4)
	s_nop 0
	s_waitcnt vmcnt(19) lgkmcnt(3)
	v_mfma_f32_16x16x32_bf16 v[34:37], v[18:21], v[58:61], v[34:37]
	s_waitcnt lgkmcnt(1)
	v_mfma_f32_16x16x32_bf16 v[18:21], v[18:21], v[62:65], v[38:41]
	s_waitcnt vmcnt(18)
	v_mfma_f32_16x16x32_bf16 v[34:37], v[10:13], v[42:45], v[34:37]
	s_waitcnt lgkmcnt(0)
	v_mfma_f32_16x16x32_bf16 v[38:41], v[10:13], v[54:57], v[18:21]
.LBB0_1865:
	ds_read_b128 v[18:21], v177
	ds_read_b128 v[178:181], v177 offset:64
	s_waitcnt vmcnt(19)
	s_nop 2
	s_nop 0
	s_waitcnt vmcnt(18)
	v_pk_mul_f32 v[12:13], v[158:159], v[32:33] op_sel_hi:[0,1]
	v_pk_mul_f32 v[10:11], v[158:159], v[30:31] op_sel_hi:[0,1]
	v_pk_mul_f32 v[8:9], v[158:159], v[8:9] op_sel_hi:[0,1]
	v_pk_mul_f32 v[6:7], v[158:159], v[6:7] op_sel_hi:[0,1]
	s_and_b64 vcc, exec, s[46:47]
	s_waitcnt lgkmcnt(1)
	v_mfma_f32_16x16x32_bf16 v[10:13], v[18:21], v[58:61], v[10:13]
	v_mfma_f32_16x16x32_bf16 v[6:9], v[18:21], v[62:65], v[6:9]
	s_nop 0
	s_waitcnt lgkmcnt(0)
	v_mfma_f32_16x16x32_bf16 v[10:13], v[178:181], v[42:45], v[10:13]
	v_mfma_f32_16x16x32_bf16 v[6:9], v[178:181], v[54:57], v[6:9]
	s_nop 6
	v_cvt_pk_bf16_f32 v18, v10, v11
	v_cvt_pk_bf16_f32 v19, v12, v13
	v_cvt_pk_bf16_f32 v20, v6, v7
	v_cvt_pk_bf16_f32 v21, v8, v9
	ds_write2st64_b64 v172, v[18:19], v[20:21] offset1:9
	s_waitcnt vmcnt(17)
	ds_write_b128 v161, v[46:49]
	s_waitcnt vmcnt(16)
	ds_write_b128 v163, v[66:69]
	s_waitcnt vmcnt(15)
	ds_write_b128 v161, v[74:77] offset:18432
	s_waitcnt vmcnt(14)
	ds_write_b128 v165, v[78:81]
	s_waitcnt vmcnt(13)
	ds_write_b128 v166, v[90:93] offset:36864
	s_waitcnt vmcnt(12)
	ds_write_b128 v167, v[94:97] offset:36864
	s_cbranch_vccnz .LBB0_1867
	v_cvt_pk_bf16_f32 v20, v34, v34
	s_mov_b64 s[0:1], 0x3a0000
	v_and_b32_e32 v20, 0xffff, v20
	v_lshl_add_u64 v[18:19], v[150:151], 0, s[0:1]
	global_store_short v[18:19], v20, off
	v_cvt_pk_bf16_f32 v20, v35, v35
	s_mov_b64 s[0:1], 0x3a0800
	v_and_b32_e32 v20, 0xffff, v20
	v_lshl_add_u64 v[18:19], v[150:151], 0, s[0:1]
	global_store_short v[18:19], v20, off
	v_cvt_pk_bf16_f32 v20, v36, v36
	s_mov_b64 s[0:1], 0x3a1000
	v_and_b32_e32 v20, 0xffff, v20
	v_lshl_add_u64 v[18:19], v[150:151], 0, s[0:1]
	global_store_short v[18:19], v20, off
	v_cvt_pk_bf16_f32 v20, v37, v37
	s_mov_b64 s[0:1], 0x3a1800
	v_and_b32_e32 v20, 0xffff, v20
	v_lshl_add_u64 v[18:19], v[150:151], 0, s[0:1]
	global_store_short v[18:19], v20, off
	v_cvt_pk_bf16_f32 v20, v38, v38
	s_mov_b64 s[0:1], 0x3a0020
	v_and_b32_e32 v20, 0xffff, v20
	v_lshl_add_u64 v[18:19], v[150:151], 0, s[0:1]
	global_store_short v[18:19], v20, off
	v_cvt_pk_bf16_f32 v20, v39, v39
	s_mov_b64 s[0:1], 0x3a0820
	v_and_b32_e32 v20, 0xffff, v20
	v_lshl_add_u64 v[18:19], v[150:151], 0, s[0:1]
	global_store_short v[18:19], v20, off
	v_cvt_pk_bf16_f32 v20, v40, v40
	s_mov_b64 s[0:1], 0x3a1020
	v_and_b32_e32 v20, 0xffff, v20
	v_lshl_add_u64 v[18:19], v[150:151], 0, s[0:1]
	global_store_short v[18:19], v20, off
	s_mov_b64 s[0:1], 0x3a1820
	v_cvt_pk_bf16_f32 v20, v41, v41
	v_lshl_add_u64 v[18:19], v[150:151], 0, s[0:1]
	v_and_b32_e32 v20, 0xffff, v20
	global_store_short v[18:19], v20, off
.LBB0_1867:
	s_waitcnt lgkmcnt(0)
	s_barrier
	ds_read_b128 v[18:21], v168
	ds_read_b128 v[30:33], v143
	ds_read_b128 v[34:37], v143 offset:4608
	ds_read_b128 v[178:181], v168 offset:64
	ds_read_b128 v[38:41], v143 offset:64
	ds_read_b128 v[182:185], v143 offset:4672
	ds_read_b128 v[186:189], v168 offset:128
	ds_read_b128 v[190:193], v143 offset:128
	ds_read_b128 v[206:209], v143 offset:4736
	ds_read_b128 v[210:213], v168 offset:192
	ds_read_b128 v[214:217], v143 offset:192
	ds_read_b128 v[218:221], v143 offset:4800
	s_and_b64 vcc, exec, s[44:45]
	s_waitcnt lgkmcnt(10)
	v_mfma_f32_16x16x32_bf16 v[30:33], v[18:21], v[30:33], 0
	s_waitcnt lgkmcnt(9)
	v_mfma_f32_16x16x32_bf16 v[18:21], v[18:21], v[34:37], 0
	s_nop 0
	s_nop 0
	s_waitcnt lgkmcnt(7)
	v_mfma_f32_16x16x32_bf16 v[30:33], v[178:181], v[38:41], v[30:33]
	s_nop 0
	s_waitcnt lgkmcnt(6)
	v_mfma_f32_16x16x32_bf16 v[18:21], v[178:181], v[182:185], v[18:21]
	s_nop 0
	s_nop 0
	s_waitcnt lgkmcnt(4)
	v_mfma_f32_16x16x32_bf16 v[30:33], v[186:189], v[190:193], v[30:33]
	s_nop 0
	s_waitcnt lgkmcnt(3)
	v_mfma_f32_16x16x32_bf16 v[34:37], v[186:189], v[206:209], v[18:21]
	s_nop 0
	s_nop 1
	s_nop 0
	s_waitcnt lgkmcnt(1)
	v_mfma_f32_16x16x32_bf16 v[18:21], v[210:213], v[214:217], v[30:33]
	s_nop 2
	s_nop 0
	s_waitcnt lgkmcnt(0)
	v_mfma_f32_16x16x32_bf16 v[30:33], v[210:213], v[218:221], v[34:37]
	s_cbranch_vccz .LBB0_1869
	s_waitcnt vmcnt(10)
	s_nop 0
	v_sub_f32_e32 v35, v25, v21
	v_sub_f32_e32 v36, v24, v20
	v_sub_f32_e32 v34, v23, v19
	v_sub_f32_e32 v37, v22, v18
	v_cvt_pk_bf16_f32 v34, v37, v34
	v_cvt_pk_bf16_f32 v35, v36, v35
	s_waitcnt vmcnt(9)
	v_sub_f32_e32 v37, v17, v33
	v_sub_f32_e32 v38, v16, v32
	v_sub_f32_e32 v36, v15, v31
	v_sub_f32_e32 v39, v14, v30
	v_cvt_pk_bf16_f32 v36, v39, v36
	v_cvt_pk_bf16_f32 v37, v38, v37
	ds_write2st64_b64 v170, v[34:35], v[36:37] offset1:5

.LBB0_1871:
	s_andn2_b64 vcc, exec, s[6:7]
	s_cbranch_vccnz .LBB0_1873
	ds_read_b128 v[42:45], v169
	ds_read_b128 v[34:37], v169 offset:64
	ds_read_b128 v[46:49], v169 offset:2560
	ds_read_b128 v[38:41], v169 offset:2624
	s_waitcnt lgkmcnt(7)
	s_nop 0
	s_waitcnt lgkmcnt(6)
	s_nop 0
	s_waitcnt lgkmcnt(5)
	s_nop 0
	s_waitcnt lgkmcnt(4)
	s_nop 0
	s_waitcnt vmcnt(10) lgkmcnt(3)
	v_mfma_f32_16x16x32_bf16 v[18:21], v[22:25], v[42:45], v[18:21]
	s_waitcnt lgkmcnt(1)
	v_mfma_f32_16x16x32_bf16 v[22:25], v[22:25], v[46:49], v[30:33]
	s_waitcnt vmcnt(9)
	v_mfma_f32_16x16x32_bf16 v[18:21], v[14:17], v[34:37], v[18:21]
	s_waitcnt lgkmcnt(0)
	v_mfma_f32_16x16x32_bf16 v[30:33], v[14:17], v[38:41], v[22:25]
.LBB0_1873:
	ds_read_b128 v[14:17], v173 offset:36864
	ds_read_b128 v[22:25], v173 offset:36928
	s_waitcnt vmcnt(9)
	s_nop 0
	s_nop 1
	s_nop 0
	v_pk_mul_f32 v[12:13], v[138:139], v[12:13] op_sel_hi:[0,1]
	v_pk_mul_f32 v[10:11], v[138:139], v[10:11] op_sel_hi:[0,1]
	v_pk_mul_f32 v[8:9], v[138:139], v[8:9] op_sel_hi:[0,1]
	v_pk_mul_f32 v[6:7], v[138:139], v[6:7] op_sel_hi:[0,1]
	s_lshl_b32 s8, s31, 7
	s_lshl_b32 s5, s78, 5
	s_and_b64 vcc, exec, s[46:47]
	s_waitcnt lgkmcnt(1)
	v_mfma_f32_16x16x32_bf16 v[10:13], v[14:17], v[42:45], v[10:13]
	v_mfma_f32_16x16x32_bf16 v[14:17], v[14:17], v[46:49], v[6:9]
	s_waitcnt lgkmcnt(0)
	v_mfma_f32_16x16x32_bf16 v[6:9], v[22:25], v[34:37], v[10:13]
	v_mfma_f32_16x16x32_bf16 v[10:13], v[22:25], v[38:41], v[14:17]
	s_nop 6
	v_cvt_pk_bf16_f32 v14, v6, v7
	v_cvt_pk_bf16_f32 v15, v8, v9
	v_cvt_pk_bf16_f32 v16, v10, v11
	v_cvt_pk_bf16_f32 v17, v12, v13
	ds_write2st64_b64 v172, v[14:15], v[16:17] offset1:9
	s_waitcnt vmcnt(8)
	ds_write_b128 v161, v[50:53] offset:57344
	s_waitcnt vmcnt(7)
	ds_write_b128 v163, v[70:73] offset:57344
	s_waitcnt vmcnt(6)
	ds_write_b128 v174, v[82:85] offset:57344
	s_waitcnt vmcnt(5)
	ds_write_b128 v165, v[86:89] offset:57344
	s_waitcnt vmcnt(4)
	ds_write_b128 v175, v[98:101]
	s_waitcnt vmcnt(3)
	ds_write_b128 v176, v[102:105]
	s_cbranch_vccnz .LBB0_1875
	s_add_i32 s0, s4, 0x740
	s_add_u32 s6, s0, s96
	s_addc_u32 s7, 0, s97
	v_lshl_add_u64 v[14:15], s[6:7], 0, v[144:145]
	v_readlane_b32 s0, v253, 62
	v_lshlrev_b64 v[14:15], 11, v[14:15]
	v_readlane_b32 s1, v253, 63
	s_lshl_b32 s60, s8, 1
	v_cvt_pk_bf16_f32 v16, v18, v18
	v_lshl_add_u64 v[14:15], s[0:1], 0, v[14:15]
	v_lshl_add_u64 v[14:15], v[14:15], 0, s[60:61]
	s_lshl_b32 s60, s5, 1
	v_lshl_add_u64 v[14:15], v[14:15], 0, s[60:61]
	v_cvt_pk_bf16_f32 v18, v19, v19
	v_lshl_add_u64 v[14:15], v[14:15], 0, v[196:197]
	v_and_b32_e32 v16, 0xffff, v16
	global_store_short v[14:15], v16, off
	s_mov_b64 s[0:1], 0x800
	v_and_b32_e32 v18, 0xffff, v18
	v_lshl_add_u64 v[16:17], v[14:15], 0, s[0:1]
	global_store_short v[16:17], v18, off
	v_cvt_pk_bf16_f32 v18, v20, v20
	v_and_b32_e32 v18, 0xffff, v18
	v_lshl_add_u64 v[16:17], v[14:15], 0, s[86:87]
	global_store_short v[16:17], v18, off
	v_cvt_pk_bf16_f32 v18, v21, v21
	s_mov_b64 s[0:1], 0x1800
	v_and_b32_e32 v18, 0xffff, v18
	v_lshl_add_u64 v[16:17], v[14:15], 0, s[0:1]
	global_store_short v[16:17], v18, off
	v_cvt_pk_bf16_f32 v18, v30, v30
	v_and_b32_e32 v18, 0xffff, v18
	v_lshl_add_u64 v[16:17], v[14:15], 0, 32
	global_store_short v[16:17], v18, off
	s_mov_b64 s[0:1], 0x820
	v_cvt_pk_bf16_f32 v18, v31, v31
	v_lshl_add_u64 v[16:17], v[14:15], 0, s[0:1]
	v_and_b32_e32 v18, 0xffff, v18
	global_store_short v[16:17], v18, off
	v_lshl_add_u64 v[16:17], v[14:15], 0, s[22:23]
	v_cvt_pk_bf16_f32 v18, v32, v32
	v_and_b32_e32 v18, 0xffff, v18
	global_store_short v[16:17], v18, off
	s_mov_b64 s[0:1], 0x1820
	v_cvt_pk_bf16_f32 v16, v33, v33
	v_lshl_add_u64 v[14:15], v[14:15], 0, s[0:1]
	v_and_b32_e32 v16, 0xffff, v16
	global_store_short v[14:15], v16, off
.LBB0_1875:
	s_waitcnt lgkmcnt(0)
	s_barrier
	ds_read_b128 v[14:17], v168 offset:57344
	ds_read_b128 v[18:21], v143
	ds_read_b128 v[22:25], v143 offset:4608
	ds_read_b128 v[178:181], v168 offset:57408
	ds_read_b128 v[30:33], v143 offset:64
	ds_read_b128 v[182:185], v143 offset:4672
	ds_read_b128 v[186:189], v168 offset:57472
	ds_read_b128 v[190:193], v143 offset:128
	ds_read_b128 v[206:209], v143 offset:4736
	ds_read_b128 v[210:213], v168 offset:57536
	ds_read_b128 v[214:217], v143 offset:192
	ds_read_b128 v[218:221], v143 offset:4800
	s_and_b64 vcc, exec, s[48:49]
	s_waitcnt lgkmcnt(10)
	v_mfma_f32_16x16x32_bf16 v[18:21], v[14:17], v[18:21], 0
	s_waitcnt lgkmcnt(9)
	v_mfma_f32_16x16x32_bf16 v[14:17], v[14:17], v[22:25], 0
	s_nop 0
	s_nop 0
	s_waitcnt lgkmcnt(7)
	v_mfma_f32_16x16x32_bf16 v[18:21], v[178:181], v[30:33], v[18:21]
	s_nop 0
	s_waitcnt lgkmcnt(6)
	v_mfma_f32_16x16x32_bf16 v[14:17], v[178:181], v[182:185], v[14:17]
	s_nop 0
	s_nop 0
	s_waitcnt lgkmcnt(4)
	v_mfma_f32_16x16x32_bf16 v[18:21], v[186:189], v[190:193], v[18:21]
	s_nop 0
	s_waitcnt lgkmcnt(3)
	v_mfma_f32_16x16x32_bf16 v[22:25], v[186:189], v[206:209], v[14:17]
	s_nop 0
	s_nop 1
	s_nop 0
	s_waitcnt lgkmcnt(1)
	v_mfma_f32_16x16x32_bf16 v[14:17], v[210:213], v[214:217], v[18:21]
	s_nop 2
	s_nop 0
	s_waitcnt lgkmcnt(0)
	v_mfma_f32_16x16x32_bf16 v[18:21], v[210:213], v[218:221], v[22:25]
	s_cbranch_vccnz .LBB0_1877
	s_waitcnt vmcnt(1)
	s_nop 0
	v_sub_f32_e32 v23, v29, v17
	v_sub_f32_e32 v24, v28, v16
	v_sub_f32_e32 v22, v27, v15
	v_sub_f32_e32 v25, v26, v14
	v_cvt_pk_bf16_f32 v22, v25, v22
	v_cvt_pk_bf16_f32 v23, v24, v23
	s_waitcnt vmcnt(0)
	v_sub_f32_e32 v25, v5, v21
	v_sub_f32_e32 v30, v4, v20
	v_sub_f32_e32 v24, v3, v19
	v_sub_f32_e32 v31, v2, v18
	v_cvt_pk_bf16_f32 v24, v31, v24
	v_cvt_pk_bf16_f32 v25, v30, v25
	ds_write2st64_b64 v170, v[22:23], v[24:25] offset1:5

.LBB0_1879:
	s_andn2_b64 vcc, exec, s[6:7]
	s_cbranch_vccnz .LBB0_1881
	ds_read_b128 v[34:37], v169
	ds_read_b128 v[22:25], v169 offset:64
	ds_read_b128 v[38:41], v169 offset:2560
	ds_read_b128 v[30:33], v169 offset:2624
	s_waitcnt lgkmcnt(7)
	s_nop 0
	s_waitcnt lgkmcnt(6)
	s_nop 0
	s_waitcnt lgkmcnt(5)
	s_nop 0
	s_waitcnt lgkmcnt(4)
	s_nop 0
	s_waitcnt vmcnt(1) lgkmcnt(3)
	v_mfma_f32_16x16x32_bf16 v[14:17], v[26:29], v[34:37], v[14:17]
	s_waitcnt lgkmcnt(1)
	v_mfma_f32_16x16x32_bf16 v[18:21], v[26:29], v[38:41], v[18:21]
	s_waitcnt vmcnt(0)
	v_mfma_f32_16x16x32_bf16 v[14:17], v[2:5], v[22:25], v[14:17]
	s_waitcnt lgkmcnt(0)
	v_mfma_f32_16x16x32_bf16 v[18:21], v[2:5], v[30:33], v[18:21]
.LBB0_1881:
	ds_read_b128 v[178:181], v177
	ds_read_b128 v[26:29], v177 offset:64
	s_waitcnt vmcnt(0)
	v_pk_mul_f32 v[4:5], v[140:141], v[8:9] op_sel_hi:[0,1]
	v_pk_mul_f32 v[2:3], v[140:141], v[6:7] op_sel_hi:[0,1]
	v_pk_mul_f32 v[8:9], v[140:141], v[12:13] op_sel_hi:[0,1]
	v_pk_mul_f32 v[6:7], v[140:141], v[10:11] op_sel_hi:[0,1]
	s_nop 0
	s_nop 0
	s_and_b64 vcc, exec, s[46:47]
	s_waitcnt lgkmcnt(1)
	v_mfma_f32_16x16x32_bf16 v[2:5], v[178:181], v[34:37], v[2:5]
	v_mfma_f32_16x16x32_bf16 v[10:13], v[178:181], v[38:41], v[6:9]
	s_waitcnt lgkmcnt(0)
	v_mfma_f32_16x16x32_bf16 v[6:9], v[26:29], v[22:25], v[2:5]
	v_mfma_f32_16x16x32_bf16 v[2:5], v[26:29], v[30:33], v[10:13]
	s_nop 6
	v_cvt_pk_bf16_f32 v10, v6, v7
	v_cvt_pk_bf16_f32 v11, v8, v9
	v_cvt_pk_bf16_f32 v12, v2, v3
	v_cvt_pk_bf16_f32 v13, v4, v5
	ds_write2st64_b64 v172, v[10:11], v[12:13] offset1:9
	s_cbranch_vccnz .LBB0_1883
	s_add_i32 s0, s4, 0x780
	s_add_u32 s6, s0, s96
	s_addc_u32 s7, 0, s97
	v_lshl_add_u64 v[10:11], s[6:7], 0, v[144:145]
	v_readlane_b32 s0, v253, 62
	v_lshlrev_b64 v[10:11], 11, v[10:11]
	v_readlane_b32 s1, v253, 63
	s_lshl_b32 s60, s8, 1
	v_cvt_pk_bf16_f32 v12, v14, v14
	v_lshl_add_u64 v[10:11], s[0:1], 0, v[10:11]
	v_lshl_add_u64 v[10:11], v[10:11], 0, s[60:61]
	s_lshl_b32 s60, s5, 1
	v_lshl_add_u64 v[10:11], v[10:11], 0, s[60:61]
	v_cvt_pk_bf16_f32 v14, v15, v15
	v_lshl_add_u64 v[10:11], v[10:11], 0, v[196:197]
	v_and_b32_e32 v12, 0xffff, v12
	global_store_short v[10:11], v12, off
	s_mov_b64 s[0:1], 0x800
	v_and_b32_e32 v14, 0xffff, v14
	v_lshl_add_u64 v[12:13], v[10:11], 0, s[0:1]
	global_store_short v[12:13], v14, off
	v_cvt_pk_bf16_f32 v14, v16, v16
	v_and_b32_e32 v14, 0xffff, v14
	v_lshl_add_u64 v[12:13], v[10:11], 0, s[86:87]
	global_store_short v[12:13], v14, off
	v_cvt_pk_bf16_f32 v14, v17, v17
	s_mov_b64 s[0:1], 0x1800
	v_and_b32_e32 v14, 0xffff, v14
	v_lshl_add_u64 v[12:13], v[10:11], 0, s[0:1]
	global_store_short v[12:13], v14, off
	v_cvt_pk_bf16_f32 v14, v18, v18
	v_and_b32_e32 v14, 0xffff, v14
	v_lshl_add_u64 v[12:13], v[10:11], 0, 32
	global_store_short v[12:13], v14, off
	s_mov_b64 s[0:1], 0x820
	v_cvt_pk_bf16_f32 v14, v19, v19
	v_lshl_add_u64 v[12:13], v[10:11], 0, s[0:1]
	v_and_b32_e32 v14, 0xffff, v14
	global_store_short v[12:13], v14, off
	v_lshl_add_u64 v[12:13], v[10:11], 0, s[22:23]
	v_cvt_pk_bf16_f32 v14, v20, v20
	v_and_b32_e32 v14, 0xffff, v14
	global_store_short v[12:13], v14, off
	s_mov_b64 s[0:1], 0x1820
	v_cvt_pk_bf16_f32 v12, v21, v21
	v_lshl_add_u64 v[10:11], v[10:11], 0, s[0:1]
	v_and_b32_e32 v12, 0xffff, v12
	global_store_short v[10:11], v12, off

.LBB0_1887:
	s_or_b64 exec, exec, s[4:5]
	s_or_b32 s0, s46, 4
	s_ashr_i32 s1, s0, 31
	s_lshl_b64 s[4:5], s[0:1], 13
	s_add_u32 s4, s92, s4
	s_addc_u32 s5, s93, s5
	s_lshl_b64 s[50:51], s[0:1], 14
	s_add_u32 s52, s73, s50
	s_addc_u32 s53, s38, s51
	s_add_u32 s50, s39, s50
	s_addc_u32 s51, s11, s51
	s_lshl_b64 s[68:69], s[0:1], 15
	v_readlane_b32 s26, v253, 56
	s_add_u32 s47, s26, s68
	s_addc_u32 s60, s27, s69
	s_waitcnt vmcnt(0)
	v_lshl_add_u64 v[2:3], s[4:5], 0, v[128:129]
	s_add_u32 s68, s47, s48
	global_load_dwordx4 v[54:57], v[2:3], off
	v_lshl_add_u64 v[2:3], s[52:53], 0, v[128:129]
	s_addc_u32 s69, s60, 0
	global_load_dwordx4 v[70:73], v[2:3], off
	v_lshl_add_u64 v[2:3], s[52:53], 0, v[130:131]
	s_lshl_b64 s[0:1], s[0:1], 9
	global_load_dwordx4 v[74:77], v[2:3], off
	v_lshl_add_u64 v[2:3], s[50:51], 0, v[128:129]
	s_add_u32 s0, s90, s0
	global_load_dwordx4 v[82:85], v[2:3], off
	v_lshl_add_u64 v[2:3], s[50:51], 0, v[130:131]
	s_addc_u32 s1, s91, s1
	global_load_dwordx4 v[78:81], v[2:3], off
	global_load_dwordx4 v[58:61], v196, s[68:69]
	global_load_dwordx4 v[66:69], v98, s[0:1]
	s_or_b32 s0, s46, 8
	s_ashr_i32 s1, s0, 31
	s_lshl_b64 s[4:5], s[0:1], 13
	s_add_u32 s4, s92, s4
	s_addc_u32 s5, s93, s5
	s_lshl_b64 s[50:51], s[0:1], 14
	s_add_u32 s52, s73, s50
	s_addc_u32 s53, s38, s51
	s_add_u32 s50, s39, s50
	s_addc_u32 s51, s11, s51
	s_lshl_b64 s[68:69], s[0:1], 15
	s_add_u32 s47, s26, s68
	s_addc_u32 s60, s27, s69
	v_lshl_add_u64 v[2:3], s[4:5], 0, v[128:129]
	s_add_u32 s68, s47, s48
	global_load_dwordx4 v[30:33], v[2:3], off
	v_lshl_add_u64 v[2:3], s[52:53], 0, v[128:129]
	s_addc_u32 s69, s60, 0
	global_load_dwordx4 v[34:37], v[2:3], off
	v_lshl_add_u64 v[2:3], s[52:53], 0, v[130:131]
	s_lshl_b64 s[0:1], s[0:1], 9
	global_load_dwordx4 v[38:41], v[2:3], off
	v_lshl_add_u64 v[2:3], s[50:51], 0, v[128:129]
	s_add_u32 s0, s90, s0
	global_load_dwordx4 v[42:45], v[2:3], off
	v_lshl_add_u64 v[2:3], s[50:51], 0, v[130:131]
	s_addc_u32 s1, s91, s1
	global_load_dwordx4 v[62:65], v[2:3], off
	global_load_dwordx4 v[46:49], v196, s[68:69]
	global_load_dwordx4 v[50:53], v98, s[0:1]
	s_or_b32 s0, s46, 12
	s_ashr_i32 s1, s0, 31
	s_lshl_b64 s[4:5], s[0:1], 13
	s_add_u32 s4, s92, s4
	s_addc_u32 s5, s93, s5
	s_lshl_b64 s[50:51], s[0:1], 14
	s_add_u32 s52, s73, s50
	s_addc_u32 s53, s38, s51
	s_add_u32 s50, s39, s50
	s_addc_u32 s51, s11, s51
	s_lshl_b64 s[68:69], s[0:1], 15
	s_add_u32 s47, s26, s68
	s_addc_u32 s60, s27, s69
	s_add_u32 s68, s47, s48
	s_addc_u32 s69, s60, 0
	s_lshl_b64 s[0:1], s[0:1], 9
	v_lshl_add_u64 v[10:11], s[52:53], 0, v[130:131]
	v_lshl_add_u64 v[14:15], s[50:51], 0, v[128:129]
	s_add_u32 s0, s90, s0
	v_lshl_add_u64 v[2:3], s[4:5], 0, v[128:129]
	v_lshl_add_u64 v[6:7], s[52:53], 0, v[128:129]
	global_load_dwordx4 v[10:13], v[10:11], off
	s_addc_u32 s1, s91, s1
	global_load_dwordx4 v[18:21], v[14:15], off
	v_lshl_add_u64 v[14:15], s[50:51], 0, v[130:131]
	global_load_dwordx4 v[2:5], v[2:3], off
	v_lshrrev_b32_e32 v87, 1, v126
	global_load_dwordx4 v[6:9], v[6:7], off
	s_nop 0
	global_load_dwordx4 v[26:29], v[14:15], off
	global_load_dwordx4 v[22:25], v196, s[68:69]
	v_and_b32_e32 v87, 24, v87
	global_load_dwordx4 v[14:17], v98, s[0:1]
	s_lshl_b32 s0, s49, 3
	s_and_b32 s4, s0, -16
	v_or_b32_e32 v104, s4, v140
	s_movk_i32 s1, 0xa0
	s_lshl_b32 s47, s49, 4
	v_mul_lo_u32 v86, v104, s1
	s_and_b32 s50, s47, 16
	v_lshlrev_b32_e32 v146, 1, v87
	v_or_b32_e32 v88, s50, v140
	s_waitcnt lgkmcnt(0)
	s_barrier
	v_add3_u32 v149, 0, v86, v146
	ds_read_b128 v[178:181], v149
	v_mul_u32_u24_e32 v103, 0xa0, v88
	v_mul_u32_u24_e32 v145, 0x120, v88
	s_nop 0
	v_add3_u32 v156, 0, v103, v146
	ds_read_b128 v[90:93], v156 offset:49152
	ds_read_b128 v[94:97], v149 offset:64
	ds_read_b128 v[106:109], v156 offset:49216
	v_lshl_add_u32 v147, v104, 7, v149
	ds_read_b128 v[182:185], v147 offset:10240
	s_nop 0
	s_waitcnt lgkmcnt(3)
	v_mfma_f32_16x16x32_bf16 v[86:89], v[178:181], v[90:93], 0
	s_nop 0
	s_add_i32 s0, 0, 0x1ac00
	v_add3_u32 v153, s0, v145, v146
	ds_read_b128 v[178:181], v153
	ds_read_b128 v[186:189], v147 offset:10304
	ds_read_b128 v[110:113], v153 offset:64
	ds_read_b128 v[114:117], v147 offset:10368
	ds_read_b128 v[118:121], v153 offset:128
	ds_read_b128 v[122:125], v147 offset:10432
	s_waitcnt lgkmcnt(7)
	v_mfma_f32_16x16x32_bf16 v[86:89], v[94:97], v[106:109], v[86:89]
	s_nop 0
	s_nop 0
	s_nop 0
	s_nop 0
	s_nop 0
	s_nop 0
	v_or_b32_e32 v105, s47, v140
	v_mul_lo_u32 v104, v105, s1
	s_waitcnt lgkmcnt(5)
	v_mfma_f32_16x16x32_bf16 v[86:89], v[182:185], v[178:181], v[86:89]
	v_add3_u32 v155, 0, v104, v146
	ds_read_b128 v[178:181], v155 offset:28672
	ds_read_b128 v[90:93], v153 offset:192
	s_andn2_b32 s9, s9, 63
	v_lshlrev_b32_e32 v102, 4, v100
	s_waitcnt lgkmcnt(5)
	v_mfma_f32_16x16x32_bf16 v[86:89], v[186:189], v[110:113], v[86:89]
	s_nop 0
	s_add_i32 s49, s9, 0
	v_add_u32_e32 v165, s49, v102
	ds_read_b128 v[106:109], v165 offset:54272
	v_mul_u32_u24_e32 v105, 0xa0, v140
	s_nop 0
	s_nop 0
	v_add3_u32 v154, 0, v105, v146
	ds_read_b128 v[182:185], v154 offset:49152
	ds_read_b128 v[186:189], v154 offset:51712
	ds_read_b128 v[190:193], v155 offset:28736
	ds_read_b128 v[206:209], v154 offset:49216
	ds_read_b128 v[210:213], v154 offset:51776
	s_waitcnt lgkmcnt(9)
	v_mfma_f32_16x16x32_bf16 v[86:89], v[114:117], v[118:121], v[86:89]
	s_nop 0
	s_add_i32 s8, s8, s0
	v_readlane_b32 s0, v253, 21
	s_waitcnt lgkmcnt(6)
	v_mfma_f32_16x16x32_bf16 v[94:97], v[122:125], v[90:93], v[86:89]
	s_nop 0
	s_movk_i32 s26, 0xa0
	v_add_u32_e32 v159, s0, v99
	s_waitcnt lgkmcnt(5)
	v_pk_mul_f32 v[88:89], v[108:109], 0 op_sel_hi:[1,0]
	v_pk_mul_f32 v[86:87], v[106:107], 0 op_sel_hi:[1,0]
	v_add_u32_e32 v160, s0, v101
	v_add_u32_e32 v158, 0x19600, v127
	s_waitcnt lgkmcnt(4)
	v_mfma_f32_16x16x32_bf16 v[106:109], v[178:181], v[182:185], v[86:89]
	s_nop 0
	s_waitcnt lgkmcnt(3)
	v_mfma_f32_16x16x32_bf16 v[90:93], v[178:181], v[186:189], v[86:89]
	s_nop 2
	s_nop 0
	s_waitcnt lgkmcnt(1)
	v_mfma_f32_16x16x32_bf16 v[86:89], v[190:193], v[206:209], v[106:109]
	s_nop 2
	s_nop 0
	s_waitcnt lgkmcnt(0)
	v_mfma_f32_16x16x32_bf16 v[90:93], v[190:193], v[210:213], v[90:93]
	v_add_u32_e32 v108, s8, v142
	s_nop 0
	v_cvt_pk_bf16_f32 v106, v86, v87
	v_cvt_pk_bf16_f32 v107, v88, v89
	v_add_u32_e32 v151, v108, v141
	s_nop 2
	v_cvt_pk_bf16_f32 v108, v90, v91
	v_cvt_pk_bf16_f32 v109, v92, v93
	ds_write2st64_b64 v151, v[106:107], v[108:109] offset0:18 offset1:27
	s_waitcnt vmcnt(20)
	ds_write_b128 v127, v[54:57] offset:54784
	s_waitcnt vmcnt(19)
	ds_write_b128 v143, v[70:73] offset:65024
	s_waitcnt vmcnt(18)
	ds_write_b128 v144, v[74:77] offset:65024
	s_waitcnt vmcnt(17)
	ds_write_b128 v159, v[82:85]
	s_waitcnt vmcnt(16)
	ds_write_b128 v160, v[78:81]
	s_and_saveexec_b64 s[8:9], vcc
	s_cbranch_execz .LBB0_1889
	s_waitcnt vmcnt(15)
	ds_write_b128 v158, v[58:61]

.LBB0_1891:
	s_or_b64 exec, exec, s[8:9]
	v_readlane_b32 s0, v253, 56
	s_add_u32 s0, s0, s48
	s_addc_u32 s1, s27, 0
	v_lshl_add_u64 v[136:137], s[0:1], 0, v[196:197]
	s_or_b32 s0, s46, 16
	s_ashr_i32 s5, s4, 31
	s_add_u32 s1, s96, s4
	v_mov_b32_e32 v99, v197
	s_addc_u32 s8, s97, s5
	v_lshlrev_b32_e32 v152, 2, v100
	v_lshl_add_u64 v[134:135], s[90:91], 0, v[98:99]
	v_or_b32_e32 v98, s1, v152
	v_mov_b32_e32 v99, s8
	s_lshl_b32 s1, s31, 9
	v_readlane_b32 s8, v253, 60
	v_readlane_b32 s9, v253, 61
	s_add_u32 s1, s8, s1
	s_addc_u32 s8, s9, 0
	s_lshl_b32 s48, s34, 1
	s_add_u32 s1, s1, s48
	s_addc_u32 s9, s8, 0
	s_lshl_b32 s50, s50, 1
	s_add_u32 s8, s1, s50
	s_addc_u32 s9, s9, 0
	v_lshlrev_b32_e32 v196, 1, v140
	s_ashr_i32 s1, s0, 31
	v_lshl_add_u64 v[100:101], s[8:9], 0, v[196:197]
	s_lshl_b64 s[8:9], s[0:1], 13
	s_lshl_b64 s[52:53], s[0:1], 14
	s_add_u32 s68, s73, s52
	v_lshl_add_u64 v[138:139], s[92:93], 0, v[128:129]
	s_addc_u32 s69, s38, s53
	s_add_u32 s52, s39, s52
	v_lshl_add_u64 v[54:55], v[138:139], 0, s[8:9]
	s_addc_u32 s53, s11, s53
	v_lshl_add_u64 v[56:57], s[68:69], 0, v[128:129]
	global_load_dwordx4 v[58:61], v[54:55], off
	global_load_dwordx4 v[66:69], v[56:57], off
	v_lshl_add_u64 v[54:55], s[68:69], 0, v[130:131]
	s_lshl_b64 s[70:71], s[0:1], 15
	v_lshl_add_u64 v[56:57], s[52:53], 0, v[128:129]
	global_load_dwordx4 v[74:77], v[54:55], off
	global_load_dwordx4 v[78:81], v[56:57], off
	v_lshl_add_u64 v[54:55], s[52:53], 0, v[130:131]
	s_lshl_b64 s[0:1], s[0:1], 9
	v_lshl_add_u64 v[56:57], v[136:137], 0, s[70:71]
	global_load_dwordx4 v[82:85], v[54:55], off
	global_load_dwordx4 v[70:73], v[56:57], off
	v_lshl_add_u64 v[54:55], v[134:135], 0, s[0:1]
	global_load_dwordx4 v[54:57], v[54:55], off
	v_cvt_pk_bf16_f32 v94, v94, v94
	v_lshlrev_b64 v[98:99], 11, v[98:99]
	v_and_b32_e32 v94, 0xffff, v94
	v_lshl_add_u64 v[132:133], v[100:101], 0, v[98:99]
	global_store_short v[132:133], v94, off
	s_mov_b64 s[0:1], 0x800
	v_cvt_pk_bf16_f32 v94, v95, v95
	v_cvt_pk_bf16_f32 v96, v96, v96
	v_lshl_add_u64 v[98:99], v[132:133], 0, s[0:1]
	v_and_b32_e32 v94, 0xffff, v94
	global_store_short v[98:99], v94, off
	v_and_b32_e32 v96, 0xffff, v96
	v_lshl_add_u64 v[94:95], v[132:133], 0, s[86:87]
	global_store_short v[94:95], v96, off
	s_mov_b64 s[0:1], 0x1800
	v_cvt_pk_bf16_f32 v96, v97, v97
	v_lshl_add_u64 v[94:95], v[132:133], 0, s[0:1]
	v_and_b32_e32 v96, 0xffff, v96
	global_store_short v[94:95], v96, off
	s_waitcnt lgkmcnt(0)
	s_barrier
	ds_read_b128 v[94:97], v149 offset:54784
	s_add_i32 s0, 0, 0x19600
	v_add3_u32 v162, s0, v103, v146
	ds_read_b128 v[98:101], v162
	ds_read_b128 v[106:109], v149 offset:54848
	ds_read_b128 v[110:113], v162 offset:64
	ds_read_b128 v[178:181], v147 offset:65024
	ds_read_b128 v[114:117], v147 offset:65088
	ds_read_b128 v[118:121], v153 offset:9216
	ds_read_b128 v[182:185], v153 offset:9280
	ds_read_b128 v[186:189], v153 offset:9344
	ds_read_b128 v[122:125], v147 offset:65152
	ds_read_b128 v[190:193], v147 offset:65216
	s_waitcnt lgkmcnt(9)
	v_mfma_f32_16x16x32_bf16 v[94:97], v[94:97], v[98:101], 0
	s_nop 0
	s_nop 0
	s_nop 0
	v_readlane_b32 s1, v253, 21
	s_add_i32 s52, s49, 0x1aa00
	s_waitcnt lgkmcnt(7)
	v_mfma_f32_16x16x32_bf16 v[94:97], v[106:109], v[110:113], v[94:97]
	s_nop 0
	s_nop 0
	s_nop 0
	v_add3_u32 v161, s1, v104, v146
	v_add_u32_e32 v166, s52, v102
	s_waitcnt lgkmcnt(4)
	v_mfma_f32_16x16x32_bf16 v[94:97], v[178:181], v[118:121], v[94:97]
	s_nop 0
	v_add3_u32 v163, s0, v105, v146
	ds_read_b128 v[118:121], v163
	ds_read_b128 v[178:181], v153 offset:9408
	ds_read_b128 v[206:209], v161
	ds_read_b128 v[210:213], v166
	ds_read_b128 v[214:217], v163 offset:2560
	ds_read_b128 v[218:221], v161 offset:64
	s_waitcnt lgkmcnt(9)
	v_mfma_f32_16x16x32_bf16 v[94:97], v[114:117], v[182:185], v[94:97]
	s_nop 0
	s_nop 0
	v_readlane_b32 s0, v253, 22
	s_waitcnt lgkmcnt(7)
	v_mfma_f32_16x16x32_bf16 v[94:97], v[122:125], v[186:189], v[94:97]
	s_nop 0
	v_add3_u32 v164, s0, v105, v146
	ds_read_b128 v[182:185], v164
	ds_read_b128 v[102:105], v164 offset:2560
	s_waitcnt lgkmcnt(4)
	v_pk_mul_f32 v[92:93], v[92:93], v[212:213]
	v_mfma_f32_16x16x32_bf16 v[94:97], v[190:193], v[178:181], v[94:97]
	s_nop 0
	s_nop 0
	v_pk_mul_f32 v[90:91], v[90:91], v[210:211]
	v_pk_mul_f32 v[88:89], v[88:89], v[212:213]
	v_pk_mul_f32 v[86:87], v[86:87], v[210:211]
	s_waitcnt lgkmcnt(3)
	v_mfma_f32_16x16x32_bf16 v[98:101], v[206:209], v[214:217], v[90:93]
	s_nop 2
	s_nop 0
	s_nop 0
	v_mfma_f32_16x16x32_bf16 v[86:89], v[206:209], v[118:121], v[86:89]
	s_waitcnt lgkmcnt(1)
	v_mfma_f32_16x16x32_bf16 v[90:93], v[218:221], v[182:185], v[86:89]
	s_waitcnt lgkmcnt(0)
	v_mfma_f32_16x16x32_bf16 v[86:89], v[218:221], v[102:105], v[98:101]
	s_nop 5
	v_cvt_pk_bf16_f32 v98, v90, v91
	v_cvt_pk_bf16_f32 v99, v92, v93
	v_cvt_pk_bf16_f32 v100, v86, v87
	v_cvt_pk_bf16_f32 v101, v88, v89
	ds_write2st64_b64 v151, v[98:99], v[100:101] offset1:9
	s_waitcnt vmcnt(20)
	ds_write_b128 v127, v[30:33]
	s_waitcnt vmcnt(19)
	ds_write_b128 v143, v[34:37] offset:10240
	s_waitcnt vmcnt(18)
	ds_write_b128 v144, v[38:41] offset:10240
	s_waitcnt vmcnt(17)
	ds_write_b128 v127, v[42:45] offset:28672
	s_waitcnt vmcnt(16)
	ds_write_b128 v148, v[62:65] offset:28672
	s_and_saveexec_b64 s[8:9], vcc
	s_cbranch_execz .LBB0_1893
	s_waitcnt vmcnt(15)
	ds_write_b128 v127, v[46:49] offset:49152

.LBB0_1895:
	s_or_b64 exec, exec, s[8:9]
	s_or_b32 s0, s46, 20
	s_ashr_i32 s1, s0, 31
	s_lshl_b64 s[8:9], s[0:1], 13
	s_lshl_b64 s[68:69], s[0:1], 14
	s_add_u32 s70, s73, s68
	s_addc_u32 s71, s38, s69
	s_add_u32 s68, s39, s68
	v_lshl_add_u64 v[30:31], v[138:139], 0, s[8:9]
	s_addc_u32 s69, s11, s69
	v_lshl_add_u64 v[32:33], s[70:71], 0, v[128:129]
	global_load_dwordx4 v[34:37], v[30:31], off
	global_load_dwordx4 v[38:41], v[32:33], off
	v_lshl_add_u64 v[30:31], s[70:71], 0, v[130:131]
	s_lshl_b64 s[78:79], s[0:1], 15
	v_lshl_add_u64 v[32:33], s[68:69], 0, v[128:129]
	global_load_dwordx4 v[46:49], v[30:31], off
	global_load_dwordx4 v[50:53], v[32:33], off
	v_lshl_add_u64 v[30:31], s[68:69], 0, v[130:131]
	s_lshl_b64 s[0:1], s[0:1], 9
	v_lshl_add_u64 v[32:33], v[136:137], 0, s[78:79]
	global_load_dwordx4 v[62:65], v[30:31], off
	global_load_dwordx4 v[42:45], v[32:33], off
	v_lshl_add_u64 v[30:31], v[134:135], 0, s[0:1]
	global_load_dwordx4 v[30:33], v[30:31], off
	v_cvt_pk_bf16_f32 v94, v94, v94
	s_mov_b64 s[0:1], 0x20000
	v_and_b32_e32 v94, 0xffff, v94
	v_lshl_add_u64 v[98:99], v[132:133], 0, s[0:1]
	global_store_short v[98:99], v94, off
	s_mov_b64 s[0:1], 0x20800
	v_cvt_pk_bf16_f32 v94, v95, v95
	v_cvt_pk_bf16_f32 v96, v96, v96
	v_lshl_add_u64 v[98:99], v[132:133], 0, s[0:1]
	v_and_b32_e32 v94, 0xffff, v94
	global_store_short v[98:99], v94, off
	s_mov_b64 s[0:1], 0x21000
	v_and_b32_e32 v96, 0xffff, v96
	v_lshl_add_u64 v[94:95], v[132:133], 0, s[0:1]
	global_store_short v[94:95], v96, off
	s_mov_b64 s[0:1], 0x21800
	v_cvt_pk_bf16_f32 v96, v97, v97
	v_lshl_add_u64 v[94:95], v[132:133], 0, s[0:1]
	v_and_b32_e32 v96, 0xffff, v96
	global_store_short v[94:95], v96, off
	s_waitcnt lgkmcnt(0)
	s_barrier
	ds_read_b128 v[94:97], v149
	ds_read_b128 v[98:101], v149 offset:64
	ds_read_b128 v[102:105], v156 offset:49152
	ds_read_b128 v[106:109], v156 offset:49216
	ds_read_b128 v[178:181], v147 offset:10240
	ds_read_b128 v[182:185], v153
	ds_read_b128 v[186:189], v147 offset:10304
	ds_read_b128 v[110:113], v153 offset:64
	ds_read_b128 v[190:193], v147 offset:10368
	ds_read_b128 v[206:209], v153 offset:128
	ds_read_b128 v[210:213], v147 offset:10432
	ds_read_b128 v[214:217], v153 offset:192
	ds_read_b128 v[114:117], v155 offset:28672
	ds_read_b128 v[218:221], v165 offset:54272
	ds_read_b128 v[222:225], v154 offset:49152
	s_waitcnt lgkmcnt(12)
	v_mfma_f32_16x16x32_bf16 v[94:97], v[94:97], v[102:105], 0
	s_nop 0
	s_waitcnt lgkmcnt(11)
	v_mfma_f32_16x16x32_bf16 v[94:97], v[98:101], v[106:109], v[94:97]
	s_nop 0
	s_nop 0
	s_nop 0
	s_waitcnt lgkmcnt(9)
	v_mfma_f32_16x16x32_bf16 v[94:97], v[178:181], v[182:185], v[94:97]
	ds_read_b128 v[178:181], v154 offset:51712
	ds_read_b128 v[182:185], v155 offset:28736
	s_nop 0
	s_nop 0
	s_waitcnt lgkmcnt(9)
	v_mfma_f32_16x16x32_bf16 v[94:97], v[186:189], v[110:113], v[94:97]
	ds_read_b128 v[186:189], v154 offset:49216
	s_nop 0
	s_nop 0
	s_nop 0
	s_waitcnt lgkmcnt(8)
	v_mfma_f32_16x16x32_bf16 v[94:97], v[190:193], v[206:209], v[94:97]
	ds_read_b128 v[190:193], v154 offset:51776
	s_nop 0
	s_nop 0
	s_waitcnt lgkmcnt(5)
	v_pk_mul_f32 v[92:93], v[92:93], v[220:221]
	v_mfma_f32_16x16x32_bf16 v[110:113], v[210:213], v[214:217], v[94:97]
	v_mul_f32_e64 v90, v90, v218
	v_mul_f32_e64 v91, v91, v219
	v_pk_mul_f32 v[88:89], v[88:89], v[220:221]
	v_pk_mul_f32 v[86:87], v[86:87], v[218:219]
	s_nop 0
	s_waitcnt lgkmcnt(4)
	v_mfma_f32_16x16x32_bf16 v[90:93], v[114:117], v[222:225], v[90:93]
	s_nop 0
	s_waitcnt lgkmcnt(3)
	v_mfma_f32_16x16x32_bf16 v[86:89], v[114:117], v[178:181], v[86:89]
	s_nop 0
	s_waitcnt lgkmcnt(1)
	v_mfma_f32_16x16x32_bf16 v[98:101], v[182:185], v[186:189], v[90:93]
	s_nop 2
	s_nop 0
	s_waitcnt lgkmcnt(0)
	v_mfma_f32_16x16x32_bf16 v[106:109], v[182:185], v[190:193], v[86:89]
	s_nop 2
	v_cvt_pk_bf16_f32 v86, v98, v99
	v_cvt_pk_bf16_f32 v87, v100, v101
	s_nop 2
	v_cvt_pk_bf16_f32 v88, v106, v107
	v_cvt_pk_bf16_f32 v89, v108, v109
	ds_write2st64_b64 v151, v[86:87], v[88:89] offset0:18 offset1:27
	s_waitcnt vmcnt(18)
	ds_write_b128 v127, v[2:5] offset:54784
	s_waitcnt vmcnt(17)
	ds_write_b128 v143, v[6:9] offset:65024
	ds_write_b128 v144, v[10:13] offset:65024
	ds_write_b128 v159, v[18:21]
	s_waitcnt vmcnt(16)
	ds_write_b128 v160, v[26:29]
	s_and_saveexec_b64 s[8:9], vcc
	s_cbranch_execz .LBB0_1897
	s_waitcnt vmcnt(15)
	ds_write_b128 v158, v[22:25]

.LBB0_1899:
	s_or_b64 exec, exec, s[8:9]
	s_or_b32 s0, s46, 24
	s_ashr_i32 s1, s0, 31
	s_lshl_b64 s[8:9], s[0:1], 13
	s_lshl_b64 s[68:69], s[0:1], 14
	s_add_u32 s70, s73, s68
	s_addc_u32 s71, s38, s69
	s_add_u32 s68, s39, s68
	v_lshl_add_u64 v[2:3], v[138:139], 0, s[8:9]
	s_addc_u32 s69, s11, s69
	v_lshl_add_u64 v[4:5], s[70:71], 0, v[128:129]
	global_load_dwordx4 v[22:25], v[2:3], off
	global_load_dwordx4 v[26:29], v[4:5], off
	v_lshl_add_u64 v[2:3], s[70:71], 0, v[130:131]
	s_lshl_b64 s[78:79], s[0:1], 15
	v_lshl_add_u64 v[4:5], s[68:69], 0, v[128:129]
	global_load_dwordx4 v[90:93], v[2:3], off
	global_load_dwordx4 v[94:97], v[4:5], off
	v_lshl_add_u64 v[2:3], s[68:69], 0, v[130:131]
	s_lshl_b64 s[0:1], s[0:1], 9
	v_lshl_add_u64 v[4:5], v[136:137], 0, s[78:79]
	global_load_dwordx4 v[102:105], v[2:3], off
	global_load_dwordx4 v[86:89], v[4:5], off
	v_lshl_add_u64 v[2:3], v[134:135], 0, s[0:1]
	global_load_dwordx4 v[6:9], v[2:3], off
	v_cvt_pk_bf16_f32 v4, v110, v110
	s_mov_b64 s[0:1], 0x40000
	v_and_b32_e32 v4, 0xffff, v4
	v_lshl_add_u64 v[2:3], v[132:133], 0, s[0:1]
	global_store_short v[2:3], v4, off
	v_cvt_pk_bf16_f32 v4, v111, v111
	s_mov_b64 s[0:1], 0x40800
	v_and_b32_e32 v4, 0xffff, v4
	v_lshl_add_u64 v[2:3], v[132:133], 0, s[0:1]
	global_store_short v[2:3], v4, off
	v_cvt_pk_bf16_f32 v4, v112, v112
	s_mov_b64 s[0:1], 0x41000
	v_and_b32_e32 v4, 0xffff, v4
	v_lshl_add_u64 v[2:3], v[132:133], 0, s[0:1]
	global_store_short v[2:3], v4, off
	s_mov_b64 s[0:1], 0x41800
	v_cvt_pk_bf16_f32 v4, v113, v113
	v_lshl_add_u64 v[2:3], v[132:133], 0, s[0:1]
	v_and_b32_e32 v4, 0xffff, v4
	global_store_short v[2:3], v4, off
	s_waitcnt lgkmcnt(0)
	s_barrier
	ds_read_b128 v[2:5], v149 offset:54784
	ds_read_b128 v[10:13], v162
	ds_read_b128 v[14:17], v149 offset:54848
	ds_read_b128 v[18:21], v162 offset:64
	ds_read_b128 v[178:181], v147 offset:65024
	ds_read_b128 v[110:113], v153 offset:9216
	ds_read_b128 v[182:185], v147 offset:65088
	ds_read_b128 v[186:189], v153 offset:9280
	ds_read_b128 v[190:193], v147 offset:65152
	ds_read_b128 v[206:209], v153 offset:9344
	ds_read_b128 v[210:213], v147 offset:65216
	ds_read_b128 v[214:217], v153 offset:9408
	ds_read_b128 v[218:221], v161
	ds_read_b128 v[114:117], v166
	ds_read_b128 v[118:121], v163
	ds_read_b128 v[222:225], v163 offset:2560
	s_waitcnt vmcnt(21)
	s_nop 0
	s_nop 0
	s_waitcnt lgkmcnt(14)
	v_mfma_f32_16x16x32_bf16 v[2:5], v[2:5], v[10:13], 0
	s_nop 0
	s_nop 0
	s_waitcnt lgkmcnt(12)
	v_mfma_f32_16x16x32_bf16 v[2:5], v[14:17], v[18:21], v[2:5]
	s_nop 0
	s_nop 0
	s_waitcnt lgkmcnt(10)
	v_mfma_f32_16x16x32_bf16 v[2:5], v[178:181], v[110:113], v[2:5]
	ds_read_b128 v[178:181], v161 offset:64
	s_nop 0
	s_nop 0
	s_waitcnt lgkmcnt(9)
	v_mfma_f32_16x16x32_bf16 v[2:5], v[182:185], v[186:189], v[2:5]
	ds_read_b128 v[182:185], v164
	ds_read_b128 v[186:189], v164 offset:2560
	s_nop 0
	s_nop 0
	s_waitcnt lgkmcnt(9)
	v_mfma_f32_16x16x32_bf16 v[2:5], v[190:193], v[206:209], v[2:5]
	s_nop 0
	s_nop 0
	s_nop 0
	s_waitcnt lgkmcnt(7)
	v_mfma_f32_16x16x32_bf16 v[110:113], v[210:213], v[214:217], v[2:5]
	s_nop 0
	s_nop 0
	s_waitcnt lgkmcnt(5)
	v_pk_mul_f32 v[4:5], v[100:101], v[116:117]
	v_pk_mul_f32 v[2:3], v[98:99], v[114:115]
	v_pk_mul_f32 v[100:101], v[108:109], v[116:117]
	v_pk_mul_f32 v[98:99], v[106:107], v[114:115]
	s_waitcnt lgkmcnt(4)
	v_mfma_f32_16x16x32_bf16 v[2:5], v[218:221], v[118:121], v[2:5]
	s_waitcnt lgkmcnt(3)
	v_mfma_f32_16x16x32_bf16 v[10:13], v[218:221], v[222:225], v[98:101]
	s_nop 0
	s_nop 1
	s_nop 0
	s_waitcnt lgkmcnt(1)
	v_mfma_f32_16x16x32_bf16 v[106:109], v[178:181], v[182:185], v[2:5]
	s_waitcnt lgkmcnt(0)
	v_mfma_f32_16x16x32_bf16 v[98:101], v[178:181], v[186:189], v[10:13]
	s_nop 5
	v_cvt_pk_bf16_f32 v2, v106, v107
	v_cvt_pk_bf16_f32 v3, v108, v109
	v_cvt_pk_bf16_f32 v4, v98, v99
	v_cvt_pk_bf16_f32 v5, v100, v101
	ds_write2st64_b64 v151, v[2:3], v[4:5] offset1:9
	s_waitcnt vmcnt(20)
	ds_write_b128 v127, v[58:61]
	s_waitcnt vmcnt(19)
	ds_write_b128 v143, v[66:69] offset:10240
	s_waitcnt vmcnt(18)
	ds_write_b128 v144, v[74:77] offset:10240
	s_waitcnt vmcnt(17)
	ds_write_b128 v127, v[78:81] offset:28672
	s_waitcnt vmcnt(16)
	ds_write_b128 v148, v[82:85] offset:28672
	s_and_saveexec_b64 s[8:9], vcc
	s_cbranch_execz .LBB0_1901
	s_waitcnt vmcnt(15)
	ds_write_b128 v127, v[70:73] offset:49152

.LBB0_1903:
	s_or_b64 exec, exec, s[8:9]
	s_or_b32 s0, s46, 28
	s_ashr_i32 s1, s0, 31
	s_lshl_b64 s[8:9], s[0:1], 13
	s_lshl_b64 s[68:69], s[0:1], 14
	s_add_u32 s70, s73, s68
	s_addc_u32 s71, s38, s69
	s_add_u32 s68, s39, s68
	v_lshl_add_u64 v[2:3], v[138:139], 0, s[8:9]
	s_addc_u32 s69, s11, s69
	v_lshl_add_u64 v[4:5], s[70:71], 0, v[128:129]
	global_load_dwordx4 v[10:13], v[2:3], off
	global_load_dwordx4 v[14:17], v[4:5], off
	v_lshl_add_u64 v[2:3], s[70:71], 0, v[130:131]
	s_lshl_b64 s[78:79], s[0:1], 15
	v_lshl_add_u64 v[4:5], s[68:69], 0, v[128:129]
	global_load_dwordx4 v[54:57], v[2:3], off
	global_load_dwordx4 v[58:61], v[4:5], off
	v_lshl_add_u64 v[2:3], s[68:69], 0, v[130:131]
	s_lshl_b64 s[0:1], s[0:1], 9
	v_lshl_add_u64 v[4:5], v[136:137], 0, s[78:79]
	global_load_dwordx4 v[66:69], v[2:3], off
	global_load_dwordx4 v[18:21], v[4:5], off
	v_lshl_add_u64 v[2:3], v[134:135], 0, s[0:1]
	global_load_dwordx4 v[2:5], v[2:3], off
	s_waitcnt vmcnt(22)
	v_cvt_pk_bf16_f32 v72, v110, v110
	s_mov_b64 s[0:1], 0x60000
	v_and_b32_e32 v72, 0xffff, v72
	v_lshl_add_u64 v[70:71], v[132:133], 0, s[0:1]
	global_store_short v[70:71], v72, off
	v_cvt_pk_bf16_f32 v72, v111, v111
	s_mov_b64 s[0:1], 0x60800
	v_and_b32_e32 v72, 0xffff, v72
	v_lshl_add_u64 v[70:71], v[132:133], 0, s[0:1]
	global_store_short v[70:71], v72, off
	v_cvt_pk_bf16_f32 v72, v112, v112
	s_mov_b64 s[0:1], 0x61000
	v_and_b32_e32 v72, 0xffff, v72
	v_lshl_add_u64 v[70:71], v[132:133], 0, s[0:1]
	global_store_short v[70:71], v72, off
	s_mov_b64 s[0:1], 0x61800
	v_cvt_pk_bf16_f32 v72, v113, v113
	v_lshl_add_u64 v[70:71], v[132:133], 0, s[0:1]
	v_and_b32_e32 v72, 0xffff, v72
	global_store_short v[70:71], v72, off
	s_waitcnt lgkmcnt(0)
	s_barrier
	ds_read_b128 v[70:73], v149
	ds_read_b128 v[74:77], v149 offset:64
	ds_read_b128 v[78:81], v156 offset:49152
	ds_read_b128 v[82:85], v156 offset:49216
	ds_read_b128 v[178:181], v147 offset:10240
	ds_read_b128 v[182:185], v153
	ds_read_b128 v[186:189], v147 offset:10304
	ds_read_b128 v[110:113], v153 offset:64
	ds_read_b128 v[190:193], v147 offset:10368
	ds_read_b128 v[206:209], v153 offset:128
	ds_read_b128 v[210:213], v147 offset:10432
	ds_read_b128 v[214:217], v153 offset:192
	ds_read_b128 v[114:117], v155 offset:28672
	ds_read_b128 v[218:221], v165 offset:54272
	ds_read_b128 v[222:225], v154 offset:49152
	s_waitcnt lgkmcnt(12)
	v_mfma_f32_16x16x32_bf16 v[70:73], v[70:73], v[78:81], 0
	s_nop 0
	s_waitcnt lgkmcnt(11)
	v_mfma_f32_16x16x32_bf16 v[70:73], v[74:77], v[82:85], v[70:73]
	s_nop 0
	s_nop 0
	s_nop 0
	s_waitcnt lgkmcnt(9)
	v_mfma_f32_16x16x32_bf16 v[70:73], v[178:181], v[182:185], v[70:73]
	ds_read_b128 v[178:181], v154 offset:51712
	ds_read_b128 v[182:185], v155 offset:28736
	s_nop 0
	s_nop 0
	s_waitcnt lgkmcnt(9)
	v_mfma_f32_16x16x32_bf16 v[70:73], v[186:189], v[110:113], v[70:73]
	ds_read_b128 v[186:189], v154 offset:49216
	s_nop 0
	s_nop 0
	s_nop 0
	s_waitcnt lgkmcnt(8)
	v_mfma_f32_16x16x32_bf16 v[70:73], v[190:193], v[206:209], v[70:73]
	ds_read_b128 v[190:193], v154 offset:51776
	s_nop 0
	s_nop 0
	s_waitcnt lgkmcnt(7)
	v_mfma_f32_16x16x32_bf16 v[110:113], v[210:213], v[214:217], v[70:73]
	s_nop 0
	s_waitcnt lgkmcnt(5)
	s_nop 1
	v_pk_mul_f32 v[72:73], v[108:109], v[220:221]
	v_pk_mul_f32 v[70:71], v[106:107], v[218:219]
	v_pk_mul_f32 v[76:77], v[100:101], v[220:221]
	v_pk_mul_f32 v[74:75], v[98:99], v[218:219]
	s_waitcnt lgkmcnt(4)
	v_mfma_f32_16x16x32_bf16 v[70:73], v[114:117], v[222:225], v[70:73]
	s_nop 0
	s_waitcnt lgkmcnt(3)
	v_mfma_f32_16x16x32_bf16 v[82:85], v[114:117], v[178:181], v[74:77]
	s_nop 2
	s_nop 0
	s_waitcnt lgkmcnt(1)
	v_mfma_f32_16x16x32_bf16 v[74:77], v[182:185], v[186:189], v[70:73]
	s_nop 2
	s_nop 0
	s_waitcnt lgkmcnt(0)
	v_mfma_f32_16x16x32_bf16 v[78:81], v[182:185], v[190:193], v[82:85]
	s_nop 1
	v_cvt_pk_bf16_f32 v70, v74, v75
	v_cvt_pk_bf16_f32 v71, v76, v77
	s_nop 3
	v_cvt_pk_bf16_f32 v72, v78, v79
	v_cvt_pk_bf16_f32 v73, v80, v81
	ds_write2st64_b64 v151, v[70:71], v[72:73] offset0:18 offset1:27
	s_waitcnt vmcnt(20)
	ds_write_b128 v127, v[34:37] offset:54784
	s_waitcnt vmcnt(19)
	ds_write_b128 v143, v[38:41] offset:65024
	s_waitcnt vmcnt(18)
	ds_write_b128 v144, v[46:49] offset:65024
	s_waitcnt vmcnt(17)
	ds_write_b128 v159, v[50:53]
	s_waitcnt vmcnt(16)
	ds_write_b128 v160, v[62:65]
	s_and_saveexec_b64 s[8:9], vcc
	s_cbranch_execz .LBB0_1905
	s_waitcnt vmcnt(15)
	ds_write_b128 v158, v[42:45]

.LBB0_1907:
	s_or_b64 exec, exec, s[8:9]
	s_or_b32 s0, s46, 32
	s_ashr_i32 s1, s0, 31
	s_lshl_b64 s[8:9], s[0:1], 13
	s_lshl_b64 s[68:69], s[0:1], 14
	s_add_u32 s70, s73, s68
	s_addc_u32 s71, s38, s69
	s_add_u32 s68, s39, s68
	s_waitcnt vmcnt(14)
	v_lshl_add_u64 v[30:31], v[138:139], 0, s[8:9]
	s_addc_u32 s69, s11, s69
	v_lshl_add_u64 v[32:33], s[70:71], 0, v[128:129]
	global_load_dwordx4 v[46:49], v[30:31], off
	global_load_dwordx4 v[62:65], v[32:33], off
	v_lshl_add_u64 v[30:31], s[70:71], 0, v[130:131]
	s_lshl_b64 s[78:79], s[0:1], 15
	v_lshl_add_u64 v[32:33], s[68:69], 0, v[128:129]
	global_load_dwordx4 v[82:85], v[30:31], off
	global_load_dwordx4 v[98:101], v[32:33], off
	v_lshl_add_u64 v[30:31], s[68:69], 0, v[130:131]
	s_lshl_b64 s[0:1], s[0:1], 9
	v_lshl_add_u64 v[32:33], v[136:137], 0, s[78:79]
	global_load_dwordx4 v[106:109], v[30:31], off
	global_load_dwordx4 v[70:73], v[32:33], off
	v_lshl_add_u64 v[30:31], v[134:135], 0, s[0:1]
	global_load_dwordx4 v[42:45], v[30:31], off
	v_cvt_pk_bf16_f32 v32, v110, v110
	s_mov_b64 s[0:1], 0x80000
	v_and_b32_e32 v32, 0xffff, v32
	v_lshl_add_u64 v[30:31], v[132:133], 0, s[0:1]
	global_store_short v[30:31], v32, off
	v_cvt_pk_bf16_f32 v32, v111, v111
	s_mov_b64 s[0:1], 0x80800
	v_and_b32_e32 v32, 0xffff, v32
	v_lshl_add_u64 v[30:31], v[132:133], 0, s[0:1]
	global_store_short v[30:31], v32, off
	v_cvt_pk_bf16_f32 v32, v112, v112
	s_mov_b64 s[0:1], 0x81000
	v_and_b32_e32 v32, 0xffff, v32
	v_lshl_add_u64 v[30:31], v[132:133], 0, s[0:1]
	global_store_short v[30:31], v32, off
	s_mov_b64 s[0:1], 0x81800
	v_cvt_pk_bf16_f32 v32, v113, v113
	v_lshl_add_u64 v[30:31], v[132:133], 0, s[0:1]
	v_and_b32_e32 v32, 0xffff, v32
	global_store_short v[30:31], v32, off
	s_waitcnt lgkmcnt(0)
	s_barrier
	ds_read_b128 v[30:33], v149 offset:54784
	ds_read_b128 v[34:37], v162
	ds_read_b128 v[38:41], v149 offset:54848
	ds_read_b128 v[50:53], v162 offset:64
	ds_read_b128 v[178:181], v147 offset:65024
	ds_read_b128 v[110:113], v153 offset:9216
	ds_read_b128 v[182:185], v147 offset:65088
	ds_read_b128 v[186:189], v153 offset:9280
	ds_read_b128 v[190:193], v147 offset:65152
	ds_read_b128 v[206:209], v153 offset:9344
	ds_read_b128 v[210:213], v147 offset:65216
	ds_read_b128 v[214:217], v153 offset:9408
	ds_read_b128 v[218:221], v161
	ds_read_b128 v[114:117], v166
	ds_read_b128 v[118:121], v163
	ds_read_b128 v[222:225], v163 offset:2560
	s_waitcnt lgkmcnt(14)
	v_mfma_f32_16x16x32_bf16 v[30:33], v[30:33], v[34:37], 0
	s_nop 0
	s_nop 0
	s_waitcnt lgkmcnt(12)
	v_mfma_f32_16x16x32_bf16 v[30:33], v[38:41], v[50:53], v[30:33]
	s_nop 0
	s_nop 0
	s_waitcnt lgkmcnt(10)
	v_mfma_f32_16x16x32_bf16 v[30:33], v[178:181], v[110:113], v[30:33]
	ds_read_b128 v[178:181], v161 offset:64
	s_nop 0
	s_nop 0
	s_waitcnt lgkmcnt(9)
	v_mfma_f32_16x16x32_bf16 v[30:33], v[182:185], v[186:189], v[30:33]
	ds_read_b128 v[182:185], v164
	ds_read_b128 v[186:189], v164 offset:2560
	s_nop 0
	s_nop 0
	s_waitcnt lgkmcnt(9)
	v_mfma_f32_16x16x32_bf16 v[30:33], v[190:193], v[206:209], v[30:33]
	s_nop 0
	s_nop 0
	s_nop 0
	s_waitcnt lgkmcnt(7)
	v_mfma_f32_16x16x32_bf16 v[110:113], v[210:213], v[214:217], v[30:33]
	s_nop 0
	s_nop 0
	s_waitcnt lgkmcnt(5)
	v_pk_mul_f32 v[32:33], v[76:77], v[116:117]
	v_pk_mul_f32 v[30:31], v[74:75], v[114:115]
	v_pk_mul_f32 v[76:77], v[80:81], v[116:117]
	v_pk_mul_f32 v[74:75], v[78:79], v[114:115]
	s_waitcnt lgkmcnt(4)
	v_mfma_f32_16x16x32_bf16 v[30:33], v[218:221], v[118:121], v[30:33]
	s_waitcnt lgkmcnt(3)
	v_mfma_f32_16x16x32_bf16 v[34:37], v[218:221], v[222:225], v[74:77]
	s_nop 0
	s_nop 1
	s_nop 0
	s_waitcnt lgkmcnt(1)
	v_mfma_f32_16x16x32_bf16 v[78:81], v[178:181], v[182:185], v[30:33]
	s_waitcnt lgkmcnt(0)
	v_mfma_f32_16x16x32_bf16 v[74:77], v[178:181], v[186:189], v[34:37]
	s_nop 5
	v_cvt_pk_bf16_f32 v30, v78, v79
	v_cvt_pk_bf16_f32 v31, v80, v81
	v_cvt_pk_bf16_f32 v32, v74, v75
	v_cvt_pk_bf16_f32 v33, v76, v77
	ds_write2st64_b64 v151, v[30:31], v[32:33] offset1:9
	s_waitcnt vmcnt(20)
	ds_write_b128 v127, v[22:25]
	s_waitcnt vmcnt(19)
	ds_write_b128 v143, v[26:29] offset:10240
	s_waitcnt vmcnt(18)
	ds_write_b128 v144, v[90:93] offset:10240
	s_waitcnt vmcnt(17)
	ds_write_b128 v127, v[94:97] offset:28672
	s_waitcnt vmcnt(16)
	ds_write_b128 v148, v[102:105] offset:28672
	s_and_saveexec_b64 s[8:9], vcc
	s_cbranch_execz .LBB0_1909
	s_waitcnt vmcnt(15)
	ds_write_b128 v127, v[86:89] offset:49152

.LBB0_1911:
	s_or_b64 exec, exec, s[8:9]
	s_or_b32 s0, s46, 36
	s_ashr_i32 s1, s0, 31
	s_lshl_b64 s[8:9], s[0:1], 13
	s_lshl_b64 s[68:69], s[0:1], 14
	s_add_u32 s70, s73, s68
	s_addc_u32 s71, s38, s69
	s_add_u32 s68, s39, s68
	s_waitcnt vmcnt(14)
	v_lshl_add_u64 v[6:7], v[138:139], 0, s[8:9]
	s_addc_u32 s69, s11, s69
	v_lshl_add_u64 v[8:9], s[70:71], 0, v[128:129]
	global_load_dwordx4 v[22:25], v[6:7], off
	global_load_dwordx4 v[26:29], v[8:9], off
	v_lshl_add_u64 v[6:7], s[70:71], 0, v[130:131]
	s_lshl_b64 s[78:79], s[0:1], 15
	v_lshl_add_u64 v[8:9], s[68:69], 0, v[128:129]
	global_load_dwordx4 v[34:37], v[6:7], off
	global_load_dwordx4 v[38:41], v[8:9], off
	v_lshl_add_u64 v[6:7], s[68:69], 0, v[130:131]
	s_lshl_b64 s[0:1], s[0:1], 9
	v_lshl_add_u64 v[8:9], v[136:137], 0, s[78:79]
	global_load_dwordx4 v[50:53], v[6:7], off
	global_load_dwordx4 v[30:33], v[8:9], off
	v_lshl_add_u64 v[6:7], v[134:135], 0, s[0:1]
	global_load_dwordx4 v[6:9], v[6:7], off
	v_cvt_pk_bf16_f32 v88, v110, v110
	s_mov_b64 s[0:1], 0xa0000
	v_and_b32_e32 v88, 0xffff, v88
	v_lshl_add_u64 v[86:87], v[132:133], 0, s[0:1]
	global_store_short v[86:87], v88, off
	v_cvt_pk_bf16_f32 v88, v111, v111
	s_mov_b64 s[0:1], 0xa0800
	v_and_b32_e32 v88, 0xffff, v88
	v_lshl_add_u64 v[86:87], v[132:133], 0, s[0:1]
	global_store_short v[86:87], v88, off
	v_cvt_pk_bf16_f32 v88, v112, v112
	s_mov_b64 s[0:1], 0xa1000
	v_and_b32_e32 v88, 0xffff, v88
	v_lshl_add_u64 v[86:87], v[132:133], 0, s[0:1]
	global_store_short v[86:87], v88, off
	s_mov_b64 s[0:1], 0xa1800
	v_cvt_pk_bf16_f32 v88, v113, v113
	v_lshl_add_u64 v[86:87], v[132:133], 0, s[0:1]
	v_and_b32_e32 v88, 0xffff, v88
	global_store_short v[86:87], v88, off
	s_waitcnt lgkmcnt(0)
	s_barrier
	ds_read_b128 v[86:89], v149
	ds_read_b128 v[90:93], v149 offset:64
	ds_read_b128 v[94:97], v156 offset:49152
	ds_read_b128 v[102:105], v156 offset:49216
	ds_read_b128 v[178:181], v147 offset:10240
	ds_read_b128 v[182:185], v153
	ds_read_b128 v[186:189], v147 offset:10304
	ds_read_b128 v[110:113], v153 offset:64
	ds_read_b128 v[190:193], v147 offset:10368
	ds_read_b128 v[206:209], v153 offset:128
	ds_read_b128 v[210:213], v147 offset:10432
	ds_read_b128 v[214:217], v153 offset:192
	ds_read_b128 v[118:121], v155 offset:28672
	ds_read_b128 v[218:221], v165 offset:54272
	ds_read_b128 v[222:225], v154 offset:49152
	s_waitcnt lgkmcnt(12)
	v_mfma_f32_16x16x32_bf16 v[86:89], v[86:89], v[94:97], 0
	s_nop 0
	s_waitcnt lgkmcnt(11)
	v_mfma_f32_16x16x32_bf16 v[86:89], v[90:93], v[102:105], v[86:89]
	s_nop 0
	s_nop 0
	s_nop 0
	s_waitcnt lgkmcnt(9)
	v_mfma_f32_16x16x32_bf16 v[86:89], v[178:181], v[182:185], v[86:89]
	ds_read_b128 v[178:181], v154 offset:51712
	ds_read_b128 v[182:185], v155 offset:28736
	s_nop 0
	s_nop 0
	s_waitcnt lgkmcnt(9)
	v_mfma_f32_16x16x32_bf16 v[86:89], v[186:189], v[110:113], v[86:89]
	ds_read_b128 v[186:189], v154 offset:49216
	s_nop 0
	s_nop 0
	s_nop 0
	s_waitcnt lgkmcnt(8)
	v_mfma_f32_16x16x32_bf16 v[86:89], v[190:193], v[206:209], v[86:89]
	ds_read_b128 v[190:193], v154 offset:51776
	s_nop 0
	s_nop 0
	s_waitcnt lgkmcnt(5)
	v_pk_mul_f32 v[80:81], v[80:81], v[220:221]
	v_mfma_f32_16x16x32_bf16 v[114:117], v[210:213], v[214:217], v[86:89]
	v_mul_f32_e64 v78, v78, v218
	v_mul_f32_e64 v79, v79, v219
	v_pk_mul_f32 v[76:77], v[76:77], v[220:221]
	v_pk_mul_f32 v[74:75], v[74:75], v[218:219]
	s_nop 0
	s_waitcnt lgkmcnt(4)
	v_mfma_f32_16x16x32_bf16 v[78:81], v[118:121], v[222:225], v[78:81]
	s_nop 0
	s_waitcnt lgkmcnt(3)
	v_mfma_f32_16x16x32_bf16 v[74:77], v[118:121], v[178:181], v[74:77]
	s_nop 0
	s_waitcnt lgkmcnt(1)
	v_mfma_f32_16x16x32_bf16 v[86:89], v[182:185], v[186:189], v[78:81]
	s_nop 2
	s_nop 0
	s_waitcnt lgkmcnt(0)
	v_mfma_f32_16x16x32_bf16 v[102:105], v[182:185], v[190:193], v[74:77]
	s_nop 2
	v_cvt_pk_bf16_f32 v74, v86, v87
	v_cvt_pk_bf16_f32 v75, v88, v89
	s_nop 2
	v_cvt_pk_bf16_f32 v76, v102, v103
	v_cvt_pk_bf16_f32 v77, v104, v105
	ds_write2st64_b64 v151, v[74:75], v[76:77] offset0:18 offset1:27
	s_waitcnt vmcnt(20)
	ds_write_b128 v127, v[10:13] offset:54784
	s_waitcnt vmcnt(19)
	ds_write_b128 v143, v[14:17] offset:65024
	s_waitcnt vmcnt(18)
	ds_write_b128 v144, v[54:57] offset:65024
	s_waitcnt vmcnt(17)
	ds_write_b128 v159, v[58:61]
	s_waitcnt vmcnt(16)
	ds_write_b128 v160, v[66:69]
	s_and_saveexec_b64 s[8:9], vcc
	s_cbranch_execz .LBB0_1913
	s_waitcnt vmcnt(15)
	ds_write_b128 v158, v[18:21]

.LBB0_1915:
	s_or_b64 exec, exec, s[8:9]
	s_or_b32 s0, s46, 40
	s_ashr_i32 s1, s0, 31
	s_lshl_b64 s[8:9], s[0:1], 13
	s_lshl_b64 s[68:69], s[0:1], 14
	s_add_u32 s70, s73, s68
	s_addc_u32 s71, s38, s69
	s_add_u32 s68, s39, s68
	s_waitcnt vmcnt(14)
	v_lshl_add_u64 v[2:3], v[138:139], 0, s[8:9]
	s_addc_u32 s69, s11, s69
	v_lshl_add_u64 v[4:5], s[70:71], 0, v[128:129]
	global_load_dwordx4 v[66:69], v[2:3], off
	global_load_dwordx4 v[74:77], v[4:5], off
	v_lshl_add_u64 v[2:3], s[70:71], 0, v[130:131]
	s_lshl_b64 s[78:79], s[0:1], 15
	v_lshl_add_u64 v[4:5], s[68:69], 0, v[128:129]
	global_load_dwordx4 v[90:93], v[2:3], off
	global_load_dwordx4 v[94:97], v[4:5], off
	v_lshl_add_u64 v[2:3], s[68:69], 0, v[130:131]
	s_lshl_b64 s[0:1], s[0:1], 9
	v_lshl_add_u64 v[4:5], v[136:137], 0, s[78:79]
	global_load_dwordx4 v[110:113], v[2:3], off
	global_load_dwordx4 v[78:81], v[4:5], off
	v_lshl_add_u64 v[2:3], v[134:135], 0, s[0:1]
	global_load_dwordx4 v[58:61], v[2:3], off
	v_cvt_pk_bf16_f32 v4, v114, v114
	s_mov_b64 s[0:1], 0xc0000
	v_and_b32_e32 v4, 0xffff, v4
	v_lshl_add_u64 v[2:3], v[132:133], 0, s[0:1]
	global_store_short v[2:3], v4, off
	v_cvt_pk_bf16_f32 v4, v115, v115
	s_mov_b64 s[0:1], 0xc0800
	v_and_b32_e32 v4, 0xffff, v4
	v_lshl_add_u64 v[2:3], v[132:133], 0, s[0:1]
	global_store_short v[2:3], v4, off
	v_cvt_pk_bf16_f32 v4, v116, v116
	s_mov_b64 s[0:1], 0xc1000
	v_and_b32_e32 v4, 0xffff, v4
	v_lshl_add_u64 v[2:3], v[132:133], 0, s[0:1]
	global_store_short v[2:3], v4, off
	s_mov_b64 s[0:1], 0xc1800
	v_cvt_pk_bf16_f32 v4, v117, v117
	v_lshl_add_u64 v[2:3], v[132:133], 0, s[0:1]
	v_and_b32_e32 v4, 0xffff, v4
	global_store_short v[2:3], v4, off
	s_waitcnt lgkmcnt(0)
	s_barrier
	ds_read_b128 v[2:5], v149 offset:54784
	ds_read_b128 v[10:13], v162
	ds_read_b128 v[14:17], v149 offset:54848
	ds_read_b128 v[18:21], v162 offset:64
	ds_read_b128 v[178:181], v147 offset:65024
	ds_read_b128 v[54:57], v153 offset:9216
	ds_read_b128 v[182:185], v147 offset:65088
	ds_read_b128 v[186:189], v153 offset:9280
	ds_read_b128 v[190:193], v147 offset:65152
	ds_read_b128 v[206:209], v153 offset:9344
	ds_read_b128 v[210:213], v147 offset:65216
	ds_read_b128 v[214:217], v153 offset:9408
	ds_read_b128 v[218:221], v161
	ds_read_b128 v[222:225], v166
	ds_read_b128 v[118:121], v163
	s_waitcnt lgkmcnt(13)
	v_mfma_f32_16x16x32_bf16 v[2:5], v[2:5], v[10:13], 0
	s_nop 0
	s_nop 0
	s_waitcnt lgkmcnt(11)
	v_mfma_f32_16x16x32_bf16 v[2:5], v[14:17], v[18:21], v[2:5]
	s_nop 0
	s_nop 0
	s_waitcnt lgkmcnt(9)
	v_mfma_f32_16x16x32_bf16 v[2:5], v[178:181], v[54:57], v[2:5]
	ds_read_b128 v[178:181], v163 offset:2560
	s_nop 0
	s_nop 0
	s_waitcnt lgkmcnt(8)
	v_mfma_f32_16x16x32_bf16 v[2:5], v[182:185], v[186:189], v[2:5]
	ds_read_b128 v[182:185], v161 offset:64
	ds_read_b128 v[186:189], v164
	s_nop 0
	s_nop 0
	s_waitcnt lgkmcnt(8)
	v_mfma_f32_16x16x32_bf16 v[2:5], v[190:193], v[206:209], v[2:5]
	ds_read_b128 v[190:193], v164 offset:2560
	s_nop 0
	s_nop 0
	s_nop 0
	s_waitcnt lgkmcnt(7)
	v_mfma_f32_16x16x32_bf16 v[114:117], v[210:213], v[214:217], v[2:5]
	s_nop 0
	s_nop 0
	s_waitcnt lgkmcnt(5)
	v_pk_mul_f32 v[4:5], v[88:89], v[224:225]
	v_pk_mul_f32 v[2:3], v[86:87], v[222:223]
	v_pk_mul_f32 v[56:57], v[104:105], v[224:225]
	v_pk_mul_f32 v[54:55], v[102:103], v[222:223]
	s_waitcnt lgkmcnt(4)
	v_mfma_f32_16x16x32_bf16 v[2:5], v[218:221], v[118:121], v[2:5]
	s_waitcnt lgkmcnt(3)
	v_mfma_f32_16x16x32_bf16 v[10:13], v[218:221], v[178:181], v[54:57]
	s_nop 0
	s_nop 1
	s_nop 0
	s_waitcnt lgkmcnt(1)
	v_mfma_f32_16x16x32_bf16 v[102:105], v[182:185], v[186:189], v[2:5]
	s_waitcnt lgkmcnt(0)
	v_mfma_f32_16x16x32_bf16 v[86:89], v[182:185], v[190:193], v[10:13]
	s_nop 5
	v_cvt_pk_bf16_f32 v2, v102, v103
	v_cvt_pk_bf16_f32 v3, v104, v105
	v_cvt_pk_bf16_f32 v4, v86, v87
	v_cvt_pk_bf16_f32 v5, v88, v89
	ds_write2st64_b64 v151, v[2:3], v[4:5] offset1:9
	s_waitcnt vmcnt(20)
	ds_write_b128 v127, v[46:49]
	s_waitcnt vmcnt(19)
	ds_write_b128 v143, v[62:65] offset:10240
	s_waitcnt vmcnt(18)
	ds_write_b128 v144, v[82:85] offset:10240
	s_waitcnt vmcnt(17)
	ds_write_b128 v127, v[98:101] offset:28672
	s_waitcnt vmcnt(16)
	ds_write_b128 v148, v[106:109] offset:28672
	s_and_saveexec_b64 s[8:9], vcc
	s_cbranch_execz .LBB0_1917
	s_waitcnt vmcnt(15)
	ds_write_b128 v127, v[70:73] offset:49152

.LBB0_1919:
	s_or_b64 exec, exec, s[8:9]
	s_or_b32 s0, s46, 44
	s_ashr_i32 s1, s0, 31
	s_lshl_b64 s[8:9], s[0:1], 13
	s_lshl_b64 s[68:69], s[0:1], 14
	s_add_u32 s70, s73, s68
	s_addc_u32 s71, s38, s69
	s_add_u32 s68, s39, s68
	v_lshl_add_u64 v[2:3], v[138:139], 0, s[8:9]
	s_addc_u32 s69, s11, s69
	v_lshl_add_u64 v[4:5], s[70:71], 0, v[128:129]
	global_load_dwordx4 v[10:13], v[2:3], off
	global_load_dwordx4 v[14:17], v[4:5], off
	v_lshl_add_u64 v[2:3], s[70:71], 0, v[130:131]
	s_lshl_b64 s[78:79], s[0:1], 15
	v_lshl_add_u64 v[4:5], s[68:69], 0, v[128:129]
	global_load_dwordx4 v[42:45], v[2:3], off
	global_load_dwordx4 v[46:49], v[4:5], off
	v_lshl_add_u64 v[2:3], s[68:69], 0, v[130:131]
	s_lshl_b64 s[0:1], s[0:1], 9
	v_lshl_add_u64 v[4:5], v[136:137], 0, s[78:79]
	global_load_dwordx4 v[54:57], v[2:3], off
	global_load_dwordx4 v[18:21], v[4:5], off
	v_lshl_add_u64 v[2:3], v[134:135], 0, s[0:1]
	global_load_dwordx4 v[2:5], v[2:3], off
	v_cvt_pk_bf16_f32 v64, v114, v114
	s_mov_b64 s[0:1], 0xe0000
	v_and_b32_e32 v64, 0xffff, v64
	v_lshl_add_u64 v[62:63], v[132:133], 0, s[0:1]
	global_store_short v[62:63], v64, off
	v_cvt_pk_bf16_f32 v64, v115, v115
	s_mov_b64 s[0:1], 0xe0800
	v_and_b32_e32 v64, 0xffff, v64
	v_lshl_add_u64 v[62:63], v[132:133], 0, s[0:1]
	global_store_short v[62:63], v64, off
	v_cvt_pk_bf16_f32 v64, v116, v116
	s_mov_b64 s[0:1], 0xe1000
	v_and_b32_e32 v64, 0xffff, v64
	v_lshl_add_u64 v[62:63], v[132:133], 0, s[0:1]
	global_store_short v[62:63], v64, off
	s_mov_b64 s[0:1], 0xe1800
	v_cvt_pk_bf16_f32 v64, v117, v117
	v_lshl_add_u64 v[62:63], v[132:133], 0, s[0:1]
	v_and_b32_e32 v64, 0xffff, v64
	global_store_short v[62:63], v64, off
	s_waitcnt lgkmcnt(0)
	s_barrier
	ds_read_b128 v[62:65], v149
	ds_read_b128 v[70:73], v149 offset:64
	ds_read_b128 v[82:85], v156 offset:49152
	ds_read_b128 v[98:101], v156 offset:49216
	ds_read_b128 v[178:181], v147 offset:10240
	ds_read_b128 v[182:185], v153
	ds_read_b128 v[186:189], v147 offset:10304
	ds_read_b128 v[106:109], v153 offset:64
	ds_read_b128 v[190:193], v147 offset:10368
	ds_read_b128 v[206:209], v153 offset:128
	ds_read_b128 v[210:213], v147 offset:10432
	ds_read_b128 v[214:217], v153 offset:192
	ds_read_b128 v[114:117], v155 offset:28672
	ds_read_b128 v[218:221], v165 offset:54272
	ds_read_b128 v[222:225], v154 offset:49152
	s_waitcnt vmcnt(22)
	s_nop 0
	s_nop 0
	s_nop 0
	s_waitcnt lgkmcnt(12)
	v_mfma_f32_16x16x32_bf16 v[62:65], v[62:65], v[82:85], 0
	s_nop 0
	s_waitcnt lgkmcnt(11)
	v_mfma_f32_16x16x32_bf16 v[62:65], v[70:73], v[98:101], v[62:65]
	s_nop 0
	s_nop 0
	s_nop 0
	s_waitcnt lgkmcnt(9)
	v_mfma_f32_16x16x32_bf16 v[62:65], v[178:181], v[182:185], v[62:65]
	ds_read_b128 v[178:181], v154 offset:51712
	ds_read_b128 v[182:185], v155 offset:28736
	s_nop 0
	s_nop 0
	s_waitcnt lgkmcnt(9)
	v_mfma_f32_16x16x32_bf16 v[62:65], v[186:189], v[106:109], v[62:65]
	ds_read_b128 v[186:189], v154 offset:49216
	s_nop 0
	s_nop 0
	s_nop 0
	s_waitcnt lgkmcnt(8)
	v_mfma_f32_16x16x32_bf16 v[62:65], v[190:193], v[206:209], v[62:65]
	ds_read_b128 v[190:193], v154 offset:51776
	s_nop 0
	s_nop 0
	s_waitcnt lgkmcnt(7)
	v_mfma_f32_16x16x32_bf16 v[122:125], v[210:213], v[214:217], v[62:65]
	s_nop 0
	s_waitcnt lgkmcnt(5)
	s_nop 1
	v_pk_mul_f32 v[64:65], v[104:105], v[220:221]
	v_pk_mul_f32 v[62:63], v[102:103], v[218:219]
	v_pk_mul_f32 v[72:73], v[88:89], v[220:221]
	v_pk_mul_f32 v[70:71], v[86:87], v[218:219]
	s_waitcnt lgkmcnt(4)
	v_mfma_f32_16x16x32_bf16 v[62:65], v[114:117], v[222:225], v[62:65]
	s_nop 0
	s_nop 0
	s_waitcnt lgkmcnt(3)
	v_mfma_f32_16x16x32_bf16 v[70:73], v[114:117], v[178:181], v[70:73]
	s_waitcnt lgkmcnt(1)
	v_mfma_f32_16x16x32_bf16 v[114:117], v[182:185], v[186:189], v[62:65]
	s_nop 2
	s_nop 0
	s_waitcnt lgkmcnt(0)
	v_mfma_f32_16x16x32_bf16 v[118:121], v[182:185], v[190:193], v[70:73]
	s_nop 1
	v_cvt_pk_bf16_f32 v62, v114, v115
	v_cvt_pk_bf16_f32 v63, v116, v117
	s_nop 3
	v_cvt_pk_bf16_f32 v64, v118, v119
	v_cvt_pk_bf16_f32 v65, v120, v121
	ds_write2st64_b64 v151, v[62:63], v[64:65] offset0:18 offset1:27
	s_waitcnt vmcnt(20)
	ds_write_b128 v127, v[22:25] offset:54784
	s_waitcnt vmcnt(19)
	ds_write_b128 v143, v[26:29] offset:65024
	s_waitcnt vmcnt(18)
	ds_write_b128 v144, v[34:37] offset:65024
	s_waitcnt vmcnt(17)
	ds_write_b128 v159, v[38:41]
	s_waitcnt vmcnt(16)
	ds_write_b128 v160, v[50:53]
	s_and_saveexec_b64 s[8:9], vcc
	s_cbranch_execz .LBB0_1921
	s_waitcnt vmcnt(15)
	ds_write_b128 v158, v[30:33]

.LBB0_1923:
	s_or_b64 exec, exec, s[8:9]
	s_or_b32 s0, s46, 48
	s_ashr_i32 s1, s0, 31
	s_lshl_b64 s[8:9], s[0:1], 13
	s_lshl_b64 s[68:69], s[0:1], 14
	s_add_u32 s70, s73, s68
	s_addc_u32 s71, s38, s69
	s_add_u32 s68, s39, s68
	s_waitcnt vmcnt(14)
	v_lshl_add_u64 v[6:7], v[138:139], 0, s[8:9]
	s_addc_u32 s69, s11, s69
	v_lshl_add_u64 v[8:9], s[70:71], 0, v[128:129]
	global_load_dwordx4 v[70:73], v[6:7], off
	global_load_dwordx4 v[82:85], v[8:9], off
	v_lshl_add_u64 v[6:7], s[70:71], 0, v[130:131]
	s_lshl_b64 s[78:79], s[0:1], 15
	v_lshl_add_u64 v[8:9], s[68:69], 0, v[128:129]
	global_load_dwordx4 v[98:101], v[6:7], off
	global_load_dwordx4 v[102:105], v[8:9], off
	v_lshl_add_u64 v[6:7], s[68:69], 0, v[130:131]
	s_lshl_b64 s[0:1], s[0:1], 9
	v_lshl_add_u64 v[8:9], v[136:137], 0, s[78:79]
	global_load_dwordx4 v[106:109], v[6:7], off
	global_load_dwordx4 v[86:89], v[8:9], off
	v_lshl_add_u64 v[6:7], v[134:135], 0, s[0:1]
	global_load_dwordx4 v[62:65], v[6:7], off
	v_cvt_pk_bf16_f32 v8, v122, v122
	s_mov_b64 s[0:1], 0x100000
	v_and_b32_e32 v8, 0xffff, v8
	v_lshl_add_u64 v[6:7], v[132:133], 0, s[0:1]
	global_store_short v[6:7], v8, off
	v_cvt_pk_bf16_f32 v8, v123, v123
	s_mov_b64 s[0:1], 0x100800
	v_and_b32_e32 v8, 0xffff, v8
	v_lshl_add_u64 v[6:7], v[132:133], 0, s[0:1]
	global_store_short v[6:7], v8, off
	v_cvt_pk_bf16_f32 v8, v124, v124
	s_mov_b64 s[0:1], 0x101000
	v_and_b32_e32 v8, 0xffff, v8
	v_lshl_add_u64 v[6:7], v[132:133], 0, s[0:1]
	global_store_short v[6:7], v8, off
	s_mov_b64 s[0:1], 0x101800
	v_cvt_pk_bf16_f32 v8, v125, v125
	v_lshl_add_u64 v[6:7], v[132:133], 0, s[0:1]
	v_and_b32_e32 v8, 0xffff, v8
	global_store_short v[6:7], v8, off
	s_waitcnt lgkmcnt(0)
	s_barrier
	ds_read_b128 v[6:9], v149 offset:54784
	ds_read_b128 v[22:25], v162
	ds_read_b128 v[26:29], v149 offset:54848
	ds_read_b128 v[30:33], v162 offset:64
	ds_read_b128 v[178:181], v147 offset:65024
	ds_read_b128 v[34:37], v153 offset:9216
	ds_read_b128 v[182:185], v147 offset:65088
	ds_read_b128 v[186:189], v153 offset:9280
	ds_read_b128 v[190:193], v147 offset:65152
	ds_read_b128 v[206:209], v153 offset:9344
	ds_read_b128 v[210:213], v147 offset:65216
	ds_read_b128 v[214:217], v153 offset:9408
	ds_read_b128 v[218:221], v161
	ds_read_b128 v[222:225], v166
	ds_read_b128 v[38:41], v163
	s_waitcnt lgkmcnt(13)
	v_mfma_f32_16x16x32_bf16 v[6:9], v[6:9], v[22:25], 0
	s_nop 0
	s_nop 0
	s_waitcnt lgkmcnt(11)
	v_mfma_f32_16x16x32_bf16 v[6:9], v[26:29], v[30:33], v[6:9]
	s_nop 0
	s_nop 0
	s_waitcnt lgkmcnt(9)
	v_mfma_f32_16x16x32_bf16 v[6:9], v[178:181], v[34:37], v[6:9]
	ds_read_b128 v[178:181], v163 offset:2560
	s_nop 0
	s_nop 0
	s_waitcnt lgkmcnt(8)
	v_mfma_f32_16x16x32_bf16 v[6:9], v[182:185], v[186:189], v[6:9]
	ds_read_b128 v[182:185], v161 offset:64
	ds_read_b128 v[186:189], v164
	s_nop 0
	s_nop 0
	s_waitcnt lgkmcnt(8)
	v_mfma_f32_16x16x32_bf16 v[6:9], v[190:193], v[206:209], v[6:9]
	ds_read_b128 v[190:193], v164 offset:2560
	s_nop 0
	s_nop 0
	s_nop 0
	s_waitcnt lgkmcnt(7)
	v_mfma_f32_16x16x32_bf16 v[122:125], v[210:213], v[214:217], v[6:9]
	s_nop 0
	s_nop 0
	s_waitcnt lgkmcnt(5)
	v_pk_mul_f32 v[8:9], v[116:117], v[224:225]
	v_pk_mul_f32 v[6:7], v[114:115], v[222:223]
	v_pk_mul_f32 v[36:37], v[120:121], v[224:225]
	v_pk_mul_f32 v[34:35], v[118:119], v[222:223]
	s_waitcnt lgkmcnt(4)
	v_mfma_f32_16x16x32_bf16 v[6:9], v[218:221], v[38:41], v[6:9]
	s_waitcnt lgkmcnt(3)
	v_mfma_f32_16x16x32_bf16 v[22:25], v[218:221], v[178:181], v[34:37]
	s_nop 0
	s_nop 1
	s_nop 0
	s_waitcnt lgkmcnt(1)
	v_mfma_f32_16x16x32_bf16 v[118:121], v[182:185], v[186:189], v[6:9]
	s_waitcnt lgkmcnt(0)
	v_mfma_f32_16x16x32_bf16 v[114:117], v[182:185], v[190:193], v[22:25]
	s_nop 5
	v_cvt_pk_bf16_f32 v6, v118, v119
	v_cvt_pk_bf16_f32 v7, v120, v121
	v_cvt_pk_bf16_f32 v8, v114, v115
	v_cvt_pk_bf16_f32 v9, v116, v117
	ds_write2st64_b64 v151, v[6:7], v[8:9] offset1:9
	s_waitcnt vmcnt(20)
	ds_write_b128 v127, v[66:69]
	s_waitcnt vmcnt(19)
	ds_write_b128 v143, v[74:77] offset:10240
	s_waitcnt vmcnt(18)
	ds_write_b128 v144, v[90:93] offset:10240
	s_waitcnt vmcnt(17)
	ds_write_b128 v127, v[94:97] offset:28672
	s_waitcnt vmcnt(16)
	ds_write_b128 v148, v[110:113] offset:28672
	s_and_saveexec_b64 s[8:9], vcc
	s_cbranch_execz .LBB0_1925
	s_waitcnt vmcnt(15)
	ds_write_b128 v127, v[78:81] offset:49152

.LBB0_1927:
	s_or_b64 exec, exec, s[8:9]
	s_or_b32 s0, s46, 52
	s_ashr_i32 s1, s0, 31
	s_lshl_b64 s[8:9], s[0:1], 13
	s_lshl_b64 s[68:69], s[0:1], 14
	s_add_u32 s70, s73, s68
	s_addc_u32 s71, s38, s69
	s_add_u32 s68, s39, s68
	v_lshl_add_u64 v[6:7], v[138:139], 0, s[8:9]
	s_addc_u32 s69, s11, s69
	v_lshl_add_u64 v[8:9], s[70:71], 0, v[128:129]
	global_load_dwordx4 v[22:25], v[6:7], off
	global_load_dwordx4 v[26:29], v[8:9], off
	v_lshl_add_u64 v[6:7], s[70:71], 0, v[130:131]
	s_lshl_b64 s[78:79], s[0:1], 15
	v_lshl_add_u64 v[8:9], s[68:69], 0, v[128:129]
	global_load_dwordx4 v[34:37], v[6:7], off
	global_load_dwordx4 v[38:41], v[8:9], off
	v_lshl_add_u64 v[6:7], s[68:69], 0, v[130:131]
	s_lshl_b64 s[0:1], s[0:1], 9
	v_lshl_add_u64 v[8:9], v[136:137], 0, s[78:79]
	global_load_dwordx4 v[50:53], v[6:7], off
	global_load_dwordx4 v[30:33], v[8:9], off
	v_lshl_add_u64 v[6:7], v[134:135], 0, s[0:1]
	global_load_dwordx4 v[6:9], v[6:7], off
	s_waitcnt vmcnt(21)
	v_cvt_pk_bf16_f32 v60, v122, v122
	s_mov_b64 s[0:1], 0x120000
	v_and_b32_e32 v60, 0xffff, v60
	v_lshl_add_u64 v[58:59], v[132:133], 0, s[0:1]
	global_store_short v[58:59], v60, off
	v_cvt_pk_bf16_f32 v60, v123, v123
	s_mov_b64 s[0:1], 0x120800
	v_and_b32_e32 v60, 0xffff, v60
	v_lshl_add_u64 v[58:59], v[132:133], 0, s[0:1]
	global_store_short v[58:59], v60, off
	v_cvt_pk_bf16_f32 v60, v124, v124
	s_mov_b64 s[0:1], 0x121000
	v_and_b32_e32 v60, 0xffff, v60
	v_lshl_add_u64 v[58:59], v[132:133], 0, s[0:1]
	global_store_short v[58:59], v60, off
	s_mov_b64 s[0:1], 0x121800
	v_cvt_pk_bf16_f32 v60, v125, v125
	v_lshl_add_u64 v[58:59], v[132:133], 0, s[0:1]
	v_and_b32_e32 v60, 0xffff, v60
	global_store_short v[58:59], v60, off
	s_waitcnt lgkmcnt(0)
	s_barrier
	ds_read_b128 v[58:61], v149
	ds_read_b128 v[66:69], v149 offset:64
	ds_read_b128 v[74:77], v156 offset:49152
	ds_read_b128 v[78:81], v156 offset:49216
	ds_read_b128 v[178:181], v147 offset:10240
	ds_read_b128 v[182:185], v153
	ds_read_b128 v[186:189], v147 offset:10304
	ds_read_b128 v[90:93], v153 offset:64
	ds_read_b128 v[190:193], v147 offset:10368
	ds_read_b128 v[206:209], v153 offset:128
	ds_read_b128 v[210:213], v147 offset:10432
	ds_read_b128 v[214:217], v153 offset:192
	ds_read_b128 v[94:97], v155 offset:28672
	ds_read_b128 v[218:221], v165 offset:54272
	ds_read_b128 v[222:225], v154 offset:49152
	s_waitcnt lgkmcnt(12)
	v_mfma_f32_16x16x32_bf16 v[58:61], v[58:61], v[74:77], 0
	s_nop 0
	s_waitcnt lgkmcnt(11)
	v_mfma_f32_16x16x32_bf16 v[58:61], v[66:69], v[78:81], v[58:61]
	s_nop 0
	s_nop 0
	s_nop 0
	s_waitcnt lgkmcnt(9)
	v_mfma_f32_16x16x32_bf16 v[58:61], v[178:181], v[182:185], v[58:61]
	ds_read_b128 v[178:181], v154 offset:51712
	ds_read_b128 v[182:185], v155 offset:28736
	s_nop 0
	s_nop 0
	s_waitcnt lgkmcnt(9)
	v_mfma_f32_16x16x32_bf16 v[58:61], v[186:189], v[90:93], v[58:61]
	ds_read_b128 v[186:189], v154 offset:49216
	s_nop 0
	s_nop 0
	s_nop 0
	s_waitcnt lgkmcnt(8)
	v_mfma_f32_16x16x32_bf16 v[58:61], v[190:193], v[206:209], v[58:61]
	ds_read_b128 v[190:193], v154 offset:51776
	s_nop 0
	s_nop 0
	s_waitcnt lgkmcnt(7)
	v_mfma_f32_16x16x32_bf16 v[122:125], v[210:213], v[214:217], v[58:61]
	s_nop 0
	s_waitcnt lgkmcnt(5)
	s_nop 1
	v_pk_mul_f32 v[60:61], v[120:121], v[220:221]
	v_pk_mul_f32 v[58:59], v[118:119], v[218:219]
	v_pk_mul_f32 v[68:69], v[116:117], v[220:221]
	v_pk_mul_f32 v[66:67], v[114:115], v[218:219]
	s_waitcnt lgkmcnt(4)
	v_mfma_f32_16x16x32_bf16 v[58:61], v[94:97], v[222:225], v[58:61]
	s_nop 0
	s_waitcnt lgkmcnt(3)
	v_mfma_f32_16x16x32_bf16 v[66:69], v[94:97], v[178:181], v[66:69]
	s_nop 0
	s_waitcnt lgkmcnt(1)
	v_mfma_f32_16x16x32_bf16 v[114:117], v[182:185], v[186:189], v[58:61]
	s_nop 2
	s_nop 0
	s_waitcnt lgkmcnt(0)
	v_mfma_f32_16x16x32_bf16 v[118:121], v[182:185], v[190:193], v[66:69]
	s_nop 1
	v_cvt_pk_bf16_f32 v58, v114, v115
	v_cvt_pk_bf16_f32 v59, v116, v117
	s_nop 3
	v_cvt_pk_bf16_f32 v60, v118, v119
	v_cvt_pk_bf16_f32 v61, v120, v121
	ds_write2st64_b64 v151, v[58:59], v[60:61] offset0:18 offset1:27
	s_waitcnt vmcnt(20)
	ds_write_b128 v127, v[10:13] offset:54784
	s_waitcnt vmcnt(19)
	ds_write_b128 v143, v[14:17] offset:65024
	s_waitcnt vmcnt(18)
	ds_write_b128 v144, v[42:45] offset:65024
	s_waitcnt vmcnt(17)
	ds_write_b128 v159, v[46:49]
	s_waitcnt vmcnt(16)
	ds_write_b128 v160, v[54:57]
	s_and_saveexec_b64 s[8:9], vcc
	s_cbranch_execz .LBB0_1929
	s_waitcnt vmcnt(15)
	ds_write_b128 v158, v[18:21]

.LBB0_1931:
	s_or_b64 exec, exec, s[8:9]
	s_or_b32 s0, s46, 56
	s_ashr_i32 s1, s0, 31
	s_lshl_b64 s[8:9], s[0:1], 13
	s_lshl_b64 s[68:69], s[0:1], 14
	s_add_u32 s70, s73, s68
	s_addc_u32 s71, s38, s69
	s_add_u32 s68, s39, s68
	s_waitcnt vmcnt(14)
	v_lshl_add_u64 v[2:3], v[138:139], 0, s[8:9]
	s_addc_u32 s69, s11, s69
	v_lshl_add_u64 v[4:5], s[70:71], 0, v[128:129]
	global_load_dwordx4 v[66:69], v[2:3], off
	global_load_dwordx4 v[74:77], v[4:5], off
	v_lshl_add_u64 v[2:3], s[70:71], 0, v[130:131]
	s_lshl_b64 s[78:79], s[0:1], 15
	v_lshl_add_u64 v[4:5], s[68:69], 0, v[128:129]
	global_load_dwordx4 v[90:93], v[2:3], off
	global_load_dwordx4 v[94:97], v[4:5], off
	v_lshl_add_u64 v[2:3], s[68:69], 0, v[130:131]
	s_lshl_b64 s[0:1], s[0:1], 9
	v_lshl_add_u64 v[4:5], v[136:137], 0, s[78:79]
	global_load_dwordx4 v[110:113], v[2:3], off
	global_load_dwordx4 v[78:81], v[4:5], off
	v_lshl_add_u64 v[2:3], v[134:135], 0, s[0:1]
	global_load_dwordx4 v[58:61], v[2:3], off
	v_cvt_pk_bf16_f32 v4, v122, v122
	s_mov_b64 s[0:1], 0x140000
	v_and_b32_e32 v4, 0xffff, v4
	v_lshl_add_u64 v[2:3], v[132:133], 0, s[0:1]
	global_store_short v[2:3], v4, off
	v_cvt_pk_bf16_f32 v4, v123, v123
	s_mov_b64 s[0:1], 0x140800
	v_and_b32_e32 v4, 0xffff, v4
	v_lshl_add_u64 v[2:3], v[132:133], 0, s[0:1]
	global_store_short v[2:3], v4, off
	v_cvt_pk_bf16_f32 v4, v124, v124
	s_mov_b64 s[0:1], 0x141000
	v_and_b32_e32 v4, 0xffff, v4
	v_lshl_add_u64 v[2:3], v[132:133], 0, s[0:1]
	global_store_short v[2:3], v4, off
	s_mov_b64 s[0:1], 0x141800
	v_cvt_pk_bf16_f32 v4, v125, v125
	v_lshl_add_u64 v[2:3], v[132:133], 0, s[0:1]
	v_and_b32_e32 v4, 0xffff, v4
	global_store_short v[2:3], v4, off
	s_waitcnt lgkmcnt(0)
	s_barrier
	ds_read_b128 v[2:5], v149 offset:54784
	ds_read_b128 v[10:13], v162
	ds_read_b128 v[14:17], v149 offset:54848
	ds_read_b128 v[18:21], v162 offset:64
	ds_read_b128 v[178:181], v147 offset:65024
	ds_read_b128 v[42:45], v153 offset:9216
	ds_read_b128 v[182:185], v147 offset:65088
	ds_read_b128 v[186:189], v153 offset:9280
	ds_read_b128 v[190:193], v147 offset:65152
	ds_read_b128 v[206:209], v153 offset:9344
	ds_read_b128 v[210:213], v147 offset:65216
	ds_read_b128 v[214:217], v153 offset:9408
	ds_read_b128 v[218:221], v161
	ds_read_b128 v[222:225], v166
	ds_read_b128 v[46:49], v163
	s_waitcnt lgkmcnt(13)
	v_mfma_f32_16x16x32_bf16 v[2:5], v[2:5], v[10:13], 0
	s_nop 0
	s_nop 0
	s_waitcnt lgkmcnt(11)
	v_mfma_f32_16x16x32_bf16 v[2:5], v[14:17], v[18:21], v[2:5]
	s_nop 0
	s_nop 0
	s_waitcnt lgkmcnt(9)
	v_mfma_f32_16x16x32_bf16 v[2:5], v[178:181], v[42:45], v[2:5]
	ds_read_b128 v[178:181], v163 offset:2560
	s_nop 0
	s_nop 0
	s_waitcnt lgkmcnt(8)
	v_mfma_f32_16x16x32_bf16 v[2:5], v[182:185], v[186:189], v[2:5]
	ds_read_b128 v[182:185], v161 offset:64
	ds_read_b128 v[186:189], v164
	s_nop 0
	s_nop 0
	s_waitcnt lgkmcnt(8)
	v_mfma_f32_16x16x32_bf16 v[2:5], v[190:193], v[206:209], v[2:5]
	ds_read_b128 v[190:193], v164 offset:2560
	s_nop 0
	s_nop 0
	s_nop 0
	s_waitcnt lgkmcnt(7)
	v_mfma_f32_16x16x32_bf16 v[122:125], v[210:213], v[214:217], v[2:5]
	s_nop 0
	s_nop 0
	s_waitcnt lgkmcnt(5)
	v_pk_mul_f32 v[4:5], v[116:117], v[224:225]
	v_pk_mul_f32 v[2:3], v[114:115], v[222:223]
	v_pk_mul_f32 v[44:45], v[120:121], v[224:225]
	v_pk_mul_f32 v[42:43], v[118:119], v[222:223]
	s_waitcnt lgkmcnt(4)
	v_mfma_f32_16x16x32_bf16 v[2:5], v[218:221], v[46:49], v[2:5]
	s_waitcnt lgkmcnt(3)
	v_mfma_f32_16x16x32_bf16 v[10:13], v[218:221], v[178:181], v[42:45]
	s_nop 0
	s_nop 1
	s_nop 0
	s_waitcnt lgkmcnt(1)
	v_mfma_f32_16x16x32_bf16 v[118:121], v[182:185], v[186:189], v[2:5]
	s_waitcnt lgkmcnt(0)
	v_mfma_f32_16x16x32_bf16 v[114:117], v[182:185], v[190:193], v[10:13]
	s_nop 5
	v_cvt_pk_bf16_f32 v2, v118, v119
	v_cvt_pk_bf16_f32 v3, v120, v121
	v_cvt_pk_bf16_f32 v4, v114, v115
	v_cvt_pk_bf16_f32 v5, v116, v117
	ds_write2st64_b64 v151, v[2:3], v[4:5] offset1:9
	s_waitcnt vmcnt(20)
	ds_write_b128 v127, v[70:73]
	s_waitcnt vmcnt(19)
	ds_write_b128 v143, v[82:85] offset:10240
	s_waitcnt vmcnt(18)
	ds_write_b128 v144, v[98:101] offset:10240
	s_waitcnt vmcnt(17)
	ds_write_b128 v127, v[102:105] offset:28672
	s_waitcnt vmcnt(16)
	ds_write_b128 v148, v[106:109] offset:28672
	s_and_saveexec_b64 s[8:9], vcc
	s_cbranch_execz .LBB0_1933
	s_waitcnt vmcnt(15)
	ds_write_b128 v127, v[86:89] offset:49152

.LBB0_1935:
	s_or_b64 exec, exec, s[8:9]
	s_or_b32 s0, s46, 60
	s_ashr_i32 s1, s0, 31
	s_lshl_b64 s[8:9], s[0:1], 13
	s_lshl_b64 s[68:69], s[0:1], 14
	s_add_u32 s70, s73, s68
	s_addc_u32 s71, s38, s69
	s_add_u32 s68, s39, s68
	v_lshl_add_u64 v[2:3], v[138:139], 0, s[8:9]
	s_addc_u32 s69, s11, s69
	v_lshl_add_u64 v[4:5], s[70:71], 0, v[128:129]
	global_load_dwordx4 v[10:13], v[2:3], off
	global_load_dwordx4 v[14:17], v[4:5], off
	v_lshl_add_u64 v[2:3], s[70:71], 0, v[130:131]
	s_lshl_b64 s[78:79], s[0:1], 15
	v_lshl_add_u64 v[4:5], s[68:69], 0, v[128:129]
	global_load_dwordx4 v[42:45], v[2:3], off
	global_load_dwordx4 v[46:49], v[4:5], off
	v_lshl_add_u64 v[2:3], s[68:69], 0, v[130:131]
	s_lshl_b64 s[0:1], s[0:1], 9
	v_lshl_add_u64 v[4:5], v[136:137], 0, s[78:79]
	global_load_dwordx4 v[54:57], v[2:3], off
	global_load_dwordx4 v[18:21], v[4:5], off
	v_lshl_add_u64 v[2:3], v[134:135], 0, s[0:1]
	global_load_dwordx4 v[2:5], v[2:3], off
	s_waitcnt vmcnt(21)
	v_cvt_pk_bf16_f32 v64, v122, v122
	s_mov_b64 s[0:1], 0x160000
	v_and_b32_e32 v64, 0xffff, v64
	v_lshl_add_u64 v[62:63], v[132:133], 0, s[0:1]
	global_store_short v[62:63], v64, off
	v_cvt_pk_bf16_f32 v64, v123, v123
	s_mov_b64 s[0:1], 0x160800
	v_and_b32_e32 v64, 0xffff, v64
	v_lshl_add_u64 v[62:63], v[132:133], 0, s[0:1]
	global_store_short v[62:63], v64, off
	v_cvt_pk_bf16_f32 v64, v124, v124
	s_mov_b64 s[0:1], 0x161000
	v_and_b32_e32 v64, 0xffff, v64
	v_lshl_add_u64 v[62:63], v[132:133], 0, s[0:1]
	global_store_short v[62:63], v64, off
	s_mov_b64 s[0:1], 0x161800
	v_cvt_pk_bf16_f32 v64, v125, v125
	v_lshl_add_u64 v[62:63], v[132:133], 0, s[0:1]
	v_and_b32_e32 v64, 0xffff, v64
	global_store_short v[62:63], v64, off
	s_waitcnt lgkmcnt(0)
	s_barrier
	ds_read_b128 v[62:65], v149
	ds_read_b128 v[70:73], v149 offset:64
	ds_read_b128 v[82:85], v156 offset:49152
	ds_read_b128 v[86:89], v156 offset:49216
	ds_read_b128 v[178:181], v147 offset:10240
	ds_read_b128 v[182:185], v153
	ds_read_b128 v[186:189], v147 offset:10304
	ds_read_b128 v[98:101], v153 offset:64
	ds_read_b128 v[190:193], v147 offset:10368
	ds_read_b128 v[206:209], v153 offset:128
	ds_read_b128 v[210:213], v147 offset:10432
	ds_read_b128 v[214:217], v153 offset:192
	ds_read_b128 v[102:105], v155 offset:28672
	ds_read_b128 v[218:221], v165 offset:54272
	ds_read_b128 v[222:225], v154 offset:49152
	s_waitcnt lgkmcnt(12)
	v_mfma_f32_16x16x32_bf16 v[62:65], v[62:65], v[82:85], 0
	s_nop 0
	s_waitcnt lgkmcnt(11)
	v_mfma_f32_16x16x32_bf16 v[62:65], v[70:73], v[86:89], v[62:65]
	s_nop 0
	s_nop 0
	s_nop 0
	s_waitcnt lgkmcnt(9)
	v_mfma_f32_16x16x32_bf16 v[62:65], v[178:181], v[182:185], v[62:65]
	ds_read_b128 v[178:181], v154 offset:51712
	ds_read_b128 v[182:185], v155 offset:28736
	s_nop 0
	s_nop 0
	s_waitcnt lgkmcnt(9)
	v_mfma_f32_16x16x32_bf16 v[62:65], v[186:189], v[98:101], v[62:65]
	ds_read_b128 v[186:189], v154 offset:49216
	s_nop 0
	s_nop 0
	s_nop 0
	s_waitcnt lgkmcnt(8)
	v_mfma_f32_16x16x32_bf16 v[62:65], v[190:193], v[206:209], v[62:65]
	ds_read_b128 v[190:193], v154 offset:51776
	s_nop 0
	s_nop 0
	s_waitcnt lgkmcnt(7)
	v_mfma_f32_16x16x32_bf16 v[122:125], v[210:213], v[214:217], v[62:65]
	s_nop 0
	s_waitcnt lgkmcnt(5)
	s_nop 1
	v_pk_mul_f32 v[64:65], v[120:121], v[220:221]
	v_pk_mul_f32 v[62:63], v[118:119], v[218:219]
	v_pk_mul_f32 v[72:73], v[116:117], v[220:221]
	v_pk_mul_f32 v[70:71], v[114:115], v[218:219]
	s_waitcnt lgkmcnt(4)
	v_mfma_f32_16x16x32_bf16 v[62:65], v[102:105], v[222:225], v[62:65]
	s_nop 0
	s_waitcnt lgkmcnt(3)
	v_mfma_f32_16x16x32_bf16 v[70:73], v[102:105], v[178:181], v[70:73]
	s_nop 0
	s_waitcnt lgkmcnt(1)
	v_mfma_f32_16x16x32_bf16 v[114:117], v[182:185], v[186:189], v[62:65]
	s_nop 2
	s_nop 0
	s_waitcnt lgkmcnt(0)
	v_mfma_f32_16x16x32_bf16 v[118:121], v[182:185], v[190:193], v[70:73]
	s_nop 1
	v_cvt_pk_bf16_f32 v62, v114, v115
	v_cvt_pk_bf16_f32 v63, v116, v117
	s_nop 3
	v_cvt_pk_bf16_f32 v64, v118, v119
	v_cvt_pk_bf16_f32 v65, v120, v121
	ds_write2st64_b64 v151, v[62:63], v[64:65] offset0:18 offset1:27
	s_waitcnt vmcnt(20)
	ds_write_b128 v127, v[22:25] offset:54784
	s_waitcnt vmcnt(19)
	ds_write_b128 v143, v[26:29] offset:65024
	s_waitcnt vmcnt(18)
	ds_write_b128 v144, v[34:37] offset:65024
	s_waitcnt vmcnt(17)
	ds_write_b128 v159, v[38:41]
	s_waitcnt vmcnt(16)
	ds_write_b128 v160, v[50:53]
	s_and_saveexec_b64 s[8:9], vcc
	s_cbranch_execz .LBB0_1937
	s_waitcnt vmcnt(15)
	ds_write_b128 v158, v[30:33]

.LBB0_1939:
	s_or_b64 exec, exec, s[8:9]
	s_or_b32 s0, s46, 64
	s_ashr_i32 s1, s0, 31
	s_lshl_b64 s[8:9], s[0:1], 13
	s_lshl_b64 s[68:69], s[0:1], 14
	s_add_u32 s70, s73, s68
	s_addc_u32 s71, s38, s69
	s_add_u32 s68, s39, s68
	s_waitcnt vmcnt(14)
	v_lshl_add_u64 v[6:7], v[138:139], 0, s[8:9]
	s_addc_u32 s69, s11, s69
	v_lshl_add_u64 v[8:9], s[70:71], 0, v[128:129]
	global_load_dwordx4 v[70:73], v[6:7], off
	global_load_dwordx4 v[82:85], v[8:9], off
	v_lshl_add_u64 v[6:7], s[70:71], 0, v[130:131]
	s_lshl_b64 s[78:79], s[0:1], 15
	v_lshl_add_u64 v[8:9], s[68:69], 0, v[128:129]
	global_load_dwordx4 v[98:101], v[6:7], off
	global_load_dwordx4 v[102:105], v[8:9], off
	v_lshl_add_u64 v[6:7], s[68:69], 0, v[130:131]
	s_lshl_b64 s[0:1], s[0:1], 9
	v_lshl_add_u64 v[8:9], v[136:137], 0, s[78:79]
	global_load_dwordx4 v[106:109], v[6:7], off
	global_load_dwordx4 v[86:89], v[8:9], off
	v_lshl_add_u64 v[6:7], v[134:135], 0, s[0:1]
	global_load_dwordx4 v[62:65], v[6:7], off
	v_cvt_pk_bf16_f32 v8, v122, v122
	s_mov_b64 s[0:1], 0x180000
	v_and_b32_e32 v8, 0xffff, v8
	v_lshl_add_u64 v[6:7], v[132:133], 0, s[0:1]
	global_store_short v[6:7], v8, off
	v_cvt_pk_bf16_f32 v8, v123, v123
	s_mov_b64 s[0:1], 0x180800
	v_and_b32_e32 v8, 0xffff, v8
	v_lshl_add_u64 v[6:7], v[132:133], 0, s[0:1]
	global_store_short v[6:7], v8, off
	v_cvt_pk_bf16_f32 v8, v124, v124
	s_mov_b64 s[0:1], 0x181000
	v_and_b32_e32 v8, 0xffff, v8
	v_lshl_add_u64 v[6:7], v[132:133], 0, s[0:1]
	global_store_short v[6:7], v8, off
	s_mov_b64 s[0:1], 0x181800
	v_cvt_pk_bf16_f32 v8, v125, v125
	v_lshl_add_u64 v[6:7], v[132:133], 0, s[0:1]
	v_and_b32_e32 v8, 0xffff, v8
	global_store_short v[6:7], v8, off
	s_waitcnt lgkmcnt(0)
	s_barrier
	ds_read_b128 v[6:9], v149 offset:54784
	ds_read_b128 v[22:25], v162
	ds_read_b128 v[26:29], v149 offset:54848
	ds_read_b128 v[30:33], v162 offset:64
	ds_read_b128 v[178:181], v147 offset:65024
	ds_read_b128 v[34:37], v153 offset:9216
	ds_read_b128 v[182:185], v147 offset:65088
	ds_read_b128 v[186:189], v153 offset:9280
	ds_read_b128 v[190:193], v147 offset:65152
	ds_read_b128 v[206:209], v153 offset:9344
	ds_read_b128 v[210:213], v147 offset:65216
	ds_read_b128 v[214:217], v153 offset:9408
	ds_read_b128 v[218:221], v161
	ds_read_b128 v[222:225], v166
	ds_read_b128 v[38:41], v163
	s_waitcnt lgkmcnt(13)
	v_mfma_f32_16x16x32_bf16 v[6:9], v[6:9], v[22:25], 0
	s_nop 0
	s_nop 0
	s_waitcnt lgkmcnt(11)
	v_mfma_f32_16x16x32_bf16 v[6:9], v[26:29], v[30:33], v[6:9]
	s_nop 0
	s_nop 0
	s_waitcnt lgkmcnt(9)
	v_mfma_f32_16x16x32_bf16 v[6:9], v[178:181], v[34:37], v[6:9]
	ds_read_b128 v[178:181], v163 offset:2560
	s_nop 0
	s_nop 0
	s_waitcnt lgkmcnt(8)
	v_mfma_f32_16x16x32_bf16 v[6:9], v[182:185], v[186:189], v[6:9]
	ds_read_b128 v[182:185], v161 offset:64
	ds_read_b128 v[186:189], v164
	s_nop 0
	s_nop 0
	s_waitcnt lgkmcnt(8)
	v_mfma_f32_16x16x32_bf16 v[6:9], v[190:193], v[206:209], v[6:9]
	ds_read_b128 v[190:193], v164 offset:2560
	s_nop 0
	s_nop 0
	s_nop 0
	s_waitcnt lgkmcnt(7)
	v_mfma_f32_16x16x32_bf16 v[122:125], v[210:213], v[214:217], v[6:9]
	s_nop 0
	s_nop 0
	s_waitcnt lgkmcnt(5)
	v_pk_mul_f32 v[8:9], v[116:117], v[224:225]
	v_pk_mul_f32 v[6:7], v[114:115], v[222:223]
	v_pk_mul_f32 v[36:37], v[120:121], v[224:225]
	v_pk_mul_f32 v[34:35], v[118:119], v[222:223]
	s_waitcnt lgkmcnt(4)
	v_mfma_f32_16x16x32_bf16 v[6:9], v[218:221], v[38:41], v[6:9]
	s_waitcnt lgkmcnt(3)
	v_mfma_f32_16x16x32_bf16 v[22:25], v[218:221], v[178:181], v[34:37]
	s_nop 0
	s_nop 1
	s_nop 0
	s_waitcnt lgkmcnt(1)
	v_mfma_f32_16x16x32_bf16 v[118:121], v[182:185], v[186:189], v[6:9]
	s_waitcnt lgkmcnt(0)
	v_mfma_f32_16x16x32_bf16 v[114:117], v[182:185], v[190:193], v[22:25]
	s_nop 5
	v_cvt_pk_bf16_f32 v6, v118, v119
	v_cvt_pk_bf16_f32 v7, v120, v121
	v_cvt_pk_bf16_f32 v8, v114, v115
	v_cvt_pk_bf16_f32 v9, v116, v117
	ds_write2st64_b64 v151, v[6:7], v[8:9] offset1:9
	s_waitcnt vmcnt(20)
	ds_write_b128 v127, v[66:69]
	s_waitcnt vmcnt(19)
	ds_write_b128 v143, v[74:77] offset:10240
	s_waitcnt vmcnt(18)
	ds_write_b128 v144, v[90:93] offset:10240
	s_waitcnt vmcnt(17)
	ds_write_b128 v127, v[94:97] offset:28672
	s_waitcnt vmcnt(16)
	ds_write_b128 v148, v[110:113] offset:28672
	s_and_saveexec_b64 s[8:9], vcc
	s_cbranch_execz .LBB0_1941
	s_waitcnt vmcnt(15)
	ds_write_b128 v127, v[78:81] offset:49152

.LBB0_1943:
	s_or_b64 exec, exec, s[8:9]
	s_or_b32 s0, s46, 0x44
	s_ashr_i32 s1, s0, 31
	s_lshl_b64 s[8:9], s[0:1], 13
	s_lshl_b64 s[68:69], s[0:1], 14
	s_add_u32 s70, s73, s68
	s_addc_u32 s71, s38, s69
	s_add_u32 s68, s39, s68
	v_lshl_add_u64 v[6:7], v[138:139], 0, s[8:9]
	s_addc_u32 s69, s11, s69
	v_lshl_add_u64 v[8:9], s[70:71], 0, v[128:129]
	global_load_dwordx4 v[22:25], v[6:7], off
	global_load_dwordx4 v[26:29], v[8:9], off
	v_lshl_add_u64 v[6:7], s[70:71], 0, v[130:131]
	s_lshl_b64 s[78:79], s[0:1], 15
	v_lshl_add_u64 v[8:9], s[68:69], 0, v[128:129]
	global_load_dwordx4 v[34:37], v[6:7], off
	global_load_dwordx4 v[38:41], v[8:9], off
	v_lshl_add_u64 v[6:7], s[68:69], 0, v[130:131]
	s_lshl_b64 s[0:1], s[0:1], 9
	v_lshl_add_u64 v[8:9], v[136:137], 0, s[78:79]
	global_load_dwordx4 v[50:53], v[6:7], off
	global_load_dwordx4 v[30:33], v[8:9], off
	v_lshl_add_u64 v[6:7], v[134:135], 0, s[0:1]
	global_load_dwordx4 v[6:9], v[6:7], off
	s_waitcnt vmcnt(21)
	v_cvt_pk_bf16_f32 v60, v122, v122
	s_mov_b64 s[0:1], 0x1a0000
	v_and_b32_e32 v60, 0xffff, v60
	v_lshl_add_u64 v[58:59], v[132:133], 0, s[0:1]
	global_store_short v[58:59], v60, off
	v_cvt_pk_bf16_f32 v60, v123, v123
	s_mov_b64 s[0:1], 0x1a0800
	v_and_b32_e32 v60, 0xffff, v60
	v_lshl_add_u64 v[58:59], v[132:133], 0, s[0:1]
	global_store_short v[58:59], v60, off
	v_cvt_pk_bf16_f32 v60, v124, v124
	s_mov_b64 s[0:1], 0x1a1000
	v_and_b32_e32 v60, 0xffff, v60
	v_lshl_add_u64 v[58:59], v[132:133], 0, s[0:1]
	global_store_short v[58:59], v60, off
	s_mov_b64 s[0:1], 0x1a1800
	v_cvt_pk_bf16_f32 v60, v125, v125
	v_lshl_add_u64 v[58:59], v[132:133], 0, s[0:1]
	v_and_b32_e32 v60, 0xffff, v60
	global_store_short v[58:59], v60, off
	s_waitcnt lgkmcnt(0)
	s_barrier
	ds_read_b128 v[58:61], v149
	ds_read_b128 v[66:69], v149 offset:64
	ds_read_b128 v[74:77], v156 offset:49152
	ds_read_b128 v[78:81], v156 offset:49216
	ds_read_b128 v[178:181], v147 offset:10240
	ds_read_b128 v[182:185], v153
	ds_read_b128 v[186:189], v147 offset:10304
	ds_read_b128 v[90:93], v153 offset:64
	ds_read_b128 v[190:193], v147 offset:10368
	ds_read_b128 v[206:209], v153 offset:128
	ds_read_b128 v[210:213], v147 offset:10432
	ds_read_b128 v[214:217], v153 offset:192
	ds_read_b128 v[94:97], v155 offset:28672
	ds_read_b128 v[218:221], v165 offset:54272
	ds_read_b128 v[222:225], v154 offset:49152
	s_waitcnt lgkmcnt(12)
	v_mfma_f32_16x16x32_bf16 v[58:61], v[58:61], v[74:77], 0
	s_nop 0
	s_waitcnt lgkmcnt(11)
	v_mfma_f32_16x16x32_bf16 v[58:61], v[66:69], v[78:81], v[58:61]
	s_nop 0
	s_nop 0
	s_nop 0
	s_waitcnt lgkmcnt(9)
	v_mfma_f32_16x16x32_bf16 v[58:61], v[178:181], v[182:185], v[58:61]
	ds_read_b128 v[178:181], v154 offset:51712
	ds_read_b128 v[182:185], v155 offset:28736
	s_nop 0
	s_nop 0
	s_waitcnt lgkmcnt(9)
	v_mfma_f32_16x16x32_bf16 v[58:61], v[186:189], v[90:93], v[58:61]
	ds_read_b128 v[186:189], v154 offset:49216
	s_nop 0
	s_nop 0
	s_nop 0
	s_waitcnt lgkmcnt(8)
	v_mfma_f32_16x16x32_bf16 v[58:61], v[190:193], v[206:209], v[58:61]
	ds_read_b128 v[190:193], v154 offset:51776
	s_nop 0
	s_nop 0
	s_waitcnt lgkmcnt(7)
	v_mfma_f32_16x16x32_bf16 v[122:125], v[210:213], v[214:217], v[58:61]
	s_nop 0
	s_waitcnt lgkmcnt(5)
	s_nop 1
	v_pk_mul_f32 v[60:61], v[120:121], v[220:221]
	v_pk_mul_f32 v[58:59], v[118:119], v[218:219]
	v_pk_mul_f32 v[68:69], v[116:117], v[220:221]
	v_pk_mul_f32 v[66:67], v[114:115], v[218:219]
	s_waitcnt lgkmcnt(4)
	v_mfma_f32_16x16x32_bf16 v[58:61], v[94:97], v[222:225], v[58:61]
	s_nop 0
	s_waitcnt lgkmcnt(3)
	v_mfma_f32_16x16x32_bf16 v[66:69], v[94:97], v[178:181], v[66:69]
	s_nop 0
	s_waitcnt lgkmcnt(1)
	v_mfma_f32_16x16x32_bf16 v[114:117], v[182:185], v[186:189], v[58:61]
	s_nop 2
	s_nop 0
	s_waitcnt lgkmcnt(0)
	v_mfma_f32_16x16x32_bf16 v[118:121], v[182:185], v[190:193], v[66:69]
	s_nop 1
	v_cvt_pk_bf16_f32 v58, v114, v115
	v_cvt_pk_bf16_f32 v59, v116, v117
	s_nop 3
	v_cvt_pk_bf16_f32 v60, v118, v119
	v_cvt_pk_bf16_f32 v61, v120, v121
	ds_write2st64_b64 v151, v[58:59], v[60:61] offset0:18 offset1:27
	s_waitcnt vmcnt(20)
	ds_write_b128 v127, v[10:13] offset:54784
	s_waitcnt vmcnt(19)
	ds_write_b128 v143, v[14:17] offset:65024
	s_waitcnt vmcnt(18)
	ds_write_b128 v144, v[42:45] offset:65024
	s_waitcnt vmcnt(17)
	ds_write_b128 v159, v[46:49]
	s_waitcnt vmcnt(16)
	ds_write_b128 v160, v[54:57]
	s_and_saveexec_b64 s[8:9], vcc
	s_cbranch_execz .LBB0_1945
	s_waitcnt vmcnt(15)
	ds_write_b128 v158, v[18:21]

.LBB0_1947:
	s_or_b64 exec, exec, s[8:9]
	s_or_b32 s0, s46, 0x48
	s_ashr_i32 s1, s0, 31
	s_lshl_b64 s[8:9], s[0:1], 13
	s_lshl_b64 s[68:69], s[0:1], 14
	s_add_u32 s70, s73, s68
	s_addc_u32 s71, s38, s69
	s_add_u32 s68, s39, s68
	s_waitcnt vmcnt(14)
	v_lshl_add_u64 v[2:3], v[138:139], 0, s[8:9]
	s_addc_u32 s69, s11, s69
	v_lshl_add_u64 v[4:5], s[70:71], 0, v[128:129]
	global_load_dwordx4 v[66:69], v[2:3], off
	global_load_dwordx4 v[74:77], v[4:5], off
	v_lshl_add_u64 v[2:3], s[70:71], 0, v[130:131]
	s_lshl_b64 s[78:79], s[0:1], 15
	v_lshl_add_u64 v[4:5], s[68:69], 0, v[128:129]
	global_load_dwordx4 v[90:93], v[2:3], off
	global_load_dwordx4 v[94:97], v[4:5], off
	v_lshl_add_u64 v[2:3], s[68:69], 0, v[130:131]
	s_lshl_b64 s[0:1], s[0:1], 9
	v_lshl_add_u64 v[4:5], v[136:137], 0, s[78:79]
	global_load_dwordx4 v[110:113], v[2:3], off
	global_load_dwordx4 v[78:81], v[4:5], off
	v_lshl_add_u64 v[2:3], v[134:135], 0, s[0:1]
	global_load_dwordx4 v[58:61], v[2:3], off
	v_cvt_pk_bf16_f32 v4, v122, v122
	s_mov_b64 s[0:1], 0x1c0000
	v_and_b32_e32 v4, 0xffff, v4
	v_lshl_add_u64 v[2:3], v[132:133], 0, s[0:1]
	global_store_short v[2:3], v4, off
	v_cvt_pk_bf16_f32 v4, v123, v123
	s_mov_b64 s[0:1], 0x1c0800
	v_and_b32_e32 v4, 0xffff, v4
	v_lshl_add_u64 v[2:3], v[132:133], 0, s[0:1]
	global_store_short v[2:3], v4, off
	v_cvt_pk_bf16_f32 v4, v124, v124
	s_mov_b64 s[0:1], 0x1c1000
	v_and_b32_e32 v4, 0xffff, v4
	v_lshl_add_u64 v[2:3], v[132:133], 0, s[0:1]
	global_store_short v[2:3], v4, off
	s_mov_b64 s[0:1], 0x1c1800
	v_cvt_pk_bf16_f32 v4, v125, v125
	v_lshl_add_u64 v[2:3], v[132:133], 0, s[0:1]
	v_and_b32_e32 v4, 0xffff, v4
	global_store_short v[2:3], v4, off
	s_waitcnt lgkmcnt(0)
	s_barrier
	ds_read_b128 v[2:5], v149 offset:54784
	ds_read_b128 v[10:13], v162
	ds_read_b128 v[14:17], v149 offset:54848
	ds_read_b128 v[18:21], v162 offset:64
	ds_read_b128 v[178:181], v147 offset:65024
	ds_read_b128 v[42:45], v153 offset:9216
	ds_read_b128 v[182:185], v147 offset:65088
	ds_read_b128 v[186:189], v153 offset:9280
	ds_read_b128 v[190:193], v147 offset:65152
	ds_read_b128 v[206:209], v153 offset:9344
	ds_read_b128 v[210:213], v147 offset:65216
	ds_read_b128 v[214:217], v153 offset:9408
	ds_read_b128 v[218:221], v161
	ds_read_b128 v[222:225], v166
	ds_read_b128 v[46:49], v163
	s_waitcnt lgkmcnt(13)
	v_mfma_f32_16x16x32_bf16 v[2:5], v[2:5], v[10:13], 0
	s_nop 0
	s_nop 0
	s_waitcnt lgkmcnt(11)
	v_mfma_f32_16x16x32_bf16 v[2:5], v[14:17], v[18:21], v[2:5]
	s_nop 0
	s_nop 0
	s_waitcnt lgkmcnt(9)
	v_mfma_f32_16x16x32_bf16 v[2:5], v[178:181], v[42:45], v[2:5]
	ds_read_b128 v[178:181], v163 offset:2560
	s_nop 0
	s_nop 0
	s_waitcnt lgkmcnt(8)
	v_mfma_f32_16x16x32_bf16 v[2:5], v[182:185], v[186:189], v[2:5]
	ds_read_b128 v[182:185], v161 offset:64
	ds_read_b128 v[186:189], v164
	s_nop 0
	s_nop 0
	s_waitcnt lgkmcnt(8)
	v_mfma_f32_16x16x32_bf16 v[2:5], v[190:193], v[206:209], v[2:5]
	ds_read_b128 v[190:193], v164 offset:2560
	s_nop 0
	s_nop 0
	s_nop 0
	s_waitcnt lgkmcnt(7)
	v_mfma_f32_16x16x32_bf16 v[122:125], v[210:213], v[214:217], v[2:5]
	s_nop 0
	s_nop 0
	s_waitcnt lgkmcnt(5)
	v_pk_mul_f32 v[4:5], v[116:117], v[224:225]
	v_pk_mul_f32 v[2:3], v[114:115], v[222:223]
	v_pk_mul_f32 v[44:45], v[120:121], v[224:225]
	v_pk_mul_f32 v[42:43], v[118:119], v[222:223]
	s_waitcnt lgkmcnt(4)
	v_mfma_f32_16x16x32_bf16 v[2:5], v[218:221], v[46:49], v[2:5]
	s_waitcnt lgkmcnt(3)
	v_mfma_f32_16x16x32_bf16 v[10:13], v[218:221], v[178:181], v[42:45]
	s_nop 0
	s_nop 1
	s_nop 0
	s_waitcnt lgkmcnt(1)
	v_mfma_f32_16x16x32_bf16 v[118:121], v[182:185], v[186:189], v[2:5]
	s_waitcnt lgkmcnt(0)
	v_mfma_f32_16x16x32_bf16 v[114:117], v[182:185], v[190:193], v[10:13]
	s_nop 5
	v_cvt_pk_bf16_f32 v2, v118, v119
	v_cvt_pk_bf16_f32 v3, v120, v121
	v_cvt_pk_bf16_f32 v4, v114, v115
	v_cvt_pk_bf16_f32 v5, v116, v117
	ds_write2st64_b64 v151, v[2:3], v[4:5] offset1:9
	s_waitcnt vmcnt(20)
	ds_write_b128 v127, v[70:73]
	s_waitcnt vmcnt(19)
	ds_write_b128 v143, v[82:85] offset:10240
	s_waitcnt vmcnt(18)
	ds_write_b128 v144, v[98:101] offset:10240
	s_waitcnt vmcnt(17)
	ds_write_b128 v127, v[102:105] offset:28672
	s_waitcnt vmcnt(16)
	ds_write_b128 v148, v[106:109] offset:28672
	s_and_saveexec_b64 s[8:9], vcc
	s_cbranch_execz .LBB0_1949
	s_waitcnt vmcnt(15)
	ds_write_b128 v127, v[86:89] offset:49152

.LBB0_1951:
	s_or_b64 exec, exec, s[8:9]
	s_or_b32 s0, s46, 0x4c
	s_ashr_i32 s1, s0, 31
	s_lshl_b64 s[8:9], s[0:1], 13
	s_lshl_b64 s[68:69], s[0:1], 14
	s_add_u32 s70, s73, s68
	s_addc_u32 s71, s38, s69
	s_add_u32 s68, s39, s68
	v_lshl_add_u64 v[2:3], v[138:139], 0, s[8:9]
	s_addc_u32 s69, s11, s69
	v_lshl_add_u64 v[4:5], s[70:71], 0, v[128:129]
	global_load_dwordx4 v[10:13], v[2:3], off
	global_load_dwordx4 v[14:17], v[4:5], off
	v_lshl_add_u64 v[2:3], s[70:71], 0, v[130:131]
	s_lshl_b64 s[78:79], s[0:1], 15
	v_lshl_add_u64 v[4:5], s[68:69], 0, v[128:129]
	global_load_dwordx4 v[42:45], v[2:3], off
	global_load_dwordx4 v[46:49], v[4:5], off
	v_lshl_add_u64 v[2:3], s[68:69], 0, v[130:131]
	s_lshl_b64 s[0:1], s[0:1], 9
	v_lshl_add_u64 v[4:5], v[136:137], 0, s[78:79]
	global_load_dwordx4 v[54:57], v[2:3], off
	global_load_dwordx4 v[18:21], v[4:5], off
	v_lshl_add_u64 v[2:3], v[134:135], 0, s[0:1]
	global_load_dwordx4 v[2:5], v[2:3], off
	s_waitcnt vmcnt(21)
	v_cvt_pk_bf16_f32 v64, v122, v122
	s_mov_b64 s[0:1], 0x1e0000
	v_and_b32_e32 v64, 0xffff, v64
	v_lshl_add_u64 v[62:63], v[132:133], 0, s[0:1]
	global_store_short v[62:63], v64, off
	v_cvt_pk_bf16_f32 v64, v123, v123
	s_mov_b64 s[0:1], 0x1e0800
	v_and_b32_e32 v64, 0xffff, v64
	v_lshl_add_u64 v[62:63], v[132:133], 0, s[0:1]
	global_store_short v[62:63], v64, off
	v_cvt_pk_bf16_f32 v64, v124, v124
	s_mov_b64 s[0:1], 0x1e1000
	v_and_b32_e32 v64, 0xffff, v64
	v_lshl_add_u64 v[62:63], v[132:133], 0, s[0:1]
	global_store_short v[62:63], v64, off
	s_mov_b64 s[0:1], 0x1e1800
	v_cvt_pk_bf16_f32 v64, v125, v125
	v_lshl_add_u64 v[62:63], v[132:133], 0, s[0:1]
	v_and_b32_e32 v64, 0xffff, v64
	global_store_short v[62:63], v64, off
	s_waitcnt lgkmcnt(0)
	s_barrier
	ds_read_b128 v[62:65], v149
	ds_read_b128 v[70:73], v149 offset:64
	ds_read_b128 v[82:85], v156 offset:49152
	ds_read_b128 v[86:89], v156 offset:49216
	ds_read_b128 v[178:181], v147 offset:10240
	ds_read_b128 v[182:185], v153
	ds_read_b128 v[186:189], v147 offset:10304
	ds_read_b128 v[98:101], v153 offset:64
	ds_read_b128 v[190:193], v147 offset:10368
	ds_read_b128 v[206:209], v153 offset:128
	ds_read_b128 v[210:213], v147 offset:10432
	ds_read_b128 v[214:217], v153 offset:192
	ds_read_b128 v[102:105], v155 offset:28672
	ds_read_b128 v[218:221], v165 offset:54272
	ds_read_b128 v[222:225], v154 offset:49152
	s_waitcnt lgkmcnt(12)
	v_mfma_f32_16x16x32_bf16 v[62:65], v[62:65], v[82:85], 0
	s_nop 0
	s_waitcnt lgkmcnt(11)
	v_mfma_f32_16x16x32_bf16 v[62:65], v[70:73], v[86:89], v[62:65]
	s_nop 0
	s_nop 0
	s_nop 0
	s_waitcnt lgkmcnt(9)
	v_mfma_f32_16x16x32_bf16 v[62:65], v[178:181], v[182:185], v[62:65]
	ds_read_b128 v[178:181], v154 offset:51712
	ds_read_b128 v[182:185], v155 offset:28736
	s_nop 0
	s_nop 0
	s_waitcnt lgkmcnt(9)
	v_mfma_f32_16x16x32_bf16 v[62:65], v[186:189], v[98:101], v[62:65]
	ds_read_b128 v[186:189], v154 offset:49216
	s_nop 0
	s_nop 0
	s_nop 0
	s_waitcnt lgkmcnt(8)
	v_mfma_f32_16x16x32_bf16 v[62:65], v[190:193], v[206:209], v[62:65]
	ds_read_b128 v[190:193], v154 offset:51776
	s_nop 0
	s_nop 0
	s_waitcnt lgkmcnt(7)
	v_mfma_f32_16x16x32_bf16 v[122:125], v[210:213], v[214:217], v[62:65]
	s_nop 0
	s_waitcnt lgkmcnt(5)
	s_nop 1
	v_pk_mul_f32 v[64:65], v[120:121], v[220:221]
	v_pk_mul_f32 v[62:63], v[118:119], v[218:219]
	v_pk_mul_f32 v[72:73], v[116:117], v[220:221]
	v_pk_mul_f32 v[70:71], v[114:115], v[218:219]
	s_waitcnt lgkmcnt(4)
	v_mfma_f32_16x16x32_bf16 v[62:65], v[102:105], v[222:225], v[62:65]
	s_nop 0
	s_waitcnt lgkmcnt(3)
	v_mfma_f32_16x16x32_bf16 v[70:73], v[102:105], v[178:181], v[70:73]
	s_nop 0
	s_waitcnt lgkmcnt(1)
	v_mfma_f32_16x16x32_bf16 v[114:117], v[182:185], v[186:189], v[62:65]
	s_nop 2
	s_nop 0
	s_waitcnt lgkmcnt(0)
	v_mfma_f32_16x16x32_bf16 v[118:121], v[182:185], v[190:193], v[70:73]
	s_nop 1
	v_cvt_pk_bf16_f32 v62, v114, v115
	v_cvt_pk_bf16_f32 v63, v116, v117
	s_nop 3
	v_cvt_pk_bf16_f32 v64, v118, v119
	v_cvt_pk_bf16_f32 v65, v120, v121
	ds_write2st64_b64 v151, v[62:63], v[64:65] offset0:18 offset1:27
	s_waitcnt vmcnt(20)
	ds_write_b128 v127, v[22:25] offset:54784
	s_waitcnt vmcnt(19)
	ds_write_b128 v143, v[26:29] offset:65024
	s_waitcnt vmcnt(18)
	ds_write_b128 v144, v[34:37] offset:65024
	s_waitcnt vmcnt(17)
	ds_write_b128 v159, v[38:41]
	s_waitcnt vmcnt(16)
	ds_write_b128 v160, v[50:53]
	s_and_saveexec_b64 s[8:9], vcc
	s_cbranch_execz .LBB0_1953
	s_waitcnt vmcnt(15)
	ds_write_b128 v158, v[30:33]

.LBB0_1955:
	s_or_b64 exec, exec, s[8:9]
	s_or_b32 s0, s46, 0x50
	s_ashr_i32 s1, s0, 31
	s_lshl_b64 s[8:9], s[0:1], 13
	s_lshl_b64 s[68:69], s[0:1], 14
	s_add_u32 s70, s73, s68
	s_addc_u32 s71, s38, s69
	s_add_u32 s68, s39, s68
	s_waitcnt vmcnt(14)
	v_lshl_add_u64 v[6:7], v[138:139], 0, s[8:9]
	s_addc_u32 s69, s11, s69
	v_lshl_add_u64 v[8:9], s[70:71], 0, v[128:129]
	global_load_dwordx4 v[70:73], v[6:7], off
	global_load_dwordx4 v[82:85], v[8:9], off
	v_lshl_add_u64 v[6:7], s[70:71], 0, v[130:131]
	s_lshl_b64 s[78:79], s[0:1], 15
	v_lshl_add_u64 v[8:9], s[68:69], 0, v[128:129]
	global_load_dwordx4 v[98:101], v[6:7], off
	global_load_dwordx4 v[102:105], v[8:9], off
	v_lshl_add_u64 v[6:7], s[68:69], 0, v[130:131]
	s_lshl_b64 s[0:1], s[0:1], 9
	v_lshl_add_u64 v[8:9], v[136:137], 0, s[78:79]
	global_load_dwordx4 v[106:109], v[6:7], off
	global_load_dwordx4 v[86:89], v[8:9], off
	v_lshl_add_u64 v[6:7], v[134:135], 0, s[0:1]
	global_load_dwordx4 v[62:65], v[6:7], off
	v_cvt_pk_bf16_f32 v8, v122, v122
	s_mov_b64 s[0:1], 0x200000
	v_and_b32_e32 v8, 0xffff, v8
	v_lshl_add_u64 v[6:7], v[132:133], 0, s[0:1]
	global_store_short v[6:7], v8, off
	v_cvt_pk_bf16_f32 v8, v123, v123
	s_mov_b64 s[0:1], 0x200800
	v_and_b32_e32 v8, 0xffff, v8
	v_lshl_add_u64 v[6:7], v[132:133], 0, s[0:1]
	global_store_short v[6:7], v8, off
	v_cvt_pk_bf16_f32 v8, v124, v124
	s_mov_b64 s[0:1], 0x201000
	v_and_b32_e32 v8, 0xffff, v8
	v_lshl_add_u64 v[6:7], v[132:133], 0, s[0:1]
	global_store_short v[6:7], v8, off
	s_mov_b64 s[0:1], 0x201800
	v_cvt_pk_bf16_f32 v8, v125, v125
	v_lshl_add_u64 v[6:7], v[132:133], 0, s[0:1]
	v_and_b32_e32 v8, 0xffff, v8
	global_store_short v[6:7], v8, off
	s_waitcnt lgkmcnt(0)
	s_barrier
	ds_read_b128 v[6:9], v149 offset:54784
	ds_read_b128 v[22:25], v162
	ds_read_b128 v[26:29], v149 offset:54848
	ds_read_b128 v[30:33], v162 offset:64
	ds_read_b128 v[178:181], v147 offset:65024
	ds_read_b128 v[34:37], v153 offset:9216
	ds_read_b128 v[182:185], v147 offset:65088
	ds_read_b128 v[186:189], v153 offset:9280
	ds_read_b128 v[190:193], v147 offset:65152
	ds_read_b128 v[206:209], v153 offset:9344
	ds_read_b128 v[210:213], v147 offset:65216
	ds_read_b128 v[214:217], v153 offset:9408
	ds_read_b128 v[218:221], v161
	ds_read_b128 v[222:225], v166
	ds_read_b128 v[38:41], v163
	s_waitcnt lgkmcnt(13)
	v_mfma_f32_16x16x32_bf16 v[6:9], v[6:9], v[22:25], 0
	s_nop 0
	s_nop 0
	s_waitcnt lgkmcnt(11)
	v_mfma_f32_16x16x32_bf16 v[6:9], v[26:29], v[30:33], v[6:9]
	s_nop 0
	s_nop 0
	s_waitcnt lgkmcnt(9)
	v_mfma_f32_16x16x32_bf16 v[6:9], v[178:181], v[34:37], v[6:9]
	ds_read_b128 v[178:181], v163 offset:2560
	s_nop 0
	s_nop 0
	s_waitcnt lgkmcnt(8)
	v_mfma_f32_16x16x32_bf16 v[6:9], v[182:185], v[186:189], v[6:9]
	ds_read_b128 v[182:185], v161 offset:64
	ds_read_b128 v[186:189], v164
	s_nop 0
	s_nop 0
	s_waitcnt lgkmcnt(8)
	v_mfma_f32_16x16x32_bf16 v[6:9], v[190:193], v[206:209], v[6:9]
	ds_read_b128 v[190:193], v164 offset:2560
	s_nop 0
	s_nop 0
	s_nop 0
	s_waitcnt lgkmcnt(7)
	v_mfma_f32_16x16x32_bf16 v[122:125], v[210:213], v[214:217], v[6:9]
	s_nop 0
	s_nop 0
	s_waitcnt lgkmcnt(5)
	v_pk_mul_f32 v[8:9], v[116:117], v[224:225]
	v_pk_mul_f32 v[6:7], v[114:115], v[222:223]
	v_pk_mul_f32 v[36:37], v[120:121], v[224:225]
	v_pk_mul_f32 v[34:35], v[118:119], v[222:223]
	s_waitcnt lgkmcnt(4)
	v_mfma_f32_16x16x32_bf16 v[6:9], v[218:221], v[38:41], v[6:9]
	s_waitcnt lgkmcnt(3)
	v_mfma_f32_16x16x32_bf16 v[22:25], v[218:221], v[178:181], v[34:37]
	s_nop 0
	s_nop 1
	s_nop 0
	s_waitcnt lgkmcnt(1)
	v_mfma_f32_16x16x32_bf16 v[118:121], v[182:185], v[186:189], v[6:9]
	s_waitcnt lgkmcnt(0)
	v_mfma_f32_16x16x32_bf16 v[114:117], v[182:185], v[190:193], v[22:25]
	s_nop 5
	v_cvt_pk_bf16_f32 v6, v118, v119
	v_cvt_pk_bf16_f32 v7, v120, v121
	v_cvt_pk_bf16_f32 v8, v114, v115
	v_cvt_pk_bf16_f32 v9, v116, v117
	ds_write2st64_b64 v151, v[6:7], v[8:9] offset1:9
	s_waitcnt vmcnt(20)
	ds_write_b128 v127, v[66:69]
	s_waitcnt vmcnt(19)
	ds_write_b128 v143, v[74:77] offset:10240
	s_waitcnt vmcnt(18)
	ds_write_b128 v144, v[90:93] offset:10240
	s_waitcnt vmcnt(17)
	ds_write_b128 v127, v[94:97] offset:28672
	s_waitcnt vmcnt(16)
	ds_write_b128 v148, v[110:113] offset:28672
	s_and_saveexec_b64 s[8:9], vcc
	s_cbranch_execz .LBB0_1957
	s_waitcnt vmcnt(15)
	ds_write_b128 v127, v[78:81] offset:49152

.LBB0_1959:
	s_or_b64 exec, exec, s[8:9]
	s_or_b32 s0, s46, 0x54
	s_ashr_i32 s1, s0, 31
	s_lshl_b64 s[8:9], s[0:1], 13
	s_lshl_b64 s[68:69], s[0:1], 14
	s_add_u32 s70, s73, s68
	s_addc_u32 s71, s38, s69
	s_add_u32 s68, s39, s68
	v_lshl_add_u64 v[6:7], v[138:139], 0, s[8:9]
	s_addc_u32 s69, s11, s69
	v_lshl_add_u64 v[8:9], s[70:71], 0, v[128:129]
	global_load_dwordx4 v[22:25], v[6:7], off
	global_load_dwordx4 v[26:29], v[8:9], off
	v_lshl_add_u64 v[6:7], s[70:71], 0, v[130:131]
	s_lshl_b64 s[78:79], s[0:1], 15
	v_lshl_add_u64 v[8:9], s[68:69], 0, v[128:129]
	global_load_dwordx4 v[34:37], v[6:7], off
	global_load_dwordx4 v[38:41], v[8:9], off
	v_lshl_add_u64 v[6:7], s[68:69], 0, v[130:131]
	s_lshl_b64 s[0:1], s[0:1], 9
	v_lshl_add_u64 v[8:9], v[136:137], 0, s[78:79]
	global_load_dwordx4 v[50:53], v[6:7], off
	global_load_dwordx4 v[30:33], v[8:9], off
	v_lshl_add_u64 v[6:7], v[134:135], 0, s[0:1]
	global_load_dwordx4 v[6:9], v[6:7], off
	s_waitcnt vmcnt(21)
	v_cvt_pk_bf16_f32 v60, v122, v122
	s_mov_b64 s[0:1], 0x220000
	v_and_b32_e32 v60, 0xffff, v60
	v_lshl_add_u64 v[58:59], v[132:133], 0, s[0:1]
	global_store_short v[58:59], v60, off
	v_cvt_pk_bf16_f32 v60, v123, v123
	s_mov_b64 s[0:1], 0x220800
	v_and_b32_e32 v60, 0xffff, v60
	v_lshl_add_u64 v[58:59], v[132:133], 0, s[0:1]
	global_store_short v[58:59], v60, off
	v_cvt_pk_bf16_f32 v60, v124, v124
	s_mov_b64 s[0:1], 0x221000
	v_and_b32_e32 v60, 0xffff, v60
	v_lshl_add_u64 v[58:59], v[132:133], 0, s[0:1]
	global_store_short v[58:59], v60, off
	s_mov_b64 s[0:1], 0x221800
	v_cvt_pk_bf16_f32 v60, v125, v125
	v_lshl_add_u64 v[58:59], v[132:133], 0, s[0:1]
	v_and_b32_e32 v60, 0xffff, v60
	global_store_short v[58:59], v60, off
	s_waitcnt lgkmcnt(0)
	s_barrier
	ds_read_b128 v[58:61], v149
	ds_read_b128 v[66:69], v149 offset:64
	ds_read_b128 v[74:77], v156 offset:49152
	ds_read_b128 v[78:81], v156 offset:49216
	ds_read_b128 v[178:181], v147 offset:10240
	ds_read_b128 v[182:185], v153
	ds_read_b128 v[186:189], v147 offset:10304
	ds_read_b128 v[90:93], v153 offset:64
	ds_read_b128 v[190:193], v147 offset:10368
	ds_read_b128 v[206:209], v153 offset:128
	ds_read_b128 v[210:213], v147 offset:10432
	ds_read_b128 v[214:217], v153 offset:192
	ds_read_b128 v[94:97], v155 offset:28672
	ds_read_b128 v[218:221], v165 offset:54272
	ds_read_b128 v[222:225], v154 offset:49152
	s_waitcnt lgkmcnt(12)
	v_mfma_f32_16x16x32_bf16 v[58:61], v[58:61], v[74:77], 0
	s_nop 0
	s_waitcnt lgkmcnt(11)
	v_mfma_f32_16x16x32_bf16 v[58:61], v[66:69], v[78:81], v[58:61]
	s_nop 0
	s_nop 0
	s_nop 0
	s_waitcnt lgkmcnt(9)
	v_mfma_f32_16x16x32_bf16 v[58:61], v[178:181], v[182:185], v[58:61]
	ds_read_b128 v[178:181], v154 offset:51712
	ds_read_b128 v[182:185], v155 offset:28736
	s_nop 0
	s_nop 0
	s_waitcnt lgkmcnt(9)
	v_mfma_f32_16x16x32_bf16 v[58:61], v[186:189], v[90:93], v[58:61]
	ds_read_b128 v[186:189], v154 offset:49216
	s_nop 0
	s_nop 0
	s_nop 0
	s_waitcnt lgkmcnt(8)
	v_mfma_f32_16x16x32_bf16 v[58:61], v[190:193], v[206:209], v[58:61]
	ds_read_b128 v[190:193], v154 offset:51776
	s_nop 0
	s_nop 0
	s_waitcnt lgkmcnt(7)
	v_mfma_f32_16x16x32_bf16 v[122:125], v[210:213], v[214:217], v[58:61]
	s_nop 0
	s_waitcnt lgkmcnt(5)
	s_nop 1
	v_pk_mul_f32 v[60:61], v[120:121], v[220:221]
	v_pk_mul_f32 v[58:59], v[118:119], v[218:219]
	v_pk_mul_f32 v[68:69], v[116:117], v[220:221]
	v_pk_mul_f32 v[66:67], v[114:115], v[218:219]
	s_waitcnt lgkmcnt(4)
	v_mfma_f32_16x16x32_bf16 v[58:61], v[94:97], v[222:225], v[58:61]
	s_nop 0
	s_waitcnt lgkmcnt(3)
	v_mfma_f32_16x16x32_bf16 v[66:69], v[94:97], v[178:181], v[66:69]
	s_nop 0
	s_waitcnt lgkmcnt(1)
	v_mfma_f32_16x16x32_bf16 v[114:117], v[182:185], v[186:189], v[58:61]
	s_nop 2
	s_nop 0
	s_waitcnt lgkmcnt(0)
	v_mfma_f32_16x16x32_bf16 v[118:121], v[182:185], v[190:193], v[66:69]
	s_nop 1
	v_cvt_pk_bf16_f32 v58, v114, v115
	v_cvt_pk_bf16_f32 v59, v116, v117
	s_nop 3
	v_cvt_pk_bf16_f32 v60, v118, v119
	v_cvt_pk_bf16_f32 v61, v120, v121
	ds_write2st64_b64 v151, v[58:59], v[60:61] offset0:18 offset1:27
	s_waitcnt vmcnt(20)
	ds_write_b128 v127, v[10:13] offset:54784
	s_waitcnt vmcnt(19)
	ds_write_b128 v143, v[14:17] offset:65024
	s_waitcnt vmcnt(18)
	ds_write_b128 v144, v[42:45] offset:65024
	s_waitcnt vmcnt(17)
	ds_write_b128 v159, v[46:49]
	s_waitcnt vmcnt(16)
	ds_write_b128 v160, v[54:57]
	s_and_saveexec_b64 s[8:9], vcc
	s_cbranch_execz .LBB0_1961
	s_waitcnt vmcnt(15)
	ds_write_b128 v158, v[18:21]

.LBB0_1963:
	s_or_b64 exec, exec, s[8:9]
	s_or_b32 s0, s46, 0x58
	s_ashr_i32 s1, s0, 31
	s_lshl_b64 s[8:9], s[0:1], 13
	s_lshl_b64 s[68:69], s[0:1], 14
	s_add_u32 s70, s73, s68
	s_addc_u32 s71, s38, s69
	s_add_u32 s68, s39, s68
	s_waitcnt vmcnt(14)
	v_lshl_add_u64 v[2:3], v[138:139], 0, s[8:9]
	s_addc_u32 s69, s11, s69
	v_lshl_add_u64 v[4:5], s[70:71], 0, v[128:129]
	global_load_dwordx4 v[66:69], v[2:3], off
	global_load_dwordx4 v[74:77], v[4:5], off
	v_lshl_add_u64 v[2:3], s[70:71], 0, v[130:131]
	s_lshl_b64 s[78:79], s[0:1], 15
	v_lshl_add_u64 v[4:5], s[68:69], 0, v[128:129]
	global_load_dwordx4 v[90:93], v[2:3], off
	global_load_dwordx4 v[94:97], v[4:5], off
	v_lshl_add_u64 v[2:3], s[68:69], 0, v[130:131]
	s_lshl_b64 s[0:1], s[0:1], 9
	v_lshl_add_u64 v[4:5], v[136:137], 0, s[78:79]
	global_load_dwordx4 v[110:113], v[2:3], off
	global_load_dwordx4 v[78:81], v[4:5], off
	v_lshl_add_u64 v[2:3], v[134:135], 0, s[0:1]
	global_load_dwordx4 v[58:61], v[2:3], off
	v_cvt_pk_bf16_f32 v4, v122, v122
	s_mov_b64 s[0:1], 0x240000
	v_and_b32_e32 v4, 0xffff, v4
	v_lshl_add_u64 v[2:3], v[132:133], 0, s[0:1]
	global_store_short v[2:3], v4, off
	v_cvt_pk_bf16_f32 v4, v123, v123
	s_mov_b64 s[0:1], 0x240800
	v_and_b32_e32 v4, 0xffff, v4
	v_lshl_add_u64 v[2:3], v[132:133], 0, s[0:1]
	global_store_short v[2:3], v4, off
	v_cvt_pk_bf16_f32 v4, v124, v124
	s_mov_b64 s[0:1], 0x241000
	v_and_b32_e32 v4, 0xffff, v4
	v_lshl_add_u64 v[2:3], v[132:133], 0, s[0:1]
	global_store_short v[2:3], v4, off
	s_mov_b64 s[0:1], 0x241800
	v_cvt_pk_bf16_f32 v4, v125, v125
	v_lshl_add_u64 v[2:3], v[132:133], 0, s[0:1]
	v_and_b32_e32 v4, 0xffff, v4
	global_store_short v[2:3], v4, off
	s_waitcnt lgkmcnt(0)
	s_barrier
	ds_read_b128 v[2:5], v149 offset:54784
	ds_read_b128 v[10:13], v162
	ds_read_b128 v[14:17], v149 offset:54848
	ds_read_b128 v[18:21], v162 offset:64
	ds_read_b128 v[178:181], v147 offset:65024
	ds_read_b128 v[42:45], v153 offset:9216
	ds_read_b128 v[182:185], v147 offset:65088
	ds_read_b128 v[186:189], v153 offset:9280
	ds_read_b128 v[190:193], v147 offset:65152
	ds_read_b128 v[206:209], v153 offset:9344
	ds_read_b128 v[210:213], v147 offset:65216
	ds_read_b128 v[214:217], v153 offset:9408
	ds_read_b128 v[218:221], v161
	ds_read_b128 v[222:225], v166
	ds_read_b128 v[46:49], v163
	s_waitcnt lgkmcnt(13)
	v_mfma_f32_16x16x32_bf16 v[2:5], v[2:5], v[10:13], 0
	s_nop 0
	s_nop 0
	s_waitcnt lgkmcnt(11)
	v_mfma_f32_16x16x32_bf16 v[2:5], v[14:17], v[18:21], v[2:5]
	s_nop 0
	s_nop 0
	s_waitcnt lgkmcnt(9)
	v_mfma_f32_16x16x32_bf16 v[2:5], v[178:181], v[42:45], v[2:5]
	ds_read_b128 v[178:181], v163 offset:2560
	s_nop 0
	s_nop 0
	s_waitcnt lgkmcnt(8)
	v_mfma_f32_16x16x32_bf16 v[2:5], v[182:185], v[186:189], v[2:5]
	ds_read_b128 v[182:185], v161 offset:64
	ds_read_b128 v[186:189], v164
	s_nop 0
	s_nop 0
	s_waitcnt lgkmcnt(8)
	v_mfma_f32_16x16x32_bf16 v[2:5], v[190:193], v[206:209], v[2:5]
	ds_read_b128 v[190:193], v164 offset:2560
	s_nop 0
	s_nop 0
	s_nop 0
	s_waitcnt lgkmcnt(7)
	v_mfma_f32_16x16x32_bf16 v[122:125], v[210:213], v[214:217], v[2:5]
	s_nop 0
	s_nop 0
	s_waitcnt lgkmcnt(5)
	v_pk_mul_f32 v[4:5], v[116:117], v[224:225]
	v_pk_mul_f32 v[2:3], v[114:115], v[222:223]
	v_pk_mul_f32 v[44:45], v[120:121], v[224:225]
	v_pk_mul_f32 v[42:43], v[118:119], v[222:223]
	s_waitcnt lgkmcnt(4)
	v_mfma_f32_16x16x32_bf16 v[2:5], v[218:221], v[46:49], v[2:5]
	s_waitcnt lgkmcnt(3)
	v_mfma_f32_16x16x32_bf16 v[10:13], v[218:221], v[178:181], v[42:45]
	s_nop 0
	s_nop 1
	s_nop 0
	s_waitcnt lgkmcnt(1)
	v_mfma_f32_16x16x32_bf16 v[118:121], v[182:185], v[186:189], v[2:5]
	s_waitcnt lgkmcnt(0)
	v_mfma_f32_16x16x32_bf16 v[114:117], v[182:185], v[190:193], v[10:13]
	s_nop 5
	v_cvt_pk_bf16_f32 v2, v118, v119
	v_cvt_pk_bf16_f32 v3, v120, v121
	v_cvt_pk_bf16_f32 v4, v114, v115
	v_cvt_pk_bf16_f32 v5, v116, v117
	ds_write2st64_b64 v151, v[2:3], v[4:5] offset1:9
	s_waitcnt vmcnt(20)
	ds_write_b128 v127, v[70:73]
	s_waitcnt vmcnt(19)
	ds_write_b128 v143, v[82:85] offset:10240
	s_waitcnt vmcnt(18)
	ds_write_b128 v144, v[98:101] offset:10240
	s_waitcnt vmcnt(17)
	ds_write_b128 v127, v[102:105] offset:28672
	s_waitcnt vmcnt(16)
	ds_write_b128 v148, v[106:109] offset:28672
	s_and_saveexec_b64 s[8:9], vcc
	s_cbranch_execz .LBB0_1965
	s_waitcnt vmcnt(15)
	ds_write_b128 v127, v[86:89] offset:49152

.LBB0_1967:
	s_or_b64 exec, exec, s[8:9]
	s_or_b32 s0, s46, 0x5c
	s_ashr_i32 s1, s0, 31
	s_lshl_b64 s[8:9], s[0:1], 13
	s_lshl_b64 s[68:69], s[0:1], 14
	s_add_u32 s70, s73, s68
	s_addc_u32 s71, s38, s69
	s_add_u32 s68, s39, s68
	v_lshl_add_u64 v[2:3], v[138:139], 0, s[8:9]
	s_addc_u32 s69, s11, s69
	v_lshl_add_u64 v[4:5], s[70:71], 0, v[128:129]
	global_load_dwordx4 v[10:13], v[2:3], off
	global_load_dwordx4 v[14:17], v[4:5], off
	v_lshl_add_u64 v[2:3], s[70:71], 0, v[130:131]
	s_lshl_b64 s[78:79], s[0:1], 15
	v_lshl_add_u64 v[4:5], s[68:69], 0, v[128:129]
	global_load_dwordx4 v[42:45], v[2:3], off
	global_load_dwordx4 v[46:49], v[4:5], off
	v_lshl_add_u64 v[2:3], s[68:69], 0, v[130:131]
	s_lshl_b64 s[0:1], s[0:1], 9
	v_lshl_add_u64 v[4:5], v[136:137], 0, s[78:79]
	global_load_dwordx4 v[54:57], v[2:3], off
	global_load_dwordx4 v[18:21], v[4:5], off
	v_lshl_add_u64 v[2:3], v[134:135], 0, s[0:1]
	global_load_dwordx4 v[2:5], v[2:3], off
	s_waitcnt vmcnt(21)
	v_cvt_pk_bf16_f32 v64, v122, v122
	s_mov_b64 s[0:1], 0x260000
	v_and_b32_e32 v64, 0xffff, v64
	v_lshl_add_u64 v[62:63], v[132:133], 0, s[0:1]
	global_store_short v[62:63], v64, off
	v_cvt_pk_bf16_f32 v64, v123, v123
	s_mov_b64 s[0:1], 0x260800
	v_and_b32_e32 v64, 0xffff, v64
	v_lshl_add_u64 v[62:63], v[132:133], 0, s[0:1]
	global_store_short v[62:63], v64, off
	v_cvt_pk_bf16_f32 v64, v124, v124
	s_mov_b64 s[0:1], 0x261000
	v_and_b32_e32 v64, 0xffff, v64
	v_lshl_add_u64 v[62:63], v[132:133], 0, s[0:1]
	global_store_short v[62:63], v64, off
	s_mov_b64 s[0:1], 0x261800
	v_cvt_pk_bf16_f32 v64, v125, v125
	v_lshl_add_u64 v[62:63], v[132:133], 0, s[0:1]
	v_and_b32_e32 v64, 0xffff, v64
	global_store_short v[62:63], v64, off
	s_waitcnt lgkmcnt(0)
	s_barrier
	ds_read_b128 v[62:65], v149
	ds_read_b128 v[70:73], v149 offset:64
	ds_read_b128 v[82:85], v156 offset:49152
	ds_read_b128 v[86:89], v156 offset:49216
	ds_read_b128 v[178:181], v147 offset:10240
	ds_read_b128 v[182:185], v153
	ds_read_b128 v[186:189], v147 offset:10304
	ds_read_b128 v[98:101], v153 offset:64
	ds_read_b128 v[190:193], v147 offset:10368
	ds_read_b128 v[206:209], v153 offset:128
	ds_read_b128 v[210:213], v147 offset:10432
	ds_read_b128 v[214:217], v153 offset:192
	ds_read_b128 v[102:105], v155 offset:28672
	ds_read_b128 v[218:221], v165 offset:54272
	ds_read_b128 v[222:225], v154 offset:49152
	s_waitcnt lgkmcnt(12)
	v_mfma_f32_16x16x32_bf16 v[62:65], v[62:65], v[82:85], 0
	s_nop 0
	s_waitcnt lgkmcnt(11)
	v_mfma_f32_16x16x32_bf16 v[62:65], v[70:73], v[86:89], v[62:65]
	s_nop 0
	s_nop 0
	s_nop 0
	s_waitcnt lgkmcnt(9)
	v_mfma_f32_16x16x32_bf16 v[62:65], v[178:181], v[182:185], v[62:65]
	ds_read_b128 v[178:181], v154 offset:51712
	ds_read_b128 v[182:185], v155 offset:28736
	s_nop 0
	s_nop 0
	s_waitcnt lgkmcnt(9)
	v_mfma_f32_16x16x32_bf16 v[62:65], v[186:189], v[98:101], v[62:65]
	ds_read_b128 v[186:189], v154 offset:49216
	s_nop 0
	s_nop 0
	s_nop 0
	s_waitcnt lgkmcnt(8)
	v_mfma_f32_16x16x32_bf16 v[62:65], v[190:193], v[206:209], v[62:65]
	ds_read_b128 v[190:193], v154 offset:51776
	s_nop 0
	s_nop 0
	s_waitcnt lgkmcnt(7)
	v_mfma_f32_16x16x32_bf16 v[122:125], v[210:213], v[214:217], v[62:65]
	s_nop 0
	s_waitcnt lgkmcnt(5)
	s_nop 1
	v_pk_mul_f32 v[64:65], v[120:121], v[220:221]
	v_pk_mul_f32 v[62:63], v[118:119], v[218:219]
	v_pk_mul_f32 v[72:73], v[116:117], v[220:221]
	v_pk_mul_f32 v[70:71], v[114:115], v[218:219]
	s_waitcnt lgkmcnt(4)
	v_mfma_f32_16x16x32_bf16 v[62:65], v[102:105], v[222:225], v[62:65]
	s_nop 0
	s_waitcnt lgkmcnt(3)
	v_mfma_f32_16x16x32_bf16 v[70:73], v[102:105], v[178:181], v[70:73]
	s_nop 0
	s_waitcnt lgkmcnt(1)
	v_mfma_f32_16x16x32_bf16 v[114:117], v[182:185], v[186:189], v[62:65]
	s_nop 2
	s_nop 0
	s_waitcnt lgkmcnt(0)
	v_mfma_f32_16x16x32_bf16 v[118:121], v[182:185], v[190:193], v[70:73]
	s_nop 1
	v_cvt_pk_bf16_f32 v62, v114, v115
	v_cvt_pk_bf16_f32 v63, v116, v117
	s_nop 3
	v_cvt_pk_bf16_f32 v64, v118, v119
	v_cvt_pk_bf16_f32 v65, v120, v121
	ds_write2st64_b64 v151, v[62:63], v[64:65] offset0:18 offset1:27
	s_waitcnt vmcnt(20)
	ds_write_b128 v127, v[22:25] offset:54784
	s_waitcnt vmcnt(19)
	ds_write_b128 v143, v[26:29] offset:65024
	s_waitcnt vmcnt(18)
	ds_write_b128 v144, v[34:37] offset:65024
	s_waitcnt vmcnt(17)
	ds_write_b128 v159, v[38:41]
	s_waitcnt vmcnt(16)
	ds_write_b128 v160, v[50:53]
	s_and_saveexec_b64 s[8:9], vcc
	s_cbranch_execz .LBB0_1969
	s_waitcnt vmcnt(15)
	ds_write_b128 v158, v[30:33]

.LBB0_1971:
	s_or_b64 exec, exec, s[8:9]
	s_or_b32 s0, s46, 0x60
	s_ashr_i32 s1, s0, 31
	s_lshl_b64 s[8:9], s[0:1], 13
	s_lshl_b64 s[68:69], s[0:1], 14
	s_add_u32 s70, s73, s68
	s_addc_u32 s71, s38, s69
	s_add_u32 s68, s39, s68
	s_waitcnt vmcnt(14)
	v_lshl_add_u64 v[6:7], v[138:139], 0, s[8:9]
	s_addc_u32 s69, s11, s69
	v_lshl_add_u64 v[8:9], s[70:71], 0, v[128:129]
	global_load_dwordx4 v[70:73], v[6:7], off
	global_load_dwordx4 v[82:85], v[8:9], off
	v_lshl_add_u64 v[6:7], s[70:71], 0, v[130:131]
	s_lshl_b64 s[78:79], s[0:1], 15
	v_lshl_add_u64 v[8:9], s[68:69], 0, v[128:129]
	global_load_dwordx4 v[98:101], v[6:7], off
	global_load_dwordx4 v[102:105], v[8:9], off
	v_lshl_add_u64 v[6:7], s[68:69], 0, v[130:131]
	s_lshl_b64 s[0:1], s[0:1], 9
	v_lshl_add_u64 v[8:9], v[136:137], 0, s[78:79]
	global_load_dwordx4 v[106:109], v[6:7], off
	global_load_dwordx4 v[86:89], v[8:9], off
	v_lshl_add_u64 v[6:7], v[134:135], 0, s[0:1]
	global_load_dwordx4 v[62:65], v[6:7], off
	v_cvt_pk_bf16_f32 v8, v122, v122
	s_mov_b64 s[0:1], 0x280000
	v_and_b32_e32 v8, 0xffff, v8
	v_lshl_add_u64 v[6:7], v[132:133], 0, s[0:1]
	global_store_short v[6:7], v8, off
	v_cvt_pk_bf16_f32 v8, v123, v123
	s_mov_b64 s[0:1], 0x280800
	v_and_b32_e32 v8, 0xffff, v8
	v_lshl_add_u64 v[6:7], v[132:133], 0, s[0:1]
	global_store_short v[6:7], v8, off
	v_cvt_pk_bf16_f32 v8, v124, v124
	s_mov_b64 s[0:1], 0x281000
	v_and_b32_e32 v8, 0xffff, v8
	v_lshl_add_u64 v[6:7], v[132:133], 0, s[0:1]
	global_store_short v[6:7], v8, off
	s_mov_b64 s[0:1], 0x281800
	v_cvt_pk_bf16_f32 v8, v125, v125
	v_lshl_add_u64 v[6:7], v[132:133], 0, s[0:1]
	v_and_b32_e32 v8, 0xffff, v8
	global_store_short v[6:7], v8, off
	s_waitcnt lgkmcnt(0)
	s_barrier
	ds_read_b128 v[6:9], v149 offset:54784
	ds_read_b128 v[22:25], v162
	ds_read_b128 v[26:29], v149 offset:54848
	ds_read_b128 v[30:33], v162 offset:64
	ds_read_b128 v[178:181], v147 offset:65024
	ds_read_b128 v[34:37], v153 offset:9216
	ds_read_b128 v[182:185], v147 offset:65088
	ds_read_b128 v[186:189], v153 offset:9280
	ds_read_b128 v[190:193], v147 offset:65152
	ds_read_b128 v[206:209], v153 offset:9344
	ds_read_b128 v[210:213], v147 offset:65216
	ds_read_b128 v[214:217], v153 offset:9408
	ds_read_b128 v[218:221], v161
	ds_read_b128 v[222:225], v166
	ds_read_b128 v[38:41], v163
	s_waitcnt lgkmcnt(13)
	v_mfma_f32_16x16x32_bf16 v[6:9], v[6:9], v[22:25], 0
	s_nop 0
	s_nop 0
	s_waitcnt lgkmcnt(11)
	v_mfma_f32_16x16x32_bf16 v[6:9], v[26:29], v[30:33], v[6:9]
	s_nop 0
	s_nop 0
	s_waitcnt lgkmcnt(9)
	v_mfma_f32_16x16x32_bf16 v[6:9], v[178:181], v[34:37], v[6:9]
	ds_read_b128 v[178:181], v163 offset:2560
	s_nop 0
	s_nop 0
	s_waitcnt lgkmcnt(8)
	v_mfma_f32_16x16x32_bf16 v[6:9], v[182:185], v[186:189], v[6:9]
	ds_read_b128 v[182:185], v161 offset:64
	ds_read_b128 v[186:189], v164
	s_nop 0
	s_nop 0
	s_waitcnt lgkmcnt(8)
	v_mfma_f32_16x16x32_bf16 v[6:9], v[190:193], v[206:209], v[6:9]
	ds_read_b128 v[190:193], v164 offset:2560
	s_nop 0
	s_nop 0
	s_nop 0
	s_waitcnt lgkmcnt(7)
	v_mfma_f32_16x16x32_bf16 v[122:125], v[210:213], v[214:217], v[6:9]
	s_nop 0
	s_nop 0
	s_waitcnt lgkmcnt(5)
	v_pk_mul_f32 v[8:9], v[116:117], v[224:225]
	v_pk_mul_f32 v[6:7], v[114:115], v[222:223]
	v_pk_mul_f32 v[36:37], v[120:121], v[224:225]
	v_pk_mul_f32 v[34:35], v[118:119], v[222:223]
	s_waitcnt lgkmcnt(4)
	v_mfma_f32_16x16x32_bf16 v[6:9], v[218:221], v[38:41], v[6:9]
	s_waitcnt lgkmcnt(3)
	v_mfma_f32_16x16x32_bf16 v[22:25], v[218:221], v[178:181], v[34:37]
	s_nop 0
	s_nop 1
	s_nop 0
	s_waitcnt lgkmcnt(1)
	v_mfma_f32_16x16x32_bf16 v[118:121], v[182:185], v[186:189], v[6:9]
	s_waitcnt lgkmcnt(0)
	v_mfma_f32_16x16x32_bf16 v[114:117], v[182:185], v[190:193], v[22:25]
	s_nop 5
	v_cvt_pk_bf16_f32 v6, v118, v119
	v_cvt_pk_bf16_f32 v7, v120, v121
	v_cvt_pk_bf16_f32 v8, v114, v115
	v_cvt_pk_bf16_f32 v9, v116, v117
	ds_write2st64_b64 v151, v[6:7], v[8:9] offset1:9
	s_waitcnt vmcnt(20)
	ds_write_b128 v127, v[66:69]
	s_waitcnt vmcnt(19)
	ds_write_b128 v143, v[74:77] offset:10240
	s_waitcnt vmcnt(18)
	ds_write_b128 v144, v[90:93] offset:10240
	s_waitcnt vmcnt(17)
	ds_write_b128 v127, v[94:97] offset:28672
	s_waitcnt vmcnt(16)
	ds_write_b128 v148, v[110:113] offset:28672
	s_and_saveexec_b64 s[8:9], vcc
	s_cbranch_execz .LBB0_1973
	s_waitcnt vmcnt(15)
	ds_write_b128 v127, v[78:81] offset:49152

.LBB0_1975:
	s_or_b64 exec, exec, s[8:9]
	s_or_b32 s0, s46, 0x64
	s_ashr_i32 s1, s0, 31
	s_lshl_b64 s[8:9], s[0:1], 13
	s_lshl_b64 s[68:69], s[0:1], 14
	s_add_u32 s70, s73, s68
	s_addc_u32 s71, s38, s69
	s_add_u32 s68, s39, s68
	v_lshl_add_u64 v[6:7], v[138:139], 0, s[8:9]
	s_addc_u32 s69, s11, s69
	v_lshl_add_u64 v[8:9], s[70:71], 0, v[128:129]
	global_load_dwordx4 v[22:25], v[6:7], off
	global_load_dwordx4 v[26:29], v[8:9], off
	v_lshl_add_u64 v[6:7], s[70:71], 0, v[130:131]
	s_lshl_b64 s[78:79], s[0:1], 15
	v_lshl_add_u64 v[8:9], s[68:69], 0, v[128:129]
	global_load_dwordx4 v[34:37], v[6:7], off
	global_load_dwordx4 v[38:41], v[8:9], off
	v_lshl_add_u64 v[6:7], s[68:69], 0, v[130:131]
	s_lshl_b64 s[0:1], s[0:1], 9
	v_lshl_add_u64 v[8:9], v[136:137], 0, s[78:79]
	global_load_dwordx4 v[50:53], v[6:7], off
	global_load_dwordx4 v[30:33], v[8:9], off
	v_lshl_add_u64 v[6:7], v[134:135], 0, s[0:1]
	global_load_dwordx4 v[6:9], v[6:7], off
	s_waitcnt vmcnt(21)
	v_cvt_pk_bf16_f32 v60, v122, v122
	s_mov_b64 s[0:1], 0x2a0000
	v_and_b32_e32 v60, 0xffff, v60
	v_lshl_add_u64 v[58:59], v[132:133], 0, s[0:1]
	global_store_short v[58:59], v60, off
	v_cvt_pk_bf16_f32 v60, v123, v123
	s_mov_b64 s[0:1], 0x2a0800
	v_and_b32_e32 v60, 0xffff, v60
	v_lshl_add_u64 v[58:59], v[132:133], 0, s[0:1]
	global_store_short v[58:59], v60, off
	v_cvt_pk_bf16_f32 v60, v124, v124
	s_mov_b64 s[0:1], 0x2a1000
	v_and_b32_e32 v60, 0xffff, v60
	v_lshl_add_u64 v[58:59], v[132:133], 0, s[0:1]
	global_store_short v[58:59], v60, off
	s_mov_b64 s[0:1], 0x2a1800
	v_cvt_pk_bf16_f32 v60, v125, v125
	v_lshl_add_u64 v[58:59], v[132:133], 0, s[0:1]
	v_and_b32_e32 v60, 0xffff, v60
	global_store_short v[58:59], v60, off
	s_waitcnt lgkmcnt(0)
	s_barrier
	ds_read_b128 v[58:61], v149
	ds_read_b128 v[66:69], v149 offset:64
	ds_read_b128 v[74:77], v156 offset:49152
	ds_read_b128 v[78:81], v156 offset:49216
	ds_read_b128 v[178:181], v147 offset:10240
	ds_read_b128 v[182:185], v153
	ds_read_b128 v[186:189], v147 offset:10304
	ds_read_b128 v[90:93], v153 offset:64
	ds_read_b128 v[190:193], v147 offset:10368
	ds_read_b128 v[206:209], v153 offset:128
	ds_read_b128 v[210:213], v147 offset:10432
	ds_read_b128 v[214:217], v153 offset:192
	ds_read_b128 v[94:97], v155 offset:28672
	ds_read_b128 v[218:221], v165 offset:54272
	ds_read_b128 v[222:225], v154 offset:49152
	s_waitcnt lgkmcnt(12)
	v_mfma_f32_16x16x32_bf16 v[58:61], v[58:61], v[74:77], 0
	s_nop 0
	s_waitcnt lgkmcnt(11)
	v_mfma_f32_16x16x32_bf16 v[58:61], v[66:69], v[78:81], v[58:61]
	s_nop 0
	s_nop 0
	s_nop 0
	s_waitcnt lgkmcnt(9)
	v_mfma_f32_16x16x32_bf16 v[58:61], v[178:181], v[182:185], v[58:61]
	ds_read_b128 v[178:181], v154 offset:51712
	ds_read_b128 v[182:185], v155 offset:28736
	s_nop 0
	s_nop 0
	s_waitcnt lgkmcnt(9)
	v_mfma_f32_16x16x32_bf16 v[58:61], v[186:189], v[90:93], v[58:61]
	ds_read_b128 v[186:189], v154 offset:49216
	s_nop 0
	s_nop 0
	s_nop 0
	s_waitcnt lgkmcnt(8)
	v_mfma_f32_16x16x32_bf16 v[58:61], v[190:193], v[206:209], v[58:61]
	ds_read_b128 v[190:193], v154 offset:51776
	s_nop 0
	s_nop 0
	s_waitcnt lgkmcnt(7)
	v_mfma_f32_16x16x32_bf16 v[122:125], v[210:213], v[214:217], v[58:61]
	s_nop 0
	s_waitcnt lgkmcnt(5)
	s_nop 1
	v_pk_mul_f32 v[60:61], v[120:121], v[220:221]
	v_pk_mul_f32 v[58:59], v[118:119], v[218:219]
	v_pk_mul_f32 v[68:69], v[116:117], v[220:221]
	v_pk_mul_f32 v[66:67], v[114:115], v[218:219]
	s_waitcnt lgkmcnt(4)
	v_mfma_f32_16x16x32_bf16 v[58:61], v[94:97], v[222:225], v[58:61]
	s_nop 0
	s_waitcnt lgkmcnt(3)
	v_mfma_f32_16x16x32_bf16 v[66:69], v[94:97], v[178:181], v[66:69]
	s_nop 0
	s_waitcnt lgkmcnt(1)
	v_mfma_f32_16x16x32_bf16 v[114:117], v[182:185], v[186:189], v[58:61]
	s_nop 2
	s_nop 0
	s_waitcnt lgkmcnt(0)
	v_mfma_f32_16x16x32_bf16 v[118:121], v[182:185], v[190:193], v[66:69]
	s_nop 1
	v_cvt_pk_bf16_f32 v58, v114, v115
	v_cvt_pk_bf16_f32 v59, v116, v117
	s_nop 3
	v_cvt_pk_bf16_f32 v60, v118, v119
	v_cvt_pk_bf16_f32 v61, v120, v121
	ds_write2st64_b64 v151, v[58:59], v[60:61] offset0:18 offset1:27
	s_waitcnt vmcnt(20)
	ds_write_b128 v127, v[10:13] offset:54784
	s_waitcnt vmcnt(19)
	ds_write_b128 v143, v[14:17] offset:65024
	s_waitcnt vmcnt(18)
	ds_write_b128 v144, v[42:45] offset:65024
	s_waitcnt vmcnt(17)
	ds_write_b128 v159, v[46:49]
	s_waitcnt vmcnt(16)
	ds_write_b128 v160, v[54:57]
	s_and_saveexec_b64 s[8:9], vcc
	s_cbranch_execz .LBB0_1977
	s_waitcnt vmcnt(15)
	ds_write_b128 v158, v[18:21]

.LBB0_1979:
	s_or_b64 exec, exec, s[8:9]
	s_or_b32 s0, s46, 0x68
	s_ashr_i32 s1, s0, 31
	s_lshl_b64 s[8:9], s[0:1], 13
	s_lshl_b64 s[68:69], s[0:1], 14
	s_add_u32 s70, s73, s68
	s_addc_u32 s71, s38, s69
	s_add_u32 s68, s39, s68
	s_waitcnt vmcnt(14)
	v_lshl_add_u64 v[2:3], v[138:139], 0, s[8:9]
	s_addc_u32 s69, s11, s69
	v_lshl_add_u64 v[4:5], s[70:71], 0, v[128:129]
	global_load_dwordx4 v[66:69], v[2:3], off
	global_load_dwordx4 v[74:77], v[4:5], off
	v_lshl_add_u64 v[2:3], s[70:71], 0, v[130:131]
	s_lshl_b64 s[78:79], s[0:1], 15
	v_lshl_add_u64 v[4:5], s[68:69], 0, v[128:129]
	global_load_dwordx4 v[90:93], v[2:3], off
	global_load_dwordx4 v[94:97], v[4:5], off
	v_lshl_add_u64 v[2:3], s[68:69], 0, v[130:131]
	s_lshl_b64 s[0:1], s[0:1], 9
	v_lshl_add_u64 v[4:5], v[136:137], 0, s[78:79]
	global_load_dwordx4 v[110:113], v[2:3], off
	global_load_dwordx4 v[78:81], v[4:5], off
	v_lshl_add_u64 v[2:3], v[134:135], 0, s[0:1]
	global_load_dwordx4 v[58:61], v[2:3], off
	v_cvt_pk_bf16_f32 v4, v122, v122
	s_mov_b64 s[0:1], 0x2c0000
	v_and_b32_e32 v4, 0xffff, v4
	v_lshl_add_u64 v[2:3], v[132:133], 0, s[0:1]
	global_store_short v[2:3], v4, off
	v_cvt_pk_bf16_f32 v4, v123, v123
	s_mov_b64 s[0:1], 0x2c0800
	v_and_b32_e32 v4, 0xffff, v4
	v_lshl_add_u64 v[2:3], v[132:133], 0, s[0:1]
	global_store_short v[2:3], v4, off
	v_cvt_pk_bf16_f32 v4, v124, v124
	s_mov_b64 s[0:1], 0x2c1000
	v_and_b32_e32 v4, 0xffff, v4
	v_lshl_add_u64 v[2:3], v[132:133], 0, s[0:1]
	global_store_short v[2:3], v4, off
	s_mov_b64 s[0:1], 0x2c1800
	v_cvt_pk_bf16_f32 v4, v125, v125
	v_lshl_add_u64 v[2:3], v[132:133], 0, s[0:1]
	v_and_b32_e32 v4, 0xffff, v4
	global_store_short v[2:3], v4, off
	s_waitcnt lgkmcnt(0)
	s_barrier
	ds_read_b128 v[2:5], v149 offset:54784
	ds_read_b128 v[10:13], v162
	ds_read_b128 v[14:17], v149 offset:54848
	ds_read_b128 v[18:21], v162 offset:64
	ds_read_b128 v[178:181], v147 offset:65024
	ds_read_b128 v[42:45], v153 offset:9216
	ds_read_b128 v[182:185], v147 offset:65088
	ds_read_b128 v[186:189], v153 offset:9280
	ds_read_b128 v[190:193], v147 offset:65152
	ds_read_b128 v[206:209], v153 offset:9344
	ds_read_b128 v[210:213], v147 offset:65216
	ds_read_b128 v[214:217], v153 offset:9408
	ds_read_b128 v[218:221], v161
	ds_read_b128 v[222:225], v166
	ds_read_b128 v[46:49], v163
	s_waitcnt lgkmcnt(13)
	v_mfma_f32_16x16x32_bf16 v[2:5], v[2:5], v[10:13], 0
	s_nop 0
	s_nop 0
	s_waitcnt lgkmcnt(11)
	v_mfma_f32_16x16x32_bf16 v[2:5], v[14:17], v[18:21], v[2:5]
	s_nop 0
	s_nop 0
	s_waitcnt lgkmcnt(9)
	v_mfma_f32_16x16x32_bf16 v[2:5], v[178:181], v[42:45], v[2:5]
	ds_read_b128 v[178:181], v163 offset:2560
	s_nop 0
	s_nop 0
	s_waitcnt lgkmcnt(8)
	v_mfma_f32_16x16x32_bf16 v[2:5], v[182:185], v[186:189], v[2:5]
	ds_read_b128 v[182:185], v161 offset:64
	ds_read_b128 v[186:189], v164
	s_nop 0
	s_nop 0
	s_waitcnt lgkmcnt(8)
	v_mfma_f32_16x16x32_bf16 v[2:5], v[190:193], v[206:209], v[2:5]
	ds_read_b128 v[190:193], v164 offset:2560
	s_nop 0
	s_nop 0
	s_nop 0
	s_waitcnt lgkmcnt(7)
	v_mfma_f32_16x16x32_bf16 v[122:125], v[210:213], v[214:217], v[2:5]
	s_nop 0
	s_nop 0
	s_waitcnt lgkmcnt(5)
	v_pk_mul_f32 v[4:5], v[116:117], v[224:225]
	v_pk_mul_f32 v[2:3], v[114:115], v[222:223]
	v_pk_mul_f32 v[44:45], v[120:121], v[224:225]
	v_pk_mul_f32 v[42:43], v[118:119], v[222:223]
	s_waitcnt lgkmcnt(4)
	v_mfma_f32_16x16x32_bf16 v[2:5], v[218:221], v[46:49], v[2:5]
	s_waitcnt lgkmcnt(3)
	v_mfma_f32_16x16x32_bf16 v[10:13], v[218:221], v[178:181], v[42:45]
	s_nop 0
	s_nop 1
	s_nop 0
	s_waitcnt lgkmcnt(1)
	v_mfma_f32_16x16x32_bf16 v[118:121], v[182:185], v[186:189], v[2:5]
	s_waitcnt lgkmcnt(0)
	v_mfma_f32_16x16x32_bf16 v[114:117], v[182:185], v[190:193], v[10:13]
	s_nop 5
	v_cvt_pk_bf16_f32 v2, v118, v119
	v_cvt_pk_bf16_f32 v3, v120, v121
	v_cvt_pk_bf16_f32 v4, v114, v115
	v_cvt_pk_bf16_f32 v5, v116, v117
	ds_write2st64_b64 v151, v[2:3], v[4:5] offset1:9
	s_waitcnt vmcnt(20)
	ds_write_b128 v127, v[70:73]
	s_waitcnt vmcnt(19)
	ds_write_b128 v143, v[82:85] offset:10240
	s_waitcnt vmcnt(18)
	ds_write_b128 v144, v[98:101] offset:10240
	s_waitcnt vmcnt(17)
	ds_write_b128 v127, v[102:105] offset:28672
	s_waitcnt vmcnt(16)
	ds_write_b128 v148, v[106:109] offset:28672
	s_and_saveexec_b64 s[8:9], vcc
	s_cbranch_execz .LBB0_1981
	s_waitcnt vmcnt(15)
	ds_write_b128 v127, v[86:89] offset:49152

.LBB0_1983:
	s_or_b64 exec, exec, s[8:9]
	s_or_b32 s0, s46, 0x6c
	s_ashr_i32 s1, s0, 31
	s_lshl_b64 s[8:9], s[0:1], 13
	s_lshl_b64 s[68:69], s[0:1], 14
	s_add_u32 s70, s73, s68
	s_addc_u32 s71, s38, s69
	s_add_u32 s68, s39, s68
	v_lshl_add_u64 v[2:3], v[138:139], 0, s[8:9]
	s_addc_u32 s69, s11, s69
	v_lshl_add_u64 v[4:5], s[70:71], 0, v[128:129]
	global_load_dwordx4 v[10:13], v[2:3], off
	global_load_dwordx4 v[14:17], v[4:5], off
	v_lshl_add_u64 v[2:3], s[70:71], 0, v[130:131]
	s_lshl_b64 s[78:79], s[0:1], 15
	v_lshl_add_u64 v[4:5], s[68:69], 0, v[128:129]
	global_load_dwordx4 v[42:45], v[2:3], off
	global_load_dwordx4 v[46:49], v[4:5], off
	v_lshl_add_u64 v[2:3], s[68:69], 0, v[130:131]
	s_lshl_b64 s[0:1], s[0:1], 9
	v_lshl_add_u64 v[4:5], v[136:137], 0, s[78:79]
	global_load_dwordx4 v[54:57], v[2:3], off
	global_load_dwordx4 v[18:21], v[4:5], off
	v_lshl_add_u64 v[2:3], v[134:135], 0, s[0:1]
	global_load_dwordx4 v[2:5], v[2:3], off
	s_waitcnt vmcnt(21)
	v_cvt_pk_bf16_f32 v64, v122, v122
	s_mov_b64 s[0:1], 0x2e0000
	v_and_b32_e32 v64, 0xffff, v64
	v_lshl_add_u64 v[62:63], v[132:133], 0, s[0:1]
	global_store_short v[62:63], v64, off
	v_cvt_pk_bf16_f32 v64, v123, v123
	s_mov_b64 s[0:1], 0x2e0800
	v_and_b32_e32 v64, 0xffff, v64
	v_lshl_add_u64 v[62:63], v[132:133], 0, s[0:1]
	global_store_short v[62:63], v64, off
	v_cvt_pk_bf16_f32 v64, v124, v124
	s_mov_b64 s[0:1], 0x2e1000
	v_and_b32_e32 v64, 0xffff, v64
	v_lshl_add_u64 v[62:63], v[132:133], 0, s[0:1]
	global_store_short v[62:63], v64, off
	s_mov_b64 s[0:1], 0x2e1800
	v_cvt_pk_bf16_f32 v64, v125, v125
	v_lshl_add_u64 v[62:63], v[132:133], 0, s[0:1]
	v_and_b32_e32 v64, 0xffff, v64
	global_store_short v[62:63], v64, off
	s_waitcnt lgkmcnt(0)
	s_barrier
	ds_read_b128 v[62:65], v149
	ds_read_b128 v[70:73], v149 offset:64
	ds_read_b128 v[82:85], v156 offset:49152
	ds_read_b128 v[86:89], v156 offset:49216
	ds_read_b128 v[178:181], v147 offset:10240
	ds_read_b128 v[182:185], v153
	ds_read_b128 v[186:189], v147 offset:10304
	ds_read_b128 v[98:101], v153 offset:64
	ds_read_b128 v[190:193], v147 offset:10368
	ds_read_b128 v[206:209], v153 offset:128
	ds_read_b128 v[210:213], v147 offset:10432
	ds_read_b128 v[214:217], v153 offset:192
	ds_read_b128 v[102:105], v155 offset:28672
	ds_read_b128 v[218:221], v165 offset:54272
	ds_read_b128 v[222:225], v154 offset:49152
	s_waitcnt lgkmcnt(12)
	v_mfma_f32_16x16x32_bf16 v[62:65], v[62:65], v[82:85], 0
	s_nop 0
	s_waitcnt lgkmcnt(11)
	v_mfma_f32_16x16x32_bf16 v[62:65], v[70:73], v[86:89], v[62:65]
	s_nop 0
	s_nop 0
	s_nop 0
	s_waitcnt lgkmcnt(9)
	v_mfma_f32_16x16x32_bf16 v[62:65], v[178:181], v[182:185], v[62:65]
	ds_read_b128 v[178:181], v154 offset:51712
	ds_read_b128 v[182:185], v155 offset:28736
	s_nop 0
	s_nop 0
	s_waitcnt lgkmcnt(9)
	v_mfma_f32_16x16x32_bf16 v[62:65], v[186:189], v[98:101], v[62:65]
	ds_read_b128 v[186:189], v154 offset:49216
	s_nop 0
	s_nop 0
	s_nop 0
	s_waitcnt lgkmcnt(8)
	v_mfma_f32_16x16x32_bf16 v[62:65], v[190:193], v[206:209], v[62:65]
	ds_read_b128 v[190:193], v154 offset:51776
	s_nop 0
	s_nop 0
	s_waitcnt lgkmcnt(7)
	v_mfma_f32_16x16x32_bf16 v[122:125], v[210:213], v[214:217], v[62:65]
	s_nop 0
	s_waitcnt lgkmcnt(5)
	s_nop 1
	v_pk_mul_f32 v[64:65], v[120:121], v[220:221]
	v_pk_mul_f32 v[62:63], v[118:119], v[218:219]
	v_pk_mul_f32 v[72:73], v[116:117], v[220:221]
	v_pk_mul_f32 v[70:71], v[114:115], v[218:219]
	s_waitcnt lgkmcnt(4)
	v_mfma_f32_16x16x32_bf16 v[62:65], v[102:105], v[222:225], v[62:65]
	s_nop 0
	s_waitcnt lgkmcnt(3)
	v_mfma_f32_16x16x32_bf16 v[70:73], v[102:105], v[178:181], v[70:73]
	s_nop 0
	s_waitcnt lgkmcnt(1)
	v_mfma_f32_16x16x32_bf16 v[114:117], v[182:185], v[186:189], v[62:65]
	s_nop 2
	s_nop 0
	s_waitcnt lgkmcnt(0)
	v_mfma_f32_16x16x32_bf16 v[118:121], v[182:185], v[190:193], v[70:73]
	s_nop 1
	v_cvt_pk_bf16_f32 v62, v114, v115
	v_cvt_pk_bf16_f32 v63, v116, v117
	s_nop 3
	v_cvt_pk_bf16_f32 v64, v118, v119
	v_cvt_pk_bf16_f32 v65, v120, v121
	ds_write2st64_b64 v151, v[62:63], v[64:65] offset0:18 offset1:27
	s_waitcnt vmcnt(20)
	ds_write_b128 v127, v[22:25] offset:54784
	s_waitcnt vmcnt(19)
	ds_write_b128 v143, v[26:29] offset:65024
	s_waitcnt vmcnt(18)
	ds_write_b128 v144, v[34:37] offset:65024
	s_waitcnt vmcnt(17)
	ds_write_b128 v159, v[38:41]
	s_waitcnt vmcnt(16)
	ds_write_b128 v160, v[50:53]
	s_and_saveexec_b64 s[8:9], vcc
	s_cbranch_execz .LBB0_1985
	s_waitcnt vmcnt(15)
	ds_write_b128 v158, v[30:33]

.LBB0_1987:
	s_or_b64 exec, exec, s[8:9]
	s_or_b32 s0, s46, 0x70
	s_ashr_i32 s1, s0, 31
	s_lshl_b64 s[8:9], s[0:1], 13
	s_lshl_b64 s[68:69], s[0:1], 14
	s_add_u32 s70, s73, s68
	s_addc_u32 s71, s38, s69
	s_add_u32 s68, s39, s68
	s_waitcnt vmcnt(14)
	v_lshl_add_u64 v[6:7], v[138:139], 0, s[8:9]
	s_addc_u32 s69, s11, s69
	v_lshl_add_u64 v[8:9], s[70:71], 0, v[128:129]
	global_load_dwordx4 v[70:73], v[6:7], off
	global_load_dwordx4 v[82:85], v[8:9], off
	v_lshl_add_u64 v[6:7], s[70:71], 0, v[130:131]
	s_lshl_b64 s[78:79], s[0:1], 15
	v_lshl_add_u64 v[8:9], s[68:69], 0, v[128:129]
	global_load_dwordx4 v[98:101], v[6:7], off
	global_load_dwordx4 v[102:105], v[8:9], off
	v_lshl_add_u64 v[6:7], s[68:69], 0, v[130:131]
	s_lshl_b64 s[0:1], s[0:1], 9
	v_lshl_add_u64 v[8:9], v[136:137], 0, s[78:79]
	global_load_dwordx4 v[106:109], v[6:7], off
	global_load_dwordx4 v[86:89], v[8:9], off
	v_lshl_add_u64 v[6:7], v[134:135], 0, s[0:1]
	global_load_dwordx4 v[62:65], v[6:7], off
	v_cvt_pk_bf16_f32 v8, v122, v122
	s_mov_b64 s[0:1], 0x300000
	v_and_b32_e32 v8, 0xffff, v8
	v_lshl_add_u64 v[6:7], v[132:133], 0, s[0:1]
	global_store_short v[6:7], v8, off
	v_cvt_pk_bf16_f32 v8, v123, v123
	s_mov_b64 s[0:1], 0x300800
	v_and_b32_e32 v8, 0xffff, v8
	v_lshl_add_u64 v[6:7], v[132:133], 0, s[0:1]
	global_store_short v[6:7], v8, off
	v_cvt_pk_bf16_f32 v8, v124, v124
	s_mov_b64 s[0:1], 0x301000
	v_and_b32_e32 v8, 0xffff, v8
	v_lshl_add_u64 v[6:7], v[132:133], 0, s[0:1]
	global_store_short v[6:7], v8, off
	s_mov_b64 s[0:1], 0x301800
	v_cvt_pk_bf16_f32 v8, v125, v125
	v_lshl_add_u64 v[6:7], v[132:133], 0, s[0:1]
	v_and_b32_e32 v8, 0xffff, v8
	global_store_short v[6:7], v8, off
	s_waitcnt lgkmcnt(0)
	s_barrier
	ds_read_b128 v[6:9], v149 offset:54784
	ds_read_b128 v[22:25], v162
	ds_read_b128 v[26:29], v149 offset:54848
	ds_read_b128 v[30:33], v162 offset:64
	ds_read_b128 v[178:181], v147 offset:65024
	ds_read_b128 v[34:37], v153 offset:9216
	ds_read_b128 v[182:185], v147 offset:65088
	ds_read_b128 v[186:189], v153 offset:9280
	ds_read_b128 v[190:193], v147 offset:65152
	ds_read_b128 v[206:209], v153 offset:9344
	ds_read_b128 v[210:213], v147 offset:65216
	ds_read_b128 v[214:217], v153 offset:9408
	ds_read_b128 v[218:221], v161
	ds_read_b128 v[222:225], v166
	ds_read_b128 v[38:41], v163
	s_waitcnt lgkmcnt(13)
	v_mfma_f32_16x16x32_bf16 v[6:9], v[6:9], v[22:25], 0
	s_nop 0
	s_nop 0
	s_waitcnt lgkmcnt(11)
	v_mfma_f32_16x16x32_bf16 v[6:9], v[26:29], v[30:33], v[6:9]
	s_nop 0
	s_nop 0
	s_waitcnt lgkmcnt(9)
	v_mfma_f32_16x16x32_bf16 v[6:9], v[178:181], v[34:37], v[6:9]
	ds_read_b128 v[178:181], v163 offset:2560
	s_nop 0
	s_nop 0
	s_waitcnt lgkmcnt(8)
	v_mfma_f32_16x16x32_bf16 v[6:9], v[182:185], v[186:189], v[6:9]
	ds_read_b128 v[182:185], v161 offset:64
	ds_read_b128 v[186:189], v164
	s_nop 0
	s_nop 0
	s_waitcnt lgkmcnt(8)
	v_mfma_f32_16x16x32_bf16 v[6:9], v[190:193], v[206:209], v[6:9]
	ds_read_b128 v[190:193], v164 offset:2560
	s_nop 0
	s_nop 0
	s_nop 0
	s_waitcnt lgkmcnt(7)
	v_mfma_f32_16x16x32_bf16 v[122:125], v[210:213], v[214:217], v[6:9]
	s_nop 0
	s_nop 0
	s_waitcnt lgkmcnt(5)
	v_pk_mul_f32 v[8:9], v[116:117], v[224:225]
	v_pk_mul_f32 v[6:7], v[114:115], v[222:223]
	v_pk_mul_f32 v[36:37], v[120:121], v[224:225]
	v_pk_mul_f32 v[34:35], v[118:119], v[222:223]
	s_waitcnt lgkmcnt(4)
	v_mfma_f32_16x16x32_bf16 v[6:9], v[218:221], v[38:41], v[6:9]
	s_waitcnt lgkmcnt(3)
	v_mfma_f32_16x16x32_bf16 v[22:25], v[218:221], v[178:181], v[34:37]
	s_nop 0
	s_nop 1
	s_nop 0
	s_waitcnt lgkmcnt(1)
	v_mfma_f32_16x16x32_bf16 v[118:121], v[182:185], v[186:189], v[6:9]
	s_waitcnt lgkmcnt(0)
	v_mfma_f32_16x16x32_bf16 v[114:117], v[182:185], v[190:193], v[22:25]
	s_nop 5
	v_cvt_pk_bf16_f32 v6, v118, v119
	v_cvt_pk_bf16_f32 v7, v120, v121
	v_cvt_pk_bf16_f32 v8, v114, v115
	v_cvt_pk_bf16_f32 v9, v116, v117
	ds_write2st64_b64 v151, v[6:7], v[8:9] offset1:9
	s_waitcnt vmcnt(20)
	ds_write_b128 v127, v[66:69]
	s_waitcnt vmcnt(19)
	ds_write_b128 v143, v[74:77] offset:10240
	s_waitcnt vmcnt(18)
	ds_write_b128 v144, v[90:93] offset:10240
	s_waitcnt vmcnt(17)
	ds_write_b128 v127, v[94:97] offset:28672
	s_waitcnt vmcnt(16)
	ds_write_b128 v148, v[110:113] offset:28672
	s_and_saveexec_b64 s[8:9], vcc
	s_cbranch_execz .LBB0_1989
	s_waitcnt vmcnt(15)
	ds_write_b128 v127, v[78:81] offset:49152

.LBB0_1991:
	s_or_b64 exec, exec, s[8:9]
	s_or_b32 s0, s46, 0x74
	s_ashr_i32 s1, s0, 31
	s_lshl_b64 s[8:9], s[0:1], 13
	s_lshl_b64 s[68:69], s[0:1], 14
	s_add_u32 s70, s73, s68
	s_addc_u32 s71, s38, s69
	s_add_u32 s68, s39, s68
	v_lshl_add_u64 v[6:7], v[138:139], 0, s[8:9]
	s_addc_u32 s69, s11, s69
	v_lshl_add_u64 v[8:9], s[70:71], 0, v[128:129]
	global_load_dwordx4 v[22:25], v[6:7], off
	global_load_dwordx4 v[26:29], v[8:9], off
	v_lshl_add_u64 v[6:7], s[70:71], 0, v[130:131]
	s_lshl_b64 s[78:79], s[0:1], 15
	v_lshl_add_u64 v[8:9], s[68:69], 0, v[128:129]
	global_load_dwordx4 v[34:37], v[6:7], off
	global_load_dwordx4 v[38:41], v[8:9], off
	v_lshl_add_u64 v[6:7], s[68:69], 0, v[130:131]
	s_lshl_b64 s[0:1], s[0:1], 9
	v_lshl_add_u64 v[8:9], v[136:137], 0, s[78:79]
	global_load_dwordx4 v[50:53], v[6:7], off
	global_load_dwordx4 v[30:33], v[8:9], off
	v_lshl_add_u64 v[6:7], v[134:135], 0, s[0:1]
	global_load_dwordx4 v[6:9], v[6:7], off
	s_waitcnt vmcnt(21)
	v_cvt_pk_bf16_f32 v60, v122, v122
	s_mov_b64 s[0:1], 0x320000
	v_and_b32_e32 v60, 0xffff, v60
	v_lshl_add_u64 v[58:59], v[132:133], 0, s[0:1]
	global_store_short v[58:59], v60, off
	v_cvt_pk_bf16_f32 v60, v123, v123
	s_mov_b64 s[0:1], 0x320800
	v_and_b32_e32 v60, 0xffff, v60
	v_lshl_add_u64 v[58:59], v[132:133], 0, s[0:1]
	global_store_short v[58:59], v60, off
	v_cvt_pk_bf16_f32 v60, v124, v124
	s_mov_b64 s[0:1], 0x321000
	v_and_b32_e32 v60, 0xffff, v60
	v_lshl_add_u64 v[58:59], v[132:133], 0, s[0:1]
	global_store_short v[58:59], v60, off
	s_mov_b64 s[0:1], 0x321800
	v_cvt_pk_bf16_f32 v60, v125, v125
	v_lshl_add_u64 v[58:59], v[132:133], 0, s[0:1]
	v_and_b32_e32 v60, 0xffff, v60
	global_store_short v[58:59], v60, off
	s_waitcnt lgkmcnt(0)
	s_barrier
	ds_read_b128 v[58:61], v149
	ds_read_b128 v[66:69], v149 offset:64
	ds_read_b128 v[74:77], v156 offset:49152
	ds_read_b128 v[78:81], v156 offset:49216
	ds_read_b128 v[178:181], v147 offset:10240
	ds_read_b128 v[182:185], v153
	ds_read_b128 v[186:189], v147 offset:10304
	ds_read_b128 v[90:93], v153 offset:64
	ds_read_b128 v[190:193], v147 offset:10368
	ds_read_b128 v[206:209], v153 offset:128
	ds_read_b128 v[210:213], v147 offset:10432
	ds_read_b128 v[214:217], v153 offset:192
	ds_read_b128 v[94:97], v155 offset:28672
	ds_read_b128 v[218:221], v165 offset:54272
	ds_read_b128 v[222:225], v154 offset:49152
	s_waitcnt lgkmcnt(12)
	v_mfma_f32_16x16x32_bf16 v[58:61], v[58:61], v[74:77], 0
	s_nop 0
	s_waitcnt lgkmcnt(11)
	v_mfma_f32_16x16x32_bf16 v[58:61], v[66:69], v[78:81], v[58:61]
	s_nop 0
	s_nop 0
	s_nop 0
	s_waitcnt lgkmcnt(9)
	v_mfma_f32_16x16x32_bf16 v[58:61], v[178:181], v[182:185], v[58:61]
	ds_read_b128 v[178:181], v154 offset:51712
	ds_read_b128 v[182:185], v155 offset:28736
	s_nop 0
	s_nop 0
	s_waitcnt lgkmcnt(9)
	v_mfma_f32_16x16x32_bf16 v[58:61], v[186:189], v[90:93], v[58:61]
	ds_read_b128 v[186:189], v154 offset:49216
	s_nop 0
	s_nop 0
	s_nop 0
	s_waitcnt lgkmcnt(8)
	v_mfma_f32_16x16x32_bf16 v[58:61], v[190:193], v[206:209], v[58:61]
	ds_read_b128 v[190:193], v154 offset:51776
	s_nop 0
	s_nop 0
	s_waitcnt lgkmcnt(7)
	v_mfma_f32_16x16x32_bf16 v[122:125], v[210:213], v[214:217], v[58:61]
	s_nop 0
	s_waitcnt lgkmcnt(5)
	s_nop 1
	v_pk_mul_f32 v[60:61], v[120:121], v[220:221]
	v_pk_mul_f32 v[58:59], v[118:119], v[218:219]
	v_pk_mul_f32 v[68:69], v[116:117], v[220:221]
	v_pk_mul_f32 v[66:67], v[114:115], v[218:219]
	s_waitcnt lgkmcnt(4)
	v_mfma_f32_16x16x32_bf16 v[58:61], v[94:97], v[222:225], v[58:61]
	s_nop 0
	s_waitcnt lgkmcnt(3)
	v_mfma_f32_16x16x32_bf16 v[66:69], v[94:97], v[178:181], v[66:69]
	s_nop 0
	s_waitcnt lgkmcnt(1)
	v_mfma_f32_16x16x32_bf16 v[114:117], v[182:185], v[186:189], v[58:61]
	s_nop 2
	s_nop 0
	s_waitcnt lgkmcnt(0)
	v_mfma_f32_16x16x32_bf16 v[118:121], v[182:185], v[190:193], v[66:69]
	s_nop 1
	v_cvt_pk_bf16_f32 v58, v114, v115
	v_cvt_pk_bf16_f32 v59, v116, v117
	s_nop 3
	v_cvt_pk_bf16_f32 v60, v118, v119
	v_cvt_pk_bf16_f32 v61, v120, v121
	ds_write2st64_b64 v151, v[58:59], v[60:61] offset0:18 offset1:27
	s_waitcnt vmcnt(20)
	ds_write_b128 v127, v[10:13] offset:54784
	s_waitcnt vmcnt(19)
	ds_write_b128 v143, v[14:17] offset:65024
	s_waitcnt vmcnt(18)
	ds_write_b128 v144, v[42:45] offset:65024
	s_waitcnt vmcnt(17)
	ds_write_b128 v159, v[46:49]
	s_waitcnt vmcnt(16)
	ds_write_b128 v160, v[54:57]
	s_and_saveexec_b64 s[8:9], vcc
	s_cbranch_execz .LBB0_1993
	s_waitcnt vmcnt(15)
	ds_write_b128 v158, v[18:21]

.LBB0_1995:
	s_or_b64 exec, exec, s[8:9]
	s_or_b32 s0, s46, 0x78
	s_ashr_i32 s1, s0, 31
	s_lshl_b64 s[8:9], s[0:1], 13
	s_lshl_b64 s[68:69], s[0:1], 14
	s_add_u32 s70, s73, s68
	s_addc_u32 s71, s38, s69
	s_add_u32 s68, s39, s68
	s_waitcnt vmcnt(14)
	v_lshl_add_u64 v[2:3], v[138:139], 0, s[8:9]
	s_addc_u32 s69, s11, s69
	v_lshl_add_u64 v[4:5], s[70:71], 0, v[128:129]
	global_load_dwordx4 v[66:69], v[2:3], off
	global_load_dwordx4 v[74:77], v[4:5], off
	v_lshl_add_u64 v[2:3], s[70:71], 0, v[130:131]
	s_lshl_b64 s[78:79], s[0:1], 15
	v_lshl_add_u64 v[4:5], s[68:69], 0, v[128:129]
	global_load_dwordx4 v[90:93], v[2:3], off
	global_load_dwordx4 v[94:97], v[4:5], off
	v_lshl_add_u64 v[2:3], s[68:69], 0, v[130:131]
	s_lshl_b64 s[0:1], s[0:1], 9
	v_lshl_add_u64 v[4:5], v[136:137], 0, s[78:79]
	global_load_dwordx4 v[110:113], v[2:3], off
	global_load_dwordx4 v[78:81], v[4:5], off
	v_lshl_add_u64 v[2:3], v[134:135], 0, s[0:1]
	global_load_dwordx4 v[58:61], v[2:3], off
	v_cvt_pk_bf16_f32 v4, v122, v122
	s_mov_b64 s[0:1], 0x340000
	v_and_b32_e32 v4, 0xffff, v4
	v_lshl_add_u64 v[2:3], v[132:133], 0, s[0:1]
	global_store_short v[2:3], v4, off
	v_cvt_pk_bf16_f32 v4, v123, v123
	s_mov_b64 s[0:1], 0x340800
	v_and_b32_e32 v4, 0xffff, v4
	v_lshl_add_u64 v[2:3], v[132:133], 0, s[0:1]
	global_store_short v[2:3], v4, off
	v_cvt_pk_bf16_f32 v4, v124, v124
	s_mov_b64 s[0:1], 0x341000
	v_and_b32_e32 v4, 0xffff, v4
	v_lshl_add_u64 v[2:3], v[132:133], 0, s[0:1]
	global_store_short v[2:3], v4, off
	s_mov_b64 s[0:1], 0x341800
	v_cvt_pk_bf16_f32 v4, v125, v125
	v_lshl_add_u64 v[2:3], v[132:133], 0, s[0:1]
	v_and_b32_e32 v4, 0xffff, v4
	global_store_short v[2:3], v4, off
	s_waitcnt lgkmcnt(0)
	s_barrier
	ds_read_b128 v[2:5], v149 offset:54784
	ds_read_b128 v[10:13], v162
	ds_read_b128 v[14:17], v149 offset:54848
	ds_read_b128 v[18:21], v162 offset:64
	ds_read_b128 v[178:181], v147 offset:65024
	ds_read_b128 v[42:45], v153 offset:9216
	ds_read_b128 v[182:185], v147 offset:65088
	ds_read_b128 v[186:189], v153 offset:9280
	ds_read_b128 v[190:193], v147 offset:65152
	ds_read_b128 v[206:209], v153 offset:9344
	ds_read_b128 v[210:213], v147 offset:65216
	ds_read_b128 v[214:217], v153 offset:9408
	ds_read_b128 v[218:221], v161
	ds_read_b128 v[222:225], v166
	ds_read_b128 v[46:49], v163
	s_waitcnt lgkmcnt(13)
	v_mfma_f32_16x16x32_bf16 v[2:5], v[2:5], v[10:13], 0
	s_nop 0
	s_nop 0
	s_waitcnt lgkmcnt(11)
	v_mfma_f32_16x16x32_bf16 v[2:5], v[14:17], v[18:21], v[2:5]
	s_nop 0
	s_nop 0
	s_waitcnt lgkmcnt(9)
	v_mfma_f32_16x16x32_bf16 v[2:5], v[178:181], v[42:45], v[2:5]
	ds_read_b128 v[178:181], v163 offset:2560
	s_nop 0
	s_nop 0
	s_waitcnt lgkmcnt(8)
	v_mfma_f32_16x16x32_bf16 v[2:5], v[182:185], v[186:189], v[2:5]
	ds_read_b128 v[182:185], v161 offset:64
	ds_read_b128 v[186:189], v164
	s_nop 0
	s_nop 0
	s_waitcnt lgkmcnt(8)
	v_mfma_f32_16x16x32_bf16 v[2:5], v[190:193], v[206:209], v[2:5]
	ds_read_b128 v[190:193], v164 offset:2560
	s_nop 0
	s_nop 0
	s_nop 0
	s_waitcnt lgkmcnt(7)
	v_mfma_f32_16x16x32_bf16 v[122:125], v[210:213], v[214:217], v[2:5]
	s_nop 0
	s_nop 0
	s_waitcnt lgkmcnt(5)
	v_pk_mul_f32 v[4:5], v[116:117], v[224:225]
	v_pk_mul_f32 v[2:3], v[114:115], v[222:223]
	v_pk_mul_f32 v[44:45], v[120:121], v[224:225]
	v_pk_mul_f32 v[42:43], v[118:119], v[222:223]
	s_waitcnt lgkmcnt(4)
	v_mfma_f32_16x16x32_bf16 v[2:5], v[218:221], v[46:49], v[2:5]
	s_waitcnt lgkmcnt(3)
	v_mfma_f32_16x16x32_bf16 v[10:13], v[218:221], v[178:181], v[42:45]
	s_nop 0
	s_nop 1
	s_nop 0
	s_waitcnt lgkmcnt(1)
	v_mfma_f32_16x16x32_bf16 v[118:121], v[182:185], v[186:189], v[2:5]
	s_waitcnt lgkmcnt(0)
	v_mfma_f32_16x16x32_bf16 v[114:117], v[182:185], v[190:193], v[10:13]
	s_nop 5
	v_cvt_pk_bf16_f32 v2, v118, v119
	v_cvt_pk_bf16_f32 v3, v120, v121
	v_cvt_pk_bf16_f32 v4, v114, v115
	v_cvt_pk_bf16_f32 v5, v116, v117
	ds_write2st64_b64 v151, v[2:3], v[4:5] offset1:9
	s_waitcnt vmcnt(20)
	ds_write_b128 v127, v[70:73]
	s_waitcnt vmcnt(19)
	ds_write_b128 v143, v[82:85] offset:10240
	s_waitcnt vmcnt(18)
	ds_write_b128 v144, v[98:101] offset:10240
	s_waitcnt vmcnt(17)
	ds_write_b128 v127, v[102:105] offset:28672
	s_waitcnt vmcnt(16)
	ds_write_b128 v148, v[106:109] offset:28672
	s_and_saveexec_b64 s[8:9], vcc
	s_cbranch_execz .LBB0_1997
	s_waitcnt vmcnt(15)
	ds_write_b128 v127, v[86:89] offset:49152

.LBB0_1999:
	s_or_b64 exec, exec, s[8:9]
	s_or_b32 s0, s46, 0x7c
	s_ashr_i32 s1, s0, 31
	s_lshl_b64 s[8:9], s[0:1], 13
	s_lshl_b64 s[68:69], s[0:1], 14
	s_add_u32 s70, s73, s68
	s_addc_u32 s71, s38, s69
	s_add_u32 s68, s39, s68
	v_lshl_add_u64 v[2:3], v[138:139], 0, s[8:9]
	s_addc_u32 s69, s11, s69
	v_lshl_add_u64 v[4:5], s[70:71], 0, v[128:129]
	global_load_dwordx4 v[14:17], v[2:3], off
	global_load_dwordx4 v[18:21], v[4:5], off
	v_lshl_add_u64 v[2:3], s[70:71], 0, v[130:131]
	s_lshl_b64 s[78:79], s[0:1], 15
	v_lshl_add_u64 v[4:5], s[68:69], 0, v[128:129]
	global_load_dwordx4 v[42:45], v[2:3], off
	global_load_dwordx4 v[46:49], v[4:5], off
	v_lshl_add_u64 v[2:3], s[68:69], 0, v[130:131]
	s_lshl_b64 s[0:1], s[0:1], 9
	v_lshl_add_u64 v[4:5], v[136:137], 0, s[78:79]
	global_load_dwordx4 v[54:57], v[2:3], off
	global_load_dwordx4 v[10:13], v[4:5], off
	v_lshl_add_u64 v[2:3], v[134:135], 0, s[0:1]
	global_load_dwordx4 v[2:5], v[2:3], off
	s_waitcnt vmcnt(21)
	v_cvt_pk_bf16_f32 v64, v122, v122
	s_mov_b64 s[0:1], 0x360000
	v_and_b32_e32 v64, 0xffff, v64
	v_lshl_add_u64 v[62:63], v[132:133], 0, s[0:1]
	global_store_short v[62:63], v64, off
	v_cvt_pk_bf16_f32 v64, v123, v123
	s_mov_b64 s[0:1], 0x360800
	v_and_b32_e32 v64, 0xffff, v64
	v_lshl_add_u64 v[62:63], v[132:133], 0, s[0:1]
	global_store_short v[62:63], v64, off
	v_cvt_pk_bf16_f32 v64, v124, v124
	s_mov_b64 s[0:1], 0x361000
	v_and_b32_e32 v64, 0xffff, v64
	v_lshl_add_u64 v[62:63], v[132:133], 0, s[0:1]
	global_store_short v[62:63], v64, off
	s_mov_b64 s[0:1], 0x361800
	v_cvt_pk_bf16_f32 v64, v125, v125
	v_lshl_add_u64 v[62:63], v[132:133], 0, s[0:1]
	v_and_b32_e32 v64, 0xffff, v64
	global_store_short v[62:63], v64, off
	s_waitcnt lgkmcnt(0)
	s_barrier
	ds_read_b128 v[62:65], v149
	ds_read_b128 v[70:73], v149 offset:64
	ds_read_b128 v[82:85], v156 offset:49152
	ds_read_b128 v[86:89], v156 offset:49216
	ds_read_b128 v[178:181], v147 offset:10240
	ds_read_b128 v[182:185], v153
	ds_read_b128 v[186:189], v147 offset:10304
	ds_read_b128 v[98:101], v153 offset:64
	ds_read_b128 v[190:193], v147 offset:10368
	ds_read_b128 v[206:209], v153 offset:128
	ds_read_b128 v[210:213], v147 offset:10432
	ds_read_b128 v[214:217], v153 offset:192
	ds_read_b128 v[102:105], v155 offset:28672
	ds_read_b128 v[218:221], v165 offset:54272
	ds_read_b128 v[106:109], v154 offset:49152
	ds_read_b128 v[222:225], v154 offset:51712
	s_waitcnt lgkmcnt(13)
	v_mfma_f32_16x16x32_bf16 v[62:65], v[62:65], v[82:85], 0
	s_nop 0
	s_waitcnt lgkmcnt(12)
	v_mfma_f32_16x16x32_bf16 v[62:65], v[70:73], v[86:89], v[62:65]
	s_nop 0
	s_nop 0
	s_nop 0
	s_waitcnt lgkmcnt(10)
	v_mfma_f32_16x16x32_bf16 v[62:65], v[178:181], v[182:185], v[62:65]
	s_nop 0
	s_nop 0
	s_waitcnt lgkmcnt(8)
	v_mfma_f32_16x16x32_bf16 v[62:65], v[186:189], v[98:101], v[62:65]
	s_nop 0
	s_nop 0
	s_nop 0
	s_waitcnt lgkmcnt(6)
	v_mfma_f32_16x16x32_bf16 v[62:65], v[190:193], v[206:209], v[62:65]
	s_nop 0
	s_nop 0
	s_waitcnt lgkmcnt(4)
	v_mfma_f32_16x16x32_bf16 v[82:85], v[210:213], v[214:217], v[62:65]
	ds_read_b128 v[98:101], v155 offset:28736
	ds_read_b128 v[178:181], v154 offset:49216
	ds_read_b128 v[182:185], v154 offset:51776
	s_nop 0
	s_nop 0
	s_waitcnt lgkmcnt(5)
	s_nop 0
	v_pk_mul_f32 v[64:65], v[120:121], v[220:221]
	v_pk_mul_f32 v[62:63], v[118:119], v[218:219]
	v_pk_mul_f32 v[72:73], v[116:117], v[220:221]
	v_pk_mul_f32 v[70:71], v[114:115], v[218:219]
	s_waitcnt lgkmcnt(4)
	v_mfma_f32_16x16x32_bf16 v[62:65], v[102:105], v[106:109], v[62:65]
	s_waitcnt lgkmcnt(3)
	v_mfma_f32_16x16x32_bf16 v[70:73], v[102:105], v[222:225], v[70:73]
	s_nop 0
	s_waitcnt lgkmcnt(1)
	v_mfma_f32_16x16x32_bf16 v[62:65], v[98:101], v[178:181], v[62:65]
	s_nop 0
	s_waitcnt lgkmcnt(0)
	v_mfma_f32_16x16x32_bf16 v[70:73], v[98:101], v[182:185], v[70:73]
	s_nop 4
	v_cvt_pk_bf16_f32 v86, v62, v63
	v_cvt_pk_bf16_f32 v87, v64, v65
	s_nop 0
	v_cvt_pk_bf16_f32 v88, v70, v71
	v_cvt_pk_bf16_f32 v89, v72, v73
	ds_write2st64_b64 v151, v[86:87], v[88:89] offset0:18 offset1:27
	s_waitcnt vmcnt(20)
	ds_write_b128 v127, v[22:25] offset:54784
	s_waitcnt vmcnt(19)
	ds_write_b128 v143, v[26:29] offset:65024
	s_waitcnt vmcnt(18)
	ds_write_b128 v144, v[34:37] offset:65024
	s_waitcnt vmcnt(17)
	ds_write_b128 v159, v[38:41]
	s_waitcnt vmcnt(16)
	ds_write_b128 v160, v[50:53]
	s_and_saveexec_b64 s[8:9], vcc
	s_cbranch_execz .LBB0_2001
	s_waitcnt vmcnt(15)
	ds_write_b128 v158, v[30:33]

.LBB0_2003:
	s_or_b64 exec, exec, s[8:9]
	s_waitcnt vmcnt(14)
	v_cvt_pk_bf16_f32 v8, v82, v82
	s_mov_b64 s[0:1], 0x380000
	v_and_b32_e32 v8, 0xffff, v8
	v_lshl_add_u64 v[6:7], v[132:133], 0, s[0:1]
	global_store_short v[6:7], v8, off
	v_cvt_pk_bf16_f32 v8, v83, v83
	s_mov_b64 s[0:1], 0x380800
	v_and_b32_e32 v8, 0xffff, v8
	v_lshl_add_u64 v[6:7], v[132:133], 0, s[0:1]
	global_store_short v[6:7], v8, off
	v_cvt_pk_bf16_f32 v8, v84, v84
	s_mov_b64 s[0:1], 0x381000
	v_and_b32_e32 v8, 0xffff, v8
	v_lshl_add_u64 v[6:7], v[132:133], 0, s[0:1]
	global_store_short v[6:7], v8, off
	s_mov_b64 s[0:1], 0x381800
	v_cvt_pk_bf16_f32 v8, v85, v85
	v_lshl_add_u64 v[6:7], v[132:133], 0, s[0:1]
	v_and_b32_e32 v8, 0xffff, v8
	global_store_short v[6:7], v8, off
	s_waitcnt lgkmcnt(0)
	s_barrier
	ds_read_b128 v[6:9], v149 offset:54784
	ds_read_b128 v[22:25], v162
	ds_read_b128 v[26:29], v149 offset:54848
	ds_read_b128 v[30:33], v162 offset:64
	ds_read_b128 v[178:181], v147 offset:65024
	ds_read_b128 v[34:37], v153 offset:9216
	ds_read_b128 v[182:185], v147 offset:65088
	ds_read_b128 v[186:189], v153 offset:9280
	ds_read_b128 v[190:193], v147 offset:65152
	ds_read_b128 v[206:209], v153 offset:9344
	ds_read_b128 v[210:213], v147 offset:65216
	ds_read_b128 v[214:217], v153 offset:9408
	ds_read_b128 v[218:221], v161
	ds_read_b128 v[222:225], v166
	ds_read_b128 v[38:41], v163
	s_waitcnt lgkmcnt(13)
	v_mfma_f32_16x16x32_bf16 v[6:9], v[6:9], v[22:25], 0
	s_nop 0
	s_nop 0
	s_waitcnt lgkmcnt(11)
	v_mfma_f32_16x16x32_bf16 v[6:9], v[26:29], v[30:33], v[6:9]
	s_nop 0
	s_nop 0
	s_waitcnt lgkmcnt(9)
	v_mfma_f32_16x16x32_bf16 v[6:9], v[178:181], v[34:37], v[6:9]
	ds_read_b128 v[178:181], v163 offset:2560
	ds_read_b128 v[50:53], v161 offset:64
	s_nop 0
	s_nop 0
	s_waitcnt lgkmcnt(9)
	v_mfma_f32_16x16x32_bf16 v[6:9], v[182:185], v[186:189], v[6:9]
	ds_read_b128 v[182:185], v164
	ds_read_b128 v[186:189], v164 offset:2560
	s_nop 0
	s_nop 0
	s_waitcnt lgkmcnt(9)
	v_mfma_f32_16x16x32_bf16 v[6:9], v[190:193], v[206:209], v[6:9]
	s_nop 0
	s_nop 0
	s_nop 0
	s_waitcnt lgkmcnt(7)
	v_mfma_f32_16x16x32_bf16 v[26:29], v[210:213], v[214:217], v[6:9]
	s_nop 0
	s_nop 0
	s_waitcnt lgkmcnt(5)
	v_pk_mul_f32 v[8:9], v[64:65], v[224:225]
	v_pk_mul_f32 v[6:7], v[62:63], v[222:223]
	v_pk_mul_f32 v[36:37], v[72:73], v[224:225]
	v_pk_mul_f32 v[34:35], v[70:71], v[222:223]
	s_waitcnt lgkmcnt(4)
	v_mfma_f32_16x16x32_bf16 v[6:9], v[218:221], v[38:41], v[6:9]
	s_waitcnt lgkmcnt(3)
	v_mfma_f32_16x16x32_bf16 v[30:33], v[218:221], v[178:181], v[34:37]
	s_nop 0
	s_nop 1
	s_nop 0
	s_waitcnt lgkmcnt(1)
	v_mfma_f32_16x16x32_bf16 v[22:25], v[50:53], v[182:185], v[6:9]
	s_waitcnt lgkmcnt(0)
	v_mfma_f32_16x16x32_bf16 v[6:9], v[50:53], v[186:189], v[30:33]
	s_nop 5
	v_cvt_pk_bf16_f32 v30, v22, v23
	v_cvt_pk_bf16_f32 v31, v24, v25
	v_cvt_pk_bf16_f32 v32, v6, v7
	v_cvt_pk_bf16_f32 v33, v8, v9
	ds_write2st64_b64 v151, v[30:31], v[32:33] offset1:9
	s_waitcnt vmcnt(13)
	ds_write_b128 v127, v[66:69]
	s_waitcnt vmcnt(12)
	ds_write_b128 v143, v[74:77] offset:10240
	s_waitcnt vmcnt(11)
	ds_write_b128 v144, v[90:93] offset:10240
	s_waitcnt vmcnt(10)
	ds_write_b128 v127, v[94:97] offset:28672
	s_waitcnt vmcnt(9)
	ds_write_b128 v148, v[110:113] offset:28672
	s_and_saveexec_b64 s[8:9], vcc
	s_cbranch_execz .LBB0_2005
	s_waitcnt vmcnt(8)
	ds_write_b128 v127, v[78:81] offset:49152

.LBB0_2007:
	s_or_b64 exec, exec, s[8:9]
	v_cvt_pk_bf16_f32 v26, v26, v26
	s_mov_b64 s[0:1], 0x3a0000
	v_and_b32_e32 v26, 0xffff, v26
	v_lshl_add_u64 v[30:31], v[132:133], 0, s[0:1]
	global_store_short v[30:31], v26, off
	s_mov_b64 s[0:1], 0x3a0800
	v_cvt_pk_bf16_f32 v26, v27, v27
	v_cvt_pk_bf16_f32 v28, v28, v28
	v_lshl_add_u64 v[30:31], v[132:133], 0, s[0:1]
	v_and_b32_e32 v26, 0xffff, v26
	global_store_short v[30:31], v26, off
	s_mov_b64 s[0:1], 0x3a1000
	v_and_b32_e32 v28, 0xffff, v28
	v_lshl_add_u64 v[26:27], v[132:133], 0, s[0:1]
	global_store_short v[26:27], v28, off
	s_mov_b64 s[0:1], 0x3a1800
	v_cvt_pk_bf16_f32 v28, v29, v29
	v_lshl_add_u64 v[26:27], v[132:133], 0, s[0:1]
	v_and_b32_e32 v28, 0xffff, v28
	global_store_short v[26:27], v28, off
	s_waitcnt lgkmcnt(0)
	s_barrier
	ds_read_b128 v[26:29], v149
	ds_read_b128 v[30:33], v156 offset:49152
	ds_read_b128 v[34:37], v149 offset:64
	ds_read_b128 v[178:181], v156 offset:49216
	ds_read_b128 v[38:41], v147 offset:10240
	ds_read_b128 v[182:185], v153
	ds_read_b128 v[186:189], v147 offset:10304
	ds_read_b128 v[50:53], v153 offset:64
	ds_read_b128 v[58:61], v147 offset:10368
	ds_read_b128 v[190:193], v153 offset:128
	ds_read_b128 v[62:65], v147 offset:10432
	ds_read_b128 v[206:209], v153 offset:192
	ds_read_b128 v[210:213], v155 offset:28672
	s_waitcnt lgkmcnt(11)
	v_mfma_f32_16x16x32_bf16 v[26:29], v[26:29], v[30:33], 0
	s_nop 0
	s_nop 0
	s_add_i32 s35, s35, 0x1d000
	s_waitcnt lgkmcnt(9)
	v_mfma_f32_16x16x32_bf16 v[26:29], v[34:37], v[178:181], v[26:29]
	s_nop 0
	s_nop 0
	s_nop 0
	s_waitcnt vmcnt(7)
	s_nop 0
	s_waitcnt lgkmcnt(7)
	v_mfma_f32_16x16x32_bf16 v[26:29], v[38:41], v[182:185], v[26:29]
	s_nop 0
	s_nop 0
	v_and_b32_e32 v30, 48, v126
	v_add_u32_e32 v31, s49, v30
	ds_read_b128 v[178:181], v31 offset:54272
	ds_read_b128 v[182:185], v154 offset:49152
	ds_read_b128 v[214:217], v154 offset:51712
	ds_read_b128 v[218:221], v155 offset:28736
	ds_read_b128 v[222:225], v154 offset:49216
	s_waitcnt lgkmcnt(10)
	v_mfma_f32_16x16x32_bf16 v[26:29], v[186:189], v[50:53], v[26:29]
	ds_read_b128 v[186:189], v154 offset:51776
	s_nop 0
	s_nop 0
	s_waitcnt lgkmcnt(9)
	v_mfma_f32_16x16x32_bf16 v[26:29], v[58:61], v[190:193], v[26:29]
	s_nop 0
	s_nop 0
	v_add3_u32 v31, s35, v142, v141
	s_waitcnt lgkmcnt(5)
	v_pk_mul_f32 v[24:25], v[24:25], v[180:181]
	v_mfma_f32_16x16x32_bf16 v[26:29], v[62:65], v[206:209], v[26:29]
	v_mul_f32_e64 v22, v22, v178
	v_mul_f32_e64 v23, v23, v179
	s_nop 0
	v_pk_mul_f32 v[8:9], v[8:9], v[180:181]
	s_waitcnt lgkmcnt(4)
	v_mfma_f32_16x16x32_bf16 v[22:25], v[210:213], v[182:185], v[22:25]
	s_nop 0
	v_pk_mul_f32 v[6:7], v[6:7], v[178:179]
	s_waitcnt lgkmcnt(3)
	s_nop 0
	v_mfma_f32_16x16x32_bf16 v[32:35], v[210:213], v[214:217], v[6:9]
	s_nop 2
	s_nop 0
	s_waitcnt lgkmcnt(1)
	v_mfma_f32_16x16x32_bf16 v[6:9], v[218:221], v[222:225], v[22:25]
	s_nop 2
	s_nop 0
	s_waitcnt lgkmcnt(0)
	v_mfma_f32_16x16x32_bf16 v[22:25], v[218:221], v[186:189], v[32:35]
	s_nop 2
	v_cvt_pk_bf16_f32 v32, v6, v7
	v_cvt_pk_bf16_f32 v33, v8, v9
	s_nop 2
	v_cvt_pk_bf16_f32 v34, v22, v23
	v_cvt_pk_bf16_f32 v35, v24, v25
	ds_write2st64_b64 v31, v[32:33], v[34:35] offset1:9
	s_waitcnt vmcnt(6)
	ds_write_b128 v127, v[14:17] offset:54784
	s_waitcnt vmcnt(5)
	ds_write_b128 v143, v[18:21] offset:65024
	s_waitcnt vmcnt(4)
	ds_write_b128 v144, v[42:45] offset:65024
	s_waitcnt vmcnt(3)
	ds_write_b128 v159, v[46:49]
	s_waitcnt vmcnt(2)
	ds_write_b128 v160, v[54:57]
	s_and_saveexec_b64 s[0:1], vcc
	s_xor_b64 s[8:9], exec, s[0:1]
	s_cbranch_execz .LBB0_2009
	s_waitcnt vmcnt(1)
	ds_write_b128 v158, v[10:13]

.LBB0_2022:
	s_or_b64 exec, exec, s[8:9]
	s_lshl_b64 s[0:1], s[6:7], 6
	s_add_u32 s0, s27, s0
	s_addc_u32 s1, s28, s1
	s_lshl_b32 s8, s42, 2
	v_mov_b32_e32 v86, s8
	global_load_dword v90, v86, s[0:1]
	s_nop 0
	global_load_dword v86, v86, s[0:1] offset:32
	s_waitcnt lgkmcnt(0)
	s_barrier
	ds_read_b128 v[92:95], v88
	ds_read_b128 v[96:99], v88 offset:16
	s_waitcnt vmcnt(0) lgkmcnt(0)
	v_pk_fma_f32 v[100:101], v[62:63], v[92:93], 0 op_sel_hi:[1,0,0]
	v_pk_fma_f32 v[102:103], v[64:65], v[92:93], 0 op_sel_hi:[1,0,0]
	v_mul_f32_e32 v91, 0x3fb8aa3b, v86
	v_pk_fma_f32 v[102:103], v[60:61], v[92:93], v[102:103] op_sel:[0,1,0]
	v_pk_fma_f32 v[92:93], v[58:59], v[92:93], v[100:101] op_sel:[0,1,0]
	v_pk_fma_f32 v[100:101], v[56:57], v[94:95], v[102:103] op_sel_hi:[1,0,1]
	v_pk_fma_f32 v[92:93], v[54:55], v[94:95], v[92:93] op_sel_hi:[1,0,1]
	v_mov_b32_e32 v86, v95
	v_pk_fma_f32 v[94:95], v[52:53], v[86:87], v[100:101] op_sel_hi:[1,0,1]
	v_pk_fma_f32 v[92:93], v[50:51], v[86:87], v[92:93] op_sel_hi:[1,0,1]
	v_pk_fma_f32 v[94:95], v[48:49], v[96:97], v[94:95] op_sel_hi:[1,0,1]
	v_pk_fma_f32 v[92:93], v[46:47], v[96:97], v[92:93] op_sel_hi:[1,0,1]
	v_pk_fma_f32 v[94:95], v[44:45], v[96:97], v[94:95] op_sel:[0,1,0]
	v_pk_fma_f32 v[92:93], v[42:43], v[96:97], v[92:93] op_sel:[0,1,0]
	v_pk_fma_f32 v[94:95], v[40:41], v[98:99], v[94:95] op_sel_hi:[1,0,1]
	v_pk_fma_f32 v[92:93], v[38:39], v[98:99], v[92:93] op_sel_hi:[1,0,1]
	v_mov_b32_e32 v86, v99
	v_pk_fma_f32 v[94:95], v[36:37], v[86:87], v[94:95] op_sel_hi:[1,0,1]
	v_pk_fma_f32 v[92:93], v[34:35], v[86:87], v[92:93] op_sel_hi:[1,0,1]
	v_exp_f32_e32 v86, v91
	ds_write_b128 v89, v[92:95] offset:2048
	s_waitcnt lgkmcnt(0)
	s_barrier
	s_and_saveexec_b64 s[8:9], s[44:45]
	s_cbranch_execz .LBB0_2024
	ds_read2st64_b32 v[92:93], v87 offset0:4 offset1:8
	ds_read2st64_b32 v[94:95], v87 offset0:10 offset1:12
	ds_read2st64_b32 v[178:179], v87 offset0:14 offset1:16
	ds_read_b32 v182, v87 offset:9728
	ds_read2st64_b32 v[186:187], v87 offset0:18 offset1:20
	ds_read2st64_b32 v[190:191], v87 offset0:22 offset1:24
	ds_read2st64_b32 v[206:207], v87 offset0:26 offset1:28
	ds_read2st64_b32 v[210:211], v87 offset0:30 offset1:32
	ds_read2st64_b32 v[214:215], v87 offset0:34 offset1:36
	s_waitcnt lgkmcnt(8)
	v_add_f32_e32 v91, 0, v93
	s_waitcnt lgkmcnt(7)
	v_add_f32_e32 v91, v91, v94
	v_add_f32_e32 v91, v91, v95
	s_nop 0
	s_nop 0
	s_waitcnt lgkmcnt(6)
	v_add_f32_e32 v91, v91, v178
	v_add_f32_e32 v91, v91, v179
	s_nop 0
	s_waitcnt lgkmcnt(4)
	v_add_f32_e32 v91, v91, v186
	v_add_f32_e32 v91, v91, v187
	s_nop 0
	s_waitcnt lgkmcnt(3)
	v_add_f32_e32 v91, v91, v190
	v_add_f32_e32 v91, v91, v191
	s_nop 0
	s_waitcnt lgkmcnt(2)
	v_add_f32_e32 v91, v91, v206
	v_add_f32_e32 v91, v91, v207
	s_nop 0
	s_waitcnt lgkmcnt(1)
	v_add_f32_e32 v91, v91, v210
	v_add_f32_e32 v91, v91, v211
	s_nop 0
	s_waitcnt lgkmcnt(0)
	v_add_f32_e32 v91, v91, v214
	v_add_f32_e32 v91, v91, v215
	v_add_f32_e32 v91, v91, v182
	v_fma_f32 v91, -v86, v91, v92
	v_mul_f32_e32 v90, v90, v91
	ds_write_b32 v87, v90 offset:1536
.LBB0_2024:
	s_or_b64 exec, exec, s[8:9]
	s_ashr_i32 s1, s43, 31
	s_add_u32 s0, s43, s26
	s_addc_u32 s1, s1, 0
	s_waitcnt lgkmcnt(0)
	s_barrier
	ds_read_b128 v[90:93], v69 offset:1536
	ds_read_b128 v[94:97], v88
	ds_read_b128 v[98:101], v88 offset:16
	ds_read_b128 v[178:181], v88 offset:512
	s_lshl_b64 s[0:1], s[0:1], 19
	s_nop 0
	s_add_u32 s0, s29, s0
	s_nop 0
	s_nop 0
	s_addc_u32 s1, s30, s1
	s_lshl_b32 s8, s42, 16
	s_add_u32 s0, s0, s8
	s_addc_u32 s1, s1, 0
	v_lshl_add_u64 v[106:107], s[0:1], 0, v[196:197]
	s_waitcnt lgkmcnt(2)
	v_pk_mul_f32 v[102:103], v[90:91], v[94:95] op_sel_hi:[1,0]
	v_pk_mul_f32 v[104:105], v[92:93], v[94:95] op_sel_hi:[1,0]
	v_pk_fma_f32 v[62:63], v[62:63], v[86:87], v[102:103] op_sel_hi:[1,0,1]
	v_pk_fma_f32 v[64:65], v[64:65], v[86:87], v[104:105] op_sel_hi:[1,0,1]
	v_lshl_add_u64 v[102:103], v[106:107], 0, v[70:71]
	global_store_dwordx4 v[102:103], v[62:65], off nt
	s_nop 0
	v_pk_mul_f32 v[108:109], v[90:91], v[94:95] op_sel:[0,1]
	v_pk_mul_f32 v[94:95], v[92:93], v[94:95] op_sel:[0,1]
	v_pk_fma_f32 v[58:59], v[58:59], v[86:87], v[108:109] op_sel_hi:[1,0,1]
	v_pk_fma_f32 v[60:61], v[60:61], v[86:87], v[94:95] op_sel_hi:[1,0,1]
	s_waitcnt lgkmcnt(0)
	v_pk_fma_f32 v[64:65], v[64:65], v[178:179], 0 op_sel_hi:[1,0,0]
	v_pk_fma_f32 v[62:63], v[62:63], v[178:179], 0 op_sel_hi:[1,0,0]
	v_lshl_add_u64 v[94:95], v[106:107], 0, v[72:73]
	global_store_dwordx4 v[94:95], v[58:61], off nt
	s_nop 1
	v_pk_fma_f32 v[60:61], v[60:61], v[178:179], v[64:65] op_sel:[0,1,0]
	v_pk_fma_f32 v[58:59], v[58:59], v[178:179], v[62:63] op_sel:[0,1,0]
	v_pk_mul_f32 v[62:63], v[92:93], v[96:97] op_sel_hi:[1,0]
	v_pk_mul_f32 v[64:65], v[90:91], v[96:97] op_sel_hi:[1,0]
	v_pk_fma_f32 v[56:57], v[56:57], v[86:87], v[62:63] op_sel_hi:[1,0,1]
	v_pk_fma_f32 v[54:55], v[54:55], v[86:87], v[64:65] op_sel_hi:[1,0,1]
	v_lshl_add_u64 v[62:63], v[106:107], 0, v[74:75]
	global_store_dwordx4 v[62:63], v[54:57], off nt
	s_nop 1
	v_pk_fma_f32 v[54:55], v[54:55], v[180:181], v[58:59] op_sel_hi:[1,0,1]
	v_mov_b32_e32 v58, v97
	v_pk_fma_f32 v[56:57], v[56:57], v[180:181], v[60:61] op_sel_hi:[1,0,1]
	v_pk_mul_f32 v[60:61], v[92:93], v[58:59] op_sel_hi:[1,0]
	v_pk_mul_f32 v[58:59], v[90:91], v[58:59] op_sel_hi:[1,0]
	v_pk_fma_f32 v[52:53], v[52:53], v[86:87], v[60:61] op_sel_hi:[1,0,1]
	v_pk_fma_f32 v[50:51], v[50:51], v[86:87], v[58:59] op_sel_hi:[1,0,1]
	v_lshl_add_u64 v[58:59], v[106:107], 0, v[76:77]
	global_store_dwordx4 v[58:59], v[50:53], off nt
	v_mov_b32_e32 v58, v181
	v_pk_fma_f32 v[56:57], v[52:53], v[58:59], v[56:57] op_sel_hi:[1,0,1]
	v_pk_fma_f32 v[54:55], v[50:51], v[58:59], v[54:55] op_sel_hi:[1,0,1]
	v_pk_mul_f32 v[50:51], v[90:91], v[98:99] op_sel_hi:[1,0]
	v_pk_mul_f32 v[52:53], v[92:93], v[98:99] op_sel_hi:[1,0]
	v_pk_fma_f32 v[46:47], v[46:47], v[86:87], v[50:51] op_sel_hi:[1,0,1]
	v_pk_fma_f32 v[48:49], v[48:49], v[86:87], v[52:53] op_sel_hi:[1,0,1]
	v_lshl_add_u64 v[50:51], v[106:107], 0, v[78:79]
	global_store_dwordx4 v[50:51], v[46:49], off nt
	ds_read_b128 v[50:53], v88 offset:528
	s_waitcnt lgkmcnt(0)
	v_pk_fma_f32 v[48:49], v[48:49], v[50:51], v[56:57] op_sel_hi:[1,0,1]
	v_pk_fma_f32 v[46:47], v[46:47], v[50:51], v[54:55] op_sel_hi:[1,0,1]
	v_pk_mul_f32 v[54:55], v[90:91], v[98:99] op_sel:[0,1]
	v_pk_mul_f32 v[56:57], v[92:93], v[98:99] op_sel:[0,1]
	v_pk_fma_f32 v[42:43], v[42:43], v[86:87], v[54:55] op_sel_hi:[1,0,1]
	v_pk_fma_f32 v[44:45], v[44:45], v[86:87], v[56:57] op_sel_hi:[1,0,1]
	v_lshl_add_u64 v[54:55], v[106:107], 0, v[80:81]
	global_store_dwordx4 v[54:55], v[42:45], off nt
	s_nop 1
	v_pk_fma_f32 v[44:45], v[44:45], v[50:51], v[48:49] op_sel:[0,1,0]
	v_pk_fma_f32 v[42:43], v[42:43], v[50:51], v[46:47] op_sel:[0,1,0]
	v_pk_mul_f32 v[46:47], v[92:93], v[100:101] op_sel_hi:[1,0]
	v_pk_mul_f32 v[48:49], v[90:91], v[100:101] op_sel_hi:[1,0]
	v_pk_fma_f32 v[40:41], v[40:41], v[86:87], v[46:47] op_sel_hi:[1,0,1]
	v_pk_fma_f32 v[38:39], v[38:39], v[86:87], v[48:49] op_sel_hi:[1,0,1]
	v_lshl_add_u64 v[46:47], v[106:107], 0, v[82:83]
	global_store_dwordx4 v[46:47], v[38:41], off nt
	s_nop 1
	v_pk_fma_f32 v[38:39], v[38:39], v[52:53], v[42:43] op_sel_hi:[1,0,1]
	v_mov_b32_e32 v42, v101
	v_pk_fma_f32 v[40:41], v[40:41], v[52:53], v[44:45] op_sel_hi:[1,0,1]
	v_pk_mul_f32 v[44:45], v[92:93], v[42:43] op_sel_hi:[1,0]
	v_pk_mul_f32 v[42:43], v[90:91], v[42:43] op_sel_hi:[1,0]
	v_pk_fma_f32 v[36:37], v[36:37], v[86:87], v[44:45] op_sel_hi:[1,0,1]
	v_pk_fma_f32 v[34:35], v[34:35], v[86:87], v[42:43] op_sel_hi:[1,0,1]
	v_lshl_add_u64 v[42:43], v[106:107], 0, v[84:85]
	global_store_dwordx4 v[42:43], v[34:37], off nt
	v_mov_b32_e32 v42, v53
	s_nop 0
	v_pk_fma_f32 v[36:37], v[36:37], v[42:43], v[40:41] op_sel_hi:[1,0,1]
	v_pk_fma_f32 v[34:35], v[34:35], v[42:43], v[38:39] op_sel_hi:[1,0,1]
	ds_write_b128 v89, v[34:37] offset:2048
	s_waitcnt lgkmcnt(0)
	s_barrier
	s_and_saveexec_b64 s[8:9], s[44:45]
	s_cbranch_execz .LBB0_2017
	ds_read2st64_b32 v[34:35], v87 offset0:8 offset1:10
	ds_read2st64_b32 v[178:179], v87 offset0:12 offset1:14
	ds_read2st64_b32 v[182:183], v87 offset0:16 offset1:18
	ds_read2st64_b32 v[186:187], v87 offset0:20 offset1:22
	ds_read2st64_b32 v[190:191], v87 offset0:24 offset1:26
	ds_read2st64_b32 v[206:207], v87 offset0:28 offset1:30
	ds_read2st64_b32 v[210:211], v87 offset0:32 offset1:34
	ds_read2st64_b32 v[214:215], v87 offset0:36 offset1:38
	s_waitcnt lgkmcnt(7)
	v_add_f32_e32 v34, 0, v34
	v_add_f32_e32 v36, v34, v35
	s_nop 0
	s_waitcnt lgkmcnt(6)
	v_add_f32_e32 v34, v36, v178
	v_add_f32_e32 v36, v34, v179
	s_nop 0
	s_waitcnt lgkmcnt(5)
	v_add_f32_e32 v34, v36, v182
	v_add_f32_e32 v36, v34, v183
	s_nop 0
	s_waitcnt lgkmcnt(4)
	v_add_f32_e32 v34, v36, v186
	v_add_f32_e32 v36, v34, v187
	s_nop 0
	s_waitcnt lgkmcnt(3)
	v_add_f32_e32 v34, v36, v190
	v_add_f32_e32 v36, v34, v191
	s_nop 0
	s_waitcnt lgkmcnt(2)
	v_add_f32_e32 v34, v36, v206
	v_add_f32_e32 v36, v34, v207
	s_nop 0
	s_waitcnt lgkmcnt(1)
	v_add_f32_e32 v34, v36, v210
	v_add_f32_e32 v36, v34, v211
	s_nop 0
	s_waitcnt lgkmcnt(0)
	v_add_f32_e32 v34, v36, v214
	v_add_f32_e32 v34, v34, v215
	v_cvt_pk_bf16_f32 v36, v34, s0
	s_lshl_b64 s[0:1], s[6:7], 11
	s_add_u32 s0, s35, s0
	s_addc_u32 s1, s38, s1
	s_lshl_b32 s6, s42, 8
	s_add_u32 s0, s0, s6
	s_addc_u32 s1, s1, 0
	v_lshl_add_u64 v[34:35], v[66:67], 1, s[0:1]
	global_store_short v[34:35], v36, off
	s_branch .LBB0_2017

.LBB0_2035:
	s_or_b64 exec, exec, s[40:41]
	s_waitcnt lgkmcnt(0)
	s_barrier
	ds_read_b128 v[78:81], v137 offset:1536
	ds_read_b128 v[178:181], v176 offset:1024
	ds_read_b128 v[182:185], v176
	ds_read_b128 v[186:189], v176 offset:16
	ds_read_b128 v[190:193], v176 offset:32
	s_ashr_i32 s1, s11, 31
	s_nop 0
	s_add_u32 s0, s11, s10
	s_addc_u32 s1, s1, 0
	s_nop 0
	s_nop 0
	s_nop 0
	s_nop 0
	s_lshl_b64 s[0:1], s[0:1], 19
	s_add_u32 s0, s28, s0
	s_addc_u32 s1, s29, s1
	s_lshl_b32 s8, s43, 17
	s_waitcnt lgkmcnt(0)
	v_pk_mul_f32 v[202:203], v[80:81], v[182:183] op_sel_hi:[1,0]
	s_add_u32 s0, s0, s8
	s_waitcnt vmcnt(0)
	v_pk_fma_f32 v[132:133], v[132:133], v[178:179], v[202:203] op_sel_hi:[1,0,1]
	ds_read_b128 v[202:205], v176 offset:512
	s_addc_u32 s1, s1, 0
	v_lshl_add_u64 v[170:171], s[0:1], 0, v[196:197]
	v_pk_mul_f32 v[194:195], v[78:79], v[182:183] op_sel_hi:[1,0]
	s_nop 0
	v_pk_fma_f32 v[130:131], v[130:131], v[178:179], v[194:195] op_sel_hi:[1,0,1]
	v_lshl_add_u64 v[194:195], v[170:171], 0, v[138:139]
	global_store_dwordx4 v[194:195], v[130:133], off nt
	v_pk_mul_f32 v[194:195], v[78:79], v[182:183] op_sel:[0,1]
	v_pk_mul_f32 v[182:183], v[80:81], v[182:183] op_sel:[0,1]
	s_waitcnt lgkmcnt(0)
	v_pk_fma_f32 v[132:133], v[132:133], v[202:203], 0 op_sel_hi:[1,0,0]
	v_pk_fma_f32 v[130:131], v[130:131], v[202:203], 0 op_sel_hi:[1,0,0]
	v_pk_fma_f32 v[128:129], v[128:129], v[178:179], v[182:183] op_sel:[0,1,0]
	v_pk_fma_f32 v[126:127], v[126:127], v[178:179], v[194:195] op_sel:[0,1,0]
	v_lshl_add_u64 v[178:179], v[170:171], 0, v[140:141]
	global_store_dwordx4 v[178:179], v[126:129], off nt
	s_nop 1
	v_pk_fma_f32 v[128:129], v[128:129], v[202:203], v[132:133] op_sel:[0,1,0]
	v_pk_fma_f32 v[126:127], v[126:127], v[202:203], v[130:131] op_sel:[0,1,0]
	v_pk_mul_f32 v[130:131], v[80:81], v[184:185] op_sel_hi:[1,0]
	v_pk_mul_f32 v[132:133], v[78:79], v[184:185] op_sel_hi:[1,0]
	v_pk_fma_f32 v[124:125], v[124:125], v[180:181], v[130:131] op_sel_hi:[1,0,1]
	v_pk_fma_f32 v[122:123], v[122:123], v[180:181], v[132:133] op_sel_hi:[1,0,1]
	v_lshl_add_u64 v[130:131], v[170:171], 0, v[142:143]
	global_store_dwordx4 v[130:131], v[122:125], off nt
	v_mov_b32_e32 v130, v181
	s_nop 0
	v_pk_fma_f32 v[122:123], v[122:123], v[204:205], v[126:127] op_sel_hi:[1,0,1]
	v_mov_b32_e32 v126, v185
	v_pk_fma_f32 v[124:125], v[124:125], v[204:205], v[128:129] op_sel_hi:[1,0,1]
	v_pk_mul_f32 v[128:129], v[80:81], v[126:127] op_sel_hi:[1,0]
	v_pk_mul_f32 v[126:127], v[78:79], v[126:127] op_sel_hi:[1,0]
	v_pk_fma_f32 v[120:121], v[120:121], v[130:131], v[128:129] op_sel_hi:[1,0,1]
	v_pk_fma_f32 v[118:119], v[118:119], v[130:131], v[126:127] op_sel_hi:[1,0,1]
	v_lshl_add_u64 v[126:127], v[170:171], 0, v[144:145]
	global_store_dwordx4 v[126:127], v[118:121], off nt
	v_mov_b32_e32 v126, v205
	v_pk_fma_f32 v[128:129], v[118:119], v[126:127], v[122:123] op_sel_hi:[1,0,1]
	v_pk_fma_f32 v[126:127], v[120:121], v[126:127], v[124:125] op_sel_hi:[1,0,1]
	ds_read_b128 v[118:121], v176 offset:1040
	v_pk_mul_f32 v[122:123], v[78:79], v[186:187] op_sel_hi:[1,0]
	v_pk_mul_f32 v[124:125], v[80:81], v[186:187] op_sel_hi:[1,0]
	s_waitcnt lgkmcnt(0)
	v_pk_fma_f32 v[114:115], v[114:115], v[118:119], v[122:123] op_sel_hi:[1,0,1]
	v_pk_fma_f32 v[116:117], v[116:117], v[118:119], v[124:125] op_sel_hi:[1,0,1]
	v_lshl_add_u64 v[122:123], v[170:171], 0, v[146:147]
	global_store_dwordx4 v[122:123], v[114:117], off nt
	ds_read_b128 v[122:125], v176 offset:528
	s_waitcnt lgkmcnt(0)
	v_pk_fma_f32 v[116:117], v[116:117], v[122:123], v[126:127] op_sel_hi:[1,0,1]
	v_pk_fma_f32 v[114:115], v[114:115], v[122:123], v[128:129] op_sel_hi:[1,0,1]
	v_pk_mul_f32 v[126:127], v[78:79], v[186:187] op_sel:[0,1]
	v_pk_mul_f32 v[128:129], v[80:81], v[186:187] op_sel:[0,1]
	v_pk_fma_f32 v[110:111], v[110:111], v[118:119], v[126:127] op_sel:[0,1,0]
	v_pk_fma_f32 v[112:113], v[112:113], v[118:119], v[128:129] op_sel:[0,1,0]
	v_lshl_add_u64 v[118:119], v[170:171], 0, v[148:149]
	global_store_dwordx4 v[118:119], v[110:113], off nt
	s_nop 1
	v_pk_fma_f32 v[110:111], v[110:111], v[122:123], v[114:115] op_sel:[0,1,0]
	v_pk_fma_f32 v[112:113], v[112:113], v[122:123], v[116:117] op_sel:[0,1,0]
	v_pk_mul_f32 v[114:115], v[80:81], v[188:189] op_sel_hi:[1,0]
	v_pk_mul_f32 v[116:117], v[78:79], v[188:189] op_sel_hi:[1,0]
	v_pk_fma_f32 v[108:109], v[108:109], v[120:121], v[114:115] op_sel_hi:[1,0,1]
	v_pk_fma_f32 v[106:107], v[106:107], v[120:121], v[116:117] op_sel_hi:[1,0,1]
	v_lshl_add_u64 v[114:115], v[170:171], 0, v[150:151]
	global_store_dwordx4 v[114:115], v[106:109], off nt
	v_mov_b32_e32 v114, v121
	s_nop 0
	v_pk_fma_f32 v[106:107], v[106:107], v[124:125], v[110:111] op_sel_hi:[1,0,1]
	v_mov_b32_e32 v110, v189
	v_pk_fma_f32 v[108:109], v[108:109], v[124:125], v[112:113] op_sel_hi:[1,0,1]
	v_pk_mul_f32 v[112:113], v[80:81], v[110:111] op_sel_hi:[1,0]
	v_pk_mul_f32 v[110:111], v[78:79], v[110:111] op_sel_hi:[1,0]
	v_pk_fma_f32 v[104:105], v[104:105], v[114:115], v[112:113] op_sel_hi:[1,0,1]
	v_pk_fma_f32 v[102:103], v[102:103], v[114:115], v[110:111] op_sel_hi:[1,0,1]
	v_lshl_add_u64 v[110:111], v[170:171], 0, v[152:153]
	global_store_dwordx4 v[110:111], v[102:105], off nt
	v_mov_b32_e32 v110, v125
	v_pk_fma_f32 v[112:113], v[102:103], v[110:111], v[106:107] op_sel_hi:[1,0,1]
	v_pk_fma_f32 v[110:111], v[104:105], v[110:111], v[108:109] op_sel_hi:[1,0,1]
	ds_read_b128 v[102:105], v176 offset:1056
	v_pk_mul_f32 v[106:107], v[78:79], v[190:191] op_sel_hi:[1,0]
	v_pk_mul_f32 v[108:109], v[80:81], v[190:191] op_sel_hi:[1,0]
	s_waitcnt lgkmcnt(0)
	v_pk_fma_f32 v[98:99], v[98:99], v[102:103], v[106:107] op_sel_hi:[1,0,1]
	v_pk_fma_f32 v[100:101], v[100:101], v[102:103], v[108:109] op_sel_hi:[1,0,1]
	v_lshl_add_u64 v[106:107], v[170:171], 0, v[154:155]
	global_store_dwordx4 v[106:107], v[98:101], off nt
	ds_read_b128 v[106:109], v176 offset:544
	ds_read_b128 v[178:181], v176 offset:1072
	s_waitcnt lgkmcnt(1)
	v_pk_fma_f32 v[100:101], v[100:101], v[106:107], v[110:111] op_sel_hi:[1,0,1]
	v_pk_fma_f32 v[98:99], v[98:99], v[106:107], v[112:113] op_sel_hi:[1,0,1]
	v_pk_mul_f32 v[110:111], v[78:79], v[190:191] op_sel:[0,1]
	v_pk_mul_f32 v[112:113], v[80:81], v[190:191] op_sel:[0,1]
	v_pk_fma_f32 v[94:95], v[94:95], v[102:103], v[110:111] op_sel:[0,1,0]
	v_pk_fma_f32 v[96:97], v[96:97], v[102:103], v[112:113] op_sel:[0,1,0]
	v_lshl_add_u64 v[102:103], v[170:171], 0, v[156:157]
	global_store_dwordx4 v[102:103], v[94:97], off nt
	s_nop 1
	v_pk_fma_f32 v[94:95], v[94:95], v[106:107], v[98:99] op_sel:[0,1,0]
	v_pk_fma_f32 v[96:97], v[96:97], v[106:107], v[100:101] op_sel:[0,1,0]
	v_pk_mul_f32 v[98:99], v[80:81], v[192:193] op_sel_hi:[1,0]
	v_pk_mul_f32 v[100:101], v[78:79], v[192:193] op_sel_hi:[1,0]
	v_pk_fma_f32 v[88:89], v[88:89], v[104:105], v[98:99] op_sel_hi:[1,0,1]
	v_pk_fma_f32 v[86:87], v[86:87], v[104:105], v[100:101] op_sel_hi:[1,0,1]
	v_lshl_add_u64 v[98:99], v[170:171], 0, v[158:159]
	global_store_dwordx4 v[98:99], v[86:89], off nt
	v_mov_b32_e32 v98, v105
	s_nop 0
	v_pk_fma_f32 v[86:87], v[86:87], v[108:109], v[94:95] op_sel_hi:[1,0,1]
	v_mov_b32_e32 v94, v193
	v_pk_fma_f32 v[88:89], v[88:89], v[108:109], v[96:97] op_sel_hi:[1,0,1]
	v_pk_mul_f32 v[96:97], v[80:81], v[94:95] op_sel_hi:[1,0]
	v_pk_mul_f32 v[94:95], v[78:79], v[94:95] op_sel_hi:[1,0]
	v_pk_fma_f32 v[84:85], v[84:85], v[98:99], v[96:97] op_sel_hi:[1,0,1]
	v_pk_fma_f32 v[82:83], v[82:83], v[98:99], v[94:95] op_sel_hi:[1,0,1]
	v_lshl_add_u64 v[94:95], v[170:171], 0, v[160:161]
	global_store_dwordx4 v[94:95], v[82:85], off nt
	v_mov_b32_e32 v94, v109
	v_pk_fma_f32 v[98:99], v[82:83], v[94:95], v[86:87] op_sel_hi:[1,0,1]
	v_pk_fma_f32 v[100:101], v[84:85], v[94:95], v[88:89] op_sel_hi:[1,0,1]
	ds_read_b128 v[86:89], v176 offset:48
	ds_read_b128 v[182:185], v176 offset:560
	s_nop 0
	s_nop 0
	s_waitcnt lgkmcnt(1)
	v_pk_mul_f32 v[94:95], v[78:79], v[86:87] op_sel_hi:[1,0]
	v_pk_mul_f32 v[96:97], v[80:81], v[86:87] op_sel_hi:[1,0]
	v_pk_fma_f32 v[90:91], v[90:91], v[178:179], v[94:95] op_sel_hi:[1,0,1]
	v_pk_fma_f32 v[92:93], v[92:93], v[178:179], v[96:97] op_sel_hi:[1,0,1]
	v_lshl_add_u64 v[94:95], v[170:171], 0, v[162:163]
	global_store_dwordx4 v[94:95], v[90:93], off nt
	s_nop 0
	s_waitcnt lgkmcnt(0)
	v_pk_fma_f32 v[90:91], v[90:91], v[182:183], v[98:99] op_sel_hi:[1,0,1]
	v_pk_mul_f32 v[98:99], v[78:79], v[86:87] op_sel:[0,1]
	v_pk_mul_f32 v[86:87], v[80:81], v[86:87] op_sel:[0,1]
	v_pk_fma_f32 v[74:75], v[74:75], v[178:179], v[98:99] op_sel:[0,1,0]
	v_pk_fma_f32 v[76:77], v[76:77], v[178:179], v[86:87] op_sel:[0,1,0]
	v_lshl_add_u64 v[82:83], v[170:171], 0, v[164:165]
	global_store_dwordx4 v[82:83], v[74:77], off nt
	v_pk_mul_f32 v[82:83], v[80:81], v[88:89] op_sel_hi:[1,0]
	v_pk_mul_f32 v[86:87], v[78:79], v[88:89] op_sel_hi:[1,0]
	v_pk_fma_f32 v[92:93], v[92:93], v[182:183], v[100:101] op_sel_hi:[1,0,1]
	v_pk_fma_f32 v[74:75], v[74:75], v[182:183], v[90:91] op_sel:[0,1,0]
	v_pk_fma_f32 v[72:73], v[72:73], v[180:181], v[82:83] op_sel_hi:[1,0,1]
	v_pk_fma_f32 v[70:71], v[70:71], v[180:181], v[86:87] op_sel_hi:[1,0,1]
	v_lshl_add_u64 v[82:83], v[170:171], 0, v[166:167]
	v_pk_fma_f32 v[76:77], v[76:77], v[182:183], v[92:93] op_sel:[0,1,0]
	global_store_dwordx4 v[82:83], v[70:73], off nt
	s_nop 1
	v_pk_fma_f32 v[70:71], v[70:71], v[184:185], v[74:75] op_sel_hi:[1,0,1]
	v_mov_b32_e32 v74, v89
	v_pk_fma_f32 v[72:73], v[72:73], v[184:185], v[76:77] op_sel_hi:[1,0,1]
	v_pk_mul_f32 v[76:77], v[80:81], v[74:75] op_sel_hi:[1,0]
	v_pk_mul_f32 v[74:75], v[78:79], v[74:75] op_sel_hi:[1,0]
	v_mov_b32_e32 v78, v181
	v_pk_fma_f32 v[12:13], v[12:13], v[78:79], v[76:77] op_sel_hi:[1,0,1]
	v_pk_fma_f32 v[10:11], v[10:11], v[78:79], v[74:75] op_sel_hi:[1,0,1]
	v_lshl_add_u64 v[74:75], v[170:171], 0, v[168:169]
	global_store_dwordx4 v[74:75], v[10:13], off nt
	v_mov_b32_e32 v74, v185
	s_nop 0
	v_pk_fma_f32 v[10:11], v[10:11], v[74:75], v[70:71] op_sel_hi:[1,0,1]
	v_pk_fma_f32 v[12:13], v[12:13], v[74:75], v[72:73] op_sel_hi:[1,0,1]
	ds_write_b128 v177, v[10:13] offset:2560
	s_waitcnt lgkmcnt(0)
	s_barrier
	s_and_saveexec_b64 s[8:9], s[46:47]
	s_cbranch_execz .LBB0_2028
	ds_read2st64_b32 v[10:11], v173 offset0:10 offset1:14
	ds_read2st64_b32 v[178:179], v173 offset0:18 offset1:22
	ds_read2st64_b32 v[182:183], v173 offset0:26 offset1:30
	ds_read2st64_b32 v[186:187], v173 offset0:34 offset1:38
	s_waitcnt lgkmcnt(3)
	v_add_f32_e32 v10, 0, v10
	v_add_f32_e32 v12, v10, v11
	s_nop 0
	s_waitcnt lgkmcnt(2)
	v_add_f32_e32 v10, v12, v178
	v_add_f32_e32 v12, v10, v179
	s_nop 0
	s_waitcnt lgkmcnt(1)
	v_add_f32_e32 v10, v12, v182
	v_add_f32_e32 v12, v10, v183
	s_nop 0
	s_waitcnt lgkmcnt(0)
	v_add_f32_e32 v10, v12, v186
	v_add_f32_e32 v10, v10, v187
	v_cvt_pk_bf16_f32 v12, v10, s0
	s_lshl_b64 s[0:1], s[6:7], 11
	s_add_u32 s0, s34, s0
	s_addc_u32 s1, s35, s1
	s_lshl_b32 s6, s43, 9
	s_add_u32 s0, s0, s6
	s_addc_u32 s1, s1, 0
	v_lshl_add_u64 v[10:11], v[134:135], 1, s[0:1]
	global_store_short v[10:11], v12, off
	s_branch .LBB0_2028
